# speedup vs baseline: 1.0210x; 1.0047x over previous
; #define STAGE(P, RS, SOFF, OFF, kt) do { const int _so = (SOFF) + (kt) * (BK * 2); \
;     _Pragma("unroll") for (int _i = 0; _i < 2; ++_i) { \
;       __builtin_amdgcn_raw_ptr_buffer_load_lds(RS, (__attribute__((address_space(3))) void*)((P) + wave * 1024 + _i * 8192), 16, OFF[_i], _so, 0, 0); } } while (0)
; #define LDA(dst, b, h) _Pragma("unroll") for (int m = 0; m < 4; ++m) _Pragma("unroll") for (int k = 0; k < 2; ++k) \
;     dst[m][k] = *reinterpret_cast<const bf16x8*>(SA(b, h) + lds_byte(wr * 64 + m * 16 + fr, k * 32 + fq * 8))
; #define LDB(dst, b, h) _Pragma("unroll") for (int n = 0; n < 2; ++n) _Pragma("unroll") for (int k = 0; k < 2; ++k) \
;     dst[n][k] = *reinterpret_cast<const bf16x8*>(SB(b, h) + lds_byte(wc * 32 + n * 16 + fr, k * 32 + fq * 8))
; #define WAIT_V(n) asm volatile("s_waitcnt vmcnt(" #n ")" ::: "memory")
; #define WAIT_L(n) asm volatile("s_waitcnt lgkmcnt(" #n ")" ::: "memory")
; #define BAR __builtin_amdgcn_s_barrier()
; #define SCHED __builtin_amdgcn_sched_barrier(0)
;     ...
;       LDB(B0, 0, 0); SCHED; LDA(At, 0, 0); STAGE(SA(1, 1), rsA, sA1, offA, t + 1);
;       WAIT_L(8); BAR; WAIT_L(0); MMA(0, 0, At, B0); BAR; SCHED;
;       LDB(B1, 0, 1); STAGE(SB(0, 0), rsB, sB0, offB, t + 2);
;       BAR; WAIT_L(0); MMA(0, 1, At, B1); BAR;
;       LDA(At, 0, 1); STAGE(SA(0, 0), rsA, sA0, offA, t + 2);
;       BAR; WAIT_L(0); MMA(1, 0, At, B0); BAR; SCHED;
;       STAGE(SB(0, 1), rsB, sB1, offB, t + 2);
;       WAIT_V(6); BAR; MMA(1, 1, At, B1); BAR;
.LBB0_95:
	ds_read_b128 v[154:157], v149
	ds_read_b128 v[158:161], v150
	ds_read_b128 v[162:165], v151
	ds_read_b128 v[166:169], v152
	s_add_i32 s43, s37, s15
	s_add_i32 s10, s43, 0x80
	s_mov_b32 m0, s30
	ds_read_b128 v[170:173], v131
	ds_read_b128 v[174:177], v131 offset:1024
	ds_read_b128 v[178:181], v134
	ds_read_b128 v[182:185], v134 offset:1024
	ds_read_b128 v[186:189], v133
	ds_read_b128 v[190:193], v133 offset:1024
	ds_read_b128 v[194:197], v132
	ds_read_b128 v[198:201], v132 offset:1024
	buffer_load_dwordx4 v143, s[4:7], s10 offen lds
	s_mov_b32 m0, s31
	s_nop 0
	buffer_load_dwordx4 v144, s[4:7], s10 offen lds
	s_waitcnt lgkmcnt(8)
	s_barrier
	s_waitcnt lgkmcnt(0)
	v_mfma_f32_16x16x32_bf16 v[124:127], v[154:157], v[170:173], v[124:127]
	v_mfma_f32_16x16x32_bf16 v[120:123], v[162:165], v[170:173], v[120:123]
	v_mfma_f32_16x16x32_bf16 v[116:119], v[154:157], v[178:181], v[116:119]
	v_mfma_f32_16x16x32_bf16 v[112:115], v[162:165], v[178:181], v[112:115]
	v_mfma_f32_16x16x32_bf16 v[108:111], v[154:157], v[186:189], v[108:111]
	v_mfma_f32_16x16x32_bf16 v[104:107], v[162:165], v[186:189], v[104:107]
	v_mfma_f32_16x16x32_bf16 v[100:103], v[154:157], v[194:197], v[100:103]
	v_mfma_f32_16x16x32_bf16 v[96:99], v[162:165], v[194:197], v[96:99]
	v_mfma_f32_16x16x32_bf16 v[124:127], v[158:161], v[174:177], v[124:127]
	v_mfma_f32_16x16x32_bf16 v[120:123], v[166:169], v[174:177], v[120:123]
	v_mfma_f32_16x16x32_bf16 v[116:119], v[158:161], v[182:185], v[116:119]
	v_mfma_f32_16x16x32_bf16 v[112:115], v[166:169], v[182:185], v[112:115]
	v_mfma_f32_16x16x32_bf16 v[108:111], v[158:161], v[190:193], v[108:111]
	v_mfma_f32_16x16x32_bf16 v[104:107], v[166:169], v[190:193], v[104:107]
	v_mfma_f32_16x16x32_bf16 v[100:103], v[158:161], v[198:201], v[100:103]
	v_mfma_f32_16x16x32_bf16 v[96:99], v[166:169], v[198:201], v[96:99]
	s_barrier
	s_add_i32 s44, s39, s15
	s_add_i32 s45, s44, 0x100
	s_mov_b32 s10, s6
	s_mov_b32 s11, s7
	s_mov_b32 m0, s1
	ds_read_b128 v[202:205], v145
	ds_read_b128 v[206:209], v146
	ds_read_b128 v[210:213], v147
	ds_read_b128 v[214:217], v148
	buffer_load_dwordx4 v143, s[8:11], s45 offen lds
	s_mov_b32 m0, s3
	s_nop 0
	buffer_load_dwordx4 v144, s[8:11], s45 offen lds
	s_barrier
	s_waitcnt lgkmcnt(0)
	v_mfma_f32_16x16x32_bf16 v[92:95], v[202:205], v[170:173], v[92:95]
	v_mfma_f32_16x16x32_bf16 v[88:91], v[210:213], v[170:173], v[88:91]
	v_mfma_f32_16x16x32_bf16 v[84:87], v[202:205], v[178:181], v[84:87]
	v_mfma_f32_16x16x32_bf16 v[80:83], v[210:213], v[178:181], v[80:83]
	v_mfma_f32_16x16x32_bf16 v[76:79], v[202:205], v[186:189], v[76:79]
	v_mfma_f32_16x16x32_bf16 v[72:75], v[210:213], v[186:189], v[72:75]
	v_mfma_f32_16x16x32_bf16 v[68:71], v[202:205], v[194:197], v[68:71]
	v_mfma_f32_16x16x32_bf16 v[64:67], v[210:213], v[194:197], v[64:67]
	v_mfma_f32_16x16x32_bf16 v[92:95], v[206:209], v[174:177], v[92:95]
	v_mfma_f32_16x16x32_bf16 v[88:91], v[214:217], v[174:177], v[88:91]
	v_mfma_f32_16x16x32_bf16 v[84:87], v[206:209], v[182:185], v[84:87]
	v_mfma_f32_16x16x32_bf16 v[80:83], v[214:217], v[182:185], v[80:83]
	v_mfma_f32_16x16x32_bf16 v[76:79], v[206:209], v[190:193], v[76:79]
	v_mfma_f32_16x16x32_bf16 v[72:75], v[214:217], v[190:193], v[72:75]
	v_mfma_f32_16x16x32_bf16 v[68:71], v[206:209], v[198:201], v[68:71]
	v_mfma_f32_16x16x32_bf16 v[64:67], v[214:217], v[198:201], v[64:67]
	s_add_i32 s45, s38, s15
	s_add_i32 s46, s45, 0x100
	s_mov_b32 m0, s0
	s_barrier
	ds_read_b128 v[170:173], v131 offset:16384
	ds_read_b128 v[174:177], v131 offset:17408
	ds_read_b128 v[178:181], v134 offset:16384
	ds_read_b128 v[182:185], v134 offset:17408
	ds_read_b128 v[186:189], v133 offset:16384
	ds_read_b128 v[190:193], v133 offset:17408
	ds_read_b128 v[194:197], v132 offset:16384
	ds_read_b128 v[198:201], v132 offset:17408
	buffer_load_dwordx4 v143, s[4:7], s46 offen lds
	s_mov_b32 m0, s18
	s_nop 0
	buffer_load_dwordx4 v144, s[4:7], s46 offen lds
	s_barrier
	s_waitcnt lgkmcnt(0)
	v_mfma_f32_16x16x32_bf16 v[60:63], v[154:157], v[170:173], v[60:63]
	v_mfma_f32_16x16x32_bf16 v[56:59], v[162:165], v[170:173], v[56:59]
	v_mfma_f32_16x16x32_bf16 v[52:55], v[154:157], v[178:181], v[52:55]
	v_mfma_f32_16x16x32_bf16 v[48:51], v[162:165], v[178:181], v[48:51]
	v_mfma_f32_16x16x32_bf16 v[44:47], v[154:157], v[186:189], v[44:47]
	v_mfma_f32_16x16x32_bf16 v[40:43], v[162:165], v[186:189], v[40:43]
	v_mfma_f32_16x16x32_bf16 v[36:39], v[154:157], v[194:197], v[36:39]
	v_mfma_f32_16x16x32_bf16 v[32:35], v[162:165], v[194:197], v[32:35]
	v_mfma_f32_16x16x32_bf16 v[60:63], v[158:161], v[174:177], v[60:63]
	v_mfma_f32_16x16x32_bf16 v[56:59], v[166:169], v[174:177], v[56:59]
	v_mfma_f32_16x16x32_bf16 v[52:55], v[158:161], v[182:185], v[52:55]
	v_mfma_f32_16x16x32_bf16 v[48:51], v[166:169], v[182:185], v[48:51]
	v_mfma_f32_16x16x32_bf16 v[44:47], v[158:161], v[190:193], v[44:47]
	v_mfma_f32_16x16x32_bf16 v[40:43], v[166:169], v[190:193], v[40:43]
	v_mfma_f32_16x16x32_bf16 v[36:39], v[158:161], v[198:201], v[36:39]
	v_mfma_f32_16x16x32_bf16 v[32:35], v[166:169], v[198:201], v[32:35]
	s_barrier
	s_add_i32 s46, s40, s15
	s_add_i32 s47, s46, 0x100
	s_mov_b32 m0, s19
	s_nop 0
	buffer_load_dwordx4 v143, s[8:11], s47 offen lds
	s_mov_b32 m0, s20
	s_nop 0
	buffer_load_dwordx4 v144, s[8:11], s47 offen lds
	s_waitcnt vmcnt(6)
	s_barrier
; #define STAGE(P, RS, SOFF, OFF, kt) do { const int _so = (SOFF) + (kt) * (BK * 2); \
;     _Pragma("unroll") for (int _i = 0; _i < 2; ++_i) { \
;       __builtin_amdgcn_raw_ptr_buffer_load_lds(RS, (__attribute__((address_space(3))) void*)((P) + wave * 1024 + _i * 8192), 16, OFF[_i], _so, 0, 0); } } while (0)
; #define LDA(dst, b, h) _Pragma("unroll") for (int m = 0; m < 4; ++m) _Pragma("unroll") for (int k = 0; k < 2; ++k) \
;     dst[m][k] = *reinterpret_cast<const bf16x8*>(SA(b, h) + lds_byte(wr * 64 + m * 16 + fr, k * 32 + fq * 8))
; #define LDB(dst, b, h) _Pragma("unroll") for (int n = 0; n < 2; ++n) _Pragma("unroll") for (int k = 0; k < 2; ++k) \
;     dst[n][k] = *reinterpret_cast<const bf16x8*>(SB(b, h) + lds_byte(wc * 32 + n * 16 + fr, k * 32 + fq * 8))
; #define WAIT_V(n) asm volatile("s_waitcnt vmcnt(" #n ")" ::: "memory")
; #define WAIT_L(n) asm volatile("s_waitcnt lgkmcnt(" #n ")" ::: "memory")
; #define BAR __builtin_amdgcn_s_barrier()
; #define SCHED __builtin_amdgcn_sched_barrier(0)
;     ...
;       WAIT_V(6); BAR; MMA(1, 1, At, B1); BAR;
;       LDB(B0, 1, 0); SCHED; LDA(At, 1, 0); STAGE(SA(0, 1), rsA, sA1, offA, t + 2);
;       WAIT_L(8); BAR; WAIT_L(0); MMA(0, 0, At, B0); BAR; SCHED;
;       LDB(B1, 1, 1); STAGE(SB(1, 0), rsB, sB0, offB, t + 3);
;       BAR; WAIT_L(0); MMA(0, 1, At, B1); BAR;
;       LDA(At, 1, 1); STAGE(SA(1, 0), rsA, sA0, offA, t + 3);
;       BAR; WAIT_L(0); MMA(1, 0, At, B0); BAR; SCHED;
	v_mfma_f32_16x16x32_bf16 v[28:31], v[202:205], v[170:173], v[28:31]
	v_mfma_f32_16x16x32_bf16 v[24:27], v[210:213], v[170:173], v[24:27]
	v_mfma_f32_16x16x32_bf16 v[20:23], v[202:205], v[178:181], v[20:23]
	v_mfma_f32_16x16x32_bf16 v[16:19], v[210:213], v[178:181], v[16:19]
	v_mfma_f32_16x16x32_bf16 v[12:15], v[202:205], v[186:189], v[12:15]
	v_mfma_f32_16x16x32_bf16 v[8:11], v[210:213], v[186:189], v[8:11]
	v_mfma_f32_16x16x32_bf16 v[4:7], v[202:205], v[194:197], v[4:7]
	v_mfma_f32_16x16x32_bf16 v[0:3], v[210:213], v[194:197], v[0:3]
	v_mfma_f32_16x16x32_bf16 v[28:31], v[206:209], v[174:177], v[28:31]
	v_mfma_f32_16x16x32_bf16 v[24:27], v[214:217], v[174:177], v[24:27]
	v_mfma_f32_16x16x32_bf16 v[20:23], v[206:209], v[182:185], v[20:23]
	v_mfma_f32_16x16x32_bf16 v[16:19], v[214:217], v[182:185], v[16:19]
	v_mfma_f32_16x16x32_bf16 v[12:15], v[206:209], v[190:193], v[12:15]
	v_mfma_f32_16x16x32_bf16 v[8:11], v[214:217], v[190:193], v[8:11]
	v_mfma_f32_16x16x32_bf16 v[4:7], v[206:209], v[198:201], v[4:7]
	v_mfma_f32_16x16x32_bf16 v[0:3], v[214:217], v[198:201], v[0:3]
	s_barrier
	ds_read_b128 v[154:157], v139
	ds_read_b128 v[158:161], v140
	ds_read_b128 v[162:165], v141
	ds_read_b128 v[166:169], v142
	s_addk_i32 s43, 0x100
	s_mov_b32 m0, s21
	ds_read_b128 v[170:173], v131 offset:32768
	ds_read_b128 v[174:177], v131 offset:33792
	ds_read_b128 v[178:181], v134 offset:32768
	ds_read_b128 v[182:185], v134 offset:33792
	ds_read_b128 v[186:189], v133 offset:32768
	ds_read_b128 v[190:193], v133 offset:33792
	ds_read_b128 v[194:197], v132 offset:32768
	ds_read_b128 v[198:201], v132 offset:33792
	buffer_load_dwordx4 v143, s[4:7], s43 offen lds
	s_mov_b32 m0, s22
	s_nop 0
	buffer_load_dwordx4 v144, s[4:7], s43 offen lds
	s_waitcnt lgkmcnt(8)
	s_barrier
	s_waitcnt lgkmcnt(0)
	v_mfma_f32_16x16x32_bf16 v[124:127], v[154:157], v[170:173], v[124:127]
	v_mfma_f32_16x16x32_bf16 v[120:123], v[162:165], v[170:173], v[120:123]
	v_mfma_f32_16x16x32_bf16 v[116:119], v[154:157], v[178:181], v[116:119]
	v_mfma_f32_16x16x32_bf16 v[112:115], v[162:165], v[178:181], v[112:115]
	v_mfma_f32_16x16x32_bf16 v[108:111], v[154:157], v[186:189], v[108:111]
	v_mfma_f32_16x16x32_bf16 v[104:107], v[162:165], v[186:189], v[104:107]
	v_mfma_f32_16x16x32_bf16 v[100:103], v[154:157], v[194:197], v[100:103]
	v_mfma_f32_16x16x32_bf16 v[96:99], v[162:165], v[194:197], v[96:99]
	v_mfma_f32_16x16x32_bf16 v[124:127], v[158:161], v[174:177], v[124:127]
	v_mfma_f32_16x16x32_bf16 v[120:123], v[166:169], v[174:177], v[120:123]
	v_mfma_f32_16x16x32_bf16 v[116:119], v[158:161], v[182:185], v[116:119]
	v_mfma_f32_16x16x32_bf16 v[112:115], v[166:169], v[182:185], v[112:115]
	v_mfma_f32_16x16x32_bf16 v[108:111], v[158:161], v[190:193], v[108:111]
	v_mfma_f32_16x16x32_bf16 v[104:107], v[166:169], v[190:193], v[104:107]
	v_mfma_f32_16x16x32_bf16 v[100:103], v[158:161], v[198:201], v[100:103]
	v_mfma_f32_16x16x32_bf16 v[96:99], v[166:169], v[198:201], v[96:99]
	s_barrier
	s_addk_i32 s44, 0x180
	s_mov_b32 m0, s23
	ds_read_b128 v[202:205], v135
	ds_read_b128 v[206:209], v136
	ds_read_b128 v[210:213], v137
	ds_read_b128 v[214:217], v138
	buffer_load_dwordx4 v143, s[8:11], s44 offen lds
	s_mov_b32 m0, s24
	s_nop 0
	buffer_load_dwordx4 v144, s[8:11], s44 offen lds
	s_barrier
	s_waitcnt lgkmcnt(0)
	v_mfma_f32_16x16x32_bf16 v[92:95], v[202:205], v[170:173], v[92:95]
	v_mfma_f32_16x16x32_bf16 v[88:91], v[210:213], v[170:173], v[88:91]
	v_mfma_f32_16x16x32_bf16 v[84:87], v[202:205], v[178:181], v[84:87]
	v_mfma_f32_16x16x32_bf16 v[80:83], v[210:213], v[178:181], v[80:83]
	v_mfma_f32_16x16x32_bf16 v[76:79], v[202:205], v[186:189], v[76:79]
	v_mfma_f32_16x16x32_bf16 v[72:75], v[210:213], v[186:189], v[72:75]
	v_mfma_f32_16x16x32_bf16 v[68:71], v[202:205], v[194:197], v[68:71]
	v_mfma_f32_16x16x32_bf16 v[64:67], v[210:213], v[194:197], v[64:67]
	v_mfma_f32_16x16x32_bf16 v[92:95], v[206:209], v[174:177], v[92:95]
	v_mfma_f32_16x16x32_bf16 v[88:91], v[214:217], v[174:177], v[88:91]
	v_mfma_f32_16x16x32_bf16 v[84:87], v[206:209], v[182:185], v[84:87]
	v_mfma_f32_16x16x32_bf16 v[80:83], v[214:217], v[182:185], v[80:83]
	v_mfma_f32_16x16x32_bf16 v[76:79], v[206:209], v[190:193], v[76:79]
	v_mfma_f32_16x16x32_bf16 v[72:75], v[214:217], v[190:193], v[72:75]
	v_mfma_f32_16x16x32_bf16 v[68:71], v[206:209], v[198:201], v[68:71]
	v_mfma_f32_16x16x32_bf16 v[64:67], v[214:217], v[198:201], v[64:67]
	s_addk_i32 s45, 0x180
	s_mov_b32 m0, s25
	s_barrier
	ds_read_b128 v[170:173], v131 offset:49152
	ds_read_b128 v[174:177], v131 offset:50176
	ds_read_b128 v[178:181], v134 offset:49152
	ds_read_b128 v[182:185], v134 offset:50176
	ds_read_b128 v[186:189], v133 offset:49152
	ds_read_b128 v[190:193], v133 offset:50176
	ds_read_b128 v[194:197], v132 offset:49152
	ds_read_b128 v[198:201], v132 offset:50176
	buffer_load_dwordx4 v143, s[4:7], s45 offen lds
	s_mov_b32 m0, s26
	s_nop 0
	buffer_load_dwordx4 v144, s[4:7], s45 offen lds
	s_barrier
	s_waitcnt lgkmcnt(0)
	v_mfma_f32_16x16x32_bf16 v[60:63], v[154:157], v[170:173], v[60:63]
	v_mfma_f32_16x16x32_bf16 v[56:59], v[162:165], v[170:173], v[56:59]
	v_mfma_f32_16x16x32_bf16 v[52:55], v[154:157], v[178:181], v[52:55]
	v_mfma_f32_16x16x32_bf16 v[48:51], v[162:165], v[178:181], v[48:51]
	v_mfma_f32_16x16x32_bf16 v[44:47], v[154:157], v[186:189], v[44:47]
	v_mfma_f32_16x16x32_bf16 v[40:43], v[162:165], v[186:189], v[40:43]
	v_mfma_f32_16x16x32_bf16 v[36:39], v[154:157], v[194:197], v[36:39]
	v_mfma_f32_16x16x32_bf16 v[32:35], v[162:165], v[194:197], v[32:35]
	v_mfma_f32_16x16x32_bf16 v[60:63], v[158:161], v[174:177], v[60:63]
	v_mfma_f32_16x16x32_bf16 v[56:59], v[166:169], v[174:177], v[56:59]
	v_mfma_f32_16x16x32_bf16 v[52:55], v[158:161], v[182:185], v[52:55]
	v_mfma_f32_16x16x32_bf16 v[48:51], v[166:169], v[182:185], v[48:51]
	v_mfma_f32_16x16x32_bf16 v[44:47], v[158:161], v[190:193], v[44:47]
	v_mfma_f32_16x16x32_bf16 v[40:43], v[166:169], v[190:193], v[40:43]
	v_mfma_f32_16x16x32_bf16 v[36:39], v[158:161], v[198:201], v[36:39]
	v_mfma_f32_16x16x32_bf16 v[32:35], v[166:169], v[198:201], v[32:35]
	s_barrier
; #define STAGE(P, RS, SOFF, OFF, kt) do { const int _so = (SOFF) + (kt) * (BK * 2); \
;     _Pragma("unroll") for (int _i = 0; _i < 2; ++_i) { \
;       __builtin_amdgcn_raw_ptr_buffer_load_lds(RS, (__attribute__((address_space(3))) void*)((P) + wave * 1024 + _i * 8192), 16, OFF[_i], _so, 0, 0); } } while (0)
; #define LDA(dst, b, h) _Pragma("unroll") for (int m = 0; m < 4; ++m) _Pragma("unroll") for (int k = 0; k < 2; ++k) \
;     dst[m][k] = *reinterpret_cast<const bf16x8*>(SA(b, h) + lds_byte(wr * 64 + m * 16 + fr, k * 32 + fq * 8))
; #define LDB(dst, b, h) _Pragma("unroll") for (int n = 0; n < 2; ++n) _Pragma("unroll") for (int k = 0; k < 2; ++k) \
;     dst[n][k] = *reinterpret_cast<const bf16x8*>(SB(b, h) + lds_byte(wc * 32 + n * 16 + fr, k * 32 + fq * 8))
; #define WAIT_V(n) asm volatile("s_waitcnt vmcnt(" #n ")" ::: "memory")
; #define WAIT_L(n) asm volatile("s_waitcnt lgkmcnt(" #n ")" ::: "memory")
; #define BAR __builtin_amdgcn_s_barrier()
;     ...
;       STAGE(SB(1, 1), rsB, sB1, offB, t + 3);
;       WAIT_V(6); BAR; MMA(1, 1, At, B1); BAR;
;     }
;     { LDB(B0, 0, 0); LDA(At, 0, 0); STAGE(SA(1, 1), rsA, sA1, offA, nt - 1);
;       BAR; WAIT_L(0); MMA(0, 0, At, B0); BAR;
;       LDB(B1, 0, 1); BAR; WAIT_L(0); MMA(0, 1, At, B1); BAR;
;       LDA(At, 0, 1); WAIT_V(4); BAR; WAIT_L(0); MMA(1, 0, At, B0); MMA(1, 1, At, B1); BAR; }
	s_addk_i32 s46, 0x180
	s_mov_b32 m0, s27
	s_nop 0
	buffer_load_dwordx4 v143, s[8:11], s46 offen lds
	s_mov_b32 m0, s28
	s_nop 0
	buffer_load_dwordx4 v144, s[8:11], s46 offen lds
	s_waitcnt vmcnt(6)
	s_barrier
	v_mfma_f32_16x16x32_bf16 v[28:31], v[202:205], v[170:173], v[28:31]
	v_mfma_f32_16x16x32_bf16 v[24:27], v[210:213], v[170:173], v[24:27]
	v_mfma_f32_16x16x32_bf16 v[20:23], v[202:205], v[178:181], v[20:23]
	v_mfma_f32_16x16x32_bf16 v[16:19], v[210:213], v[178:181], v[16:19]
	v_mfma_f32_16x16x32_bf16 v[12:15], v[202:205], v[186:189], v[12:15]
	v_mfma_f32_16x16x32_bf16 v[8:11], v[210:213], v[186:189], v[8:11]
	v_mfma_f32_16x16x32_bf16 v[4:7], v[202:205], v[194:197], v[4:7]
	v_mfma_f32_16x16x32_bf16 v[0:3], v[210:213], v[194:197], v[0:3]
	v_mfma_f32_16x16x32_bf16 v[28:31], v[206:209], v[174:177], v[28:31]
	v_mfma_f32_16x16x32_bf16 v[24:27], v[214:217], v[174:177], v[24:27]
	v_mfma_f32_16x16x32_bf16 v[20:23], v[206:209], v[182:185], v[20:23]
	v_mfma_f32_16x16x32_bf16 v[16:19], v[214:217], v[182:185], v[16:19]
	v_mfma_f32_16x16x32_bf16 v[12:15], v[206:209], v[190:193], v[12:15]
	v_mfma_f32_16x16x32_bf16 v[8:11], v[214:217], v[190:193], v[8:11]
	v_mfma_f32_16x16x32_bf16 v[4:7], v[206:209], v[198:201], v[4:7]
	v_mfma_f32_16x16x32_bf16 v[0:3], v[214:217], v[198:201], v[0:3]
	s_add_i32 s14, s14, 2
	s_addk_i32 s15, 0x100
	s_cmp_gt_u32 s14, 27
	s_barrier
	s_cbranch_scc0 .LBB0_95
	s_add_i32 s10, s37, 0xf80
	s_mov_b32 m0, s30
	ds_read_b128 v[154:157], v149
	ds_read_b128 v[158:161], v150
	ds_read_b128 v[162:165], v151
	ds_read_b128 v[150:153], v152
	ds_read_b128 v[166:169], v131
	ds_read_b128 v[170:173], v131 offset:1024
	ds_read_b128 v[174:177], v134
	ds_read_b128 v[178:181], v134 offset:1024
	ds_read_b128 v[182:185], v133
	ds_read_b128 v[186:189], v133 offset:1024
	ds_read_b128 v[190:193], v132
	ds_read_b128 v[194:197], v132 offset:1024
	buffer_load_dwordx4 v143, s[4:7], s10 offen lds
	s_mov_b32 m0, s31
	s_nop 0
	buffer_load_dwordx4 v144, s[4:7], s10 offen lds
	s_barrier
	s_waitcnt lgkmcnt(0)
	v_mfma_f32_16x16x32_bf16 v[124:127], v[154:157], v[166:169], v[124:127]
	v_mfma_f32_16x16x32_bf16 v[120:123], v[162:165], v[166:169], v[120:123]
	v_mfma_f32_16x16x32_bf16 v[116:119], v[154:157], v[174:177], v[116:119]
	v_mfma_f32_16x16x32_bf16 v[112:115], v[162:165], v[174:177], v[112:115]
	v_mfma_f32_16x16x32_bf16 v[108:111], v[154:157], v[182:185], v[108:111]
	v_mfma_f32_16x16x32_bf16 v[104:107], v[162:165], v[182:185], v[104:107]
	v_mfma_f32_16x16x32_bf16 v[100:103], v[154:157], v[190:193], v[100:103]
	v_mfma_f32_16x16x32_bf16 v[96:99], v[162:165], v[190:193], v[96:99]
	v_mfma_f32_16x16x32_bf16 v[124:127], v[158:161], v[170:173], v[124:127]
	v_mfma_f32_16x16x32_bf16 v[120:123], v[150:153], v[170:173], v[120:123]
	v_mfma_f32_16x16x32_bf16 v[116:119], v[158:161], v[178:181], v[116:119]
	v_mfma_f32_16x16x32_bf16 v[112:115], v[150:153], v[178:181], v[112:115]
	v_mfma_f32_16x16x32_bf16 v[108:111], v[158:161], v[186:189], v[108:111]
	v_mfma_f32_16x16x32_bf16 v[104:107], v[150:153], v[186:189], v[104:107]
	v_mfma_f32_16x16x32_bf16 v[100:103], v[158:161], v[194:197], v[100:103]
	v_mfma_f32_16x16x32_bf16 v[96:99], v[150:153], v[194:197], v[96:99]
	s_barrier
	ds_read_b128 v[198:201], v145
	ds_read_b128 v[202:205], v146
	ds_read_b128 v[144:147], v147
	ds_read_b128 v[206:209], v148
	s_barrier
	s_waitcnt lgkmcnt(0)
	v_mfma_f32_16x16x32_bf16 v[92:95], v[198:201], v[166:169], v[92:95]
	v_mfma_f32_16x16x32_bf16 v[84:87], v[198:201], v[174:177], v[84:87]
	v_mfma_f32_16x16x32_bf16 v[76:79], v[198:201], v[182:185], v[76:79]
	v_mfma_f32_16x16x32_bf16 v[68:71], v[198:201], v[190:193], v[68:71]
	v_mfma_f32_16x16x32_bf16 v[88:91], v[144:147], v[166:169], v[88:91]
	v_mfma_f32_16x16x32_bf16 v[80:83], v[144:147], v[174:177], v[80:83]
	v_mfma_f32_16x16x32_bf16 v[72:75], v[144:147], v[182:185], v[72:75]
	v_mfma_f32_16x16x32_bf16 v[64:67], v[144:147], v[190:193], v[64:67]
	v_mfma_f32_16x16x32_bf16 v[92:95], v[202:205], v[170:173], v[92:95]
	v_mfma_f32_16x16x32_bf16 v[84:87], v[202:205], v[178:181], v[84:87]
	v_mfma_f32_16x16x32_bf16 v[76:79], v[202:205], v[186:189], v[76:79]
	v_mfma_f32_16x16x32_bf16 v[68:71], v[202:205], v[194:197], v[68:71]
	v_mfma_f32_16x16x32_bf16 v[166:169], v[206:209], v[170:173], v[88:91]
	v_mfma_f32_16x16x32_bf16 v[170:173], v[206:209], v[178:181], v[80:83]
	v_mfma_f32_16x16x32_bf16 v[174:177], v[206:209], v[186:189], v[72:75]
	v_mfma_f32_16x16x32_bf16 v[178:181], v[206:209], v[194:197], v[64:67]
	s_barrier
	s_nop 0
	ds_read_b128 v[64:67], v131 offset:16384
	ds_read_b128 v[72:75], v131 offset:17408
	ds_read_b128 v[80:83], v134 offset:16384
	ds_read_b128 v[88:91], v134 offset:17408
	ds_read_b128 v[182:185], v133 offset:16384
	ds_read_b128 v[186:189], v133 offset:17408
	ds_read_b128 v[190:193], v132 offset:16384
	ds_read_b128 v[194:197], v132 offset:17408
	s_waitcnt vmcnt(4)
	s_barrier
; #define LDA(dst, b, h) _Pragma("unroll") for (int m = 0; m < 4; ++m) _Pragma("unroll") for (int k = 0; k < 2; ++k) \
;     dst[m][k] = *reinterpret_cast<const bf16x8*>(SA(b, h) + lds_byte(wr * 64 + m * 16 + fr, k * 32 + fq * 8))
; #define LDB(dst, b, h) _Pragma("unroll") for (int n = 0; n < 2; ++n) _Pragma("unroll") for (int k = 0; k < 2; ++k) \
;     dst[n][k] = *reinterpret_cast<const bf16x8*>(SB(b, h) + lds_byte(wc * 32 + n * 16 + fr, k * 32 + fq * 8))
; #define WAIT_V(n) asm volatile("s_waitcnt vmcnt(" #n ")" ::: "memory")
; #define WAIT_L(n) asm volatile("s_waitcnt lgkmcnt(" #n ")" ::: "memory")
; #define BAR __builtin_amdgcn_s_barrier()
;     ...
;       LDA(At, 0, 1); WAIT_V(4); BAR; WAIT_L(0); MMA(1, 0, At, B0); MMA(1, 1, At, B1); BAR; }
;     { LDB(B0, 1, 0); LDA(At, 1, 0); WAIT_V(2); BAR; WAIT_L(0); MMA(0, 0, At, B0); BAR;
	s_waitcnt lgkmcnt(0)
	v_mfma_f32_16x16x32_bf16 v[60:63], v[154:157], v[64:67], v[60:63]
	v_mfma_f32_16x16x32_bf16 v[56:59], v[162:165], v[64:67], v[56:59]
	v_mfma_f32_16x16x32_bf16 v[52:55], v[154:157], v[80:83], v[52:55]
	v_mfma_f32_16x16x32_bf16 v[48:51], v[162:165], v[80:83], v[48:51]
	v_mfma_f32_16x16x32_bf16 v[44:47], v[154:157], v[182:185], v[44:47]
	v_mfma_f32_16x16x32_bf16 v[40:43], v[162:165], v[182:185], v[40:43]
	v_mfma_f32_16x16x32_bf16 v[36:39], v[154:157], v[190:193], v[36:39]
	v_mfma_f32_16x16x32_bf16 v[32:35], v[162:165], v[190:193], v[32:35]
	v_mfma_f32_16x16x32_bf16 v[60:63], v[158:161], v[72:75], v[60:63]
	v_mfma_f32_16x16x32_bf16 v[56:59], v[150:153], v[72:75], v[56:59]
	v_mfma_f32_16x16x32_bf16 v[52:55], v[158:161], v[88:91], v[52:55]
	v_mfma_f32_16x16x32_bf16 v[48:51], v[150:153], v[88:91], v[48:51]
	v_mfma_f32_16x16x32_bf16 v[44:47], v[158:161], v[186:189], v[44:47]
	v_mfma_f32_16x16x32_bf16 v[40:43], v[150:153], v[186:189], v[40:43]
	v_mfma_f32_16x16x32_bf16 v[36:39], v[158:161], v[194:197], v[36:39]
	v_mfma_f32_16x16x32_bf16 v[32:35], v[150:153], v[194:197], v[32:35]
	v_mfma_f32_16x16x32_bf16 v[28:31], v[198:201], v[64:67], v[28:31]
	v_mfma_f32_16x16x32_bf16 v[20:23], v[198:201], v[80:83], v[20:23]
	v_mfma_f32_16x16x32_bf16 v[12:15], v[198:201], v[182:185], v[12:15]
	v_mfma_f32_16x16x32_bf16 v[4:7], v[198:201], v[190:193], v[4:7]
	v_mfma_f32_16x16x32_bf16 v[24:27], v[144:147], v[64:67], v[24:27]
	v_mfma_f32_16x16x32_bf16 v[16:19], v[144:147], v[80:83], v[16:19]
	v_mfma_f32_16x16x32_bf16 v[8:11], v[144:147], v[182:185], v[8:11]
	v_mfma_f32_16x16x32_bf16 v[0:3], v[144:147], v[190:193], v[0:3]
	v_mfma_f32_16x16x32_bf16 v[28:31], v[202:205], v[72:75], v[28:31]
	v_mfma_f32_16x16x32_bf16 v[20:23], v[202:205], v[88:91], v[20:23]
	v_mfma_f32_16x16x32_bf16 v[12:15], v[202:205], v[186:189], v[12:15]
	v_mfma_f32_16x16x32_bf16 v[4:7], v[202:205], v[194:197], v[4:7]
	v_mfma_f32_16x16x32_bf16 v[144:147], v[206:209], v[72:75], v[24:27]
	v_mfma_f32_16x16x32_bf16 v[148:151], v[206:209], v[88:91], v[16:19]
	v_mfma_f32_16x16x32_bf16 v[152:155], v[206:209], v[186:189], v[8:11]
	v_mfma_f32_16x16x32_bf16 v[156:159], v[206:209], v[194:197], v[0:3]
	s_barrier
	s_nop 0
	ds_read_b128 v[0:3], v139
	ds_read_b128 v[8:11], v140
	ds_read_b128 v[16:19], v141
	ds_read_b128 v[140:143], v142
	ds_read_b128 v[24:27], v131 offset:32768
	ds_read_b128 v[160:163], v131 offset:33792
	ds_read_b128 v[182:185], v134 offset:32768
	ds_read_b128 v[186:189], v134 offset:33792
	ds_read_b128 v[190:193], v133 offset:32768
	ds_read_b128 v[194:197], v133 offset:33792
	ds_read_b128 v[198:201], v132 offset:32768
	ds_read_b128 v[202:205], v132 offset:33792
	s_waitcnt vmcnt(2)
	s_barrier
	s_waitcnt lgkmcnt(0)
	v_mfma_f32_16x16x32_bf16 v[64:67], v[0:3], v[24:27], v[124:127]
	v_mfma_f32_16x16x32_bf16 v[72:75], v[16:19], v[24:27], v[120:123]
	v_mfma_f32_16x16x32_bf16 v[80:83], v[0:3], v[182:185], v[116:119]
	v_mfma_f32_16x16x32_bf16 v[88:91], v[16:19], v[182:185], v[112:115]
	v_mfma_f32_16x16x32_bf16 v[108:111], v[0:3], v[190:193], v[108:111]
	v_mfma_f32_16x16x32_bf16 v[116:119], v[16:19], v[190:193], v[104:107]
	v_mfma_f32_16x16x32_bf16 v[100:103], v[0:3], v[198:201], v[100:103]
	v_mfma_f32_16x16x32_bf16 v[124:127], v[16:19], v[198:201], v[96:99]
	v_mfma_f32_16x16x32_bf16 v[120:123], v[8:11], v[160:163], v[64:67]
	v_mfma_f32_16x16x32_bf16 v[112:115], v[140:143], v[160:163], v[72:75]
	v_mfma_f32_16x16x32_bf16 v[104:107], v[8:11], v[186:189], v[80:83]
	v_mfma_f32_16x16x32_bf16 v[96:99], v[140:143], v[186:189], v[88:91]
	v_mfma_f32_16x16x32_bf16 v[88:91], v[8:11], v[194:197], v[108:111]
	v_mfma_f32_16x16x32_bf16 v[80:83], v[140:143], v[194:197], v[116:119]
	v_mfma_f32_16x16x32_bf16 v[72:75], v[8:11], v[202:205], v[100:103]
	v_mfma_f32_16x16x32_bf16 v[64:67], v[140:143], v[202:205], v[124:127]
	s_barrier
	ds_read_b128 v[206:209], v135
	ds_read_b128 v[210:213], v136
	ds_read_b128 v[214:217], v137
	ds_read_b128 v[136:139], v138
	s_waitcnt vmcnt(0)
	s_barrier
; #define LDA(dst, b, h) _Pragma("unroll") for (int m = 0; m < 4; ++m) _Pragma("unroll") for (int k = 0; k < 2; ++k) \
;     dst[m][k] = *reinterpret_cast<const bf16x8*>(SA(b, h) + lds_byte(wr * 64 + m * 16 + fr, k * 32 + fq * 8))
; #define LDB(dst, b, h) _Pragma("unroll") for (int n = 0; n < 2; ++n) _Pragma("unroll") for (int k = 0; k < 2; ++k) \
;     dst[n][k] = *reinterpret_cast<const bf16x8*>(SB(b, h) + lds_byte(wc * 32 + n * 16 + fr, k * 32 + fq * 8))
; #define WAIT_V(n) asm volatile("s_waitcnt vmcnt(" #n ")" ::: "memory")
; #define WAIT_L(n) asm volatile("s_waitcnt lgkmcnt(" #n ")" ::: "memory")
; #define BAR __builtin_amdgcn_s_barrier()
;     ...
;       LDB(B1, 1, 1); WAIT_V(0); BAR; WAIT_L(0); MMA(0, 1, At, B1); BAR;
;       LDA(At, 1, 1); BAR; WAIT_L(0); MMA(1, 0, At, B0); MMA(1, 1, At, B1); BAR; }
;     if (wr == 0) BAR;
	s_waitcnt lgkmcnt(0)
	v_mfma_f32_16x16x32_bf16 v[92:95], v[206:209], v[24:27], v[92:95]
	v_mfma_f32_16x16x32_bf16 v[24:27], v[214:217], v[24:27], v[166:169]
	v_mfma_f32_16x16x32_bf16 v[84:87], v[206:209], v[182:185], v[84:87]
	v_mfma_f32_16x16x32_bf16 v[100:103], v[214:217], v[182:185], v[170:173]
	v_mfma_f32_16x16x32_bf16 v[76:79], v[206:209], v[190:193], v[76:79]
	v_mfma_f32_16x16x32_bf16 v[164:167], v[214:217], v[190:193], v[174:177]
	v_mfma_f32_16x16x32_bf16 v[68:71], v[206:209], v[198:201], v[68:71]
	v_mfma_f32_16x16x32_bf16 v[168:171], v[214:217], v[198:201], v[178:181]
	v_mfma_f32_16x16x32_bf16 v[124:127], v[210:213], v[160:163], v[92:95]
	v_mfma_f32_16x16x32_bf16 v[116:119], v[136:139], v[160:163], v[24:27]
	v_mfma_f32_16x16x32_bf16 v[108:111], v[210:213], v[186:189], v[84:87]
	v_mfma_f32_16x16x32_bf16 v[100:103], v[136:139], v[186:189], v[100:103]
	v_mfma_f32_16x16x32_bf16 v[92:95], v[210:213], v[194:197], v[76:79]
	v_mfma_f32_16x16x32_bf16 v[84:87], v[136:139], v[194:197], v[164:167]
	v_mfma_f32_16x16x32_bf16 v[76:79], v[210:213], v[202:205], v[68:71]
	v_mfma_f32_16x16x32_bf16 v[68:71], v[136:139], v[202:205], v[168:171]
	s_barrier
	ds_read_b128 v[160:163], v131 offset:49152
	ds_read_b128 v[164:167], v131 offset:50176
	ds_read_b128 v[168:171], v134 offset:49152
	ds_read_b128 v[172:175], v134 offset:50176
	ds_read_b128 v[176:179], v133 offset:49152
	ds_read_b128 v[180:183], v133 offset:50176
	ds_read_b128 v[184:187], v132 offset:49152
	ds_read_b128 v[132:135], v132 offset:50176
	s_barrier
	s_waitcnt lgkmcnt(0)
	v_mfma_f32_16x16x32_bf16 v[24:27], v[0:3], v[160:163], v[60:63]
	v_mfma_f32_16x16x32_bf16 v[60:63], v[16:19], v[160:163], v[56:59]
	v_mfma_f32_16x16x32_bf16 v[52:55], v[0:3], v[168:171], v[52:55]
	v_mfma_f32_16x16x32_bf16 v[188:191], v[16:19], v[168:171], v[48:51]
	v_mfma_f32_16x16x32_bf16 v[44:47], v[0:3], v[176:179], v[44:47]
	v_mfma_f32_16x16x32_bf16 v[192:195], v[16:19], v[176:179], v[40:43]
	v_mfma_f32_16x16x32_bf16 v[0:3], v[0:3], v[184:187], v[36:39]
	v_mfma_f32_16x16x32_bf16 v[36:39], v[16:19], v[184:187], v[32:35]
	v_mfma_f32_16x16x32_bf16 v[56:59], v[8:11], v[164:167], v[24:27]
	v_mfma_f32_16x16x32_bf16 v[48:51], v[140:143], v[164:167], v[60:63]
	v_mfma_f32_16x16x32_bf16 v[40:43], v[8:11], v[172:175], v[52:55]
	v_mfma_f32_16x16x32_bf16 v[32:35], v[140:143], v[172:175], v[188:191]
	v_mfma_f32_16x16x32_bf16 v[24:27], v[8:11], v[180:183], v[44:47]
	v_mfma_f32_16x16x32_bf16 v[16:19], v[140:143], v[180:183], v[192:195]
	v_mfma_f32_16x16x32_bf16 v[8:11], v[8:11], v[132:135], v[0:3]
	v_mfma_f32_16x16x32_bf16 v[0:3], v[140:143], v[132:135], v[36:39]
	v_mfma_f32_16x16x32_bf16 v[28:31], v[206:209], v[160:163], v[28:31]
	v_mfma_f32_16x16x32_bf16 v[36:39], v[214:217], v[160:163], v[144:147]
	v_mfma_f32_16x16x32_bf16 v[20:23], v[206:209], v[168:171], v[20:23]
	v_mfma_f32_16x16x32_bf16 v[140:143], v[214:217], v[168:171], v[148:151]
	v_mfma_f32_16x16x32_bf16 v[12:15], v[206:209], v[176:179], v[12:15]
	v_mfma_f32_16x16x32_bf16 v[144:147], v[214:217], v[176:179], v[152:155]
	v_mfma_f32_16x16x32_bf16 v[4:7], v[206:209], v[184:187], v[4:7]
	v_mfma_f32_16x16x32_bf16 v[148:151], v[214:217], v[184:187], v[156:159]
	v_mfma_f32_16x16x32_bf16 v[60:63], v[210:213], v[164:167], v[28:31]
	v_mfma_f32_16x16x32_bf16 v[52:55], v[136:139], v[164:167], v[36:39]
	v_mfma_f32_16x16x32_bf16 v[44:47], v[210:213], v[172:175], v[20:23]
	v_mfma_f32_16x16x32_bf16 v[36:39], v[136:139], v[172:175], v[140:143]
	v_mfma_f32_16x16x32_bf16 v[28:31], v[210:213], v[180:183], v[12:15]
	v_mfma_f32_16x16x32_bf16 v[20:23], v[136:139], v[180:183], v[144:147]
	v_mfma_f32_16x16x32_bf16 v[12:15], v[210:213], v[132:135], v[4:7]
	v_mfma_f32_16x16x32_bf16 v[4:7], v[136:139], v[132:135], v[148:151]
	v_cmp_gt_u32_e32 vcc, s35, v130
	s_barrier
	s_and_saveexec_b64 s[10:11], vcc
	s_cbranch_execz .LBB0_98
	s_barrier

; #define STAGE(P, RS, SOFF, OFF, kt) do { const int _so = (SOFF) + (kt) * (BK * 2); \
;     _Pragma("unroll") for (int _i = 0; _i < 2; ++_i) { \
;       __builtin_amdgcn_raw_ptr_buffer_load_lds(RS, (__attribute__((address_space(3))) void*)((P) + wave * 1024 + _i * 8192), 16, OFF[_i], _so, 0, 0); } } while (0)
; #define LDA(dst, b, h) _Pragma("unroll") for (int m = 0; m < 4; ++m) _Pragma("unroll") for (int k = 0; k < 2; ++k) \
;     dst[m][k] = *reinterpret_cast<const bf16x8*>(SA(b, h) + lds_byte(wr * 64 + m * 16 + fr, k * 32 + fq * 8))
; #define LDB(dst, b, h) _Pragma("unroll") for (int n = 0; n < 2; ++n) _Pragma("unroll") for (int k = 0; k < 2; ++k) \
;     dst[n][k] = *reinterpret_cast<const bf16x8*>(SB(b, h) + lds_byte(wc * 32 + n * 16 + fr, k * 32 + fq * 8))
; #define WAIT_V(n) asm volatile("s_waitcnt vmcnt(" #n ")" ::: "memory")
; #define WAIT_L(n) asm volatile("s_waitcnt lgkmcnt(" #n ")" ::: "memory")
; #define BAR __builtin_amdgcn_s_barrier()
; #define SCHED __builtin_amdgcn_sched_barrier(0)
;     ...
;       LDB(B0, 0, 0); SCHED; LDA(At, 0, 0); STAGE(SA(1, 1), rsA, sA1, offA, t + 1);
;       WAIT_L(8); BAR; WAIT_L(0); MMA(0, 0, At, B0); BAR; SCHED;
;       LDB(B1, 0, 1); STAGE(SB(0, 0), rsB, sB0, offB, t + 2);
;       BAR; WAIT_L(0); MMA(0, 1, At, B1); BAR;
;       LDA(At, 0, 1); STAGE(SA(0, 0), rsA, sA0, offA, t + 2);
;       BAR; WAIT_L(0); MMA(1, 0, At, B0); BAR; SCHED;
;       STAGE(SB(0, 1), rsB, sB1, offB, t + 2);
;       WAIT_V(6); BAR; MMA(1, 1, At, B1); BAR;
.LBB0_110:
	ds_read_b128 v[156:159], v151
	ds_read_b128 v[160:163], v152
	ds_read_b128 v[164:167], v153
	ds_read_b128 v[168:171], v154
	s_add_i32 s44, s38, s17
	s_add_i32 s10, s44, 0x80
	s_mov_b32 m0, s31
	ds_read_b128 v[172:175], v131
	ds_read_b128 v[176:179], v131 offset:1024
	ds_read_b128 v[180:183], v138
	ds_read_b128 v[184:187], v138 offset:1024
	ds_read_b128 v[188:191], v137
	ds_read_b128 v[192:195], v137 offset:1024
	ds_read_b128 v[196:199], v135
	ds_read_b128 v[200:203], v135 offset:1024
	buffer_load_dwordx4 v128, s[4:7], s10 offen lds
	s_mov_b32 m0, s33
	s_nop 0
	buffer_load_dwordx4 v132, s[4:7], s10 offen lds
	s_waitcnt lgkmcnt(8)
	s_barrier
	s_waitcnt lgkmcnt(0)
	v_mfma_f32_16x16x32_bf16 v[124:127], v[156:159], v[172:175], v[124:127]
	v_mfma_f32_16x16x32_bf16 v[120:123], v[164:167], v[172:175], v[120:123]
	v_mfma_f32_16x16x32_bf16 v[116:119], v[156:159], v[180:183], v[116:119]
	v_mfma_f32_16x16x32_bf16 v[112:115], v[164:167], v[180:183], v[112:115]
	v_mfma_f32_16x16x32_bf16 v[108:111], v[156:159], v[188:191], v[108:111]
	v_mfma_f32_16x16x32_bf16 v[104:107], v[164:167], v[188:191], v[104:107]
	v_mfma_f32_16x16x32_bf16 v[100:103], v[156:159], v[196:199], v[100:103]
	v_mfma_f32_16x16x32_bf16 v[96:99], v[164:167], v[196:199], v[96:99]
	v_mfma_f32_16x16x32_bf16 v[124:127], v[160:163], v[176:179], v[124:127]
	v_mfma_f32_16x16x32_bf16 v[120:123], v[168:171], v[176:179], v[120:123]
	v_mfma_f32_16x16x32_bf16 v[116:119], v[160:163], v[184:187], v[116:119]
	v_mfma_f32_16x16x32_bf16 v[112:115], v[168:171], v[184:187], v[112:115]
	v_mfma_f32_16x16x32_bf16 v[108:111], v[160:163], v[192:195], v[108:111]
	v_mfma_f32_16x16x32_bf16 v[104:107], v[168:171], v[192:195], v[104:107]
	v_mfma_f32_16x16x32_bf16 v[100:103], v[160:163], v[200:203], v[100:103]
	v_mfma_f32_16x16x32_bf16 v[96:99], v[168:171], v[200:203], v[96:99]
	s_barrier
	s_add_i32 s45, s40, s17
	s_add_i32 s46, s45, 0x100
	s_mov_b32 s10, s6
	s_mov_b32 s11, s7
	s_mov_b32 m0, s3
	ds_read_b128 v[204:207], v147
	ds_read_b128 v[208:211], v148
	ds_read_b128 v[212:215], v149
	ds_read_b128 v[216:219], v150
	buffer_load_dwordx4 v130, s[8:11], s46 offen lds
	s_mov_b32 m0, s18
	s_nop 0
	buffer_load_dwordx4 v134, s[8:11], s46 offen lds
	s_barrier
	s_waitcnt lgkmcnt(0)
	v_mfma_f32_16x16x32_bf16 v[92:95], v[204:207], v[172:175], v[92:95]
	v_mfma_f32_16x16x32_bf16 v[88:91], v[212:215], v[172:175], v[88:91]
	v_mfma_f32_16x16x32_bf16 v[84:87], v[204:207], v[180:183], v[84:87]
	v_mfma_f32_16x16x32_bf16 v[80:83], v[212:215], v[180:183], v[80:83]
	v_mfma_f32_16x16x32_bf16 v[76:79], v[204:207], v[188:191], v[76:79]
	v_mfma_f32_16x16x32_bf16 v[72:75], v[212:215], v[188:191], v[72:75]
	v_mfma_f32_16x16x32_bf16 v[68:71], v[204:207], v[196:199], v[68:71]
	v_mfma_f32_16x16x32_bf16 v[64:67], v[212:215], v[196:199], v[64:67]
	v_mfma_f32_16x16x32_bf16 v[92:95], v[208:211], v[176:179], v[92:95]
	v_mfma_f32_16x16x32_bf16 v[88:91], v[216:219], v[176:179], v[88:91]
	v_mfma_f32_16x16x32_bf16 v[84:87], v[208:211], v[184:187], v[84:87]
	v_mfma_f32_16x16x32_bf16 v[80:83], v[216:219], v[184:187], v[80:83]
	v_mfma_f32_16x16x32_bf16 v[76:79], v[208:211], v[192:195], v[76:79]
	v_mfma_f32_16x16x32_bf16 v[72:75], v[216:219], v[192:195], v[72:75]
	v_mfma_f32_16x16x32_bf16 v[68:71], v[208:211], v[200:203], v[68:71]
	v_mfma_f32_16x16x32_bf16 v[64:67], v[216:219], v[200:203], v[64:67]
	s_add_i32 s46, s39, s17
	s_add_i32 s47, s46, 0x100
	s_mov_b32 m0, s0
	s_barrier
	ds_read_b128 v[172:175], v131 offset:16384
	ds_read_b128 v[176:179], v131 offset:17408
	ds_read_b128 v[180:183], v138 offset:16384
	ds_read_b128 v[184:187], v138 offset:17408
	ds_read_b128 v[188:191], v137 offset:16384
	ds_read_b128 v[192:195], v137 offset:17408
	ds_read_b128 v[196:199], v135 offset:16384
	ds_read_b128 v[200:203], v135 offset:17408
	buffer_load_dwordx4 v128, s[4:7], s47 offen lds
	s_mov_b32 m0, s19
	s_nop 0
	buffer_load_dwordx4 v132, s[4:7], s47 offen lds
	s_barrier
	s_waitcnt lgkmcnt(0)
	v_mfma_f32_16x16x32_bf16 v[60:63], v[156:159], v[172:175], v[60:63]
	v_mfma_f32_16x16x32_bf16 v[56:59], v[164:167], v[172:175], v[56:59]
	v_mfma_f32_16x16x32_bf16 v[52:55], v[156:159], v[180:183], v[52:55]
	v_mfma_f32_16x16x32_bf16 v[48:51], v[164:167], v[180:183], v[48:51]
	v_mfma_f32_16x16x32_bf16 v[44:47], v[156:159], v[188:191], v[44:47]
	v_mfma_f32_16x16x32_bf16 v[40:43], v[164:167], v[188:191], v[40:43]
	v_mfma_f32_16x16x32_bf16 v[36:39], v[156:159], v[196:199], v[36:39]
	v_mfma_f32_16x16x32_bf16 v[32:35], v[164:167], v[196:199], v[32:35]
	v_mfma_f32_16x16x32_bf16 v[60:63], v[160:163], v[176:179], v[60:63]
	v_mfma_f32_16x16x32_bf16 v[56:59], v[168:171], v[176:179], v[56:59]
	v_mfma_f32_16x16x32_bf16 v[52:55], v[160:163], v[184:187], v[52:55]
	v_mfma_f32_16x16x32_bf16 v[48:51], v[168:171], v[184:187], v[48:51]
	v_mfma_f32_16x16x32_bf16 v[44:47], v[160:163], v[192:195], v[44:47]
	v_mfma_f32_16x16x32_bf16 v[40:43], v[168:171], v[192:195], v[40:43]
	v_mfma_f32_16x16x32_bf16 v[36:39], v[160:163], v[200:203], v[36:39]
	v_mfma_f32_16x16x32_bf16 v[32:35], v[168:171], v[200:203], v[32:35]
	s_barrier
	s_add_i32 s47, s41, s17
	s_add_i32 s48, s47, 0x100
	s_mov_b32 m0, s20
	s_nop 0
	buffer_load_dwordx4 v130, s[8:11], s48 offen lds
	s_mov_b32 m0, s21
	s_nop 0
	buffer_load_dwordx4 v134, s[8:11], s48 offen lds
	s_waitcnt vmcnt(6)
	s_barrier
; #define STAGE(P, RS, SOFF, OFF, kt) do { const int _so = (SOFF) + (kt) * (BK * 2); \
;     _Pragma("unroll") for (int _i = 0; _i < 2; ++_i) { \
;       __builtin_amdgcn_raw_ptr_buffer_load_lds(RS, (__attribute__((address_space(3))) void*)((P) + wave * 1024 + _i * 8192), 16, OFF[_i], _so, 0, 0); } } while (0)
; #define LDA(dst, b, h) _Pragma("unroll") for (int m = 0; m < 4; ++m) _Pragma("unroll") for (int k = 0; k < 2; ++k) \
;     dst[m][k] = *reinterpret_cast<const bf16x8*>(SA(b, h) + lds_byte(wr * 64 + m * 16 + fr, k * 32 + fq * 8))
; #define LDB(dst, b, h) _Pragma("unroll") for (int n = 0; n < 2; ++n) _Pragma("unroll") for (int k = 0; k < 2; ++k) \
;     dst[n][k] = *reinterpret_cast<const bf16x8*>(SB(b, h) + lds_byte(wc * 32 + n * 16 + fr, k * 32 + fq * 8))
; #define WAIT_V(n) asm volatile("s_waitcnt vmcnt(" #n ")" ::: "memory")
; #define WAIT_L(n) asm volatile("s_waitcnt lgkmcnt(" #n ")" ::: "memory")
; #define BAR __builtin_amdgcn_s_barrier()
; #define SCHED __builtin_amdgcn_sched_barrier(0)
;     ...
;       WAIT_V(6); BAR; MMA(1, 1, At, B1); BAR;
;       LDB(B0, 1, 0); SCHED; LDA(At, 1, 0); STAGE(SA(0, 1), rsA, sA1, offA, t + 2);
;       WAIT_L(8); BAR; WAIT_L(0); MMA(0, 0, At, B0); BAR; SCHED;
;       LDB(B1, 1, 1); STAGE(SB(1, 0), rsB, sB0, offB, t + 3);
;       BAR; WAIT_L(0); MMA(0, 1, At, B1); BAR;
;       LDA(At, 1, 1); STAGE(SA(1, 0), rsA, sA0, offA, t + 3);
;       BAR; WAIT_L(0); MMA(1, 0, At, B0); BAR; SCHED;
	v_mfma_f32_16x16x32_bf16 v[28:31], v[204:207], v[172:175], v[28:31]
	v_mfma_f32_16x16x32_bf16 v[24:27], v[212:215], v[172:175], v[24:27]
	v_mfma_f32_16x16x32_bf16 v[20:23], v[204:207], v[180:183], v[20:23]
	v_mfma_f32_16x16x32_bf16 v[16:19], v[212:215], v[180:183], v[16:19]
	v_mfma_f32_16x16x32_bf16 v[12:15], v[204:207], v[188:191], v[12:15]
	v_mfma_f32_16x16x32_bf16 v[8:11], v[212:215], v[188:191], v[8:11]
	v_mfma_f32_16x16x32_bf16 v[4:7], v[204:207], v[196:199], v[4:7]
	v_mfma_f32_16x16x32_bf16 v[0:3], v[212:215], v[196:199], v[0:3]
	v_mfma_f32_16x16x32_bf16 v[28:31], v[208:211], v[176:179], v[28:31]
	v_mfma_f32_16x16x32_bf16 v[24:27], v[216:219], v[176:179], v[24:27]
	v_mfma_f32_16x16x32_bf16 v[20:23], v[208:211], v[184:187], v[20:23]
	v_mfma_f32_16x16x32_bf16 v[16:19], v[216:219], v[184:187], v[16:19]
	v_mfma_f32_16x16x32_bf16 v[12:15], v[208:211], v[192:195], v[12:15]
	v_mfma_f32_16x16x32_bf16 v[8:11], v[216:219], v[192:195], v[8:11]
	v_mfma_f32_16x16x32_bf16 v[4:7], v[208:211], v[200:203], v[4:7]
	v_mfma_f32_16x16x32_bf16 v[0:3], v[216:219], v[200:203], v[0:3]
	s_barrier
	ds_read_b128 v[156:159], v143
	ds_read_b128 v[160:163], v144
	ds_read_b128 v[164:167], v145
	ds_read_b128 v[168:171], v146
	s_addk_i32 s44, 0x100
	s_mov_b32 m0, s22
	ds_read_b128 v[172:175], v131 offset:32768
	ds_read_b128 v[176:179], v131 offset:33792
	ds_read_b128 v[180:183], v138 offset:32768
	ds_read_b128 v[184:187], v138 offset:33792
	ds_read_b128 v[188:191], v137 offset:32768
	ds_read_b128 v[192:195], v137 offset:33792
	ds_read_b128 v[196:199], v135 offset:32768
	ds_read_b128 v[200:203], v135 offset:33792
	buffer_load_dwordx4 v128, s[4:7], s44 offen lds
	s_mov_b32 m0, s23
	s_nop 0
	buffer_load_dwordx4 v132, s[4:7], s44 offen lds
	s_waitcnt lgkmcnt(8)
	s_barrier
	s_waitcnt lgkmcnt(0)
	v_mfma_f32_16x16x32_bf16 v[124:127], v[156:159], v[172:175], v[124:127]
	v_mfma_f32_16x16x32_bf16 v[120:123], v[164:167], v[172:175], v[120:123]
	v_mfma_f32_16x16x32_bf16 v[116:119], v[156:159], v[180:183], v[116:119]
	v_mfma_f32_16x16x32_bf16 v[112:115], v[164:167], v[180:183], v[112:115]
	v_mfma_f32_16x16x32_bf16 v[108:111], v[156:159], v[188:191], v[108:111]
	v_mfma_f32_16x16x32_bf16 v[104:107], v[164:167], v[188:191], v[104:107]
	v_mfma_f32_16x16x32_bf16 v[100:103], v[156:159], v[196:199], v[100:103]
	v_mfma_f32_16x16x32_bf16 v[96:99], v[164:167], v[196:199], v[96:99]
	v_mfma_f32_16x16x32_bf16 v[124:127], v[160:163], v[176:179], v[124:127]
	v_mfma_f32_16x16x32_bf16 v[120:123], v[168:171], v[176:179], v[120:123]
	v_mfma_f32_16x16x32_bf16 v[116:119], v[160:163], v[184:187], v[116:119]
	v_mfma_f32_16x16x32_bf16 v[112:115], v[168:171], v[184:187], v[112:115]
	v_mfma_f32_16x16x32_bf16 v[108:111], v[160:163], v[192:195], v[108:111]
	v_mfma_f32_16x16x32_bf16 v[104:107], v[168:171], v[192:195], v[104:107]
	v_mfma_f32_16x16x32_bf16 v[100:103], v[160:163], v[200:203], v[100:103]
	v_mfma_f32_16x16x32_bf16 v[96:99], v[168:171], v[200:203], v[96:99]
	s_barrier
	s_addk_i32 s45, 0x180
	s_mov_b32 m0, s24
	ds_read_b128 v[204:207], v139
	ds_read_b128 v[208:211], v140
	ds_read_b128 v[212:215], v141
	ds_read_b128 v[216:219], v142
	buffer_load_dwordx4 v130, s[8:11], s45 offen lds
	s_mov_b32 m0, s25
	s_nop 0
	buffer_load_dwordx4 v134, s[8:11], s45 offen lds
	s_barrier
	s_waitcnt lgkmcnt(0)
	v_mfma_f32_16x16x32_bf16 v[92:95], v[204:207], v[172:175], v[92:95]
	v_mfma_f32_16x16x32_bf16 v[88:91], v[212:215], v[172:175], v[88:91]
	v_mfma_f32_16x16x32_bf16 v[84:87], v[204:207], v[180:183], v[84:87]
	v_mfma_f32_16x16x32_bf16 v[80:83], v[212:215], v[180:183], v[80:83]
	v_mfma_f32_16x16x32_bf16 v[76:79], v[204:207], v[188:191], v[76:79]
	v_mfma_f32_16x16x32_bf16 v[72:75], v[212:215], v[188:191], v[72:75]
	v_mfma_f32_16x16x32_bf16 v[68:71], v[204:207], v[196:199], v[68:71]
	v_mfma_f32_16x16x32_bf16 v[64:67], v[212:215], v[196:199], v[64:67]
	v_mfma_f32_16x16x32_bf16 v[92:95], v[208:211], v[176:179], v[92:95]
	v_mfma_f32_16x16x32_bf16 v[88:91], v[216:219], v[176:179], v[88:91]
	v_mfma_f32_16x16x32_bf16 v[84:87], v[208:211], v[184:187], v[84:87]
	v_mfma_f32_16x16x32_bf16 v[80:83], v[216:219], v[184:187], v[80:83]
	v_mfma_f32_16x16x32_bf16 v[76:79], v[208:211], v[192:195], v[76:79]
	v_mfma_f32_16x16x32_bf16 v[72:75], v[216:219], v[192:195], v[72:75]
	v_mfma_f32_16x16x32_bf16 v[68:71], v[208:211], v[200:203], v[68:71]
	v_mfma_f32_16x16x32_bf16 v[64:67], v[216:219], v[200:203], v[64:67]
	s_addk_i32 s46, 0x180
	s_mov_b32 m0, s26
	s_barrier
	ds_read_b128 v[172:175], v131 offset:49152
	ds_read_b128 v[176:179], v131 offset:50176
	ds_read_b128 v[180:183], v138 offset:49152
	ds_read_b128 v[184:187], v138 offset:50176
	ds_read_b128 v[188:191], v137 offset:49152
	ds_read_b128 v[192:195], v137 offset:50176
	ds_read_b128 v[196:199], v135 offset:49152
	ds_read_b128 v[200:203], v135 offset:50176
	buffer_load_dwordx4 v128, s[4:7], s46 offen lds
	s_mov_b32 m0, s27
	s_nop 0
	buffer_load_dwordx4 v132, s[4:7], s46 offen lds
	s_barrier
	s_waitcnt lgkmcnt(0)
	v_mfma_f32_16x16x32_bf16 v[60:63], v[156:159], v[172:175], v[60:63]
	v_mfma_f32_16x16x32_bf16 v[56:59], v[164:167], v[172:175], v[56:59]
	v_mfma_f32_16x16x32_bf16 v[52:55], v[156:159], v[180:183], v[52:55]
	v_mfma_f32_16x16x32_bf16 v[48:51], v[164:167], v[180:183], v[48:51]
	v_mfma_f32_16x16x32_bf16 v[44:47], v[156:159], v[188:191], v[44:47]
	v_mfma_f32_16x16x32_bf16 v[40:43], v[164:167], v[188:191], v[40:43]
	v_mfma_f32_16x16x32_bf16 v[36:39], v[156:159], v[196:199], v[36:39]
	v_mfma_f32_16x16x32_bf16 v[32:35], v[164:167], v[196:199], v[32:35]
	v_mfma_f32_16x16x32_bf16 v[60:63], v[160:163], v[176:179], v[60:63]
	v_mfma_f32_16x16x32_bf16 v[56:59], v[168:171], v[176:179], v[56:59]
	v_mfma_f32_16x16x32_bf16 v[52:55], v[160:163], v[184:187], v[52:55]
	v_mfma_f32_16x16x32_bf16 v[48:51], v[168:171], v[184:187], v[48:51]
	v_mfma_f32_16x16x32_bf16 v[44:47], v[160:163], v[192:195], v[44:47]
	v_mfma_f32_16x16x32_bf16 v[40:43], v[168:171], v[192:195], v[40:43]
	v_mfma_f32_16x16x32_bf16 v[36:39], v[160:163], v[200:203], v[36:39]
	v_mfma_f32_16x16x32_bf16 v[32:35], v[168:171], v[200:203], v[32:35]
	s_barrier
; #define STAGE(P, RS, SOFF, OFF, kt) do { const int _so = (SOFF) + (kt) * (BK * 2); \
;     _Pragma("unroll") for (int _i = 0; _i < 2; ++_i) { \
;       __builtin_amdgcn_raw_ptr_buffer_load_lds(RS, (__attribute__((address_space(3))) void*)((P) + wave * 1024 + _i * 8192), 16, OFF[_i], _so, 0, 0); } } while (0)
; #define LDA(dst, b, h) _Pragma("unroll") for (int m = 0; m < 4; ++m) _Pragma("unroll") for (int k = 0; k < 2; ++k) \
;     dst[m][k] = *reinterpret_cast<const bf16x8*>(SA(b, h) + lds_byte(wr * 64 + m * 16 + fr, k * 32 + fq * 8))
; #define LDB(dst, b, h) _Pragma("unroll") for (int n = 0; n < 2; ++n) _Pragma("unroll") for (int k = 0; k < 2; ++k) \
;     dst[n][k] = *reinterpret_cast<const bf16x8*>(SB(b, h) + lds_byte(wc * 32 + n * 16 + fr, k * 32 + fq * 8))
; #define WAIT_V(n) asm volatile("s_waitcnt vmcnt(" #n ")" ::: "memory")
; #define WAIT_L(n) asm volatile("s_waitcnt lgkmcnt(" #n ")" ::: "memory")
; #define BAR __builtin_amdgcn_s_barrier()
;     ...
;       STAGE(SB(1, 1), rsB, sB1, offB, t + 3);
;       WAIT_V(6); BAR; MMA(1, 1, At, B1); BAR;
;     }
;     { LDB(B0, 0, 0); LDA(At, 0, 0); STAGE(SA(1, 1), rsA, sA1, offA, nt - 1);
;       BAR; WAIT_L(0); MMA(0, 0, At, B0); BAR;
;       LDB(B1, 0, 1); BAR; WAIT_L(0); MMA(0, 1, At, B1); BAR;
;       LDA(At, 0, 1); WAIT_V(4); BAR; WAIT_L(0); MMA(1, 0, At, B0); MMA(1, 1, At, B1); BAR; }
	s_addk_i32 s47, 0x180
	s_mov_b32 m0, s28
	s_nop 0
	buffer_load_dwordx4 v130, s[8:11], s47 offen lds
	s_mov_b32 m0, s29
	s_nop 0
	buffer_load_dwordx4 v134, s[8:11], s47 offen lds
	s_waitcnt vmcnt(6)
	s_barrier
	v_mfma_f32_16x16x32_bf16 v[28:31], v[204:207], v[172:175], v[28:31]
	v_mfma_f32_16x16x32_bf16 v[24:27], v[212:215], v[172:175], v[24:27]
	v_mfma_f32_16x16x32_bf16 v[20:23], v[204:207], v[180:183], v[20:23]
	v_mfma_f32_16x16x32_bf16 v[16:19], v[212:215], v[180:183], v[16:19]
	v_mfma_f32_16x16x32_bf16 v[12:15], v[204:207], v[188:191], v[12:15]
	v_mfma_f32_16x16x32_bf16 v[8:11], v[212:215], v[188:191], v[8:11]
	v_mfma_f32_16x16x32_bf16 v[4:7], v[204:207], v[196:199], v[4:7]
	v_mfma_f32_16x16x32_bf16 v[0:3], v[212:215], v[196:199], v[0:3]
	v_mfma_f32_16x16x32_bf16 v[28:31], v[208:211], v[176:179], v[28:31]
	v_mfma_f32_16x16x32_bf16 v[24:27], v[216:219], v[176:179], v[24:27]
	v_mfma_f32_16x16x32_bf16 v[20:23], v[208:211], v[184:187], v[20:23]
	v_mfma_f32_16x16x32_bf16 v[16:19], v[216:219], v[184:187], v[16:19]
	v_mfma_f32_16x16x32_bf16 v[12:15], v[208:211], v[192:195], v[12:15]
	v_mfma_f32_16x16x32_bf16 v[8:11], v[216:219], v[192:195], v[8:11]
	v_mfma_f32_16x16x32_bf16 v[4:7], v[208:211], v[200:203], v[4:7]
	v_mfma_f32_16x16x32_bf16 v[0:3], v[216:219], v[200:203], v[0:3]
	s_add_i32 s16, s16, 2
	s_addk_i32 s17, 0x100
	s_cmp_gt_u32 s16, 3
	s_barrier
	s_cbranch_scc0 .LBB0_110
	s_add_i32 s10, s38, 0x380
	s_mov_b32 m0, s31
	ds_read_b128 v[156:159], v151
	ds_read_b128 v[160:163], v152
	ds_read_b128 v[164:167], v153
	ds_read_b128 v[152:155], v154
	ds_read_b128 v[168:171], v131
	ds_read_b128 v[172:175], v131 offset:1024
	ds_read_b128 v[176:179], v138
	ds_read_b128 v[180:183], v138 offset:1024
	ds_read_b128 v[184:187], v137
	ds_read_b128 v[188:191], v137 offset:1024
	ds_read_b128 v[192:195], v135
	ds_read_b128 v[196:199], v135 offset:1024
	buffer_load_dwordx4 v128, s[4:7], s10 offen lds
	s_mov_b32 m0, s33
	s_nop 0
	buffer_load_dwordx4 v132, s[4:7], s10 offen lds
	s_barrier
	s_waitcnt lgkmcnt(0)
	v_mfma_f32_16x16x32_bf16 v[124:127], v[156:159], v[168:171], v[124:127]
	v_mfma_f32_16x16x32_bf16 v[120:123], v[164:167], v[168:171], v[120:123]
	v_mfma_f32_16x16x32_bf16 v[116:119], v[156:159], v[176:179], v[116:119]
	v_mfma_f32_16x16x32_bf16 v[112:115], v[164:167], v[176:179], v[112:115]
	v_mfma_f32_16x16x32_bf16 v[108:111], v[156:159], v[184:187], v[108:111]
	v_mfma_f32_16x16x32_bf16 v[104:107], v[164:167], v[184:187], v[104:107]
	v_mfma_f32_16x16x32_bf16 v[100:103], v[156:159], v[192:195], v[100:103]
	v_mfma_f32_16x16x32_bf16 v[96:99], v[164:167], v[192:195], v[96:99]
	v_mfma_f32_16x16x32_bf16 v[124:127], v[160:163], v[172:175], v[124:127]
	v_mfma_f32_16x16x32_bf16 v[120:123], v[152:155], v[172:175], v[120:123]
	v_mfma_f32_16x16x32_bf16 v[116:119], v[160:163], v[180:183], v[116:119]
	v_mfma_f32_16x16x32_bf16 v[112:115], v[152:155], v[180:183], v[112:115]
	v_mfma_f32_16x16x32_bf16 v[108:111], v[160:163], v[188:191], v[108:111]
	v_mfma_f32_16x16x32_bf16 v[104:107], v[152:155], v[188:191], v[104:107]
	v_mfma_f32_16x16x32_bf16 v[100:103], v[160:163], v[196:199], v[100:103]
	v_mfma_f32_16x16x32_bf16 v[96:99], v[152:155], v[196:199], v[96:99]
	s_barrier
	ds_read_b128 v[200:203], v147
	ds_read_b128 v[204:207], v148
	ds_read_b128 v[208:211], v149
	ds_read_b128 v[148:151], v150
	s_barrier
	s_waitcnt lgkmcnt(0)
	v_mfma_f32_16x16x32_bf16 v[92:95], v[200:203], v[168:171], v[92:95]
	v_mfma_f32_16x16x32_bf16 v[88:91], v[208:211], v[168:171], v[88:91]
	v_mfma_f32_16x16x32_bf16 v[84:87], v[200:203], v[176:179], v[84:87]
	v_mfma_f32_16x16x32_bf16 v[80:83], v[208:211], v[176:179], v[80:83]
	v_mfma_f32_16x16x32_bf16 v[76:79], v[200:203], v[184:187], v[76:79]
	v_mfma_f32_16x16x32_bf16 v[72:75], v[208:211], v[184:187], v[72:75]
	v_mfma_f32_16x16x32_bf16 v[68:71], v[200:203], v[192:195], v[68:71]
	v_mfma_f32_16x16x32_bf16 v[64:67], v[208:211], v[192:195], v[64:67]
	v_mfma_f32_16x16x32_bf16 v[92:95], v[204:207], v[172:175], v[92:95]
	v_mfma_f32_16x16x32_bf16 v[88:91], v[148:151], v[172:175], v[88:91]
	v_mfma_f32_16x16x32_bf16 v[84:87], v[204:207], v[180:183], v[84:87]
	v_mfma_f32_16x16x32_bf16 v[80:83], v[148:151], v[180:183], v[80:83]
	v_mfma_f32_16x16x32_bf16 v[76:79], v[204:207], v[188:191], v[76:79]
	v_mfma_f32_16x16x32_bf16 v[72:75], v[148:151], v[188:191], v[72:75]
	v_mfma_f32_16x16x32_bf16 v[68:71], v[204:207], v[196:199], v[68:71]
	v_mfma_f32_16x16x32_bf16 v[64:67], v[148:151], v[196:199], v[64:67]
	s_barrier
	ds_read_b128 v[168:171], v131 offset:16384
	ds_read_b128 v[172:175], v131 offset:17408
	ds_read_b128 v[176:179], v138 offset:16384
	ds_read_b128 v[180:183], v138 offset:17408
	ds_read_b128 v[184:187], v137 offset:16384
	ds_read_b128 v[188:191], v137 offset:17408
	ds_read_b128 v[192:195], v135 offset:16384
	ds_read_b128 v[196:199], v135 offset:17408
	s_waitcnt vmcnt(4)
	s_barrier
; #define LDA(dst, b, h) _Pragma("unroll") for (int m = 0; m < 4; ++m) _Pragma("unroll") for (int k = 0; k < 2; ++k) \
;     dst[m][k] = *reinterpret_cast<const bf16x8*>(SA(b, h) + lds_byte(wr * 64 + m * 16 + fr, k * 32 + fq * 8))
; #define LDB(dst, b, h) _Pragma("unroll") for (int n = 0; n < 2; ++n) _Pragma("unroll") for (int k = 0; k < 2; ++k) \
;     dst[n][k] = *reinterpret_cast<const bf16x8*>(SB(b, h) + lds_byte(wc * 32 + n * 16 + fr, k * 32 + fq * 8))
; #define WAIT_V(n) asm volatile("s_waitcnt vmcnt(" #n ")" ::: "memory")
; #define WAIT_L(n) asm volatile("s_waitcnt lgkmcnt(" #n ")" ::: "memory")
; #define BAR __builtin_amdgcn_s_barrier()
;     ...
;       LDA(At, 0, 1); WAIT_V(4); BAR; WAIT_L(0); MMA(1, 0, At, B0); MMA(1, 1, At, B1); BAR; }
;     { LDB(B0, 1, 0); LDA(At, 1, 0); WAIT_V(2); BAR; WAIT_L(0); MMA(0, 0, At, B0); BAR;
	s_waitcnt lgkmcnt(0)
	v_mfma_f32_16x16x32_bf16 v[60:63], v[156:159], v[168:171], v[60:63]
	v_mfma_f32_16x16x32_bf16 v[56:59], v[164:167], v[168:171], v[56:59]
	v_mfma_f32_16x16x32_bf16 v[52:55], v[156:159], v[176:179], v[52:55]
	v_mfma_f32_16x16x32_bf16 v[48:51], v[164:167], v[176:179], v[48:51]
	v_mfma_f32_16x16x32_bf16 v[44:47], v[156:159], v[184:187], v[44:47]
	v_mfma_f32_16x16x32_bf16 v[40:43], v[164:167], v[184:187], v[40:43]
	v_mfma_f32_16x16x32_bf16 v[36:39], v[156:159], v[192:195], v[36:39]
	v_mfma_f32_16x16x32_bf16 v[32:35], v[164:167], v[192:195], v[32:35]
	v_mfma_f32_16x16x32_bf16 v[60:63], v[160:163], v[172:175], v[60:63]
	v_mfma_f32_16x16x32_bf16 v[56:59], v[152:155], v[172:175], v[56:59]
	v_mfma_f32_16x16x32_bf16 v[52:55], v[160:163], v[180:183], v[52:55]
	v_mfma_f32_16x16x32_bf16 v[48:51], v[152:155], v[180:183], v[48:51]
	v_mfma_f32_16x16x32_bf16 v[44:47], v[160:163], v[188:191], v[44:47]
	v_mfma_f32_16x16x32_bf16 v[40:43], v[152:155], v[188:191], v[40:43]
	v_mfma_f32_16x16x32_bf16 v[36:39], v[160:163], v[196:199], v[36:39]
	v_mfma_f32_16x16x32_bf16 v[32:35], v[152:155], v[196:199], v[32:35]
	v_mfma_f32_16x16x32_bf16 v[28:31], v[200:203], v[168:171], v[28:31]
	v_mfma_f32_16x16x32_bf16 v[24:27], v[208:211], v[168:171], v[24:27]
	v_mfma_f32_16x16x32_bf16 v[20:23], v[200:203], v[176:179], v[20:23]
	v_mfma_f32_16x16x32_bf16 v[16:19], v[208:211], v[176:179], v[16:19]
	v_mfma_f32_16x16x32_bf16 v[12:15], v[200:203], v[184:187], v[12:15]
	v_mfma_f32_16x16x32_bf16 v[8:11], v[208:211], v[184:187], v[8:11]
	v_mfma_f32_16x16x32_bf16 v[4:7], v[200:203], v[192:195], v[4:7]
	v_mfma_f32_16x16x32_bf16 v[0:3], v[208:211], v[192:195], v[0:3]
	v_mfma_f32_16x16x32_bf16 v[28:31], v[204:207], v[172:175], v[28:31]
	v_mfma_f32_16x16x32_bf16 v[24:27], v[148:151], v[172:175], v[24:27]
	v_mfma_f32_16x16x32_bf16 v[20:23], v[204:207], v[180:183], v[20:23]
	v_mfma_f32_16x16x32_bf16 v[16:19], v[148:151], v[180:183], v[16:19]
	v_mfma_f32_16x16x32_bf16 v[12:15], v[204:207], v[188:191], v[12:15]
	v_mfma_f32_16x16x32_bf16 v[8:11], v[148:151], v[188:191], v[8:11]
	v_mfma_f32_16x16x32_bf16 v[4:7], v[204:207], v[196:199], v[4:7]
	v_mfma_f32_16x16x32_bf16 v[0:3], v[148:151], v[196:199], v[0:3]
	s_barrier
	ds_read_b128 v[148:151], v143
	ds_read_b128 v[152:155], v144
	ds_read_b128 v[156:159], v145
	ds_read_b128 v[144:147], v146
	ds_read_b128 v[160:163], v131 offset:32768
	ds_read_b128 v[164:167], v131 offset:33792
	ds_read_b128 v[168:171], v138 offset:32768
	ds_read_b128 v[172:175], v138 offset:33792
	ds_read_b128 v[176:179], v137 offset:32768
	ds_read_b128 v[180:183], v137 offset:33792
	ds_read_b128 v[184:187], v135 offset:32768
	ds_read_b128 v[188:191], v135 offset:33792
	s_waitcnt vmcnt(2)
	s_barrier
	s_waitcnt lgkmcnt(0)
	v_mfma_f32_16x16x32_bf16 v[124:127], v[148:151], v[160:163], v[124:127]
	v_mfma_f32_16x16x32_bf16 v[120:123], v[156:159], v[160:163], v[120:123]
	v_mfma_f32_16x16x32_bf16 v[116:119], v[148:151], v[168:171], v[116:119]
	v_mfma_f32_16x16x32_bf16 v[112:115], v[156:159], v[168:171], v[112:115]
	v_mfma_f32_16x16x32_bf16 v[108:111], v[148:151], v[176:179], v[108:111]
	v_mfma_f32_16x16x32_bf16 v[104:107], v[156:159], v[176:179], v[104:107]
	v_mfma_f32_16x16x32_bf16 v[100:103], v[148:151], v[184:187], v[100:103]
	v_mfma_f32_16x16x32_bf16 v[96:99], v[156:159], v[184:187], v[96:99]
	v_mfma_f32_16x16x32_bf16 v[124:127], v[152:155], v[164:167], v[124:127]
	v_mfma_f32_16x16x32_bf16 v[120:123], v[144:147], v[164:167], v[120:123]
	v_mfma_f32_16x16x32_bf16 v[116:119], v[152:155], v[172:175], v[116:119]
	v_mfma_f32_16x16x32_bf16 v[112:115], v[144:147], v[172:175], v[112:115]
	v_mfma_f32_16x16x32_bf16 v[108:111], v[152:155], v[180:183], v[108:111]
	v_mfma_f32_16x16x32_bf16 v[104:107], v[144:147], v[180:183], v[104:107]
	v_mfma_f32_16x16x32_bf16 v[100:103], v[152:155], v[188:191], v[100:103]
	v_mfma_f32_16x16x32_bf16 v[96:99], v[144:147], v[188:191], v[96:99]
	s_barrier
; #define LDA(dst, b, h) _Pragma("unroll") for (int m = 0; m < 4; ++m) _Pragma("unroll") for (int k = 0; k < 2; ++k) \
;     dst[m][k] = *reinterpret_cast<const bf16x8*>(SA(b, h) + lds_byte(wr * 64 + m * 16 + fr, k * 32 + fq * 8))
; #define LDB(dst, b, h) _Pragma("unroll") for (int n = 0; n < 2; ++n) _Pragma("unroll") for (int k = 0; k < 2; ++k) \
;     dst[n][k] = *reinterpret_cast<const bf16x8*>(SB(b, h) + lds_byte(wc * 32 + n * 16 + fr, k * 32 + fq * 8))
; #define WAIT_V(n) asm volatile("s_waitcnt vmcnt(" #n ")" ::: "memory")
; #define WAIT_L(n) asm volatile("s_waitcnt lgkmcnt(" #n ")" ::: "memory")
; #define BAR __builtin_amdgcn_s_barrier()
;     ...
;       LDB(B1, 1, 1); WAIT_V(0); BAR; WAIT_L(0); MMA(0, 1, At, B1); BAR;
;       LDA(At, 1, 1); BAR; WAIT_L(0); MMA(1, 0, At, B0); MMA(1, 1, At, B1); BAR; }
;     if (wr == 0) BAR;
	ds_read_b128 v[192:195], v139
	ds_read_b128 v[196:199], v140
	ds_read_b128 v[200:203], v141
	ds_read_b128 v[140:143], v142
	s_waitcnt vmcnt(0)
	s_barrier
	s_waitcnt lgkmcnt(0)
	v_mfma_f32_16x16x32_bf16 v[92:95], v[192:195], v[160:163], v[92:95]
	v_mfma_f32_16x16x32_bf16 v[88:91], v[200:203], v[160:163], v[88:91]
	v_mfma_f32_16x16x32_bf16 v[84:87], v[192:195], v[168:171], v[84:87]
	v_mfma_f32_16x16x32_bf16 v[80:83], v[200:203], v[168:171], v[80:83]
	v_mfma_f32_16x16x32_bf16 v[76:79], v[192:195], v[176:179], v[76:79]
	v_mfma_f32_16x16x32_bf16 v[72:75], v[200:203], v[176:179], v[72:75]
	v_mfma_f32_16x16x32_bf16 v[68:71], v[192:195], v[184:187], v[68:71]
	v_mfma_f32_16x16x32_bf16 v[64:67], v[200:203], v[184:187], v[64:67]
	v_mfma_f32_16x16x32_bf16 v[92:95], v[196:199], v[164:167], v[92:95]
	v_mfma_f32_16x16x32_bf16 v[88:91], v[140:143], v[164:167], v[88:91]
	v_mfma_f32_16x16x32_bf16 v[84:87], v[196:199], v[172:175], v[84:87]
	v_mfma_f32_16x16x32_bf16 v[80:83], v[140:143], v[172:175], v[80:83]
	v_mfma_f32_16x16x32_bf16 v[76:79], v[196:199], v[180:183], v[76:79]
	v_mfma_f32_16x16x32_bf16 v[72:75], v[140:143], v[180:183], v[72:75]
	v_mfma_f32_16x16x32_bf16 v[68:71], v[196:199], v[188:191], v[68:71]
	v_mfma_f32_16x16x32_bf16 v[64:67], v[140:143], v[188:191], v[64:67]
	s_barrier
	ds_read_b128 v[160:163], v131 offset:49152
	ds_read_b128 v[164:167], v131 offset:50176
	ds_read_b128 v[168:171], v138 offset:49152
	ds_read_b128 v[172:175], v138 offset:50176
	ds_read_b128 v[176:179], v137 offset:49152
	ds_read_b128 v[180:183], v137 offset:50176
	ds_read_b128 v[184:187], v135 offset:49152
	ds_read_b128 v[188:191], v135 offset:50176
	s_barrier
	s_waitcnt lgkmcnt(0)
	v_mfma_f32_16x16x32_bf16 v[60:63], v[148:151], v[160:163], v[60:63]
	v_mfma_f32_16x16x32_bf16 v[56:59], v[156:159], v[160:163], v[56:59]
	v_mfma_f32_16x16x32_bf16 v[52:55], v[148:151], v[168:171], v[52:55]
	v_mfma_f32_16x16x32_bf16 v[48:51], v[156:159], v[168:171], v[48:51]
	v_mfma_f32_16x16x32_bf16 v[44:47], v[148:151], v[176:179], v[44:47]
	v_mfma_f32_16x16x32_bf16 v[40:43], v[156:159], v[176:179], v[40:43]
	v_mfma_f32_16x16x32_bf16 v[36:39], v[148:151], v[184:187], v[36:39]
	v_mfma_f32_16x16x32_bf16 v[32:35], v[156:159], v[184:187], v[32:35]
	v_mfma_f32_16x16x32_bf16 v[60:63], v[152:155], v[164:167], v[60:63]
	v_mfma_f32_16x16x32_bf16 v[56:59], v[144:147], v[164:167], v[56:59]
	v_mfma_f32_16x16x32_bf16 v[52:55], v[152:155], v[172:175], v[52:55]
	v_mfma_f32_16x16x32_bf16 v[48:51], v[144:147], v[172:175], v[48:51]
	v_mfma_f32_16x16x32_bf16 v[44:47], v[152:155], v[180:183], v[44:47]
	v_mfma_f32_16x16x32_bf16 v[40:43], v[144:147], v[180:183], v[40:43]
	v_mfma_f32_16x16x32_bf16 v[36:39], v[152:155], v[188:191], v[36:39]
	v_mfma_f32_16x16x32_bf16 v[32:35], v[144:147], v[188:191], v[32:35]
	v_mfma_f32_16x16x32_bf16 v[28:31], v[192:195], v[160:163], v[28:31]
	v_mfma_f32_16x16x32_bf16 v[24:27], v[200:203], v[160:163], v[24:27]
	v_mfma_f32_16x16x32_bf16 v[20:23], v[192:195], v[168:171], v[20:23]
	v_mfma_f32_16x16x32_bf16 v[16:19], v[200:203], v[168:171], v[16:19]
	v_mfma_f32_16x16x32_bf16 v[12:15], v[192:195], v[176:179], v[12:15]
	v_mfma_f32_16x16x32_bf16 v[8:11], v[200:203], v[176:179], v[8:11]
	v_mfma_f32_16x16x32_bf16 v[4:7], v[192:195], v[184:187], v[4:7]
	v_mfma_f32_16x16x32_bf16 v[0:3], v[200:203], v[184:187], v[0:3]
	v_mfma_f32_16x16x32_bf16 v[28:31], v[196:199], v[164:167], v[28:31]
	v_mfma_f32_16x16x32_bf16 v[24:27], v[140:143], v[164:167], v[24:27]
	v_mfma_f32_16x16x32_bf16 v[20:23], v[196:199], v[172:175], v[20:23]
	v_mfma_f32_16x16x32_bf16 v[16:19], v[140:143], v[172:175], v[16:19]
	v_mfma_f32_16x16x32_bf16 v[12:15], v[196:199], v[180:183], v[12:15]
	v_mfma_f32_16x16x32_bf16 v[8:11], v[140:143], v[180:183], v[8:11]
	v_mfma_f32_16x16x32_bf16 v[4:7], v[196:199], v[188:191], v[4:7]
	v_mfma_f32_16x16x32_bf16 v[0:3], v[140:143], v[188:191], v[0:3]
	v_cmp_gt_u32_e32 vcc, s36, v136
	s_barrier
	s_and_saveexec_b64 s[10:11], vcc
	s_cbranch_execz .LBB0_113
	s_barrier

; #define STAGE(P, RS, SOFF, OFF, kt) do { const int _so = (SOFF) + (kt) * (BK * 2); \
;     _Pragma("unroll") for (int _i = 0; _i < 2; ++_i) { \
;       __builtin_amdgcn_raw_ptr_buffer_load_lds(RS, (__attribute__((address_space(3))) void*)((P) + wave * 1024 + _i * 8192), 16, OFF[_i], _so, 0, 0); } } while (0)
; #define LDA(dst, b, h) _Pragma("unroll") for (int m = 0; m < 4; ++m) _Pragma("unroll") for (int k = 0; k < 2; ++k) \
;     dst[m][k] = *reinterpret_cast<const bf16x8*>(SA(b, h) + lds_byte(wr * 64 + m * 16 + fr, k * 32 + fq * 8))
; #define LDB(dst, b, h) _Pragma("unroll") for (int n = 0; n < 2; ++n) _Pragma("unroll") for (int k = 0; k < 2; ++k) \
;     dst[n][k] = *reinterpret_cast<const bf16x8*>(SB(b, h) + lds_byte(wc * 32 + n * 16 + fr, k * 32 + fq * 8))
; #define WAIT_V(n) asm volatile("s_waitcnt vmcnt(" #n ")" ::: "memory")
; #define WAIT_L(n) asm volatile("s_waitcnt lgkmcnt(" #n ")" ::: "memory")
; #define BAR __builtin_amdgcn_s_barrier()
; #define SCHED __builtin_amdgcn_sched_barrier(0)
;     ...
;       LDB(B0, 0, 0); SCHED; LDA(At, 0, 0); STAGE(SA(1, 1), rsA, sA1, offA, t + 1);
;       WAIT_L(8); BAR; WAIT_L(0); MMA(0, 0, At, B0); BAR; SCHED;
;       LDB(B1, 0, 1); STAGE(SB(0, 0), rsB, sB0, offB, t + 2);
;       BAR; WAIT_L(0); MMA(0, 1, At, B1); BAR;
;       LDA(At, 0, 1); STAGE(SA(0, 0), rsA, sA0, offA, t + 2);
;       BAR; WAIT_L(0); MMA(1, 0, At, B0); BAR; SCHED;
;       STAGE(SB(0, 1), rsB, sB1, offB, t + 2);
;       WAIT_V(6); BAR; MMA(1, 1, At, B1); BAR;
.LBB0_148:
	ds_read_b128 v[152:155], v147
	ds_read_b128 v[156:159], v148
	ds_read_b128 v[160:163], v149
	ds_read_b128 v[164:167], v150
	s_add_i32 s4, s82, s3
	s_add_i32 s5, s4, 0x80
	s_mov_b32 m0, s31
	ds_read_b128 v[168:171], v129
	ds_read_b128 v[172:175], v129 offset:1024
	ds_read_b128 v[176:179], v132
	ds_read_b128 v[180:183], v132 offset:1024
	ds_read_b128 v[184:187], v131
	ds_read_b128 v[188:191], v131 offset:1024
	ds_read_b128 v[192:195], v130
	ds_read_b128 v[196:199], v130 offset:1024
	buffer_load_dwordx4 v141, s[8:11], s5 offen lds
	s_mov_b32 m0, s58
	s_nop 0
	buffer_load_dwordx4 v142, s[8:11], s5 offen lds
	s_waitcnt lgkmcnt(8)
	s_barrier
	s_waitcnt lgkmcnt(0)
	v_mfma_f32_16x16x32_bf16 v[124:127], v[152:155], v[168:171], v[124:127]
	v_mfma_f32_16x16x32_bf16 v[120:123], v[160:163], v[168:171], v[120:123]
	v_mfma_f32_16x16x32_bf16 v[116:119], v[152:155], v[176:179], v[116:119]
	v_mfma_f32_16x16x32_bf16 v[112:115], v[160:163], v[176:179], v[112:115]
	v_mfma_f32_16x16x32_bf16 v[108:111], v[152:155], v[184:187], v[108:111]
	v_mfma_f32_16x16x32_bf16 v[104:107], v[160:163], v[184:187], v[104:107]
	v_mfma_f32_16x16x32_bf16 v[100:103], v[152:155], v[192:195], v[100:103]
	v_mfma_f32_16x16x32_bf16 v[96:99], v[160:163], v[192:195], v[96:99]
	v_mfma_f32_16x16x32_bf16 v[124:127], v[156:159], v[172:175], v[124:127]
	v_mfma_f32_16x16x32_bf16 v[120:123], v[164:167], v[172:175], v[120:123]
	v_mfma_f32_16x16x32_bf16 v[116:119], v[156:159], v[180:183], v[116:119]
	v_mfma_f32_16x16x32_bf16 v[112:115], v[164:167], v[180:183], v[112:115]
	v_mfma_f32_16x16x32_bf16 v[108:111], v[156:159], v[188:191], v[108:111]
	v_mfma_f32_16x16x32_bf16 v[104:107], v[164:167], v[188:191], v[104:107]
	v_mfma_f32_16x16x32_bf16 v[100:103], v[156:159], v[196:199], v[100:103]
	v_mfma_f32_16x16x32_bf16 v[96:99], v[164:167], v[196:199], v[96:99]
	s_barrier
	s_add_i32 s5, s84, s3
	s_add_i32 s6, s5, 0x100
	s_mov_b32 s14, s10
	s_mov_b32 s15, s11
	s_mov_b32 m0, s34
	ds_read_b128 v[200:203], v143
	ds_read_b128 v[204:207], v144
	ds_read_b128 v[208:211], v145
	ds_read_b128 v[212:215], v146
	buffer_load_dwordx4 v141, s[12:15], s6 offen lds
	s_mov_b32 m0, s43
	s_nop 0
	buffer_load_dwordx4 v142, s[12:15], s6 offen lds
	s_barrier
	s_waitcnt lgkmcnt(0)
	v_mfma_f32_16x16x32_bf16 v[92:95], v[200:203], v[168:171], v[92:95]
	v_mfma_f32_16x16x32_bf16 v[88:91], v[208:211], v[168:171], v[88:91]
	v_mfma_f32_16x16x32_bf16 v[80:83], v[200:203], v[176:179], v[80:83]
	v_mfma_f32_16x16x32_bf16 v[68:71], v[208:211], v[176:179], v[68:71]
	v_mfma_f32_16x16x32_bf16 v[60:63], v[200:203], v[184:187], v[60:63]
	v_mfma_f32_16x16x32_bf16 v[56:59], v[208:211], v[184:187], v[56:59]
	v_mfma_f32_16x16x32_bf16 v[52:55], v[200:203], v[192:195], v[52:55]
	v_mfma_f32_16x16x32_bf16 v[48:51], v[208:211], v[192:195], v[48:51]
	v_mfma_f32_16x16x32_bf16 v[92:95], v[204:207], v[172:175], v[92:95]
	v_mfma_f32_16x16x32_bf16 v[88:91], v[212:215], v[172:175], v[88:91]
	v_mfma_f32_16x16x32_bf16 v[80:83], v[204:207], v[180:183], v[80:83]
	v_mfma_f32_16x16x32_bf16 v[68:71], v[212:215], v[180:183], v[68:71]
	v_mfma_f32_16x16x32_bf16 v[60:63], v[204:207], v[188:191], v[60:63]
	v_mfma_f32_16x16x32_bf16 v[56:59], v[212:215], v[188:191], v[56:59]
	v_mfma_f32_16x16x32_bf16 v[52:55], v[204:207], v[196:199], v[52:55]
	v_mfma_f32_16x16x32_bf16 v[48:51], v[212:215], v[196:199], v[48:51]
	s_add_i32 s6, s83, s3
	s_add_i32 s7, s6, 0x100
	s_mov_b32 m0, s30
	s_barrier
	ds_read_b128 v[168:171], v129 offset:16384
	ds_read_b128 v[172:175], v129 offset:17408
	ds_read_b128 v[176:179], v132 offset:16384
	ds_read_b128 v[180:183], v132 offset:17408
	ds_read_b128 v[184:187], v131 offset:16384
	ds_read_b128 v[188:191], v131 offset:17408
	ds_read_b128 v[192:195], v130 offset:16384
	ds_read_b128 v[196:199], v130 offset:17408
	buffer_load_dwordx4 v141, s[8:11], s7 offen lds
	s_mov_b32 m0, s44
	s_nop 0
	buffer_load_dwordx4 v142, s[8:11], s7 offen lds
	s_barrier
	s_waitcnt lgkmcnt(0)
	v_mfma_f32_16x16x32_bf16 v[44:47], v[152:155], v[168:171], v[44:47]
	v_mfma_f32_16x16x32_bf16 v[40:43], v[160:163], v[168:171], v[40:43]
	v_mfma_f32_16x16x32_bf16 v[36:39], v[152:155], v[176:179], v[36:39]
	v_mfma_f32_16x16x32_bf16 v[32:35], v[160:163], v[176:179], v[32:35]
	v_mfma_f32_16x16x32_bf16 v[28:31], v[152:155], v[184:187], v[28:31]
	v_mfma_f32_16x16x32_bf16 v[24:27], v[160:163], v[184:187], v[24:27]
	v_mfma_f32_16x16x32_bf16 v[20:23], v[152:155], v[192:195], v[20:23]
	v_mfma_f32_16x16x32_bf16 v[16:19], v[160:163], v[192:195], v[16:19]
	v_mfma_f32_16x16x32_bf16 v[44:47], v[156:159], v[172:175], v[44:47]
	v_mfma_f32_16x16x32_bf16 v[40:43], v[164:167], v[172:175], v[40:43]
	v_mfma_f32_16x16x32_bf16 v[36:39], v[156:159], v[180:183], v[36:39]
	v_mfma_f32_16x16x32_bf16 v[32:35], v[164:167], v[180:183], v[32:35]
	v_mfma_f32_16x16x32_bf16 v[28:31], v[156:159], v[188:191], v[28:31]
	v_mfma_f32_16x16x32_bf16 v[24:27], v[164:167], v[188:191], v[24:27]
	v_mfma_f32_16x16x32_bf16 v[20:23], v[156:159], v[196:199], v[20:23]
	v_mfma_f32_16x16x32_bf16 v[16:19], v[164:167], v[196:199], v[16:19]
	s_barrier
	s_add_i32 s7, s85, s3
	s_add_i32 s19, s7, 0x100
	s_mov_b32 m0, s35
	s_nop 0
	buffer_load_dwordx4 v141, s[12:15], s19 offen lds
	s_mov_b32 m0, s45
	s_nop 0
	buffer_load_dwordx4 v142, s[12:15], s19 offen lds
	s_waitcnt vmcnt(6)
	s_barrier
; #define STAGE(P, RS, SOFF, OFF, kt) do { const int _so = (SOFF) + (kt) * (BK * 2); \
;     _Pragma("unroll") for (int _i = 0; _i < 2; ++_i) { \
;       __builtin_amdgcn_raw_ptr_buffer_load_lds(RS, (__attribute__((address_space(3))) void*)((P) + wave * 1024 + _i * 8192), 16, OFF[_i], _so, 0, 0); } } while (0)
; #define LDA(dst, b, h) _Pragma("unroll") for (int m = 0; m < 4; ++m) _Pragma("unroll") for (int k = 0; k < 2; ++k) \
;     dst[m][k] = *reinterpret_cast<const bf16x8*>(SA(b, h) + lds_byte(wr * 64 + m * 16 + fr, k * 32 + fq * 8))
; #define LDB(dst, b, h) _Pragma("unroll") for (int n = 0; n < 2; ++n) _Pragma("unroll") for (int k = 0; k < 2; ++k) \
;     dst[n][k] = *reinterpret_cast<const bf16x8*>(SB(b, h) + lds_byte(wc * 32 + n * 16 + fr, k * 32 + fq * 8))
; #define WAIT_V(n) asm volatile("s_waitcnt vmcnt(" #n ")" ::: "memory")
; #define WAIT_L(n) asm volatile("s_waitcnt lgkmcnt(" #n ")" ::: "memory")
; #define BAR __builtin_amdgcn_s_barrier()
; #define SCHED __builtin_amdgcn_sched_barrier(0)
;     ...
;       WAIT_V(6); BAR; MMA(1, 1, At, B1); BAR;
;       LDB(B0, 1, 0); SCHED; LDA(At, 1, 0); STAGE(SA(0, 1), rsA, sA1, offA, t + 2);
;       WAIT_L(8); BAR; WAIT_L(0); MMA(0, 0, At, B0); BAR; SCHED;
;       LDB(B1, 1, 1); STAGE(SB(1, 0), rsB, sB0, offB, t + 3);
;       BAR; WAIT_L(0); MMA(0, 1, At, B1); BAR;
;       LDA(At, 1, 1); STAGE(SA(1, 0), rsA, sA0, offA, t + 3);
;       BAR; WAIT_L(0); MMA(1, 0, At, B0); BAR; SCHED;
	v_mfma_f32_16x16x32_bf16 v[12:15], v[200:203], v[168:171], v[12:15]
	v_mfma_f32_16x16x32_bf16 v[8:11], v[208:211], v[168:171], v[8:11]
	v_mfma_f32_16x16x32_bf16 v[4:7], v[200:203], v[176:179], v[4:7]
	v_mfma_f32_16x16x32_bf16 v[0:3], v[208:211], v[176:179], v[0:3]
	v_mfma_f32_16x16x32_bf16 v[64:67], v[200:203], v[184:187], v[64:67]
	v_mfma_f32_16x16x32_bf16 v[72:75], v[208:211], v[184:187], v[72:75]
	v_mfma_f32_16x16x32_bf16 v[76:79], v[200:203], v[192:195], v[76:79]
	v_mfma_f32_16x16x32_bf16 v[84:87], v[208:211], v[192:195], v[84:87]
	v_mfma_f32_16x16x32_bf16 v[12:15], v[204:207], v[172:175], v[12:15]
	v_mfma_f32_16x16x32_bf16 v[8:11], v[212:215], v[172:175], v[8:11]
	v_mfma_f32_16x16x32_bf16 v[4:7], v[204:207], v[180:183], v[4:7]
	v_mfma_f32_16x16x32_bf16 v[0:3], v[212:215], v[180:183], v[0:3]
	v_mfma_f32_16x16x32_bf16 v[64:67], v[204:207], v[188:191], v[64:67]
	v_mfma_f32_16x16x32_bf16 v[72:75], v[212:215], v[188:191], v[72:75]
	v_mfma_f32_16x16x32_bf16 v[76:79], v[204:207], v[196:199], v[76:79]
	v_mfma_f32_16x16x32_bf16 v[84:87], v[212:215], v[196:199], v[84:87]
	s_barrier
	ds_read_b128 v[152:155], v137
	ds_read_b128 v[156:159], v138
	ds_read_b128 v[160:163], v139
	ds_read_b128 v[164:167], v140
	s_addk_i32 s4, 0x100
	s_mov_b32 m0, s36
	ds_read_b128 v[168:171], v129 offset:32768
	ds_read_b128 v[172:175], v129 offset:33792
	ds_read_b128 v[176:179], v132 offset:32768
	ds_read_b128 v[180:183], v132 offset:33792
	ds_read_b128 v[184:187], v131 offset:32768
	ds_read_b128 v[188:191], v131 offset:33792
	ds_read_b128 v[192:195], v130 offset:32768
	ds_read_b128 v[196:199], v130 offset:33792
	buffer_load_dwordx4 v141, s[8:11], s4 offen lds
	s_mov_b32 m0, s48
	s_nop 0
	buffer_load_dwordx4 v142, s[8:11], s4 offen lds
	s_waitcnt lgkmcnt(8)
	s_barrier
	s_waitcnt lgkmcnt(0)
	v_mfma_f32_16x16x32_bf16 v[124:127], v[152:155], v[168:171], v[124:127]
	v_mfma_f32_16x16x32_bf16 v[120:123], v[160:163], v[168:171], v[120:123]
	v_mfma_f32_16x16x32_bf16 v[116:119], v[152:155], v[176:179], v[116:119]
	v_mfma_f32_16x16x32_bf16 v[112:115], v[160:163], v[176:179], v[112:115]
	v_mfma_f32_16x16x32_bf16 v[108:111], v[152:155], v[184:187], v[108:111]
	v_mfma_f32_16x16x32_bf16 v[104:107], v[160:163], v[184:187], v[104:107]
	v_mfma_f32_16x16x32_bf16 v[100:103], v[152:155], v[192:195], v[100:103]
	v_mfma_f32_16x16x32_bf16 v[96:99], v[160:163], v[192:195], v[96:99]
	v_mfma_f32_16x16x32_bf16 v[124:127], v[156:159], v[172:175], v[124:127]
	v_mfma_f32_16x16x32_bf16 v[120:123], v[164:167], v[172:175], v[120:123]
	v_mfma_f32_16x16x32_bf16 v[116:119], v[156:159], v[180:183], v[116:119]
	v_mfma_f32_16x16x32_bf16 v[112:115], v[164:167], v[180:183], v[112:115]
	v_mfma_f32_16x16x32_bf16 v[108:111], v[156:159], v[188:191], v[108:111]
	v_mfma_f32_16x16x32_bf16 v[104:107], v[164:167], v[188:191], v[104:107]
	v_mfma_f32_16x16x32_bf16 v[100:103], v[156:159], v[196:199], v[100:103]
	v_mfma_f32_16x16x32_bf16 v[96:99], v[164:167], v[196:199], v[96:99]
	s_barrier
	s_addk_i32 s5, 0x180
	s_mov_b32 m0, s37
	ds_read_b128 v[200:203], v133
	ds_read_b128 v[204:207], v134
	ds_read_b128 v[208:211], v135
	ds_read_b128 v[212:215], v136
	buffer_load_dwordx4 v141, s[12:15], s5 offen lds
	s_mov_b32 m0, s49
	s_nop 0
	buffer_load_dwordx4 v142, s[12:15], s5 offen lds
	s_barrier
	s_waitcnt lgkmcnt(0)
	v_mfma_f32_16x16x32_bf16 v[92:95], v[200:203], v[168:171], v[92:95]
	v_mfma_f32_16x16x32_bf16 v[88:91], v[208:211], v[168:171], v[88:91]
	v_mfma_f32_16x16x32_bf16 v[80:83], v[200:203], v[176:179], v[80:83]
	v_mfma_f32_16x16x32_bf16 v[68:71], v[208:211], v[176:179], v[68:71]
	v_mfma_f32_16x16x32_bf16 v[60:63], v[200:203], v[184:187], v[60:63]
	v_mfma_f32_16x16x32_bf16 v[56:59], v[208:211], v[184:187], v[56:59]
	v_mfma_f32_16x16x32_bf16 v[52:55], v[200:203], v[192:195], v[52:55]
	v_mfma_f32_16x16x32_bf16 v[48:51], v[208:211], v[192:195], v[48:51]
	v_mfma_f32_16x16x32_bf16 v[92:95], v[204:207], v[172:175], v[92:95]
	v_mfma_f32_16x16x32_bf16 v[88:91], v[212:215], v[172:175], v[88:91]
	v_mfma_f32_16x16x32_bf16 v[80:83], v[204:207], v[180:183], v[80:83]
	v_mfma_f32_16x16x32_bf16 v[68:71], v[212:215], v[180:183], v[68:71]
	v_mfma_f32_16x16x32_bf16 v[60:63], v[204:207], v[188:191], v[60:63]
	v_mfma_f32_16x16x32_bf16 v[56:59], v[212:215], v[188:191], v[56:59]
	v_mfma_f32_16x16x32_bf16 v[52:55], v[204:207], v[196:199], v[52:55]
	v_mfma_f32_16x16x32_bf16 v[48:51], v[212:215], v[196:199], v[48:51]
	s_addk_i32 s6, 0x180
	s_mov_b32 m0, s38
	s_barrier
	ds_read_b128 v[168:171], v129 offset:49152
	ds_read_b128 v[172:175], v129 offset:50176
	ds_read_b128 v[176:179], v132 offset:49152
	ds_read_b128 v[180:183], v132 offset:50176
	ds_read_b128 v[184:187], v131 offset:49152
	ds_read_b128 v[188:191], v131 offset:50176
	ds_read_b128 v[192:195], v130 offset:49152
	ds_read_b128 v[196:199], v130 offset:50176
	buffer_load_dwordx4 v141, s[8:11], s6 offen lds
	s_mov_b32 m0, s54
	s_nop 0
	buffer_load_dwordx4 v142, s[8:11], s6 offen lds
	s_barrier
	s_waitcnt lgkmcnt(0)
	v_mfma_f32_16x16x32_bf16 v[44:47], v[152:155], v[168:171], v[44:47]
	v_mfma_f32_16x16x32_bf16 v[40:43], v[160:163], v[168:171], v[40:43]
	v_mfma_f32_16x16x32_bf16 v[36:39], v[152:155], v[176:179], v[36:39]
	v_mfma_f32_16x16x32_bf16 v[32:35], v[160:163], v[176:179], v[32:35]
	v_mfma_f32_16x16x32_bf16 v[28:31], v[152:155], v[184:187], v[28:31]
	v_mfma_f32_16x16x32_bf16 v[24:27], v[160:163], v[184:187], v[24:27]
	v_mfma_f32_16x16x32_bf16 v[20:23], v[152:155], v[192:195], v[20:23]
	v_mfma_f32_16x16x32_bf16 v[16:19], v[160:163], v[192:195], v[16:19]
	v_mfma_f32_16x16x32_bf16 v[44:47], v[156:159], v[172:175], v[44:47]
	v_mfma_f32_16x16x32_bf16 v[40:43], v[164:167], v[172:175], v[40:43]
	v_mfma_f32_16x16x32_bf16 v[36:39], v[156:159], v[180:183], v[36:39]
	v_mfma_f32_16x16x32_bf16 v[32:35], v[164:167], v[180:183], v[32:35]
	v_mfma_f32_16x16x32_bf16 v[28:31], v[156:159], v[188:191], v[28:31]
	v_mfma_f32_16x16x32_bf16 v[24:27], v[164:167], v[188:191], v[24:27]
	v_mfma_f32_16x16x32_bf16 v[20:23], v[156:159], v[196:199], v[20:23]
	v_mfma_f32_16x16x32_bf16 v[16:19], v[164:167], v[196:199], v[16:19]
	s_barrier
; #define STAGE(P, RS, SOFF, OFF, kt) do { const int _so = (SOFF) + (kt) * (BK * 2); \
;     _Pragma("unroll") for (int _i = 0; _i < 2; ++_i) { \
;       __builtin_amdgcn_raw_ptr_buffer_load_lds(RS, (__attribute__((address_space(3))) void*)((P) + wave * 1024 + _i * 8192), 16, OFF[_i], _so, 0, 0); } } while (0)
; #define LDA(dst, b, h) _Pragma("unroll") for (int m = 0; m < 4; ++m) _Pragma("unroll") for (int k = 0; k < 2; ++k) \
;     dst[m][k] = *reinterpret_cast<const bf16x8*>(SA(b, h) + lds_byte(wr * 64 + m * 16 + fr, k * 32 + fq * 8))
; #define LDB(dst, b, h) _Pragma("unroll") for (int n = 0; n < 2; ++n) _Pragma("unroll") for (int k = 0; k < 2; ++k) \
;     dst[n][k] = *reinterpret_cast<const bf16x8*>(SB(b, h) + lds_byte(wc * 32 + n * 16 + fr, k * 32 + fq * 8))
; #define WAIT_V(n) asm volatile("s_waitcnt vmcnt(" #n ")" ::: "memory")
; #define WAIT_L(n) asm volatile("s_waitcnt lgkmcnt(" #n ")" ::: "memory")
; #define BAR __builtin_amdgcn_s_barrier()
;     ...
;       STAGE(SB(1, 1), rsB, sB1, offB, t + 3);
;       WAIT_V(6); BAR; MMA(1, 1, At, B1); BAR;
;     }
;     { LDB(B0, 0, 0); LDA(At, 0, 0); STAGE(SA(1, 1), rsA, sA1, offA, nt - 1);
;       BAR; WAIT_L(0); MMA(0, 0, At, B0); BAR;
;       LDB(B1, 0, 1); BAR; WAIT_L(0); MMA(0, 1, At, B1); BAR;
;       LDA(At, 0, 1); WAIT_V(4); BAR; WAIT_L(0); MMA(1, 0, At, B0); MMA(1, 1, At, B1); BAR; }
	s_addk_i32 s7, 0x180
	s_mov_b32 m0, s39
	s_nop 0
	buffer_load_dwordx4 v141, s[12:15], s7 offen lds
	s_mov_b32 m0, s55
	s_nop 0
	buffer_load_dwordx4 v142, s[12:15], s7 offen lds
	s_waitcnt vmcnt(6)
	s_barrier
	v_mfma_f32_16x16x32_bf16 v[12:15], v[200:203], v[168:171], v[12:15]
	v_mfma_f32_16x16x32_bf16 v[8:11], v[208:211], v[168:171], v[8:11]
	v_mfma_f32_16x16x32_bf16 v[4:7], v[200:203], v[176:179], v[4:7]
	v_mfma_f32_16x16x32_bf16 v[0:3], v[208:211], v[176:179], v[0:3]
	v_mfma_f32_16x16x32_bf16 v[64:67], v[200:203], v[184:187], v[64:67]
	v_mfma_f32_16x16x32_bf16 v[72:75], v[208:211], v[184:187], v[72:75]
	v_mfma_f32_16x16x32_bf16 v[76:79], v[200:203], v[192:195], v[76:79]
	v_mfma_f32_16x16x32_bf16 v[84:87], v[208:211], v[192:195], v[84:87]
	v_mfma_f32_16x16x32_bf16 v[12:15], v[204:207], v[172:175], v[12:15]
	v_mfma_f32_16x16x32_bf16 v[8:11], v[212:215], v[172:175], v[8:11]
	v_mfma_f32_16x16x32_bf16 v[4:7], v[204:207], v[180:183], v[4:7]
	v_mfma_f32_16x16x32_bf16 v[0:3], v[212:215], v[180:183], v[0:3]
	v_mfma_f32_16x16x32_bf16 v[64:67], v[204:207], v[188:191], v[64:67]
	v_mfma_f32_16x16x32_bf16 v[72:75], v[212:215], v[188:191], v[72:75]
	v_mfma_f32_16x16x32_bf16 v[76:79], v[204:207], v[196:199], v[76:79]
	v_mfma_f32_16x16x32_bf16 v[84:87], v[212:215], v[196:199], v[84:87]
	s_add_i32 s1, s1, 2
	s_addk_i32 s3, 0x100
	s_cmp_gt_u32 s1, 59
	s_barrier
	s_cbranch_scc0 .LBB0_148
	s_add_i32 s1, s82, 0x1f80
	s_mov_b32 m0, s31
	ds_read_b128 v[152:155], v147
	ds_read_b128 v[156:159], v148
	ds_read_b128 v[160:163], v149
	ds_read_b128 v[148:151], v150
	ds_read_b128 v[164:167], v129
	ds_read_b128 v[168:171], v129 offset:1024
	ds_read_b128 v[172:175], v132
	ds_read_b128 v[176:179], v132 offset:1024
	ds_read_b128 v[180:183], v131
	ds_read_b128 v[184:187], v131 offset:1024
	ds_read_b128 v[188:191], v130
	ds_read_b128 v[192:195], v130 offset:1024
	buffer_load_dwordx4 v141, s[8:11], s1 offen lds
	s_mov_b32 m0, s58
	s_nop 0
	buffer_load_dwordx4 v142, s[8:11], s1 offen lds
	s_barrier
	s_waitcnt lgkmcnt(0)
	v_mfma_f32_16x16x32_bf16 v[124:127], v[152:155], v[164:167], v[124:127]
	v_mfma_f32_16x16x32_bf16 v[120:123], v[160:163], v[164:167], v[120:123]
	v_mfma_f32_16x16x32_bf16 v[116:119], v[152:155], v[172:175], v[116:119]
	v_mfma_f32_16x16x32_bf16 v[112:115], v[160:163], v[172:175], v[112:115]
	v_mfma_f32_16x16x32_bf16 v[108:111], v[152:155], v[180:183], v[108:111]
	v_mfma_f32_16x16x32_bf16 v[104:107], v[160:163], v[180:183], v[104:107]
	v_mfma_f32_16x16x32_bf16 v[100:103], v[152:155], v[188:191], v[100:103]
	v_mfma_f32_16x16x32_bf16 v[96:99], v[160:163], v[188:191], v[96:99]
	v_mfma_f32_16x16x32_bf16 v[124:127], v[156:159], v[168:171], v[124:127]
	v_mfma_f32_16x16x32_bf16 v[120:123], v[148:151], v[168:171], v[120:123]
	v_mfma_f32_16x16x32_bf16 v[116:119], v[156:159], v[176:179], v[116:119]
	v_mfma_f32_16x16x32_bf16 v[112:115], v[148:151], v[176:179], v[112:115]
	v_mfma_f32_16x16x32_bf16 v[108:111], v[156:159], v[184:187], v[108:111]
	v_mfma_f32_16x16x32_bf16 v[104:107], v[148:151], v[184:187], v[104:107]
	v_mfma_f32_16x16x32_bf16 v[100:103], v[156:159], v[192:195], v[100:103]
	v_mfma_f32_16x16x32_bf16 v[96:99], v[148:151], v[192:195], v[96:99]
	s_barrier
	ds_read_b128 v[196:199], v143
	ds_read_b128 v[200:203], v144
	ds_read_b128 v[142:145], v145
	ds_read_b128 v[204:207], v146
	s_barrier
	s_waitcnt lgkmcnt(0)
	v_mfma_f32_16x16x32_bf16 v[88:91], v[142:145], v[164:167], v[88:91]
	v_mfma_f32_16x16x32_bf16 v[80:83], v[196:199], v[172:175], v[80:83]
	v_mfma_f32_16x16x32_bf16 v[60:63], v[196:199], v[180:183], v[60:63]
	v_mfma_f32_16x16x32_bf16 v[56:59], v[142:145], v[180:183], v[56:59]
	v_mfma_f32_16x16x32_bf16 v[52:55], v[196:199], v[188:191], v[52:55]
	v_mfma_f32_16x16x32_bf16 v[48:51], v[142:145], v[188:191], v[48:51]
	v_mfma_f32_16x16x32_bf16 v[92:95], v[196:199], v[164:167], v[92:95]
	v_mfma_f32_16x16x32_bf16 v[68:71], v[142:145], v[172:175], v[68:71]
	v_mfma_f32_16x16x32_bf16 v[88:91], v[204:207], v[168:171], v[88:91]
	v_mfma_f32_16x16x32_bf16 v[80:83], v[200:203], v[176:179], v[80:83]
	v_mfma_f32_16x16x32_bf16 v[60:63], v[200:203], v[184:187], v[60:63]
	v_mfma_f32_16x16x32_bf16 v[56:59], v[204:207], v[184:187], v[56:59]
	v_mfma_f32_16x16x32_bf16 v[52:55], v[200:203], v[192:195], v[52:55]
	v_mfma_f32_16x16x32_bf16 v[48:51], v[204:207], v[192:195], v[48:51]
	v_mfma_f32_16x16x32_bf16 v[164:167], v[200:203], v[168:171], v[92:95]
	v_mfma_f32_16x16x32_bf16 v[168:171], v[204:207], v[176:179], v[68:71]
	s_barrier
	s_nop 0
	ds_read_b128 v[68:71], v129 offset:16384
	ds_read_b128 v[92:95], v129 offset:17408
	ds_read_b128 v[172:175], v132 offset:16384
	ds_read_b128 v[176:179], v132 offset:17408
	ds_read_b128 v[180:183], v131 offset:16384
	ds_read_b128 v[184:187], v131 offset:17408
	ds_read_b128 v[188:191], v130 offset:16384
	ds_read_b128 v[192:195], v130 offset:17408
	s_waitcnt vmcnt(4)
	s_barrier
; #define LDA(dst, b, h) _Pragma("unroll") for (int m = 0; m < 4; ++m) _Pragma("unroll") for (int k = 0; k < 2; ++k) \
;     dst[m][k] = *reinterpret_cast<const bf16x8*>(SA(b, h) + lds_byte(wr * 64 + m * 16 + fr, k * 32 + fq * 8))
; #define LDB(dst, b, h) _Pragma("unroll") for (int n = 0; n < 2; ++n) _Pragma("unroll") for (int k = 0; k < 2; ++k) \
;     dst[n][k] = *reinterpret_cast<const bf16x8*>(SB(b, h) + lds_byte(wc * 32 + n * 16 + fr, k * 32 + fq * 8))
; #define WAIT_V(n) asm volatile("s_waitcnt vmcnt(" #n ")" ::: "memory")
; #define WAIT_L(n) asm volatile("s_waitcnt lgkmcnt(" #n ")" ::: "memory")
; #define BAR __builtin_amdgcn_s_barrier()
;     ...
;       LDA(At, 0, 1); WAIT_V(4); BAR; WAIT_L(0); MMA(1, 0, At, B0); MMA(1, 1, At, B1); BAR; }
;     { LDB(B0, 1, 0); LDA(At, 1, 0); WAIT_V(2); BAR; WAIT_L(0); MMA(0, 0, At, B0); BAR;
;       LDB(B1, 1, 1); WAIT_V(0); BAR; WAIT_L(0); MMA(0, 1, At, B1); BAR;
	s_waitcnt lgkmcnt(0)
	v_mfma_f32_16x16x32_bf16 v[44:47], v[152:155], v[68:71], v[44:47]
	v_mfma_f32_16x16x32_bf16 v[40:43], v[160:163], v[68:71], v[40:43]
	v_mfma_f32_16x16x32_bf16 v[36:39], v[152:155], v[172:175], v[36:39]
	v_mfma_f32_16x16x32_bf16 v[32:35], v[160:163], v[172:175], v[32:35]
	v_mfma_f32_16x16x32_bf16 v[28:31], v[152:155], v[180:183], v[28:31]
	v_mfma_f32_16x16x32_bf16 v[24:27], v[160:163], v[180:183], v[24:27]
	v_mfma_f32_16x16x32_bf16 v[20:23], v[152:155], v[188:191], v[20:23]
	v_mfma_f32_16x16x32_bf16 v[16:19], v[160:163], v[188:191], v[16:19]
	v_mfma_f32_16x16x32_bf16 v[44:47], v[156:159], v[92:95], v[44:47]
	v_mfma_f32_16x16x32_bf16 v[40:43], v[148:151], v[92:95], v[40:43]
	v_mfma_f32_16x16x32_bf16 v[36:39], v[156:159], v[176:179], v[36:39]
	v_mfma_f32_16x16x32_bf16 v[32:35], v[148:151], v[176:179], v[32:35]
	v_mfma_f32_16x16x32_bf16 v[28:31], v[156:159], v[184:187], v[28:31]
	v_mfma_f32_16x16x32_bf16 v[24:27], v[148:151], v[184:187], v[24:27]
	v_mfma_f32_16x16x32_bf16 v[20:23], v[156:159], v[192:195], v[20:23]
	v_mfma_f32_16x16x32_bf16 v[16:19], v[148:151], v[192:195], v[16:19]
	v_mfma_f32_16x16x32_bf16 v[8:11], v[142:145], v[68:71], v[8:11]
	v_mfma_f32_16x16x32_bf16 v[0:3], v[142:145], v[172:175], v[0:3]
	v_mfma_f32_16x16x32_bf16 v[12:15], v[196:199], v[68:71], v[12:15]
	v_mfma_f32_16x16x32_bf16 v[4:7], v[196:199], v[172:175], v[4:7]
	v_mfma_f32_16x16x32_bf16 v[64:67], v[196:199], v[180:183], v[64:67]
	v_mfma_f32_16x16x32_bf16 v[68:71], v[142:145], v[180:183], v[72:75]
	v_mfma_f32_16x16x32_bf16 v[72:75], v[196:199], v[188:191], v[76:79]
	v_mfma_f32_16x16x32_bf16 v[76:79], v[142:145], v[188:191], v[84:87]
	v_mfma_f32_16x16x32_bf16 v[8:11], v[204:207], v[92:95], v[8:11]
	v_mfma_f32_16x16x32_bf16 v[0:3], v[204:207], v[176:179], v[0:3]
	v_mfma_f32_16x16x32_bf16 v[160:163], v[200:203], v[92:95], v[12:15]
	v_mfma_f32_16x16x32_bf16 v[172:175], v[200:203], v[176:179], v[4:7]
	v_mfma_f32_16x16x32_bf16 v[176:179], v[200:203], v[184:187], v[64:67]
	v_mfma_f32_16x16x32_bf16 v[180:183], v[204:207], v[184:187], v[68:71]
	v_mfma_f32_16x16x32_bf16 v[184:187], v[200:203], v[192:195], v[72:75]
	v_mfma_f32_16x16x32_bf16 v[188:191], v[204:207], v[192:195], v[76:79]
	s_barrier
	ds_read_b128 v[4:7], v137
	ds_read_b128 v[12:15], v138
	ds_read_b128 v[192:195], v139
	ds_read_b128 v[138:141], v140
	ds_read_b128 v[72:75], v129 offset:32768
	ds_read_b128 v[142:145], v129 offset:33792
	ds_read_b128 v[76:79], v132 offset:32768
	ds_read_b128 v[196:199], v132 offset:33792
	ds_read_b128 v[152:155], v131 offset:32768
	ds_read_b128 v[200:203], v131 offset:33792
	ds_read_b128 v[204:207], v130 offset:32768
	ds_read_b128 v[208:211], v130 offset:33792
	s_waitcnt vmcnt(2)
	s_barrier
	s_waitcnt lgkmcnt(0)
	v_mfma_f32_16x16x32_bf16 v[64:67], v[4:7], v[72:75], v[124:127]
	v_mfma_f32_16x16x32_bf16 v[84:87], v[192:195], v[72:75], v[120:123]
	v_mfma_f32_16x16x32_bf16 v[92:95], v[4:7], v[76:79], v[116:119]
	v_mfma_f32_16x16x32_bf16 v[112:115], v[192:195], v[76:79], v[112:115]
	v_mfma_f32_16x16x32_bf16 v[108:111], v[4:7], v[152:155], v[108:111]
	v_mfma_f32_16x16x32_bf16 v[104:107], v[192:195], v[152:155], v[104:107]
	v_mfma_f32_16x16x32_bf16 v[100:103], v[4:7], v[204:207], v[100:103]
	v_mfma_f32_16x16x32_bf16 v[96:99], v[192:195], v[204:207], v[96:99]
	v_mfma_f32_16x16x32_bf16 v[68:71], v[12:15], v[142:145], v[64:67]
	v_mfma_f32_16x16x32_bf16 v[64:67], v[138:141], v[142:145], v[84:87]
	v_mfma_f32_16x16x32_bf16 v[156:159], v[12:15], v[196:199], v[92:95]
	v_mfma_f32_16x16x32_bf16 v[148:151], v[138:141], v[196:199], v[112:115]
	v_mfma_f32_16x16x32_bf16 v[124:127], v[12:15], v[200:203], v[108:111]
	v_mfma_f32_16x16x32_bf16 v[116:119], v[138:141], v[200:203], v[104:107]
	v_mfma_f32_16x16x32_bf16 v[92:95], v[12:15], v[208:211], v[100:103]
	v_mfma_f32_16x16x32_bf16 v[84:87], v[138:141], v[208:211], v[96:99]
	s_barrier
; #define LDA(dst, b, h) _Pragma("unroll") for (int m = 0; m < 4; ++m) _Pragma("unroll") for (int k = 0; k < 2; ++k) \
;     dst[m][k] = *reinterpret_cast<const bf16x8*>(SA(b, h) + lds_byte(wr * 64 + m * 16 + fr, k * 32 + fq * 8))
; #define LDB(dst, b, h) _Pragma("unroll") for (int n = 0; n < 2; ++n) _Pragma("unroll") for (int k = 0; k < 2; ++k) \
;     dst[n][k] = *reinterpret_cast<const bf16x8*>(SB(b, h) + lds_byte(wc * 32 + n * 16 + fr, k * 32 + fq * 8))
; #define WAIT_V(n) asm volatile("s_waitcnt vmcnt(" #n ")" ::: "memory")
; #define WAIT_L(n) asm volatile("s_waitcnt lgkmcnt(" #n ")" ::: "memory")
; #define BAR __builtin_amdgcn_s_barrier()
;     ...
;       LDB(B1, 1, 1); WAIT_V(0); BAR; WAIT_L(0); MMA(0, 1, At, B1); BAR;
;       LDA(At, 1, 1); BAR; WAIT_L(0); MMA(1, 0, At, B0); MMA(1, 1, At, B1); BAR; }
;     if (wr == 0) BAR;
	s_nop 0
	ds_read_b128 v[96:99], v133
	ds_read_b128 v[100:103], v134
	ds_read_b128 v[104:107], v135
	ds_read_b128 v[108:111], v136
	s_waitcnt vmcnt(0)
	s_barrier
	s_waitcnt lgkmcnt(0)
	v_mfma_f32_16x16x32_bf16 v[112:115], v[96:99], v[72:75], v[164:167]
	v_mfma_f32_16x16x32_bf16 v[72:75], v[104:107], v[72:75], v[88:91]
	v_mfma_f32_16x16x32_bf16 v[80:83], v[96:99], v[76:79], v[80:83]
	v_mfma_f32_16x16x32_bf16 v[88:91], v[104:107], v[76:79], v[168:171]
	v_mfma_f32_16x16x32_bf16 v[60:63], v[96:99], v[152:155], v[60:63]
	v_mfma_f32_16x16x32_bf16 v[56:59], v[104:107], v[152:155], v[56:59]
	v_mfma_f32_16x16x32_bf16 v[52:55], v[96:99], v[204:207], v[52:55]
	v_mfma_f32_16x16x32_bf16 v[48:51], v[104:107], v[204:207], v[48:51]
	v_mfma_f32_16x16x32_bf16 v[76:79], v[100:103], v[142:145], v[112:115]
	v_mfma_f32_16x16x32_bf16 v[72:75], v[108:111], v[142:145], v[72:75]
	v_mfma_f32_16x16x32_bf16 v[152:155], v[100:103], v[196:199], v[80:83]
	v_mfma_f32_16x16x32_bf16 v[144:147], v[108:111], v[196:199], v[88:91]
	v_mfma_f32_16x16x32_bf16 v[120:123], v[100:103], v[200:203], v[60:63]
	v_mfma_f32_16x16x32_bf16 v[112:115], v[108:111], v[200:203], v[56:59]
	v_mfma_f32_16x16x32_bf16 v[88:91], v[100:103], v[208:211], v[52:55]
	v_mfma_f32_16x16x32_bf16 v[80:83], v[108:111], v[208:211], v[48:51]
	s_barrier
	s_nop 0
	ds_read_b128 v[48:51], v129 offset:49152
	ds_read_b128 v[134:137], v129 offset:50176
	ds_read_b128 v[56:59], v132 offset:49152
	ds_read_b128 v[164:167], v132 offset:50176
	ds_read_b128 v[168:171], v131 offset:49152
	ds_read_b128 v[196:199], v131 offset:50176
	ds_read_b128 v[200:203], v130 offset:49152
	ds_read_b128 v[130:133], v130 offset:50176
	s_barrier
	s_waitcnt lgkmcnt(0)
	v_mfma_f32_16x16x32_bf16 v[44:47], v[4:7], v[48:51], v[44:47]
	v_mfma_f32_16x16x32_bf16 v[40:43], v[192:195], v[48:51], v[40:43]
	v_mfma_f32_16x16x32_bf16 v[36:39], v[4:7], v[56:59], v[36:39]
	v_mfma_f32_16x16x32_bf16 v[32:35], v[192:195], v[56:59], v[32:35]
	v_mfma_f32_16x16x32_bf16 v[28:31], v[4:7], v[168:171], v[28:31]
	v_mfma_f32_16x16x32_bf16 v[24:27], v[192:195], v[168:171], v[24:27]
	v_mfma_f32_16x16x32_bf16 v[4:7], v[4:7], v[200:203], v[20:23]
	v_mfma_f32_16x16x32_bf16 v[16:19], v[192:195], v[200:203], v[16:19]
	v_mfma_f32_16x16x32_bf16 v[60:63], v[12:15], v[134:137], v[44:47]
	v_mfma_f32_16x16x32_bf16 v[52:55], v[138:141], v[134:137], v[40:43]
	v_mfma_f32_16x16x32_bf16 v[44:47], v[12:15], v[164:167], v[36:39]
	v_mfma_f32_16x16x32_bf16 v[36:39], v[138:141], v[164:167], v[32:35]
	v_mfma_f32_16x16x32_bf16 v[28:31], v[12:15], v[196:199], v[28:31]
	v_mfma_f32_16x16x32_bf16 v[20:23], v[138:141], v[196:199], v[24:27]
	v_mfma_f32_16x16x32_bf16 v[12:15], v[12:15], v[130:133], v[4:7]
	v_mfma_f32_16x16x32_bf16 v[4:7], v[138:141], v[130:133], v[16:19]
	v_mfma_f32_16x16x32_bf16 v[16:19], v[96:99], v[48:51], v[160:163]
	v_mfma_f32_16x16x32_bf16 v[8:11], v[104:107], v[48:51], v[8:11]
	v_mfma_f32_16x16x32_bf16 v[24:27], v[96:99], v[56:59], v[172:175]
	v_mfma_f32_16x16x32_bf16 v[0:3], v[104:107], v[56:59], v[0:3]
	v_mfma_f32_16x16x32_bf16 v[138:141], v[96:99], v[168:171], v[176:179]
	v_mfma_f32_16x16x32_bf16 v[160:163], v[104:107], v[168:171], v[180:183]
	v_mfma_f32_16x16x32_bf16 v[96:99], v[96:99], v[200:203], v[184:187]
	v_mfma_f32_16x16x32_bf16 v[104:107], v[104:107], v[200:203], v[188:191]
	v_mfma_f32_16x16x32_bf16 v[56:59], v[100:103], v[134:137], v[16:19]
	v_mfma_f32_16x16x32_bf16 v[48:51], v[108:111], v[134:137], v[8:11]
	v_mfma_f32_16x16x32_bf16 v[40:43], v[100:103], v[164:167], v[24:27]
	v_mfma_f32_16x16x32_bf16 v[32:35], v[108:111], v[164:167], v[0:3]
	v_mfma_f32_16x16x32_bf16 v[24:27], v[100:103], v[196:199], v[138:141]
	v_mfma_f32_16x16x32_bf16 v[16:19], v[108:111], v[196:199], v[160:163]
	v_mfma_f32_16x16x32_bf16 v[8:11], v[100:103], v[130:133], v[96:99]
	v_mfma_f32_16x16x32_bf16 v[0:3], v[108:111], v[130:133], v[104:107]
	v_cmp_gt_u32_e32 vcc, s60, v128
	s_barrier
	s_and_saveexec_b64 s[4:5], vcc
	s_cbranch_execz .LBB0_151
	s_barrier

;     ...
;       const int tid3 = opaque_tid(wave);
;       const int wr3 = tid3 >> 8, wc3 = (tid3 >> 6) & 3, fr3 = tid3 & 15, fq3 = (tid3 & 63) >> 4;
;       const int ebase3 = (brow + wr3 * 64 + fr3) * DM + pn * BM + wc3 * 32 + fq3 * 4;
;       const int vo4b = ebase3 * 4, vo2 = ebase3 * 2, vo1 = ebase3;
;       (void)vo4b; (void)vo2; (void)vo1;
;       if constexpr (OUTF) {
;         _Pragma("unroll") for (int bj = 0; bj < 2; ++bj) _Pragma("unroll") for (int n = 0; n < 2; ++n) {
;           const int col = pn * BM + bj * HALF + wc3 * 32 + n * 16 + fq3 * 4;
;           const float4 gm = *reinterpret_cast<const float4*>(g.gam + col), bt = *reinterpret_cast<const float4*>(g.bet + col);
;           _Pragma("unroll") for (int ai = 0; ai < 2; ++ai) _Pragma("unroll") for (int m = 0; m < 4; ++m) {
;             const int rl = ai * HALF + wr3 * 64 + m * 16 + fr3;
;             const float2 ms = *reinterpret_cast<const float2*>(mr + rl * 2);
;             f32x4 y = acc[ai][bj][m][n];
;             u32x4 o;
;             o[0] = __float_as_uint((y[0] - ms.x) * ms.y * gm.x + bt.x); o[1] = __float_as_uint((y[1] - ms.x) * ms.y * gm.y + bt.y);
;             o[2] = __float_as_uint((y[2] - ms.x) * ms.y * gm.z + bt.z); o[3] = __float_as_uint((y[3] - ms.x) * ms.y * gm.w + bt.w);
;             __builtin_amdgcn_raw_buffer_store_b128(o, rsO, vo4b + ((ai * HALF + m * 16) * DM + bj * HALF + n * 16) * 4, 0, 0);
;           }
;         }
;       } else {
;         constexpr int PIECE = 1024 + 16, LOBASE = 64 * PIECE;
;         const int lane3 = tid3 & 63;
;         const int hvo = (lane3 >> 5) * (DM * 2) + (lane3 & 31) * 16;
;         const int lvo = (lane3 >> 4) * DM + (lane3 & 15) * 16;
;         _Pragma("unroll") for (int ai = 0; ai < 2; ++ai) {
;           _Pragma("unroll") for (int bj = 0; bj < 2; ++bj) _Pragma("unroll") for (int n = 0; n < 2; ++n) {
;             const int cc = bj * HALF + wc3 * 32 + n * 16 + fq3 * 4;
;             const float4 gm = *reinterpret_cast<const float4*>(g.gam + pn * BM + cc), bt = *reinterpret_cast<const float4*>(g.bet + pn * BM + cc);
;             _Pragma("unroll") for (int m = 0; m < 4; ++m) {
;               const int rr = wr3 * 64 + m * 16 + fr3;
;               const float2 ms = *reinterpret_cast<const float2*>(mr + (ai * HALF + rr) * 2);
;               f32x4 y = acc[ai][bj][m][n];
.LBB0_177:
	s_or_b64 exec, exec, s[6:7]
	s_waitcnt lgkmcnt(0)
	s_barrier
	v_mbcnt_lo_u32_b32 v0, -1, 0
	v_mbcnt_hi_u32_b32 v0, -1, v0
	s_movk_i32 s4, 0x1000
	v_add_u32_e32 v1, s29, v0
	v_ashrrev_i32_e32 v5, 2, v1
	v_lshrrev_b32_e32 v6, 1, v1
	v_lshlrev_b32_e32 v1, 4, v1
	v_lshlrev_b32_e32 v12, 7, v0
	v_and_b32_e32 v13, 0x1f0, v1
	v_and_b32_e32 v2, 15, v0
	v_and_or_b32 v70, v12, s4, v13
	s_lshl_b32 s4, s0, 8
	s_movk_i32 s0, 0xffc0
	v_and_or_b32 v97, v5, s0, v2
	s_lshl_b32 s0, s18, 19
	v_bfe_u32 v4, v0, 4, 2
	s_ashr_i32 s5, s4, 31
	s_add_i32 s0, s0, s42
	v_lshlrev_b32_e32 v7, 2, v4
	s_add_i32 s0, s0, s4
	s_lshl_b64 s[4:5], s[4:5], 2
	v_and_or_b32 v12, v6, s61, v7
	s_add_u32 s6, s78, s4
	v_and_b32_e32 v3, 63, v0
	v_and_b32_e32 v1, 0xf0, v1
	v_lshlrev_b32_e32 v13, 9, v0
	v_lshlrev_b32_e32 v0, 8, v0
	s_addc_u32 s7, s79, s5
	v_lshlrev_b32_e32 v72, 2, v12
	v_lshl_or_b32 v68, v4, 11, v1
	v_and_b32_e32 v14, 0x300, v0
	v_lshlrev_b32_e32 v74, 4, v3
	global_load_dwordx4 v[196:199], v72, s[6:7]
	global_load_dwordx4 v[200:203], v72, s[6:7] offset:64
	global_load_dwordx4 v[204:207], v72, s[6:7] offset:512
	global_load_dwordx4 v[208:211], v72, s[6:7] offset:576
	s_add_u32 s4, s80, s4
	s_addc_u32 s5, s81, s5
	global_load_dwordx4 v[212:215], v72, s[4:5]
	global_load_dwordx4 v[220:223], v72, s[4:5] offset:64
	global_load_dwordx4 v[240:243], v72, s[4:5] offset:512
	global_load_dwordx4 v[248:251], v72, s[4:5] offset:576
	v_lshl_add_u32 v71, v97, 3, v246
	s_mov_b32 s18, 0x10400
	v_lshrrev_b32_e32 v67, 1, v97
	v_mul_lo_u32 v105, v67, s68
	v_add_u32_e32 v69, s59, v74
	s_lshl_b32 s22, s0, 1
	s_mov_b32 s23, s75
	s_andn2_b64 vcc, exec, s[14:15]
	s_waitcnt vmcnt(0)
	v_mov_b32_e32 v0, v196
	v_mov_b32_e32 v1, v197
	v_mov_b32_e32 v2, v198
	v_mov_b32_e32 v3, v199
	v_mov_b32_e32 v4, v212
	v_mov_b32_e32 v5, v213
	v_mov_b32_e32 v6, v214
	v_mov_b32_e32 v7, v215
	v_mov_b32_e32 v22, v1
	v_lshlrev_b32_e32 v1, 1, v12
	v_mov_b32_e32 v23, v2
	v_and_or_b32 v109, v13, s66, v1
	v_or3_b32 v2, v14, v12, s18
	ds_read_b64 v[12:13], v71
	v_mov_b32_e32 v64, v5
	v_mov_b32_e32 v65, v6
	v_mov_b32_e32 v1, v3
	v_mov_b32_e32 v5, v7
	s_waitcnt lgkmcnt(0)
	v_mov_b32_e32 v180, v12
	v_mov_b32_e32 v181, v13
	v_pk_add_f32 v[14:15], v[238:239], v[12:13] op_sel_hi:[1,0] neg_lo:[0,1] neg_hi:[0,1]
	v_pk_add_f32 v[20:21], v[236:237], v[12:13] op_sel_hi:[1,0] neg_lo:[0,1] neg_hi:[0,1]
	v_pk_mul_f32 v[14:15], v[12:13], v[14:15] op_sel:[1,0]
	v_pk_mul_f32 v[12:13], v[12:13], v[20:21] op_sel:[1,0]
	v_pk_fma_f32 v[14:15], v[22:23], v[14:15], v[64:65]
	v_pk_fma_f32 v[6:7], v[0:1], v[12:13], v[4:5]
	v_and_b32_sdwa v12, v14, v244 dst_sel:DWORD dst_unused:UNUSED_PAD src0_sel:WORD_1 src1_sel:DWORD
	v_add3_u32 v12, v14, v12, s67
	v_and_b32_e32 v20, 0xffff0000, v12
	v_and_b32_sdwa v12, v7, v244 dst_sel:DWORD dst_unused:UNUSED_PAD src0_sel:WORD_1 src1_sel:DWORD
	v_and_b32_sdwa v3, v15, v244 dst_sel:DWORD dst_unused:UNUSED_PAD src0_sel:WORD_1 src1_sel:DWORD
	v_and_b32_sdwa v13, v6, v244 dst_sel:DWORD dst_unused:UNUSED_PAD src0_sel:WORD_1 src1_sel:DWORD
	v_add3_u32 v12, v7, v12, s67
	v_add3_u32 v3, v15, v3, s67
	v_add3_u32 v21, v6, v13, s67
	v_and_b32_e32 v66, 0xffff0000, v12
	v_or_b32_sdwa v13, v66, v3 dst_sel:DWORD dst_unused:UNUSED_PAD src0_sel:DWORD src1_sel:WORD_1
	v_or_b32_sdwa v12, v21, v20 dst_sel:DWORD dst_unused:UNUSED_PAD src0_sel:WORD_1 src1_sel:DWORD
	v_add_u32_e32 v73, v109, v105
	ds_write_b64 v73, v[12:13]
	v_and_b32_e32 v12, 0xffff0000, v21
	v_sub_u32_e32 v6, v6, v12
	v_sub_u32_e32 v12, v14, v20
	v_and_b32_e32 v3, 0xffff0000, v3
	v_add_u32_e32 v12, 0x80, v12
	v_sub_u32_e32 v3, v15, v3
	v_sub_u32_e32 v7, v7, v66
	v_add_u32_e32 v6, 0x80, v6
	v_ashrrev_i32_e32 v12, 8, v12
	v_add_u32_e32 v3, 0x80, v3
	v_add_u32_e32 v7, 0x80, v7
	v_ashrrev_i32_e32 v6, 8, v6
	v_min_i32_e32 v12, 0x7f, v12
	v_ashrrev_i32_e32 v3, 8, v3
	v_ashrrev_i32_e32 v7, 8, v7
	v_min_i32_e32 v6, 0x7f, v6
	v_min_i32_sdwa v3, v3, s69 dst_sel:WORD_1 dst_unused:UNUSED_PAD src0_sel:DWORD src1_sel:DWORD
	v_min_i32_e32 v7, 0x7f, v7
	v_lshlrev_b32_e32 v12, 8, v12
	v_and_b32_e32 v12, 0xff00, v12
	v_and_b32_e32 v3, 0xff0000, v3
	v_perm_b32 v6, v7, v6, s76
	v_or3_b32 v3, v6, v12, v3
	v_lshrrev_b32_e32 v6, 2, v97
	v_mad_u64_u32 v[12:13], s[18:19], v6, s68, v[2:3]
	ds_write_b32 v12, v3
	v_or_b32_e32 v3, 16, v97
	v_lshl_add_u32 v13, v3, 3, v246
	ds_read_b64 v[6:7], v13
	v_lshrrev_b32_e32 v75, 1, v3
	v_mul_lo_u32 v106, v75, s68
	v_add_u32_e32 v75, v109, v106
	v_lshrrev_b32_e32 v3, 2, v3
	s_waitcnt lgkmcnt(0)
	v_mov_b32_e32 v182, v6
	v_mov_b32_e32 v183, v7
	v_pk_add_f32 v[14:15], v[218:219], v[6:7] op_sel_hi:[1,0] neg_lo:[0,1] neg_hi:[0,1]
	v_pk_add_f32 v[20:21], v[216:217], v[6:7] op_sel_hi:[1,0] neg_lo:[0,1] neg_hi:[0,1]
	v_pk_mul_f32 v[14:15], v[6:7], v[14:15] op_sel:[1,0]
	v_pk_mul_f32 v[6:7], v[6:7], v[20:21] op_sel:[1,0]
	v_pk_fma_f32 v[14:15], v[22:23], v[14:15], v[64:65]
	v_pk_fma_f32 v[6:7], v[0:1], v[6:7], v[4:5]
	v_and_b32_sdwa v20, v15, v244 dst_sel:DWORD dst_unused:UNUSED_PAD src0_sel:WORD_1 src1_sel:DWORD
	v_and_b32_sdwa v21, v14, v244 dst_sel:DWORD dst_unused:UNUSED_PAD src0_sel:WORD_1 src1_sel:DWORD
	v_add3_u32 v66, v15, v20, s67
	v_add3_u32 v20, v14, v21, s67
	v_and_b32_e32 v67, 0xffff0000, v20
	v_and_b32_sdwa v20, v7, v244 dst_sel:DWORD dst_unused:UNUSED_PAD src0_sel:WORD_1 src1_sel:DWORD
	v_and_b32_sdwa v21, v6, v244 dst_sel:DWORD dst_unused:UNUSED_PAD src0_sel:WORD_1 src1_sel:DWORD
	v_add3_u32 v20, v7, v20, s67
	v_add3_u32 v96, v6, v21, s67
	v_and_b32_e32 v98, 0xffff0000, v20
	v_or_b32_sdwa v21, v98, v66 dst_sel:DWORD dst_unused:UNUSED_PAD src0_sel:DWORD src1_sel:WORD_1
	v_or_b32_sdwa v20, v96, v67 dst_sel:DWORD dst_unused:UNUSED_PAD src0_sel:WORD_1 src1_sel:DWORD
	ds_write_b64 v75, v[20:21]
	v_and_b32_e32 v20, 0xffff0000, v96
	v_sub_u32_e32 v6, v6, v20
	v_sub_u32_e32 v14, v14, v67
	v_and_b32_e32 v20, 0xffff0000, v66
	v_add_u32_e32 v14, 0x80, v14
	v_sub_u32_e32 v15, v15, v20
	v_sub_u32_e32 v7, v7, v98
	v_add_u32_e32 v6, 0x80, v6
	v_ashrrev_i32_e32 v14, 8, v14
	v_add_u32_e32 v15, 0x80, v15
	v_add_u32_e32 v7, 0x80, v7
	v_ashrrev_i32_e32 v6, 8, v6
	v_min_i32_e32 v14, 0x7f, v14
	v_ashrrev_i32_e32 v15, 8, v15
	v_ashrrev_i32_e32 v7, 8, v7
	v_min_i32_e32 v6, 0x7f, v6
	v_min_i32_sdwa v15, v15, s69 dst_sel:WORD_1 dst_unused:UNUSED_PAD src0_sel:DWORD src1_sel:DWORD
	v_min_i32_e32 v7, 0x7f, v7
	v_lshlrev_b32_e32 v14, 8, v14
	v_and_b32_e32 v14, 0xff00, v14
	v_and_b32_e32 v15, 0xff0000, v15
	v_perm_b32 v6, v7, v6, s76
	v_or3_b32 v6, v6, v14, v15
	v_mad_u64_u32 v[14:15], s[18:19], v3, s68, v[2:3]
	v_or_b32_e32 v3, 32, v97
	ds_write_b32 v14, v6
	v_lshl_add_u32 v15, v3, 3, v246
	ds_read_b64 v[6:7], v15
	v_lshrrev_b32_e32 v96, 1, v3
	v_mul_lo_u32 v107, v96, s68
	v_add_u32_e32 v96, v109, v107
	v_lshrrev_b32_e32 v3, 2, v3
	s_waitcnt lgkmcnt(0)
;     ...
;             _Pragma("unroll") for (int m = 0; m < 4; ++m) {
;               const int rr = wr3 * 64 + m * 16 + fr3;
;               const float2 ms = *reinterpret_cast<const float2*>(mr + (ai * HALF + rr) * 2);
;               f32x4 y = acc[ai][bj][m][n];
;               const float o0 = (y[0] - ms.x) * ms.y * gm.x + bt.x, o1 = (y[1] - ms.x) * ms.y * gm.y + bt.y;
;               const float o2 = (y[2] - ms.x) * ms.y * gm.z + bt.z, o3 = (y[3] - ms.x) * ms.y * gm.w + bt.w;
;               const unsigned h0 = f2bf(o0), h1 = f2bf(o1), h2 = f2bf(o2), h3 = f2bf(o3);
;               u32x2 ob; ob[0] = h0 | (h1 << 16); ob[1] = h2 | (h3 << 16);
;               *reinterpret_cast<u32x2*>(smem + (rr >> 1) * PIECE + (rr & 1) * 512 + cc * 2) = ob;
;               const int l0 = min(((int)__float_as_uint(o0) - (int)(h0 << 16) + 128) >> 8, 127);
;               const int l1 = min(((int)__float_as_uint(o1) - (int)(h1 << 16) + 128) >> 8, 127);
;               const int l2 = min(((int)__float_as_uint(o2) - (int)(h2 << 16) + 128) >> 8, 127);
;               const int l3 = min(((int)__float_as_uint(o3) - (int)(h3 << 16) + 128) >> 8, 127);
;               *reinterpret_cast<unsigned*>(smem + LOBASE + (rr >> 2) * PIECE + (rr & 3) * 256 + cc) =
;                   (unsigned)(l0 & 255) | ((unsigned)(l1 & 255) << 8) | ((unsigned)(l2 & 255) << 16) | ((unsigned)l3 << 24);
;             }
	v_mov_b32_e32 v184, v6
	v_mov_b32_e32 v185, v7
	v_pk_add_f32 v[20:21], v[194:195], v[6:7] op_sel_hi:[1,0] neg_lo:[0,1] neg_hi:[0,1]
	v_pk_add_f32 v[66:67], v[192:193], v[6:7] op_sel_hi:[1,0] neg_lo:[0,1] neg_hi:[0,1]
	v_pk_mul_f32 v[20:21], v[6:7], v[20:21] op_sel:[1,0]
	v_pk_mul_f32 v[6:7], v[6:7], v[66:67] op_sel:[1,0]
	v_pk_fma_f32 v[20:21], v[22:23], v[20:21], v[64:65]
	v_pk_fma_f32 v[6:7], v[0:1], v[6:7], v[4:5]
	v_and_b32_sdwa v66, v21, v244 dst_sel:DWORD dst_unused:UNUSED_PAD src0_sel:WORD_1 src1_sel:DWORD
	v_and_b32_sdwa v67, v20, v244 dst_sel:DWORD dst_unused:UNUSED_PAD src0_sel:WORD_1 src1_sel:DWORD
	v_add3_u32 v98, v21, v66, s67
	v_add3_u32 v66, v20, v67, s67
	v_and_b32_e32 v99, 0xffff0000, v66
	v_and_b32_sdwa v66, v7, v244 dst_sel:DWORD dst_unused:UNUSED_PAD src0_sel:WORD_1 src1_sel:DWORD
	v_and_b32_sdwa v67, v6, v244 dst_sel:DWORD dst_unused:UNUSED_PAD src0_sel:WORD_1 src1_sel:DWORD
	v_add3_u32 v66, v7, v66, s67
	v_add3_u32 v100, v6, v67, s67
	v_and_b32_e32 v101, 0xffff0000, v66
	v_or_b32_sdwa v67, v101, v98 dst_sel:DWORD dst_unused:UNUSED_PAD src0_sel:DWORD src1_sel:WORD_1
	v_or_b32_sdwa v66, v100, v99 dst_sel:DWORD dst_unused:UNUSED_PAD src0_sel:WORD_1 src1_sel:DWORD
	ds_write_b64 v96, v[66:67]
	v_and_b32_e32 v66, 0xffff0000, v100
	v_sub_u32_e32 v6, v6, v66
	v_sub_u32_e32 v20, v20, v99
	v_and_b32_e32 v66, 0xffff0000, v98
	v_add_u32_e32 v20, 0x80, v20
	v_sub_u32_e32 v21, v21, v66
	v_sub_u32_e32 v7, v7, v101
	v_add_u32_e32 v6, 0x80, v6
	v_ashrrev_i32_e32 v20, 8, v20
	v_add_u32_e32 v21, 0x80, v21
	v_add_u32_e32 v7, 0x80, v7
	v_ashrrev_i32_e32 v6, 8, v6
	v_min_i32_e32 v20, 0x7f, v20
	v_ashrrev_i32_e32 v21, 8, v21
	v_ashrrev_i32_e32 v7, 8, v7
	v_min_i32_e32 v6, 0x7f, v6
	v_min_i32_sdwa v21, v21, s69 dst_sel:WORD_1 dst_unused:UNUSED_PAD src0_sel:DWORD src1_sel:DWORD
	v_min_i32_e32 v7, 0x7f, v7
	v_lshlrev_b32_e32 v20, 8, v20
	v_and_b32_e32 v20, 0xff00, v20
	v_and_b32_e32 v21, 0xff0000, v21
	v_perm_b32 v6, v7, v6, s76
	v_or3_b32 v6, v6, v20, v21
	v_mad_u64_u32 v[20:21], s[18:19], v3, s68, v[2:3]
	v_or_b32_e32 v3, 48, v97
	ds_write_b32 v20, v6
	v_lshl_add_u32 v21, v3, 3, v246
	ds_read_b64 v[6:7], v21
	s_waitcnt lgkmcnt(0)
	v_mov_b32_e32 v186, v6
	v_mov_b32_e32 v187, v7
	v_pk_add_f32 v[66:67], v[190:191], v[6:7] op_sel_hi:[1,0] neg_lo:[0,1] neg_hi:[0,1]
	s_nop 0
	v_pk_mul_f32 v[66:67], v[6:7], v[66:67] op_sel:[1,0]
	s_nop 0
	v_pk_fma_f32 v[22:23], v[22:23], v[66:67], v[64:65]
	v_pk_add_f32 v[64:65], v[188:189], v[6:7] op_sel_hi:[1,0] neg_lo:[0,1] neg_hi:[0,1]
	v_lshrrev_b32_e32 v66, 1, v3
	v_pk_mul_f32 v[6:7], v[6:7], v[64:65] op_sel:[1,0]
	v_mul_lo_u32 v108, v66, s68
	v_pk_fma_f32 v[0:1], v[0:1], v[6:7], v[4:5]
	v_and_b32_sdwa v4, v23, v244 dst_sel:DWORD dst_unused:UNUSED_PAD src0_sel:WORD_1 src1_sel:DWORD
	v_and_b32_sdwa v5, v22, v244 dst_sel:DWORD dst_unused:UNUSED_PAD src0_sel:WORD_1 src1_sel:DWORD
	v_add3_u32 v6, v23, v4, s67
	v_add3_u32 v4, v22, v5, s67
	v_and_b32_e32 v7, 0xffff0000, v4
	v_and_b32_sdwa v4, v1, v244 dst_sel:DWORD dst_unused:UNUSED_PAD src0_sel:WORD_1 src1_sel:DWORD
	v_and_b32_sdwa v5, v0, v244 dst_sel:DWORD dst_unused:UNUSED_PAD src0_sel:WORD_1 src1_sel:DWORD
	v_add3_u32 v4, v1, v4, s67
	v_add3_u32 v64, v0, v5, s67
	v_and_b32_e32 v65, 0xffff0000, v4
	v_or_b32_sdwa v5, v65, v6 dst_sel:DWORD dst_unused:UNUSED_PAD src0_sel:DWORD src1_sel:WORD_1
	v_or_b32_sdwa v4, v64, v7 dst_sel:DWORD dst_unused:UNUSED_PAD src0_sel:WORD_1 src1_sel:DWORD
	v_add_u32_e32 v97, v109, v108
	ds_write_b64 v97, v[4:5]
	v_and_b32_e32 v4, 0xffff0000, v64
	v_sub_u32_e32 v0, v0, v4
	v_sub_u32_e32 v4, v22, v7
	v_and_b32_e32 v5, 0xffff0000, v6
	v_add_u32_e32 v4, 0x80, v4
	v_sub_u32_e32 v5, v23, v5
	v_sub_u32_e32 v1, v1, v65
	v_add_u32_e32 v0, 0x80, v0
	v_ashrrev_i32_e32 v4, 8, v4
	v_add_u32_e32 v5, 0x80, v5
	v_add_u32_e32 v1, 0x80, v1
	v_ashrrev_i32_e32 v0, 8, v0
	v_min_i32_e32 v4, 0x7f, v4
	v_ashrrev_i32_e32 v5, 8, v5
	v_ashrrev_i32_e32 v1, 8, v1
	v_min_i32_e32 v0, 0x7f, v0
	v_min_i32_sdwa v5, v5, s69 dst_sel:WORD_1 dst_unused:UNUSED_PAD src0_sel:DWORD src1_sel:DWORD
	v_min_i32_e32 v1, 0x7f, v1
	v_lshlrev_b32_e32 v4, 8, v4
	v_and_b32_e32 v4, 0xff00, v4
	v_and_b32_e32 v5, 0xff0000, v5
	v_perm_b32 v0, v1, v0, s76
	v_lshrrev_b32_e32 v1, 2, v3
	v_or3_b32 v0, v0, v4, v5
	v_mad_u64_u32 v[22:23], s[18:19], v1, s68, v[2:3]
	ds_write_b32 v22, v0
	v_mov_b32_e32 v0, v200
	v_mov_b32_e32 v1, v201
	v_mov_b32_e32 v2, v202
	v_mov_b32_e32 v3, v203
	v_mov_b32_e32 v4, v220
	v_mov_b32_e32 v5, v221
	v_mov_b32_e32 v6, v222
	v_mov_b32_e32 v7, v223
	v_mov_b32_e32 v98, v180
	v_mov_b32_e32 v99, v181
	s_mul_i32 s18, s52, 0x2080
	v_add_u32_e32 v74, s18, v74
	s_mov_b32 s18, s74
	s_mov_b32 s19, s75
	v_pk_add_f32 v[100:101], v[234:235], v[98:99] op_sel_hi:[1,0] neg_lo:[0,1] neg_hi:[0,1]
	v_pk_add_f32 v[102:103], v[232:233], v[98:99] op_sel_hi:[1,0] neg_lo:[0,1] neg_hi:[0,1]
	v_pk_mul_f32 v[100:101], v[98:99], v[100:101] op_sel:[1,0]
	v_pk_mul_f32 v[98:99], v[98:99], v[102:103] op_sel:[1,0]
	v_mov_b32_e32 v64, v1
	v_mov_b32_e32 v65, v2
	v_mov_b32_e32 v66, v5
	v_mov_b32_e32 v67, v6
	v_pk_fma_f32 v[100:101], v[64:65], v[100:101], v[66:67]
	v_mov_b32_e32 v1, v3
	v_mov_b32_e32 v5, v7
	v_and_b32_sdwa v23, v100, v244 dst_sel:DWORD dst_unused:UNUSED_PAD src0_sel:WORD_1 src1_sel:DWORD
	v_pk_fma_f32 v[6:7], v[0:1], v[98:99], v[4:5]
	v_add3_u32 v23, v100, v23, s67
	v_and_b32_e32 v102, 0xffff0000, v23
	v_and_b32_sdwa v23, v7, v244 dst_sel:DWORD dst_unused:UNUSED_PAD src0_sel:WORD_1 src1_sel:DWORD
	v_and_b32_sdwa v3, v101, v244 dst_sel:DWORD dst_unused:UNUSED_PAD src0_sel:WORD_1 src1_sel:DWORD
	v_and_b32_sdwa v98, v6, v244 dst_sel:DWORD dst_unused:UNUSED_PAD src0_sel:WORD_1 src1_sel:DWORD
;     ...
;             _Pragma("unroll") for (int m = 0; m < 4; ++m) {
;               const int rr = wr3 * 64 + m * 16 + fr3;
;               const float2 ms = *reinterpret_cast<const float2*>(mr + (ai * HALF + rr) * 2);
;               f32x4 y = acc[ai][bj][m][n];
;               const float o0 = (y[0] - ms.x) * ms.y * gm.x + bt.x, o1 = (y[1] - ms.x) * ms.y * gm.y + bt.y;
;               const float o2 = (y[2] - ms.x) * ms.y * gm.z + bt.z, o3 = (y[3] - ms.x) * ms.y * gm.w + bt.w;
;               const unsigned h0 = f2bf(o0), h1 = f2bf(o1), h2 = f2bf(o2), h3 = f2bf(o3);
;               u32x2 ob; ob[0] = h0 | (h1 << 16); ob[1] = h2 | (h3 << 16);
;               *reinterpret_cast<u32x2*>(smem + (rr >> 1) * PIECE + (rr & 1) * 512 + cc * 2) = ob;
;               const int l0 = min(((int)__float_as_uint(o0) - (int)(h0 << 16) + 128) >> 8, 127);
;               const int l1 = min(((int)__float_as_uint(o1) - (int)(h1 << 16) + 128) >> 8, 127);
;               const int l2 = min(((int)__float_as_uint(o2) - (int)(h2 << 16) + 128) >> 8, 127);
;               const int l3 = min(((int)__float_as_uint(o3) - (int)(h3 << 16) + 128) >> 8, 127);
;               *reinterpret_cast<unsigned*>(smem + LOBASE + (rr >> 2) * PIECE + (rr & 3) * 256 + cc) =
;                   (unsigned)(l0 & 255) | ((unsigned)(l1 & 255) << 8) | ((unsigned)(l2 & 255) << 16) | ((unsigned)l3 << 24);
;             }
	v_add3_u32 v23, v7, v23, s67
	v_or_b32_e32 v2, 32, v109
	v_add3_u32 v3, v101, v3, s67
	v_add3_u32 v103, v6, v98, s67
	v_and_b32_e32 v104, 0xffff0000, v23
	v_or_b32_sdwa v99, v104, v3 dst_sel:DWORD dst_unused:UNUSED_PAD src0_sel:DWORD src1_sel:WORD_1
	v_or_b32_sdwa v98, v103, v102 dst_sel:DWORD dst_unused:UNUSED_PAD src0_sel:WORD_1 src1_sel:DWORD
	v_add_u32_e32 v23, v2, v105
	ds_write_b64 v23, v[98:99]
	v_and_b32_e32 v98, 0xffff0000, v103
	v_sub_u32_e32 v6, v6, v98
	v_sub_u32_e32 v98, v100, v102
	v_and_b32_e32 v3, 0xffff0000, v3
	v_add_u32_e32 v98, 0x80, v98
	v_sub_u32_e32 v3, v101, v3
	v_sub_u32_e32 v7, v7, v104
	v_add_u32_e32 v6, 0x80, v6
	v_ashrrev_i32_e32 v98, 8, v98
	v_add_u32_e32 v3, 0x80, v3
	v_add_u32_e32 v7, 0x80, v7
	v_ashrrev_i32_e32 v6, 8, v6
	v_min_i32_e32 v98, 0x7f, v98
	v_ashrrev_i32_e32 v3, 8, v3
	v_ashrrev_i32_e32 v7, 8, v7
	v_min_i32_e32 v6, 0x7f, v6
	v_min_i32_sdwa v3, v3, s69 dst_sel:WORD_1 dst_unused:UNUSED_PAD src0_sel:DWORD src1_sel:DWORD
	v_min_i32_e32 v7, 0x7f, v7
	v_lshlrev_b32_e32 v98, 8, v98
	v_and_b32_e32 v98, 0xff00, v98
	v_and_b32_e32 v3, 0xff0000, v3
	v_perm_b32 v6, v7, v6, s76
	v_or3_b32 v3, v6, v98, v3
	ds_write_b32 v12, v3 offset:16
	v_mov_b32_e32 v6, v182
	v_mov_b32_e32 v7, v183
	v_pk_add_f32 v[98:99], v[158:159], v[6:7] op_sel_hi:[1,0] neg_lo:[0,1] neg_hi:[0,1]
	s_nop 0
	v_pk_mul_f32 v[98:99], v[6:7], v[98:99] op_sel:[1,0]
	s_nop 0
	v_pk_fma_f32 v[100:101], v[64:65], v[98:99], v[66:67]
	v_pk_add_f32 v[98:99], v[156:157], v[6:7] op_sel_hi:[1,0] neg_lo:[0,1] neg_hi:[0,1]
	v_and_b32_sdwa v3, v101, v244 dst_sel:DWORD dst_unused:UNUSED_PAD src0_sel:WORD_1 src1_sel:DWORD
	v_pk_mul_f32 v[6:7], v[6:7], v[98:99] op_sel:[1,0]
	v_and_b32_sdwa v98, v100, v244 dst_sel:DWORD dst_unused:UNUSED_PAD src0_sel:WORD_1 src1_sel:DWORD
	v_pk_fma_f32 v[6:7], v[0:1], v[6:7], v[4:5]
	v_add3_u32 v98, v100, v98, s67
	v_and_b32_e32 v99, 0xffff0000, v98
	v_and_b32_sdwa v98, v7, v244 dst_sel:DWORD dst_unused:UNUSED_PAD src0_sel:WORD_1 src1_sel:DWORD
	v_and_b32_sdwa v102, v6, v244 dst_sel:DWORD dst_unused:UNUSED_PAD src0_sel:WORD_1 src1_sel:DWORD
	v_add3_u32 v98, v7, v98, s67
	v_add3_u32 v3, v101, v3, s67
	v_add3_u32 v104, v6, v102, s67
	v_and_b32_e32 v110, 0xffff0000, v98
	v_or_b32_sdwa v103, v110, v3 dst_sel:DWORD dst_unused:UNUSED_PAD src0_sel:DWORD src1_sel:WORD_1
	v_or_b32_sdwa v102, v104, v99 dst_sel:DWORD dst_unused:UNUSED_PAD src0_sel:WORD_1 src1_sel:DWORD
	v_add_u32_e32 v98, v2, v106
	ds_write_b64 v98, v[102:103]
	v_and_b32_e32 v102, 0xffff0000, v104
	v_sub_u32_e32 v99, v100, v99
	v_and_b32_e32 v3, 0xffff0000, v3
	v_sub_u32_e32 v6, v6, v102
	v_add_u32_e32 v99, 0x80, v99
	v_sub_u32_e32 v3, v101, v3
	v_sub_u32_e32 v7, v7, v110
	v_add_u32_e32 v6, 0x80, v6
	v_ashrrev_i32_e32 v99, 8, v99
	v_add_u32_e32 v3, 0x80, v3
	v_add_u32_e32 v7, 0x80, v7
	v_ashrrev_i32_e32 v6, 8, v6
	v_min_i32_e32 v99, 0x7f, v99
	v_ashrrev_i32_e32 v3, 8, v3
	v_ashrrev_i32_e32 v7, 8, v7
	v_min_i32_e32 v6, 0x7f, v6
	v_min_i32_sdwa v3, v3, s69 dst_sel:WORD_1 dst_unused:UNUSED_PAD src0_sel:DWORD src1_sel:DWORD
	v_min_i32_e32 v7, 0x7f, v7
	v_lshlrev_b32_e32 v99, 8, v99
	v_and_b32_e32 v99, 0xff00, v99
	v_and_b32_e32 v3, 0xff0000, v3
	v_perm_b32 v6, v7, v6, s76
	v_or3_b32 v3, v6, v99, v3
	ds_write_b32 v14, v3 offset:16
	v_mov_b32_e32 v6, v184
	v_mov_b32_e32 v7, v185
	v_pk_add_f32 v[100:101], v[126:127], v[6:7] op_sel_hi:[1,0] neg_lo:[0,1] neg_hi:[0,1]
	s_nop 0
	v_pk_mul_f32 v[100:101], v[6:7], v[100:101] op_sel:[1,0]
	v_pk_add_f32 v[102:103], v[124:125], v[6:7] op_sel_hi:[1,0] neg_lo:[0,1] neg_hi:[0,1]
	v_pk_fma_f32 v[100:101], v[64:65], v[100:101], v[66:67]
	v_pk_mul_f32 v[6:7], v[6:7], v[102:103] op_sel:[1,0]
	v_and_b32_sdwa v99, v100, v244 dst_sel:DWORD dst_unused:UNUSED_PAD src0_sel:WORD_1 src1_sel:DWORD
	v_pk_fma_f32 v[6:7], v[0:1], v[6:7], v[4:5]
	v_add3_u32 v99, v100, v99, s67
	v_and_b32_e32 v104, 0xffff0000, v99
	v_and_b32_sdwa v99, v7, v244 dst_sel:DWORD dst_unused:UNUSED_PAD src0_sel:WORD_1 src1_sel:DWORD
	v_and_b32_sdwa v3, v101, v244 dst_sel:DWORD dst_unused:UNUSED_PAD src0_sel:WORD_1 src1_sel:DWORD
	v_and_b32_sdwa v102, v6, v244 dst_sel:DWORD dst_unused:UNUSED_PAD src0_sel:WORD_1 src1_sel:DWORD
	v_add3_u32 v99, v7, v99, s67
	v_add3_u32 v3, v101, v3, s67
	v_add3_u32 v110, v6, v102, s67
	v_and_b32_e32 v111, 0xffff0000, v99
	v_or_b32_sdwa v103, v111, v3 dst_sel:DWORD dst_unused:UNUSED_PAD src0_sel:DWORD src1_sel:WORD_1
	v_or_b32_sdwa v102, v110, v104 dst_sel:DWORD dst_unused:UNUSED_PAD src0_sel:WORD_1 src1_sel:DWORD
	v_add_u32_e32 v99, v2, v107
	ds_write_b64 v99, v[102:103]
	v_and_b32_e32 v102, 0xffff0000, v110
	v_sub_u32_e32 v100, v100, v104
	v_and_b32_e32 v3, 0xffff0000, v3
	v_sub_u32_e32 v6, v6, v102
	v_add_u32_e32 v100, 0x80, v100
	v_sub_u32_e32 v3, v101, v3
	v_sub_u32_e32 v7, v7, v111
	v_add_u32_e32 v6, 0x80, v6
	v_ashrrev_i32_e32 v100, 8, v100
	v_add_u32_e32 v3, 0x80, v3
	v_add_u32_e32 v7, 0x80, v7
	v_ashrrev_i32_e32 v6, 8, v6
	v_min_i32_e32 v100, 0x7f, v100
	v_ashrrev_i32_e32 v3, 8, v3
	v_ashrrev_i32_e32 v7, 8, v7
	v_min_i32_e32 v6, 0x7f, v6
	v_min_i32_sdwa v3, v3, s69 dst_sel:WORD_1 dst_unused:UNUSED_PAD src0_sel:DWORD src1_sel:DWORD
	v_min_i32_e32 v7, 0x7f, v7
	v_lshlrev_b32_e32 v100, 8, v100
	v_and_b32_e32 v100, 0xff00, v100
	v_and_b32_e32 v3, 0xff0000, v3
	v_perm_b32 v6, v7, v6, s76
	v_or3_b32 v3, v6, v100, v3
	ds_write_b32 v20, v3 offset:16
	v_mov_b32_e32 v6, v186
	v_mov_b32_e32 v7, v187
	v_or_b32_e32 v104, 0x100, v109
	v_pk_add_f32 v[100:101], v[154:155], v[6:7] op_sel_hi:[1,0] neg_lo:[0,1] neg_hi:[0,1]
	s_nop 0
	v_pk_mul_f32 v[100:101], v[6:7], v[100:101] op_sel:[1,0]
	s_nop 0
	v_pk_fma_f32 v[64:65], v[64:65], v[100:101], v[66:67]
;     ...
;             _Pragma("unroll") for (int m = 0; m < 4; ++m) {
;               const int rr = wr3 * 64 + m * 16 + fr3;
;               const float2 ms = *reinterpret_cast<const float2*>(mr + (ai * HALF + rr) * 2);
;               f32x4 y = acc[ai][bj][m][n];
;               const float o0 = (y[0] - ms.x) * ms.y * gm.x + bt.x, o1 = (y[1] - ms.x) * ms.y * gm.y + bt.y;
;               const float o2 = (y[2] - ms.x) * ms.y * gm.z + bt.z, o3 = (y[3] - ms.x) * ms.y * gm.w + bt.w;
;               const unsigned h0 = f2bf(o0), h1 = f2bf(o1), h2 = f2bf(o2), h3 = f2bf(o3);
;               u32x2 ob; ob[0] = h0 | (h1 << 16); ob[1] = h2 | (h3 << 16);
;               *reinterpret_cast<u32x2*>(smem + (rr >> 1) * PIECE + (rr & 1) * 512 + cc * 2) = ob;
;               const int l0 = min(((int)__float_as_uint(o0) - (int)(h0 << 16) + 128) >> 8, 127);
;               const int l1 = min(((int)__float_as_uint(o1) - (int)(h1 << 16) + 128) >> 8, 127);
;               const int l2 = min(((int)__float_as_uint(o2) - (int)(h2 << 16) + 128) >> 8, 127);
;               const int l3 = min(((int)__float_as_uint(o3) - (int)(h3 << 16) + 128) >> 8, 127);
;               *reinterpret_cast<unsigned*>(smem + LOBASE + (rr >> 2) * PIECE + (rr & 3) * 256 + cc) =
;                   (unsigned)(l0 & 255) | ((unsigned)(l1 & 255) << 8) | ((unsigned)(l2 & 255) << 16) | ((unsigned)l3 << 24);
;             }
	v_pk_add_f32 v[66:67], v[152:153], v[6:7] op_sel_hi:[1,0] neg_lo:[0,1] neg_hi:[0,1]
	v_and_b32_sdwa v3, v65, v244 dst_sel:DWORD dst_unused:UNUSED_PAD src0_sel:WORD_1 src1_sel:DWORD
	v_pk_mul_f32 v[6:7], v[6:7], v[66:67] op_sel:[1,0]
	v_add3_u32 v3, v65, v3, s67
	v_pk_fma_f32 v[0:1], v[0:1], v[6:7], v[4:5]
	v_and_b32_sdwa v4, v64, v244 dst_sel:DWORD dst_unused:UNUSED_PAD src0_sel:WORD_1 src1_sel:DWORD
	v_add3_u32 v4, v64, v4, s67
	v_and_b32_e32 v6, 0xffff0000, v4
	v_and_b32_sdwa v4, v1, v244 dst_sel:DWORD dst_unused:UNUSED_PAD src0_sel:WORD_1 src1_sel:DWORD
	v_and_b32_sdwa v5, v0, v244 dst_sel:DWORD dst_unused:UNUSED_PAD src0_sel:WORD_1 src1_sel:DWORD
	v_add3_u32 v4, v1, v4, s67
	v_add3_u32 v7, v0, v5, s67
	v_and_b32_e32 v66, 0xffff0000, v4
	v_add_u32_e32 v100, v2, v108
	v_and_b32_e32 v2, 0xffff0000, v7
	v_or_b32_sdwa v5, v66, v3 dst_sel:DWORD dst_unused:UNUSED_PAD src0_sel:DWORD src1_sel:WORD_1
	v_sub_u32_e32 v0, v0, v2
	v_sub_u32_e32 v2, v64, v6
	v_and_b32_e32 v3, 0xffff0000, v3
	v_add_u32_e32 v2, 0x80, v2
	v_sub_u32_e32 v3, v65, v3
	v_sub_u32_e32 v1, v1, v66
	v_add_u32_e32 v0, 0x80, v0
	v_ashrrev_i32_e32 v2, 8, v2
	v_add_u32_e32 v3, 0x80, v3
	v_add_u32_e32 v1, 0x80, v1
	v_ashrrev_i32_e32 v0, 8, v0
	v_min_i32_e32 v2, 0x7f, v2
	v_ashrrev_i32_e32 v3, 8, v3
	v_ashrrev_i32_e32 v1, 8, v1
	v_min_i32_e32 v0, 0x7f, v0
	v_min_i32_sdwa v3, v3, s69 dst_sel:WORD_1 dst_unused:UNUSED_PAD src0_sel:DWORD src1_sel:DWORD
	v_min_i32_e32 v1, 0x7f, v1
	v_lshlrev_b32_e32 v2, 8, v2
	v_and_b32_e32 v2, 0xff00, v2
	v_and_b32_e32 v3, 0xff0000, v3
	v_perm_b32 v0, v1, v0, s76
	v_or_b32_sdwa v4, v7, v6 dst_sel:DWORD dst_unused:UNUSED_PAD src0_sel:WORD_1 src1_sel:DWORD
	v_or3_b32 v0, v0, v2, v3
	ds_write_b64 v100, v[4:5]
	ds_write_b32 v22, v0 offset:16
	v_mov_b32_e32 v0, v204
	v_mov_b32_e32 v1, v205
	v_mov_b32_e32 v2, v206
	v_mov_b32_e32 v3, v207
	v_mov_b32_e32 v4, v240
	v_mov_b32_e32 v5, v241
	v_mov_b32_e32 v6, v242
	v_mov_b32_e32 v7, v243
	v_mov_b32_e32 v102, v180
	v_mov_b32_e32 v103, v181
	v_add_u32_e32 v101, v104, v105
	v_pk_add_f32 v[110:111], v[230:231], v[102:103] op_sel_hi:[1,0] neg_lo:[0,1] neg_hi:[0,1]
	s_nop 0
	v_pk_mul_f32 v[110:111], v[102:103], v[110:111] op_sel:[1,0]
	v_pk_add_f32 v[124:125], v[228:229], v[102:103] op_sel_hi:[1,0] neg_lo:[0,1] neg_hi:[0,1]
	v_mov_b32_e32 v64, v1
	v_mov_b32_e32 v65, v2
	v_mov_b32_e32 v66, v5
	v_mov_b32_e32 v67, v6
	v_pk_fma_f32 v[110:111], v[64:65], v[110:111], v[66:67]
	v_pk_mul_f32 v[102:103], v[102:103], v[124:125] op_sel:[1,0]
	v_mov_b32_e32 v1, v3
	v_mov_b32_e32 v5, v7
	v_and_b32_sdwa v6, v111, v244 dst_sel:DWORD dst_unused:UNUSED_PAD src0_sel:WORD_1 src1_sel:DWORD
	v_and_b32_sdwa v7, v110, v244 dst_sel:DWORD dst_unused:UNUSED_PAD src0_sel:WORD_1 src1_sel:DWORD
	v_pk_fma_f32 v[2:3], v[0:1], v[102:103], v[4:5]
	v_add3_u32 v102, v111, v6, s67
	v_add3_u32 v6, v110, v7, s67
	v_and_b32_e32 v103, 0xffff0000, v6
	v_and_b32_sdwa v6, v3, v244 dst_sel:DWORD dst_unused:UNUSED_PAD src0_sel:WORD_1 src1_sel:DWORD
	v_and_b32_sdwa v7, v2, v244 dst_sel:DWORD dst_unused:UNUSED_PAD src0_sel:WORD_1 src1_sel:DWORD
	v_add3_u32 v6, v3, v6, s67
	v_add3_u32 v124, v2, v7, s67
	v_and_b32_e32 v125, 0xffff0000, v6
	v_or_b32_sdwa v7, v125, v102 dst_sel:DWORD dst_unused:UNUSED_PAD src0_sel:DWORD src1_sel:WORD_1
	v_or_b32_sdwa v6, v124, v103 dst_sel:DWORD dst_unused:UNUSED_PAD src0_sel:WORD_1 src1_sel:DWORD
	ds_write_b64 v101, v[6:7]
	v_and_b32_e32 v6, 0xffff0000, v124
	v_sub_u32_e32 v2, v2, v6
	v_sub_u32_e32 v6, v110, v103
	v_and_b32_e32 v7, 0xffff0000, v102
	v_add_u32_e32 v6, 0x80, v6
	v_sub_u32_e32 v7, v111, v7
	v_sub_u32_e32 v3, v3, v125
	v_add_u32_e32 v2, 0x80, v2
	v_ashrrev_i32_e32 v6, 8, v6
	v_add_u32_e32 v7, 0x80, v7
	v_add_u32_e32 v3, 0x80, v3
	v_ashrrev_i32_e32 v2, 8, v2
	v_min_i32_e32 v6, 0x7f, v6
	v_ashrrev_i32_e32 v7, 8, v7
	v_ashrrev_i32_e32 v3, 8, v3
	v_min_i32_e32 v2, 0x7f, v2
	v_min_i32_sdwa v7, v7, s69 dst_sel:WORD_1 dst_unused:UNUSED_PAD src0_sel:DWORD src1_sel:DWORD
	v_min_i32_e32 v3, 0x7f, v3
	v_lshlrev_b32_e32 v6, 8, v6
	v_and_b32_e32 v6, 0xff00, v6
	v_and_b32_e32 v7, 0xff0000, v7
	v_perm_b32 v2, v3, v2, s76
	v_or3_b32 v2, v2, v6, v7
	ds_write_b32 v12, v2 offset:128
	v_mov_b32_e32 v2, v182
	v_mov_b32_e32 v3, v183
	v_pk_add_f32 v[6:7], v[150:151], v[2:3] op_sel_hi:[1,0] neg_lo:[0,1] neg_hi:[0,1]
	s_nop 0
	v_pk_mul_f32 v[6:7], v[2:3], v[6:7] op_sel:[1,0]
	v_pk_add_f32 v[102:103], v[148:149], v[2:3] op_sel_hi:[1,0] neg_lo:[0,1] neg_hi:[0,1]
	v_pk_fma_f32 v[6:7], v[64:65], v[6:7], v[66:67]
	v_pk_mul_f32 v[2:3], v[2:3], v[102:103] op_sel:[1,0]
	v_and_b32_sdwa v102, v7, v244 dst_sel:DWORD dst_unused:UNUSED_PAD src0_sel:WORD_1 src1_sel:DWORD
	v_and_b32_sdwa v103, v6, v244 dst_sel:DWORD dst_unused:UNUSED_PAD src0_sel:WORD_1 src1_sel:DWORD
	v_pk_fma_f32 v[2:3], v[0:1], v[2:3], v[4:5]
	v_add3_u32 v124, v7, v102, s67
	v_add3_u32 v102, v6, v103, s67
	v_and_b32_e32 v103, 0xffff0000, v102
	v_and_b32_sdwa v102, v3, v244 dst_sel:DWORD dst_unused:UNUSED_PAD src0_sel:WORD_1 src1_sel:DWORD
	v_and_b32_sdwa v110, v2, v244 dst_sel:DWORD dst_unused:UNUSED_PAD src0_sel:WORD_1 src1_sel:DWORD
	v_add3_u32 v102, v3, v102, s67
	v_add3_u32 v125, v2, v110, s67
	v_and_b32_e32 v126, 0xffff0000, v102
	v_or_b32_sdwa v111, v126, v124 dst_sel:DWORD dst_unused:UNUSED_PAD src0_sel:DWORD src1_sel:WORD_1
	v_or_b32_sdwa v110, v125, v103 dst_sel:DWORD dst_unused:UNUSED_PAD src0_sel:WORD_1 src1_sel:DWORD
	v_add_u32_e32 v102, v104, v106
	ds_write_b64 v102, v[110:111]
	v_and_b32_e32 v110, 0xffff0000, v125
	v_sub_u32_e32 v6, v6, v103
	v_and_b32_e32 v103, 0xffff0000, v124
	v_sub_u32_e32 v2, v2, v110
	v_add_u32_e32 v6, 0x80, v6
	v_sub_u32_e32 v7, v7, v103
;     ...
;             _Pragma("unroll") for (int m = 0; m < 4; ++m) {
;               const int rr = wr3 * 64 + m * 16 + fr3;
;               const float2 ms = *reinterpret_cast<const float2*>(mr + (ai * HALF + rr) * 2);
;               f32x4 y = acc[ai][bj][m][n];
;               const float o0 = (y[0] - ms.x) * ms.y * gm.x + bt.x, o1 = (y[1] - ms.x) * ms.y * gm.y + bt.y;
;               const float o2 = (y[2] - ms.x) * ms.y * gm.z + bt.z, o3 = (y[3] - ms.x) * ms.y * gm.w + bt.w;
;               const unsigned h0 = f2bf(o0), h1 = f2bf(o1), h2 = f2bf(o2), h3 = f2bf(o3);
;               u32x2 ob; ob[0] = h0 | (h1 << 16); ob[1] = h2 | (h3 << 16);
;               *reinterpret_cast<u32x2*>(smem + (rr >> 1) * PIECE + (rr & 1) * 512 + cc * 2) = ob;
;               const int l0 = min(((int)__float_as_uint(o0) - (int)(h0 << 16) + 128) >> 8, 127);
;               const int l1 = min(((int)__float_as_uint(o1) - (int)(h1 << 16) + 128) >> 8, 127);
;               const int l2 = min(((int)__float_as_uint(o2) - (int)(h2 << 16) + 128) >> 8, 127);
;               const int l3 = min(((int)__float_as_uint(o3) - (int)(h3 << 16) + 128) >> 8, 127);
;               *reinterpret_cast<unsigned*>(smem + LOBASE + (rr >> 2) * PIECE + (rr & 3) * 256 + cc) =
;                   (unsigned)(l0 & 255) | ((unsigned)(l1 & 255) << 8) | ((unsigned)(l2 & 255) << 16) | ((unsigned)l3 << 24);
;             }
	v_sub_u32_e32 v3, v3, v126
	v_add_u32_e32 v2, 0x80, v2
	v_ashrrev_i32_e32 v6, 8, v6
	v_add_u32_e32 v7, 0x80, v7
	v_add_u32_e32 v3, 0x80, v3
	v_ashrrev_i32_e32 v2, 8, v2
	v_min_i32_e32 v6, 0x7f, v6
	v_ashrrev_i32_e32 v7, 8, v7
	v_ashrrev_i32_e32 v3, 8, v3
	v_min_i32_e32 v2, 0x7f, v2
	v_min_i32_sdwa v7, v7, s69 dst_sel:WORD_1 dst_unused:UNUSED_PAD src0_sel:DWORD src1_sel:DWORD
	v_min_i32_e32 v3, 0x7f, v3
	v_lshlrev_b32_e32 v6, 8, v6
	v_and_b32_e32 v6, 0xff00, v6
	v_and_b32_e32 v7, 0xff0000, v7
	v_perm_b32 v2, v3, v2, s76
	v_or3_b32 v2, v2, v6, v7
	ds_write_b32 v14, v2 offset:128
	v_mov_b32_e32 v2, v184
	v_mov_b32_e32 v3, v185
	v_pk_add_f32 v[6:7], v[118:119], v[2:3] op_sel_hi:[1,0] neg_lo:[0,1] neg_hi:[0,1]
	s_nop 0
	v_pk_mul_f32 v[6:7], v[2:3], v[6:7] op_sel:[1,0]
	v_pk_add_f32 v[110:111], v[116:117], v[2:3] op_sel_hi:[1,0] neg_lo:[0,1] neg_hi:[0,1]
	v_pk_fma_f32 v[6:7], v[64:65], v[6:7], v[66:67]
	v_pk_mul_f32 v[2:3], v[2:3], v[110:111] op_sel:[1,0]
	v_and_b32_sdwa v103, v7, v244 dst_sel:DWORD dst_unused:UNUSED_PAD src0_sel:WORD_1 src1_sel:DWORD
	v_and_b32_sdwa v110, v6, v244 dst_sel:DWORD dst_unused:UNUSED_PAD src0_sel:WORD_1 src1_sel:DWORD
	v_pk_fma_f32 v[2:3], v[0:1], v[2:3], v[4:5]
	v_add3_u32 v116, v7, v103, s67
	v_add3_u32 v103, v6, v110, s67
	v_and_b32_e32 v117, 0xffff0000, v103
	v_and_b32_sdwa v103, v3, v244 dst_sel:DWORD dst_unused:UNUSED_PAD src0_sel:WORD_1 src1_sel:DWORD
	v_and_b32_sdwa v110, v2, v244 dst_sel:DWORD dst_unused:UNUSED_PAD src0_sel:WORD_1 src1_sel:DWORD
	v_add3_u32 v103, v3, v103, s67
	v_add3_u32 v118, v2, v110, s67
	v_and_b32_e32 v119, 0xffff0000, v103
	v_or_b32_sdwa v111, v119, v116 dst_sel:DWORD dst_unused:UNUSED_PAD src0_sel:DWORD src1_sel:WORD_1
	v_or_b32_sdwa v110, v118, v117 dst_sel:DWORD dst_unused:UNUSED_PAD src0_sel:WORD_1 src1_sel:DWORD
	v_add_u32_e32 v103, v104, v107
	ds_write_b64 v103, v[110:111]
	v_and_b32_e32 v110, 0xffff0000, v118
	v_sub_u32_e32 v2, v2, v110
	v_sub_u32_e32 v6, v6, v117
	v_and_b32_e32 v110, 0xffff0000, v116
	v_add_u32_e32 v6, 0x80, v6
	v_sub_u32_e32 v7, v7, v110
	v_sub_u32_e32 v3, v3, v119
	v_add_u32_e32 v2, 0x80, v2
	v_ashrrev_i32_e32 v6, 8, v6
	v_add_u32_e32 v7, 0x80, v7
	v_add_u32_e32 v3, 0x80, v3
	v_ashrrev_i32_e32 v2, 8, v2
	v_min_i32_e32 v6, 0x7f, v6
	v_ashrrev_i32_e32 v7, 8, v7
	v_ashrrev_i32_e32 v3, 8, v3
	v_min_i32_e32 v2, 0x7f, v2
	v_min_i32_sdwa v7, v7, s69 dst_sel:WORD_1 dst_unused:UNUSED_PAD src0_sel:DWORD src1_sel:DWORD
	v_min_i32_e32 v3, 0x7f, v3
	v_lshlrev_b32_e32 v6, 8, v6
	v_and_b32_e32 v6, 0xff00, v6
	v_and_b32_e32 v7, 0xff0000, v7
	v_perm_b32 v2, v3, v2, s76
	v_or3_b32 v2, v2, v6, v7
	ds_write_b32 v20, v2 offset:128
	v_mov_b32_e32 v2, v186
	v_mov_b32_e32 v3, v187
	v_add_u32_e32 v104, v104, v108
	v_pk_add_f32 v[6:7], v[122:123], v[2:3] op_sel_hi:[1,0] neg_lo:[0,1] neg_hi:[0,1]
	s_nop 0
	v_pk_mul_f32 v[6:7], v[2:3], v[6:7] op_sel:[1,0]
	s_nop 0
	v_pk_fma_f32 v[6:7], v[64:65], v[6:7], v[66:67]
	v_pk_add_f32 v[64:65], v[120:121], v[2:3] op_sel_hi:[1,0] neg_lo:[0,1] neg_hi:[0,1]
	s_nop 0
	v_pk_mul_f32 v[2:3], v[2:3], v[64:65] op_sel:[1,0]
	s_nop 0
	v_pk_fma_f32 v[0:1], v[0:1], v[2:3], v[4:5]
	v_and_b32_sdwa v2, v7, v244 dst_sel:DWORD dst_unused:UNUSED_PAD src0_sel:WORD_1 src1_sel:DWORD
	v_and_b32_sdwa v3, v6, v244 dst_sel:DWORD dst_unused:UNUSED_PAD src0_sel:WORD_1 src1_sel:DWORD
	v_add3_u32 v4, v7, v2, s67
	v_add3_u32 v2, v6, v3, s67
	v_and_b32_e32 v5, 0xffff0000, v2
	v_and_b32_sdwa v2, v1, v244 dst_sel:DWORD dst_unused:UNUSED_PAD src0_sel:WORD_1 src1_sel:DWORD
	v_and_b32_sdwa v3, v0, v244 dst_sel:DWORD dst_unused:UNUSED_PAD src0_sel:WORD_1 src1_sel:DWORD
	v_add3_u32 v2, v1, v2, s67
	v_add3_u32 v64, v0, v3, s67
	v_and_b32_e32 v65, 0xffff0000, v2
	v_or_b32_sdwa v3, v65, v4 dst_sel:DWORD dst_unused:UNUSED_PAD src0_sel:DWORD src1_sel:WORD_1
	v_or_b32_sdwa v2, v64, v5 dst_sel:DWORD dst_unused:UNUSED_PAD src0_sel:WORD_1 src1_sel:DWORD
	ds_write_b64 v104, v[2:3]
	v_and_b32_e32 v2, 0xffff0000, v64
	v_sub_u32_e32 v0, v0, v2
	v_sub_u32_e32 v2, v6, v5
	v_and_b32_e32 v3, 0xffff0000, v4
	v_add_u32_e32 v2, 0x80, v2
	v_sub_u32_e32 v3, v7, v3
	v_sub_u32_e32 v1, v1, v65
	v_add_u32_e32 v0, 0x80, v0
	v_ashrrev_i32_e32 v2, 8, v2
	v_add_u32_e32 v3, 0x80, v3
	v_add_u32_e32 v1, 0x80, v1
	v_ashrrev_i32_e32 v0, 8, v0
	v_min_i32_e32 v2, 0x7f, v2
	v_ashrrev_i32_e32 v3, 8, v3
	v_ashrrev_i32_e32 v1, 8, v1
	v_min_i32_e32 v0, 0x7f, v0
	v_min_i32_sdwa v3, v3, s69 dst_sel:WORD_1 dst_unused:UNUSED_PAD src0_sel:DWORD src1_sel:DWORD
	v_min_i32_e32 v1, 0x7f, v1
	v_lshlrev_b32_e32 v2, 8, v2
	v_and_b32_e32 v2, 0xff00, v2
	v_and_b32_e32 v3, 0xff0000, v3
	v_perm_b32 v0, v1, v0, s76
	v_or3_b32 v0, v0, v2, v3
	ds_write_b32 v22, v0 offset:128
	v_mov_b32_e32 v0, v208
	v_mov_b32_e32 v1, v209
	v_mov_b32_e32 v2, v210
	v_mov_b32_e32 v3, v211
	v_mov_b32_e32 v4, v248
	v_mov_b32_e32 v5, v249
	v_mov_b32_e32 v6, v250
	v_mov_b32_e32 v7, v251
	v_mov_b32_e32 v110, v180
	v_mov_b32_e32 v111, v181
	v_pk_add_f32 v[116:117], v[226:227], v[110:111] op_sel_hi:[1,0] neg_lo:[0,1] neg_hi:[0,1]
	v_pk_add_f32 v[118:119], v[224:225], v[110:111] op_sel_hi:[1,0] neg_lo:[0,1] neg_hi:[0,1]
	v_pk_mul_f32 v[116:117], v[110:111], v[116:117] op_sel:[1,0]
	v_pk_mul_f32 v[110:111], v[110:111], v[118:119] op_sel:[1,0]
	v_mov_b32_e32 v64, v1
	v_mov_b32_e32 v65, v2
	v_mov_b32_e32 v66, v5
	v_mov_b32_e32 v67, v6
	v_mov_b32_e32 v1, v3
	v_mov_b32_e32 v5, v7
	v_pk_fma_f32 v[116:117], v[64:65], v[116:117], v[66:67]
	v_pk_fma_f32 v[6:7], v[0:1], v[110:111], v[4:5]
	v_or_b32_e32 v2, 0x120, v109
	v_and_b32_sdwa v109, v116, v244 dst_sel:DWORD dst_unused:UNUSED_PAD src0_sel:WORD_1 src1_sel:DWORD
	v_and_b32_sdwa v110, v7, v244 dst_sel:DWORD dst_unused:UNUSED_PAD src0_sel:WORD_1 src1_sel:DWORD
;     ...
;             _Pragma("unroll") for (int m = 0; m < 4; ++m) {
;               const int rr = wr3 * 64 + m * 16 + fr3;
;               const float2 ms = *reinterpret_cast<const float2*>(mr + (ai * HALF + rr) * 2);
;               f32x4 y = acc[ai][bj][m][n];
;               const float o0 = (y[0] - ms.x) * ms.y * gm.x + bt.x, o1 = (y[1] - ms.x) * ms.y * gm.y + bt.y;
;               const float o2 = (y[2] - ms.x) * ms.y * gm.z + bt.z, o3 = (y[3] - ms.x) * ms.y * gm.w + bt.w;
;               const unsigned h0 = f2bf(o0), h1 = f2bf(o1), h2 = f2bf(o2), h3 = f2bf(o3);
;               u32x2 ob; ob[0] = h0 | (h1 << 16); ob[1] = h2 | (h3 << 16);
;               *reinterpret_cast<u32x2*>(smem + (rr >> 1) * PIECE + (rr & 1) * 512 + cc * 2) = ob;
;               const int l0 = min(((int)__float_as_uint(o0) - (int)(h0 << 16) + 128) >> 8, 127);
;               const int l1 = min(((int)__float_as_uint(o1) - (int)(h1 << 16) + 128) >> 8, 127);
;               const int l2 = min(((int)__float_as_uint(o2) - (int)(h2 << 16) + 128) >> 8, 127);
;               const int l3 = min(((int)__float_as_uint(o3) - (int)(h3 << 16) + 128) >> 8, 127);
;               *reinterpret_cast<unsigned*>(smem + LOBASE + (rr >> 2) * PIECE + (rr & 3) * 256 + cc) =
;                   (unsigned)(l0 & 255) | ((unsigned)(l1 & 255) << 8) | ((unsigned)(l2 & 255) << 16) | ((unsigned)l3 << 24);
;             }
	v_and_b32_sdwa v3, v117, v244 dst_sel:DWORD dst_unused:UNUSED_PAD src0_sel:WORD_1 src1_sel:DWORD
	v_add3_u32 v109, v116, v109, s67
	v_and_b32_sdwa v111, v6, v244 dst_sel:DWORD dst_unused:UNUSED_PAD src0_sel:WORD_1 src1_sel:DWORD
	v_add3_u32 v110, v7, v110, s67
	v_add3_u32 v3, v117, v3, s67
	v_and_b32_e32 v109, 0xffff0000, v109
	v_add3_u32 v118, v6, v111, s67
	v_and_b32_e32 v119, 0xffff0000, v110
	v_or_b32_sdwa v111, v119, v3 dst_sel:DWORD dst_unused:UNUSED_PAD src0_sel:DWORD src1_sel:WORD_1
	v_or_b32_sdwa v110, v118, v109 dst_sel:DWORD dst_unused:UNUSED_PAD src0_sel:WORD_1 src1_sel:DWORD
	v_add_u32_e32 v105, v2, v105
	ds_write_b64 v105, v[110:111]
	v_and_b32_e32 v110, 0xffff0000, v118
	v_sub_u32_e32 v109, v116, v109
	v_and_b32_e32 v3, 0xffff0000, v3
	v_sub_u32_e32 v6, v6, v110
	v_add_u32_e32 v109, 0x80, v109
	v_sub_u32_e32 v3, v117, v3
	v_sub_u32_e32 v7, v7, v119
	v_add_u32_e32 v6, 0x80, v6
	v_ashrrev_i32_e32 v109, 8, v109
	v_add_u32_e32 v3, 0x80, v3
	v_add_u32_e32 v7, 0x80, v7
	v_ashrrev_i32_e32 v6, 8, v6
	v_min_i32_e32 v109, 0x7f, v109
	v_ashrrev_i32_e32 v3, 8, v3
	v_ashrrev_i32_e32 v7, 8, v7
	v_min_i32_e32 v6, 0x7f, v6
	v_min_i32_sdwa v3, v3, s69 dst_sel:WORD_1 dst_unused:UNUSED_PAD src0_sel:DWORD src1_sel:DWORD
	v_min_i32_e32 v7, 0x7f, v7
	v_lshlrev_b32_e32 v109, 8, v109
	v_and_b32_e32 v109, 0xff00, v109
	v_and_b32_e32 v3, 0xff0000, v3
	v_perm_b32 v6, v7, v6, s76
	v_or3_b32 v3, v6, v109, v3
	ds_write_b32 v12, v3 offset:144
	v_mov_b32_e32 v6, v182
	v_mov_b32_e32 v7, v183
	v_add_u32_e32 v106, v2, v106
	v_add_u32_e32 v107, v2, v107
	v_pk_add_f32 v[110:111], v[146:147], v[6:7] op_sel_hi:[1,0] neg_lo:[0,1] neg_hi:[0,1]
	v_pk_add_f32 v[116:117], v[144:145], v[6:7] op_sel_hi:[1,0] neg_lo:[0,1] neg_hi:[0,1]
	v_pk_mul_f32 v[110:111], v[6:7], v[110:111] op_sel:[1,0]
	v_pk_mul_f32 v[6:7], v[6:7], v[116:117] op_sel:[1,0]
	v_pk_fma_f32 v[110:111], v[64:65], v[110:111], v[66:67]
	v_pk_fma_f32 v[6:7], v[0:1], v[6:7], v[4:5]
	v_and_b32_sdwa v109, v110, v244 dst_sel:DWORD dst_unused:UNUSED_PAD src0_sel:WORD_1 src1_sel:DWORD
	v_and_b32_sdwa v116, v7, v244 dst_sel:DWORD dst_unused:UNUSED_PAD src0_sel:WORD_1 src1_sel:DWORD
	v_and_b32_sdwa v3, v111, v244 dst_sel:DWORD dst_unused:UNUSED_PAD src0_sel:WORD_1 src1_sel:DWORD
	v_add3_u32 v109, v110, v109, s67
	v_and_b32_sdwa v117, v6, v244 dst_sel:DWORD dst_unused:UNUSED_PAD src0_sel:WORD_1 src1_sel:DWORD
	v_add3_u32 v116, v7, v116, s67
	v_add3_u32 v3, v111, v3, s67
	v_and_b32_e32 v109, 0xffff0000, v109
	v_add3_u32 v118, v6, v117, s67
	v_and_b32_e32 v119, 0xffff0000, v116
	v_or_b32_sdwa v117, v119, v3 dst_sel:DWORD dst_unused:UNUSED_PAD src0_sel:DWORD src1_sel:WORD_1
	v_or_b32_sdwa v116, v118, v109 dst_sel:DWORD dst_unused:UNUSED_PAD src0_sel:WORD_1 src1_sel:DWORD
	ds_write_b64 v106, v[116:117]
	v_and_b32_e32 v116, 0xffff0000, v118
	v_sub_u32_e32 v109, v110, v109
	v_and_b32_e32 v3, 0xffff0000, v3
	v_sub_u32_e32 v6, v6, v116
	v_add_u32_e32 v109, 0x80, v109
	v_sub_u32_e32 v3, v111, v3
	v_sub_u32_e32 v7, v7, v119
	v_add_u32_e32 v6, 0x80, v6
	v_ashrrev_i32_e32 v109, 8, v109
	v_add_u32_e32 v3, 0x80, v3
	v_add_u32_e32 v7, 0x80, v7
	v_ashrrev_i32_e32 v6, 8, v6
	v_min_i32_e32 v109, 0x7f, v109
	v_ashrrev_i32_e32 v3, 8, v3
	v_ashrrev_i32_e32 v7, 8, v7
	v_min_i32_e32 v6, 0x7f, v6
	v_min_i32_sdwa v3, v3, s69 dst_sel:WORD_1 dst_unused:UNUSED_PAD src0_sel:DWORD src1_sel:DWORD
	v_min_i32_e32 v7, 0x7f, v7
	v_lshlrev_b32_e32 v109, 8, v109
	v_and_b32_e32 v109, 0xff00, v109
	v_and_b32_e32 v3, 0xff0000, v3
	v_perm_b32 v6, v7, v6, s76
	v_or3_b32 v3, v6, v109, v3
	ds_write_b32 v14, v3 offset:144
	v_mov_b32_e32 v6, v184
	v_mov_b32_e32 v7, v185
	v_pk_add_f32 v[110:111], v[114:115], v[6:7] op_sel_hi:[1,0] neg_lo:[0,1] neg_hi:[0,1]
	v_pk_add_f32 v[112:113], v[112:113], v[6:7] op_sel_hi:[1,0] neg_lo:[0,1] neg_hi:[0,1]
	v_pk_mul_f32 v[110:111], v[6:7], v[110:111] op_sel:[1,0]
	v_pk_mul_f32 v[6:7], v[6:7], v[112:113] op_sel:[1,0]
	v_pk_fma_f32 v[110:111], v[64:65], v[110:111], v[66:67]
	v_pk_fma_f32 v[6:7], v[0:1], v[6:7], v[4:5]
	v_and_b32_sdwa v109, v110, v244 dst_sel:DWORD dst_unused:UNUSED_PAD src0_sel:WORD_1 src1_sel:DWORD
	v_and_b32_sdwa v112, v7, v244 dst_sel:DWORD dst_unused:UNUSED_PAD src0_sel:WORD_1 src1_sel:DWORD
	v_and_b32_sdwa v3, v111, v244 dst_sel:DWORD dst_unused:UNUSED_PAD src0_sel:WORD_1 src1_sel:DWORD
	v_add3_u32 v109, v110, v109, s67
	v_and_b32_sdwa v113, v6, v244 dst_sel:DWORD dst_unused:UNUSED_PAD src0_sel:WORD_1 src1_sel:DWORD
	v_add3_u32 v112, v7, v112, s67
	v_add3_u32 v3, v111, v3, s67
	v_and_b32_e32 v109, 0xffff0000, v109
	v_add3_u32 v114, v6, v113, s67
	v_and_b32_e32 v115, 0xffff0000, v112
	v_or_b32_sdwa v113, v115, v3 dst_sel:DWORD dst_unused:UNUSED_PAD src0_sel:DWORD src1_sel:WORD_1
	v_or_b32_sdwa v112, v114, v109 dst_sel:DWORD dst_unused:UNUSED_PAD src0_sel:WORD_1 src1_sel:DWORD
	ds_write_b64 v107, v[112:113]
	v_and_b32_e32 v112, 0xffff0000, v114
	v_sub_u32_e32 v109, v110, v109
	v_and_b32_e32 v3, 0xffff0000, v3
	v_sub_u32_e32 v6, v6, v112
	v_add_u32_e32 v109, 0x80, v109
	v_sub_u32_e32 v3, v111, v3
	v_sub_u32_e32 v7, v7, v115
	v_add_u32_e32 v6, 0x80, v6
	v_ashrrev_i32_e32 v109, 8, v109
	v_add_u32_e32 v3, 0x80, v3
	v_add_u32_e32 v7, 0x80, v7
	v_ashrrev_i32_e32 v6, 8, v6
	v_min_i32_e32 v109, 0x7f, v109
	v_ashrrev_i32_e32 v3, 8, v3
	v_ashrrev_i32_e32 v7, 8, v7
	v_min_i32_e32 v6, 0x7f, v6
	v_min_i32_sdwa v3, v3, s69 dst_sel:WORD_1 dst_unused:UNUSED_PAD src0_sel:DWORD src1_sel:DWORD
	v_min_i32_e32 v7, 0x7f, v7
	v_lshlrev_b32_e32 v109, 8, v109
	v_and_b32_e32 v109, 0xff00, v109
	v_and_b32_e32 v3, 0xff0000, v3
	v_perm_b32 v6, v7, v6, s76
	v_or3_b32 v3, v6, v109, v3
	ds_write_b32 v20, v3 offset:144
	v_mov_b32_e32 v6, v186
; #define WAIT_L(n) asm volatile("s_waitcnt lgkmcnt(" #n ")" ::: "memory")
; #define BAR __builtin_amdgcn_s_barrier()
;     ...
;             _Pragma("unroll") for (int m = 0; m < 4; ++m) {
;               const int rr = wr3 * 64 + m * 16 + fr3;
;               const float2 ms = *reinterpret_cast<const float2*>(mr + (ai * HALF + rr) * 2);
;               f32x4 y = acc[ai][bj][m][n];
;               const float o0 = (y[0] - ms.x) * ms.y * gm.x + bt.x, o1 = (y[1] - ms.x) * ms.y * gm.y + bt.y;
;               const float o2 = (y[2] - ms.x) * ms.y * gm.z + bt.z, o3 = (y[3] - ms.x) * ms.y * gm.w + bt.w;
;               const unsigned h0 = f2bf(o0), h1 = f2bf(o1), h2 = f2bf(o2), h3 = f2bf(o3);
;               u32x2 ob; ob[0] = h0 | (h1 << 16); ob[1] = h2 | (h3 << 16);
;               *reinterpret_cast<u32x2*>(smem + (rr >> 1) * PIECE + (rr & 1) * 512 + cc * 2) = ob;
;               const int l0 = min(((int)__float_as_uint(o0) - (int)(h0 << 16) + 128) >> 8, 127);
;               const int l1 = min(((int)__float_as_uint(o1) - (int)(h1 << 16) + 128) >> 8, 127);
;               const int l2 = min(((int)__float_as_uint(o2) - (int)(h2 << 16) + 128) >> 8, 127);
;               const int l3 = min(((int)__float_as_uint(o3) - (int)(h3 << 16) + 128) >> 8, 127);
;               *reinterpret_cast<unsigned*>(smem + LOBASE + (rr >> 2) * PIECE + (rr & 3) * 256 + cc) =
;                   (unsigned)(l0 & 255) | ((unsigned)(l1 & 255) << 8) | ((unsigned)(l2 & 255) << 16) | ((unsigned)l3 << 24);
;             }
;           }
;           WAIT_L(0); BAR;
;           const int hso = ((brow + ai * HALF + 16 * wave) * DM + pn * BM) * 2;
;           const int lso = (brow + ai * HALF + 16 * wave) * DM + pn * BM;
;           _Pragma("unroll") for (int i = 0; i < 8; ++i) {
;             const u32x4 v = *reinterpret_cast<const u32x4*>(smem + (wave * 8 + i) * PIECE + lane3 * 16);
;             __builtin_amdgcn_raw_buffer_store_b128(v, rsXB, hvo + i * (2 * DM * 2), hso, 0);
;           }
;           _Pragma("unroll") for (int i = 0; i < 4; ++i) {
;             const u32x4 v = *reinterpret_cast<const u32x4*>(smem + LOBASE + (wave * 4 + i) * PIECE + lane3 * 16);
;             __builtin_amdgcn_raw_buffer_store_b128(v, rsLO, lvo + i * (4 * DM), lso, 0);
;           }
;           WAIT_L(0); BAR;
	v_mov_b32_e32 v7, v187
	v_or_b32_e32 v109, 0xa000, v70
	v_or_b32_e32 v110, 0xc000, v70
	v_or_b32_e32 v111, 0xe000, v70
	v_or_b32_e32 v112, 0x2000, v68
	v_pk_add_f32 v[90:91], v[90:91], v[6:7] op_sel_hi:[1,0] neg_lo:[0,1] neg_hi:[0,1]
	v_or_b32_e32 v113, 0x4000, v68
	v_pk_mul_f32 v[90:91], v[6:7], v[90:91] op_sel:[1,0]
	v_or_b32_e32 v114, 0x6000, v68
	v_pk_fma_f32 v[64:65], v[64:65], v[90:91], v[66:67]
	v_pk_add_f32 v[66:67], v[88:89], v[6:7] op_sel_hi:[1,0] neg_lo:[0,1] neg_hi:[0,1]
	v_and_b32_sdwa v3, v65, v244 dst_sel:DWORD dst_unused:UNUSED_PAD src0_sel:WORD_1 src1_sel:DWORD
	v_pk_mul_f32 v[6:7], v[6:7], v[66:67] op_sel:[1,0]
	v_add3_u32 v3, v65, v3, s67
	v_pk_fma_f32 v[0:1], v[0:1], v[6:7], v[4:5]
	v_and_b32_sdwa v4, v64, v244 dst_sel:DWORD dst_unused:UNUSED_PAD src0_sel:WORD_1 src1_sel:DWORD
	v_add3_u32 v4, v64, v4, s67
	v_and_b32_e32 v6, 0xffff0000, v4
	v_and_b32_sdwa v4, v1, v244 dst_sel:DWORD dst_unused:UNUSED_PAD src0_sel:WORD_1 src1_sel:DWORD
	v_and_b32_sdwa v5, v0, v244 dst_sel:DWORD dst_unused:UNUSED_PAD src0_sel:WORD_1 src1_sel:DWORD
	v_add3_u32 v4, v1, v4, s67
	v_add3_u32 v7, v0, v5, s67
	v_and_b32_e32 v66, 0xffff0000, v4
	v_add_u32_e32 v88, v2, v108
	v_and_b32_e32 v2, 0xffff0000, v7
	v_or_b32_sdwa v5, v66, v3 dst_sel:DWORD dst_unused:UNUSED_PAD src0_sel:DWORD src1_sel:WORD_1
	v_sub_u32_e32 v0, v0, v2
	v_sub_u32_e32 v2, v64, v6
	v_and_b32_e32 v3, 0xffff0000, v3
	v_add_u32_e32 v2, 0x80, v2
	v_sub_u32_e32 v3, v65, v3
	v_sub_u32_e32 v1, v1, v66
	v_add_u32_e32 v0, 0x80, v0
	v_ashrrev_i32_e32 v2, 8, v2
	v_add_u32_e32 v3, 0x80, v3
	v_add_u32_e32 v1, 0x80, v1
	v_ashrrev_i32_e32 v0, 8, v0
	v_min_i32_e32 v2, 0x7f, v2
	v_ashrrev_i32_e32 v3, 8, v3
	v_ashrrev_i32_e32 v1, 8, v1
	v_min_i32_e32 v0, 0x7f, v0
	v_min_i32_sdwa v3, v3, s69 dst_sel:WORD_1 dst_unused:UNUSED_PAD src0_sel:DWORD src1_sel:DWORD
	v_min_i32_e32 v1, 0x7f, v1
	v_lshlrev_b32_e32 v2, 8, v2
	v_and_b32_e32 v2, 0xff00, v2
	v_and_b32_e32 v3, 0xff0000, v3
	v_perm_b32 v0, v1, v0, s76
	v_or_b32_sdwa v4, v7, v6 dst_sel:DWORD dst_unused:UNUSED_PAD src0_sel:WORD_1 src1_sel:DWORD
	v_or3_b32 v0, v0, v2, v3
	ds_write_b64 v88, v[4:5]
	ds_write_b32 v22, v0 offset:144
	s_waitcnt lgkmcnt(0)
	s_barrier
	ds_read_b128 v[0:3], v74
	v_or_b32_e32 v89, 0x2000, v70
	v_or_b32_e32 v90, 0x4000, v70
	v_or_b32_e32 v91, 0x6000, v70
	v_or_b32_e32 v108, 0x8000, v70
	s_waitcnt lgkmcnt(0)
	buffer_store_dwordx4 v[0:3], v70, s[16:19], s22 offen
	ds_read_b128 v[0:3], v74 offset:1040
	s_waitcnt lgkmcnt(0)
	buffer_store_dwordx4 v[0:3], v89, s[16:19], s22 offen
	ds_read_b128 v[0:3], v74 offset:2080
	s_waitcnt lgkmcnt(0)
	buffer_store_dwordx4 v[0:3], v90, s[16:19], s22 offen
	ds_read_b128 v[0:3], v74 offset:3120
	s_waitcnt lgkmcnt(0)
	buffer_store_dwordx4 v[0:3], v91, s[16:19], s22 offen
	ds_read_b128 v[0:3], v74 offset:4160
	s_waitcnt lgkmcnt(0)
	buffer_store_dwordx4 v[0:3], v108, s[16:19], s22 offen
	ds_read_b128 v[0:3], v74 offset:5200
	s_waitcnt lgkmcnt(0)
	buffer_store_dwordx4 v[0:3], v109, s[16:19], s22 offen
	ds_read_b128 v[0:3], v74 offset:6240
	s_waitcnt lgkmcnt(0)
	buffer_store_dwordx4 v[0:3], v110, s[16:19], s22 offen
	ds_read_b128 v[0:3], v74 offset:7280
	s_waitcnt lgkmcnt(0)
	buffer_store_dwordx4 v[0:3], v111, s[16:19], s22 offen
	ds_read_b128 v[0:3], v69
	s_mov_b32 s22, s74
	s_waitcnt lgkmcnt(0)
	buffer_store_dwordx4 v[0:3], v68, s[20:23], s0 offen
	ds_read_b128 v[0:3], v69 offset:1040
	s_waitcnt lgkmcnt(0)
	buffer_store_dwordx4 v[0:3], v112, s[20:23], s0 offen
	ds_read_b128 v[0:3], v69 offset:2080
	s_waitcnt lgkmcnt(0)
	buffer_store_dwordx4 v[0:3], v113, s[20:23], s0 offen
	ds_read_b128 v[0:3], v69 offset:3120
	s_waitcnt lgkmcnt(0)
	buffer_store_dwordx4 v[0:3], v114, s[20:23], s0 offen
	s_barrier
	s_nop 1
	v_mov_b32_e32 v0, v196
	v_mov_b32_e32 v1, v197
	v_mov_b32_e32 v2, v198
	v_mov_b32_e32 v3, v199
	v_mov_b32_e32 v4, v212
	v_mov_b32_e32 v5, v213
	v_mov_b32_e32 v6, v214
	v_mov_b32_e32 v7, v215
	ds_read_b64 v[116:117], v71 offset:1024
	s_add_i32 s0, s0, 0x40000
	s_waitcnt lgkmcnt(0)
	v_mov_b32_e32 v180, v116
	v_mov_b32_e32 v181, v117
	v_pk_add_f32 v[82:83], v[82:83], v[116:117] op_sel_hi:[1,0] neg_lo:[0,1] neg_hi:[0,1]
	s_nop 0
	v_pk_mul_f32 v[82:83], v[116:117], v[82:83] op_sel:[1,0]
	v_pk_add_f32 v[80:81], v[80:81], v[116:117] op_sel_hi:[1,0] neg_lo:[0,1] neg_hi:[0,1]
	v_mov_b32_e32 v64, v1
	v_mov_b32_e32 v65, v2
	v_mov_b32_e32 v66, v5
	v_mov_b32_e32 v67, v6
	v_pk_fma_f32 v[82:83], v[64:65], v[82:83], v[66:67]
	v_pk_mul_f32 v[80:81], v[116:117], v[80:81] op_sel:[1,0]
	v_mov_b32_e32 v1, v3
	v_mov_b32_e32 v5, v7
	v_and_b32_sdwa v6, v83, v244 dst_sel:DWORD dst_unused:UNUSED_PAD src0_sel:WORD_1 src1_sel:DWORD
	v_and_b32_sdwa v7, v82, v244 dst_sel:DWORD dst_unused:UNUSED_PAD src0_sel:WORD_1 src1_sel:DWORD
	v_pk_fma_f32 v[2:3], v[0:1], v[80:81], v[4:5]
	v_add3_u32 v80, v83, v6, s67
	v_add3_u32 v6, v82, v7, s67
	v_and_b32_e32 v81, 0xffff0000, v6
	v_and_b32_sdwa v6, v3, v244 dst_sel:DWORD dst_unused:UNUSED_PAD src0_sel:WORD_1 src1_sel:DWORD
	v_and_b32_sdwa v7, v2, v244 dst_sel:DWORD dst_unused:UNUSED_PAD src0_sel:WORD_1 src1_sel:DWORD
	v_add3_u32 v6, v3, v6, s67
	v_add3_u32 v115, v2, v7, s67
	v_and_b32_e32 v116, 0xffff0000, v6
	v_or_b32_sdwa v7, v116, v80 dst_sel:DWORD dst_unused:UNUSED_PAD src0_sel:DWORD src1_sel:WORD_1
	v_or_b32_sdwa v6, v115, v81 dst_sel:DWORD dst_unused:UNUSED_PAD src0_sel:WORD_1 src1_sel:DWORD
	ds_write_b64 v73, v[6:7]
	v_and_b32_e32 v6, 0xffff0000, v115
	v_sub_u32_e32 v2, v2, v6
	v_sub_u32_e32 v6, v82, v81
	v_and_b32_e32 v7, 0xffff0000, v80
	v_add_u32_e32 v6, 0x80, v6
	v_sub_u32_e32 v7, v83, v7
	v_sub_u32_e32 v3, v3, v116
	v_add_u32_e32 v2, 0x80, v2
	v_ashrrev_i32_e32 v6, 8, v6
	v_add_u32_e32 v7, 0x80, v7
	v_add_u32_e32 v3, 0x80, v3
	v_ashrrev_i32_e32 v2, 8, v2
	v_min_i32_e32 v6, 0x7f, v6
	v_ashrrev_i32_e32 v7, 8, v7
	v_ashrrev_i32_e32 v3, 8, v3
	v_min_i32_e32 v2, 0x7f, v2
	v_min_i32_sdwa v7, v7, s69 dst_sel:WORD_1 dst_unused:UNUSED_PAD src0_sel:DWORD src1_sel:DWORD
	v_min_i32_e32 v3, 0x7f, v3
	v_lshlrev_b32_e32 v6, 8, v6
	v_and_b32_e32 v6, 0xff00, v6
	v_and_b32_e32 v7, 0xff0000, v7
	v_perm_b32 v2, v3, v2, s76
	v_or3_b32 v2, v2, v6, v7
	ds_write_b32 v12, v2
	ds_read_b64 v[2:3], v13 offset:1024
	s_waitcnt lgkmcnt(0)
;     ...
;           _Pragma("unroll") for (int bj = 0; bj < 2; ++bj) _Pragma("unroll") for (int n = 0; n < 2; ++n) {
;             const int cc = bj * HALF + wc3 * 32 + n * 16 + fq3 * 4;
;             const float4 gm = *reinterpret_cast<const float4*>(g.gam + pn * BM + cc), bt = *reinterpret_cast<const float4*>(g.bet + pn * BM + cc);
;             _Pragma("unroll") for (int m = 0; m < 4; ++m) {
;               const int rr = wr3 * 64 + m * 16 + fr3;
;               const float2 ms = *reinterpret_cast<const float2*>(mr + (ai * HALF + rr) * 2);
;               f32x4 y = acc[ai][bj][m][n];
;               const float o0 = (y[0] - ms.x) * ms.y * gm.x + bt.x, o1 = (y[1] - ms.x) * ms.y * gm.y + bt.y;
;               const float o2 = (y[2] - ms.x) * ms.y * gm.z + bt.z, o3 = (y[3] - ms.x) * ms.y * gm.w + bt.w;
;               const unsigned h0 = f2bf(o0), h1 = f2bf(o1), h2 = f2bf(o2), h3 = f2bf(o3);
;               u32x2 ob; ob[0] = h0 | (h1 << 16); ob[1] = h2 | (h3 << 16);
;               *reinterpret_cast<u32x2*>(smem + (rr >> 1) * PIECE + (rr & 1) * 512 + cc * 2) = ob;
;               const int l0 = min(((int)__float_as_uint(o0) - (int)(h0 << 16) + 128) >> 8, 127);
;               const int l1 = min(((int)__float_as_uint(o1) - (int)(h1 << 16) + 128) >> 8, 127);
;               const int l2 = min(((int)__float_as_uint(o2) - (int)(h2 << 16) + 128) >> 8, 127);
;               const int l3 = min(((int)__float_as_uint(o3) - (int)(h3 << 16) + 128) >> 8, 127);
;               *reinterpret_cast<unsigned*>(smem + LOBASE + (rr >> 2) * PIECE + (rr & 3) * 256 + cc) =
;                   (unsigned)(l0 & 255) | ((unsigned)(l1 & 255) << 8) | ((unsigned)(l2 & 255) << 16) | ((unsigned)l3 << 24);
;             }
	v_mov_b32_e32 v182, v2
	v_mov_b32_e32 v183, v3
	v_pk_add_f32 v[6:7], v[86:87], v[2:3] op_sel_hi:[1,0] neg_lo:[0,1] neg_hi:[0,1]
	s_nop 0
	v_pk_mul_f32 v[6:7], v[2:3], v[6:7] op_sel:[1,0]
	v_pk_add_f32 v[80:81], v[84:85], v[2:3] op_sel_hi:[1,0] neg_lo:[0,1] neg_hi:[0,1]
	v_pk_fma_f32 v[6:7], v[64:65], v[6:7], v[66:67]
	v_pk_mul_f32 v[2:3], v[2:3], v[80:81] op_sel:[1,0]
	v_and_b32_sdwa v80, v6, v244 dst_sel:DWORD dst_unused:UNUSED_PAD src0_sel:WORD_1 src1_sel:DWORD
	v_pk_fma_f32 v[2:3], v[0:1], v[2:3], v[4:5]
	v_add3_u32 v80, v6, v80, s67
	v_and_b32_e32 v82, 0xffff0000, v80
	v_and_b32_sdwa v80, v3, v244 dst_sel:DWORD dst_unused:UNUSED_PAD src0_sel:WORD_1 src1_sel:DWORD
	v_and_b32_sdwa v73, v7, v244 dst_sel:DWORD dst_unused:UNUSED_PAD src0_sel:WORD_1 src1_sel:DWORD
	v_and_b32_sdwa v81, v2, v244 dst_sel:DWORD dst_unused:UNUSED_PAD src0_sel:WORD_1 src1_sel:DWORD
	v_add3_u32 v80, v3, v80, s67
	v_add3_u32 v73, v7, v73, s67
	v_add3_u32 v83, v2, v81, s67
	v_and_b32_e32 v84, 0xffff0000, v80
	v_or_b32_sdwa v81, v84, v73 dst_sel:DWORD dst_unused:UNUSED_PAD src0_sel:DWORD src1_sel:WORD_1
	v_or_b32_sdwa v80, v83, v82 dst_sel:DWORD dst_unused:UNUSED_PAD src0_sel:WORD_1 src1_sel:DWORD
	ds_write_b64 v75, v[80:81]
	v_and_b32_e32 v75, 0xffff0000, v83
	v_sub_u32_e32 v6, v6, v82
	v_and_b32_e32 v73, 0xffff0000, v73
	v_sub_u32_e32 v2, v2, v75
	v_add_u32_e32 v6, 0x80, v6
	v_sub_u32_e32 v7, v7, v73
	v_sub_u32_e32 v3, v3, v84
	v_add_u32_e32 v2, 0x80, v2
	v_ashrrev_i32_e32 v6, 8, v6
	v_add_u32_e32 v7, 0x80, v7
	v_add_u32_e32 v3, 0x80, v3
	v_ashrrev_i32_e32 v2, 8, v2
	v_min_i32_e32 v6, 0x7f, v6
	v_ashrrev_i32_e32 v7, 8, v7
	v_ashrrev_i32_e32 v3, 8, v3
	v_min_i32_e32 v2, 0x7f, v2
	v_min_i32_sdwa v7, v7, s69 dst_sel:WORD_1 dst_unused:UNUSED_PAD src0_sel:DWORD src1_sel:DWORD
	v_min_i32_e32 v3, 0x7f, v3
	v_lshlrev_b32_e32 v6, 8, v6
	v_and_b32_e32 v6, 0xff00, v6
	v_and_b32_e32 v7, 0xff0000, v7
	v_perm_b32 v2, v3, v2, s76
	v_or3_b32 v2, v2, v6, v7
	ds_write_b32 v14, v2
	ds_read_b64 v[2:3], v15 offset:1024
	s_waitcnt lgkmcnt(0)
	v_mov_b32_e32 v184, v2
	v_mov_b32_e32 v185, v3
	v_pk_add_f32 v[6:7], v[94:95], v[2:3] op_sel_hi:[1,0] neg_lo:[0,1] neg_hi:[0,1]
	v_pk_add_f32 v[80:81], v[92:93], v[2:3] op_sel_hi:[1,0] neg_lo:[0,1] neg_hi:[0,1]
	v_pk_mul_f32 v[6:7], v[2:3], v[6:7] op_sel:[1,0]
	v_pk_mul_f32 v[2:3], v[2:3], v[80:81] op_sel:[1,0]
	v_pk_fma_f32 v[6:7], v[64:65], v[6:7], v[66:67]
	v_pk_fma_f32 v[2:3], v[0:1], v[2:3], v[4:5]
	v_and_b32_sdwa v75, v6, v244 dst_sel:DWORD dst_unused:UNUSED_PAD src0_sel:WORD_1 src1_sel:DWORD
	v_and_b32_sdwa v80, v3, v244 dst_sel:DWORD dst_unused:UNUSED_PAD src0_sel:WORD_1 src1_sel:DWORD
	v_and_b32_sdwa v73, v7, v244 dst_sel:DWORD dst_unused:UNUSED_PAD src0_sel:WORD_1 src1_sel:DWORD
	v_add3_u32 v75, v6, v75, s67
	v_and_b32_sdwa v81, v2, v244 dst_sel:DWORD dst_unused:UNUSED_PAD src0_sel:WORD_1 src1_sel:DWORD
	v_add3_u32 v80, v3, v80, s67
	v_add3_u32 v73, v7, v73, s67
	v_and_b32_e32 v75, 0xffff0000, v75
	v_add3_u32 v82, v2, v81, s67
	v_and_b32_e32 v83, 0xffff0000, v80
	v_or_b32_sdwa v81, v83, v73 dst_sel:DWORD dst_unused:UNUSED_PAD src0_sel:DWORD src1_sel:WORD_1
	v_or_b32_sdwa v80, v82, v75 dst_sel:DWORD dst_unused:UNUSED_PAD src0_sel:WORD_1 src1_sel:DWORD
	ds_write_b64 v96, v[80:81]
	v_and_b32_e32 v80, 0xffff0000, v82
	v_sub_u32_e32 v6, v6, v75
	v_and_b32_e32 v73, 0xffff0000, v73
	v_sub_u32_e32 v2, v2, v80
	v_add_u32_e32 v6, 0x80, v6
	v_sub_u32_e32 v7, v7, v73
	v_sub_u32_e32 v3, v3, v83
	v_add_u32_e32 v2, 0x80, v2
	v_ashrrev_i32_e32 v6, 8, v6
	v_add_u32_e32 v7, 0x80, v7
	v_add_u32_e32 v3, 0x80, v3
	v_ashrrev_i32_e32 v2, 8, v2
	v_min_i32_e32 v6, 0x7f, v6
	v_ashrrev_i32_e32 v7, 8, v7
	v_ashrrev_i32_e32 v3, 8, v3
	v_min_i32_e32 v2, 0x7f, v2
	v_min_i32_sdwa v7, v7, s69 dst_sel:WORD_1 dst_unused:UNUSED_PAD src0_sel:DWORD src1_sel:DWORD
	v_min_i32_e32 v3, 0x7f, v3
	v_lshlrev_b32_e32 v6, 8, v6
	v_and_b32_e32 v6, 0xff00, v6
	v_and_b32_e32 v7, 0xff0000, v7
	v_perm_b32 v2, v3, v2, s76
	v_or3_b32 v2, v2, v6, v7
	ds_write_b32 v20, v2
	ds_read_b64 v[2:3], v21 offset:1024
	s_waitcnt lgkmcnt(0)
	v_mov_b32_e32 v186, v2
	v_mov_b32_e32 v187, v3
	v_pk_add_f32 v[6:7], v[78:79], v[2:3] op_sel_hi:[1,0] neg_lo:[0,1] neg_hi:[0,1]
	s_nop 0
	v_pk_mul_f32 v[6:7], v[2:3], v[6:7] op_sel:[1,0]
	s_nop 0
	v_pk_fma_f32 v[6:7], v[64:65], v[6:7], v[66:67]
	v_pk_add_f32 v[64:65], v[76:77], v[2:3] op_sel_hi:[1,0] neg_lo:[0,1] neg_hi:[0,1]
	s_nop 0
	v_pk_mul_f32 v[2:3], v[2:3], v[64:65] op_sel:[1,0]
	s_nop 0
	v_pk_fma_f32 v[0:1], v[0:1], v[2:3], v[4:5]
	v_and_b32_sdwa v2, v7, v244 dst_sel:DWORD dst_unused:UNUSED_PAD src0_sel:WORD_1 src1_sel:DWORD
	v_and_b32_sdwa v3, v6, v244 dst_sel:DWORD dst_unused:UNUSED_PAD src0_sel:WORD_1 src1_sel:DWORD
	v_add3_u32 v4, v7, v2, s67
	v_add3_u32 v2, v6, v3, s67
	v_and_b32_e32 v5, 0xffff0000, v2
	v_and_b32_sdwa v2, v1, v244 dst_sel:DWORD dst_unused:UNUSED_PAD src0_sel:WORD_1 src1_sel:DWORD
	v_and_b32_sdwa v3, v0, v244 dst_sel:DWORD dst_unused:UNUSED_PAD src0_sel:WORD_1 src1_sel:DWORD
	v_add3_u32 v2, v1, v2, s67
	v_add3_u32 v64, v0, v3, s67
	v_and_b32_e32 v65, 0xffff0000, v2
	v_or_b32_sdwa v3, v65, v4 dst_sel:DWORD dst_unused:UNUSED_PAD src0_sel:DWORD src1_sel:WORD_1
	v_or_b32_sdwa v2, v64, v5 dst_sel:DWORD dst_unused:UNUSED_PAD src0_sel:WORD_1 src1_sel:DWORD
	ds_write_b64 v97, v[2:3]
	v_and_b32_e32 v2, 0xffff0000, v64
	v_sub_u32_e32 v0, v0, v2
	v_sub_u32_e32 v2, v6, v5
	v_and_b32_e32 v3, 0xffff0000, v4
	v_add_u32_e32 v2, 0x80, v2
	v_sub_u32_e32 v3, v7, v3
	v_sub_u32_e32 v1, v1, v65
	v_add_u32_e32 v0, 0x80, v0
	v_ashrrev_i32_e32 v2, 8, v2
	v_add_u32_e32 v3, 0x80, v3
	v_add_u32_e32 v1, 0x80, v1
	v_ashrrev_i32_e32 v0, 8, v0
	v_min_i32_e32 v2, 0x7f, v2
;     ...
;           _Pragma("unroll") for (int bj = 0; bj < 2; ++bj) _Pragma("unroll") for (int n = 0; n < 2; ++n) {
;             const int cc = bj * HALF + wc3 * 32 + n * 16 + fq3 * 4;
;             const float4 gm = *reinterpret_cast<const float4*>(g.gam + pn * BM + cc), bt = *reinterpret_cast<const float4*>(g.bet + pn * BM + cc);
;             _Pragma("unroll") for (int m = 0; m < 4; ++m) {
;               const int rr = wr3 * 64 + m * 16 + fr3;
;               const float2 ms = *reinterpret_cast<const float2*>(mr + (ai * HALF + rr) * 2);
;               f32x4 y = acc[ai][bj][m][n];
;               const float o0 = (y[0] - ms.x) * ms.y * gm.x + bt.x, o1 = (y[1] - ms.x) * ms.y * gm.y + bt.y;
;               const float o2 = (y[2] - ms.x) * ms.y * gm.z + bt.z, o3 = (y[3] - ms.x) * ms.y * gm.w + bt.w;
;               const unsigned h0 = f2bf(o0), h1 = f2bf(o1), h2 = f2bf(o2), h3 = f2bf(o3);
;               u32x2 ob; ob[0] = h0 | (h1 << 16); ob[1] = h2 | (h3 << 16);
;               *reinterpret_cast<u32x2*>(smem + (rr >> 1) * PIECE + (rr & 1) * 512 + cc * 2) = ob;
;               const int l0 = min(((int)__float_as_uint(o0) - (int)(h0 << 16) + 128) >> 8, 127);
;               const int l1 = min(((int)__float_as_uint(o1) - (int)(h1 << 16) + 128) >> 8, 127);
;               const int l2 = min(((int)__float_as_uint(o2) - (int)(h2 << 16) + 128) >> 8, 127);
;               const int l3 = min(((int)__float_as_uint(o3) - (int)(h3 << 16) + 128) >> 8, 127);
;               *reinterpret_cast<unsigned*>(smem + LOBASE + (rr >> 2) * PIECE + (rr & 3) * 256 + cc) =
;                   (unsigned)(l0 & 255) | ((unsigned)(l1 & 255) << 8) | ((unsigned)(l2 & 255) << 16) | ((unsigned)l3 << 24);
;             }
	v_ashrrev_i32_e32 v3, 8, v3
	v_ashrrev_i32_e32 v1, 8, v1
	v_min_i32_e32 v0, 0x7f, v0
	v_min_i32_sdwa v3, v3, s69 dst_sel:WORD_1 dst_unused:UNUSED_PAD src0_sel:DWORD src1_sel:DWORD
	v_min_i32_e32 v1, 0x7f, v1
	v_lshlrev_b32_e32 v2, 8, v2
	v_and_b32_e32 v2, 0xff00, v2
	v_and_b32_e32 v3, 0xff0000, v3
	v_perm_b32 v0, v1, v0, s76
	v_or3_b32 v0, v0, v2, v3
	ds_write_b32 v22, v0
	v_mov_b32_e32 v0, v200
	v_mov_b32_e32 v1, v201
	v_mov_b32_e32 v2, v202
	v_mov_b32_e32 v3, v203
	v_mov_b32_e32 v4, v220
	v_mov_b32_e32 v5, v221
	v_mov_b32_e32 v6, v222
	v_mov_b32_e32 v7, v223
	v_mov_b32_e32 v76, v180
	v_mov_b32_e32 v77, v181
	v_pk_add_f32 v[62:63], v[62:63], v[76:77] op_sel_hi:[1,0] neg_lo:[0,1] neg_hi:[0,1]
	s_nop 0
	v_pk_mul_f32 v[62:63], v[76:77], v[62:63] op_sel:[1,0]
	v_pk_add_f32 v[60:61], v[60:61], v[76:77] op_sel_hi:[1,0] neg_lo:[0,1] neg_hi:[0,1]
	v_mov_b32_e32 v64, v1
	v_mov_b32_e32 v65, v2
	v_mov_b32_e32 v66, v5
	v_mov_b32_e32 v67, v6
	v_pk_fma_f32 v[62:63], v[64:65], v[62:63], v[66:67]
	v_pk_mul_f32 v[60:61], v[76:77], v[60:61] op_sel:[1,0]
	v_mov_b32_e32 v1, v3
	v_mov_b32_e32 v5, v7
	v_and_b32_sdwa v6, v63, v244 dst_sel:DWORD dst_unused:UNUSED_PAD src0_sel:WORD_1 src1_sel:DWORD
	v_and_b32_sdwa v7, v62, v244 dst_sel:DWORD dst_unused:UNUSED_PAD src0_sel:WORD_1 src1_sel:DWORD
	v_pk_fma_f32 v[2:3], v[0:1], v[60:61], v[4:5]
	v_add3_u32 v60, v63, v6, s67
	v_add3_u32 v6, v62, v7, s67
	v_and_b32_e32 v61, 0xffff0000, v6
	v_and_b32_sdwa v6, v3, v244 dst_sel:DWORD dst_unused:UNUSED_PAD src0_sel:WORD_1 src1_sel:DWORD
	v_and_b32_sdwa v7, v2, v244 dst_sel:DWORD dst_unused:UNUSED_PAD src0_sel:WORD_1 src1_sel:DWORD
	v_add3_u32 v6, v3, v6, s67
	v_add3_u32 v73, v2, v7, s67
	v_and_b32_e32 v75, 0xffff0000, v6
	v_or_b32_sdwa v7, v75, v60 dst_sel:DWORD dst_unused:UNUSED_PAD src0_sel:DWORD src1_sel:WORD_1
	v_or_b32_sdwa v6, v73, v61 dst_sel:DWORD dst_unused:UNUSED_PAD src0_sel:WORD_1 src1_sel:DWORD
	ds_write_b64 v23, v[6:7]
	v_and_b32_e32 v6, 0xffff0000, v73
	v_sub_u32_e32 v2, v2, v6
	v_sub_u32_e32 v6, v62, v61
	v_and_b32_e32 v7, 0xffff0000, v60
	v_add_u32_e32 v6, 0x80, v6
	v_sub_u32_e32 v7, v63, v7
	v_sub_u32_e32 v3, v3, v75
	v_add_u32_e32 v2, 0x80, v2
	v_ashrrev_i32_e32 v6, 8, v6
	v_add_u32_e32 v7, 0x80, v7
	v_add_u32_e32 v3, 0x80, v3
	v_ashrrev_i32_e32 v2, 8, v2
	v_min_i32_e32 v6, 0x7f, v6
	v_ashrrev_i32_e32 v7, 8, v7
	v_ashrrev_i32_e32 v3, 8, v3
	v_min_i32_e32 v2, 0x7f, v2
	v_min_i32_sdwa v7, v7, s69 dst_sel:WORD_1 dst_unused:UNUSED_PAD src0_sel:DWORD src1_sel:DWORD
	v_min_i32_e32 v3, 0x7f, v3
	v_lshlrev_b32_e32 v6, 8, v6
	v_and_b32_e32 v6, 0xff00, v6
	v_and_b32_e32 v7, 0xff0000, v7
	v_perm_b32 v2, v3, v2, s76
	v_or3_b32 v2, v2, v6, v7
	ds_write_b32 v12, v2 offset:16
	v_mov_b32_e32 v2, v182
	v_mov_b32_e32 v3, v183
	v_pk_add_f32 v[6:7], v[46:47], v[2:3] op_sel_hi:[1,0] neg_lo:[0,1] neg_hi:[0,1]
	s_nop 0
	v_pk_mul_f32 v[6:7], v[2:3], v[6:7] op_sel:[1,0]
	v_pk_add_f32 v[44:45], v[44:45], v[2:3] op_sel_hi:[1,0] neg_lo:[0,1] neg_hi:[0,1]
	v_pk_fma_f32 v[6:7], v[64:65], v[6:7], v[66:67]
	v_pk_mul_f32 v[2:3], v[2:3], v[44:45] op_sel:[1,0]
	v_and_b32_sdwa v44, v6, v244 dst_sel:DWORD dst_unused:UNUSED_PAD src0_sel:WORD_1 src1_sel:DWORD
	v_pk_fma_f32 v[2:3], v[0:1], v[2:3], v[4:5]
	v_add3_u32 v44, v6, v44, s67
	v_and_b32_e32 v46, 0xffff0000, v44
	v_and_b32_sdwa v44, v3, v244 dst_sel:DWORD dst_unused:UNUSED_PAD src0_sel:WORD_1 src1_sel:DWORD
	v_and_b32_sdwa v23, v7, v244 dst_sel:DWORD dst_unused:UNUSED_PAD src0_sel:WORD_1 src1_sel:DWORD
	v_and_b32_sdwa v45, v2, v244 dst_sel:DWORD dst_unused:UNUSED_PAD src0_sel:WORD_1 src1_sel:DWORD
	v_add3_u32 v44, v3, v44, s67
	v_add3_u32 v23, v7, v23, s67
	v_add3_u32 v47, v2, v45, s67
	v_and_b32_e32 v60, 0xffff0000, v44
	v_or_b32_sdwa v45, v60, v23 dst_sel:DWORD dst_unused:UNUSED_PAD src0_sel:DWORD src1_sel:WORD_1
	v_or_b32_sdwa v44, v47, v46 dst_sel:DWORD dst_unused:UNUSED_PAD src0_sel:WORD_1 src1_sel:DWORD
	ds_write_b64 v98, v[44:45]
	v_and_b32_e32 v44, 0xffff0000, v47
	v_sub_u32_e32 v6, v6, v46
	v_and_b32_e32 v23, 0xffff0000, v23
	v_sub_u32_e32 v2, v2, v44
	v_add_u32_e32 v6, 0x80, v6
	v_sub_u32_e32 v7, v7, v23
	v_sub_u32_e32 v3, v3, v60
	v_add_u32_e32 v2, 0x80, v2
	v_ashrrev_i32_e32 v6, 8, v6
	v_add_u32_e32 v7, 0x80, v7
	v_add_u32_e32 v3, 0x80, v3
	v_ashrrev_i32_e32 v2, 8, v2
	v_min_i32_e32 v6, 0x7f, v6
	v_ashrrev_i32_e32 v7, 8, v7
	v_ashrrev_i32_e32 v3, 8, v3
	v_min_i32_e32 v2, 0x7f, v2
	v_min_i32_sdwa v7, v7, s69 dst_sel:WORD_1 dst_unused:UNUSED_PAD src0_sel:DWORD src1_sel:DWORD
	v_min_i32_e32 v3, 0x7f, v3
	v_lshlrev_b32_e32 v6, 8, v6
	v_and_b32_e32 v6, 0xff00, v6
	v_and_b32_e32 v7, 0xff0000, v7
	v_perm_b32 v2, v3, v2, s76
	v_or3_b32 v2, v2, v6, v7
	ds_write_b32 v14, v2 offset:16
	v_mov_b32_e32 v2, v184
	v_mov_b32_e32 v3, v185
	v_pk_add_f32 v[6:7], v[42:43], v[2:3] op_sel_hi:[1,0] neg_lo:[0,1] neg_hi:[0,1]
	s_nop 0
	v_pk_mul_f32 v[6:7], v[2:3], v[6:7] op_sel:[1,0]
	v_pk_add_f32 v[40:41], v[40:41], v[2:3] op_sel_hi:[1,0] neg_lo:[0,1] neg_hi:[0,1]
	v_pk_fma_f32 v[6:7], v[64:65], v[6:7], v[66:67]
	v_pk_mul_f32 v[2:3], v[2:3], v[40:41] op_sel:[1,0]
	v_and_b32_sdwa v40, v6, v244 dst_sel:DWORD dst_unused:UNUSED_PAD src0_sel:WORD_1 src1_sel:DWORD
	v_pk_fma_f32 v[2:3], v[0:1], v[2:3], v[4:5]
	v_add3_u32 v40, v6, v40, s67
	v_and_b32_e32 v42, 0xffff0000, v40
	v_and_b32_sdwa v40, v3, v244 dst_sel:DWORD dst_unused:UNUSED_PAD src0_sel:WORD_1 src1_sel:DWORD
	v_and_b32_sdwa v23, v7, v244 dst_sel:DWORD dst_unused:UNUSED_PAD src0_sel:WORD_1 src1_sel:DWORD
	v_and_b32_sdwa v41, v2, v244 dst_sel:DWORD dst_unused:UNUSED_PAD src0_sel:WORD_1 src1_sel:DWORD
	v_add3_u32 v40, v3, v40, s67
	v_add3_u32 v23, v7, v23, s67
	v_add3_u32 v43, v2, v41, s67
;     ...
;           _Pragma("unroll") for (int bj = 0; bj < 2; ++bj) _Pragma("unroll") for (int n = 0; n < 2; ++n) {
;             const int cc = bj * HALF + wc3 * 32 + n * 16 + fq3 * 4;
;             const float4 gm = *reinterpret_cast<const float4*>(g.gam + pn * BM + cc), bt = *reinterpret_cast<const float4*>(g.bet + pn * BM + cc);
;             _Pragma("unroll") for (int m = 0; m < 4; ++m) {
;               const int rr = wr3 * 64 + m * 16 + fr3;
;               const float2 ms = *reinterpret_cast<const float2*>(mr + (ai * HALF + rr) * 2);
;               f32x4 y = acc[ai][bj][m][n];
;               const float o0 = (y[0] - ms.x) * ms.y * gm.x + bt.x, o1 = (y[1] - ms.x) * ms.y * gm.y + bt.y;
;               const float o2 = (y[2] - ms.x) * ms.y * gm.z + bt.z, o3 = (y[3] - ms.x) * ms.y * gm.w + bt.w;
;               const unsigned h0 = f2bf(o0), h1 = f2bf(o1), h2 = f2bf(o2), h3 = f2bf(o3);
;               u32x2 ob; ob[0] = h0 | (h1 << 16); ob[1] = h2 | (h3 << 16);
;               *reinterpret_cast<u32x2*>(smem + (rr >> 1) * PIECE + (rr & 1) * 512 + cc * 2) = ob;
;               const int l0 = min(((int)__float_as_uint(o0) - (int)(h0 << 16) + 128) >> 8, 127);
;               const int l1 = min(((int)__float_as_uint(o1) - (int)(h1 << 16) + 128) >> 8, 127);
;               const int l2 = min(((int)__float_as_uint(o2) - (int)(h2 << 16) + 128) >> 8, 127);
;               const int l3 = min(((int)__float_as_uint(o3) - (int)(h3 << 16) + 128) >> 8, 127);
;               *reinterpret_cast<unsigned*>(smem + LOBASE + (rr >> 2) * PIECE + (rr & 3) * 256 + cc) =
;                   (unsigned)(l0 & 255) | ((unsigned)(l1 & 255) << 8) | ((unsigned)(l2 & 255) << 16) | ((unsigned)l3 << 24);
;             }
	v_and_b32_e32 v44, 0xffff0000, v40
	v_or_b32_sdwa v41, v44, v23 dst_sel:DWORD dst_unused:UNUSED_PAD src0_sel:DWORD src1_sel:WORD_1
	v_or_b32_sdwa v40, v43, v42 dst_sel:DWORD dst_unused:UNUSED_PAD src0_sel:WORD_1 src1_sel:DWORD
	ds_write_b64 v99, v[40:41]
	v_and_b32_e32 v40, 0xffff0000, v43
	v_sub_u32_e32 v6, v6, v42
	v_and_b32_e32 v23, 0xffff0000, v23
	v_sub_u32_e32 v2, v2, v40
	v_add_u32_e32 v6, 0x80, v6
	v_sub_u32_e32 v7, v7, v23
	v_sub_u32_e32 v3, v3, v44
	v_add_u32_e32 v2, 0x80, v2
	v_ashrrev_i32_e32 v6, 8, v6
	v_add_u32_e32 v7, 0x80, v7
	v_add_u32_e32 v3, 0x80, v3
	v_ashrrev_i32_e32 v2, 8, v2
	v_min_i32_e32 v6, 0x7f, v6
	v_ashrrev_i32_e32 v7, 8, v7
	v_ashrrev_i32_e32 v3, 8, v3
	v_min_i32_e32 v2, 0x7f, v2
	v_min_i32_sdwa v7, v7, s69 dst_sel:WORD_1 dst_unused:UNUSED_PAD src0_sel:DWORD src1_sel:DWORD
	v_min_i32_e32 v3, 0x7f, v3
	v_lshlrev_b32_e32 v6, 8, v6
	v_and_b32_e32 v6, 0xff00, v6
	v_and_b32_e32 v7, 0xff0000, v7
	v_perm_b32 v2, v3, v2, s76
	v_or3_b32 v2, v2, v6, v7
	ds_write_b32 v20, v2 offset:16
	v_mov_b32_e32 v2, v186
	v_mov_b32_e32 v3, v187
	v_pk_add_f32 v[6:7], v[58:59], v[2:3] op_sel_hi:[1,0] neg_lo:[0,1] neg_hi:[0,1]
	s_nop 0
	v_pk_mul_f32 v[6:7], v[2:3], v[6:7] op_sel:[1,0]
	v_pk_add_f32 v[40:41], v[56:57], v[2:3] op_sel_hi:[1,0] neg_lo:[0,1] neg_hi:[0,1]
	v_pk_fma_f32 v[6:7], v[64:65], v[6:7], v[66:67]
	v_pk_mul_f32 v[2:3], v[2:3], v[40:41] op_sel:[1,0]
	s_nop 0
	v_pk_fma_f32 v[0:1], v[0:1], v[2:3], v[4:5]
	v_and_b32_sdwa v2, v7, v244 dst_sel:DWORD dst_unused:UNUSED_PAD src0_sel:WORD_1 src1_sel:DWORD
	v_and_b32_sdwa v3, v6, v244 dst_sel:DWORD dst_unused:UNUSED_PAD src0_sel:WORD_1 src1_sel:DWORD
	v_add3_u32 v4, v7, v2, s67
	v_add3_u32 v2, v6, v3, s67
	v_and_b32_e32 v5, 0xffff0000, v2
	v_and_b32_sdwa v2, v1, v244 dst_sel:DWORD dst_unused:UNUSED_PAD src0_sel:WORD_1 src1_sel:DWORD
	v_and_b32_sdwa v3, v0, v244 dst_sel:DWORD dst_unused:UNUSED_PAD src0_sel:WORD_1 src1_sel:DWORD
	v_add3_u32 v2, v1, v2, s67
	v_add3_u32 v23, v0, v3, s67
	v_and_b32_e32 v40, 0xffff0000, v2
	v_or_b32_sdwa v3, v40, v4 dst_sel:DWORD dst_unused:UNUSED_PAD src0_sel:DWORD src1_sel:WORD_1
	v_or_b32_sdwa v2, v23, v5 dst_sel:DWORD dst_unused:UNUSED_PAD src0_sel:WORD_1 src1_sel:DWORD
	ds_write_b64 v100, v[2:3]
	v_and_b32_e32 v2, 0xffff0000, v23
	v_sub_u32_e32 v0, v0, v2
	v_sub_u32_e32 v2, v6, v5
	v_and_b32_e32 v3, 0xffff0000, v4
	v_add_u32_e32 v2, 0x80, v2
	v_sub_u32_e32 v3, v7, v3
	v_sub_u32_e32 v1, v1, v40
	v_add_u32_e32 v0, 0x80, v0
	v_ashrrev_i32_e32 v2, 8, v2
	v_add_u32_e32 v3, 0x80, v3
	v_add_u32_e32 v1, 0x80, v1
	v_ashrrev_i32_e32 v0, 8, v0
	v_min_i32_e32 v2, 0x7f, v2
	v_ashrrev_i32_e32 v3, 8, v3
	v_ashrrev_i32_e32 v1, 8, v1
	v_min_i32_e32 v0, 0x7f, v0
	v_min_i32_sdwa v3, v3, s69 dst_sel:WORD_1 dst_unused:UNUSED_PAD src0_sel:DWORD src1_sel:DWORD
	v_min_i32_e32 v1, 0x7f, v1
	v_lshlrev_b32_e32 v2, 8, v2
	v_and_b32_e32 v2, 0xff00, v2
	v_and_b32_e32 v3, 0xff0000, v3
	v_perm_b32 v0, v1, v0, s76
	v_or3_b32 v0, v0, v2, v3
	ds_write_b32 v22, v0 offset:16
	v_mov_b32_e32 v0, v204
	v_mov_b32_e32 v1, v205
	v_mov_b32_e32 v2, v206
	v_mov_b32_e32 v3, v207
	v_mov_b32_e32 v4, v240
	v_mov_b32_e32 v5, v241
	v_mov_b32_e32 v6, v242
	v_mov_b32_e32 v7, v243
	v_mov_b32_e32 v44, v180
	v_mov_b32_e32 v45, v181
	v_pk_add_f32 v[46:47], v[54:55], v[44:45] op_sel_hi:[1,0] neg_lo:[0,1] neg_hi:[0,1]
	s_nop 0
	v_pk_mul_f32 v[46:47], v[44:45], v[46:47] op_sel:[1,0]
	v_pk_add_f32 v[52:53], v[52:53], v[44:45] op_sel_hi:[1,0] neg_lo:[0,1] neg_hi:[0,1]
	v_mov_b32_e32 v40, v1
	v_mov_b32_e32 v41, v2
	v_mov_b32_e32 v42, v5
	v_mov_b32_e32 v43, v6
	v_pk_fma_f32 v[46:47], v[40:41], v[46:47], v[42:43]
	v_pk_mul_f32 v[44:45], v[44:45], v[52:53] op_sel:[1,0]
	v_mov_b32_e32 v1, v3
	v_mov_b32_e32 v5, v7
	v_and_b32_sdwa v6, v47, v244 dst_sel:DWORD dst_unused:UNUSED_PAD src0_sel:WORD_1 src1_sel:DWORD
	v_and_b32_sdwa v7, v46, v244 dst_sel:DWORD dst_unused:UNUSED_PAD src0_sel:WORD_1 src1_sel:DWORD
	v_pk_fma_f32 v[2:3], v[0:1], v[44:45], v[4:5]
	v_add3_u32 v23, v47, v6, s67
	v_add3_u32 v6, v46, v7, s67
	v_and_b32_e32 v44, 0xffff0000, v6
	v_and_b32_sdwa v6, v3, v244 dst_sel:DWORD dst_unused:UNUSED_PAD src0_sel:WORD_1 src1_sel:DWORD
	v_and_b32_sdwa v7, v2, v244 dst_sel:DWORD dst_unused:UNUSED_PAD src0_sel:WORD_1 src1_sel:DWORD
	v_add3_u32 v6, v3, v6, s67
	v_add3_u32 v45, v2, v7, s67
	v_and_b32_e32 v52, 0xffff0000, v6
	v_or_b32_sdwa v7, v52, v23 dst_sel:DWORD dst_unused:UNUSED_PAD src0_sel:DWORD src1_sel:WORD_1
	v_or_b32_sdwa v6, v45, v44 dst_sel:DWORD dst_unused:UNUSED_PAD src0_sel:WORD_1 src1_sel:DWORD
	ds_write_b64 v101, v[6:7]
	v_and_b32_e32 v6, 0xffff0000, v45
	v_sub_u32_e32 v2, v2, v6
	v_sub_u32_e32 v6, v46, v44
	v_and_b32_e32 v7, 0xffff0000, v23
	v_add_u32_e32 v6, 0x80, v6
	v_sub_u32_e32 v7, v47, v7
	v_sub_u32_e32 v3, v3, v52
	v_add_u32_e32 v2, 0x80, v2
	v_ashrrev_i32_e32 v6, 8, v6
	v_add_u32_e32 v7, 0x80, v7
	v_add_u32_e32 v3, 0x80, v3
	v_ashrrev_i32_e32 v2, 8, v2
	v_min_i32_e32 v6, 0x7f, v6
	v_ashrrev_i32_e32 v7, 8, v7
	v_ashrrev_i32_e32 v3, 8, v3
	v_min_i32_e32 v2, 0x7f, v2
	v_min_i32_sdwa v7, v7, s69 dst_sel:WORD_1 dst_unused:UNUSED_PAD src0_sel:DWORD src1_sel:DWORD
	v_min_i32_e32 v3, 0x7f, v3
	v_lshlrev_b32_e32 v6, 8, v6
	v_and_b32_e32 v6, 0xff00, v6
	v_and_b32_e32 v7, 0xff0000, v7
	v_perm_b32 v2, v3, v2, s76
	v_or3_b32 v2, v2, v6, v7
	ds_write_b32 v12, v2 offset:128
	v_mov_b32_e32 v2, v182
	v_mov_b32_e32 v3, v183
	v_pk_add_f32 v[6:7], v[38:39], v[2:3] op_sel_hi:[1,0] neg_lo:[0,1] neg_hi:[0,1]
	s_nop 0
	v_pk_mul_f32 v[6:7], v[2:3], v[6:7] op_sel:[1,0]
	v_pk_add_f32 v[36:37], v[36:37], v[2:3] op_sel_hi:[1,0] neg_lo:[0,1] neg_hi:[0,1]
	v_pk_fma_f32 v[6:7], v[40:41], v[6:7], v[42:43]
;     ...
;           _Pragma("unroll") for (int bj = 0; bj < 2; ++bj) _Pragma("unroll") for (int n = 0; n < 2; ++n) {
;             const int cc = bj * HALF + wc3 * 32 + n * 16 + fq3 * 4;
;             const float4 gm = *reinterpret_cast<const float4*>(g.gam + pn * BM + cc), bt = *reinterpret_cast<const float4*>(g.bet + pn * BM + cc);
;             _Pragma("unroll") for (int m = 0; m < 4; ++m) {
;               const int rr = wr3 * 64 + m * 16 + fr3;
;               const float2 ms = *reinterpret_cast<const float2*>(mr + (ai * HALF + rr) * 2);
;               f32x4 y = acc[ai][bj][m][n];
;               const float o0 = (y[0] - ms.x) * ms.y * gm.x + bt.x, o1 = (y[1] - ms.x) * ms.y * gm.y + bt.y;
;               const float o2 = (y[2] - ms.x) * ms.y * gm.z + bt.z, o3 = (y[3] - ms.x) * ms.y * gm.w + bt.w;
;               const unsigned h0 = f2bf(o0), h1 = f2bf(o1), h2 = f2bf(o2), h3 = f2bf(o3);
;               u32x2 ob; ob[0] = h0 | (h1 << 16); ob[1] = h2 | (h3 << 16);
;               *reinterpret_cast<u32x2*>(smem + (rr >> 1) * PIECE + (rr & 1) * 512 + cc * 2) = ob;
;               const int l0 = min(((int)__float_as_uint(o0) - (int)(h0 << 16) + 128) >> 8, 127);
;               const int l1 = min(((int)__float_as_uint(o1) - (int)(h1 << 16) + 128) >> 8, 127);
;               const int l2 = min(((int)__float_as_uint(o2) - (int)(h2 << 16) + 128) >> 8, 127);
;               const int l3 = min(((int)__float_as_uint(o3) - (int)(h3 << 16) + 128) >> 8, 127);
;               *reinterpret_cast<unsigned*>(smem + LOBASE + (rr >> 2) * PIECE + (rr & 3) * 256 + cc) =
;                   (unsigned)(l0 & 255) | ((unsigned)(l1 & 255) << 8) | ((unsigned)(l2 & 255) << 16) | ((unsigned)l3 << 24);
;             }
	v_pk_mul_f32 v[2:3], v[2:3], v[36:37] op_sel:[1,0]
	v_and_b32_sdwa v36, v6, v244 dst_sel:DWORD dst_unused:UNUSED_PAD src0_sel:WORD_1 src1_sel:DWORD
	v_pk_fma_f32 v[2:3], v[0:1], v[2:3], v[4:5]
	v_add3_u32 v36, v6, v36, s67
	v_and_b32_e32 v38, 0xffff0000, v36
	v_and_b32_sdwa v36, v3, v244 dst_sel:DWORD dst_unused:UNUSED_PAD src0_sel:WORD_1 src1_sel:DWORD
	v_and_b32_sdwa v23, v7, v244 dst_sel:DWORD dst_unused:UNUSED_PAD src0_sel:WORD_1 src1_sel:DWORD
	v_and_b32_sdwa v37, v2, v244 dst_sel:DWORD dst_unused:UNUSED_PAD src0_sel:WORD_1 src1_sel:DWORD
	v_add3_u32 v36, v3, v36, s67
	v_add3_u32 v23, v7, v23, s67
	v_add3_u32 v39, v2, v37, s67
	v_and_b32_e32 v44, 0xffff0000, v36
	v_or_b32_sdwa v37, v44, v23 dst_sel:DWORD dst_unused:UNUSED_PAD src0_sel:DWORD src1_sel:WORD_1
	v_or_b32_sdwa v36, v39, v38 dst_sel:DWORD dst_unused:UNUSED_PAD src0_sel:WORD_1 src1_sel:DWORD
	ds_write_b64 v102, v[36:37]
	v_and_b32_e32 v36, 0xffff0000, v39
	v_sub_u32_e32 v6, v6, v38
	v_and_b32_e32 v23, 0xffff0000, v23
	v_sub_u32_e32 v2, v2, v36
	v_add_u32_e32 v6, 0x80, v6
	v_sub_u32_e32 v7, v7, v23
	v_sub_u32_e32 v3, v3, v44
	v_add_u32_e32 v2, 0x80, v2
	v_ashrrev_i32_e32 v6, 8, v6
	v_add_u32_e32 v7, 0x80, v7
	v_add_u32_e32 v3, 0x80, v3
	v_ashrrev_i32_e32 v2, 8, v2
	v_min_i32_e32 v6, 0x7f, v6
	v_ashrrev_i32_e32 v7, 8, v7
	v_ashrrev_i32_e32 v3, 8, v3
	v_min_i32_e32 v2, 0x7f, v2
	v_min_i32_sdwa v7, v7, s69 dst_sel:WORD_1 dst_unused:UNUSED_PAD src0_sel:DWORD src1_sel:DWORD
	v_min_i32_e32 v3, 0x7f, v3
	v_lshlrev_b32_e32 v6, 8, v6
	v_and_b32_e32 v6, 0xff00, v6
	v_and_b32_e32 v7, 0xff0000, v7
	v_perm_b32 v2, v3, v2, s76
	v_or3_b32 v2, v2, v6, v7
	ds_write_b32 v14, v2 offset:128
	v_mov_b32_e32 v2, v184
	v_mov_b32_e32 v3, v185
	v_pk_add_f32 v[6:7], v[26:27], v[2:3] op_sel_hi:[1,0] neg_lo:[0,1] neg_hi:[0,1]
	s_nop 0
	v_pk_mul_f32 v[6:7], v[2:3], v[6:7] op_sel:[1,0]
	v_pk_add_f32 v[24:25], v[24:25], v[2:3] op_sel_hi:[1,0] neg_lo:[0,1] neg_hi:[0,1]
	v_pk_fma_f32 v[6:7], v[40:41], v[6:7], v[42:43]
	v_pk_mul_f32 v[2:3], v[2:3], v[24:25] op_sel:[1,0]
	v_and_b32_sdwa v24, v6, v244 dst_sel:DWORD dst_unused:UNUSED_PAD src0_sel:WORD_1 src1_sel:DWORD
	v_pk_fma_f32 v[2:3], v[0:1], v[2:3], v[4:5]
	v_add3_u32 v24, v6, v24, s67
	v_and_b32_e32 v26, 0xffff0000, v24
	v_and_b32_sdwa v24, v3, v244 dst_sel:DWORD dst_unused:UNUSED_PAD src0_sel:WORD_1 src1_sel:DWORD
	v_and_b32_sdwa v23, v7, v244 dst_sel:DWORD dst_unused:UNUSED_PAD src0_sel:WORD_1 src1_sel:DWORD
	v_and_b32_sdwa v25, v2, v244 dst_sel:DWORD dst_unused:UNUSED_PAD src0_sel:WORD_1 src1_sel:DWORD
	v_add3_u32 v24, v3, v24, s67
	v_add3_u32 v23, v7, v23, s67
	v_add3_u32 v27, v2, v25, s67
	v_and_b32_e32 v36, 0xffff0000, v24
	v_or_b32_sdwa v25, v36, v23 dst_sel:DWORD dst_unused:UNUSED_PAD src0_sel:DWORD src1_sel:WORD_1
	v_or_b32_sdwa v24, v27, v26 dst_sel:DWORD dst_unused:UNUSED_PAD src0_sel:WORD_1 src1_sel:DWORD
	ds_write_b64 v103, v[24:25]
	v_and_b32_e32 v24, 0xffff0000, v27
	v_sub_u32_e32 v6, v6, v26
	v_and_b32_e32 v23, 0xffff0000, v23
	v_sub_u32_e32 v2, v2, v24
	v_add_u32_e32 v6, 0x80, v6
	v_sub_u32_e32 v7, v7, v23
	v_sub_u32_e32 v3, v3, v36
	v_add_u32_e32 v2, 0x80, v2
	v_ashrrev_i32_e32 v6, 8, v6
	v_add_u32_e32 v7, 0x80, v7
	v_add_u32_e32 v3, 0x80, v3
	v_ashrrev_i32_e32 v2, 8, v2
	v_min_i32_e32 v6, 0x7f, v6
	v_ashrrev_i32_e32 v7, 8, v7
	v_ashrrev_i32_e32 v3, 8, v3
	v_min_i32_e32 v2, 0x7f, v2
	v_min_i32_sdwa v7, v7, s69 dst_sel:WORD_1 dst_unused:UNUSED_PAD src0_sel:DWORD src1_sel:DWORD
	v_min_i32_e32 v3, 0x7f, v3
	v_lshlrev_b32_e32 v6, 8, v6
	v_and_b32_e32 v6, 0xff00, v6
	v_and_b32_e32 v7, 0xff0000, v7
	v_perm_b32 v2, v3, v2, s76
	v_or3_b32 v2, v2, v6, v7
	ds_write_b32 v20, v2 offset:128
	v_mov_b32_e32 v2, v186
	v_mov_b32_e32 v3, v187
	v_pk_add_f32 v[6:7], v[30:31], v[2:3] op_sel_hi:[1,0] neg_lo:[0,1] neg_hi:[0,1]
	s_nop 0
	v_pk_mul_f32 v[6:7], v[2:3], v[6:7] op_sel:[1,0]
	v_pk_add_f32 v[24:25], v[28:29], v[2:3] op_sel_hi:[1,0] neg_lo:[0,1] neg_hi:[0,1]
	v_pk_fma_f32 v[6:7], v[40:41], v[6:7], v[42:43]
	v_pk_mul_f32 v[2:3], v[2:3], v[24:25] op_sel:[1,0]
	s_nop 0
	v_pk_fma_f32 v[0:1], v[0:1], v[2:3], v[4:5]
	v_and_b32_sdwa v2, v7, v244 dst_sel:DWORD dst_unused:UNUSED_PAD src0_sel:WORD_1 src1_sel:DWORD
	v_and_b32_sdwa v3, v6, v244 dst_sel:DWORD dst_unused:UNUSED_PAD src0_sel:WORD_1 src1_sel:DWORD
	v_add3_u32 v4, v7, v2, s67
	v_add3_u32 v2, v6, v3, s67
	v_and_b32_e32 v5, 0xffff0000, v2
	v_and_b32_sdwa v2, v1, v244 dst_sel:DWORD dst_unused:UNUSED_PAD src0_sel:WORD_1 src1_sel:DWORD
	v_and_b32_sdwa v3, v0, v244 dst_sel:DWORD dst_unused:UNUSED_PAD src0_sel:WORD_1 src1_sel:DWORD
	v_add3_u32 v2, v1, v2, s67
	v_add3_u32 v23, v0, v3, s67
	v_and_b32_e32 v24, 0xffff0000, v2
	v_or_b32_sdwa v3, v24, v4 dst_sel:DWORD dst_unused:UNUSED_PAD src0_sel:DWORD src1_sel:WORD_1
	v_or_b32_sdwa v2, v23, v5 dst_sel:DWORD dst_unused:UNUSED_PAD src0_sel:WORD_1 src1_sel:DWORD
	ds_write_b64 v104, v[2:3]
	v_and_b32_e32 v2, 0xffff0000, v23
	v_sub_u32_e32 v0, v0, v2
	v_sub_u32_e32 v2, v6, v5
	v_and_b32_e32 v3, 0xffff0000, v4
	v_add_u32_e32 v2, 0x80, v2
	v_sub_u32_e32 v3, v7, v3
	v_sub_u32_e32 v1, v1, v24
	v_add_u32_e32 v0, 0x80, v0
	v_ashrrev_i32_e32 v2, 8, v2
	v_add_u32_e32 v3, 0x80, v3
	v_add_u32_e32 v1, 0x80, v1
	v_ashrrev_i32_e32 v0, 8, v0
	v_min_i32_e32 v2, 0x7f, v2
	v_ashrrev_i32_e32 v3, 8, v3
	v_ashrrev_i32_e32 v1, 8, v1
	v_min_i32_e32 v0, 0x7f, v0
	v_min_i32_sdwa v3, v3, s69 dst_sel:WORD_1 dst_unused:UNUSED_PAD src0_sel:DWORD src1_sel:DWORD
	v_min_i32_e32 v1, 0x7f, v1
	v_lshlrev_b32_e32 v2, 8, v2
	v_and_b32_e32 v2, 0xff00, v2
	v_and_b32_e32 v3, 0xff0000, v3
	v_perm_b32 v0, v1, v0, s76
	v_or3_b32 v0, v0, v2, v3
	ds_write_b32 v22, v0 offset:128
	v_mov_b32_e32 v0, v208
;     ...
;           _Pragma("unroll") for (int bj = 0; bj < 2; ++bj) _Pragma("unroll") for (int n = 0; n < 2; ++n) {
;             const int cc = bj * HALF + wc3 * 32 + n * 16 + fq3 * 4;
;             const float4 gm = *reinterpret_cast<const float4*>(g.gam + pn * BM + cc), bt = *reinterpret_cast<const float4*>(g.bet + pn * BM + cc);
;             _Pragma("unroll") for (int m = 0; m < 4; ++m) {
;               const int rr = wr3 * 64 + m * 16 + fr3;
;               const float2 ms = *reinterpret_cast<const float2*>(mr + (ai * HALF + rr) * 2);
;               f32x4 y = acc[ai][bj][m][n];
;               const float o0 = (y[0] - ms.x) * ms.y * gm.x + bt.x, o1 = (y[1] - ms.x) * ms.y * gm.y + bt.y;
;               const float o2 = (y[2] - ms.x) * ms.y * gm.z + bt.z, o3 = (y[3] - ms.x) * ms.y * gm.w + bt.w;
;               const unsigned h0 = f2bf(o0), h1 = f2bf(o1), h2 = f2bf(o2), h3 = f2bf(o3);
;               u32x2 ob; ob[0] = h0 | (h1 << 16); ob[1] = h2 | (h3 << 16);
;               *reinterpret_cast<u32x2*>(smem + (rr >> 1) * PIECE + (rr & 1) * 512 + cc * 2) = ob;
;               const int l0 = min(((int)__float_as_uint(o0) - (int)(h0 << 16) + 128) >> 8, 127);
;               const int l1 = min(((int)__float_as_uint(o1) - (int)(h1 << 16) + 128) >> 8, 127);
;               const int l2 = min(((int)__float_as_uint(o2) - (int)(h2 << 16) + 128) >> 8, 127);
;               const int l3 = min(((int)__float_as_uint(o3) - (int)(h3 << 16) + 128) >> 8, 127);
;               *reinterpret_cast<unsigned*>(smem + LOBASE + (rr >> 2) * PIECE + (rr & 3) * 256 + cc) =
;                   (unsigned)(l0 & 255) | ((unsigned)(l1 & 255) << 8) | ((unsigned)(l2 & 255) << 16) | ((unsigned)l3 << 24);
;             }
	v_mov_b32_e32 v1, v209
	v_mov_b32_e32 v2, v210
	v_mov_b32_e32 v3, v211
	v_mov_b32_e32 v4, v248
	v_mov_b32_e32 v5, v249
	v_mov_b32_e32 v6, v250
	v_mov_b32_e32 v7, v251
	v_mov_b32_e32 v28, v180
	v_mov_b32_e32 v29, v181
	s_lshl_b32 s4, s0, 1
	s_mov_b64 s[6:7], -1
	v_pk_add_f32 v[30:31], v[50:51], v[28:29] op_sel_hi:[1,0] neg_lo:[0,1] neg_hi:[0,1]
	s_nop 0
	v_pk_mul_f32 v[30:31], v[28:29], v[30:31] op_sel:[1,0]
	v_pk_add_f32 v[36:37], v[48:49], v[28:29] op_sel_hi:[1,0] neg_lo:[0,1] neg_hi:[0,1]
	v_mov_b32_e32 v24, v1
	v_mov_b32_e32 v25, v2
	v_mov_b32_e32 v26, v5
	v_mov_b32_e32 v27, v6
	v_pk_fma_f32 v[30:31], v[24:25], v[30:31], v[26:27]
	v_pk_mul_f32 v[28:29], v[28:29], v[36:37] op_sel:[1,0]
	v_mov_b32_e32 v1, v3
	v_mov_b32_e32 v5, v7
	v_and_b32_sdwa v6, v31, v244 dst_sel:DWORD dst_unused:UNUSED_PAD src0_sel:WORD_1 src1_sel:DWORD
	v_and_b32_sdwa v7, v30, v244 dst_sel:DWORD dst_unused:UNUSED_PAD src0_sel:WORD_1 src1_sel:DWORD
	v_pk_fma_f32 v[2:3], v[0:1], v[28:29], v[4:5]
	v_add3_u32 v23, v31, v6, s67
	v_add3_u32 v6, v30, v7, s67
	v_and_b32_e32 v28, 0xffff0000, v6
	v_and_b32_sdwa v6, v3, v244 dst_sel:DWORD dst_unused:UNUSED_PAD src0_sel:WORD_1 src1_sel:DWORD
	v_and_b32_sdwa v7, v2, v244 dst_sel:DWORD dst_unused:UNUSED_PAD src0_sel:WORD_1 src1_sel:DWORD
	v_add3_u32 v6, v3, v6, s67
	v_add3_u32 v29, v2, v7, s67
	v_and_b32_e32 v36, 0xffff0000, v6
	v_or_b32_sdwa v7, v36, v23 dst_sel:DWORD dst_unused:UNUSED_PAD src0_sel:DWORD src1_sel:WORD_1
	v_or_b32_sdwa v6, v29, v28 dst_sel:DWORD dst_unused:UNUSED_PAD src0_sel:WORD_1 src1_sel:DWORD
	ds_write_b64 v105, v[6:7]
	v_and_b32_e32 v6, 0xffff0000, v29
	v_sub_u32_e32 v2, v2, v6
	v_sub_u32_e32 v6, v30, v28
	v_and_b32_e32 v7, 0xffff0000, v23
	v_add_u32_e32 v6, 0x80, v6
	v_sub_u32_e32 v7, v31, v7
	v_sub_u32_e32 v3, v3, v36
	v_add_u32_e32 v2, 0x80, v2
	v_ashrrev_i32_e32 v6, 8, v6
	v_add_u32_e32 v7, 0x80, v7
	v_add_u32_e32 v3, 0x80, v3
	v_ashrrev_i32_e32 v2, 8, v2
	v_min_i32_e32 v6, 0x7f, v6
	v_ashrrev_i32_e32 v7, 8, v7
	v_ashrrev_i32_e32 v3, 8, v3
	v_min_i32_e32 v2, 0x7f, v2
	v_min_i32_sdwa v7, v7, s69 dst_sel:WORD_1 dst_unused:UNUSED_PAD src0_sel:DWORD src1_sel:DWORD
	v_min_i32_e32 v3, 0x7f, v3
	v_lshlrev_b32_e32 v6, 8, v6
	v_and_b32_e32 v6, 0xff00, v6
	v_and_b32_e32 v7, 0xff0000, v7
	v_perm_b32 v2, v3, v2, s76
	v_or3_b32 v2, v2, v6, v7
	ds_write_b32 v12, v2 offset:144
	v_mov_b32_e32 v2, v182
	v_mov_b32_e32 v3, v183
	v_pk_add_f32 v[6:7], v[34:35], v[2:3] op_sel_hi:[1,0] neg_lo:[0,1] neg_hi:[0,1]
	s_nop 0
	v_pk_mul_f32 v[6:7], v[2:3], v[6:7] op_sel:[1,0]
	v_pk_add_f32 v[12:13], v[32:33], v[2:3] op_sel_hi:[1,0] neg_lo:[0,1] neg_hi:[0,1]
	v_pk_fma_f32 v[6:7], v[24:25], v[6:7], v[26:27]
	v_pk_mul_f32 v[2:3], v[2:3], v[12:13] op_sel:[1,0]
	v_and_b32_sdwa v12, v7, v244 dst_sel:DWORD dst_unused:UNUSED_PAD src0_sel:WORD_1 src1_sel:DWORD
	v_and_b32_sdwa v13, v6, v244 dst_sel:DWORD dst_unused:UNUSED_PAD src0_sel:WORD_1 src1_sel:DWORD
	v_pk_fma_f32 v[2:3], v[0:1], v[2:3], v[4:5]
	v_add3_u32 v23, v7, v12, s67
	v_add3_u32 v12, v6, v13, s67
	v_and_b32_e32 v28, 0xffff0000, v12
	v_and_b32_sdwa v12, v3, v244 dst_sel:DWORD dst_unused:UNUSED_PAD src0_sel:WORD_1 src1_sel:DWORD
	v_and_b32_sdwa v13, v2, v244 dst_sel:DWORD dst_unused:UNUSED_PAD src0_sel:WORD_1 src1_sel:DWORD
	v_add3_u32 v12, v3, v12, s67
	v_add3_u32 v29, v2, v13, s67
	v_and_b32_e32 v30, 0xffff0000, v12
	v_or_b32_sdwa v13, v30, v23 dst_sel:DWORD dst_unused:UNUSED_PAD src0_sel:DWORD src1_sel:WORD_1
	v_or_b32_sdwa v12, v29, v28 dst_sel:DWORD dst_unused:UNUSED_PAD src0_sel:WORD_1 src1_sel:DWORD
	ds_write_b64 v106, v[12:13]
	v_and_b32_e32 v12, 0xffff0000, v29
	v_sub_u32_e32 v2, v2, v12
	v_sub_u32_e32 v6, v6, v28
	v_and_b32_e32 v12, 0xffff0000, v23
	v_add_u32_e32 v6, 0x80, v6
	v_sub_u32_e32 v7, v7, v12
	v_sub_u32_e32 v3, v3, v30
	v_add_u32_e32 v2, 0x80, v2
	v_ashrrev_i32_e32 v6, 8, v6
	v_add_u32_e32 v7, 0x80, v7
	v_add_u32_e32 v3, 0x80, v3
	v_ashrrev_i32_e32 v2, 8, v2
	v_min_i32_e32 v6, 0x7f, v6
	v_ashrrev_i32_e32 v7, 8, v7
	v_ashrrev_i32_e32 v3, 8, v3
	v_min_i32_e32 v2, 0x7f, v2
	v_min_i32_sdwa v7, v7, s69 dst_sel:WORD_1 dst_unused:UNUSED_PAD src0_sel:DWORD src1_sel:DWORD
	v_min_i32_e32 v3, 0x7f, v3
	v_lshlrev_b32_e32 v6, 8, v6
	v_and_b32_e32 v6, 0xff00, v6
	v_and_b32_e32 v7, 0xff0000, v7
	v_perm_b32 v2, v3, v2, s76
	v_or3_b32 v2, v2, v6, v7
	ds_write_b32 v14, v2 offset:144
	v_mov_b32_e32 v2, v184
	v_mov_b32_e32 v3, v185
	v_pk_add_f32 v[6:7], v[18:19], v[2:3] op_sel_hi:[1,0] neg_lo:[0,1] neg_hi:[0,1]
	s_nop 0
	v_pk_mul_f32 v[6:7], v[2:3], v[6:7] op_sel:[1,0]
	v_pk_add_f32 v[12:13], v[16:17], v[2:3] op_sel_hi:[1,0] neg_lo:[0,1] neg_hi:[0,1]
	v_pk_fma_f32 v[6:7], v[24:25], v[6:7], v[26:27]
	v_pk_mul_f32 v[2:3], v[2:3], v[12:13] op_sel:[1,0]
	v_and_b32_sdwa v12, v7, v244 dst_sel:DWORD dst_unused:UNUSED_PAD src0_sel:WORD_1 src1_sel:DWORD
	v_and_b32_sdwa v13, v6, v244 dst_sel:DWORD dst_unused:UNUSED_PAD src0_sel:WORD_1 src1_sel:DWORD
	v_pk_fma_f32 v[2:3], v[0:1], v[2:3], v[4:5]
	v_add3_u32 v14, v7, v12, s67
	v_add3_u32 v12, v6, v13, s67
	v_and_b32_e32 v15, 0xffff0000, v12
	v_and_b32_sdwa v12, v3, v244 dst_sel:DWORD dst_unused:UNUSED_PAD src0_sel:WORD_1 src1_sel:DWORD
	v_and_b32_sdwa v13, v2, v244 dst_sel:DWORD dst_unused:UNUSED_PAD src0_sel:WORD_1 src1_sel:DWORD
	v_add3_u32 v12, v3, v12, s67
	v_add3_u32 v16, v2, v13, s67
	v_and_b32_e32 v17, 0xffff0000, v12
	v_or_b32_sdwa v13, v17, v14 dst_sel:DWORD dst_unused:UNUSED_PAD src0_sel:DWORD src1_sel:WORD_1
	v_or_b32_sdwa v12, v16, v15 dst_sel:DWORD dst_unused:UNUSED_PAD src0_sel:WORD_1 src1_sel:DWORD
	ds_write_b64 v107, v[12:13]
	v_and_b32_e32 v12, 0xffff0000, v16
	v_sub_u32_e32 v2, v2, v12
	v_sub_u32_e32 v6, v6, v15
; #define STAGE(P, RS, SOFF, OFF, kt) do { const int _so = (SOFF) + (kt) * (BK * 2); \
;     _Pragma("unroll") for (int _i = 0; _i < 2; ++_i) { \
;       __builtin_amdgcn_raw_ptr_buffer_load_lds(RS, (__attribute__((address_space(3))) void*)((P) + wave * 1024 + _i * 8192), 16, OFF[_i], _so, 0, 0); } } while (0)
; #define WAIT_L(n) asm volatile("s_waitcnt lgkmcnt(" #n ")" ::: "memory")
; #define BAR __builtin_amdgcn_s_barrier()
;     ...
;   auto issue_prologue = [&](int sA0, int sA1, int sB0, int sB1) {
;     const int tid = opaque_tid(wave);
;     int offA[2], offB[2];
;     _Pragma("unroll") for (int i = 0; i < 2; ++i) {
;       int r, c; stage_rc(tid * 16 + i * 8192, r, c);
;       offA[i] = (r * lda + c) * 2; offB[i] = (r * ldb + c) * 2;
;     }
;     STAGE(SB(0, 0), rsB, sB0, offB, 0); STAGE(SA(0, 0), rsA, sA0, offA, 0);
;     STAGE(SB(0, 1), rsB, sB1, offB, 0); STAGE(SA(0, 1), rsA, sA1, offA, 0);
;     STAGE(SB(1, 0), rsB, sB0, offB, 1); STAGE(SA(1, 0), rsA, sA0, offA, 1); STAGE(SB(1, 1), rsB, sB1, offB, 1);
;   };
;     ...
;           WAIT_L(0); BAR;
;           const int hso = ((brow + ai * HALF + 16 * wave) * DM + pn * BM) * 2;
;           const int lso = (brow + ai * HALF + 16 * wave) * DM + pn * BM;
;           _Pragma("unroll") for (int i = 0; i < 8; ++i) {
;             const u32x4 v = *reinterpret_cast<const u32x4*>(smem + (wave * 8 + i) * PIECE + lane3 * 16);
;             __builtin_amdgcn_raw_buffer_store_b128(v, rsXB, hvo + i * (2 * DM * 2), hso, 0);
;           }
;           _Pragma("unroll") for (int i = 0; i < 4; ++i) {
;             const u32x4 v = *reinterpret_cast<const u32x4*>(smem + LOBASE + (wave * 4 + i) * PIECE + lane3 * 16);
;             __builtin_amdgcn_raw_buffer_store_b128(v, rsLO, lvo + i * (4 * DM), lso, 0);
;           }
;           WAIT_L(0); BAR;
;         }
;       }
;       if (has_next) issue_prologue(nA0, nA1, nB0, nB1);
	v_and_b32_e32 v12, 0xffff0000, v14
	v_add_u32_e32 v6, 0x80, v6
	v_sub_u32_e32 v7, v7, v12
	v_sub_u32_e32 v3, v3, v17
	v_add_u32_e32 v2, 0x80, v2
	v_ashrrev_i32_e32 v6, 8, v6
	v_add_u32_e32 v7, 0x80, v7
	v_add_u32_e32 v3, 0x80, v3
	v_ashrrev_i32_e32 v2, 8, v2
	v_min_i32_e32 v6, 0x7f, v6
	v_ashrrev_i32_e32 v7, 8, v7
	v_ashrrev_i32_e32 v3, 8, v3
	v_min_i32_e32 v2, 0x7f, v2
	v_min_i32_sdwa v7, v7, s69 dst_sel:WORD_1 dst_unused:UNUSED_PAD src0_sel:DWORD src1_sel:DWORD
	v_min_i32_e32 v3, 0x7f, v3
	v_lshlrev_b32_e32 v6, 8, v6
	v_and_b32_e32 v6, 0xff00, v6
	v_and_b32_e32 v7, 0xff0000, v7
	v_perm_b32 v2, v3, v2, s76
	v_or3_b32 v2, v2, v6, v7
	ds_write_b32 v20, v2 offset:144
	v_mov_b32_e32 v2, v186
	v_mov_b32_e32 v3, v187
	v_pk_add_f32 v[6:7], v[10:11], v[2:3] op_sel_hi:[1,0] neg_lo:[0,1] neg_hi:[0,1]
	s_nop 0
	v_pk_mul_f32 v[6:7], v[2:3], v[6:7] op_sel:[1,0]
	v_pk_add_f32 v[8:9], v[8:9], v[2:3] op_sel_hi:[1,0] neg_lo:[0,1] neg_hi:[0,1]
	v_pk_fma_f32 v[6:7], v[24:25], v[6:7], v[26:27]
	v_pk_mul_f32 v[2:3], v[2:3], v[8:9] op_sel:[1,0]
	s_nop 0
	v_pk_fma_f32 v[0:1], v[0:1], v[2:3], v[4:5]
	v_and_b32_sdwa v2, v7, v244 dst_sel:DWORD dst_unused:UNUSED_PAD src0_sel:WORD_1 src1_sel:DWORD
	v_and_b32_sdwa v3, v6, v244 dst_sel:DWORD dst_unused:UNUSED_PAD src0_sel:WORD_1 src1_sel:DWORD
	v_add3_u32 v4, v7, v2, s67
	v_add3_u32 v2, v6, v3, s67
	v_and_b32_e32 v5, 0xffff0000, v2
	v_and_b32_sdwa v2, v1, v244 dst_sel:DWORD dst_unused:UNUSED_PAD src0_sel:WORD_1 src1_sel:DWORD
	v_and_b32_sdwa v3, v0, v244 dst_sel:DWORD dst_unused:UNUSED_PAD src0_sel:WORD_1 src1_sel:DWORD
	v_add3_u32 v2, v1, v2, s67
	v_add3_u32 v8, v0, v3, s67
	v_and_b32_e32 v9, 0xffff0000, v2
	v_or_b32_sdwa v3, v9, v4 dst_sel:DWORD dst_unused:UNUSED_PAD src0_sel:DWORD src1_sel:WORD_1
	v_or_b32_sdwa v2, v8, v5 dst_sel:DWORD dst_unused:UNUSED_PAD src0_sel:WORD_1 src1_sel:DWORD
	ds_write_b64 v88, v[2:3]
	v_and_b32_e32 v2, 0xffff0000, v8
	v_sub_u32_e32 v0, v0, v2
	v_sub_u32_e32 v2, v6, v5
	v_and_b32_e32 v3, 0xffff0000, v4
	v_add_u32_e32 v2, 0x80, v2
	v_sub_u32_e32 v3, v7, v3
	v_sub_u32_e32 v1, v1, v9
	v_add_u32_e32 v0, 0x80, v0
	v_ashrrev_i32_e32 v2, 8, v2
	v_add_u32_e32 v3, 0x80, v3
	v_add_u32_e32 v1, 0x80, v1
	v_ashrrev_i32_e32 v0, 8, v0
	v_min_i32_e32 v2, 0x7f, v2
	v_ashrrev_i32_e32 v3, 8, v3
	v_ashrrev_i32_e32 v1, 8, v1
	v_min_i32_e32 v0, 0x7f, v0
	v_min_i32_sdwa v3, v3, s69 dst_sel:WORD_1 dst_unused:UNUSED_PAD src0_sel:DWORD src1_sel:DWORD
	v_min_i32_e32 v1, 0x7f, v1
	v_lshlrev_b32_e32 v2, 8, v2
	v_and_b32_e32 v2, 0xff00, v2
	v_and_b32_e32 v3, 0xff0000, v3
	v_perm_b32 v0, v1, v0, s76
	v_or3_b32 v0, v0, v2, v3
	ds_write_b32 v22, v0 offset:144
	s_waitcnt lgkmcnt(0)
	s_barrier
	ds_read_b128 v[128:131], v74
	ds_read_b128 v[132:135], v74 offset:1040
	ds_read_b128 v[136:139], v74 offset:2080
	ds_read_b128 v[140:143], v74 offset:3120
	ds_read_b128 v[144:147], v74 offset:4160
	ds_read_b128 v[148:151], v74 offset:5200
	ds_read_b128 v[152:155], v74 offset:6240
	ds_read_b128 v[156:159], v74 offset:7280
	ds_read_b128 v[160:163], v69
	ds_read_b128 v[164:167], v69 offset:1040
	ds_read_b128 v[168:171], v69 offset:2080
	ds_read_b128 v[172:175], v69 offset:3120
	s_waitcnt lgkmcnt(0)
	s_barrier
	s_mov_b32 s98, s0
	s_cbranch_vccnz .Lmy_s1n_135
	v_mbcnt_lo_u32_b32 v0, -1, 0
	v_mbcnt_hi_u32_b32 v0, -1, v0
	s_mov_b32 m0, s34
	v_lshl_add_u32 v0, v0, 4, s30
	v_ashrrev_i32_e32 v1, 31, v0
	v_lshrrev_b32_e32 v1, 22, v1
	v_add_u32_e32 v1, v0, v1
	v_ashrrev_i32_e32 v1, 10, v1
	v_mul_i32_i24_e32 v2, 0x400, v1
	v_sub_u32_e32 v2, v0, v2
	v_lshrrev_b32_e32 v3, 4, v2
	v_bitop3_b32 v2, v3, v2, 32 bitop3:0x6c
	v_ashrrev_i32_e32 v4, 31, v2
	v_lshrrev_b32_e32 v4, 26, v4
	v_add_u32_e32 v4, v2, v4
	v_lshrrev_b32_e32 v5, 6, v4
	v_and_b32_e32 v4, 0xc0, v4
	v_lshlrev_b32_e32 v3, 3, v1
	v_lshlrev_b32_e32 v1, 5, v1
	v_sub_u32_e32 v2, v2, v4
	v_and_b32_e32 v3, 0x7fff0, v3
	v_and_b32_e32 v1, 32, v1
	v_ashrrev_i16_sdwa v2, v244, sext(v2) dst_sel:DWORD dst_unused:UNUSED_PAD src0_sel:DWORD src1_sel:BYTE_0
	v_add_u32_sdwa v1, v1, sext(v2) dst_sel:DWORD dst_unused:UNUSED_PAD src0_sel:DWORD src1_sel:WORD_0
	v_add_lshl_u32 v2, v5, v3, 13
	v_add_u32_e32 v0, 0x2000, v0
	v_lshl_add_u32 v1, v1, 1, v2
	v_ashrrev_i32_e32 v2, 31, v0
	v_lshrrev_b32_e32 v2, 22, v2
	v_add_u32_e32 v2, v0, v2
	v_ashrrev_i32_e32 v2, 10, v2
	v_mul_i32_i24_e32 v3, 0x400, v2
	v_sub_u32_e32 v0, v0, v3
	v_lshrrev_b32_e32 v3, 4, v0
	v_bitop3_b32 v0, v3, v0, 32 bitop3:0x6c
	v_ashrrev_i32_e32 v4, 31, v0
	v_lshrrev_b32_e32 v4, 26, v4
	v_add_u32_e32 v4, v0, v4
	v_lshrrev_b32_e32 v5, 6, v4
	v_and_b32_e32 v4, 0xffc0, v4
	v_sub_u32_e32 v0, v0, v4
	v_lshrrev_b16_e32 v4, 7, v0
	v_and_b32_e32 v4, 1, v4
	v_lshlrev_b32_e32 v3, 3, v2
	v_lshlrev_b32_e32 v2, 5, v2
	v_add_u16_e32 v0, v0, v4
	v_and_b32_e32 v3, 0x7fff0, v3
	v_and_b32_e32 v2, 32, v2
	v_ashrrev_i16_sdwa v0, v244, sext(v0) dst_sel:DWORD dst_unused:UNUSED_PAD src0_sel:DWORD src1_sel:BYTE_0
	v_add_u32_sdwa v0, v2, sext(v0) dst_sel:DWORD dst_unused:UNUSED_PAD src0_sel:DWORD src1_sel:WORD_0
	v_add_lshl_u32 v2, v5, v3, 13
	s_mov_b32 s14, s10
	s_mov_b32 s15, s11
	v_lshl_add_u32 v0, v0, 1, v2
	buffer_load_dwordx4 v1, s[12:15], s84 offen lds
	s_mov_b32 m0, s43
	s_or_b32 s0, s84, 0x80
	buffer_load_dwordx4 v0, s[12:15], s84 offen lds
	s_mov_b32 m0, s30
	s_mov_b64 s[6:7], 0
	buffer_load_dwordx4 v1, s[8:11], s83 offen lds
	s_mov_b32 m0, s44
	s_nop 0
	buffer_load_dwordx4 v0, s[8:11], s83 offen lds
	s_mov_b32 m0, s35
	s_nop 0
	buffer_load_dwordx4 v1, s[12:15], s85 offen lds
	s_mov_b32 m0, s45
	s_nop 0
	buffer_load_dwordx4 v0, s[12:15], s85 offen lds
	s_mov_b32 m0, s36
	s_nop 0
	buffer_load_dwordx4 v1, s[8:11], s82 offen lds
	s_mov_b32 m0, s48
	s_nop 0
	buffer_load_dwordx4 v0, s[8:11], s82 offen lds
	s_mov_b32 m0, s37
	s_nop 0
	buffer_load_dwordx4 v1, s[12:15], s0 offen lds
	s_mov_b32 m0, s49
	s_nop 0
	buffer_load_dwordx4 v0, s[12:15], s0 offen lds
	s_or_b32 s0, s83, 0x80
	s_mov_b32 m0, s38
	s_nop 0
	buffer_load_dwordx4 v1, s[8:11], s0 offen lds
	s_mov_b32 m0, s54
	s_nop 0
	buffer_load_dwordx4 v0, s[8:11], s0 offen lds
	s_add_i32 s0, s85, 0x80
	s_mov_b32 m0, s39
	s_nop 0
	buffer_load_dwordx4 v1, s[12:15], s0 offen lds
	s_mov_b32 m0, s55
	s_nop 0
	buffer_load_dwordx4 v0, s[12:15], s0 offen lds
	buffer_store_dwordx4 v[128:131], v70, s[16:19], s4 offen
	buffer_store_dwordx4 v[132:135], v89, s[16:19], s4 offen
	buffer_store_dwordx4 v[136:139], v90, s[16:19], s4 offen
	buffer_store_dwordx4 v[140:143], v91, s[16:19], s4 offen
	buffer_store_dwordx4 v[144:147], v108, s[16:19], s4 offen
	buffer_store_dwordx4 v[148:151], v109, s[16:19], s4 offen
	buffer_store_dwordx4 v[152:155], v110, s[16:19], s4 offen
	buffer_store_dwordx4 v[156:159], v111, s[16:19], s4 offen
	buffer_store_dwordx4 v[160:163], v68, s[20:23], s98 offen
	buffer_store_dwordx4 v[164:167], v112, s[20:23], s98 offen
	buffer_store_dwordx4 v[168:171], v113, s[20:23], s98 offen
	buffer_store_dwordx4 v[172:175], v114, s[20:23], s98 offen
	s_branch .LBB0_140

; #define STAGE(P, RS, SOFF, OFF, kt) do { const int _so = (SOFF) + (kt) * (BK * 2); \
;     _Pragma("unroll") for (int _i = 0; _i < 2; ++_i) { \
;       __builtin_amdgcn_raw_ptr_buffer_load_lds(RS, (__attribute__((address_space(3))) void*)((P) + wave * 1024 + _i * 8192), 16, OFF[_i], _so, 0, 0); } } while (0)
; #define LDA(dst, b, h) _Pragma("unroll") for (int m = 0; m < 4; ++m) _Pragma("unroll") for (int k = 0; k < 2; ++k) \
;     dst[m][k] = *reinterpret_cast<const bf16x8*>(SA(b, h) + lds_byte(wr * 64 + m * 16 + fr, k * 32 + fq * 8))
; #define LDB(dst, b, h) _Pragma("unroll") for (int n = 0; n < 2; ++n) _Pragma("unroll") for (int k = 0; k < 2; ++k) \
;     dst[n][k] = *reinterpret_cast<const bf16x8*>(SB(b, h) + lds_byte(wc * 32 + n * 16 + fr, k * 32 + fq * 8))
; #define WAIT_V(n) asm volatile("s_waitcnt vmcnt(" #n ")" ::: "memory")
; #define WAIT_L(n) asm volatile("s_waitcnt lgkmcnt(" #n ")" ::: "memory")
; #define BAR __builtin_amdgcn_s_barrier()
; #define SCHED __builtin_amdgcn_sched_barrier(0)
;     ...
;       LDB(B0, 0, 0); SCHED; LDA(At, 0, 0); STAGE(SA(1, 1), rsA, sA1, offA, t + 1);
;       WAIT_L(8); BAR; WAIT_L(0); MMA(0, 0, At, B0); BAR; SCHED;
;       LDB(B1, 0, 1); STAGE(SB(0, 0), rsB, sB0, offB, t + 2);
;       BAR; WAIT_L(0); MMA(0, 1, At, B1); BAR;
;       LDA(At, 0, 1); STAGE(SA(0, 0), rsA, sA0, offA, t + 2);
;       BAR; WAIT_L(0); MMA(1, 0, At, B0); BAR; SCHED;
;       STAGE(SB(0, 1), rsB, sB1, offB, t + 2);
;       WAIT_V(6); BAR; MMA(1, 1, At, B1); BAR;
.LBB0_210:
	ds_read_b128 v[154:157], v149
	ds_read_b128 v[158:161], v150
	ds_read_b128 v[162:165], v151
	ds_read_b128 v[166:169], v152
	s_add_i32 s44, s38, s17
	s_add_i32 s10, s44, 0x80
	s_mov_b32 m0, s30
	ds_read_b128 v[170:173], v131
	ds_read_b128 v[174:177], v131 offset:1024
	ds_read_b128 v[178:181], v134
	ds_read_b128 v[182:185], v134 offset:1024
	ds_read_b128 v[186:189], v133
	ds_read_b128 v[190:193], v133 offset:1024
	ds_read_b128 v[194:197], v132
	ds_read_b128 v[198:201], v132 offset:1024
	buffer_load_dwordx4 v143, s[4:7], s10 offen lds
	s_mov_b32 m0, s31
	s_nop 0
	buffer_load_dwordx4 v144, s[4:7], s10 offen lds
	s_waitcnt lgkmcnt(8)
	s_barrier
	s_waitcnt lgkmcnt(0)
	v_mfma_f32_16x16x32_bf16 v[124:127], v[154:157], v[170:173], v[124:127]
	v_mfma_f32_16x16x32_bf16 v[120:123], v[162:165], v[170:173], v[120:123]
	v_mfma_f32_16x16x32_bf16 v[116:119], v[154:157], v[178:181], v[116:119]
	v_mfma_f32_16x16x32_bf16 v[112:115], v[162:165], v[178:181], v[112:115]
	v_mfma_f32_16x16x32_bf16 v[108:111], v[154:157], v[186:189], v[108:111]
	v_mfma_f32_16x16x32_bf16 v[104:107], v[162:165], v[186:189], v[104:107]
	v_mfma_f32_16x16x32_bf16 v[100:103], v[154:157], v[194:197], v[100:103]
	v_mfma_f32_16x16x32_bf16 v[96:99], v[162:165], v[194:197], v[96:99]
	v_mfma_f32_16x16x32_bf16 v[124:127], v[158:161], v[174:177], v[124:127]
	v_mfma_f32_16x16x32_bf16 v[120:123], v[166:169], v[174:177], v[120:123]
	v_mfma_f32_16x16x32_bf16 v[116:119], v[158:161], v[182:185], v[116:119]
	v_mfma_f32_16x16x32_bf16 v[112:115], v[166:169], v[182:185], v[112:115]
	v_mfma_f32_16x16x32_bf16 v[108:111], v[158:161], v[190:193], v[108:111]
	v_mfma_f32_16x16x32_bf16 v[104:107], v[166:169], v[190:193], v[104:107]
	v_mfma_f32_16x16x32_bf16 v[100:103], v[158:161], v[198:201], v[100:103]
	v_mfma_f32_16x16x32_bf16 v[96:99], v[166:169], v[198:201], v[96:99]
	s_barrier
	s_add_i32 s45, s40, s17
	s_add_i32 s46, s45, 0x100
	s_mov_b32 s10, s6
	s_mov_b32 s11, s7
	s_mov_b32 m0, s1
	ds_read_b128 v[202:205], v145
	ds_read_b128 v[206:209], v146
	ds_read_b128 v[210:213], v147
	ds_read_b128 v[214:217], v148
	buffer_load_dwordx4 v143, s[8:11], s46 offen lds
	s_mov_b32 m0, s3
	s_nop 0
	buffer_load_dwordx4 v144, s[8:11], s46 offen lds
	s_barrier
	s_waitcnt lgkmcnt(0)
	v_mfma_f32_16x16x32_bf16 v[92:95], v[202:205], v[170:173], v[92:95]
	v_mfma_f32_16x16x32_bf16 v[88:91], v[210:213], v[170:173], v[88:91]
	v_mfma_f32_16x16x32_bf16 v[84:87], v[202:205], v[178:181], v[84:87]
	v_mfma_f32_16x16x32_bf16 v[80:83], v[210:213], v[178:181], v[80:83]
	v_mfma_f32_16x16x32_bf16 v[76:79], v[202:205], v[186:189], v[76:79]
	v_mfma_f32_16x16x32_bf16 v[72:75], v[210:213], v[186:189], v[72:75]
	v_mfma_f32_16x16x32_bf16 v[68:71], v[202:205], v[194:197], v[68:71]
	v_mfma_f32_16x16x32_bf16 v[64:67], v[210:213], v[194:197], v[64:67]
	v_mfma_f32_16x16x32_bf16 v[92:95], v[206:209], v[174:177], v[92:95]
	v_mfma_f32_16x16x32_bf16 v[88:91], v[214:217], v[174:177], v[88:91]
	v_mfma_f32_16x16x32_bf16 v[84:87], v[206:209], v[182:185], v[84:87]
	v_mfma_f32_16x16x32_bf16 v[80:83], v[214:217], v[182:185], v[80:83]
	v_mfma_f32_16x16x32_bf16 v[76:79], v[206:209], v[190:193], v[76:79]
	v_mfma_f32_16x16x32_bf16 v[72:75], v[214:217], v[190:193], v[72:75]
	v_mfma_f32_16x16x32_bf16 v[68:71], v[206:209], v[198:201], v[68:71]
	v_mfma_f32_16x16x32_bf16 v[64:67], v[214:217], v[198:201], v[64:67]
	s_add_i32 s46, s39, s17
	s_add_i32 s47, s46, 0x100
	s_mov_b32 m0, s0
	s_barrier
	ds_read_b128 v[170:173], v131 offset:16384
	ds_read_b128 v[174:177], v131 offset:17408
	ds_read_b128 v[178:181], v134 offset:16384
	ds_read_b128 v[182:185], v134 offset:17408
	ds_read_b128 v[186:189], v133 offset:16384
	ds_read_b128 v[190:193], v133 offset:17408
	ds_read_b128 v[194:197], v132 offset:16384
	ds_read_b128 v[198:201], v132 offset:17408
	buffer_load_dwordx4 v143, s[4:7], s47 offen lds
	s_mov_b32 m0, s18
	s_nop 0
	buffer_load_dwordx4 v144, s[4:7], s47 offen lds
	s_barrier
	s_waitcnt lgkmcnt(0)
	v_mfma_f32_16x16x32_bf16 v[60:63], v[154:157], v[170:173], v[60:63]
	v_mfma_f32_16x16x32_bf16 v[56:59], v[162:165], v[170:173], v[56:59]
	v_mfma_f32_16x16x32_bf16 v[52:55], v[154:157], v[178:181], v[52:55]
	v_mfma_f32_16x16x32_bf16 v[48:51], v[162:165], v[178:181], v[48:51]
	v_mfma_f32_16x16x32_bf16 v[44:47], v[154:157], v[186:189], v[44:47]
	v_mfma_f32_16x16x32_bf16 v[40:43], v[162:165], v[186:189], v[40:43]
	v_mfma_f32_16x16x32_bf16 v[36:39], v[154:157], v[194:197], v[36:39]
	v_mfma_f32_16x16x32_bf16 v[32:35], v[162:165], v[194:197], v[32:35]
	v_mfma_f32_16x16x32_bf16 v[60:63], v[158:161], v[174:177], v[60:63]
	v_mfma_f32_16x16x32_bf16 v[56:59], v[166:169], v[174:177], v[56:59]
	v_mfma_f32_16x16x32_bf16 v[52:55], v[158:161], v[182:185], v[52:55]
	v_mfma_f32_16x16x32_bf16 v[48:51], v[166:169], v[182:185], v[48:51]
	v_mfma_f32_16x16x32_bf16 v[44:47], v[158:161], v[190:193], v[44:47]
	v_mfma_f32_16x16x32_bf16 v[40:43], v[166:169], v[190:193], v[40:43]
	v_mfma_f32_16x16x32_bf16 v[36:39], v[158:161], v[198:201], v[36:39]
	v_mfma_f32_16x16x32_bf16 v[32:35], v[166:169], v[198:201], v[32:35]
	s_barrier
	s_add_i32 s47, s41, s17
	s_add_i32 s48, s47, 0x100
	s_mov_b32 m0, s19
	s_nop 0
	buffer_load_dwordx4 v143, s[8:11], s48 offen lds
	s_mov_b32 m0, s20
	s_nop 0
	buffer_load_dwordx4 v144, s[8:11], s48 offen lds
	s_waitcnt vmcnt(6)
	s_barrier
; #define STAGE(P, RS, SOFF, OFF, kt) do { const int _so = (SOFF) + (kt) * (BK * 2); \
;     _Pragma("unroll") for (int _i = 0; _i < 2; ++_i) { \
;       __builtin_amdgcn_raw_ptr_buffer_load_lds(RS, (__attribute__((address_space(3))) void*)((P) + wave * 1024 + _i * 8192), 16, OFF[_i], _so, 0, 0); } } while (0)
; #define LDA(dst, b, h) _Pragma("unroll") for (int m = 0; m < 4; ++m) _Pragma("unroll") for (int k = 0; k < 2; ++k) \
;     dst[m][k] = *reinterpret_cast<const bf16x8*>(SA(b, h) + lds_byte(wr * 64 + m * 16 + fr, k * 32 + fq * 8))
; #define LDB(dst, b, h) _Pragma("unroll") for (int n = 0; n < 2; ++n) _Pragma("unroll") for (int k = 0; k < 2; ++k) \
;     dst[n][k] = *reinterpret_cast<const bf16x8*>(SB(b, h) + lds_byte(wc * 32 + n * 16 + fr, k * 32 + fq * 8))
; #define WAIT_V(n) asm volatile("s_waitcnt vmcnt(" #n ")" ::: "memory")
; #define WAIT_L(n) asm volatile("s_waitcnt lgkmcnt(" #n ")" ::: "memory")
; #define BAR __builtin_amdgcn_s_barrier()
; #define SCHED __builtin_amdgcn_sched_barrier(0)
;     ...
;       WAIT_V(6); BAR; MMA(1, 1, At, B1); BAR;
;       LDB(B0, 1, 0); SCHED; LDA(At, 1, 0); STAGE(SA(0, 1), rsA, sA1, offA, t + 2);
;       WAIT_L(8); BAR; WAIT_L(0); MMA(0, 0, At, B0); BAR; SCHED;
;       LDB(B1, 1, 1); STAGE(SB(1, 0), rsB, sB0, offB, t + 3);
;       BAR; WAIT_L(0); MMA(0, 1, At, B1); BAR;
;       LDA(At, 1, 1); STAGE(SA(1, 0), rsA, sA0, offA, t + 3);
;       BAR; WAIT_L(0); MMA(1, 0, At, B0); BAR; SCHED;
	v_mfma_f32_16x16x32_bf16 v[28:31], v[202:205], v[170:173], v[28:31]
	v_mfma_f32_16x16x32_bf16 v[24:27], v[210:213], v[170:173], v[24:27]
	v_mfma_f32_16x16x32_bf16 v[20:23], v[202:205], v[178:181], v[20:23]
	v_mfma_f32_16x16x32_bf16 v[16:19], v[210:213], v[178:181], v[16:19]
	v_mfma_f32_16x16x32_bf16 v[12:15], v[202:205], v[186:189], v[12:15]
	v_mfma_f32_16x16x32_bf16 v[8:11], v[210:213], v[186:189], v[8:11]
	v_mfma_f32_16x16x32_bf16 v[4:7], v[202:205], v[194:197], v[4:7]
	v_mfma_f32_16x16x32_bf16 v[0:3], v[210:213], v[194:197], v[0:3]
	v_mfma_f32_16x16x32_bf16 v[28:31], v[206:209], v[174:177], v[28:31]
	v_mfma_f32_16x16x32_bf16 v[24:27], v[214:217], v[174:177], v[24:27]
	v_mfma_f32_16x16x32_bf16 v[20:23], v[206:209], v[182:185], v[20:23]
	v_mfma_f32_16x16x32_bf16 v[16:19], v[214:217], v[182:185], v[16:19]
	v_mfma_f32_16x16x32_bf16 v[12:15], v[206:209], v[190:193], v[12:15]
	v_mfma_f32_16x16x32_bf16 v[8:11], v[214:217], v[190:193], v[8:11]
	v_mfma_f32_16x16x32_bf16 v[4:7], v[206:209], v[198:201], v[4:7]
	v_mfma_f32_16x16x32_bf16 v[0:3], v[214:217], v[198:201], v[0:3]
	s_barrier
	ds_read_b128 v[154:157], v139
	ds_read_b128 v[158:161], v140
	ds_read_b128 v[162:165], v141
	ds_read_b128 v[166:169], v142
	s_addk_i32 s44, 0x100
	s_mov_b32 m0, s21
	ds_read_b128 v[170:173], v131 offset:32768
	ds_read_b128 v[174:177], v131 offset:33792
	ds_read_b128 v[178:181], v134 offset:32768
	ds_read_b128 v[182:185], v134 offset:33792
	ds_read_b128 v[186:189], v133 offset:32768
	ds_read_b128 v[190:193], v133 offset:33792
	ds_read_b128 v[194:197], v132 offset:32768
	ds_read_b128 v[198:201], v132 offset:33792
	buffer_load_dwordx4 v143, s[4:7], s44 offen lds
	s_mov_b32 m0, s22
	s_nop 0
	buffer_load_dwordx4 v144, s[4:7], s44 offen lds
	s_waitcnt lgkmcnt(8)
	s_barrier
	s_waitcnt lgkmcnt(0)
	v_mfma_f32_16x16x32_bf16 v[124:127], v[154:157], v[170:173], v[124:127]
	v_mfma_f32_16x16x32_bf16 v[120:123], v[162:165], v[170:173], v[120:123]
	v_mfma_f32_16x16x32_bf16 v[116:119], v[154:157], v[178:181], v[116:119]
	v_mfma_f32_16x16x32_bf16 v[112:115], v[162:165], v[178:181], v[112:115]
	v_mfma_f32_16x16x32_bf16 v[108:111], v[154:157], v[186:189], v[108:111]
	v_mfma_f32_16x16x32_bf16 v[104:107], v[162:165], v[186:189], v[104:107]
	v_mfma_f32_16x16x32_bf16 v[100:103], v[154:157], v[194:197], v[100:103]
	v_mfma_f32_16x16x32_bf16 v[96:99], v[162:165], v[194:197], v[96:99]
	v_mfma_f32_16x16x32_bf16 v[124:127], v[158:161], v[174:177], v[124:127]
	v_mfma_f32_16x16x32_bf16 v[120:123], v[166:169], v[174:177], v[120:123]
	v_mfma_f32_16x16x32_bf16 v[116:119], v[158:161], v[182:185], v[116:119]
	v_mfma_f32_16x16x32_bf16 v[112:115], v[166:169], v[182:185], v[112:115]
	v_mfma_f32_16x16x32_bf16 v[108:111], v[158:161], v[190:193], v[108:111]
	v_mfma_f32_16x16x32_bf16 v[104:107], v[166:169], v[190:193], v[104:107]
	v_mfma_f32_16x16x32_bf16 v[100:103], v[158:161], v[198:201], v[100:103]
	v_mfma_f32_16x16x32_bf16 v[96:99], v[166:169], v[198:201], v[96:99]
	s_barrier
	s_addk_i32 s45, 0x180
	s_mov_b32 m0, s23
	ds_read_b128 v[202:205], v135
	ds_read_b128 v[206:209], v136
	ds_read_b128 v[210:213], v137
	ds_read_b128 v[214:217], v138
	buffer_load_dwordx4 v143, s[8:11], s45 offen lds
	s_mov_b32 m0, s24
	s_nop 0
	buffer_load_dwordx4 v144, s[8:11], s45 offen lds
	s_barrier
	s_waitcnt lgkmcnt(0)
	v_mfma_f32_16x16x32_bf16 v[92:95], v[202:205], v[170:173], v[92:95]
	v_mfma_f32_16x16x32_bf16 v[88:91], v[210:213], v[170:173], v[88:91]
	v_mfma_f32_16x16x32_bf16 v[84:87], v[202:205], v[178:181], v[84:87]
	v_mfma_f32_16x16x32_bf16 v[80:83], v[210:213], v[178:181], v[80:83]
	v_mfma_f32_16x16x32_bf16 v[76:79], v[202:205], v[186:189], v[76:79]
	v_mfma_f32_16x16x32_bf16 v[72:75], v[210:213], v[186:189], v[72:75]
	v_mfma_f32_16x16x32_bf16 v[68:71], v[202:205], v[194:197], v[68:71]
	v_mfma_f32_16x16x32_bf16 v[64:67], v[210:213], v[194:197], v[64:67]
	v_mfma_f32_16x16x32_bf16 v[92:95], v[206:209], v[174:177], v[92:95]
	v_mfma_f32_16x16x32_bf16 v[88:91], v[214:217], v[174:177], v[88:91]
	v_mfma_f32_16x16x32_bf16 v[84:87], v[206:209], v[182:185], v[84:87]
	v_mfma_f32_16x16x32_bf16 v[80:83], v[214:217], v[182:185], v[80:83]
	v_mfma_f32_16x16x32_bf16 v[76:79], v[206:209], v[190:193], v[76:79]
	v_mfma_f32_16x16x32_bf16 v[72:75], v[214:217], v[190:193], v[72:75]
	v_mfma_f32_16x16x32_bf16 v[68:71], v[206:209], v[198:201], v[68:71]
	v_mfma_f32_16x16x32_bf16 v[64:67], v[214:217], v[198:201], v[64:67]
	s_addk_i32 s46, 0x180
	s_mov_b32 m0, s25
	s_barrier
	ds_read_b128 v[170:173], v131 offset:49152
	ds_read_b128 v[174:177], v131 offset:50176
	ds_read_b128 v[178:181], v134 offset:49152
	ds_read_b128 v[182:185], v134 offset:50176
	ds_read_b128 v[186:189], v133 offset:49152
	ds_read_b128 v[190:193], v133 offset:50176
	ds_read_b128 v[194:197], v132 offset:49152
	ds_read_b128 v[198:201], v132 offset:50176
	buffer_load_dwordx4 v143, s[4:7], s46 offen lds
	s_mov_b32 m0, s26
	s_nop 0
	buffer_load_dwordx4 v144, s[4:7], s46 offen lds
	s_barrier
	s_waitcnt lgkmcnt(0)
	v_mfma_f32_16x16x32_bf16 v[60:63], v[154:157], v[170:173], v[60:63]
	v_mfma_f32_16x16x32_bf16 v[56:59], v[162:165], v[170:173], v[56:59]
	v_mfma_f32_16x16x32_bf16 v[52:55], v[154:157], v[178:181], v[52:55]
	v_mfma_f32_16x16x32_bf16 v[48:51], v[162:165], v[178:181], v[48:51]
	v_mfma_f32_16x16x32_bf16 v[44:47], v[154:157], v[186:189], v[44:47]
	v_mfma_f32_16x16x32_bf16 v[40:43], v[162:165], v[186:189], v[40:43]
	v_mfma_f32_16x16x32_bf16 v[36:39], v[154:157], v[194:197], v[36:39]
	v_mfma_f32_16x16x32_bf16 v[32:35], v[162:165], v[194:197], v[32:35]
	v_mfma_f32_16x16x32_bf16 v[60:63], v[158:161], v[174:177], v[60:63]
	v_mfma_f32_16x16x32_bf16 v[56:59], v[166:169], v[174:177], v[56:59]
	v_mfma_f32_16x16x32_bf16 v[52:55], v[158:161], v[182:185], v[52:55]
	v_mfma_f32_16x16x32_bf16 v[48:51], v[166:169], v[182:185], v[48:51]
	v_mfma_f32_16x16x32_bf16 v[44:47], v[158:161], v[190:193], v[44:47]
	v_mfma_f32_16x16x32_bf16 v[40:43], v[166:169], v[190:193], v[40:43]
	v_mfma_f32_16x16x32_bf16 v[36:39], v[158:161], v[198:201], v[36:39]
	v_mfma_f32_16x16x32_bf16 v[32:35], v[166:169], v[198:201], v[32:35]
	s_barrier
; #define STAGE(P, RS, SOFF, OFF, kt) do { const int _so = (SOFF) + (kt) * (BK * 2); \
;     _Pragma("unroll") for (int _i = 0; _i < 2; ++_i) { \
;       __builtin_amdgcn_raw_ptr_buffer_load_lds(RS, (__attribute__((address_space(3))) void*)((P) + wave * 1024 + _i * 8192), 16, OFF[_i], _so, 0, 0); } } while (0)
; #define LDA(dst, b, h) _Pragma("unroll") for (int m = 0; m < 4; ++m) _Pragma("unroll") for (int k = 0; k < 2; ++k) \
;     dst[m][k] = *reinterpret_cast<const bf16x8*>(SA(b, h) + lds_byte(wr * 64 + m * 16 + fr, k * 32 + fq * 8))
; #define LDB(dst, b, h) _Pragma("unroll") for (int n = 0; n < 2; ++n) _Pragma("unroll") for (int k = 0; k < 2; ++k) \
;     dst[n][k] = *reinterpret_cast<const bf16x8*>(SB(b, h) + lds_byte(wc * 32 + n * 16 + fr, k * 32 + fq * 8))
; #define WAIT_V(n) asm volatile("s_waitcnt vmcnt(" #n ")" ::: "memory")
; #define WAIT_L(n) asm volatile("s_waitcnt lgkmcnt(" #n ")" ::: "memory")
; #define BAR __builtin_amdgcn_s_barrier()
;     ...
;       STAGE(SB(1, 1), rsB, sB1, offB, t + 3);
;       WAIT_V(6); BAR; MMA(1, 1, At, B1); BAR;
;     }
;     { LDB(B0, 0, 0); LDA(At, 0, 0); STAGE(SA(1, 1), rsA, sA1, offA, nt - 1);
;       BAR; WAIT_L(0); MMA(0, 0, At, B0); BAR;
;       LDB(B1, 0, 1); BAR; WAIT_L(0); MMA(0, 1, At, B1); BAR;
;       LDA(At, 0, 1); WAIT_V(4); BAR; WAIT_L(0); MMA(1, 0, At, B0); MMA(1, 1, At, B1); BAR; }
	s_addk_i32 s47, 0x180
	s_mov_b32 m0, s27
	s_nop 0
	buffer_load_dwordx4 v143, s[8:11], s47 offen lds
	s_mov_b32 m0, s28
	s_nop 0
	buffer_load_dwordx4 v144, s[8:11], s47 offen lds
	s_waitcnt vmcnt(6)
	s_barrier
	v_mfma_f32_16x16x32_bf16 v[28:31], v[202:205], v[170:173], v[28:31]
	v_mfma_f32_16x16x32_bf16 v[24:27], v[210:213], v[170:173], v[24:27]
	v_mfma_f32_16x16x32_bf16 v[20:23], v[202:205], v[178:181], v[20:23]
	v_mfma_f32_16x16x32_bf16 v[16:19], v[210:213], v[178:181], v[16:19]
	v_mfma_f32_16x16x32_bf16 v[12:15], v[202:205], v[186:189], v[12:15]
	v_mfma_f32_16x16x32_bf16 v[8:11], v[210:213], v[186:189], v[8:11]
	v_mfma_f32_16x16x32_bf16 v[4:7], v[202:205], v[194:197], v[4:7]
	v_mfma_f32_16x16x32_bf16 v[0:3], v[210:213], v[194:197], v[0:3]
	v_mfma_f32_16x16x32_bf16 v[28:31], v[206:209], v[174:177], v[28:31]
	v_mfma_f32_16x16x32_bf16 v[24:27], v[214:217], v[174:177], v[24:27]
	v_mfma_f32_16x16x32_bf16 v[20:23], v[206:209], v[182:185], v[20:23]
	v_mfma_f32_16x16x32_bf16 v[16:19], v[214:217], v[182:185], v[16:19]
	v_mfma_f32_16x16x32_bf16 v[12:15], v[206:209], v[190:193], v[12:15]
	v_mfma_f32_16x16x32_bf16 v[8:11], v[214:217], v[190:193], v[8:11]
	v_mfma_f32_16x16x32_bf16 v[4:7], v[206:209], v[198:201], v[4:7]
	v_mfma_f32_16x16x32_bf16 v[0:3], v[214:217], v[198:201], v[0:3]
	s_add_i32 s16, s16, 2
	s_addk_i32 s17, 0x100
	s_cmp_gt_u32 s16, 27
	s_barrier
	s_cbranch_scc0 .LBB0_210
	s_add_i32 s10, s38, 0xf80
	s_mov_b32 m0, s30
	ds_read_b128 v[154:157], v149
	ds_read_b128 v[158:161], v150
	ds_read_b128 v[162:165], v151
	ds_read_b128 v[150:153], v152
	ds_read_b128 v[166:169], v131
	ds_read_b128 v[170:173], v131 offset:1024
	ds_read_b128 v[174:177], v134
	ds_read_b128 v[178:181], v134 offset:1024
	ds_read_b128 v[182:185], v133
	ds_read_b128 v[186:189], v133 offset:1024
	ds_read_b128 v[190:193], v132
	ds_read_b128 v[194:197], v132 offset:1024
	buffer_load_dwordx4 v143, s[4:7], s10 offen lds
	s_mov_b32 m0, s31
	s_nop 0
	buffer_load_dwordx4 v144, s[4:7], s10 offen lds
	s_barrier
	s_waitcnt lgkmcnt(0)
	v_mfma_f32_16x16x32_bf16 v[124:127], v[154:157], v[166:169], v[124:127]
	v_mfma_f32_16x16x32_bf16 v[120:123], v[162:165], v[166:169], v[120:123]
	v_mfma_f32_16x16x32_bf16 v[116:119], v[154:157], v[174:177], v[116:119]
	v_mfma_f32_16x16x32_bf16 v[112:115], v[162:165], v[174:177], v[112:115]
	v_mfma_f32_16x16x32_bf16 v[108:111], v[154:157], v[182:185], v[108:111]
	v_mfma_f32_16x16x32_bf16 v[104:107], v[162:165], v[182:185], v[104:107]
	v_mfma_f32_16x16x32_bf16 v[100:103], v[154:157], v[190:193], v[100:103]
	v_mfma_f32_16x16x32_bf16 v[96:99], v[162:165], v[190:193], v[96:99]
	v_mfma_f32_16x16x32_bf16 v[124:127], v[158:161], v[170:173], v[124:127]
	v_mfma_f32_16x16x32_bf16 v[120:123], v[150:153], v[170:173], v[120:123]
	v_mfma_f32_16x16x32_bf16 v[116:119], v[158:161], v[178:181], v[116:119]
	v_mfma_f32_16x16x32_bf16 v[112:115], v[150:153], v[178:181], v[112:115]
	v_mfma_f32_16x16x32_bf16 v[108:111], v[158:161], v[186:189], v[108:111]
	v_mfma_f32_16x16x32_bf16 v[104:107], v[150:153], v[186:189], v[104:107]
	v_mfma_f32_16x16x32_bf16 v[100:103], v[158:161], v[194:197], v[100:103]
	v_mfma_f32_16x16x32_bf16 v[96:99], v[150:153], v[194:197], v[96:99]
	s_barrier
	ds_read_b128 v[198:201], v145
	ds_read_b128 v[202:205], v146
	ds_read_b128 v[144:147], v147
	ds_read_b128 v[206:209], v148
	s_barrier
	s_waitcnt lgkmcnt(0)
	v_mfma_f32_16x16x32_bf16 v[92:95], v[198:201], v[166:169], v[92:95]
	v_mfma_f32_16x16x32_bf16 v[88:91], v[144:147], v[166:169], v[88:91]
	v_mfma_f32_16x16x32_bf16 v[84:87], v[198:201], v[174:177], v[84:87]
	v_mfma_f32_16x16x32_bf16 v[80:83], v[144:147], v[174:177], v[80:83]
	v_mfma_f32_16x16x32_bf16 v[76:79], v[198:201], v[182:185], v[76:79]
	v_mfma_f32_16x16x32_bf16 v[72:75], v[144:147], v[182:185], v[72:75]
	v_mfma_f32_16x16x32_bf16 v[68:71], v[198:201], v[190:193], v[68:71]
	v_mfma_f32_16x16x32_bf16 v[64:67], v[144:147], v[190:193], v[64:67]
	v_mfma_f32_16x16x32_bf16 v[92:95], v[202:205], v[170:173], v[92:95]
	v_mfma_f32_16x16x32_bf16 v[88:91], v[206:209], v[170:173], v[88:91]
	v_mfma_f32_16x16x32_bf16 v[84:87], v[202:205], v[178:181], v[84:87]
	v_mfma_f32_16x16x32_bf16 v[80:83], v[206:209], v[178:181], v[80:83]
	v_mfma_f32_16x16x32_bf16 v[76:79], v[202:205], v[186:189], v[76:79]
	v_mfma_f32_16x16x32_bf16 v[72:75], v[206:209], v[186:189], v[72:75]
	v_mfma_f32_16x16x32_bf16 v[68:71], v[202:205], v[194:197], v[68:71]
	v_mfma_f32_16x16x32_bf16 v[64:67], v[206:209], v[194:197], v[64:67]
	s_barrier
	ds_read_b128 v[166:169], v131 offset:16384
	ds_read_b128 v[170:173], v131 offset:17408
	ds_read_b128 v[174:177], v134 offset:16384
	ds_read_b128 v[178:181], v134 offset:17408
	ds_read_b128 v[182:185], v133 offset:16384
	ds_read_b128 v[186:189], v133 offset:17408
	ds_read_b128 v[190:193], v132 offset:16384
	ds_read_b128 v[194:197], v132 offset:17408
	s_waitcnt vmcnt(4)
	s_barrier
; #define LDA(dst, b, h) _Pragma("unroll") for (int m = 0; m < 4; ++m) _Pragma("unroll") for (int k = 0; k < 2; ++k) \
;     dst[m][k] = *reinterpret_cast<const bf16x8*>(SA(b, h) + lds_byte(wr * 64 + m * 16 + fr, k * 32 + fq * 8))
; #define LDB(dst, b, h) _Pragma("unroll") for (int n = 0; n < 2; ++n) _Pragma("unroll") for (int k = 0; k < 2; ++k) \
;     dst[n][k] = *reinterpret_cast<const bf16x8*>(SB(b, h) + lds_byte(wc * 32 + n * 16 + fr, k * 32 + fq * 8))
; #define WAIT_V(n) asm volatile("s_waitcnt vmcnt(" #n ")" ::: "memory")
; #define WAIT_L(n) asm volatile("s_waitcnt lgkmcnt(" #n ")" ::: "memory")
; #define BAR __builtin_amdgcn_s_barrier()
;     ...
;       LDA(At, 0, 1); WAIT_V(4); BAR; WAIT_L(0); MMA(1, 0, At, B0); MMA(1, 1, At, B1); BAR; }
;     { LDB(B0, 1, 0); LDA(At, 1, 0); WAIT_V(2); BAR; WAIT_L(0); MMA(0, 0, At, B0); BAR;
	s_waitcnt lgkmcnt(0)
	v_mfma_f32_16x16x32_bf16 v[60:63], v[154:157], v[166:169], v[60:63]
	v_mfma_f32_16x16x32_bf16 v[56:59], v[162:165], v[166:169], v[56:59]
	v_mfma_f32_16x16x32_bf16 v[52:55], v[154:157], v[174:177], v[52:55]
	v_mfma_f32_16x16x32_bf16 v[48:51], v[162:165], v[174:177], v[48:51]
	v_mfma_f32_16x16x32_bf16 v[44:47], v[154:157], v[182:185], v[44:47]
	v_mfma_f32_16x16x32_bf16 v[40:43], v[162:165], v[182:185], v[40:43]
	v_mfma_f32_16x16x32_bf16 v[36:39], v[154:157], v[190:193], v[36:39]
	v_mfma_f32_16x16x32_bf16 v[32:35], v[162:165], v[190:193], v[32:35]
	v_mfma_f32_16x16x32_bf16 v[60:63], v[158:161], v[170:173], v[60:63]
	v_mfma_f32_16x16x32_bf16 v[56:59], v[150:153], v[170:173], v[56:59]
	v_mfma_f32_16x16x32_bf16 v[52:55], v[158:161], v[178:181], v[52:55]
	v_mfma_f32_16x16x32_bf16 v[48:51], v[150:153], v[178:181], v[48:51]
	v_mfma_f32_16x16x32_bf16 v[44:47], v[158:161], v[186:189], v[44:47]
	v_mfma_f32_16x16x32_bf16 v[40:43], v[150:153], v[186:189], v[40:43]
	v_mfma_f32_16x16x32_bf16 v[36:39], v[158:161], v[194:197], v[36:39]
	v_mfma_f32_16x16x32_bf16 v[32:35], v[150:153], v[194:197], v[32:35]
	v_mfma_f32_16x16x32_bf16 v[28:31], v[198:201], v[166:169], v[28:31]
	v_mfma_f32_16x16x32_bf16 v[24:27], v[144:147], v[166:169], v[24:27]
	v_mfma_f32_16x16x32_bf16 v[20:23], v[198:201], v[174:177], v[20:23]
	v_mfma_f32_16x16x32_bf16 v[16:19], v[144:147], v[174:177], v[16:19]
	v_mfma_f32_16x16x32_bf16 v[12:15], v[198:201], v[182:185], v[12:15]
	v_mfma_f32_16x16x32_bf16 v[8:11], v[144:147], v[182:185], v[8:11]
	v_mfma_f32_16x16x32_bf16 v[4:7], v[198:201], v[190:193], v[4:7]
	v_mfma_f32_16x16x32_bf16 v[0:3], v[144:147], v[190:193], v[0:3]
	v_mfma_f32_16x16x32_bf16 v[28:31], v[202:205], v[170:173], v[28:31]
	v_mfma_f32_16x16x32_bf16 v[24:27], v[206:209], v[170:173], v[24:27]
	v_mfma_f32_16x16x32_bf16 v[20:23], v[202:205], v[178:181], v[20:23]
	v_mfma_f32_16x16x32_bf16 v[16:19], v[206:209], v[178:181], v[16:19]
	v_mfma_f32_16x16x32_bf16 v[12:15], v[202:205], v[186:189], v[12:15]
	v_mfma_f32_16x16x32_bf16 v[8:11], v[206:209], v[186:189], v[8:11]
	v_mfma_f32_16x16x32_bf16 v[4:7], v[202:205], v[194:197], v[4:7]
	v_mfma_f32_16x16x32_bf16 v[0:3], v[206:209], v[194:197], v[0:3]
	s_barrier
	ds_read_b128 v[144:147], v139
	ds_read_b128 v[148:151], v140
	ds_read_b128 v[152:155], v141
	ds_read_b128 v[140:143], v142
	ds_read_b128 v[156:159], v131 offset:32768
	ds_read_b128 v[160:163], v131 offset:33792
	ds_read_b128 v[164:167], v134 offset:32768
	ds_read_b128 v[168:171], v134 offset:33792
	ds_read_b128 v[172:175], v133 offset:32768
	ds_read_b128 v[176:179], v133 offset:33792
	ds_read_b128 v[180:183], v132 offset:32768
	ds_read_b128 v[184:187], v132 offset:33792
	s_waitcnt vmcnt(2)
	s_barrier
	s_waitcnt lgkmcnt(0)
	v_mfma_f32_16x16x32_bf16 v[124:127], v[144:147], v[156:159], v[124:127]
	v_mfma_f32_16x16x32_bf16 v[120:123], v[152:155], v[156:159], v[120:123]
	v_mfma_f32_16x16x32_bf16 v[116:119], v[144:147], v[164:167], v[116:119]
	v_mfma_f32_16x16x32_bf16 v[112:115], v[152:155], v[164:167], v[112:115]
	v_mfma_f32_16x16x32_bf16 v[108:111], v[144:147], v[172:175], v[108:111]
	v_mfma_f32_16x16x32_bf16 v[104:107], v[152:155], v[172:175], v[104:107]
	v_mfma_f32_16x16x32_bf16 v[100:103], v[144:147], v[180:183], v[100:103]
	v_mfma_f32_16x16x32_bf16 v[96:99], v[152:155], v[180:183], v[96:99]
	v_mfma_f32_16x16x32_bf16 v[124:127], v[148:151], v[160:163], v[124:127]
	v_mfma_f32_16x16x32_bf16 v[120:123], v[140:143], v[160:163], v[120:123]
	v_mfma_f32_16x16x32_bf16 v[116:119], v[148:151], v[168:171], v[116:119]
	v_mfma_f32_16x16x32_bf16 v[112:115], v[140:143], v[168:171], v[112:115]
	v_mfma_f32_16x16x32_bf16 v[108:111], v[148:151], v[176:179], v[108:111]
	v_mfma_f32_16x16x32_bf16 v[104:107], v[140:143], v[176:179], v[104:107]
	v_mfma_f32_16x16x32_bf16 v[100:103], v[148:151], v[184:187], v[100:103]
	v_mfma_f32_16x16x32_bf16 v[96:99], v[140:143], v[184:187], v[96:99]
	s_barrier
; #define LDA(dst, b, h) _Pragma("unroll") for (int m = 0; m < 4; ++m) _Pragma("unroll") for (int k = 0; k < 2; ++k) \
;     dst[m][k] = *reinterpret_cast<const bf16x8*>(SA(b, h) + lds_byte(wr * 64 + m * 16 + fr, k * 32 + fq * 8))
; #define LDB(dst, b, h) _Pragma("unroll") for (int n = 0; n < 2; ++n) _Pragma("unroll") for (int k = 0; k < 2; ++k) \
;     dst[n][k] = *reinterpret_cast<const bf16x8*>(SB(b, h) + lds_byte(wc * 32 + n * 16 + fr, k * 32 + fq * 8))
; #define WAIT_V(n) asm volatile("s_waitcnt vmcnt(" #n ")" ::: "memory")
; #define WAIT_L(n) asm volatile("s_waitcnt lgkmcnt(" #n ")" ::: "memory")
; #define BAR __builtin_amdgcn_s_barrier()
;     ...
;       LDB(B1, 1, 1); WAIT_V(0); BAR; WAIT_L(0); MMA(0, 1, At, B1); BAR;
;       LDA(At, 1, 1); BAR; WAIT_L(0); MMA(1, 0, At, B0); MMA(1, 1, At, B1); BAR; }
;     if (wr == 0) BAR;
	ds_read_b128 v[188:191], v135
	ds_read_b128 v[192:195], v136
	ds_read_b128 v[196:199], v137
	ds_read_b128 v[136:139], v138
	s_waitcnt vmcnt(0)
	s_barrier
	s_waitcnt lgkmcnt(0)
	v_mfma_f32_16x16x32_bf16 v[92:95], v[188:191], v[156:159], v[92:95]
	v_mfma_f32_16x16x32_bf16 v[88:91], v[196:199], v[156:159], v[88:91]
	v_mfma_f32_16x16x32_bf16 v[84:87], v[188:191], v[164:167], v[84:87]
	v_mfma_f32_16x16x32_bf16 v[80:83], v[196:199], v[164:167], v[80:83]
	v_mfma_f32_16x16x32_bf16 v[76:79], v[188:191], v[172:175], v[76:79]
	v_mfma_f32_16x16x32_bf16 v[72:75], v[196:199], v[172:175], v[72:75]
	v_mfma_f32_16x16x32_bf16 v[68:71], v[188:191], v[180:183], v[68:71]
	v_mfma_f32_16x16x32_bf16 v[64:67], v[196:199], v[180:183], v[64:67]
	v_mfma_f32_16x16x32_bf16 v[92:95], v[192:195], v[160:163], v[92:95]
	v_mfma_f32_16x16x32_bf16 v[88:91], v[136:139], v[160:163], v[88:91]
	v_mfma_f32_16x16x32_bf16 v[84:87], v[192:195], v[168:171], v[84:87]
	v_mfma_f32_16x16x32_bf16 v[80:83], v[136:139], v[168:171], v[80:83]
	v_mfma_f32_16x16x32_bf16 v[76:79], v[192:195], v[176:179], v[76:79]
	v_mfma_f32_16x16x32_bf16 v[72:75], v[136:139], v[176:179], v[72:75]
	v_mfma_f32_16x16x32_bf16 v[68:71], v[192:195], v[184:187], v[68:71]
	v_mfma_f32_16x16x32_bf16 v[64:67], v[136:139], v[184:187], v[64:67]
	s_barrier
	ds_read_b128 v[156:159], v131 offset:49152
	ds_read_b128 v[160:163], v131 offset:50176
	ds_read_b128 v[164:167], v134 offset:49152
	ds_read_b128 v[168:171], v134 offset:50176
	ds_read_b128 v[172:175], v133 offset:49152
	ds_read_b128 v[176:179], v133 offset:50176
	ds_read_b128 v[180:183], v132 offset:49152
	ds_read_b128 v[132:135], v132 offset:50176
	s_barrier
	s_waitcnt lgkmcnt(0)
	v_mfma_f32_16x16x32_bf16 v[60:63], v[144:147], v[156:159], v[60:63]
	v_mfma_f32_16x16x32_bf16 v[56:59], v[152:155], v[156:159], v[56:59]
	v_mfma_f32_16x16x32_bf16 v[52:55], v[144:147], v[164:167], v[52:55]
	v_mfma_f32_16x16x32_bf16 v[48:51], v[152:155], v[164:167], v[48:51]
	v_mfma_f32_16x16x32_bf16 v[44:47], v[144:147], v[172:175], v[44:47]
	v_mfma_f32_16x16x32_bf16 v[40:43], v[152:155], v[172:175], v[40:43]
	v_mfma_f32_16x16x32_bf16 v[36:39], v[144:147], v[180:183], v[36:39]
	v_mfma_f32_16x16x32_bf16 v[32:35], v[152:155], v[180:183], v[32:35]
	v_mfma_f32_16x16x32_bf16 v[60:63], v[148:151], v[160:163], v[60:63]
	v_mfma_f32_16x16x32_bf16 v[56:59], v[140:143], v[160:163], v[56:59]
	v_mfma_f32_16x16x32_bf16 v[52:55], v[148:151], v[168:171], v[52:55]
	v_mfma_f32_16x16x32_bf16 v[48:51], v[140:143], v[168:171], v[48:51]
	v_mfma_f32_16x16x32_bf16 v[44:47], v[148:151], v[176:179], v[44:47]
	v_mfma_f32_16x16x32_bf16 v[40:43], v[140:143], v[176:179], v[40:43]
	v_mfma_f32_16x16x32_bf16 v[36:39], v[148:151], v[132:135], v[36:39]
	v_mfma_f32_16x16x32_bf16 v[32:35], v[140:143], v[132:135], v[32:35]
	v_mfma_f32_16x16x32_bf16 v[28:31], v[188:191], v[156:159], v[28:31]
	v_mfma_f32_16x16x32_bf16 v[24:27], v[196:199], v[156:159], v[24:27]
	v_mfma_f32_16x16x32_bf16 v[20:23], v[188:191], v[164:167], v[20:23]
	v_mfma_f32_16x16x32_bf16 v[16:19], v[196:199], v[164:167], v[16:19]
	v_mfma_f32_16x16x32_bf16 v[12:15], v[188:191], v[172:175], v[12:15]
	v_mfma_f32_16x16x32_bf16 v[8:11], v[196:199], v[172:175], v[8:11]
	v_mfma_f32_16x16x32_bf16 v[4:7], v[188:191], v[180:183], v[4:7]
	v_mfma_f32_16x16x32_bf16 v[0:3], v[196:199], v[180:183], v[0:3]
	v_mfma_f32_16x16x32_bf16 v[28:31], v[192:195], v[160:163], v[28:31]
	v_mfma_f32_16x16x32_bf16 v[24:27], v[136:139], v[160:163], v[24:27]
	v_mfma_f32_16x16x32_bf16 v[20:23], v[192:195], v[168:171], v[20:23]
	v_mfma_f32_16x16x32_bf16 v[16:19], v[136:139], v[168:171], v[16:19]
	v_mfma_f32_16x16x32_bf16 v[12:15], v[192:195], v[176:179], v[12:15]
	v_mfma_f32_16x16x32_bf16 v[8:11], v[136:139], v[176:179], v[8:11]
	v_mfma_f32_16x16x32_bf16 v[4:7], v[192:195], v[132:135], v[4:7]
	v_mfma_f32_16x16x32_bf16 v[0:3], v[136:139], v[132:135], v[0:3]
	v_cmp_gt_u32_e32 vcc, s35, v130
	s_barrier
	s_and_saveexec_b64 s[10:11], vcc
	s_cbranch_execz .LBB0_213
	s_barrier

; #define STAGE(P, RS, SOFF, OFF, kt) do { const int _so = (SOFF) + (kt) * (BK * 2); \
;     _Pragma("unroll") for (int _i = 0; _i < 2; ++_i) { \
;       __builtin_amdgcn_raw_ptr_buffer_load_lds(RS, (__attribute__((address_space(3))) void*)((P) + wave * 1024 + _i * 8192), 16, OFF[_i], _so, 0, 0); } } while (0)
; #define LDA(dst, b, h) _Pragma("unroll") for (int m = 0; m < 4; ++m) _Pragma("unroll") for (int k = 0; k < 2; ++k) \
;     dst[m][k] = *reinterpret_cast<const bf16x8*>(SA(b, h) + lds_byte(wr * 64 + m * 16 + fr, k * 32 + fq * 8))
; #define LDB(dst, b, h) _Pragma("unroll") for (int n = 0; n < 2; ++n) _Pragma("unroll") for (int k = 0; k < 2; ++k) \
;     dst[n][k] = *reinterpret_cast<const bf16x8*>(SB(b, h) + lds_byte(wc * 32 + n * 16 + fr, k * 32 + fq * 8))
; #define WAIT_V(n) asm volatile("s_waitcnt vmcnt(" #n ")" ::: "memory")
; #define WAIT_L(n) asm volatile("s_waitcnt lgkmcnt(" #n ")" ::: "memory")
; #define BAR __builtin_amdgcn_s_barrier()
; #define SCHED __builtin_amdgcn_sched_barrier(0)
;     ...
;       LDB(B0, 0, 0); SCHED; LDA(At, 0, 0); STAGE(SA(1, 1), rsA, sA1, offA, t + 1);
;       WAIT_L(8); BAR; WAIT_L(0); MMA(0, 0, At, B0); BAR; SCHED;
;       LDB(B1, 0, 1); STAGE(SB(0, 0), rsB, sB0, offB, t + 2);
;       BAR; WAIT_L(0); MMA(0, 1, At, B1); BAR;
;       LDA(At, 0, 1); STAGE(SA(0, 0), rsA, sA0, offA, t + 2);
;       BAR; WAIT_L(0); MMA(1, 0, At, B0); BAR; SCHED;
;       STAGE(SB(0, 1), rsB, sB1, offB, t + 2);
;       WAIT_V(6); BAR; MMA(1, 1, At, B1); BAR;
.LBB0_225:
	ds_read_b128 v[152:155], v148
	ds_read_b128 v[156:159], v149
	ds_read_b128 v[160:163], v150
	ds_read_b128 v[164:167], v151
	s_add_i32 s18, s41, s17
	s_add_i32 s19, s18, 0x80
	s_mov_b32 m0, s33
	ds_read_b128 v[168:171], v130
	ds_read_b128 v[172:175], v130 offset:1024
	ds_read_b128 v[176:179], v133
	ds_read_b128 v[180:183], v133 offset:1024
	ds_read_b128 v[184:187], v132
	ds_read_b128 v[188:191], v132 offset:1024
	ds_read_b128 v[192:195], v131
	ds_read_b128 v[196:199], v131 offset:1024
	buffer_load_dwordx4 v142, s[4:7], s19 offen lds
	s_mov_b32 m0, s34
	s_nop 0
	buffer_load_dwordx4 v143, s[4:7], s19 offen lds
	s_waitcnt lgkmcnt(8)
	s_barrier
	s_waitcnt lgkmcnt(0)
	v_mfma_f32_16x16x32_bf16 v[124:127], v[168:171], v[152:155], v[124:127]
	v_mfma_f32_16x16x32_bf16 v[120:123], v[168:171], v[160:163], v[120:123]
	v_mfma_f32_16x16x32_bf16 v[116:119], v[176:179], v[152:155], v[116:119]
	v_mfma_f32_16x16x32_bf16 v[112:115], v[176:179], v[160:163], v[112:115]
	v_mfma_f32_16x16x32_bf16 v[108:111], v[184:187], v[152:155], v[108:111]
	v_mfma_f32_16x16x32_bf16 v[104:107], v[184:187], v[160:163], v[104:107]
	v_mfma_f32_16x16x32_bf16 v[100:103], v[192:195], v[152:155], v[100:103]
	v_mfma_f32_16x16x32_bf16 v[96:99], v[192:195], v[160:163], v[96:99]
	v_mfma_f32_16x16x32_bf16 v[124:127], v[172:175], v[156:159], v[124:127]
	v_mfma_f32_16x16x32_bf16 v[120:123], v[172:175], v[164:167], v[120:123]
	v_mfma_f32_16x16x32_bf16 v[116:119], v[180:183], v[156:159], v[116:119]
	v_mfma_f32_16x16x32_bf16 v[112:115], v[180:183], v[164:167], v[112:115]
	v_mfma_f32_16x16x32_bf16 v[108:111], v[188:191], v[156:159], v[108:111]
	v_mfma_f32_16x16x32_bf16 v[104:107], v[188:191], v[164:167], v[104:107]
	v_mfma_f32_16x16x32_bf16 v[100:103], v[196:199], v[156:159], v[100:103]
	v_mfma_f32_16x16x32_bf16 v[96:99], v[196:199], v[164:167], v[96:99]
	s_barrier
	s_add_i32 s19, s43, s17
	s_add_i32 s47, s19, 0x100
	s_mov_b32 m0, s1
	ds_read_b128 v[200:203], v144
	ds_read_b128 v[204:207], v145
	ds_read_b128 v[208:211], v146
	ds_read_b128 v[212:215], v147
	buffer_load_dwordx4 v142, s[8:11], s47 offen lds
	s_mov_b32 m0, s3
	s_nop 0
	buffer_load_dwordx4 v143, s[8:11], s47 offen lds
	s_barrier
	s_waitcnt lgkmcnt(0)
	v_mfma_f32_16x16x32_bf16 v[92:95], v[168:171], v[200:203], v[92:95]
	v_mfma_f32_16x16x32_bf16 v[88:91], v[168:171], v[208:211], v[88:91]
	v_mfma_f32_16x16x32_bf16 v[84:87], v[176:179], v[200:203], v[84:87]
	v_mfma_f32_16x16x32_bf16 v[80:83], v[176:179], v[208:211], v[80:83]
	v_mfma_f32_16x16x32_bf16 v[76:79], v[184:187], v[200:203], v[76:79]
	v_mfma_f32_16x16x32_bf16 v[72:75], v[184:187], v[208:211], v[72:75]
	v_mfma_f32_16x16x32_bf16 v[68:71], v[192:195], v[200:203], v[68:71]
	v_mfma_f32_16x16x32_bf16 v[64:67], v[192:195], v[208:211], v[64:67]
	v_mfma_f32_16x16x32_bf16 v[92:95], v[172:175], v[204:207], v[92:95]
	v_mfma_f32_16x16x32_bf16 v[88:91], v[172:175], v[212:215], v[88:91]
	v_mfma_f32_16x16x32_bf16 v[84:87], v[180:183], v[204:207], v[84:87]
	v_mfma_f32_16x16x32_bf16 v[80:83], v[180:183], v[212:215], v[80:83]
	v_mfma_f32_16x16x32_bf16 v[76:79], v[188:191], v[204:207], v[76:79]
	v_mfma_f32_16x16x32_bf16 v[72:75], v[188:191], v[212:215], v[72:75]
	v_mfma_f32_16x16x32_bf16 v[68:71], v[196:199], v[204:207], v[68:71]
	v_mfma_f32_16x16x32_bf16 v[64:67], v[196:199], v[212:215], v[64:67]
	s_add_i32 s47, s42, s17
	s_add_i32 s48, s47, 0x100
	s_mov_b32 m0, s0
	s_barrier
	ds_read_b128 v[168:171], v130 offset:16384
	ds_read_b128 v[172:175], v130 offset:17408
	ds_read_b128 v[176:179], v133 offset:16384
	ds_read_b128 v[180:183], v133 offset:17408
	ds_read_b128 v[184:187], v132 offset:16384
	ds_read_b128 v[188:191], v132 offset:17408
	ds_read_b128 v[192:195], v131 offset:16384
	ds_read_b128 v[196:199], v131 offset:17408
	buffer_load_dwordx4 v142, s[4:7], s48 offen lds
	s_mov_b32 m0, s20
	s_nop 0
	buffer_load_dwordx4 v143, s[4:7], s48 offen lds
	s_barrier
	s_waitcnt lgkmcnt(0)
	v_mfma_f32_16x16x32_bf16 v[60:63], v[168:171], v[152:155], v[60:63]
	v_mfma_f32_16x16x32_bf16 v[56:59], v[168:171], v[160:163], v[56:59]
	v_mfma_f32_16x16x32_bf16 v[52:55], v[176:179], v[152:155], v[52:55]
	v_mfma_f32_16x16x32_bf16 v[48:51], v[176:179], v[160:163], v[48:51]
	v_mfma_f32_16x16x32_bf16 v[44:47], v[184:187], v[152:155], v[44:47]
	v_mfma_f32_16x16x32_bf16 v[40:43], v[184:187], v[160:163], v[40:43]
	v_mfma_f32_16x16x32_bf16 v[36:39], v[192:195], v[152:155], v[36:39]
	v_mfma_f32_16x16x32_bf16 v[32:35], v[192:195], v[160:163], v[32:35]
	v_mfma_f32_16x16x32_bf16 v[60:63], v[172:175], v[156:159], v[60:63]
	v_mfma_f32_16x16x32_bf16 v[56:59], v[172:175], v[164:167], v[56:59]
	v_mfma_f32_16x16x32_bf16 v[52:55], v[180:183], v[156:159], v[52:55]
	v_mfma_f32_16x16x32_bf16 v[48:51], v[180:183], v[164:167], v[48:51]
	v_mfma_f32_16x16x32_bf16 v[44:47], v[188:191], v[156:159], v[44:47]
	v_mfma_f32_16x16x32_bf16 v[40:43], v[188:191], v[164:167], v[40:43]
	v_mfma_f32_16x16x32_bf16 v[36:39], v[196:199], v[156:159], v[36:39]
	v_mfma_f32_16x16x32_bf16 v[32:35], v[196:199], v[164:167], v[32:35]
	s_barrier
	s_add_i32 s48, s44, s17
	s_add_i32 s49, s48, 0x100
	s_mov_b32 m0, s21
	s_nop 0
	buffer_load_dwordx4 v142, s[8:11], s49 offen lds
	s_mov_b32 m0, s22
	s_nop 0
	buffer_load_dwordx4 v143, s[8:11], s49 offen lds
	s_waitcnt vmcnt(6)
	s_barrier
; #define STAGE(P, RS, SOFF, OFF, kt) do { const int _so = (SOFF) + (kt) * (BK * 2); \
;     _Pragma("unroll") for (int _i = 0; _i < 2; ++_i) { \
;       __builtin_amdgcn_raw_ptr_buffer_load_lds(RS, (__attribute__((address_space(3))) void*)((P) + wave * 1024 + _i * 8192), 16, OFF[_i], _so, 0, 0); } } while (0)
; #define LDA(dst, b, h) _Pragma("unroll") for (int m = 0; m < 4; ++m) _Pragma("unroll") for (int k = 0; k < 2; ++k) \
;     dst[m][k] = *reinterpret_cast<const bf16x8*>(SA(b, h) + lds_byte(wr * 64 + m * 16 + fr, k * 32 + fq * 8))
; #define LDB(dst, b, h) _Pragma("unroll") for (int n = 0; n < 2; ++n) _Pragma("unroll") for (int k = 0; k < 2; ++k) \
;     dst[n][k] = *reinterpret_cast<const bf16x8*>(SB(b, h) + lds_byte(wc * 32 + n * 16 + fr, k * 32 + fq * 8))
; #define WAIT_V(n) asm volatile("s_waitcnt vmcnt(" #n ")" ::: "memory")
; #define WAIT_L(n) asm volatile("s_waitcnt lgkmcnt(" #n ")" ::: "memory")
; #define BAR __builtin_amdgcn_s_barrier()
; #define SCHED __builtin_amdgcn_sched_barrier(0)
;     ...
;       WAIT_V(6); BAR; MMA(1, 1, At, B1); BAR;
;       LDB(B0, 1, 0); SCHED; LDA(At, 1, 0); STAGE(SA(0, 1), rsA, sA1, offA, t + 2);
;       WAIT_L(8); BAR; WAIT_L(0); MMA(0, 0, At, B0); BAR; SCHED;
;       LDB(B1, 1, 1); STAGE(SB(1, 0), rsB, sB0, offB, t + 3);
;       BAR; WAIT_L(0); MMA(0, 1, At, B1); BAR;
;       LDA(At, 1, 1); STAGE(SA(1, 0), rsA, sA0, offA, t + 3);
;       BAR; WAIT_L(0); MMA(1, 0, At, B0); BAR; SCHED;
	v_mfma_f32_16x16x32_bf16 v[28:31], v[168:171], v[200:203], v[28:31]
	v_mfma_f32_16x16x32_bf16 v[24:27], v[168:171], v[208:211], v[24:27]
	v_mfma_f32_16x16x32_bf16 v[20:23], v[176:179], v[200:203], v[20:23]
	v_mfma_f32_16x16x32_bf16 v[16:19], v[176:179], v[208:211], v[16:19]
	v_mfma_f32_16x16x32_bf16 v[12:15], v[184:187], v[200:203], v[12:15]
	v_mfma_f32_16x16x32_bf16 v[8:11], v[184:187], v[208:211], v[8:11]
	v_mfma_f32_16x16x32_bf16 v[4:7], v[192:195], v[200:203], v[4:7]
	v_mfma_f32_16x16x32_bf16 v[0:3], v[192:195], v[208:211], v[0:3]
	v_mfma_f32_16x16x32_bf16 v[28:31], v[172:175], v[204:207], v[28:31]
	v_mfma_f32_16x16x32_bf16 v[24:27], v[172:175], v[212:215], v[24:27]
	v_mfma_f32_16x16x32_bf16 v[20:23], v[180:183], v[204:207], v[20:23]
	v_mfma_f32_16x16x32_bf16 v[16:19], v[180:183], v[212:215], v[16:19]
	v_mfma_f32_16x16x32_bf16 v[12:15], v[188:191], v[204:207], v[12:15]
	v_mfma_f32_16x16x32_bf16 v[8:11], v[188:191], v[212:215], v[8:11]
	v_mfma_f32_16x16x32_bf16 v[4:7], v[196:199], v[204:207], v[4:7]
	v_mfma_f32_16x16x32_bf16 v[0:3], v[196:199], v[212:215], v[0:3]
	s_barrier
	ds_read_b128 v[152:155], v138
	ds_read_b128 v[156:159], v139
	ds_read_b128 v[160:163], v140
	ds_read_b128 v[164:167], v141
	s_addk_i32 s18, 0x100
	s_mov_b32 m0, s23
	ds_read_b128 v[168:171], v130 offset:32768
	ds_read_b128 v[172:175], v130 offset:33792
	ds_read_b128 v[176:179], v133 offset:32768
	ds_read_b128 v[180:183], v133 offset:33792
	ds_read_b128 v[184:187], v132 offset:32768
	ds_read_b128 v[188:191], v132 offset:33792
	ds_read_b128 v[192:195], v131 offset:32768
	ds_read_b128 v[196:199], v131 offset:33792
	buffer_load_dwordx4 v142, s[4:7], s18 offen lds
	s_mov_b32 m0, s24
	s_nop 0
	buffer_load_dwordx4 v143, s[4:7], s18 offen lds
	s_waitcnt lgkmcnt(8)
	s_barrier
	s_waitcnt lgkmcnt(0)
	v_mfma_f32_16x16x32_bf16 v[124:127], v[168:171], v[152:155], v[124:127]
	v_mfma_f32_16x16x32_bf16 v[120:123], v[168:171], v[160:163], v[120:123]
	v_mfma_f32_16x16x32_bf16 v[116:119], v[176:179], v[152:155], v[116:119]
	v_mfma_f32_16x16x32_bf16 v[112:115], v[176:179], v[160:163], v[112:115]
	v_mfma_f32_16x16x32_bf16 v[108:111], v[184:187], v[152:155], v[108:111]
	v_mfma_f32_16x16x32_bf16 v[104:107], v[184:187], v[160:163], v[104:107]
	v_mfma_f32_16x16x32_bf16 v[100:103], v[192:195], v[152:155], v[100:103]
	v_mfma_f32_16x16x32_bf16 v[96:99], v[192:195], v[160:163], v[96:99]
	v_mfma_f32_16x16x32_bf16 v[124:127], v[172:175], v[156:159], v[124:127]
	v_mfma_f32_16x16x32_bf16 v[120:123], v[172:175], v[164:167], v[120:123]
	v_mfma_f32_16x16x32_bf16 v[116:119], v[180:183], v[156:159], v[116:119]
	v_mfma_f32_16x16x32_bf16 v[112:115], v[180:183], v[164:167], v[112:115]
	v_mfma_f32_16x16x32_bf16 v[108:111], v[188:191], v[156:159], v[108:111]
	v_mfma_f32_16x16x32_bf16 v[104:107], v[188:191], v[164:167], v[104:107]
	v_mfma_f32_16x16x32_bf16 v[100:103], v[196:199], v[156:159], v[100:103]
	v_mfma_f32_16x16x32_bf16 v[96:99], v[196:199], v[164:167], v[96:99]
	s_barrier
	s_addk_i32 s19, 0x180
	s_mov_b32 m0, s25
	ds_read_b128 v[200:203], v134
	ds_read_b128 v[204:207], v135
	ds_read_b128 v[208:211], v136
	ds_read_b128 v[212:215], v137
	buffer_load_dwordx4 v142, s[8:11], s19 offen lds
	s_mov_b32 m0, s26
	s_nop 0
	buffer_load_dwordx4 v143, s[8:11], s19 offen lds
	s_barrier
	s_waitcnt lgkmcnt(0)
	v_mfma_f32_16x16x32_bf16 v[92:95], v[168:171], v[200:203], v[92:95]
	v_mfma_f32_16x16x32_bf16 v[88:91], v[168:171], v[208:211], v[88:91]
	v_mfma_f32_16x16x32_bf16 v[84:87], v[176:179], v[200:203], v[84:87]
	v_mfma_f32_16x16x32_bf16 v[80:83], v[176:179], v[208:211], v[80:83]
	v_mfma_f32_16x16x32_bf16 v[76:79], v[184:187], v[200:203], v[76:79]
	v_mfma_f32_16x16x32_bf16 v[72:75], v[184:187], v[208:211], v[72:75]
	v_mfma_f32_16x16x32_bf16 v[68:71], v[192:195], v[200:203], v[68:71]
	v_mfma_f32_16x16x32_bf16 v[64:67], v[192:195], v[208:211], v[64:67]
	v_mfma_f32_16x16x32_bf16 v[92:95], v[172:175], v[204:207], v[92:95]
	v_mfma_f32_16x16x32_bf16 v[88:91], v[172:175], v[212:215], v[88:91]
	v_mfma_f32_16x16x32_bf16 v[84:87], v[180:183], v[204:207], v[84:87]
	v_mfma_f32_16x16x32_bf16 v[80:83], v[180:183], v[212:215], v[80:83]
	v_mfma_f32_16x16x32_bf16 v[76:79], v[188:191], v[204:207], v[76:79]
	v_mfma_f32_16x16x32_bf16 v[72:75], v[188:191], v[212:215], v[72:75]
	v_mfma_f32_16x16x32_bf16 v[68:71], v[196:199], v[204:207], v[68:71]
	v_mfma_f32_16x16x32_bf16 v[64:67], v[196:199], v[212:215], v[64:67]
	s_addk_i32 s47, 0x180
	s_mov_b32 m0, s27
	s_barrier
	ds_read_b128 v[168:171], v130 offset:49152
	ds_read_b128 v[172:175], v130 offset:50176
	ds_read_b128 v[176:179], v133 offset:49152
	ds_read_b128 v[180:183], v133 offset:50176
	ds_read_b128 v[184:187], v132 offset:49152
	ds_read_b128 v[188:191], v132 offset:50176
	ds_read_b128 v[192:195], v131 offset:49152
	ds_read_b128 v[196:199], v131 offset:50176
	buffer_load_dwordx4 v142, s[4:7], s47 offen lds
	s_mov_b32 m0, s28
	s_nop 0
	buffer_load_dwordx4 v143, s[4:7], s47 offen lds
	s_barrier
	s_waitcnt lgkmcnt(0)
	v_mfma_f32_16x16x32_bf16 v[60:63], v[168:171], v[152:155], v[60:63]
	v_mfma_f32_16x16x32_bf16 v[56:59], v[168:171], v[160:163], v[56:59]
	v_mfma_f32_16x16x32_bf16 v[52:55], v[176:179], v[152:155], v[52:55]
	v_mfma_f32_16x16x32_bf16 v[48:51], v[176:179], v[160:163], v[48:51]
	v_mfma_f32_16x16x32_bf16 v[44:47], v[184:187], v[152:155], v[44:47]
	v_mfma_f32_16x16x32_bf16 v[40:43], v[184:187], v[160:163], v[40:43]
	v_mfma_f32_16x16x32_bf16 v[36:39], v[192:195], v[152:155], v[36:39]
	v_mfma_f32_16x16x32_bf16 v[32:35], v[192:195], v[160:163], v[32:35]
	v_mfma_f32_16x16x32_bf16 v[60:63], v[172:175], v[156:159], v[60:63]
	v_mfma_f32_16x16x32_bf16 v[56:59], v[172:175], v[164:167], v[56:59]
	v_mfma_f32_16x16x32_bf16 v[52:55], v[180:183], v[156:159], v[52:55]
	v_mfma_f32_16x16x32_bf16 v[48:51], v[180:183], v[164:167], v[48:51]
	v_mfma_f32_16x16x32_bf16 v[44:47], v[188:191], v[156:159], v[44:47]
	v_mfma_f32_16x16x32_bf16 v[40:43], v[188:191], v[164:167], v[40:43]
	v_mfma_f32_16x16x32_bf16 v[36:39], v[196:199], v[156:159], v[36:39]
	v_mfma_f32_16x16x32_bf16 v[32:35], v[196:199], v[164:167], v[32:35]
	s_barrier
; #define STAGE(P, RS, SOFF, OFF, kt) do { const int _so = (SOFF) + (kt) * (BK * 2); \
;     _Pragma("unroll") for (int _i = 0; _i < 2; ++_i) { \
;       __builtin_amdgcn_raw_ptr_buffer_load_lds(RS, (__attribute__((address_space(3))) void*)((P) + wave * 1024 + _i * 8192), 16, OFF[_i], _so, 0, 0); } } while (0)
; #define LDA(dst, b, h) _Pragma("unroll") for (int m = 0; m < 4; ++m) _Pragma("unroll") for (int k = 0; k < 2; ++k) \
;     dst[m][k] = *reinterpret_cast<const bf16x8*>(SA(b, h) + lds_byte(wr * 64 + m * 16 + fr, k * 32 + fq * 8))
; #define LDB(dst, b, h) _Pragma("unroll") for (int n = 0; n < 2; ++n) _Pragma("unroll") for (int k = 0; k < 2; ++k) \
;     dst[n][k] = *reinterpret_cast<const bf16x8*>(SB(b, h) + lds_byte(wc * 32 + n * 16 + fr, k * 32 + fq * 8))
; #define WAIT_V(n) asm volatile("s_waitcnt vmcnt(" #n ")" ::: "memory")
; #define WAIT_L(n) asm volatile("s_waitcnt lgkmcnt(" #n ")" ::: "memory")
; #define BAR __builtin_amdgcn_s_barrier()
;     ...
;       STAGE(SB(1, 1), rsB, sB1, offB, t + 3);
;       WAIT_V(6); BAR; MMA(1, 1, At, B1); BAR;
;     }
;     { LDB(B0, 0, 0); LDA(At, 0, 0); STAGE(SA(1, 1), rsA, sA1, offA, nt - 1);
;       BAR; WAIT_L(0); MMA(0, 0, At, B0); BAR;
;       LDB(B1, 0, 1); BAR; WAIT_L(0); MMA(0, 1, At, B1); BAR;
;       LDA(At, 0, 1); WAIT_V(4); BAR; WAIT_L(0); MMA(1, 0, At, B0); MMA(1, 1, At, B1); BAR; }
	s_addk_i32 s48, 0x180
	s_mov_b32 m0, s29
	s_nop 0
	buffer_load_dwordx4 v142, s[8:11], s48 offen lds
	s_mov_b32 m0, s30
	s_nop 0
	buffer_load_dwordx4 v143, s[8:11], s48 offen lds
	s_waitcnt vmcnt(6)
	s_barrier
	v_mfma_f32_16x16x32_bf16 v[28:31], v[168:171], v[200:203], v[28:31]
	v_mfma_f32_16x16x32_bf16 v[24:27], v[168:171], v[208:211], v[24:27]
	v_mfma_f32_16x16x32_bf16 v[20:23], v[176:179], v[200:203], v[20:23]
	v_mfma_f32_16x16x32_bf16 v[16:19], v[176:179], v[208:211], v[16:19]
	v_mfma_f32_16x16x32_bf16 v[12:15], v[184:187], v[200:203], v[12:15]
	v_mfma_f32_16x16x32_bf16 v[8:11], v[184:187], v[208:211], v[8:11]
	v_mfma_f32_16x16x32_bf16 v[4:7], v[192:195], v[200:203], v[4:7]
	v_mfma_f32_16x16x32_bf16 v[0:3], v[192:195], v[208:211], v[0:3]
	v_mfma_f32_16x16x32_bf16 v[28:31], v[172:175], v[204:207], v[28:31]
	v_mfma_f32_16x16x32_bf16 v[24:27], v[172:175], v[212:215], v[24:27]
	v_mfma_f32_16x16x32_bf16 v[20:23], v[180:183], v[204:207], v[20:23]
	v_mfma_f32_16x16x32_bf16 v[16:19], v[180:183], v[212:215], v[16:19]
	v_mfma_f32_16x16x32_bf16 v[12:15], v[188:191], v[204:207], v[12:15]
	v_mfma_f32_16x16x32_bf16 v[8:11], v[188:191], v[212:215], v[8:11]
	v_mfma_f32_16x16x32_bf16 v[4:7], v[196:199], v[204:207], v[4:7]
	v_mfma_f32_16x16x32_bf16 v[0:3], v[196:199], v[212:215], v[0:3]
	s_add_i32 s16, s16, 2
	s_addk_i32 s17, 0x100
	s_cmp_gt_u32 s16, 27
	s_barrier
	s_cbranch_scc0 .LBB0_225
	s_add_i32 s16, s41, 0xf80
	s_mov_b32 m0, s33
	ds_read_b128 v[152:155], v148
	ds_read_b128 v[156:159], v149
	ds_read_b128 v[160:163], v150
	ds_read_b128 v[148:151], v151
	ds_read_b128 v[164:167], v130
	ds_read_b128 v[168:171], v130 offset:1024
	ds_read_b128 v[172:175], v133
	ds_read_b128 v[176:179], v133 offset:1024
	ds_read_b128 v[180:183], v132
	ds_read_b128 v[184:187], v132 offset:1024
	ds_read_b128 v[188:191], v131
	ds_read_b128 v[192:195], v131 offset:1024
	buffer_load_dwordx4 v142, s[4:7], s16 offen lds
	s_mov_b32 m0, s34
	s_nop 0
	buffer_load_dwordx4 v143, s[4:7], s16 offen lds
	s_barrier
	s_waitcnt lgkmcnt(0)
	v_mfma_f32_16x16x32_bf16 v[124:127], v[164:167], v[152:155], v[124:127]
	v_mfma_f32_16x16x32_bf16 v[120:123], v[164:167], v[160:163], v[120:123]
	v_mfma_f32_16x16x32_bf16 v[116:119], v[172:175], v[152:155], v[116:119]
	v_mfma_f32_16x16x32_bf16 v[112:115], v[172:175], v[160:163], v[112:115]
	v_mfma_f32_16x16x32_bf16 v[108:111], v[180:183], v[152:155], v[108:111]
	v_mfma_f32_16x16x32_bf16 v[104:107], v[180:183], v[160:163], v[104:107]
	v_mfma_f32_16x16x32_bf16 v[100:103], v[188:191], v[152:155], v[100:103]
	v_mfma_f32_16x16x32_bf16 v[96:99], v[188:191], v[160:163], v[96:99]
	v_mfma_f32_16x16x32_bf16 v[124:127], v[168:171], v[156:159], v[124:127]
	v_mfma_f32_16x16x32_bf16 v[120:123], v[168:171], v[148:151], v[120:123]
	v_mfma_f32_16x16x32_bf16 v[116:119], v[176:179], v[156:159], v[116:119]
	v_mfma_f32_16x16x32_bf16 v[112:115], v[176:179], v[148:151], v[112:115]
	v_mfma_f32_16x16x32_bf16 v[108:111], v[184:187], v[156:159], v[108:111]
	v_mfma_f32_16x16x32_bf16 v[104:107], v[184:187], v[148:151], v[104:107]
	v_mfma_f32_16x16x32_bf16 v[100:103], v[192:195], v[156:159], v[100:103]
	v_mfma_f32_16x16x32_bf16 v[96:99], v[192:195], v[148:151], v[96:99]
	s_barrier
	ds_read_b128 v[196:199], v144
	ds_read_b128 v[142:145], v145
	ds_read_b128 v[200:203], v146
	ds_read_b128 v[204:207], v147
	s_barrier
	s_waitcnt lgkmcnt(0)
	v_mfma_f32_16x16x32_bf16 v[88:91], v[164:167], v[200:203], v[88:91]
	v_mfma_f32_16x16x32_bf16 v[84:87], v[172:175], v[196:199], v[84:87]
	v_mfma_f32_16x16x32_bf16 v[80:83], v[172:175], v[200:203], v[80:83]
	v_mfma_f32_16x16x32_bf16 v[76:79], v[180:183], v[196:199], v[76:79]
	v_mfma_f32_16x16x32_bf16 v[72:75], v[180:183], v[200:203], v[72:75]
	v_mfma_f32_16x16x32_bf16 v[68:71], v[188:191], v[196:199], v[68:71]
	v_mfma_f32_16x16x32_bf16 v[64:67], v[188:191], v[200:203], v[64:67]
	v_mfma_f32_16x16x32_bf16 v[92:95], v[164:167], v[196:199], v[92:95]
	v_mfma_f32_16x16x32_bf16 v[88:91], v[168:171], v[204:207], v[88:91]
	v_mfma_f32_16x16x32_bf16 v[84:87], v[176:179], v[142:145], v[84:87]
	v_mfma_f32_16x16x32_bf16 v[80:83], v[176:179], v[204:207], v[80:83]
	v_mfma_f32_16x16x32_bf16 v[76:79], v[184:187], v[142:145], v[76:79]
	v_mfma_f32_16x16x32_bf16 v[72:75], v[184:187], v[204:207], v[72:75]
	v_mfma_f32_16x16x32_bf16 v[68:71], v[192:195], v[142:145], v[68:71]
	v_mfma_f32_16x16x32_bf16 v[64:67], v[192:195], v[204:207], v[64:67]
	v_mfma_f32_16x16x32_bf16 v[164:167], v[168:171], v[142:145], v[92:95]
	s_barrier
	s_nop 0
	ds_read_b128 v[92:95], v130 offset:16384
	ds_read_b128 v[168:171], v130 offset:17408
	ds_read_b128 v[172:175], v133 offset:16384
	ds_read_b128 v[176:179], v133 offset:17408
	ds_read_b128 v[180:183], v132 offset:16384
	ds_read_b128 v[184:187], v132 offset:17408
	ds_read_b128 v[188:191], v131 offset:16384
	ds_read_b128 v[192:195], v131 offset:17408
	s_waitcnt vmcnt(4)
	s_barrier
; #define STAGE(P, RS, SOFF, OFF, kt) do { const int _so = (SOFF) + (kt) * (BK * 2); \
;     _Pragma("unroll") for (int _i = 0; _i < 2; ++_i) { \
;       __builtin_amdgcn_raw_ptr_buffer_load_lds(RS, (__attribute__((address_space(3))) void*)((P) + wave * 1024 + _i * 8192), 16, OFF[_i], _so, 0, 0); } } while (0)
; #define LDA(dst, b, h) _Pragma("unroll") for (int m = 0; m < 4; ++m) _Pragma("unroll") for (int k = 0; k < 2; ++k) \
;     dst[m][k] = *reinterpret_cast<const bf16x8*>(SA(b, h) + lds_byte(wr * 64 + m * 16 + fr, k * 32 + fq * 8))
; #define LDB(dst, b, h) _Pragma("unroll") for (int n = 0; n < 2; ++n) _Pragma("unroll") for (int k = 0; k < 2; ++k) \
;     dst[n][k] = *reinterpret_cast<const bf16x8*>(SB(b, h) + lds_byte(wc * 32 + n * 16 + fr, k * 32 + fq * 8))
; #define WAIT_V(n) asm volatile("s_waitcnt vmcnt(" #n ")" ::: "memory")
; #define WAIT_L(n) asm volatile("s_waitcnt lgkmcnt(" #n ")" ::: "memory")
; #define BAR __builtin_amdgcn_s_barrier()
;     ...
;     { LDB(B0, 0, 0); LDA(At, 0, 0); STAGE(SA(1, 1), rsA, sA1, offA, nt - 1);
;       BAR; WAIT_L(0); MMA(0, 0, At, B0); BAR;
;       LDB(B1, 0, 1); BAR; WAIT_L(0); MMA(0, 1, At, B1); BAR;
;       LDA(At, 0, 1); WAIT_V(4); BAR; WAIT_L(0); MMA(1, 0, At, B0); MMA(1, 1, At, B1); BAR; }
;     { LDB(B0, 1, 0); LDA(At, 1, 0); WAIT_V(2); BAR; WAIT_L(0); MMA(0, 0, At, B0); BAR;
	s_waitcnt lgkmcnt(0)
	v_mfma_f32_16x16x32_bf16 v[60:63], v[92:95], v[152:155], v[60:63]
	v_mfma_f32_16x16x32_bf16 v[56:59], v[92:95], v[160:163], v[56:59]
	v_mfma_f32_16x16x32_bf16 v[52:55], v[172:175], v[152:155], v[52:55]
	v_mfma_f32_16x16x32_bf16 v[48:51], v[172:175], v[160:163], v[48:51]
	v_mfma_f32_16x16x32_bf16 v[44:47], v[180:183], v[152:155], v[44:47]
	v_mfma_f32_16x16x32_bf16 v[40:43], v[180:183], v[160:163], v[40:43]
	v_mfma_f32_16x16x32_bf16 v[36:39], v[188:191], v[152:155], v[36:39]
	v_mfma_f32_16x16x32_bf16 v[32:35], v[188:191], v[160:163], v[32:35]
	v_mfma_f32_16x16x32_bf16 v[60:63], v[168:171], v[156:159], v[60:63]
	v_mfma_f32_16x16x32_bf16 v[56:59], v[168:171], v[148:151], v[56:59]
	v_mfma_f32_16x16x32_bf16 v[52:55], v[176:179], v[156:159], v[52:55]
	v_mfma_f32_16x16x32_bf16 v[48:51], v[176:179], v[148:151], v[48:51]
	v_mfma_f32_16x16x32_bf16 v[44:47], v[184:187], v[156:159], v[44:47]
	v_mfma_f32_16x16x32_bf16 v[40:43], v[184:187], v[148:151], v[40:43]
	v_mfma_f32_16x16x32_bf16 v[36:39], v[192:195], v[156:159], v[36:39]
	v_mfma_f32_16x16x32_bf16 v[32:35], v[192:195], v[148:151], v[32:35]
	v_mfma_f32_16x16x32_bf16 v[28:31], v[92:95], v[196:199], v[28:31]
	v_mfma_f32_16x16x32_bf16 v[24:27], v[92:95], v[200:203], v[24:27]
	v_mfma_f32_16x16x32_bf16 v[20:23], v[172:175], v[196:199], v[20:23]
	v_mfma_f32_16x16x32_bf16 v[16:19], v[172:175], v[200:203], v[16:19]
	v_mfma_f32_16x16x32_bf16 v[12:15], v[180:183], v[196:199], v[12:15]
	v_mfma_f32_16x16x32_bf16 v[8:11], v[180:183], v[200:203], v[8:11]
	v_mfma_f32_16x16x32_bf16 v[4:7], v[188:191], v[196:199], v[4:7]
	v_mfma_f32_16x16x32_bf16 v[0:3], v[188:191], v[200:203], v[0:3]
	v_mfma_f32_16x16x32_bf16 v[28:31], v[168:171], v[142:145], v[28:31]
	v_mfma_f32_16x16x32_bf16 v[24:27], v[168:171], v[204:207], v[24:27]
	v_mfma_f32_16x16x32_bf16 v[20:23], v[176:179], v[142:145], v[20:23]
	v_mfma_f32_16x16x32_bf16 v[16:19], v[176:179], v[204:207], v[16:19]
	v_mfma_f32_16x16x32_bf16 v[12:15], v[184:187], v[142:145], v[12:15]
	v_mfma_f32_16x16x32_bf16 v[8:11], v[184:187], v[204:207], v[8:11]
	v_mfma_f32_16x16x32_bf16 v[4:7], v[192:195], v[142:145], v[4:7]
	v_mfma_f32_16x16x32_bf16 v[0:3], v[192:195], v[204:207], v[0:3]
	s_barrier
	ds_read_b128 v[142:145], v138
	ds_read_b128 v[146:149], v139
	ds_read_b128 v[150:153], v140
	ds_read_b128 v[138:141], v141
	ds_read_b128 v[154:157], v130 offset:32768
	ds_read_b128 v[158:161], v130 offset:33792
	ds_read_b128 v[168:171], v133 offset:32768
	ds_read_b128 v[172:175], v133 offset:33792
	ds_read_b128 v[176:179], v132 offset:32768
	ds_read_b128 v[180:183], v132 offset:33792
	ds_read_b128 v[184:187], v131 offset:32768
	ds_read_b128 v[188:191], v131 offset:33792
	s_waitcnt vmcnt(2)
	s_barrier
	s_waitcnt lgkmcnt(0)
	v_mfma_f32_16x16x32_bf16 v[92:95], v[154:157], v[142:145], v[124:127]
	v_mfma_f32_16x16x32_bf16 v[120:123], v[154:157], v[150:153], v[120:123]
	v_mfma_f32_16x16x32_bf16 v[116:119], v[168:171], v[142:145], v[116:119]
	v_mfma_f32_16x16x32_bf16 v[112:115], v[168:171], v[150:153], v[112:115]
	v_mfma_f32_16x16x32_bf16 v[108:111], v[176:179], v[142:145], v[108:111]
	v_mfma_f32_16x16x32_bf16 v[104:107], v[176:179], v[150:153], v[104:107]
	v_mfma_f32_16x16x32_bf16 v[100:103], v[184:187], v[142:145], v[100:103]
	v_mfma_f32_16x16x32_bf16 v[96:99], v[184:187], v[150:153], v[96:99]
	v_mfma_f32_16x16x32_bf16 v[124:127], v[158:161], v[146:149], v[92:95]
	v_mfma_f32_16x16x32_bf16 v[120:123], v[158:161], v[138:141], v[120:123]
	v_mfma_f32_16x16x32_bf16 v[116:119], v[172:175], v[146:149], v[116:119]
	v_mfma_f32_16x16x32_bf16 v[112:115], v[172:175], v[138:141], v[112:115]
	v_mfma_f32_16x16x32_bf16 v[108:111], v[180:183], v[146:149], v[108:111]
	v_mfma_f32_16x16x32_bf16 v[104:107], v[180:183], v[138:141], v[104:107]
	v_mfma_f32_16x16x32_bf16 v[100:103], v[188:191], v[146:149], v[100:103]
	v_mfma_f32_16x16x32_bf16 v[92:95], v[188:191], v[138:141], v[96:99]
	s_barrier
; #define LDA(dst, b, h) _Pragma("unroll") for (int m = 0; m < 4; ++m) _Pragma("unroll") for (int k = 0; k < 2; ++k) \
;     dst[m][k] = *reinterpret_cast<const bf16x8*>(SA(b, h) + lds_byte(wr * 64 + m * 16 + fr, k * 32 + fq * 8))
; #define LDB(dst, b, h) _Pragma("unroll") for (int n = 0; n < 2; ++n) _Pragma("unroll") for (int k = 0; k < 2; ++k) \
;     dst[n][k] = *reinterpret_cast<const bf16x8*>(SB(b, h) + lds_byte(wc * 32 + n * 16 + fr, k * 32 + fq * 8))
; #define WAIT_V(n) asm volatile("s_waitcnt vmcnt(" #n ")" ::: "memory")
; #define WAIT_L(n) asm volatile("s_waitcnt lgkmcnt(" #n ")" ::: "memory")
; #define BAR __builtin_amdgcn_s_barrier()
;     ...
;     { LDB(B0, 1, 0); LDA(At, 1, 0); WAIT_V(2); BAR; WAIT_L(0); MMA(0, 0, At, B0); BAR;
;       LDB(B1, 1, 1); WAIT_V(0); BAR; WAIT_L(0); MMA(0, 1, At, B1); BAR;
;       LDA(At, 1, 1); BAR; WAIT_L(0); MMA(1, 0, At, B0); MMA(1, 1, At, B1); BAR; }
;     if (wr == 0) BAR;
	ds_read_b128 v[192:195], v134
	ds_read_b128 v[196:199], v135
	ds_read_b128 v[200:203], v136
	ds_read_b128 v[134:137], v137
	s_waitcnt vmcnt(0)
	s_barrier
	s_waitcnt lgkmcnt(0)
	v_mfma_f32_16x16x32_bf16 v[96:99], v[154:157], v[192:195], v[164:167]
	v_mfma_f32_16x16x32_bf16 v[88:91], v[154:157], v[200:203], v[88:91]
	v_mfma_f32_16x16x32_bf16 v[84:87], v[168:171], v[192:195], v[84:87]
	v_mfma_f32_16x16x32_bf16 v[80:83], v[168:171], v[200:203], v[80:83]
	v_mfma_f32_16x16x32_bf16 v[76:79], v[176:179], v[192:195], v[76:79]
	v_mfma_f32_16x16x32_bf16 v[72:75], v[176:179], v[200:203], v[72:75]
	v_mfma_f32_16x16x32_bf16 v[68:71], v[184:187], v[192:195], v[68:71]
	v_mfma_f32_16x16x32_bf16 v[64:67], v[184:187], v[200:203], v[64:67]
	v_mfma_f32_16x16x32_bf16 v[96:99], v[158:161], v[196:199], v[96:99]
	v_mfma_f32_16x16x32_bf16 v[88:91], v[158:161], v[134:137], v[88:91]
	v_mfma_f32_16x16x32_bf16 v[84:87], v[172:175], v[196:199], v[84:87]
	v_mfma_f32_16x16x32_bf16 v[80:83], v[172:175], v[134:137], v[80:83]
	v_mfma_f32_16x16x32_bf16 v[76:79], v[180:183], v[196:199], v[76:79]
	v_mfma_f32_16x16x32_bf16 v[72:75], v[180:183], v[134:137], v[72:75]
	v_mfma_f32_16x16x32_bf16 v[68:71], v[188:191], v[196:199], v[68:71]
	v_mfma_f32_16x16x32_bf16 v[64:67], v[188:191], v[134:137], v[64:67]
	s_barrier
	ds_read_b128 v[154:157], v130 offset:49152
	ds_read_b128 v[158:161], v130 offset:50176
	ds_read_b128 v[162:165], v133 offset:49152
	ds_read_b128 v[166:169], v133 offset:50176
	ds_read_b128 v[170:173], v132 offset:49152
	ds_read_b128 v[174:177], v132 offset:50176
	ds_read_b128 v[178:181], v131 offset:49152
	ds_read_b128 v[130:133], v131 offset:50176
	s_barrier
	s_waitcnt lgkmcnt(0)
	v_mfma_f32_16x16x32_bf16 v[60:63], v[154:157], v[142:145], v[60:63]
	v_mfma_f32_16x16x32_bf16 v[56:59], v[154:157], v[150:153], v[56:59]
	v_mfma_f32_16x16x32_bf16 v[52:55], v[162:165], v[142:145], v[52:55]
	v_mfma_f32_16x16x32_bf16 v[48:51], v[162:165], v[150:153], v[48:51]
	v_mfma_f32_16x16x32_bf16 v[44:47], v[170:173], v[142:145], v[44:47]
	v_mfma_f32_16x16x32_bf16 v[40:43], v[170:173], v[150:153], v[40:43]
	v_mfma_f32_16x16x32_bf16 v[36:39], v[178:181], v[142:145], v[36:39]
	v_mfma_f32_16x16x32_bf16 v[32:35], v[178:181], v[150:153], v[32:35]
	v_mfma_f32_16x16x32_bf16 v[60:63], v[158:161], v[146:149], v[60:63]
	v_mfma_f32_16x16x32_bf16 v[56:59], v[158:161], v[138:141], v[56:59]
	v_mfma_f32_16x16x32_bf16 v[52:55], v[166:169], v[146:149], v[52:55]
	v_mfma_f32_16x16x32_bf16 v[48:51], v[166:169], v[138:141], v[48:51]
	v_mfma_f32_16x16x32_bf16 v[44:47], v[174:177], v[146:149], v[44:47]
	v_mfma_f32_16x16x32_bf16 v[40:43], v[174:177], v[138:141], v[40:43]
	v_mfma_f32_16x16x32_bf16 v[36:39], v[130:133], v[146:149], v[36:39]
	v_mfma_f32_16x16x32_bf16 v[32:35], v[130:133], v[138:141], v[32:35]
	v_mfma_f32_16x16x32_bf16 v[28:31], v[154:157], v[192:195], v[28:31]
	v_mfma_f32_16x16x32_bf16 v[24:27], v[154:157], v[200:203], v[24:27]
	v_mfma_f32_16x16x32_bf16 v[20:23], v[162:165], v[192:195], v[20:23]
	v_mfma_f32_16x16x32_bf16 v[16:19], v[162:165], v[200:203], v[16:19]
	v_mfma_f32_16x16x32_bf16 v[12:15], v[170:173], v[192:195], v[12:15]
	v_mfma_f32_16x16x32_bf16 v[8:11], v[170:173], v[200:203], v[8:11]
	v_mfma_f32_16x16x32_bf16 v[4:7], v[178:181], v[192:195], v[4:7]
	v_mfma_f32_16x16x32_bf16 v[0:3], v[178:181], v[200:203], v[0:3]
	v_mfma_f32_16x16x32_bf16 v[28:31], v[158:161], v[196:199], v[28:31]
	v_mfma_f32_16x16x32_bf16 v[24:27], v[158:161], v[134:137], v[24:27]
	v_mfma_f32_16x16x32_bf16 v[20:23], v[166:169], v[196:199], v[20:23]
	v_mfma_f32_16x16x32_bf16 v[16:19], v[166:169], v[134:137], v[16:19]
	v_mfma_f32_16x16x32_bf16 v[12:15], v[174:177], v[196:199], v[12:15]
	v_mfma_f32_16x16x32_bf16 v[8:11], v[174:177], v[134:137], v[8:11]
	v_mfma_f32_16x16x32_bf16 v[4:7], v[130:133], v[196:199], v[4:7]
	v_mfma_f32_16x16x32_bf16 v[0:3], v[130:133], v[134:137], v[0:3]
	v_cmp_gt_u32_e32 vcc, s37, v129
	s_barrier
	s_and_saveexec_b64 s[16:17], vcc
	s_cbranch_execz .LBB0_228
	s_barrier

; #define STAGE(P, RS, SOFF, OFF, kt) do { const int _so = (SOFF) + (kt) * (BK * 2); \
;     _Pragma("unroll") for (int _i = 0; _i < 2; ++_i) { \
;       __builtin_amdgcn_raw_ptr_buffer_load_lds(RS, (__attribute__((address_space(3))) void*)((P) + wave * 1024 + _i * 8192), 16, OFF[_i], _so, 0, 0); } } while (0)
; #define LDA(dst, b, h) _Pragma("unroll") for (int m = 0; m < 4; ++m) _Pragma("unroll") for (int k = 0; k < 2; ++k) \
;     dst[m][k] = *reinterpret_cast<const bf16x8*>(SA(b, h) + lds_byte(wr * 64 + m * 16 + fr, k * 32 + fq * 8))
; #define LDB(dst, b, h) _Pragma("unroll") for (int n = 0; n < 2; ++n) _Pragma("unroll") for (int k = 0; k < 2; ++k) \
;     dst[n][k] = *reinterpret_cast<const bf16x8*>(SB(b, h) + lds_byte(wc * 32 + n * 16 + fr, k * 32 + fq * 8))
; #define WAIT_V(n) asm volatile("s_waitcnt vmcnt(" #n ")" ::: "memory")
; #define WAIT_L(n) asm volatile("s_waitcnt lgkmcnt(" #n ")" ::: "memory")
; #define BAR __builtin_amdgcn_s_barrier()
; #define SCHED __builtin_amdgcn_sched_barrier(0)
;     ...
;     for (int t = 0; t < nt - 2; t += 2) {
;       LDB(B0, 0, 0); SCHED; LDA(At, 0, 0); STAGE(SA(1, 1), rsA, sA1, offA, t + 1);
;       WAIT_L(8); BAR; WAIT_L(0); MMA(0, 0, At, B0); BAR; SCHED;
;       LDB(B1, 0, 1); STAGE(SB(0, 0), rsB, sB0, offB, t + 2);
;       BAR; WAIT_L(0); MMA(0, 1, At, B1); BAR;
;       LDA(At, 0, 1); STAGE(SA(0, 0), rsA, sA0, offA, t + 2);
;       BAR; WAIT_L(0); MMA(1, 0, At, B0); BAR; SCHED;
;       STAGE(SB(0, 1), rsB, sB1, offB, t + 2);
;       WAIT_V(6); BAR; MMA(1, 1, At, B1); BAR;
.LBB0_291:
	ds_read_b128 v[152:155], v147
	ds_read_b128 v[156:159], v148
	ds_read_b128 v[160:163], v149
	ds_read_b128 v[164:167], v150
	s_add_i32 s5, s94, s3
	s_add_i32 s6, s5, 0x80
	s_mov_b32 m0, s36
	ds_read_b128 v[168:171], v129
	ds_read_b128 v[172:175], v129 offset:1024
	ds_read_b128 v[176:179], v132
	ds_read_b128 v[180:183], v132 offset:1024
	ds_read_b128 v[184:187], v131
	ds_read_b128 v[188:191], v131 offset:1024
	ds_read_b128 v[192:195], v130
	ds_read_b128 v[196:199], v130 offset:1024
	buffer_load_dwordx4 v141, s[8:11], s6 offen lds
	s_mov_b32 m0, s61
	s_nop 0
	buffer_load_dwordx4 v142, s[8:11], s6 offen lds
	s_waitcnt lgkmcnt(8)
	s_barrier
	s_waitcnt lgkmcnt(0)
	v_mfma_f32_16x16x32_bf16 v[124:127], v[152:155], v[168:171], v[124:127]
	v_mfma_f32_16x16x32_bf16 v[120:123], v[160:163], v[168:171], v[120:123]
	v_mfma_f32_16x16x32_bf16 v[116:119], v[152:155], v[176:179], v[116:119]
	v_mfma_f32_16x16x32_bf16 v[112:115], v[160:163], v[176:179], v[112:115]
	v_mfma_f32_16x16x32_bf16 v[108:111], v[152:155], v[184:187], v[108:111]
	v_mfma_f32_16x16x32_bf16 v[104:107], v[160:163], v[184:187], v[104:107]
	v_mfma_f32_16x16x32_bf16 v[100:103], v[152:155], v[192:195], v[100:103]
	v_mfma_f32_16x16x32_bf16 v[96:99], v[160:163], v[192:195], v[96:99]
	v_mfma_f32_16x16x32_bf16 v[124:127], v[156:159], v[172:175], v[124:127]
	v_mfma_f32_16x16x32_bf16 v[120:123], v[164:167], v[172:175], v[120:123]
	v_mfma_f32_16x16x32_bf16 v[116:119], v[156:159], v[180:183], v[116:119]
	v_mfma_f32_16x16x32_bf16 v[112:115], v[164:167], v[180:183], v[112:115]
	v_mfma_f32_16x16x32_bf16 v[108:111], v[156:159], v[188:191], v[108:111]
	v_mfma_f32_16x16x32_bf16 v[104:107], v[164:167], v[188:191], v[104:107]
	v_mfma_f32_16x16x32_bf16 v[100:103], v[156:159], v[196:199], v[100:103]
	v_mfma_f32_16x16x32_bf16 v[96:99], v[164:167], v[196:199], v[96:99]
	s_barrier
	s_add_i32 s6, s96, s3
	s_add_i32 s7, s6, 0x100
	s_mov_b32 s14, s10
	s_mov_b32 s15, s11
	s_mov_b32 m0, s37
	ds_read_b128 v[200:203], v143
	ds_read_b128 v[204:207], v144
	ds_read_b128 v[208:211], v145
	ds_read_b128 v[212:215], v146
	buffer_load_dwordx4 v141, s[12:15], s7 offen lds
	s_mov_b32 m0, s48
	s_nop 0
	buffer_load_dwordx4 v142, s[12:15], s7 offen lds
	s_barrier
	s_waitcnt lgkmcnt(0)
	v_mfma_f32_16x16x32_bf16 v[92:95], v[200:203], v[168:171], v[92:95]
	v_mfma_f32_16x16x32_bf16 v[88:91], v[208:211], v[168:171], v[88:91]
	v_mfma_f32_16x16x32_bf16 v[80:83], v[200:203], v[176:179], v[80:83]
	v_mfma_f32_16x16x32_bf16 v[68:71], v[208:211], v[176:179], v[68:71]
	v_mfma_f32_16x16x32_bf16 v[60:63], v[200:203], v[184:187], v[60:63]
	v_mfma_f32_16x16x32_bf16 v[56:59], v[208:211], v[184:187], v[56:59]
	v_mfma_f32_16x16x32_bf16 v[52:55], v[200:203], v[192:195], v[52:55]
	v_mfma_f32_16x16x32_bf16 v[48:51], v[208:211], v[192:195], v[48:51]
	v_mfma_f32_16x16x32_bf16 v[92:95], v[204:207], v[172:175], v[92:95]
	v_mfma_f32_16x16x32_bf16 v[88:91], v[212:215], v[172:175], v[88:91]
	v_mfma_f32_16x16x32_bf16 v[80:83], v[204:207], v[180:183], v[80:83]
	v_mfma_f32_16x16x32_bf16 v[68:71], v[212:215], v[180:183], v[68:71]
	v_mfma_f32_16x16x32_bf16 v[60:63], v[204:207], v[188:191], v[60:63]
	v_mfma_f32_16x16x32_bf16 v[56:59], v[212:215], v[188:191], v[56:59]
	v_mfma_f32_16x16x32_bf16 v[52:55], v[204:207], v[196:199], v[52:55]
	v_mfma_f32_16x16x32_bf16 v[48:51], v[212:215], v[196:199], v[48:51]
	s_add_i32 s7, s95, s3
	s_add_i32 s22, s7, 0x100
	s_mov_b32 m0, s35
	s_barrier
	ds_read_b128 v[168:171], v129 offset:16384
	ds_read_b128 v[172:175], v129 offset:17408
	ds_read_b128 v[176:179], v132 offset:16384
	ds_read_b128 v[180:183], v132 offset:17408
	ds_read_b128 v[184:187], v131 offset:16384
	ds_read_b128 v[188:191], v131 offset:17408
	ds_read_b128 v[192:195], v130 offset:16384
	ds_read_b128 v[196:199], v130 offset:17408
	buffer_load_dwordx4 v141, s[8:11], s22 offen lds
	s_mov_b32 m0, s49
	s_nop 0
	buffer_load_dwordx4 v142, s[8:11], s22 offen lds
	s_barrier
	s_waitcnt lgkmcnt(0)
	v_mfma_f32_16x16x32_bf16 v[44:47], v[152:155], v[168:171], v[44:47]
	v_mfma_f32_16x16x32_bf16 v[40:43], v[160:163], v[168:171], v[40:43]
	v_mfma_f32_16x16x32_bf16 v[36:39], v[152:155], v[176:179], v[36:39]
	v_mfma_f32_16x16x32_bf16 v[32:35], v[160:163], v[176:179], v[32:35]
	v_mfma_f32_16x16x32_bf16 v[28:31], v[152:155], v[184:187], v[28:31]
	v_mfma_f32_16x16x32_bf16 v[24:27], v[160:163], v[184:187], v[24:27]
	v_mfma_f32_16x16x32_bf16 v[20:23], v[152:155], v[192:195], v[20:23]
	v_mfma_f32_16x16x32_bf16 v[16:19], v[160:163], v[192:195], v[16:19]
	v_mfma_f32_16x16x32_bf16 v[44:47], v[156:159], v[172:175], v[44:47]
	v_mfma_f32_16x16x32_bf16 v[40:43], v[164:167], v[172:175], v[40:43]
	v_mfma_f32_16x16x32_bf16 v[36:39], v[156:159], v[180:183], v[36:39]
	v_mfma_f32_16x16x32_bf16 v[32:35], v[164:167], v[180:183], v[32:35]
	v_mfma_f32_16x16x32_bf16 v[28:31], v[156:159], v[188:191], v[28:31]
	v_mfma_f32_16x16x32_bf16 v[24:27], v[164:167], v[188:191], v[24:27]
	v_mfma_f32_16x16x32_bf16 v[20:23], v[156:159], v[196:199], v[20:23]
	v_mfma_f32_16x16x32_bf16 v[16:19], v[164:167], v[196:199], v[16:19]
	s_barrier
	s_add_i32 s22, s97, s3
	s_add_i32 s23, s22, 0x100
	s_mov_b32 m0, s38
	s_nop 0
	buffer_load_dwordx4 v141, s[12:15], s23 offen lds
	s_mov_b32 m0, s54
	s_nop 0
	buffer_load_dwordx4 v142, s[12:15], s23 offen lds
	s_waitcnt vmcnt(6)
	s_barrier
; #define STAGE(P, RS, SOFF, OFF, kt) do { const int _so = (SOFF) + (kt) * (BK * 2); \
;     _Pragma("unroll") for (int _i = 0; _i < 2; ++_i) { \
;       __builtin_amdgcn_raw_ptr_buffer_load_lds(RS, (__attribute__((address_space(3))) void*)((P) + wave * 1024 + _i * 8192), 16, OFF[_i], _so, 0, 0); } } while (0)
; #define LDA(dst, b, h) _Pragma("unroll") for (int m = 0; m < 4; ++m) _Pragma("unroll") for (int k = 0; k < 2; ++k) \
;     dst[m][k] = *reinterpret_cast<const bf16x8*>(SA(b, h) + lds_byte(wr * 64 + m * 16 + fr, k * 32 + fq * 8))
; #define LDB(dst, b, h) _Pragma("unroll") for (int n = 0; n < 2; ++n) _Pragma("unroll") for (int k = 0; k < 2; ++k) \
;     dst[n][k] = *reinterpret_cast<const bf16x8*>(SB(b, h) + lds_byte(wc * 32 + n * 16 + fr, k * 32 + fq * 8))
; #define WAIT_V(n) asm volatile("s_waitcnt vmcnt(" #n ")" ::: "memory")
; #define WAIT_L(n) asm volatile("s_waitcnt lgkmcnt(" #n ")" ::: "memory")
; #define BAR __builtin_amdgcn_s_barrier()
; #define SCHED __builtin_amdgcn_sched_barrier(0)
;     ...
;       WAIT_V(6); BAR; MMA(1, 1, At, B1); BAR;
;       LDB(B0, 1, 0); SCHED; LDA(At, 1, 0); STAGE(SA(0, 1), rsA, sA1, offA, t + 2);
;       WAIT_L(8); BAR; WAIT_L(0); MMA(0, 0, At, B0); BAR; SCHED;
;       LDB(B1, 1, 1); STAGE(SB(1, 0), rsB, sB0, offB, t + 3);
;       BAR; WAIT_L(0); MMA(0, 1, At, B1); BAR;
;       LDA(At, 1, 1); STAGE(SA(1, 0), rsA, sA0, offA, t + 3);
;       BAR; WAIT_L(0); MMA(1, 0, At, B0); BAR; SCHED;
;       STAGE(SB(1, 1), rsB, sB1, offB, t + 3);
;       WAIT_V(6); BAR; MMA(1, 1, At, B1); BAR;
	v_mfma_f32_16x16x32_bf16 v[12:15], v[200:203], v[168:171], v[12:15]
	v_mfma_f32_16x16x32_bf16 v[8:11], v[208:211], v[168:171], v[8:11]
	v_mfma_f32_16x16x32_bf16 v[4:7], v[200:203], v[176:179], v[4:7]
	v_mfma_f32_16x16x32_bf16 v[0:3], v[208:211], v[176:179], v[0:3]
	v_mfma_f32_16x16x32_bf16 v[64:67], v[200:203], v[184:187], v[64:67]
	v_mfma_f32_16x16x32_bf16 v[72:75], v[208:211], v[184:187], v[72:75]
	v_mfma_f32_16x16x32_bf16 v[76:79], v[200:203], v[192:195], v[76:79]
	v_mfma_f32_16x16x32_bf16 v[84:87], v[208:211], v[192:195], v[84:87]
	v_mfma_f32_16x16x32_bf16 v[12:15], v[204:207], v[172:175], v[12:15]
	v_mfma_f32_16x16x32_bf16 v[8:11], v[212:215], v[172:175], v[8:11]
	v_mfma_f32_16x16x32_bf16 v[4:7], v[204:207], v[180:183], v[4:7]
	v_mfma_f32_16x16x32_bf16 v[0:3], v[212:215], v[180:183], v[0:3]
	v_mfma_f32_16x16x32_bf16 v[64:67], v[204:207], v[188:191], v[64:67]
	v_mfma_f32_16x16x32_bf16 v[72:75], v[212:215], v[188:191], v[72:75]
	v_mfma_f32_16x16x32_bf16 v[76:79], v[204:207], v[196:199], v[76:79]
	v_mfma_f32_16x16x32_bf16 v[84:87], v[212:215], v[196:199], v[84:87]
	s_barrier
	ds_read_b128 v[152:155], v137
	ds_read_b128 v[156:159], v138
	ds_read_b128 v[160:163], v139
	ds_read_b128 v[164:167], v140
	s_addk_i32 s5, 0x100
	s_mov_b32 m0, s39
	ds_read_b128 v[168:171], v129 offset:32768
	ds_read_b128 v[172:175], v129 offset:33792
	ds_read_b128 v[176:179], v132 offset:32768
	ds_read_b128 v[180:183], v132 offset:33792
	ds_read_b128 v[184:187], v131 offset:32768
	ds_read_b128 v[188:191], v131 offset:33792
	ds_read_b128 v[192:195], v130 offset:32768
	ds_read_b128 v[196:199], v130 offset:33792
	buffer_load_dwordx4 v141, s[8:11], s5 offen lds
	s_mov_b32 m0, s55
	s_nop 0
	buffer_load_dwordx4 v142, s[8:11], s5 offen lds
	s_waitcnt lgkmcnt(8)
	s_barrier
	s_waitcnt lgkmcnt(0)
	v_mfma_f32_16x16x32_bf16 v[124:127], v[152:155], v[168:171], v[124:127]
	v_mfma_f32_16x16x32_bf16 v[120:123], v[160:163], v[168:171], v[120:123]
	v_mfma_f32_16x16x32_bf16 v[116:119], v[152:155], v[176:179], v[116:119]
	v_mfma_f32_16x16x32_bf16 v[112:115], v[160:163], v[176:179], v[112:115]
	v_mfma_f32_16x16x32_bf16 v[108:111], v[152:155], v[184:187], v[108:111]
	v_mfma_f32_16x16x32_bf16 v[104:107], v[160:163], v[184:187], v[104:107]
	v_mfma_f32_16x16x32_bf16 v[100:103], v[152:155], v[192:195], v[100:103]
	v_mfma_f32_16x16x32_bf16 v[96:99], v[160:163], v[192:195], v[96:99]
	v_mfma_f32_16x16x32_bf16 v[124:127], v[156:159], v[172:175], v[124:127]
	v_mfma_f32_16x16x32_bf16 v[120:123], v[164:167], v[172:175], v[120:123]
	v_mfma_f32_16x16x32_bf16 v[116:119], v[156:159], v[180:183], v[116:119]
	v_mfma_f32_16x16x32_bf16 v[112:115], v[164:167], v[180:183], v[112:115]
	v_mfma_f32_16x16x32_bf16 v[108:111], v[156:159], v[188:191], v[108:111]
	v_mfma_f32_16x16x32_bf16 v[104:107], v[164:167], v[188:191], v[104:107]
	v_mfma_f32_16x16x32_bf16 v[100:103], v[156:159], v[196:199], v[100:103]
	v_mfma_f32_16x16x32_bf16 v[96:99], v[164:167], v[196:199], v[96:99]
	s_barrier
	s_addk_i32 s6, 0x180
	s_mov_b32 m0, s42
	ds_read_b128 v[200:203], v133
	ds_read_b128 v[204:207], v134
	ds_read_b128 v[208:211], v135
	ds_read_b128 v[212:215], v136
	buffer_load_dwordx4 v141, s[12:15], s6 offen lds
	s_mov_b32 m0, s58
	s_nop 0
	buffer_load_dwordx4 v142, s[12:15], s6 offen lds
	s_barrier
	s_waitcnt lgkmcnt(0)
	v_mfma_f32_16x16x32_bf16 v[92:95], v[200:203], v[168:171], v[92:95]
	v_mfma_f32_16x16x32_bf16 v[88:91], v[208:211], v[168:171], v[88:91]
	v_mfma_f32_16x16x32_bf16 v[80:83], v[200:203], v[176:179], v[80:83]
	v_mfma_f32_16x16x32_bf16 v[68:71], v[208:211], v[176:179], v[68:71]
	v_mfma_f32_16x16x32_bf16 v[60:63], v[200:203], v[184:187], v[60:63]
	v_mfma_f32_16x16x32_bf16 v[56:59], v[208:211], v[184:187], v[56:59]
	v_mfma_f32_16x16x32_bf16 v[52:55], v[200:203], v[192:195], v[52:55]
	v_mfma_f32_16x16x32_bf16 v[48:51], v[208:211], v[192:195], v[48:51]
	v_mfma_f32_16x16x32_bf16 v[92:95], v[204:207], v[172:175], v[92:95]
	v_mfma_f32_16x16x32_bf16 v[88:91], v[212:215], v[172:175], v[88:91]
	v_mfma_f32_16x16x32_bf16 v[80:83], v[204:207], v[180:183], v[80:83]
	v_mfma_f32_16x16x32_bf16 v[68:71], v[212:215], v[180:183], v[68:71]
	v_mfma_f32_16x16x32_bf16 v[60:63], v[204:207], v[188:191], v[60:63]
	v_mfma_f32_16x16x32_bf16 v[56:59], v[212:215], v[188:191], v[56:59]
	v_mfma_f32_16x16x32_bf16 v[52:55], v[204:207], v[196:199], v[52:55]
	v_mfma_f32_16x16x32_bf16 v[48:51], v[212:215], v[196:199], v[48:51]
	s_addk_i32 s7, 0x180
	s_mov_b32 m0, s43
	s_barrier
	ds_read_b128 v[168:171], v129 offset:49152
	ds_read_b128 v[172:175], v129 offset:50176
	ds_read_b128 v[176:179], v132 offset:49152
	ds_read_b128 v[180:183], v132 offset:50176
	ds_read_b128 v[184:187], v131 offset:49152
	ds_read_b128 v[188:191], v131 offset:50176
	ds_read_b128 v[192:195], v130 offset:49152
	ds_read_b128 v[196:199], v130 offset:50176
	buffer_load_dwordx4 v141, s[8:11], s7 offen lds
	s_mov_b32 m0, s59
	s_nop 0
	buffer_load_dwordx4 v142, s[8:11], s7 offen lds
	s_barrier
	s_waitcnt lgkmcnt(0)
	v_mfma_f32_16x16x32_bf16 v[44:47], v[152:155], v[168:171], v[44:47]
	v_mfma_f32_16x16x32_bf16 v[40:43], v[160:163], v[168:171], v[40:43]
	v_mfma_f32_16x16x32_bf16 v[36:39], v[152:155], v[176:179], v[36:39]
	v_mfma_f32_16x16x32_bf16 v[32:35], v[160:163], v[176:179], v[32:35]
	v_mfma_f32_16x16x32_bf16 v[28:31], v[152:155], v[184:187], v[28:31]
	v_mfma_f32_16x16x32_bf16 v[24:27], v[160:163], v[184:187], v[24:27]
	v_mfma_f32_16x16x32_bf16 v[20:23], v[152:155], v[192:195], v[20:23]
	v_mfma_f32_16x16x32_bf16 v[16:19], v[160:163], v[192:195], v[16:19]
	v_mfma_f32_16x16x32_bf16 v[44:47], v[156:159], v[172:175], v[44:47]
	v_mfma_f32_16x16x32_bf16 v[40:43], v[164:167], v[172:175], v[40:43]
	v_mfma_f32_16x16x32_bf16 v[36:39], v[156:159], v[180:183], v[36:39]
	v_mfma_f32_16x16x32_bf16 v[32:35], v[164:167], v[180:183], v[32:35]
	v_mfma_f32_16x16x32_bf16 v[28:31], v[156:159], v[188:191], v[28:31]
	v_mfma_f32_16x16x32_bf16 v[24:27], v[164:167], v[188:191], v[24:27]
	v_mfma_f32_16x16x32_bf16 v[20:23], v[156:159], v[196:199], v[20:23]
	v_mfma_f32_16x16x32_bf16 v[16:19], v[164:167], v[196:199], v[16:19]
	s_barrier
; #define STAGE(P, RS, SOFF, OFF, kt) do { const int _so = (SOFF) + (kt) * (BK * 2); \
;     _Pragma("unroll") for (int _i = 0; _i < 2; ++_i) { \
;       __builtin_amdgcn_raw_ptr_buffer_load_lds(RS, (__attribute__((address_space(3))) void*)((P) + wave * 1024 + _i * 8192), 16, OFF[_i], _so, 0, 0); } } while (0)
; #define LDA(dst, b, h) _Pragma("unroll") for (int m = 0; m < 4; ++m) _Pragma("unroll") for (int k = 0; k < 2; ++k) \
;     dst[m][k] = *reinterpret_cast<const bf16x8*>(SA(b, h) + lds_byte(wr * 64 + m * 16 + fr, k * 32 + fq * 8))
; #define LDB(dst, b, h) _Pragma("unroll") for (int n = 0; n < 2; ++n) _Pragma("unroll") for (int k = 0; k < 2; ++k) \
;     dst[n][k] = *reinterpret_cast<const bf16x8*>(SB(b, h) + lds_byte(wc * 32 + n * 16 + fr, k * 32 + fq * 8))
; #define WAIT_V(n) asm volatile("s_waitcnt vmcnt(" #n ")" ::: "memory")
; #define WAIT_L(n) asm volatile("s_waitcnt lgkmcnt(" #n ")" ::: "memory")
; #define BAR __builtin_amdgcn_s_barrier()
;     ...
;       STAGE(SB(1, 1), rsB, sB1, offB, t + 3);
;       WAIT_V(6); BAR; MMA(1, 1, At, B1); BAR;
;     }
;     { LDB(B0, 0, 0); LDA(At, 0, 0); STAGE(SA(1, 1), rsA, sA1, offA, nt - 1);
;       BAR; WAIT_L(0); MMA(0, 0, At, B0); BAR;
;       LDB(B1, 0, 1); BAR; WAIT_L(0); MMA(0, 1, At, B1); BAR;
;       LDA(At, 0, 1); WAIT_V(4); BAR; WAIT_L(0); MMA(1, 0, At, B0); MMA(1, 1, At, B1); BAR; }
	s_addk_i32 s22, 0x180
	s_mov_b32 m0, s44
	s_nop 0
	buffer_load_dwordx4 v141, s[12:15], s22 offen lds
	s_mov_b32 m0, s60
	s_nop 0
	buffer_load_dwordx4 v142, s[12:15], s22 offen lds
	s_waitcnt vmcnt(6)
	s_barrier
	v_mfma_f32_16x16x32_bf16 v[12:15], v[200:203], v[168:171], v[12:15]
	v_mfma_f32_16x16x32_bf16 v[8:11], v[208:211], v[168:171], v[8:11]
	v_mfma_f32_16x16x32_bf16 v[4:7], v[200:203], v[176:179], v[4:7]
	v_mfma_f32_16x16x32_bf16 v[0:3], v[208:211], v[176:179], v[0:3]
	v_mfma_f32_16x16x32_bf16 v[64:67], v[200:203], v[184:187], v[64:67]
	v_mfma_f32_16x16x32_bf16 v[72:75], v[208:211], v[184:187], v[72:75]
	v_mfma_f32_16x16x32_bf16 v[76:79], v[200:203], v[192:195], v[76:79]
	v_mfma_f32_16x16x32_bf16 v[84:87], v[208:211], v[192:195], v[84:87]
	v_mfma_f32_16x16x32_bf16 v[12:15], v[204:207], v[172:175], v[12:15]
	v_mfma_f32_16x16x32_bf16 v[8:11], v[212:215], v[172:175], v[8:11]
	v_mfma_f32_16x16x32_bf16 v[4:7], v[204:207], v[180:183], v[4:7]
	v_mfma_f32_16x16x32_bf16 v[0:3], v[212:215], v[180:183], v[0:3]
	v_mfma_f32_16x16x32_bf16 v[64:67], v[204:207], v[188:191], v[64:67]
	v_mfma_f32_16x16x32_bf16 v[72:75], v[212:215], v[188:191], v[72:75]
	v_mfma_f32_16x16x32_bf16 v[76:79], v[204:207], v[196:199], v[76:79]
	v_mfma_f32_16x16x32_bf16 v[84:87], v[212:215], v[196:199], v[84:87]
	s_add_i32 s1, s1, 2
	s_addk_i32 s3, 0x100
	s_cmp_gt_u32 s1, 11
	s_barrier
	s_cbranch_scc0 .LBB0_291
	s_add_i32 s1, s94, 0x780
	s_mov_b32 m0, s36
	ds_read_b128 v[152:155], v147
	ds_read_b128 v[156:159], v148
	ds_read_b128 v[160:163], v149
	ds_read_b128 v[148:151], v150
	ds_read_b128 v[164:167], v129
	ds_read_b128 v[168:171], v129 offset:1024
	ds_read_b128 v[172:175], v132
	ds_read_b128 v[176:179], v132 offset:1024
	ds_read_b128 v[180:183], v131
	ds_read_b128 v[184:187], v131 offset:1024
	ds_read_b128 v[188:191], v130
	ds_read_b128 v[192:195], v130 offset:1024
	buffer_load_dwordx4 v141, s[8:11], s1 offen lds
	s_mov_b32 m0, s61
	s_nop 0
	buffer_load_dwordx4 v142, s[8:11], s1 offen lds
	s_barrier
	s_waitcnt lgkmcnt(0)
	v_mfma_f32_16x16x32_bf16 v[124:127], v[152:155], v[164:167], v[124:127]
	v_mfma_f32_16x16x32_bf16 v[120:123], v[160:163], v[164:167], v[120:123]
	v_mfma_f32_16x16x32_bf16 v[116:119], v[152:155], v[172:175], v[116:119]
	v_mfma_f32_16x16x32_bf16 v[112:115], v[160:163], v[172:175], v[112:115]
	v_mfma_f32_16x16x32_bf16 v[108:111], v[152:155], v[180:183], v[108:111]
	v_mfma_f32_16x16x32_bf16 v[104:107], v[160:163], v[180:183], v[104:107]
	v_mfma_f32_16x16x32_bf16 v[100:103], v[152:155], v[188:191], v[100:103]
	v_mfma_f32_16x16x32_bf16 v[96:99], v[160:163], v[188:191], v[96:99]
	v_mfma_f32_16x16x32_bf16 v[124:127], v[156:159], v[168:171], v[124:127]
	v_mfma_f32_16x16x32_bf16 v[120:123], v[148:151], v[168:171], v[120:123]
	v_mfma_f32_16x16x32_bf16 v[116:119], v[156:159], v[176:179], v[116:119]
	v_mfma_f32_16x16x32_bf16 v[112:115], v[148:151], v[176:179], v[112:115]
	v_mfma_f32_16x16x32_bf16 v[108:111], v[156:159], v[184:187], v[108:111]
	v_mfma_f32_16x16x32_bf16 v[104:107], v[148:151], v[184:187], v[104:107]
	v_mfma_f32_16x16x32_bf16 v[100:103], v[156:159], v[192:195], v[100:103]
	v_mfma_f32_16x16x32_bf16 v[96:99], v[148:151], v[192:195], v[96:99]
	s_barrier
	ds_read_b128 v[196:199], v143
	ds_read_b128 v[200:203], v144
	ds_read_b128 v[142:145], v145
	ds_read_b128 v[204:207], v146
	s_barrier
	s_waitcnt lgkmcnt(0)
	v_mfma_f32_16x16x32_bf16 v[88:91], v[142:145], v[164:167], v[88:91]
	v_mfma_f32_16x16x32_bf16 v[80:83], v[196:199], v[172:175], v[80:83]
	v_mfma_f32_16x16x32_bf16 v[60:63], v[196:199], v[180:183], v[60:63]
	v_mfma_f32_16x16x32_bf16 v[56:59], v[142:145], v[180:183], v[56:59]
	v_mfma_f32_16x16x32_bf16 v[52:55], v[196:199], v[188:191], v[52:55]
	v_mfma_f32_16x16x32_bf16 v[48:51], v[142:145], v[188:191], v[48:51]
	v_mfma_f32_16x16x32_bf16 v[92:95], v[196:199], v[164:167], v[92:95]
	v_mfma_f32_16x16x32_bf16 v[68:71], v[142:145], v[172:175], v[68:71]
	v_mfma_f32_16x16x32_bf16 v[88:91], v[204:207], v[168:171], v[88:91]
	v_mfma_f32_16x16x32_bf16 v[80:83], v[200:203], v[176:179], v[80:83]
	v_mfma_f32_16x16x32_bf16 v[60:63], v[200:203], v[184:187], v[60:63]
	v_mfma_f32_16x16x32_bf16 v[56:59], v[204:207], v[184:187], v[56:59]
	v_mfma_f32_16x16x32_bf16 v[52:55], v[200:203], v[192:195], v[52:55]
	v_mfma_f32_16x16x32_bf16 v[48:51], v[204:207], v[192:195], v[48:51]
	v_mfma_f32_16x16x32_bf16 v[164:167], v[200:203], v[168:171], v[92:95]
	v_mfma_f32_16x16x32_bf16 v[168:171], v[204:207], v[176:179], v[68:71]
	s_barrier
	s_nop 0
	ds_read_b128 v[68:71], v129 offset:16384
	ds_read_b128 v[92:95], v129 offset:17408
	ds_read_b128 v[172:175], v132 offset:16384
	ds_read_b128 v[176:179], v132 offset:17408
	ds_read_b128 v[180:183], v131 offset:16384
	ds_read_b128 v[184:187], v131 offset:17408
	ds_read_b128 v[188:191], v130 offset:16384
	ds_read_b128 v[192:195], v130 offset:17408
	s_waitcnt vmcnt(4)
	s_barrier
; #define LDA(dst, b, h) _Pragma("unroll") for (int m = 0; m < 4; ++m) _Pragma("unroll") for (int k = 0; k < 2; ++k) \
;     dst[m][k] = *reinterpret_cast<const bf16x8*>(SA(b, h) + lds_byte(wr * 64 + m * 16 + fr, k * 32 + fq * 8))
; #define LDB(dst, b, h) _Pragma("unroll") for (int n = 0; n < 2; ++n) _Pragma("unroll") for (int k = 0; k < 2; ++k) \
;     dst[n][k] = *reinterpret_cast<const bf16x8*>(SB(b, h) + lds_byte(wc * 32 + n * 16 + fr, k * 32 + fq * 8))
; #define WAIT_V(n) asm volatile("s_waitcnt vmcnt(" #n ")" ::: "memory")
; #define WAIT_L(n) asm volatile("s_waitcnt lgkmcnt(" #n ")" ::: "memory")
; #define BAR __builtin_amdgcn_s_barrier()
;     ...
;       LDA(At, 0, 1); WAIT_V(4); BAR; WAIT_L(0); MMA(1, 0, At, B0); MMA(1, 1, At, B1); BAR; }
;     { LDB(B0, 1, 0); LDA(At, 1, 0); WAIT_V(2); BAR; WAIT_L(0); MMA(0, 0, At, B0); BAR;
	s_waitcnt lgkmcnt(0)
	v_mfma_f32_16x16x32_bf16 v[44:47], v[152:155], v[68:71], v[44:47]
	v_mfma_f32_16x16x32_bf16 v[40:43], v[160:163], v[68:71], v[40:43]
	v_mfma_f32_16x16x32_bf16 v[36:39], v[152:155], v[172:175], v[36:39]
	v_mfma_f32_16x16x32_bf16 v[32:35], v[160:163], v[172:175], v[32:35]
	v_mfma_f32_16x16x32_bf16 v[28:31], v[152:155], v[180:183], v[28:31]
	v_mfma_f32_16x16x32_bf16 v[24:27], v[160:163], v[180:183], v[24:27]
	v_mfma_f32_16x16x32_bf16 v[20:23], v[152:155], v[188:191], v[20:23]
	v_mfma_f32_16x16x32_bf16 v[16:19], v[160:163], v[188:191], v[16:19]
	v_mfma_f32_16x16x32_bf16 v[44:47], v[156:159], v[92:95], v[44:47]
	v_mfma_f32_16x16x32_bf16 v[40:43], v[148:151], v[92:95], v[40:43]
	v_mfma_f32_16x16x32_bf16 v[36:39], v[156:159], v[176:179], v[36:39]
	v_mfma_f32_16x16x32_bf16 v[32:35], v[148:151], v[176:179], v[32:35]
	v_mfma_f32_16x16x32_bf16 v[28:31], v[156:159], v[184:187], v[28:31]
	v_mfma_f32_16x16x32_bf16 v[24:27], v[148:151], v[184:187], v[24:27]
	v_mfma_f32_16x16x32_bf16 v[20:23], v[156:159], v[192:195], v[20:23]
	v_mfma_f32_16x16x32_bf16 v[16:19], v[148:151], v[192:195], v[16:19]
	v_mfma_f32_16x16x32_bf16 v[4:7], v[196:199], v[172:175], v[4:7]
	v_mfma_f32_16x16x32_bf16 v[0:3], v[142:145], v[172:175], v[0:3]
	v_mfma_f32_16x16x32_bf16 v[12:15], v[196:199], v[68:71], v[12:15]
	v_mfma_f32_16x16x32_bf16 v[8:11], v[142:145], v[68:71], v[8:11]
	v_mfma_f32_16x16x32_bf16 v[64:67], v[196:199], v[180:183], v[64:67]
	v_mfma_f32_16x16x32_bf16 v[68:71], v[142:145], v[180:183], v[72:75]
	v_mfma_f32_16x16x32_bf16 v[72:75], v[196:199], v[188:191], v[76:79]
	v_mfma_f32_16x16x32_bf16 v[76:79], v[142:145], v[188:191], v[84:87]
	v_mfma_f32_16x16x32_bf16 v[4:7], v[200:203], v[176:179], v[4:7]
	v_mfma_f32_16x16x32_bf16 v[0:3], v[204:207], v[176:179], v[0:3]
	v_mfma_f32_16x16x32_bf16 v[142:145], v[200:203], v[92:95], v[12:15]
	v_mfma_f32_16x16x32_bf16 v[146:149], v[204:207], v[92:95], v[8:11]
	v_mfma_f32_16x16x32_bf16 v[150:153], v[200:203], v[184:187], v[64:67]
	v_mfma_f32_16x16x32_bf16 v[154:157], v[204:207], v[184:187], v[68:71]
	v_mfma_f32_16x16x32_bf16 v[158:161], v[200:203], v[192:195], v[72:75]
	v_mfma_f32_16x16x32_bf16 v[172:175], v[204:207], v[192:195], v[76:79]
	s_barrier
	ds_read_b128 v[8:11], v137
	ds_read_b128 v[12:15], v138
	ds_read_b128 v[176:179], v139
	ds_read_b128 v[138:141], v140
	ds_read_b128 v[64:67], v129 offset:32768
	ds_read_b128 v[72:75], v129 offset:33792
	ds_read_b128 v[180:183], v132 offset:32768
	ds_read_b128 v[184:187], v132 offset:33792
	ds_read_b128 v[188:191], v131 offset:32768
	ds_read_b128 v[192:195], v131 offset:33792
	ds_read_b128 v[196:199], v130 offset:32768
	ds_read_b128 v[200:203], v130 offset:33792
	s_waitcnt vmcnt(2)
	s_barrier
	s_waitcnt lgkmcnt(0)
	v_mfma_f32_16x16x32_bf16 v[68:71], v[8:11], v[64:67], v[124:127]
	v_mfma_f32_16x16x32_bf16 v[76:79], v[176:179], v[64:67], v[120:123]
	v_mfma_f32_16x16x32_bf16 v[84:87], v[8:11], v[180:183], v[116:119]
	v_mfma_f32_16x16x32_bf16 v[92:95], v[176:179], v[180:183], v[112:115]
	v_mfma_f32_16x16x32_bf16 v[112:115], v[8:11], v[188:191], v[108:111]
	v_mfma_f32_16x16x32_bf16 v[104:107], v[176:179], v[188:191], v[104:107]
	v_mfma_f32_16x16x32_bf16 v[120:123], v[8:11], v[196:199], v[100:103]
	v_mfma_f32_16x16x32_bf16 v[96:99], v[176:179], v[196:199], v[96:99]
	v_mfma_f32_16x16x32_bf16 v[124:127], v[12:15], v[72:75], v[68:71]
	v_mfma_f32_16x16x32_bf16 v[116:119], v[138:141], v[72:75], v[76:79]
	v_mfma_f32_16x16x32_bf16 v[108:111], v[12:15], v[184:187], v[84:87]
	v_mfma_f32_16x16x32_bf16 v[100:103], v[138:141], v[184:187], v[92:95]
	v_mfma_f32_16x16x32_bf16 v[92:95], v[12:15], v[192:195], v[112:115]
	v_mfma_f32_16x16x32_bf16 v[84:87], v[138:141], v[192:195], v[104:107]
	v_mfma_f32_16x16x32_bf16 v[76:79], v[12:15], v[200:203], v[120:123]
	v_mfma_f32_16x16x32_bf16 v[68:71], v[138:141], v[200:203], v[96:99]
	s_barrier
; #define LDA(dst, b, h) _Pragma("unroll") for (int m = 0; m < 4; ++m) _Pragma("unroll") for (int k = 0; k < 2; ++k) \
;     dst[m][k] = *reinterpret_cast<const bf16x8*>(SA(b, h) + lds_byte(wr * 64 + m * 16 + fr, k * 32 + fq * 8))
; #define LDB(dst, b, h) _Pragma("unroll") for (int n = 0; n < 2; ++n) _Pragma("unroll") for (int k = 0; k < 2; ++k) \
;     dst[n][k] = *reinterpret_cast<const bf16x8*>(SB(b, h) + lds_byte(wc * 32 + n * 16 + fr, k * 32 + fq * 8))
; #define WAIT_V(n) asm volatile("s_waitcnt vmcnt(" #n ")" ::: "memory")
; #define WAIT_L(n) asm volatile("s_waitcnt lgkmcnt(" #n ")" ::: "memory")
; #define BAR __builtin_amdgcn_s_barrier()
;     ...
;       LDB(B1, 1, 1); WAIT_V(0); BAR; WAIT_L(0); MMA(0, 1, At, B1); BAR;
;       LDA(At, 1, 1); BAR; WAIT_L(0); MMA(1, 0, At, B0); MMA(1, 1, At, B1); BAR; }
;     if (wr == 0) BAR;
	ds_read_b128 v[204:207], v133
	ds_read_b128 v[208:211], v134
	ds_read_b128 v[212:215], v135
	ds_read_b128 v[134:137], v136
	s_waitcnt vmcnt(0)
	s_barrier
	s_waitcnt lgkmcnt(0)
	v_mfma_f32_16x16x32_bf16 v[96:99], v[204:207], v[64:67], v[164:167]
	v_mfma_f32_16x16x32_bf16 v[64:67], v[212:215], v[64:67], v[88:91]
	v_mfma_f32_16x16x32_bf16 v[80:83], v[204:207], v[180:183], v[80:83]
	v_mfma_f32_16x16x32_bf16 v[88:91], v[212:215], v[180:183], v[168:171]
	v_mfma_f32_16x16x32_bf16 v[60:63], v[204:207], v[188:191], v[60:63]
	v_mfma_f32_16x16x32_bf16 v[56:59], v[212:215], v[188:191], v[56:59]
	v_mfma_f32_16x16x32_bf16 v[52:55], v[204:207], v[196:199], v[52:55]
	v_mfma_f32_16x16x32_bf16 v[48:51], v[212:215], v[196:199], v[48:51]
	v_mfma_f32_16x16x32_bf16 v[120:123], v[208:211], v[72:75], v[96:99]
	v_mfma_f32_16x16x32_bf16 v[112:115], v[134:137], v[72:75], v[64:67]
	v_mfma_f32_16x16x32_bf16 v[104:107], v[208:211], v[184:187], v[80:83]
	v_mfma_f32_16x16x32_bf16 v[96:99], v[134:137], v[184:187], v[88:91]
	v_mfma_f32_16x16x32_bf16 v[88:91], v[208:211], v[192:195], v[60:63]
	v_mfma_f32_16x16x32_bf16 v[80:83], v[134:137], v[192:195], v[56:59]
	v_mfma_f32_16x16x32_bf16 v[72:75], v[208:211], v[200:203], v[52:55]
	v_mfma_f32_16x16x32_bf16 v[64:67], v[134:137], v[200:203], v[48:51]
	s_barrier
	s_nop 0
	ds_read_b128 v[48:51], v129 offset:49152
	ds_read_b128 v[162:165], v129 offset:50176
	ds_read_b128 v[52:55], v132 offset:49152
	ds_read_b128 v[166:169], v132 offset:50176
	ds_read_b128 v[180:183], v131 offset:49152
	ds_read_b128 v[184:187], v131 offset:50176
	ds_read_b128 v[188:191], v130 offset:49152
	ds_read_b128 v[130:133], v130 offset:50176
	s_barrier
	s_waitcnt lgkmcnt(0)
	v_mfma_f32_16x16x32_bf16 v[44:47], v[8:11], v[48:51], v[44:47]
	v_mfma_f32_16x16x32_bf16 v[40:43], v[176:179], v[48:51], v[40:43]
	v_mfma_f32_16x16x32_bf16 v[36:39], v[8:11], v[52:55], v[36:39]
	v_mfma_f32_16x16x32_bf16 v[32:35], v[176:179], v[52:55], v[32:35]
	v_mfma_f32_16x16x32_bf16 v[28:31], v[8:11], v[180:183], v[28:31]
	v_mfma_f32_16x16x32_bf16 v[24:27], v[176:179], v[180:183], v[24:27]
	v_mfma_f32_16x16x32_bf16 v[8:11], v[8:11], v[188:191], v[20:23]
	v_mfma_f32_16x16x32_bf16 v[16:19], v[176:179], v[188:191], v[16:19]
	v_mfma_f32_16x16x32_bf16 v[60:63], v[12:15], v[162:165], v[44:47]
	v_mfma_f32_16x16x32_bf16 v[56:59], v[138:141], v[162:165], v[40:43]
	v_mfma_f32_16x16x32_bf16 v[44:47], v[12:15], v[166:169], v[36:39]
	v_mfma_f32_16x16x32_bf16 v[40:43], v[138:141], v[166:169], v[32:35]
	v_mfma_f32_16x16x32_bf16 v[28:31], v[12:15], v[184:187], v[28:31]
	v_mfma_f32_16x16x32_bf16 v[24:27], v[138:141], v[184:187], v[24:27]
	v_mfma_f32_16x16x32_bf16 v[12:15], v[12:15], v[130:133], v[8:11]
	v_mfma_f32_16x16x32_bf16 v[8:11], v[138:141], v[130:133], v[16:19]
	v_mfma_f32_16x16x32_bf16 v[16:19], v[204:207], v[48:51], v[142:145]
	v_mfma_f32_16x16x32_bf16 v[20:23], v[212:215], v[48:51], v[146:149]
	v_mfma_f32_16x16x32_bf16 v[4:7], v[204:207], v[52:55], v[4:7]
	v_mfma_f32_16x16x32_bf16 v[0:3], v[212:215], v[52:55], v[0:3]
	v_mfma_f32_16x16x32_bf16 v[138:141], v[204:207], v[180:183], v[150:153]
	v_mfma_f32_16x16x32_bf16 v[142:145], v[212:215], v[180:183], v[154:157]
	v_mfma_f32_16x16x32_bf16 v[146:149], v[204:207], v[188:191], v[158:161]
	v_mfma_f32_16x16x32_bf16 v[150:153], v[212:215], v[188:191], v[172:175]
	v_mfma_f32_16x16x32_bf16 v[52:55], v[208:211], v[162:165], v[16:19]
	v_mfma_f32_16x16x32_bf16 v[48:51], v[134:137], v[162:165], v[20:23]
	v_mfma_f32_16x16x32_bf16 v[36:39], v[208:211], v[166:169], v[4:7]
	v_mfma_f32_16x16x32_bf16 v[32:35], v[134:137], v[166:169], v[0:3]
	v_mfma_f32_16x16x32_bf16 v[20:23], v[208:211], v[184:187], v[138:141]
	v_mfma_f32_16x16x32_bf16 v[16:19], v[134:137], v[184:187], v[142:145]
	v_mfma_f32_16x16x32_bf16 v[4:7], v[208:211], v[130:133], v[146:149]
	v_mfma_f32_16x16x32_bf16 v[0:3], v[134:137], v[130:133], v[150:153]
	v_cmp_gt_u32_e32 vcc, s46, v128
	s_barrier
	s_and_saveexec_b64 s[6:7], vcc
	s_cbranch_execz .LBB0_294
	s_barrier

; #define WAIT_V(n) asm volatile("s_waitcnt vmcnt(" #n ")" ::: "memory")
; #define BAR __builtin_amdgcn_s_barrier()
;     ...
;         constexpr int PIECE = 1024 + 16, LOBASE = 64 * PIECE;
;         const int hvo = (lane >> 5) * (DM * 2) + (lane & 31) * 16;
;         const int lvo = (lane >> 4) * DM + (lane & 15) * 16;
;         _Pragma("unroll") for (int ai = 0; ai < 2; ++ai) {
;           const int rbase = brow + ai * HALF;
;           const int hso = ((rbase + 16 * wave) * DM + pn * BM) * 2;
;           const int lso = (rbase + 16 * wave) * DM + pn * BM;
;           _Pragma("unroll") for (int i = 0; i < 8; ++i)
;             __builtin_amdgcn_raw_ptr_buffer_load_lds(rsXB, (__attribute__((address_space(3))) void*)(smem + (wave * 8 + i) * PIECE), 16,
;                                                      hvo + i * (2 * DM * 2), hso, 0, 0);
;           _Pragma("unroll") for (int i = 0; i < 4; ++i)
;             __builtin_amdgcn_raw_ptr_buffer_load_lds(rsLO, (__attribute__((address_space(3))) void*)(smem + LOBASE + (wave * 4 + i) * PIECE), 16,
;                                                      lvo + i * (4 * DM), lso, 0, 0);
;           WAIT_V(0); BAR;
;           _Pragma("unroll") for (int m = 0; m < 4; ++m) _Pragma("unroll") for (int bj = 0; bj < 2; ++bj) _Pragma("unroll") for (int n = 0; n < 2; ++n) {
;             const int rr = wr * 64 + m * 16 + fr;
;             const int cc = bj * HALF + wc * 32 + n * 16 + fq * 4;
;             const u32x2 hv = *reinterpret_cast<const u32x2*>(smem + (rr >> 1) * PIECE + (rr & 1) * 512 + cc * 2);
;             const unsigned lv = *reinterpret_cast<const unsigned*>(smem + LOBASE + (rr >> 2) * PIECE + (rr & 3) * 256 + cc);
;             float x0 = __int_as_float((int)(hv[0] << 16) + (((int)(lv << 24)) >> 24) * 256);
;             float x1 = __int_as_float((int)(hv[0] & 0xffff0000u) + (((int)(lv << 16)) >> 24) * 256);
;             float x2 = __int_as_float((int)(hv[1] << 16) + (((int)(lv << 8)) >> 24) * 256);
;             float x3 = __int_as_float((int)(hv[1] & 0xffff0000u) + (((int)lv) >> 24) * 256);
;             acc[ai][bj][m][n][0] = ALPHA * x0 + sc * acc[ai][bj][m][n][0];
;             acc[ai][bj][m][n][1] = ALPHA * x1 + sc * acc[ai][bj][m][n][1];
;             acc[ai][bj][m][n][2] = ALPHA * x2 + sc * acc[ai][bj][m][n][2];
;             acc[ai][bj][m][n][3] = ALPHA * x3 + sc * acc[ai][bj][m][n][3];
.LBB0_296:
	s_lshl_b32 s1, s4, 19
	v_mbcnt_lo_u32_b32 v128, -1, 0
	v_mbcnt_hi_u32_b32 v128, -1, v128
	s_lshl_b32 s28, s0, 8
	v_lshlrev_b32_e32 v134, 4, v128
	s_add_i32 s1, s1, s45
	v_lshlrev_b32_e32 v133, 7, v128
	v_and_b32_e32 v134, 0x1f0, v134
	s_add_i32 s1, s1, s28
	s_mov_b32 m0, s2
	v_and_or_b32 v146, v133, s29, v134
	s_lshl_b32 s41, s1, 1
	buffer_load_dwordx4 v146, s[16:19], s41 offen lds
	v_or_b32_e32 v152, 0x2000, v146
	s_mov_b32 m0, s53
	v_or_b32_e32 v153, 0x4000, v146
	buffer_load_dwordx4 v152, s[16:19], s41 offen lds
	s_mov_b32 m0, s50
	v_or_b32_e32 v154, 0x6000, v146
	buffer_load_dwordx4 v153, s[16:19], s41 offen lds
	s_mov_b32 m0, s51
	v_or_b32_e32 v155, 0x8000, v146
	buffer_load_dwordx4 v154, s[16:19], s41 offen lds
	s_mov_b32 m0, s52
	v_add_u32_e32 v220, s34, v128
	buffer_load_dwordx4 v155, s[16:19], s41 offen lds
	v_or_b32_e32 v156, 0xa000, v146
	s_mov_b32 m0, s31
	v_and_b32_e32 v129, 15, v128
	v_ashrrev_i32_e32 v131, 2, v220
	buffer_load_dwordx4 v156, s[16:19], s41 offen lds
	v_or_b32_e32 v157, 0xc000, v146
	s_mov_b32 m0, s81
	v_and_b32_e32 v222, 63, v128
	v_bfe_u32 v130, v128, 4, 2
	v_lshlrev_b32_e32 v133, 4, v129
	v_and_or_b32 v225, v131, s64, v129
	v_lshlrev_b32_e32 v129, 9, v128
	v_lshlrev_b32_e32 v128, 8, v128
	buffer_load_dwordx4 v157, s[16:19], s41 offen lds
	v_or_b32_e32 v158, 0xe000, v146
	s_mov_b32 m0, s82
	v_lshl_or_b32 v147, v130, 11, v133
	v_and_b32_e32 v128, 0x300, v128
	v_or_b32_e32 v150, 48, v225
	buffer_load_dwordx4 v158, s[16:19], s41 offen lds
	s_mov_b32 s22, s18
	s_mov_b32 s23, s19
	s_mov_b32 m0, s56
	v_bfe_u32 v223, v220, 6, 2
	v_lshlrev_b32_e32 v132, 2, v130
	v_and_b32_e32 v136, 0x200, v129
	v_or_b32_e32 v149, 0x10400, v128
	v_lshrrev_b32_e32 v128, 1, v150
	buffer_load_dwordx4 v147, s[20:23], s1 offen lds
	v_or_b32_e32 v159, 0x2000, v147
	s_mov_b32 m0, s57
	v_lshl_or_b32 v148, v223, 5, v132
	v_mad_u64_u32 v[134:135], s[6:7], v128, s63, v[136:137]
	buffer_load_dwordx4 v159, s[20:23], s1 offen lds
	v_or_b32_e32 v160, 0x4000, v147
	s_mov_b32 m0, s62
	v_lshrrev_b32_e32 v128, 2, v225
	v_lshlrev_b32_e32 v135, 1, v148
	buffer_load_dwordx4 v160, s[20:23], s1 offen lds
	v_or_b32_e32 v161, 0x6000, v147
	s_mov_b32 m0, s80
	v_mul_lo_u32 v128, v128, s63
	v_or_b32_e32 v137, 0x100, v135
	buffer_load_dwordx4 v161, s[20:23], s1 offen lds
	v_lshrrev_b32_e32 v130, 1, v225
	v_add3_u32 v162, v149, v128, v148
	s_waitcnt vmcnt(0)
	s_barrier
	ds_read2_b32 v[128:129], v162 offset1:4
	v_mad_u64_u32 v[138:139], s[6:7], v130, s63, v[136:137]
	v_add_u32_e32 v166, v138, v135
	ds_read_b64 v[130:131], v166
	s_waitcnt lgkmcnt(1)
	v_lshlrev_b32_e32 v132, 24, v128
	v_ashrrev_i32_e32 v132, 16, v132
	v_or_b32_e32 v163, 32, v135
	v_add_u32_e32 v167, v138, v163
	s_waitcnt lgkmcnt(0)
	v_lshl_add_u32 v144, v130, 16, v132
	v_and_b32_e32 v130, 0xffff0000, v130
	v_and_b32_sdwa v132, sext(v128), s83 dst_sel:DWORD dst_unused:UNUSED_PAD src0_sel:WORD_0 src1_sel:DWORD
	v_add_u32_e32 v132, v132, v130
	v_bfe_i32 v130, v128, 8, 16
	v_add_u32_e32 v151, v134, v137
	v_add_u32_e32 v186, v138, v137
	ds_read_b64 v[140:141], v167
	ds_read_b64 v[142:143], v186
	ds_read_b64 v[188:189], v151
	v_and_b32_e32 v130, 0xffffff00, v130
	v_lshl_add_u32 v133, v131, 16, v130
	v_and_b32_e32 v130, 0xffff0000, v131
	v_and_b32_sdwa v128, sext(v128), s83 dst_sel:DWORD dst_unused:UNUSED_PAD src0_sel:WORD_1 src1_sel:DWORD
	v_add_u32_e32 v145, v128, v130
	v_mov_b32_e32 v130, v125
	v_mov_b32_e32 v131, v126
	v_mov_b32_e32 v125, v127
	v_pk_fma_f32 v[132:133], v[132:133], s[26:27], v[130:131] op_sel_hi:[1,0,1]
	v_pk_fma_f32 v[130:131], v[144:145], s[26:27], v[124:125] op_sel_hi:[1,0,1]
	s_waitcnt lgkmcnt(2)
	v_and_b32_e32 v125, 0xffff0000, v140
	v_and_b32_sdwa v126, sext(v129), s83 dst_sel:DWORD dst_unused:UNUSED_PAD src0_sel:WORD_0 src1_sel:DWORD
	v_lshlrev_b32_e32 v124, 24, v129
	v_add_u32_e32 v126, v126, v125
	v_bfe_i32 v125, v129, 8, 16
	v_ashrrev_i32_e32 v124, 16, v124
	v_and_b32_e32 v125, 0xffffff00, v125
	v_lshl_add_u32 v124, v140, 16, v124
	v_lshl_add_u32 v127, v141, 16, v125
	v_and_b32_e32 v125, 0xffff0000, v141
	ds_read2_b32 v[140:141], v162 offset0:32 offset1:36
	v_and_b32_sdwa v128, sext(v129), s83 dst_sel:DWORD dst_unused:UNUSED_PAD src0_sel:WORD_1 src1_sel:DWORD
	v_add_u32_e32 v125, v128, v125
	v_mov_b32_e32 v128, v117
	v_mov_b32_e32 v129, v118
	v_mov_b32_e32 v117, v119
	v_pk_fma_f32 v[128:129], v[126:127], s[26:27], v[128:129] op_sel_hi:[1,0,1]
	v_pk_fma_f32 v[126:127], v[124:125], s[26:27], v[116:117] op_sel_hi:[1,0,1]
	s_waitcnt lgkmcnt(2)
	v_and_b32_e32 v117, 0xffff0000, v142
	s_waitcnt lgkmcnt(0)
	v_and_b32_sdwa v118, sext(v140), s83 dst_sel:DWORD dst_unused:UNUSED_PAD src0_sel:WORD_0 src1_sel:DWORD
	v_add_u32_e32 v118, v118, v117
	v_bfe_i32 v117, v140, 8, 16
	v_lshlrev_b32_e32 v116, 24, v140
	v_and_b32_e32 v117, 0xffffff00, v117
	v_ashrrev_i32_e32 v116, 16, v116
	v_lshl_add_u32 v119, v143, 16, v117
	v_and_b32_e32 v117, 0xffff0000, v143
	v_and_b32_sdwa v124, sext(v140), s83 dst_sel:DWORD dst_unused:UNUSED_PAD src0_sel:WORD_1 src1_sel:DWORD
	v_or_b32_e32 v140, 0x120, v135
	v_lshl_add_u32 v116, v142, 16, v116
	v_add_u32_e32 v117, v124, v117
	v_mov_b32_e32 v124, v121
	v_mov_b32_e32 v125, v122
	v_mov_b32_e32 v121, v123
	v_add_u32_e32 v144, v138, v140
	v_pk_fma_f32 v[124:125], v[118:119], s[26:27], v[124:125] op_sel_hi:[1,0,1]
	v_pk_fma_f32 v[118:119], v[116:117], s[26:27], v[120:121] op_sel_hi:[1,0,1]
	ds_read_b64 v[116:117], v144
	v_lshlrev_b32_e32 v120, 24, v141
	v_or_b32_e32 v145, 16, v225
	v_ashrrev_i32_e32 v138, 16, v120
	v_lshrrev_b32_e32 v120, 1, v145
	v_mad_u64_u32 v[120:121], s[6:7], v120, s63, v[136:137]
	s_waitcnt lgkmcnt(0)
; #define BAR __builtin_amdgcn_s_barrier()
;     ...
;         _Pragma("unroll") for (int ai = 0; ai < 2; ++ai) {
;           const int rbase = brow + ai * HALF;
;           const int hso = ((rbase + 16 * wave) * DM + pn * BM) * 2;
;           const int lso = (rbase + 16 * wave) * DM + pn * BM;
;           _Pragma("unroll") for (int i = 0; i < 8; ++i)
;             __builtin_amdgcn_raw_ptr_buffer_load_lds(rsXB, (__attribute__((address_space(3))) void*)(smem + (wave * 8 + i) * PIECE), 16,
;                                                      hvo + i * (2 * DM * 2), hso, 0, 0);
;           _Pragma("unroll") for (int i = 0; i < 4; ++i)
;             __builtin_amdgcn_raw_ptr_buffer_load_lds(rsLO, (__attribute__((address_space(3))) void*)(smem + LOBASE + (wave * 4 + i) * PIECE), 16,
;                                                      lvo + i * (4 * DM), lso, 0, 0);
;           WAIT_V(0); BAR;
;           _Pragma("unroll") for (int m = 0; m < 4; ++m) _Pragma("unroll") for (int bj = 0; bj < 2; ++bj) _Pragma("unroll") for (int n = 0; n < 2; ++n) {
;             const int rr = wr * 64 + m * 16 + fr;
;             const int cc = bj * HALF + wc * 32 + n * 16 + fq * 4;
;             const u32x2 hv = *reinterpret_cast<const u32x2*>(smem + (rr >> 1) * PIECE + (rr & 1) * 512 + cc * 2);
;             const unsigned lv = *reinterpret_cast<const unsigned*>(smem + LOBASE + (rr >> 2) * PIECE + (rr & 3) * 256 + cc);
;             float x0 = __int_as_float((int)(hv[0] << 16) + (((int)(lv << 24)) >> 24) * 256);
;             float x1 = __int_as_float((int)(hv[0] & 0xffff0000u) + (((int)(lv << 16)) >> 24) * 256);
;             float x2 = __int_as_float((int)(hv[1] << 16) + (((int)(lv << 8)) >> 24) * 256);
;             float x3 = __int_as_float((int)(hv[1] & 0xffff0000u) + (((int)lv) >> 24) * 256);
;             acc[ai][bj][m][n][0] = ALPHA * x0 + sc * acc[ai][bj][m][n][0];
;             acc[ai][bj][m][n][1] = ALPHA * x1 + sc * acc[ai][bj][m][n][1];
;             acc[ai][bj][m][n][2] = ALPHA * x2 + sc * acc[ai][bj][m][n][2];
;             acc[ai][bj][m][n][3] = ALPHA * x3 + sc * acc[ai][bj][m][n][3];
;           }
;           WAIT_L(0); BAR;
;         }
;       }
;       float* red = reinterpret_cast<float*>(smem + 8 * HTB);
;       const int bp16 = (lane ^ 16) << 2, bp32 = (lane ^ 32) << 2;
;       float* red2 = red + 4 * 256 * 2;
;       float* mr = red2 + 2 * 256 * 2;
	v_lshl_add_u32 v138, v116, 16, v138
	v_and_b32_e32 v116, 0xffff0000, v116
	v_and_b32_sdwa v121, sext(v141), s83 dst_sel:DWORD dst_unused:UNUSED_PAD src0_sel:WORD_0 src1_sel:DWORD
	v_add_u32_e32 v142, v121, v116
	v_bfe_i32 v116, v141, 8, 16
	v_and_b32_e32 v116, 0xffffff00, v116
	v_lshl_add_u32 v143, v117, 16, v116
	v_and_b32_e32 v116, 0xffff0000, v117
	v_and_b32_sdwa v117, sext(v141), s83 dst_sel:DWORD dst_unused:UNUSED_PAD src0_sel:WORD_1 src1_sel:DWORD
	v_add_u32_e32 v139, v117, v116
	v_mov_b32_e32 v117, v114
	v_lshrrev_b32_e32 v114, 2, v145
	v_add_u32_e32 v164, v120, v135
	v_add_u32_e32 v165, v120, v163
	v_add_u32_e32 v168, v120, v137
	v_mul_lo_u32 v114, v114, s63
	v_add_u32_e32 v170, v120, v140
	v_or_b32_e32 v120, 32, v225
	v_add3_u32 v145, v149, v114, v148
	v_lshrrev_b32_e32 v114, 1, v120
	v_mov_b32_e32 v116, v113
	v_mov_b32_e32 v113, v115
	v_mad_u64_u32 v[114:115], s[6:7], v114, s63, v[136:137]
	v_lshrrev_b32_e32 v115, 2, v120
	v_add_u32_e32 v187, v114, v135
	v_add_u32_e32 v191, v114, v163
	v_add_u32_e32 v192, v114, v137
	v_add_u32_e32 v224, v114, v140
	v_lshrrev_b32_e32 v114, 2, v150
	v_mul_lo_u32 v115, v115, s63
	v_mul_lo_u32 v114, v114, s63
	s_add_i32 s40, s1, 0x40000
	v_add3_u32 v190, v149, v115, v148
	v_add_u32_e32 v226, v134, v135
	v_add3_u32 v135, v149, v114, v148
	s_lshl_b32 s0, s40, 1
	s_mov_b32 m0, s2
	ds_read_b64 v[122:123], v164
	ds_read_b64 v[210:211], v165
	ds_read_b64 v[206:207], v168
	v_pk_fma_f32 v[116:117], v[142:143], s[26:27], v[116:117] op_sel_hi:[1,0,1]
	v_pk_fma_f32 v[112:113], v[138:139], s[26:27], v[112:113] op_sel_hi:[1,0,1]
	ds_read2_b32 v[212:213], v145 offset1:4
	ds_read2_b32 v[138:139], v145 offset0:32 offset1:36
	ds_read2_b32 v[202:203], v190 offset1:4
	ds_read_b64 v[208:209], v170
	ds_read_b64 v[136:137], v187
	ds_read_b64 v[204:205], v191
	ds_read_b64 v[200:201], v192
	ds_read2_b32 v[142:143], v190 offset0:32 offset1:36
	ds_read2_b32 v[114:115], v135 offset1:4
	v_add_u32_e32 v227, v134, v163
	ds_read2_b32 v[194:195], v135 offset0:32 offset1:36
	v_add_u32_e32 v228, v134, v140
	ds_read_b64 v[198:199], v224
	ds_read_b64 v[140:141], v226
	ds_read_b64 v[120:121], v227
	ds_read_b64 v[196:197], v228
	s_waitcnt lgkmcnt(0)
	s_barrier
	buffer_load_dwordx4 v146, s[16:19], s0 offen lds
	s_mov_b32 m0, s53
	v_add_f32_e32 v134, 0, v130
	buffer_load_dwordx4 v152, s[16:19], s0 offen lds
	s_mov_b32 m0, s50
	v_add_f32_e32 v150, v134, v132
	buffer_load_dwordx4 v153, s[16:19], s0 offen lds
	s_mov_b32 m0, s51
	v_add_f32_e32 v150, v133, v150
	buffer_load_dwordx4 v154, s[16:19], s0 offen lds
	s_mov_b32 m0, s52
	v_add_f32_e32 v153, v131, v150
	buffer_load_dwordx4 v155, s[16:19], s0 offen lds
	s_mov_b32 m0, s31
	v_mul_f32_e32 v152, v133, v133
	buffer_load_dwordx4 v156, s[16:19], s0 offen lds
	s_mov_b32 m0, s81
	v_mov_b32_e32 v150, v131
	buffer_load_dwordx4 v157, s[16:19], s0 offen lds
	s_mov_b32 m0, s82
	v_mul_f32_e32 v154, v112, v112
	buffer_load_dwordx4 v158, s[16:19], s0 offen lds
	s_mov_b32 m0, s56
	v_lshlrev_b32_e32 v229, 2, v222
	buffer_load_dwordx4 v147, s[20:23], s40 offen lds
	s_mov_b32 m0, s57
	v_xor_b32_e32 v221, 64, v229
	buffer_load_dwordx4 v159, s[20:23], s40 offen lds
	s_mov_b32 m0, s62
	v_lshlrev_b32_e32 v223, 9, v223
	buffer_load_dwordx4 v160, s[20:23], s40 offen lds
	s_mov_b32 m0, s80
	v_cmp_gt_u32_e32 vcc, 16, v222
	buffer_load_dwordx4 v161, s[20:23], s40 offen lds
	s_waitcnt vmcnt(0)
	s_barrier
	ds_read2_b32 v[184:185], v162 offset1:4
	ds_read2_b32 v[180:181], v162 offset0:32 offset1:36
	ds_read2_b32 v[174:175], v145 offset1:4
	ds_read_b64 v[182:183], v144
	ds_read_b64 v[178:179], v164
	ds_read_b64 v[176:177], v165
	ds_read_b64 v[172:173], v168
	ds_read2_b32 v[168:169], v145 offset0:32 offset1:36
	ds_read2_b32 v[160:161], v190 offset1:4
	ds_read_b64 v[170:171], v170
	ds_read_b64 v[164:165], v187
	ds_read_b64 v[162:163], v191
	ds_read_b64 v[158:159], v192
	ds_read2_b32 v[156:157], v190 offset0:32 offset1:36
	ds_read2_b32 v[148:149], v135 offset1:4
	ds_read_b64 v[192:193], v166
	ds_read_b64 v[190:191], v167
	ds_read_b64 v[186:187], v186
	ds_read_b64 v[146:147], v151
	ds_read2_b32 v[144:145], v135 offset0:32 offset1:36
	v_pk_mul_f32 v[134:135], v[132:133], v[132:133]
	v_mov_b32_e32 v151, v133
	v_pk_fma_f32 v[134:135], v[130:131], v[130:131], v[134:135]
	v_lshlrev_b32_e32 v222, 3, v225
	v_pk_add_f32 v[134:135], v[152:153], v[134:135] op_sel_hi:[0,1]
	v_pk_fma_f32 v[134:135], v[150:151], v[150:151], v[134:135]
	v_add_f32_e32 v150, v126, v153
	v_add_f32_e32 v153, v128, v150
	v_mul_f32_e32 v152, v126, v126
	v_mov_b32_e32 v150, v128
	v_mov_b32_e32 v151, v126
	v_pk_add_f32 v[134:135], v[152:153], v[134:135] op_sel_hi:[0,1]
	v_pk_fma_f32 v[134:135], v[150:151], v[150:151], v[134:135]
	v_add_f32_e32 v150, v129, v153
	v_add_f32_e32 v153, v127, v150
	v_mul_f32_e32 v152, v129, v129
	v_mov_b32_e32 v150, v127
	v_mov_b32_e32 v151, v129
	v_pk_add_f32 v[134:135], v[152:153], v[134:135] op_sel_hi:[0,1]
	v_pk_fma_f32 v[134:135], v[150:151], v[150:151], v[134:135]
	v_add_f32_e32 v150, v118, v153
	v_add_f32_e32 v153, v124, v150
	v_mul_f32_e32 v152, v118, v118
	v_mov_b32_e32 v150, v124
	v_mov_b32_e32 v151, v118
	v_pk_add_f32 v[134:135], v[152:153], v[134:135] op_sel_hi:[0,1]
	v_pk_fma_f32 v[134:135], v[150:151], v[150:151], v[134:135]
	v_add_f32_e32 v150, v125, v153
	v_add_f32_e32 v153, v119, v150
	v_mul_f32_e32 v152, v125, v125
	v_mov_b32_e32 v150, v119
	v_mov_b32_e32 v151, v125
	v_pk_add_f32 v[134:135], v[152:153], v[134:135] op_sel_hi:[0,1]
	v_pk_fma_f32 v[134:135], v[150:151], v[150:151], v[134:135]
	v_add_f32_e32 v150, v112, v153
	v_mov_b32_e32 v152, v116
	v_mov_b32_e32 v153, v112
	v_pk_add_f32 v[134:135], v[154:155], v[134:135] op_sel_hi:[0,1]
	v_pk_fma_f32 v[134:135], v[152:153], v[152:153], v[134:135]
	v_pk_mul_f32 v[152:153], v[116:117], v[116:117]
	v_add_f32_e32 v150, v116, v150
	v_pk_mul_f32 v[154:155], v[112:113], v[112:113]
	v_pk_mov_b32 v[134:135], v[116:117], v[134:135] op_sel:[1,0]
	v_mov_b32_e32 v151, v153
	v_pk_add_f32 v[134:135], v[134:135], v[150:151]
	v_mov_b32_e32 v154, v113
	v_pk_add_f32 v[134:135], v[154:155], v[134:135]
	ds_bpermute_b32 v214, v221, v134
	ds_bpermute_b32 v215, v221, v135
	ds_read_b64 v[166:167], v224
	ds_read_b64 v[154:155], v226
	ds_read_b64 v[152:153], v227
	ds_read_b64 v[150:151], v228
	v_xor_b32_e32 v224, 0x80, v229
	s_waitcnt lgkmcnt(0)
	v_lshlrev_b32_e32 v223, 2, v223
	v_pk_add_f32 v[134:135], v[134:135], v[214:215]
	ds_bpermute_b32 v214, v224, v134
	ds_bpermute_b32 v215, v224, v135
	s_barrier
	s_and_saveexec_b64 s[6:7], vcc
	s_cbranch_execz .LBB0_298
	v_add3_u32 v225, v222, v223, s19
	s_waitcnt lgkmcnt(0)
	v_pk_add_f32 v[134:135], v[134:135], v[214:215]
	s_waitcnt vmcnt(0)
	ds_write_b64 v225, v[134:135]

; #define STAGE(P, RS, SOFF, OFF, kt) do { const int _so = (SOFF) + (kt) * (BK * 2); \
;     _Pragma("unroll") for (int _i = 0; _i < 2; ++_i) { \
;       __builtin_amdgcn_raw_ptr_buffer_load_lds(RS, (__attribute__((address_space(3))) void*)((P) + wave * 1024 + _i * 8192), 16, OFF[_i], _so, 0, 0); } } while (0)
; #define LDA(dst, b, h) _Pragma("unroll") for (int m = 0; m < 4; ++m) _Pragma("unroll") for (int k = 0; k < 2; ++k) \
;     dst[m][k] = *reinterpret_cast<const bf16x8*>(SA(b, h) + lds_byte(wr * 64 + m * 16 + fr, k * 32 + fq * 8))
; #define LDB(dst, b, h) _Pragma("unroll") for (int n = 0; n < 2; ++n) _Pragma("unroll") for (int k = 0; k < 2; ++k) \
;     dst[n][k] = *reinterpret_cast<const bf16x8*>(SB(b, h) + lds_byte(wc * 32 + n * 16 + fr, k * 32 + fq * 8))
; #define WAIT_V(n) asm volatile("s_waitcnt vmcnt(" #n ")" ::: "memory")
; #define WAIT_L(n) asm volatile("s_waitcnt lgkmcnt(" #n ")" ::: "memory")
; #define BAR __builtin_amdgcn_s_barrier()
; #define SCHED __builtin_amdgcn_sched_barrier(0)
;     ...
;     for (int t = 0; t < nt - 2; t += 2) {
;       LDB(B0, 0, 0); SCHED; LDA(At, 0, 0); STAGE(SA(1, 1), rsA, sA1, offA, t + 1);
;       WAIT_L(8); BAR; WAIT_L(0); MMA(0, 0, At, B0); BAR; SCHED;
;       LDB(B1, 0, 1); STAGE(SB(0, 0), rsB, sB0, offB, t + 2);
;       BAR; WAIT_L(0); MMA(0, 1, At, B1); BAR;
;       LDA(At, 0, 1); STAGE(SA(0, 0), rsA, sA0, offA, t + 2);
;       BAR; WAIT_L(0); MMA(1, 0, At, B0); BAR; SCHED;
;       STAGE(SB(0, 1), rsB, sB1, offB, t + 2);
;       WAIT_V(6); BAR; MMA(1, 1, At, B1); BAR;
.LBB0_354:
	ds_read_b128 v[154:157], v149
	ds_read_b128 v[158:161], v150
	ds_read_b128 v[162:165], v151
	ds_read_b128 v[166:169], v152
	s_add_i32 s43, s37, s17
	s_add_i32 s10, s43, 0x80
	s_mov_b32 m0, s30
	ds_read_b128 v[170:173], v131
	ds_read_b128 v[174:177], v131 offset:1024
	ds_read_b128 v[178:181], v134
	ds_read_b128 v[182:185], v134 offset:1024
	ds_read_b128 v[186:189], v133
	ds_read_b128 v[190:193], v133 offset:1024
	ds_read_b128 v[194:197], v132
	ds_read_b128 v[198:201], v132 offset:1024
	buffer_load_dwordx4 v143, s[4:7], s10 offen lds
	s_mov_b32 m0, s31
	s_nop 0
	buffer_load_dwordx4 v144, s[4:7], s10 offen lds
	s_waitcnt lgkmcnt(8)
	s_barrier
	s_waitcnt lgkmcnt(0)
	v_mfma_f32_16x16x32_bf16 v[124:127], v[154:157], v[170:173], v[124:127]
	v_mfma_f32_16x16x32_bf16 v[120:123], v[162:165], v[170:173], v[120:123]
	v_mfma_f32_16x16x32_bf16 v[116:119], v[154:157], v[178:181], v[116:119]
	v_mfma_f32_16x16x32_bf16 v[112:115], v[162:165], v[178:181], v[112:115]
	v_mfma_f32_16x16x32_bf16 v[108:111], v[154:157], v[186:189], v[108:111]
	v_mfma_f32_16x16x32_bf16 v[104:107], v[162:165], v[186:189], v[104:107]
	v_mfma_f32_16x16x32_bf16 v[100:103], v[154:157], v[194:197], v[100:103]
	v_mfma_f32_16x16x32_bf16 v[96:99], v[162:165], v[194:197], v[96:99]
	v_mfma_f32_16x16x32_bf16 v[124:127], v[158:161], v[174:177], v[124:127]
	v_mfma_f32_16x16x32_bf16 v[120:123], v[166:169], v[174:177], v[120:123]
	v_mfma_f32_16x16x32_bf16 v[116:119], v[158:161], v[182:185], v[116:119]
	v_mfma_f32_16x16x32_bf16 v[112:115], v[166:169], v[182:185], v[112:115]
	v_mfma_f32_16x16x32_bf16 v[108:111], v[158:161], v[190:193], v[108:111]
	v_mfma_f32_16x16x32_bf16 v[104:107], v[166:169], v[190:193], v[104:107]
	v_mfma_f32_16x16x32_bf16 v[100:103], v[158:161], v[198:201], v[100:103]
	v_mfma_f32_16x16x32_bf16 v[96:99], v[166:169], v[198:201], v[96:99]
	s_barrier
	s_add_i32 s44, s39, s17
	s_add_i32 s45, s44, 0x100
	s_mov_b32 s10, s6
	s_mov_b32 s11, s7
	s_mov_b32 m0, s1
	ds_read_b128 v[202:205], v145
	ds_read_b128 v[206:209], v146
	ds_read_b128 v[210:213], v147
	ds_read_b128 v[214:217], v148
	buffer_load_dwordx4 v143, s[8:11], s45 offen lds
	s_mov_b32 m0, s3
	s_nop 0
	buffer_load_dwordx4 v144, s[8:11], s45 offen lds
	s_barrier
	s_waitcnt lgkmcnt(0)
	v_mfma_f32_16x16x32_bf16 v[92:95], v[202:205], v[170:173], v[92:95]
	v_mfma_f32_16x16x32_bf16 v[88:91], v[210:213], v[170:173], v[88:91]
	v_mfma_f32_16x16x32_bf16 v[84:87], v[202:205], v[178:181], v[84:87]
	v_mfma_f32_16x16x32_bf16 v[80:83], v[210:213], v[178:181], v[80:83]
	v_mfma_f32_16x16x32_bf16 v[76:79], v[202:205], v[186:189], v[76:79]
	v_mfma_f32_16x16x32_bf16 v[72:75], v[210:213], v[186:189], v[72:75]
	v_mfma_f32_16x16x32_bf16 v[68:71], v[202:205], v[194:197], v[68:71]
	v_mfma_f32_16x16x32_bf16 v[64:67], v[210:213], v[194:197], v[64:67]
	v_mfma_f32_16x16x32_bf16 v[92:95], v[206:209], v[174:177], v[92:95]
	v_mfma_f32_16x16x32_bf16 v[88:91], v[214:217], v[174:177], v[88:91]
	v_mfma_f32_16x16x32_bf16 v[84:87], v[206:209], v[182:185], v[84:87]
	v_mfma_f32_16x16x32_bf16 v[80:83], v[214:217], v[182:185], v[80:83]
	v_mfma_f32_16x16x32_bf16 v[76:79], v[206:209], v[190:193], v[76:79]
	v_mfma_f32_16x16x32_bf16 v[72:75], v[214:217], v[190:193], v[72:75]
	v_mfma_f32_16x16x32_bf16 v[68:71], v[206:209], v[198:201], v[68:71]
	v_mfma_f32_16x16x32_bf16 v[64:67], v[214:217], v[198:201], v[64:67]
	s_add_i32 s45, s38, s17
	s_add_i32 s46, s45, 0x100
	s_mov_b32 m0, s0
	s_barrier
	ds_read_b128 v[170:173], v131 offset:16384
	ds_read_b128 v[174:177], v131 offset:17408
	ds_read_b128 v[178:181], v134 offset:16384
	ds_read_b128 v[182:185], v134 offset:17408
	ds_read_b128 v[186:189], v133 offset:16384
	ds_read_b128 v[190:193], v133 offset:17408
	ds_read_b128 v[194:197], v132 offset:16384
	ds_read_b128 v[198:201], v132 offset:17408
	buffer_load_dwordx4 v143, s[4:7], s46 offen lds
	s_mov_b32 m0, s18
	s_nop 0
	buffer_load_dwordx4 v144, s[4:7], s46 offen lds
	s_barrier
	s_waitcnt lgkmcnt(0)
	v_mfma_f32_16x16x32_bf16 v[60:63], v[154:157], v[170:173], v[60:63]
	v_mfma_f32_16x16x32_bf16 v[56:59], v[162:165], v[170:173], v[56:59]
	v_mfma_f32_16x16x32_bf16 v[52:55], v[154:157], v[178:181], v[52:55]
	v_mfma_f32_16x16x32_bf16 v[48:51], v[162:165], v[178:181], v[48:51]
	v_mfma_f32_16x16x32_bf16 v[44:47], v[154:157], v[186:189], v[44:47]
	v_mfma_f32_16x16x32_bf16 v[40:43], v[162:165], v[186:189], v[40:43]
	v_mfma_f32_16x16x32_bf16 v[36:39], v[154:157], v[194:197], v[36:39]
	v_mfma_f32_16x16x32_bf16 v[32:35], v[162:165], v[194:197], v[32:35]
	v_mfma_f32_16x16x32_bf16 v[60:63], v[158:161], v[174:177], v[60:63]
	v_mfma_f32_16x16x32_bf16 v[56:59], v[166:169], v[174:177], v[56:59]
	v_mfma_f32_16x16x32_bf16 v[52:55], v[158:161], v[182:185], v[52:55]
	v_mfma_f32_16x16x32_bf16 v[48:51], v[166:169], v[182:185], v[48:51]
	v_mfma_f32_16x16x32_bf16 v[44:47], v[158:161], v[190:193], v[44:47]
	v_mfma_f32_16x16x32_bf16 v[40:43], v[166:169], v[190:193], v[40:43]
	v_mfma_f32_16x16x32_bf16 v[36:39], v[158:161], v[198:201], v[36:39]
	v_mfma_f32_16x16x32_bf16 v[32:35], v[166:169], v[198:201], v[32:35]
	s_barrier
	s_add_i32 s46, s40, s17
	s_add_i32 s47, s46, 0x100
	s_mov_b32 m0, s19
	s_nop 0
	buffer_load_dwordx4 v143, s[8:11], s47 offen lds
	s_mov_b32 m0, s20
	s_nop 0
	buffer_load_dwordx4 v144, s[8:11], s47 offen lds
	s_waitcnt vmcnt(6)
	s_barrier
; #define STAGE(P, RS, SOFF, OFF, kt) do { const int _so = (SOFF) + (kt) * (BK * 2); \
;     _Pragma("unroll") for (int _i = 0; _i < 2; ++_i) { \
;       __builtin_amdgcn_raw_ptr_buffer_load_lds(RS, (__attribute__((address_space(3))) void*)((P) + wave * 1024 + _i * 8192), 16, OFF[_i], _so, 0, 0); } } while (0)
; #define LDA(dst, b, h) _Pragma("unroll") for (int m = 0; m < 4; ++m) _Pragma("unroll") for (int k = 0; k < 2; ++k) \
;     dst[m][k] = *reinterpret_cast<const bf16x8*>(SA(b, h) + lds_byte(wr * 64 + m * 16 + fr, k * 32 + fq * 8))
; #define LDB(dst, b, h) _Pragma("unroll") for (int n = 0; n < 2; ++n) _Pragma("unroll") for (int k = 0; k < 2; ++k) \
;     dst[n][k] = *reinterpret_cast<const bf16x8*>(SB(b, h) + lds_byte(wc * 32 + n * 16 + fr, k * 32 + fq * 8))
; #define WAIT_V(n) asm volatile("s_waitcnt vmcnt(" #n ")" ::: "memory")
; #define WAIT_L(n) asm volatile("s_waitcnt lgkmcnt(" #n ")" ::: "memory")
; #define BAR __builtin_amdgcn_s_barrier()
; #define SCHED __builtin_amdgcn_sched_barrier(0)
;     ...
;       WAIT_V(6); BAR; MMA(1, 1, At, B1); BAR;
;       LDB(B0, 1, 0); SCHED; LDA(At, 1, 0); STAGE(SA(0, 1), rsA, sA1, offA, t + 2);
;       WAIT_L(8); BAR; WAIT_L(0); MMA(0, 0, At, B0); BAR; SCHED;
;       LDB(B1, 1, 1); STAGE(SB(1, 0), rsB, sB0, offB, t + 3);
;       BAR; WAIT_L(0); MMA(0, 1, At, B1); BAR;
;       LDA(At, 1, 1); STAGE(SA(1, 0), rsA, sA0, offA, t + 3);
;       BAR; WAIT_L(0); MMA(1, 0, At, B0); BAR; SCHED;
;       STAGE(SB(1, 1), rsB, sB1, offB, t + 3);
;       WAIT_V(6); BAR; MMA(1, 1, At, B1); BAR;
	v_mfma_f32_16x16x32_bf16 v[28:31], v[202:205], v[170:173], v[28:31]
	v_mfma_f32_16x16x32_bf16 v[24:27], v[210:213], v[170:173], v[24:27]
	v_mfma_f32_16x16x32_bf16 v[20:23], v[202:205], v[178:181], v[20:23]
	v_mfma_f32_16x16x32_bf16 v[16:19], v[210:213], v[178:181], v[16:19]
	v_mfma_f32_16x16x32_bf16 v[12:15], v[202:205], v[186:189], v[12:15]
	v_mfma_f32_16x16x32_bf16 v[8:11], v[210:213], v[186:189], v[8:11]
	v_mfma_f32_16x16x32_bf16 v[4:7], v[202:205], v[194:197], v[4:7]
	v_mfma_f32_16x16x32_bf16 v[0:3], v[210:213], v[194:197], v[0:3]
	v_mfma_f32_16x16x32_bf16 v[28:31], v[206:209], v[174:177], v[28:31]
	v_mfma_f32_16x16x32_bf16 v[24:27], v[214:217], v[174:177], v[24:27]
	v_mfma_f32_16x16x32_bf16 v[20:23], v[206:209], v[182:185], v[20:23]
	v_mfma_f32_16x16x32_bf16 v[16:19], v[214:217], v[182:185], v[16:19]
	v_mfma_f32_16x16x32_bf16 v[12:15], v[206:209], v[190:193], v[12:15]
	v_mfma_f32_16x16x32_bf16 v[8:11], v[214:217], v[190:193], v[8:11]
	v_mfma_f32_16x16x32_bf16 v[4:7], v[206:209], v[198:201], v[4:7]
	v_mfma_f32_16x16x32_bf16 v[0:3], v[214:217], v[198:201], v[0:3]
	s_barrier
	ds_read_b128 v[154:157], v139
	ds_read_b128 v[158:161], v140
	ds_read_b128 v[162:165], v141
	ds_read_b128 v[166:169], v142
	s_addk_i32 s43, 0x100
	s_mov_b32 m0, s21
	ds_read_b128 v[170:173], v131 offset:32768
	ds_read_b128 v[174:177], v131 offset:33792
	ds_read_b128 v[178:181], v134 offset:32768
	ds_read_b128 v[182:185], v134 offset:33792
	ds_read_b128 v[186:189], v133 offset:32768
	ds_read_b128 v[190:193], v133 offset:33792
	ds_read_b128 v[194:197], v132 offset:32768
	ds_read_b128 v[198:201], v132 offset:33792
	buffer_load_dwordx4 v143, s[4:7], s43 offen lds
	s_mov_b32 m0, s22
	s_nop 0
	buffer_load_dwordx4 v144, s[4:7], s43 offen lds
	s_waitcnt lgkmcnt(8)
	s_barrier
	s_waitcnt lgkmcnt(0)
	v_mfma_f32_16x16x32_bf16 v[124:127], v[154:157], v[170:173], v[124:127]
	v_mfma_f32_16x16x32_bf16 v[120:123], v[162:165], v[170:173], v[120:123]
	v_mfma_f32_16x16x32_bf16 v[116:119], v[154:157], v[178:181], v[116:119]
	v_mfma_f32_16x16x32_bf16 v[112:115], v[162:165], v[178:181], v[112:115]
	v_mfma_f32_16x16x32_bf16 v[108:111], v[154:157], v[186:189], v[108:111]
	v_mfma_f32_16x16x32_bf16 v[104:107], v[162:165], v[186:189], v[104:107]
	v_mfma_f32_16x16x32_bf16 v[100:103], v[154:157], v[194:197], v[100:103]
	v_mfma_f32_16x16x32_bf16 v[96:99], v[162:165], v[194:197], v[96:99]
	v_mfma_f32_16x16x32_bf16 v[124:127], v[158:161], v[174:177], v[124:127]
	v_mfma_f32_16x16x32_bf16 v[120:123], v[166:169], v[174:177], v[120:123]
	v_mfma_f32_16x16x32_bf16 v[116:119], v[158:161], v[182:185], v[116:119]
	v_mfma_f32_16x16x32_bf16 v[112:115], v[166:169], v[182:185], v[112:115]
	v_mfma_f32_16x16x32_bf16 v[108:111], v[158:161], v[190:193], v[108:111]
	v_mfma_f32_16x16x32_bf16 v[104:107], v[166:169], v[190:193], v[104:107]
	v_mfma_f32_16x16x32_bf16 v[100:103], v[158:161], v[198:201], v[100:103]
	v_mfma_f32_16x16x32_bf16 v[96:99], v[166:169], v[198:201], v[96:99]
	s_barrier
	s_addk_i32 s44, 0x180
	s_mov_b32 m0, s23
	ds_read_b128 v[202:205], v135
	ds_read_b128 v[206:209], v136
	ds_read_b128 v[210:213], v137
	ds_read_b128 v[214:217], v138
	buffer_load_dwordx4 v143, s[8:11], s44 offen lds
	s_mov_b32 m0, s24
	s_nop 0
	buffer_load_dwordx4 v144, s[8:11], s44 offen lds
	s_barrier
	s_waitcnt lgkmcnt(0)
	v_mfma_f32_16x16x32_bf16 v[92:95], v[202:205], v[170:173], v[92:95]
	v_mfma_f32_16x16x32_bf16 v[88:91], v[210:213], v[170:173], v[88:91]
	v_mfma_f32_16x16x32_bf16 v[84:87], v[202:205], v[178:181], v[84:87]
	v_mfma_f32_16x16x32_bf16 v[80:83], v[210:213], v[178:181], v[80:83]
	v_mfma_f32_16x16x32_bf16 v[76:79], v[202:205], v[186:189], v[76:79]
	v_mfma_f32_16x16x32_bf16 v[72:75], v[210:213], v[186:189], v[72:75]
	v_mfma_f32_16x16x32_bf16 v[68:71], v[202:205], v[194:197], v[68:71]
	v_mfma_f32_16x16x32_bf16 v[64:67], v[210:213], v[194:197], v[64:67]
	v_mfma_f32_16x16x32_bf16 v[92:95], v[206:209], v[174:177], v[92:95]
	v_mfma_f32_16x16x32_bf16 v[88:91], v[214:217], v[174:177], v[88:91]
	v_mfma_f32_16x16x32_bf16 v[84:87], v[206:209], v[182:185], v[84:87]
	v_mfma_f32_16x16x32_bf16 v[80:83], v[214:217], v[182:185], v[80:83]
	v_mfma_f32_16x16x32_bf16 v[76:79], v[206:209], v[190:193], v[76:79]
	v_mfma_f32_16x16x32_bf16 v[72:75], v[214:217], v[190:193], v[72:75]
	v_mfma_f32_16x16x32_bf16 v[68:71], v[206:209], v[198:201], v[68:71]
	v_mfma_f32_16x16x32_bf16 v[64:67], v[214:217], v[198:201], v[64:67]
	s_addk_i32 s45, 0x180
	s_mov_b32 m0, s25
	s_barrier
	ds_read_b128 v[170:173], v131 offset:49152
	ds_read_b128 v[174:177], v131 offset:50176
	ds_read_b128 v[178:181], v134 offset:49152
	ds_read_b128 v[182:185], v134 offset:50176
	ds_read_b128 v[186:189], v133 offset:49152
	ds_read_b128 v[190:193], v133 offset:50176
	ds_read_b128 v[194:197], v132 offset:49152
	ds_read_b128 v[198:201], v132 offset:50176
	buffer_load_dwordx4 v143, s[4:7], s45 offen lds
	s_mov_b32 m0, s26
	s_nop 0
	buffer_load_dwordx4 v144, s[4:7], s45 offen lds
	s_barrier
	s_waitcnt lgkmcnt(0)
	v_mfma_f32_16x16x32_bf16 v[60:63], v[154:157], v[170:173], v[60:63]
	v_mfma_f32_16x16x32_bf16 v[56:59], v[162:165], v[170:173], v[56:59]
	v_mfma_f32_16x16x32_bf16 v[52:55], v[154:157], v[178:181], v[52:55]
	v_mfma_f32_16x16x32_bf16 v[48:51], v[162:165], v[178:181], v[48:51]
	v_mfma_f32_16x16x32_bf16 v[44:47], v[154:157], v[186:189], v[44:47]
	v_mfma_f32_16x16x32_bf16 v[40:43], v[162:165], v[186:189], v[40:43]
	v_mfma_f32_16x16x32_bf16 v[36:39], v[154:157], v[194:197], v[36:39]
	v_mfma_f32_16x16x32_bf16 v[32:35], v[162:165], v[194:197], v[32:35]
	v_mfma_f32_16x16x32_bf16 v[60:63], v[158:161], v[174:177], v[60:63]
	v_mfma_f32_16x16x32_bf16 v[56:59], v[166:169], v[174:177], v[56:59]
	v_mfma_f32_16x16x32_bf16 v[52:55], v[158:161], v[182:185], v[52:55]
	v_mfma_f32_16x16x32_bf16 v[48:51], v[166:169], v[182:185], v[48:51]
	v_mfma_f32_16x16x32_bf16 v[44:47], v[158:161], v[190:193], v[44:47]
	v_mfma_f32_16x16x32_bf16 v[40:43], v[166:169], v[190:193], v[40:43]
	v_mfma_f32_16x16x32_bf16 v[36:39], v[158:161], v[198:201], v[36:39]
	v_mfma_f32_16x16x32_bf16 v[32:35], v[166:169], v[198:201], v[32:35]
	s_barrier
; #define STAGE(P, RS, SOFF, OFF, kt) do { const int _so = (SOFF) + (kt) * (BK * 2); \
;     _Pragma("unroll") for (int _i = 0; _i < 2; ++_i) { \
;       __builtin_amdgcn_raw_ptr_buffer_load_lds(RS, (__attribute__((address_space(3))) void*)((P) + wave * 1024 + _i * 8192), 16, OFF[_i], _so, 0, 0); } } while (0)
; #define LDA(dst, b, h) _Pragma("unroll") for (int m = 0; m < 4; ++m) _Pragma("unroll") for (int k = 0; k < 2; ++k) \
;     dst[m][k] = *reinterpret_cast<const bf16x8*>(SA(b, h) + lds_byte(wr * 64 + m * 16 + fr, k * 32 + fq * 8))
; #define LDB(dst, b, h) _Pragma("unroll") for (int n = 0; n < 2; ++n) _Pragma("unroll") for (int k = 0; k < 2; ++k) \
;     dst[n][k] = *reinterpret_cast<const bf16x8*>(SB(b, h) + lds_byte(wc * 32 + n * 16 + fr, k * 32 + fq * 8))
; #define WAIT_V(n) asm volatile("s_waitcnt vmcnt(" #n ")" ::: "memory")
; #define WAIT_L(n) asm volatile("s_waitcnt lgkmcnt(" #n ")" ::: "memory")
; #define BAR __builtin_amdgcn_s_barrier()
;     ...
;       STAGE(SB(1, 1), rsB, sB1, offB, t + 3);
;       WAIT_V(6); BAR; MMA(1, 1, At, B1); BAR;
;     }
;     { LDB(B0, 0, 0); LDA(At, 0, 0); STAGE(SA(1, 1), rsA, sA1, offA, nt - 1);
;       BAR; WAIT_L(0); MMA(0, 0, At, B0); BAR;
;       LDB(B1, 0, 1); BAR; WAIT_L(0); MMA(0, 1, At, B1); BAR;
;       LDA(At, 0, 1); WAIT_V(4); BAR; WAIT_L(0); MMA(1, 0, At, B0); MMA(1, 1, At, B1); BAR; }
	s_addk_i32 s46, 0x180
	s_mov_b32 m0, s27
	s_nop 0
	buffer_load_dwordx4 v143, s[8:11], s46 offen lds
	s_mov_b32 m0, s28
	s_nop 0
	buffer_load_dwordx4 v144, s[8:11], s46 offen lds
	s_waitcnt vmcnt(6)
	s_barrier
	v_mfma_f32_16x16x32_bf16 v[28:31], v[202:205], v[170:173], v[28:31]
	v_mfma_f32_16x16x32_bf16 v[24:27], v[210:213], v[170:173], v[24:27]
	v_mfma_f32_16x16x32_bf16 v[20:23], v[202:205], v[178:181], v[20:23]
	v_mfma_f32_16x16x32_bf16 v[16:19], v[210:213], v[178:181], v[16:19]
	v_mfma_f32_16x16x32_bf16 v[12:15], v[202:205], v[186:189], v[12:15]
	v_mfma_f32_16x16x32_bf16 v[8:11], v[210:213], v[186:189], v[8:11]
	v_mfma_f32_16x16x32_bf16 v[4:7], v[202:205], v[194:197], v[4:7]
	v_mfma_f32_16x16x32_bf16 v[0:3], v[210:213], v[194:197], v[0:3]
	v_mfma_f32_16x16x32_bf16 v[28:31], v[206:209], v[174:177], v[28:31]
	v_mfma_f32_16x16x32_bf16 v[24:27], v[214:217], v[174:177], v[24:27]
	v_mfma_f32_16x16x32_bf16 v[20:23], v[206:209], v[182:185], v[20:23]
	v_mfma_f32_16x16x32_bf16 v[16:19], v[214:217], v[182:185], v[16:19]
	v_mfma_f32_16x16x32_bf16 v[12:15], v[206:209], v[190:193], v[12:15]
	v_mfma_f32_16x16x32_bf16 v[8:11], v[214:217], v[190:193], v[8:11]
	v_mfma_f32_16x16x32_bf16 v[4:7], v[206:209], v[198:201], v[4:7]
	v_mfma_f32_16x16x32_bf16 v[0:3], v[214:217], v[198:201], v[0:3]
	s_add_i32 s16, s16, 2
	s_addk_i32 s17, 0x100
	s_cmp_gt_u32 s16, 27
	s_barrier
	s_cbranch_scc0 .LBB0_354
	s_add_i32 s10, s37, 0xf80
	s_mov_b32 m0, s30
	ds_read_b128 v[154:157], v149
	ds_read_b128 v[158:161], v150
	ds_read_b128 v[162:165], v151
	ds_read_b128 v[150:153], v152
	ds_read_b128 v[166:169], v131
	ds_read_b128 v[170:173], v131 offset:1024
	ds_read_b128 v[174:177], v134
	ds_read_b128 v[178:181], v134 offset:1024
	ds_read_b128 v[182:185], v133
	ds_read_b128 v[186:189], v133 offset:1024
	ds_read_b128 v[190:193], v132
	ds_read_b128 v[194:197], v132 offset:1024
	buffer_load_dwordx4 v143, s[4:7], s10 offen lds
	s_mov_b32 m0, s31
	s_nop 0
	buffer_load_dwordx4 v144, s[4:7], s10 offen lds
	s_barrier
	s_waitcnt lgkmcnt(0)
	v_mfma_f32_16x16x32_bf16 v[124:127], v[154:157], v[166:169], v[124:127]
	v_mfma_f32_16x16x32_bf16 v[120:123], v[162:165], v[166:169], v[120:123]
	v_mfma_f32_16x16x32_bf16 v[116:119], v[154:157], v[174:177], v[116:119]
	v_mfma_f32_16x16x32_bf16 v[112:115], v[162:165], v[174:177], v[112:115]
	v_mfma_f32_16x16x32_bf16 v[108:111], v[154:157], v[182:185], v[108:111]
	v_mfma_f32_16x16x32_bf16 v[104:107], v[162:165], v[182:185], v[104:107]
	v_mfma_f32_16x16x32_bf16 v[100:103], v[154:157], v[190:193], v[100:103]
	v_mfma_f32_16x16x32_bf16 v[96:99], v[162:165], v[190:193], v[96:99]
	v_mfma_f32_16x16x32_bf16 v[124:127], v[158:161], v[170:173], v[124:127]
	v_mfma_f32_16x16x32_bf16 v[120:123], v[150:153], v[170:173], v[120:123]
	v_mfma_f32_16x16x32_bf16 v[116:119], v[158:161], v[178:181], v[116:119]
	v_mfma_f32_16x16x32_bf16 v[112:115], v[150:153], v[178:181], v[112:115]
	v_mfma_f32_16x16x32_bf16 v[108:111], v[158:161], v[186:189], v[108:111]
	v_mfma_f32_16x16x32_bf16 v[104:107], v[150:153], v[186:189], v[104:107]
	v_mfma_f32_16x16x32_bf16 v[100:103], v[158:161], v[194:197], v[100:103]
	v_mfma_f32_16x16x32_bf16 v[96:99], v[150:153], v[194:197], v[96:99]
	s_barrier
	ds_read_b128 v[198:201], v145
	ds_read_b128 v[202:205], v146
	ds_read_b128 v[144:147], v147
	ds_read_b128 v[206:209], v148
	s_barrier
	s_waitcnt lgkmcnt(0)
	v_mfma_f32_16x16x32_bf16 v[92:95], v[198:201], v[166:169], v[92:95]
	v_mfma_f32_16x16x32_bf16 v[84:87], v[198:201], v[174:177], v[84:87]
	v_mfma_f32_16x16x32_bf16 v[76:79], v[198:201], v[182:185], v[76:79]
	v_mfma_f32_16x16x32_bf16 v[68:71], v[198:201], v[190:193], v[68:71]
	v_mfma_f32_16x16x32_bf16 v[88:91], v[144:147], v[166:169], v[88:91]
	v_mfma_f32_16x16x32_bf16 v[80:83], v[144:147], v[174:177], v[80:83]
	v_mfma_f32_16x16x32_bf16 v[72:75], v[144:147], v[182:185], v[72:75]
	v_mfma_f32_16x16x32_bf16 v[64:67], v[144:147], v[190:193], v[64:67]
	v_mfma_f32_16x16x32_bf16 v[92:95], v[202:205], v[170:173], v[92:95]
	v_mfma_f32_16x16x32_bf16 v[84:87], v[202:205], v[178:181], v[84:87]
	v_mfma_f32_16x16x32_bf16 v[76:79], v[202:205], v[186:189], v[76:79]
	v_mfma_f32_16x16x32_bf16 v[68:71], v[202:205], v[194:197], v[68:71]
	v_mfma_f32_16x16x32_bf16 v[166:169], v[206:209], v[170:173], v[88:91]
	v_mfma_f32_16x16x32_bf16 v[170:173], v[206:209], v[178:181], v[80:83]
	v_mfma_f32_16x16x32_bf16 v[174:177], v[206:209], v[186:189], v[72:75]
	v_mfma_f32_16x16x32_bf16 v[178:181], v[206:209], v[194:197], v[64:67]
	s_barrier
	s_nop 0
	ds_read_b128 v[64:67], v131 offset:16384
	ds_read_b128 v[72:75], v131 offset:17408
	ds_read_b128 v[80:83], v134 offset:16384
	ds_read_b128 v[88:91], v134 offset:17408
	ds_read_b128 v[182:185], v133 offset:16384
	ds_read_b128 v[186:189], v133 offset:17408
	ds_read_b128 v[190:193], v132 offset:16384
	ds_read_b128 v[194:197], v132 offset:17408
	s_waitcnt vmcnt(4)
	s_barrier
; #define LDA(dst, b, h) _Pragma("unroll") for (int m = 0; m < 4; ++m) _Pragma("unroll") for (int k = 0; k < 2; ++k) \
;     dst[m][k] = *reinterpret_cast<const bf16x8*>(SA(b, h) + lds_byte(wr * 64 + m * 16 + fr, k * 32 + fq * 8))
; #define LDB(dst, b, h) _Pragma("unroll") for (int n = 0; n < 2; ++n) _Pragma("unroll") for (int k = 0; k < 2; ++k) \
;     dst[n][k] = *reinterpret_cast<const bf16x8*>(SB(b, h) + lds_byte(wc * 32 + n * 16 + fr, k * 32 + fq * 8))
; #define WAIT_V(n) asm volatile("s_waitcnt vmcnt(" #n ")" ::: "memory")
; #define WAIT_L(n) asm volatile("s_waitcnt lgkmcnt(" #n ")" ::: "memory")
; #define BAR __builtin_amdgcn_s_barrier()
;     ...
;       LDA(At, 0, 1); WAIT_V(4); BAR; WAIT_L(0); MMA(1, 0, At, B0); MMA(1, 1, At, B1); BAR; }
;     { LDB(B0, 1, 0); LDA(At, 1, 0); WAIT_V(2); BAR; WAIT_L(0); MMA(0, 0, At, B0); BAR;
;       LDB(B1, 1, 1); WAIT_V(0); BAR; WAIT_L(0); MMA(0, 1, At, B1); BAR;
	s_waitcnt lgkmcnt(0)
	v_mfma_f32_16x16x32_bf16 v[60:63], v[154:157], v[64:67], v[60:63]
	v_mfma_f32_16x16x32_bf16 v[56:59], v[162:165], v[64:67], v[56:59]
	v_mfma_f32_16x16x32_bf16 v[52:55], v[154:157], v[80:83], v[52:55]
	v_mfma_f32_16x16x32_bf16 v[48:51], v[162:165], v[80:83], v[48:51]
	v_mfma_f32_16x16x32_bf16 v[44:47], v[154:157], v[182:185], v[44:47]
	v_mfma_f32_16x16x32_bf16 v[40:43], v[162:165], v[182:185], v[40:43]
	v_mfma_f32_16x16x32_bf16 v[36:39], v[154:157], v[190:193], v[36:39]
	v_mfma_f32_16x16x32_bf16 v[32:35], v[162:165], v[190:193], v[32:35]
	v_mfma_f32_16x16x32_bf16 v[60:63], v[158:161], v[72:75], v[60:63]
	v_mfma_f32_16x16x32_bf16 v[56:59], v[150:153], v[72:75], v[56:59]
	v_mfma_f32_16x16x32_bf16 v[52:55], v[158:161], v[88:91], v[52:55]
	v_mfma_f32_16x16x32_bf16 v[48:51], v[150:153], v[88:91], v[48:51]
	v_mfma_f32_16x16x32_bf16 v[44:47], v[158:161], v[186:189], v[44:47]
	v_mfma_f32_16x16x32_bf16 v[40:43], v[150:153], v[186:189], v[40:43]
	v_mfma_f32_16x16x32_bf16 v[36:39], v[158:161], v[194:197], v[36:39]
	v_mfma_f32_16x16x32_bf16 v[32:35], v[150:153], v[194:197], v[32:35]
	v_mfma_f32_16x16x32_bf16 v[28:31], v[198:201], v[64:67], v[28:31]
	v_mfma_f32_16x16x32_bf16 v[20:23], v[198:201], v[80:83], v[20:23]
	v_mfma_f32_16x16x32_bf16 v[12:15], v[198:201], v[182:185], v[12:15]
	v_mfma_f32_16x16x32_bf16 v[4:7], v[198:201], v[190:193], v[4:7]
	v_mfma_f32_16x16x32_bf16 v[24:27], v[144:147], v[64:67], v[24:27]
	v_mfma_f32_16x16x32_bf16 v[16:19], v[144:147], v[80:83], v[16:19]
	v_mfma_f32_16x16x32_bf16 v[8:11], v[144:147], v[182:185], v[8:11]
	v_mfma_f32_16x16x32_bf16 v[0:3], v[144:147], v[190:193], v[0:3]
	v_mfma_f32_16x16x32_bf16 v[28:31], v[202:205], v[72:75], v[28:31]
	v_mfma_f32_16x16x32_bf16 v[20:23], v[202:205], v[88:91], v[20:23]
	v_mfma_f32_16x16x32_bf16 v[12:15], v[202:205], v[186:189], v[12:15]
	v_mfma_f32_16x16x32_bf16 v[4:7], v[202:205], v[194:197], v[4:7]
	v_mfma_f32_16x16x32_bf16 v[144:147], v[206:209], v[72:75], v[24:27]
	v_mfma_f32_16x16x32_bf16 v[148:151], v[206:209], v[88:91], v[16:19]
	v_mfma_f32_16x16x32_bf16 v[152:155], v[206:209], v[186:189], v[8:11]
	v_mfma_f32_16x16x32_bf16 v[156:159], v[206:209], v[194:197], v[0:3]
	s_barrier
	s_nop 0
	ds_read_b128 v[0:3], v139
	ds_read_b128 v[8:11], v140
	ds_read_b128 v[16:19], v141
	ds_read_b128 v[140:143], v142
	ds_read_b128 v[24:27], v131 offset:32768
	ds_read_b128 v[160:163], v131 offset:33792
	ds_read_b128 v[182:185], v134 offset:32768
	ds_read_b128 v[186:189], v134 offset:33792
	ds_read_b128 v[190:193], v133 offset:32768
	ds_read_b128 v[194:197], v133 offset:33792
	ds_read_b128 v[198:201], v132 offset:32768
	ds_read_b128 v[202:205], v132 offset:33792
	s_waitcnt vmcnt(2)
	s_barrier
	s_waitcnt lgkmcnt(0)
	v_mfma_f32_16x16x32_bf16 v[64:67], v[0:3], v[24:27], v[124:127]
	v_mfma_f32_16x16x32_bf16 v[72:75], v[16:19], v[24:27], v[120:123]
	v_mfma_f32_16x16x32_bf16 v[80:83], v[0:3], v[182:185], v[116:119]
	v_mfma_f32_16x16x32_bf16 v[88:91], v[16:19], v[182:185], v[112:115]
	v_mfma_f32_16x16x32_bf16 v[108:111], v[0:3], v[190:193], v[108:111]
	v_mfma_f32_16x16x32_bf16 v[116:119], v[16:19], v[190:193], v[104:107]
	v_mfma_f32_16x16x32_bf16 v[100:103], v[0:3], v[198:201], v[100:103]
	v_mfma_f32_16x16x32_bf16 v[124:127], v[16:19], v[198:201], v[96:99]
	v_mfma_f32_16x16x32_bf16 v[120:123], v[8:11], v[160:163], v[64:67]
	v_mfma_f32_16x16x32_bf16 v[112:115], v[140:143], v[160:163], v[72:75]
	v_mfma_f32_16x16x32_bf16 v[104:107], v[8:11], v[186:189], v[80:83]
	v_mfma_f32_16x16x32_bf16 v[96:99], v[140:143], v[186:189], v[88:91]
	v_mfma_f32_16x16x32_bf16 v[88:91], v[8:11], v[194:197], v[108:111]
	v_mfma_f32_16x16x32_bf16 v[80:83], v[140:143], v[194:197], v[116:119]
	v_mfma_f32_16x16x32_bf16 v[72:75], v[8:11], v[202:205], v[100:103]
	v_mfma_f32_16x16x32_bf16 v[64:67], v[140:143], v[202:205], v[124:127]
	s_barrier
	ds_read_b128 v[206:209], v135
	ds_read_b128 v[210:213], v136
	ds_read_b128 v[214:217], v137
	ds_read_b128 v[136:139], v138
	s_waitcnt vmcnt(0)
	s_barrier
; #define LDA(dst, b, h) _Pragma("unroll") for (int m = 0; m < 4; ++m) _Pragma("unroll") for (int k = 0; k < 2; ++k) \
;     dst[m][k] = *reinterpret_cast<const bf16x8*>(SA(b, h) + lds_byte(wr * 64 + m * 16 + fr, k * 32 + fq * 8))
; #define LDB(dst, b, h) _Pragma("unroll") for (int n = 0; n < 2; ++n) _Pragma("unroll") for (int k = 0; k < 2; ++k) \
;     dst[n][k] = *reinterpret_cast<const bf16x8*>(SB(b, h) + lds_byte(wc * 32 + n * 16 + fr, k * 32 + fq * 8))
; #define WAIT_V(n) asm volatile("s_waitcnt vmcnt(" #n ")" ::: "memory")
; #define WAIT_L(n) asm volatile("s_waitcnt lgkmcnt(" #n ")" ::: "memory")
; #define BAR __builtin_amdgcn_s_barrier()
;     ...
;       LDB(B1, 1, 1); WAIT_V(0); BAR; WAIT_L(0); MMA(0, 1, At, B1); BAR;
;       LDA(At, 1, 1); BAR; WAIT_L(0); MMA(1, 0, At, B0); MMA(1, 1, At, B1); BAR; }
;     if (wr == 0) BAR;
	s_waitcnt lgkmcnt(0)
	v_mfma_f32_16x16x32_bf16 v[92:95], v[206:209], v[24:27], v[92:95]
	v_mfma_f32_16x16x32_bf16 v[24:27], v[214:217], v[24:27], v[166:169]
	v_mfma_f32_16x16x32_bf16 v[84:87], v[206:209], v[182:185], v[84:87]
	v_mfma_f32_16x16x32_bf16 v[100:103], v[214:217], v[182:185], v[170:173]
	v_mfma_f32_16x16x32_bf16 v[76:79], v[206:209], v[190:193], v[76:79]
	v_mfma_f32_16x16x32_bf16 v[164:167], v[214:217], v[190:193], v[174:177]
	v_mfma_f32_16x16x32_bf16 v[68:71], v[206:209], v[198:201], v[68:71]
	v_mfma_f32_16x16x32_bf16 v[168:171], v[214:217], v[198:201], v[178:181]
	v_mfma_f32_16x16x32_bf16 v[124:127], v[210:213], v[160:163], v[92:95]
	v_mfma_f32_16x16x32_bf16 v[116:119], v[136:139], v[160:163], v[24:27]
	v_mfma_f32_16x16x32_bf16 v[108:111], v[210:213], v[186:189], v[84:87]
	v_mfma_f32_16x16x32_bf16 v[100:103], v[136:139], v[186:189], v[100:103]
	v_mfma_f32_16x16x32_bf16 v[92:95], v[210:213], v[194:197], v[76:79]
	v_mfma_f32_16x16x32_bf16 v[84:87], v[136:139], v[194:197], v[164:167]
	v_mfma_f32_16x16x32_bf16 v[76:79], v[210:213], v[202:205], v[68:71]
	v_mfma_f32_16x16x32_bf16 v[68:71], v[136:139], v[202:205], v[168:171]
	s_barrier
	ds_read_b128 v[160:163], v131 offset:49152
	ds_read_b128 v[164:167], v131 offset:50176
	ds_read_b128 v[168:171], v134 offset:49152
	ds_read_b128 v[172:175], v134 offset:50176
	ds_read_b128 v[176:179], v133 offset:49152
	ds_read_b128 v[180:183], v133 offset:50176
	ds_read_b128 v[184:187], v132 offset:49152
	ds_read_b128 v[132:135], v132 offset:50176
	s_barrier
	s_waitcnt lgkmcnt(0)
	v_mfma_f32_16x16x32_bf16 v[24:27], v[0:3], v[160:163], v[60:63]
	v_mfma_f32_16x16x32_bf16 v[60:63], v[16:19], v[160:163], v[56:59]
	v_mfma_f32_16x16x32_bf16 v[52:55], v[0:3], v[168:171], v[52:55]
	v_mfma_f32_16x16x32_bf16 v[188:191], v[16:19], v[168:171], v[48:51]
	v_mfma_f32_16x16x32_bf16 v[44:47], v[0:3], v[176:179], v[44:47]
	v_mfma_f32_16x16x32_bf16 v[192:195], v[16:19], v[176:179], v[40:43]
	v_mfma_f32_16x16x32_bf16 v[0:3], v[0:3], v[184:187], v[36:39]
	v_mfma_f32_16x16x32_bf16 v[36:39], v[16:19], v[184:187], v[32:35]
	v_mfma_f32_16x16x32_bf16 v[56:59], v[8:11], v[164:167], v[24:27]
	v_mfma_f32_16x16x32_bf16 v[48:51], v[140:143], v[164:167], v[60:63]
	v_mfma_f32_16x16x32_bf16 v[40:43], v[8:11], v[172:175], v[52:55]
	v_mfma_f32_16x16x32_bf16 v[32:35], v[140:143], v[172:175], v[188:191]
	v_mfma_f32_16x16x32_bf16 v[24:27], v[8:11], v[180:183], v[44:47]
	v_mfma_f32_16x16x32_bf16 v[16:19], v[140:143], v[180:183], v[192:195]
	v_mfma_f32_16x16x32_bf16 v[8:11], v[8:11], v[132:135], v[0:3]
	v_mfma_f32_16x16x32_bf16 v[0:3], v[140:143], v[132:135], v[36:39]
	v_mfma_f32_16x16x32_bf16 v[28:31], v[206:209], v[160:163], v[28:31]
	v_mfma_f32_16x16x32_bf16 v[36:39], v[214:217], v[160:163], v[144:147]
	v_mfma_f32_16x16x32_bf16 v[20:23], v[206:209], v[168:171], v[20:23]
	v_mfma_f32_16x16x32_bf16 v[140:143], v[214:217], v[168:171], v[148:151]
	v_mfma_f32_16x16x32_bf16 v[12:15], v[206:209], v[176:179], v[12:15]
	v_mfma_f32_16x16x32_bf16 v[144:147], v[214:217], v[176:179], v[152:155]
	v_mfma_f32_16x16x32_bf16 v[4:7], v[206:209], v[184:187], v[4:7]
	v_mfma_f32_16x16x32_bf16 v[148:151], v[214:217], v[184:187], v[156:159]
	v_mfma_f32_16x16x32_bf16 v[60:63], v[210:213], v[164:167], v[28:31]
	v_mfma_f32_16x16x32_bf16 v[52:55], v[136:139], v[164:167], v[36:39]
	v_mfma_f32_16x16x32_bf16 v[44:47], v[210:213], v[172:175], v[20:23]
	v_mfma_f32_16x16x32_bf16 v[36:39], v[136:139], v[172:175], v[140:143]
	v_mfma_f32_16x16x32_bf16 v[28:31], v[210:213], v[180:183], v[12:15]
	v_mfma_f32_16x16x32_bf16 v[20:23], v[136:139], v[180:183], v[144:147]
	v_mfma_f32_16x16x32_bf16 v[12:15], v[210:213], v[132:135], v[4:7]
	v_mfma_f32_16x16x32_bf16 v[4:7], v[136:139], v[132:135], v[148:151]
	v_cmp_gt_u32_e32 vcc, s35, v130
	s_barrier
	s_and_saveexec_b64 s[10:11], vcc
	s_cbranch_execz .LBB0_357
	s_barrier

; #define STAGE(P, RS, SOFF, OFF, kt) do { const int _so = (SOFF) + (kt) * (BK * 2); \
;     _Pragma("unroll") for (int _i = 0; _i < 2; ++_i) { \
;       __builtin_amdgcn_raw_ptr_buffer_load_lds(RS, (__attribute__((address_space(3))) void*)((P) + wave * 1024 + _i * 8192), 16, OFF[_i], _so, 0, 0); } } while (0)
; #define LDA(dst, b, h) _Pragma("unroll") for (int m = 0; m < 4; ++m) _Pragma("unroll") for (int k = 0; k < 2; ++k) \
;     dst[m][k] = *reinterpret_cast<const bf16x8*>(SA(b, h) + lds_byte(wr * 64 + m * 16 + fr, k * 32 + fq * 8))
; #define LDB(dst, b, h) _Pragma("unroll") for (int n = 0; n < 2; ++n) _Pragma("unroll") for (int k = 0; k < 2; ++k) \
;     dst[n][k] = *reinterpret_cast<const bf16x8*>(SB(b, h) + lds_byte(wc * 32 + n * 16 + fr, k * 32 + fq * 8))
; #define WAIT_V(n) asm volatile("s_waitcnt vmcnt(" #n ")" ::: "memory")
; #define WAIT_L(n) asm volatile("s_waitcnt lgkmcnt(" #n ")" ::: "memory")
; #define BAR __builtin_amdgcn_s_barrier()
; #define SCHED __builtin_amdgcn_sched_barrier(0)
;     ...
;     for (int t = 0; t < nt - 2; t += 2) {
;       LDB(B0, 0, 0); SCHED; LDA(At, 0, 0); STAGE(SA(1, 1), rsA, sA1, offA, t + 1);
;       WAIT_L(8); BAR; WAIT_L(0); MMA(0, 0, At, B0); BAR; SCHED;
;       LDB(B1, 0, 1); STAGE(SB(0, 0), rsB, sB0, offB, t + 2);
;       BAR; WAIT_L(0); MMA(0, 1, At, B1); BAR;
;       LDA(At, 0, 1); STAGE(SA(0, 0), rsA, sA0, offA, t + 2);
;       BAR; WAIT_L(0); MMA(1, 0, At, B0); BAR; SCHED;
;       STAGE(SB(0, 1), rsB, sB1, offB, t + 2);
;       WAIT_V(6); BAR; MMA(1, 1, At, B1); BAR;
.LBB0_392:
	ds_read_b128 v[152:155], v147
	ds_read_b128 v[156:159], v148
	ds_read_b128 v[160:163], v149
	ds_read_b128 v[164:167], v150
	s_add_i32 s5, s86, s3
	s_add_i32 s6, s5, 0x80
	s_mov_b32 m0, s36
	ds_read_b128 v[168:171], v129
	ds_read_b128 v[172:175], v129 offset:1024
	ds_read_b128 v[176:179], v132
	ds_read_b128 v[180:183], v132 offset:1024
	ds_read_b128 v[184:187], v131
	ds_read_b128 v[188:191], v131 offset:1024
	ds_read_b128 v[192:195], v130
	ds_read_b128 v[196:199], v130 offset:1024
	buffer_load_dwordx4 v141, s[8:11], s6 offen lds
	s_mov_b32 m0, s59
	s_nop 0
	buffer_load_dwordx4 v142, s[8:11], s6 offen lds
	s_waitcnt lgkmcnt(8)
	s_barrier
	s_waitcnt lgkmcnt(0)
	v_mfma_f32_16x16x32_bf16 v[124:127], v[152:155], v[168:171], v[124:127]
	v_mfma_f32_16x16x32_bf16 v[120:123], v[160:163], v[168:171], v[120:123]
	v_mfma_f32_16x16x32_bf16 v[116:119], v[152:155], v[176:179], v[116:119]
	v_mfma_f32_16x16x32_bf16 v[112:115], v[160:163], v[176:179], v[112:115]
	v_mfma_f32_16x16x32_bf16 v[108:111], v[152:155], v[184:187], v[108:111]
	v_mfma_f32_16x16x32_bf16 v[104:107], v[160:163], v[184:187], v[104:107]
	v_mfma_f32_16x16x32_bf16 v[100:103], v[152:155], v[192:195], v[100:103]
	v_mfma_f32_16x16x32_bf16 v[96:99], v[160:163], v[192:195], v[96:99]
	v_mfma_f32_16x16x32_bf16 v[124:127], v[156:159], v[172:175], v[124:127]
	v_mfma_f32_16x16x32_bf16 v[120:123], v[164:167], v[172:175], v[120:123]
	v_mfma_f32_16x16x32_bf16 v[116:119], v[156:159], v[180:183], v[116:119]
	v_mfma_f32_16x16x32_bf16 v[112:115], v[164:167], v[180:183], v[112:115]
	v_mfma_f32_16x16x32_bf16 v[108:111], v[156:159], v[188:191], v[108:111]
	v_mfma_f32_16x16x32_bf16 v[104:107], v[164:167], v[188:191], v[104:107]
	v_mfma_f32_16x16x32_bf16 v[100:103], v[156:159], v[196:199], v[100:103]
	v_mfma_f32_16x16x32_bf16 v[96:99], v[164:167], v[196:199], v[96:99]
	s_barrier
	s_add_i32 s6, s92, s3
	s_add_i32 s7, s6, 0x100
	s_mov_b32 s14, s10
	s_mov_b32 s15, s11
	s_mov_b32 m0, s37
	ds_read_b128 v[200:203], v143
	ds_read_b128 v[204:207], v144
	ds_read_b128 v[208:211], v145
	ds_read_b128 v[212:215], v146
	buffer_load_dwordx4 v141, s[12:15], s7 offen lds
	s_mov_b32 m0, s48
	s_nop 0
	buffer_load_dwordx4 v142, s[12:15], s7 offen lds
	s_barrier
	s_waitcnt lgkmcnt(0)
	v_mfma_f32_16x16x32_bf16 v[92:95], v[200:203], v[168:171], v[92:95]
	v_mfma_f32_16x16x32_bf16 v[88:91], v[208:211], v[168:171], v[88:91]
	v_mfma_f32_16x16x32_bf16 v[80:83], v[200:203], v[176:179], v[80:83]
	v_mfma_f32_16x16x32_bf16 v[68:71], v[208:211], v[176:179], v[68:71]
	v_mfma_f32_16x16x32_bf16 v[60:63], v[200:203], v[184:187], v[60:63]
	v_mfma_f32_16x16x32_bf16 v[56:59], v[208:211], v[184:187], v[56:59]
	v_mfma_f32_16x16x32_bf16 v[52:55], v[200:203], v[192:195], v[52:55]
	v_mfma_f32_16x16x32_bf16 v[48:51], v[208:211], v[192:195], v[48:51]
	v_mfma_f32_16x16x32_bf16 v[92:95], v[204:207], v[172:175], v[92:95]
	v_mfma_f32_16x16x32_bf16 v[88:91], v[212:215], v[172:175], v[88:91]
	v_mfma_f32_16x16x32_bf16 v[80:83], v[204:207], v[180:183], v[80:83]
	v_mfma_f32_16x16x32_bf16 v[68:71], v[212:215], v[180:183], v[68:71]
	v_mfma_f32_16x16x32_bf16 v[60:63], v[204:207], v[188:191], v[60:63]
	v_mfma_f32_16x16x32_bf16 v[56:59], v[212:215], v[188:191], v[56:59]
	v_mfma_f32_16x16x32_bf16 v[52:55], v[204:207], v[196:199], v[52:55]
	v_mfma_f32_16x16x32_bf16 v[48:51], v[212:215], v[196:199], v[48:51]
	s_add_i32 s7, s87, s3
	s_add_i32 s22, s7, 0x100
	s_mov_b32 m0, s35
	s_barrier
	ds_read_b128 v[168:171], v129 offset:16384
	ds_read_b128 v[172:175], v129 offset:17408
	ds_read_b128 v[176:179], v132 offset:16384
	ds_read_b128 v[180:183], v132 offset:17408
	ds_read_b128 v[184:187], v131 offset:16384
	ds_read_b128 v[188:191], v131 offset:17408
	ds_read_b128 v[192:195], v130 offset:16384
	ds_read_b128 v[196:199], v130 offset:17408
	buffer_load_dwordx4 v141, s[8:11], s22 offen lds
	s_mov_b32 m0, s49
	s_nop 0
	buffer_load_dwordx4 v142, s[8:11], s22 offen lds
	s_barrier
	s_waitcnt lgkmcnt(0)
	v_mfma_f32_16x16x32_bf16 v[44:47], v[152:155], v[168:171], v[44:47]
	v_mfma_f32_16x16x32_bf16 v[40:43], v[160:163], v[168:171], v[40:43]
	v_mfma_f32_16x16x32_bf16 v[36:39], v[152:155], v[176:179], v[36:39]
	v_mfma_f32_16x16x32_bf16 v[32:35], v[160:163], v[176:179], v[32:35]
	v_mfma_f32_16x16x32_bf16 v[28:31], v[152:155], v[184:187], v[28:31]
	v_mfma_f32_16x16x32_bf16 v[24:27], v[160:163], v[184:187], v[24:27]
	v_mfma_f32_16x16x32_bf16 v[20:23], v[152:155], v[192:195], v[20:23]
	v_mfma_f32_16x16x32_bf16 v[16:19], v[160:163], v[192:195], v[16:19]
	v_mfma_f32_16x16x32_bf16 v[44:47], v[156:159], v[172:175], v[44:47]
	v_mfma_f32_16x16x32_bf16 v[40:43], v[164:167], v[172:175], v[40:43]
	v_mfma_f32_16x16x32_bf16 v[36:39], v[156:159], v[180:183], v[36:39]
	v_mfma_f32_16x16x32_bf16 v[32:35], v[164:167], v[180:183], v[32:35]
	v_mfma_f32_16x16x32_bf16 v[28:31], v[156:159], v[188:191], v[28:31]
	v_mfma_f32_16x16x32_bf16 v[24:27], v[164:167], v[188:191], v[24:27]
	v_mfma_f32_16x16x32_bf16 v[20:23], v[156:159], v[196:199], v[20:23]
	v_mfma_f32_16x16x32_bf16 v[16:19], v[164:167], v[196:199], v[16:19]
	s_barrier
	s_add_i32 s22, s93, s3
	s_add_i32 s23, s22, 0x100
	s_mov_b32 m0, s38
	s_nop 0
	buffer_load_dwordx4 v141, s[12:15], s23 offen lds
	s_mov_b32 m0, s54
	s_nop 0
	buffer_load_dwordx4 v142, s[12:15], s23 offen lds
	s_waitcnt vmcnt(6)
	s_barrier
; #define STAGE(P, RS, SOFF, OFF, kt) do { const int _so = (SOFF) + (kt) * (BK * 2); \
;     _Pragma("unroll") for (int _i = 0; _i < 2; ++_i) { \
;       __builtin_amdgcn_raw_ptr_buffer_load_lds(RS, (__attribute__((address_space(3))) void*)((P) + wave * 1024 + _i * 8192), 16, OFF[_i], _so, 0, 0); } } while (0)
; #define LDA(dst, b, h) _Pragma("unroll") for (int m = 0; m < 4; ++m) _Pragma("unroll") for (int k = 0; k < 2; ++k) \
;     dst[m][k] = *reinterpret_cast<const bf16x8*>(SA(b, h) + lds_byte(wr * 64 + m * 16 + fr, k * 32 + fq * 8))
; #define LDB(dst, b, h) _Pragma("unroll") for (int n = 0; n < 2; ++n) _Pragma("unroll") for (int k = 0; k < 2; ++k) \
;     dst[n][k] = *reinterpret_cast<const bf16x8*>(SB(b, h) + lds_byte(wc * 32 + n * 16 + fr, k * 32 + fq * 8))
; #define WAIT_V(n) asm volatile("s_waitcnt vmcnt(" #n ")" ::: "memory")
; #define WAIT_L(n) asm volatile("s_waitcnt lgkmcnt(" #n ")" ::: "memory")
; #define BAR __builtin_amdgcn_s_barrier()
; #define SCHED __builtin_amdgcn_sched_barrier(0)
;     ...
;       WAIT_V(6); BAR; MMA(1, 1, At, B1); BAR;
;       LDB(B0, 1, 0); SCHED; LDA(At, 1, 0); STAGE(SA(0, 1), rsA, sA1, offA, t + 2);
;       WAIT_L(8); BAR; WAIT_L(0); MMA(0, 0, At, B0); BAR; SCHED;
;       LDB(B1, 1, 1); STAGE(SB(1, 0), rsB, sB0, offB, t + 3);
;       BAR; WAIT_L(0); MMA(0, 1, At, B1); BAR;
;       LDA(At, 1, 1); STAGE(SA(1, 0), rsA, sA0, offA, t + 3);
;       BAR; WAIT_L(0); MMA(1, 0, At, B0); BAR; SCHED;
;       STAGE(SB(1, 1), rsB, sB1, offB, t + 3);
;       WAIT_V(6); BAR; MMA(1, 1, At, B1); BAR;
	v_mfma_f32_16x16x32_bf16 v[12:15], v[200:203], v[168:171], v[12:15]
	v_mfma_f32_16x16x32_bf16 v[8:11], v[208:211], v[168:171], v[8:11]
	v_mfma_f32_16x16x32_bf16 v[4:7], v[200:203], v[176:179], v[4:7]
	v_mfma_f32_16x16x32_bf16 v[0:3], v[208:211], v[176:179], v[0:3]
	v_mfma_f32_16x16x32_bf16 v[64:67], v[200:203], v[184:187], v[64:67]
	v_mfma_f32_16x16x32_bf16 v[72:75], v[208:211], v[184:187], v[72:75]
	v_mfma_f32_16x16x32_bf16 v[76:79], v[200:203], v[192:195], v[76:79]
	v_mfma_f32_16x16x32_bf16 v[84:87], v[208:211], v[192:195], v[84:87]
	v_mfma_f32_16x16x32_bf16 v[12:15], v[204:207], v[172:175], v[12:15]
	v_mfma_f32_16x16x32_bf16 v[8:11], v[212:215], v[172:175], v[8:11]
	v_mfma_f32_16x16x32_bf16 v[4:7], v[204:207], v[180:183], v[4:7]
	v_mfma_f32_16x16x32_bf16 v[0:3], v[212:215], v[180:183], v[0:3]
	v_mfma_f32_16x16x32_bf16 v[64:67], v[204:207], v[188:191], v[64:67]
	v_mfma_f32_16x16x32_bf16 v[72:75], v[212:215], v[188:191], v[72:75]
	v_mfma_f32_16x16x32_bf16 v[76:79], v[204:207], v[196:199], v[76:79]
	v_mfma_f32_16x16x32_bf16 v[84:87], v[212:215], v[196:199], v[84:87]
	s_barrier
	ds_read_b128 v[152:155], v137
	ds_read_b128 v[156:159], v138
	ds_read_b128 v[160:163], v139
	ds_read_b128 v[164:167], v140
	s_addk_i32 s5, 0x100
	s_mov_b32 m0, s39
	ds_read_b128 v[168:171], v129 offset:32768
	ds_read_b128 v[172:175], v129 offset:33792
	ds_read_b128 v[176:179], v132 offset:32768
	ds_read_b128 v[180:183], v132 offset:33792
	ds_read_b128 v[184:187], v131 offset:32768
	ds_read_b128 v[188:191], v131 offset:33792
	ds_read_b128 v[192:195], v130 offset:32768
	ds_read_b128 v[196:199], v130 offset:33792
	buffer_load_dwordx4 v141, s[8:11], s5 offen lds
	s_mov_b32 m0, s55
	s_nop 0
	buffer_load_dwordx4 v142, s[8:11], s5 offen lds
	s_waitcnt lgkmcnt(8)
	s_barrier
	s_waitcnt lgkmcnt(0)
	v_mfma_f32_16x16x32_bf16 v[124:127], v[152:155], v[168:171], v[124:127]
	v_mfma_f32_16x16x32_bf16 v[120:123], v[160:163], v[168:171], v[120:123]
	v_mfma_f32_16x16x32_bf16 v[116:119], v[152:155], v[176:179], v[116:119]
	v_mfma_f32_16x16x32_bf16 v[112:115], v[160:163], v[176:179], v[112:115]
	v_mfma_f32_16x16x32_bf16 v[108:111], v[152:155], v[184:187], v[108:111]
	v_mfma_f32_16x16x32_bf16 v[104:107], v[160:163], v[184:187], v[104:107]
	v_mfma_f32_16x16x32_bf16 v[100:103], v[152:155], v[192:195], v[100:103]
	v_mfma_f32_16x16x32_bf16 v[96:99], v[160:163], v[192:195], v[96:99]
	v_mfma_f32_16x16x32_bf16 v[124:127], v[156:159], v[172:175], v[124:127]
	v_mfma_f32_16x16x32_bf16 v[120:123], v[164:167], v[172:175], v[120:123]
	v_mfma_f32_16x16x32_bf16 v[116:119], v[156:159], v[180:183], v[116:119]
	v_mfma_f32_16x16x32_bf16 v[112:115], v[164:167], v[180:183], v[112:115]
	v_mfma_f32_16x16x32_bf16 v[108:111], v[156:159], v[188:191], v[108:111]
	v_mfma_f32_16x16x32_bf16 v[104:107], v[164:167], v[188:191], v[104:107]
	v_mfma_f32_16x16x32_bf16 v[100:103], v[156:159], v[196:199], v[100:103]
	v_mfma_f32_16x16x32_bf16 v[96:99], v[164:167], v[196:199], v[96:99]
	s_barrier
	s_addk_i32 s6, 0x180
	s_mov_b32 m0, s42
	ds_read_b128 v[200:203], v133
	ds_read_b128 v[204:207], v134
	ds_read_b128 v[208:211], v135
	ds_read_b128 v[212:215], v136
	buffer_load_dwordx4 v141, s[12:15], s6 offen lds
	s_mov_b32 m0, s56
	s_nop 0
	buffer_load_dwordx4 v142, s[12:15], s6 offen lds
	s_barrier
	s_waitcnt lgkmcnt(0)
	v_mfma_f32_16x16x32_bf16 v[92:95], v[200:203], v[168:171], v[92:95]
	v_mfma_f32_16x16x32_bf16 v[88:91], v[208:211], v[168:171], v[88:91]
	v_mfma_f32_16x16x32_bf16 v[80:83], v[200:203], v[176:179], v[80:83]
	v_mfma_f32_16x16x32_bf16 v[68:71], v[208:211], v[176:179], v[68:71]
	v_mfma_f32_16x16x32_bf16 v[60:63], v[200:203], v[184:187], v[60:63]
	v_mfma_f32_16x16x32_bf16 v[56:59], v[208:211], v[184:187], v[56:59]
	v_mfma_f32_16x16x32_bf16 v[52:55], v[200:203], v[192:195], v[52:55]
	v_mfma_f32_16x16x32_bf16 v[48:51], v[208:211], v[192:195], v[48:51]
	v_mfma_f32_16x16x32_bf16 v[92:95], v[204:207], v[172:175], v[92:95]
	v_mfma_f32_16x16x32_bf16 v[88:91], v[212:215], v[172:175], v[88:91]
	v_mfma_f32_16x16x32_bf16 v[80:83], v[204:207], v[180:183], v[80:83]
	v_mfma_f32_16x16x32_bf16 v[68:71], v[212:215], v[180:183], v[68:71]
	v_mfma_f32_16x16x32_bf16 v[60:63], v[204:207], v[188:191], v[60:63]
	v_mfma_f32_16x16x32_bf16 v[56:59], v[212:215], v[188:191], v[56:59]
	v_mfma_f32_16x16x32_bf16 v[52:55], v[204:207], v[196:199], v[52:55]
	v_mfma_f32_16x16x32_bf16 v[48:51], v[212:215], v[196:199], v[48:51]
	s_addk_i32 s7, 0x180
	s_mov_b32 m0, s43
	s_barrier
	ds_read_b128 v[168:171], v129 offset:49152
	ds_read_b128 v[172:175], v129 offset:50176
	ds_read_b128 v[176:179], v132 offset:49152
	ds_read_b128 v[180:183], v132 offset:50176
	ds_read_b128 v[184:187], v131 offset:49152
	ds_read_b128 v[188:191], v131 offset:50176
	ds_read_b128 v[192:195], v130 offset:49152
	ds_read_b128 v[196:199], v130 offset:50176
	buffer_load_dwordx4 v141, s[8:11], s7 offen lds
	s_mov_b32 m0, s57
	s_nop 0
	buffer_load_dwordx4 v142, s[8:11], s7 offen lds
	s_barrier
	s_waitcnt lgkmcnt(0)
	v_mfma_f32_16x16x32_bf16 v[44:47], v[152:155], v[168:171], v[44:47]
	v_mfma_f32_16x16x32_bf16 v[40:43], v[160:163], v[168:171], v[40:43]
	v_mfma_f32_16x16x32_bf16 v[36:39], v[152:155], v[176:179], v[36:39]
	v_mfma_f32_16x16x32_bf16 v[32:35], v[160:163], v[176:179], v[32:35]
	v_mfma_f32_16x16x32_bf16 v[28:31], v[152:155], v[184:187], v[28:31]
	v_mfma_f32_16x16x32_bf16 v[24:27], v[160:163], v[184:187], v[24:27]
	v_mfma_f32_16x16x32_bf16 v[20:23], v[152:155], v[192:195], v[20:23]
	v_mfma_f32_16x16x32_bf16 v[16:19], v[160:163], v[192:195], v[16:19]
	v_mfma_f32_16x16x32_bf16 v[44:47], v[156:159], v[172:175], v[44:47]
	v_mfma_f32_16x16x32_bf16 v[40:43], v[164:167], v[172:175], v[40:43]
	v_mfma_f32_16x16x32_bf16 v[36:39], v[156:159], v[180:183], v[36:39]
	v_mfma_f32_16x16x32_bf16 v[32:35], v[164:167], v[180:183], v[32:35]
	v_mfma_f32_16x16x32_bf16 v[28:31], v[156:159], v[188:191], v[28:31]
	v_mfma_f32_16x16x32_bf16 v[24:27], v[164:167], v[188:191], v[24:27]
	v_mfma_f32_16x16x32_bf16 v[20:23], v[156:159], v[196:199], v[20:23]
	v_mfma_f32_16x16x32_bf16 v[16:19], v[164:167], v[196:199], v[16:19]
	s_barrier
; #define STAGE(P, RS, SOFF, OFF, kt) do { const int _so = (SOFF) + (kt) * (BK * 2); \
;     _Pragma("unroll") for (int _i = 0; _i < 2; ++_i) { \
;       __builtin_amdgcn_raw_ptr_buffer_load_lds(RS, (__attribute__((address_space(3))) void*)((P) + wave * 1024 + _i * 8192), 16, OFF[_i], _so, 0, 0); } } while (0)
; #define LDA(dst, b, h) _Pragma("unroll") for (int m = 0; m < 4; ++m) _Pragma("unroll") for (int k = 0; k < 2; ++k) \
;     dst[m][k] = *reinterpret_cast<const bf16x8*>(SA(b, h) + lds_byte(wr * 64 + m * 16 + fr, k * 32 + fq * 8))
; #define LDB(dst, b, h) _Pragma("unroll") for (int n = 0; n < 2; ++n) _Pragma("unroll") for (int k = 0; k < 2; ++k) \
;     dst[n][k] = *reinterpret_cast<const bf16x8*>(SB(b, h) + lds_byte(wc * 32 + n * 16 + fr, k * 32 + fq * 8))
; #define WAIT_V(n) asm volatile("s_waitcnt vmcnt(" #n ")" ::: "memory")
; #define WAIT_L(n) asm volatile("s_waitcnt lgkmcnt(" #n ")" ::: "memory")
; #define BAR __builtin_amdgcn_s_barrier()
;     ...
;       STAGE(SB(1, 1), rsB, sB1, offB, t + 3);
;       WAIT_V(6); BAR; MMA(1, 1, At, B1); BAR;
;     }
;     { LDB(B0, 0, 0); LDA(At, 0, 0); STAGE(SA(1, 1), rsA, sA1, offA, nt - 1);
;       BAR; WAIT_L(0); MMA(0, 0, At, B0); BAR;
;       LDB(B1, 0, 1); BAR; WAIT_L(0); MMA(0, 1, At, B1); BAR;
;       LDA(At, 0, 1); WAIT_V(4); BAR; WAIT_L(0); MMA(1, 0, At, B0); MMA(1, 1, At, B1); BAR; }
	s_addk_i32 s22, 0x180
	s_mov_b32 m0, s44
	s_nop 0
	buffer_load_dwordx4 v141, s[12:15], s22 offen lds
	s_mov_b32 m0, s58
	s_nop 0
	buffer_load_dwordx4 v142, s[12:15], s22 offen lds
	s_waitcnt vmcnt(6)
	s_barrier
	v_mfma_f32_16x16x32_bf16 v[12:15], v[200:203], v[168:171], v[12:15]
	v_mfma_f32_16x16x32_bf16 v[8:11], v[208:211], v[168:171], v[8:11]
	v_mfma_f32_16x16x32_bf16 v[4:7], v[200:203], v[176:179], v[4:7]
	v_mfma_f32_16x16x32_bf16 v[0:3], v[208:211], v[176:179], v[0:3]
	v_mfma_f32_16x16x32_bf16 v[64:67], v[200:203], v[184:187], v[64:67]
	v_mfma_f32_16x16x32_bf16 v[72:75], v[208:211], v[184:187], v[72:75]
	v_mfma_f32_16x16x32_bf16 v[76:79], v[200:203], v[192:195], v[76:79]
	v_mfma_f32_16x16x32_bf16 v[84:87], v[208:211], v[192:195], v[84:87]
	v_mfma_f32_16x16x32_bf16 v[12:15], v[204:207], v[172:175], v[12:15]
	v_mfma_f32_16x16x32_bf16 v[8:11], v[212:215], v[172:175], v[8:11]
	v_mfma_f32_16x16x32_bf16 v[4:7], v[204:207], v[180:183], v[4:7]
	v_mfma_f32_16x16x32_bf16 v[0:3], v[212:215], v[180:183], v[0:3]
	v_mfma_f32_16x16x32_bf16 v[64:67], v[204:207], v[188:191], v[64:67]
	v_mfma_f32_16x16x32_bf16 v[72:75], v[212:215], v[188:191], v[72:75]
	v_mfma_f32_16x16x32_bf16 v[76:79], v[204:207], v[196:199], v[76:79]
	v_mfma_f32_16x16x32_bf16 v[84:87], v[212:215], v[196:199], v[84:87]
	s_add_i32 s1, s1, 2
	s_addk_i32 s3, 0x100
	s_cmp_gt_u32 s1, 59
	s_barrier
	s_cbranch_scc0 .LBB0_392
	s_add_i32 s1, s86, 0x1f80
	s_mov_b32 m0, s36
	ds_read_b128 v[152:155], v147
	ds_read_b128 v[156:159], v148
	ds_read_b128 v[160:163], v149
	ds_read_b128 v[148:151], v150
	ds_read_b128 v[164:167], v129
	ds_read_b128 v[168:171], v129 offset:1024
	ds_read_b128 v[172:175], v132
	ds_read_b128 v[176:179], v132 offset:1024
	ds_read_b128 v[180:183], v131
	ds_read_b128 v[184:187], v131 offset:1024
	ds_read_b128 v[188:191], v130
	ds_read_b128 v[192:195], v130 offset:1024
	buffer_load_dwordx4 v141, s[8:11], s1 offen lds
	s_mov_b32 m0, s59
	s_nop 0
	buffer_load_dwordx4 v142, s[8:11], s1 offen lds
	s_barrier
	s_waitcnt lgkmcnt(0)
	v_mfma_f32_16x16x32_bf16 v[124:127], v[152:155], v[164:167], v[124:127]
	v_mfma_f32_16x16x32_bf16 v[120:123], v[160:163], v[164:167], v[120:123]
	v_mfma_f32_16x16x32_bf16 v[116:119], v[152:155], v[172:175], v[116:119]
	v_mfma_f32_16x16x32_bf16 v[112:115], v[160:163], v[172:175], v[112:115]
	v_mfma_f32_16x16x32_bf16 v[108:111], v[152:155], v[180:183], v[108:111]
	v_mfma_f32_16x16x32_bf16 v[104:107], v[160:163], v[180:183], v[104:107]
	v_mfma_f32_16x16x32_bf16 v[100:103], v[152:155], v[188:191], v[100:103]
	v_mfma_f32_16x16x32_bf16 v[96:99], v[160:163], v[188:191], v[96:99]
	v_mfma_f32_16x16x32_bf16 v[124:127], v[156:159], v[168:171], v[124:127]
	v_mfma_f32_16x16x32_bf16 v[120:123], v[148:151], v[168:171], v[120:123]
	v_mfma_f32_16x16x32_bf16 v[116:119], v[156:159], v[176:179], v[116:119]
	v_mfma_f32_16x16x32_bf16 v[112:115], v[148:151], v[176:179], v[112:115]
	v_mfma_f32_16x16x32_bf16 v[108:111], v[156:159], v[184:187], v[108:111]
	v_mfma_f32_16x16x32_bf16 v[104:107], v[148:151], v[184:187], v[104:107]
	v_mfma_f32_16x16x32_bf16 v[100:103], v[156:159], v[192:195], v[100:103]
	v_mfma_f32_16x16x32_bf16 v[96:99], v[148:151], v[192:195], v[96:99]
	s_barrier
	ds_read_b128 v[196:199], v143
	ds_read_b128 v[200:203], v144
	ds_read_b128 v[142:145], v145
	ds_read_b128 v[204:207], v146
	s_barrier
	s_waitcnt lgkmcnt(0)
	v_mfma_f32_16x16x32_bf16 v[80:83], v[196:199], v[172:175], v[80:83]
	v_mfma_f32_16x16x32_bf16 v[68:71], v[142:145], v[172:175], v[68:71]
	v_mfma_f32_16x16x32_bf16 v[60:63], v[196:199], v[180:183], v[60:63]
	v_mfma_f32_16x16x32_bf16 v[56:59], v[142:145], v[180:183], v[56:59]
	v_mfma_f32_16x16x32_bf16 v[52:55], v[196:199], v[188:191], v[52:55]
	v_mfma_f32_16x16x32_bf16 v[48:51], v[142:145], v[188:191], v[48:51]
	v_mfma_f32_16x16x32_bf16 v[92:95], v[196:199], v[164:167], v[92:95]
	v_mfma_f32_16x16x32_bf16 v[88:91], v[142:145], v[164:167], v[88:91]
	v_mfma_f32_16x16x32_bf16 v[80:83], v[200:203], v[176:179], v[80:83]
	v_mfma_f32_16x16x32_bf16 v[68:71], v[204:207], v[176:179], v[68:71]
	v_mfma_f32_16x16x32_bf16 v[60:63], v[200:203], v[184:187], v[60:63]
	v_mfma_f32_16x16x32_bf16 v[56:59], v[204:207], v[184:187], v[56:59]
	v_mfma_f32_16x16x32_bf16 v[52:55], v[200:203], v[192:195], v[52:55]
	v_mfma_f32_16x16x32_bf16 v[48:51], v[204:207], v[192:195], v[48:51]
	v_mfma_f32_16x16x32_bf16 v[164:167], v[200:203], v[168:171], v[92:95]
	v_mfma_f32_16x16x32_bf16 v[168:171], v[204:207], v[168:171], v[88:91]
	s_barrier
	s_nop 0
	ds_read_b128 v[88:91], v129 offset:16384
	ds_read_b128 v[92:95], v129 offset:17408
	ds_read_b128 v[172:175], v132 offset:16384
	ds_read_b128 v[176:179], v132 offset:17408
	ds_read_b128 v[180:183], v131 offset:16384
	ds_read_b128 v[184:187], v131 offset:17408
	ds_read_b128 v[188:191], v130 offset:16384
	ds_read_b128 v[192:195], v130 offset:17408
	s_waitcnt vmcnt(4)
	s_barrier
; #define LDA(dst, b, h) _Pragma("unroll") for (int m = 0; m < 4; ++m) _Pragma("unroll") for (int k = 0; k < 2; ++k) \
;     dst[m][k] = *reinterpret_cast<const bf16x8*>(SA(b, h) + lds_byte(wr * 64 + m * 16 + fr, k * 32 + fq * 8))
; #define LDB(dst, b, h) _Pragma("unroll") for (int n = 0; n < 2; ++n) _Pragma("unroll") for (int k = 0; k < 2; ++k) \
;     dst[n][k] = *reinterpret_cast<const bf16x8*>(SB(b, h) + lds_byte(wc * 32 + n * 16 + fr, k * 32 + fq * 8))
; #define WAIT_V(n) asm volatile("s_waitcnt vmcnt(" #n ")" ::: "memory")
; #define WAIT_L(n) asm volatile("s_waitcnt lgkmcnt(" #n ")" ::: "memory")
; #define BAR __builtin_amdgcn_s_barrier()
;     ...
;       LDA(At, 0, 1); WAIT_V(4); BAR; WAIT_L(0); MMA(1, 0, At, B0); MMA(1, 1, At, B1); BAR; }
;     { LDB(B0, 1, 0); LDA(At, 1, 0); WAIT_V(2); BAR; WAIT_L(0); MMA(0, 0, At, B0); BAR;
;       LDB(B1, 1, 1); WAIT_V(0); BAR; WAIT_L(0); MMA(0, 1, At, B1); BAR;
	s_waitcnt lgkmcnt(0)
	v_mfma_f32_16x16x32_bf16 v[44:47], v[152:155], v[88:91], v[44:47]
	v_mfma_f32_16x16x32_bf16 v[40:43], v[160:163], v[88:91], v[40:43]
	v_mfma_f32_16x16x32_bf16 v[36:39], v[152:155], v[172:175], v[36:39]
	v_mfma_f32_16x16x32_bf16 v[32:35], v[160:163], v[172:175], v[32:35]
	v_mfma_f32_16x16x32_bf16 v[28:31], v[152:155], v[180:183], v[28:31]
	v_mfma_f32_16x16x32_bf16 v[24:27], v[160:163], v[180:183], v[24:27]
	v_mfma_f32_16x16x32_bf16 v[20:23], v[152:155], v[188:191], v[20:23]
	v_mfma_f32_16x16x32_bf16 v[16:19], v[160:163], v[188:191], v[16:19]
	v_mfma_f32_16x16x32_bf16 v[44:47], v[156:159], v[92:95], v[44:47]
	v_mfma_f32_16x16x32_bf16 v[40:43], v[148:151], v[92:95], v[40:43]
	v_mfma_f32_16x16x32_bf16 v[36:39], v[156:159], v[176:179], v[36:39]
	v_mfma_f32_16x16x32_bf16 v[32:35], v[148:151], v[176:179], v[32:35]
	v_mfma_f32_16x16x32_bf16 v[28:31], v[156:159], v[184:187], v[28:31]
	v_mfma_f32_16x16x32_bf16 v[24:27], v[148:151], v[184:187], v[24:27]
	v_mfma_f32_16x16x32_bf16 v[20:23], v[156:159], v[192:195], v[20:23]
	v_mfma_f32_16x16x32_bf16 v[16:19], v[148:151], v[192:195], v[16:19]
	v_mfma_f32_16x16x32_bf16 v[4:7], v[196:199], v[172:175], v[4:7]
	v_mfma_f32_16x16x32_bf16 v[0:3], v[142:145], v[172:175], v[0:3]
	v_mfma_f32_16x16x32_bf16 v[12:15], v[196:199], v[88:91], v[12:15]
	v_mfma_f32_16x16x32_bf16 v[8:11], v[142:145], v[88:91], v[8:11]
	v_mfma_f32_16x16x32_bf16 v[64:67], v[196:199], v[180:183], v[64:67]
	v_mfma_f32_16x16x32_bf16 v[72:75], v[142:145], v[180:183], v[72:75]
	v_mfma_f32_16x16x32_bf16 v[76:79], v[196:199], v[188:191], v[76:79]
	v_mfma_f32_16x16x32_bf16 v[84:87], v[142:145], v[188:191], v[84:87]
	v_mfma_f32_16x16x32_bf16 v[4:7], v[200:203], v[176:179], v[4:7]
	v_mfma_f32_16x16x32_bf16 v[0:3], v[204:207], v[176:179], v[0:3]
	v_mfma_f32_16x16x32_bf16 v[142:145], v[200:203], v[92:95], v[12:15]
	v_mfma_f32_16x16x32_bf16 v[146:149], v[204:207], v[92:95], v[8:11]
	v_mfma_f32_16x16x32_bf16 v[150:153], v[200:203], v[184:187], v[64:67]
	v_mfma_f32_16x16x32_bf16 v[154:157], v[204:207], v[184:187], v[72:75]
	v_mfma_f32_16x16x32_bf16 v[158:161], v[200:203], v[192:195], v[76:79]
	v_mfma_f32_16x16x32_bf16 v[172:175], v[204:207], v[192:195], v[84:87]
	s_barrier
	ds_read_b128 v[8:11], v137
	ds_read_b128 v[12:15], v138
	ds_read_b128 v[176:179], v139
	ds_read_b128 v[138:141], v140
	ds_read_b128 v[64:67], v129 offset:32768
	ds_read_b128 v[84:87], v129 offset:33792
	ds_read_b128 v[180:183], v132 offset:32768
	ds_read_b128 v[184:187], v132 offset:33792
	ds_read_b128 v[188:191], v131 offset:32768
	ds_read_b128 v[192:195], v131 offset:33792
	ds_read_b128 v[196:199], v130 offset:32768
	ds_read_b128 v[200:203], v130 offset:33792
	s_waitcnt vmcnt(2)
	s_barrier
	s_waitcnt lgkmcnt(0)
	v_mfma_f32_16x16x32_bf16 v[72:75], v[8:11], v[64:67], v[124:127]
	v_mfma_f32_16x16x32_bf16 v[76:79], v[176:179], v[64:67], v[120:123]
	v_mfma_f32_16x16x32_bf16 v[88:91], v[8:11], v[180:183], v[116:119]
	v_mfma_f32_16x16x32_bf16 v[92:95], v[176:179], v[180:183], v[112:115]
	v_mfma_f32_16x16x32_bf16 v[112:115], v[8:11], v[188:191], v[108:111]
	v_mfma_f32_16x16x32_bf16 v[120:123], v[176:179], v[188:191], v[104:107]
	v_mfma_f32_16x16x32_bf16 v[100:103], v[8:11], v[196:199], v[100:103]
	v_mfma_f32_16x16x32_bf16 v[96:99], v[176:179], v[196:199], v[96:99]
	v_mfma_f32_16x16x32_bf16 v[124:127], v[12:15], v[84:87], v[72:75]
	v_mfma_f32_16x16x32_bf16 v[116:119], v[138:141], v[84:87], v[76:79]
	v_mfma_f32_16x16x32_bf16 v[108:111], v[12:15], v[184:187], v[88:91]
	v_mfma_f32_16x16x32_bf16 v[104:107], v[138:141], v[184:187], v[92:95]
	v_mfma_f32_16x16x32_bf16 v[92:95], v[12:15], v[192:195], v[112:115]
	v_mfma_f32_16x16x32_bf16 v[88:91], v[138:141], v[192:195], v[120:123]
	v_mfma_f32_16x16x32_bf16 v[76:79], v[12:15], v[200:203], v[100:103]
	v_mfma_f32_16x16x32_bf16 v[72:75], v[138:141], v[200:203], v[96:99]
	s_barrier
; #define LDA(dst, b, h) _Pragma("unroll") for (int m = 0; m < 4; ++m) _Pragma("unroll") for (int k = 0; k < 2; ++k) \
;     dst[m][k] = *reinterpret_cast<const bf16x8*>(SA(b, h) + lds_byte(wr * 64 + m * 16 + fr, k * 32 + fq * 8))
; #define LDB(dst, b, h) _Pragma("unroll") for (int n = 0; n < 2; ++n) _Pragma("unroll") for (int k = 0; k < 2; ++k) \
;     dst[n][k] = *reinterpret_cast<const bf16x8*>(SB(b, h) + lds_byte(wc * 32 + n * 16 + fr, k * 32 + fq * 8))
; #define WAIT_V(n) asm volatile("s_waitcnt vmcnt(" #n ")" ::: "memory")
; #define WAIT_L(n) asm volatile("s_waitcnt lgkmcnt(" #n ")" ::: "memory")
; #define BAR __builtin_amdgcn_s_barrier()
;     ...
;       LDB(B1, 1, 1); WAIT_V(0); BAR; WAIT_L(0); MMA(0, 1, At, B1); BAR;
;       LDA(At, 1, 1); BAR; WAIT_L(0); MMA(1, 0, At, B0); MMA(1, 1, At, B1); BAR; }
;     if (wr == 0) BAR;
	ds_read_b128 v[204:207], v133
	ds_read_b128 v[208:211], v134
	ds_read_b128 v[212:215], v135
	ds_read_b128 v[134:137], v136
	s_waitcnt vmcnt(0)
	s_barrier
	s_waitcnt lgkmcnt(0)
	v_mfma_f32_16x16x32_bf16 v[96:99], v[204:207], v[64:67], v[164:167]
	v_mfma_f32_16x16x32_bf16 v[64:67], v[212:215], v[64:67], v[168:171]
	v_mfma_f32_16x16x32_bf16 v[80:83], v[204:207], v[180:183], v[80:83]
	v_mfma_f32_16x16x32_bf16 v[68:71], v[212:215], v[180:183], v[68:71]
	v_mfma_f32_16x16x32_bf16 v[60:63], v[204:207], v[188:191], v[60:63]
	v_mfma_f32_16x16x32_bf16 v[56:59], v[212:215], v[188:191], v[56:59]
	v_mfma_f32_16x16x32_bf16 v[52:55], v[204:207], v[196:199], v[52:55]
	v_mfma_f32_16x16x32_bf16 v[48:51], v[212:215], v[196:199], v[48:51]
	v_mfma_f32_16x16x32_bf16 v[120:123], v[208:211], v[84:87], v[96:99]
	v_mfma_f32_16x16x32_bf16 v[112:115], v[134:137], v[84:87], v[64:67]
	v_mfma_f32_16x16x32_bf16 v[100:103], v[208:211], v[184:187], v[80:83]
	v_mfma_f32_16x16x32_bf16 v[96:99], v[134:137], v[184:187], v[68:71]
	v_mfma_f32_16x16x32_bf16 v[84:87], v[208:211], v[192:195], v[60:63]
	v_mfma_f32_16x16x32_bf16 v[80:83], v[134:137], v[192:195], v[56:59]
	v_mfma_f32_16x16x32_bf16 v[68:71], v[208:211], v[200:203], v[52:55]
	v_mfma_f32_16x16x32_bf16 v[64:67], v[134:137], v[200:203], v[48:51]
	s_barrier
	s_nop 0
	ds_read_b128 v[48:51], v129 offset:49152
	ds_read_b128 v[162:165], v129 offset:50176
	ds_read_b128 v[52:55], v132 offset:49152
	ds_read_b128 v[166:169], v132 offset:50176
	ds_read_b128 v[180:183], v131 offset:49152
	ds_read_b128 v[184:187], v131 offset:50176
	ds_read_b128 v[188:191], v130 offset:49152
	ds_read_b128 v[130:133], v130 offset:50176
	s_barrier
	s_waitcnt lgkmcnt(0)
	v_mfma_f32_16x16x32_bf16 v[44:47], v[8:11], v[48:51], v[44:47]
	v_mfma_f32_16x16x32_bf16 v[40:43], v[176:179], v[48:51], v[40:43]
	v_mfma_f32_16x16x32_bf16 v[36:39], v[8:11], v[52:55], v[36:39]
	v_mfma_f32_16x16x32_bf16 v[32:35], v[176:179], v[52:55], v[32:35]
	v_mfma_f32_16x16x32_bf16 v[28:31], v[8:11], v[180:183], v[28:31]
	v_mfma_f32_16x16x32_bf16 v[24:27], v[176:179], v[180:183], v[24:27]
	v_mfma_f32_16x16x32_bf16 v[8:11], v[8:11], v[188:191], v[20:23]
	v_mfma_f32_16x16x32_bf16 v[16:19], v[176:179], v[188:191], v[16:19]
	v_mfma_f32_16x16x32_bf16 v[60:63], v[12:15], v[162:165], v[44:47]
	v_mfma_f32_16x16x32_bf16 v[56:59], v[138:141], v[162:165], v[40:43]
	v_mfma_f32_16x16x32_bf16 v[44:47], v[12:15], v[166:169], v[36:39]
	v_mfma_f32_16x16x32_bf16 v[40:43], v[138:141], v[166:169], v[32:35]
	v_mfma_f32_16x16x32_bf16 v[28:31], v[12:15], v[184:187], v[28:31]
	v_mfma_f32_16x16x32_bf16 v[24:27], v[138:141], v[184:187], v[24:27]
	v_mfma_f32_16x16x32_bf16 v[12:15], v[12:15], v[130:133], v[8:11]
	v_mfma_f32_16x16x32_bf16 v[8:11], v[138:141], v[130:133], v[16:19]
	v_mfma_f32_16x16x32_bf16 v[16:19], v[204:207], v[48:51], v[142:145]
	v_mfma_f32_16x16x32_bf16 v[20:23], v[212:215], v[48:51], v[146:149]
	v_mfma_f32_16x16x32_bf16 v[4:7], v[204:207], v[52:55], v[4:7]
	v_mfma_f32_16x16x32_bf16 v[0:3], v[212:215], v[52:55], v[0:3]
	v_mfma_f32_16x16x32_bf16 v[138:141], v[204:207], v[180:183], v[150:153]
	v_mfma_f32_16x16x32_bf16 v[142:145], v[212:215], v[180:183], v[154:157]
	v_mfma_f32_16x16x32_bf16 v[146:149], v[204:207], v[188:191], v[158:161]
	v_mfma_f32_16x16x32_bf16 v[150:153], v[212:215], v[188:191], v[172:175]
	v_mfma_f32_16x16x32_bf16 v[52:55], v[208:211], v[162:165], v[16:19]
	v_mfma_f32_16x16x32_bf16 v[48:51], v[134:137], v[162:165], v[20:23]
	v_mfma_f32_16x16x32_bf16 v[36:39], v[208:211], v[166:169], v[4:7]
	v_mfma_f32_16x16x32_bf16 v[32:35], v[134:137], v[166:169], v[0:3]
	v_mfma_f32_16x16x32_bf16 v[20:23], v[208:211], v[184:187], v[138:141]
	v_mfma_f32_16x16x32_bf16 v[16:19], v[134:137], v[184:187], v[142:145]
	v_mfma_f32_16x16x32_bf16 v[4:7], v[208:211], v[130:133], v[146:149]
	v_mfma_f32_16x16x32_bf16 v[0:3], v[134:137], v[130:133], v[150:153]
	v_cmp_gt_u32_e32 vcc, s40, v128
	s_barrier
	s_and_saveexec_b64 s[6:7], vcc
	s_cbranch_execz .LBB0_395
	s_barrier

; #define WAIT_V(n) asm volatile("s_waitcnt vmcnt(" #n ")" ::: "memory")
; #define BAR __builtin_amdgcn_s_barrier()
;     ...
;         constexpr int PIECE = 1024 + 16, LOBASE = 64 * PIECE;
;         const int hvo = (lane >> 5) * (DM * 2) + (lane & 31) * 16;
;         const int lvo = (lane >> 4) * DM + (lane & 15) * 16;
;         _Pragma("unroll") for (int ai = 0; ai < 2; ++ai) {
;           const int rbase = brow + ai * HALF;
;           const int hso = ((rbase + 16 * wave) * DM + pn * BM) * 2;
;           const int lso = (rbase + 16 * wave) * DM + pn * BM;
;           _Pragma("unroll") for (int i = 0; i < 8; ++i)
;             __builtin_amdgcn_raw_ptr_buffer_load_lds(rsXB, (__attribute__((address_space(3))) void*)(smem + (wave * 8 + i) * PIECE), 16,
;                                                      hvo + i * (2 * DM * 2), hso, 0, 0);
;           _Pragma("unroll") for (int i = 0; i < 4; ++i)
;             __builtin_amdgcn_raw_ptr_buffer_load_lds(rsLO, (__attribute__((address_space(3))) void*)(smem + LOBASE + (wave * 4 + i) * PIECE), 16,
;                                                      lvo + i * (4 * DM), lso, 0, 0);
;           WAIT_V(0); BAR;
;           _Pragma("unroll") for (int m = 0; m < 4; ++m) _Pragma("unroll") for (int bj = 0; bj < 2; ++bj) _Pragma("unroll") for (int n = 0; n < 2; ++n) {
;             const int rr = wr * 64 + m * 16 + fr;
;             const int cc = bj * HALF + wc * 32 + n * 16 + fq * 4;
;             const u32x2 hv = *reinterpret_cast<const u32x2*>(smem + (rr >> 1) * PIECE + (rr & 1) * 512 + cc * 2);
;             const unsigned lv = *reinterpret_cast<const unsigned*>(smem + LOBASE + (rr >> 2) * PIECE + (rr & 3) * 256 + cc);
;             float x0 = __int_as_float((int)(hv[0] << 16) + (((int)(lv << 24)) >> 24) * 256);
;             float x1 = __int_as_float((int)(hv[0] & 0xffff0000u) + (((int)(lv << 16)) >> 24) * 256);
;             float x2 = __int_as_float((int)(hv[1] << 16) + (((int)(lv << 8)) >> 24) * 256);
;             float x3 = __int_as_float((int)(hv[1] & 0xffff0000u) + (((int)lv) >> 24) * 256);
;             acc[ai][bj][m][n][0] = ALPHA * x0 + sc * acc[ai][bj][m][n][0];
;             acc[ai][bj][m][n][1] = ALPHA * x1 + sc * acc[ai][bj][m][n][1];
;             acc[ai][bj][m][n][2] = ALPHA * x2 + sc * acc[ai][bj][m][n][2];
;             acc[ai][bj][m][n][3] = ALPHA * x3 + sc * acc[ai][bj][m][n][3];
.LBB0_397:
	s_lshl_b32 s1, s4, 19
	v_mbcnt_lo_u32_b32 v128, -1, 0
	v_mbcnt_hi_u32_b32 v128, -1, v128
	s_lshl_b32 s28, s0, 8
	v_lshlrev_b32_e32 v134, 4, v128
	s_add_i32 s0, s1, s45
	v_lshlrev_b32_e32 v133, 7, v128
	v_and_b32_e32 v134, 0x1f0, v134
	s_add_i32 s0, s0, s28
	s_mov_b32 m0, s47
	v_and_or_b32 v135, v133, s29, v134
	s_lshl_b32 s33, s0, 1
	buffer_load_dwordx4 v135, s[16:19], s33 offen lds
	v_or_b32_e32 v152, 0x2000, v135
	s_mov_b32 m0, s51
	v_or_b32_e32 v153, 0x4000, v135
	buffer_load_dwordx4 v152, s[16:19], s33 offen lds
	s_mov_b32 m0, s52
	v_or_b32_e32 v154, 0x6000, v135
	buffer_load_dwordx4 v153, s[16:19], s33 offen lds
	s_mov_b32 m0, s53
	v_or_b32_e32 v155, 0x8000, v135
	buffer_load_dwordx4 v154, s[16:19], s33 offen lds
	s_mov_b32 m0, s31
	v_or_b32_e32 v156, 0xa000, v135
	buffer_load_dwordx4 v155, s[16:19], s33 offen lds
	s_mov_b32 m0, s79
	v_and_b32_e32 v129, 15, v128
	buffer_load_dwordx4 v156, s[16:19], s33 offen lds
	v_or_b32_e32 v157, 0xc000, v135
	s_mov_b32 m0, s80
	v_add_u32_e32 v220, s34, v128
	v_bfe_u32 v130, v128, 4, 2
	v_lshlrev_b32_e32 v133, 4, v129
	buffer_load_dwordx4 v157, s[16:19], s33 offen lds
	v_or_b32_e32 v158, 0xe000, v135
	s_mov_b32 m0, s27
	v_ashrrev_i32_e32 v131, 2, v220
	v_lshl_or_b32 v146, v130, 11, v133
	buffer_load_dwordx4 v158, s[16:19], s33 offen lds
	s_mov_b32 s22, s18
	s_mov_b32 s23, s19
	s_mov_b32 m0, s46
	v_and_b32_e32 v222, 63, v128
	v_and_or_b32 v225, v131, s2, v129
	v_lshlrev_b32_e32 v129, 9, v128
	v_lshlrev_b32_e32 v128, 8, v128
	buffer_load_dwordx4 v146, s[20:23], s0 offen lds
	v_or_b32_e32 v159, 0x2000, v146
	s_mov_b32 m0, s76
	v_bfe_u32 v223, v220, 6, 2
	v_lshlrev_b32_e32 v132, 2, v130
	v_and_b32_e32 v134, 0x200, v129
	v_and_b32_e32 v128, 0x300, v128
	v_or_b32_e32 v149, 48, v225
	buffer_load_dwordx4 v159, s[20:23], s0 offen lds
	v_or_b32_e32 v160, 0x4000, v146
	s_mov_b32 m0, s77
	v_lshrrev_b32_e32 v129, 2, v225
	v_lshl_or_b32 v147, v223, 5, v132
	v_or_b32_e32 v148, 0x10400, v128
	v_lshrrev_b32_e32 v128, 1, v149
	buffer_load_dwordx4 v160, s[20:23], s0 offen lds
	v_or_b32_e32 v161, 0x6000, v146
	s_mov_b32 m0, s78
	v_mul_lo_u32 v129, v129, s50
	v_mad_u64_u32 v[132:133], s[6:7], v128, s50, v[134:135]
	buffer_load_dwordx4 v161, s[20:23], s0 offen lds
	v_lshrrev_b32_e32 v128, 1, v225
	v_add3_u32 v162, v148, v129, v147
	v_lshlrev_b32_e32 v133, 1, v147
	s_waitcnt vmcnt(0)
	s_barrier
	ds_read2_b32 v[136:137], v162 offset1:4
	v_mad_u64_u32 v[138:139], s[6:7], v128, s50, v[134:135]
	v_add_u32_e32 v166, v138, v133
	ds_read_b64 v[128:129], v166
	s_waitcnt lgkmcnt(1)
	v_lshlrev_b32_e32 v130, 24, v136
	v_ashrrev_i32_e32 v130, 16, v130
	v_and_b32_sdwa v131, sext(v136), s81 dst_sel:DWORD dst_unused:UNUSED_PAD src0_sel:WORD_0 src1_sel:DWORD
	v_or_b32_e32 v163, 32, v133
	s_waitcnt lgkmcnt(0)
	v_lshl_add_u32 v130, v128, 16, v130
	v_and_b32_e32 v128, 0xffff0000, v128
	v_add_u32_e32 v144, v131, v128
	v_bfe_i32 v128, v136, 8, 16
	v_and_b32_e32 v128, 0xffffff00, v128
	v_lshl_add_u32 v145, v129, 16, v128
	v_and_b32_e32 v128, 0xffff0000, v129
	v_and_b32_sdwa v129, sext(v136), s81 dst_sel:DWORD dst_unused:UNUSED_PAD src0_sel:WORD_1 src1_sel:DWORD
	v_or_b32_e32 v150, 0x100, v133
	v_add_u32_e32 v167, v138, v163
	v_add_u32_e32 v131, v129, v128
	v_add_u32_e32 v151, v132, v150
	v_add_u32_e32 v186, v138, v150
	ds_read_b64 v[140:141], v167
	ds_read_b64 v[142:143], v186
	ds_read_b64 v[188:189], v151
	v_pk_mul_f32 v[128:129], v[144:145], s[26:27] op_sel_hi:[1,0]
	v_mov_b32_e32 v144, v125
	v_pk_mul_f32 v[130:131], v[130:131], s[26:27] op_sel_hi:[1,0]
	v_mov_b32_e32 v125, v127
	v_pk_fma_f32 v[130:131], v[124:125], 0.5, v[130:131] op_sel_hi:[1,0,1]
	v_lshlrev_b32_e32 v124, 24, v137
	v_ashrrev_i32_e32 v124, 16, v124
	v_mov_b32_e32 v145, v126
	s_waitcnt lgkmcnt(2)
	v_lshl_add_u32 v126, v140, 16, v124
	v_and_b32_e32 v124, 0xffff0000, v140
	v_and_b32_sdwa v125, sext(v137), s81 dst_sel:DWORD dst_unused:UNUSED_PAD src0_sel:WORD_0 src1_sel:DWORD
	v_add_u32_e32 v124, v125, v124
	v_bfe_i32 v125, v137, 8, 16
	v_and_b32_e32 v125, 0xffffff00, v125
	v_lshl_add_u32 v125, v141, 16, v125
	v_and_b32_e32 v127, 0xffff0000, v141
	ds_read2_b32 v[140:141], v162 offset0:32 offset1:36
	v_and_b32_sdwa v136, sext(v137), s81 dst_sel:DWORD dst_unused:UNUSED_PAD src0_sel:WORD_1 src1_sel:DWORD
	v_add_u32_e32 v127, v136, v127
	v_mov_b32_e32 v136, v117
	v_pk_mul_f32 v[126:127], v[126:127], s[26:27] op_sel_hi:[1,0]
	v_mov_b32_e32 v117, v119
	v_mov_b32_e32 v137, v118
	v_pk_fma_f32 v[126:127], v[116:117], 0.5, v[126:127] op_sel_hi:[1,0,1]
	s_waitcnt lgkmcnt(2)
	v_and_b32_e32 v117, 0xffff0000, v142
	s_waitcnt lgkmcnt(0)
	v_and_b32_sdwa v118, sext(v140), s81 dst_sel:DWORD dst_unused:UNUSED_PAD src0_sel:WORD_0 src1_sel:DWORD
	v_add_u32_e32 v118, v118, v117
	v_bfe_i32 v117, v140, 8, 16
	v_pk_mul_f32 v[124:125], v[124:125], s[26:27] op_sel_hi:[1,0]
	v_lshlrev_b32_e32 v116, 24, v140
	v_and_b32_e32 v117, 0xffffff00, v117
	v_pk_fma_f32 v[124:125], v[136:137], 0.5, v[124:125] op_sel_hi:[1,0,1]
	v_ashrrev_i32_e32 v116, 16, v116
	v_lshl_add_u32 v119, v143, 16, v117
	v_and_b32_e32 v117, 0xffff0000, v143
	v_and_b32_sdwa v136, sext(v140), s81 dst_sel:DWORD dst_unused:UNUSED_PAD src0_sel:WORD_1 src1_sel:DWORD
	v_lshl_add_u32 v116, v142, 16, v116
	v_add_u32_e32 v117, v136, v117
	v_or_b32_e32 v140, 0x120, v133
	v_pk_fma_f32 v[128:129], v[144:145], 0.5, v[128:129] op_sel_hi:[1,0,1]
	v_mov_b32_e32 v136, v121
	v_pk_mul_f32 v[116:117], v[116:117], s[26:27] op_sel_hi:[1,0]
	v_mov_b32_e32 v121, v123
	v_add_u32_e32 v144, v138, v140
	v_pk_fma_f32 v[120:121], v[120:121], 0.5, v[116:117] op_sel_hi:[1,0,1]
	ds_read_b64 v[116:117], v144
	v_pk_mul_f32 v[118:119], v[118:119], s[26:27] op_sel_hi:[1,0]
	v_mov_b32_e32 v137, v122
	v_lshlrev_b32_e32 v122, 24, v141
	v_or_b32_e32 v142, 16, v225
	v_pk_fma_f32 v[118:119], v[136:137], 0.5, v[118:119] op_sel_hi:[1,0,1]
	v_ashrrev_i32_e32 v136, 16, v122
	v_lshrrev_b32_e32 v122, 1, v142
	v_mad_u64_u32 v[122:123], s[6:7], v122, s50, v[134:135]
	s_waitcnt lgkmcnt(0)
; #define BAR __builtin_amdgcn_s_barrier()
;     ...
;         _Pragma("unroll") for (int ai = 0; ai < 2; ++ai) {
;           const int rbase = brow + ai * HALF;
;           const int hso = ((rbase + 16 * wave) * DM + pn * BM) * 2;
;           const int lso = (rbase + 16 * wave) * DM + pn * BM;
;           _Pragma("unroll") for (int i = 0; i < 8; ++i)
;             __builtin_amdgcn_raw_ptr_buffer_load_lds(rsXB, (__attribute__((address_space(3))) void*)(smem + (wave * 8 + i) * PIECE), 16,
;                                                      hvo + i * (2 * DM * 2), hso, 0, 0);
;           _Pragma("unroll") for (int i = 0; i < 4; ++i)
;             __builtin_amdgcn_raw_ptr_buffer_load_lds(rsLO, (__attribute__((address_space(3))) void*)(smem + LOBASE + (wave * 4 + i) * PIECE), 16,
;                                                      lvo + i * (4 * DM), lso, 0, 0);
;           WAIT_V(0); BAR;
;           _Pragma("unroll") for (int m = 0; m < 4; ++m) _Pragma("unroll") for (int bj = 0; bj < 2; ++bj) _Pragma("unroll") for (int n = 0; n < 2; ++n) {
;             const int rr = wr * 64 + m * 16 + fr;
;             const int cc = bj * HALF + wc * 32 + n * 16 + fq * 4;
;             const u32x2 hv = *reinterpret_cast<const u32x2*>(smem + (rr >> 1) * PIECE + (rr & 1) * 512 + cc * 2);
;             const unsigned lv = *reinterpret_cast<const unsigned*>(smem + LOBASE + (rr >> 2) * PIECE + (rr & 3) * 256 + cc);
;             float x0 = __int_as_float((int)(hv[0] << 16) + (((int)(lv << 24)) >> 24) * 256);
;             float x1 = __int_as_float((int)(hv[0] & 0xffff0000u) + (((int)(lv << 16)) >> 24) * 256);
;             float x2 = __int_as_float((int)(hv[1] << 16) + (((int)(lv << 8)) >> 24) * 256);
;             float x3 = __int_as_float((int)(hv[1] & 0xffff0000u) + (((int)lv) >> 24) * 256);
;             acc[ai][bj][m][n][0] = ALPHA * x0 + sc * acc[ai][bj][m][n][0];
;             acc[ai][bj][m][n][1] = ALPHA * x1 + sc * acc[ai][bj][m][n][1];
;             acc[ai][bj][m][n][2] = ALPHA * x2 + sc * acc[ai][bj][m][n][2];
;             acc[ai][bj][m][n][3] = ALPHA * x3 + sc * acc[ai][bj][m][n][3];
;           }
;           WAIT_L(0); BAR;
;         }
;       }
;       float* red = reinterpret_cast<float*>(smem + 8 * HTB);
;       const int bp16 = (lane ^ 16) << 2, bp32 = (lane ^ 32) << 2;
;       float* red2 = red + 4 * 256 * 2;
;       float* mr = red2 + 2 * 256 * 2;
	v_lshl_add_u32 v136, v116, 16, v136
	v_and_b32_e32 v116, 0xffff0000, v116
	v_and_b32_sdwa v123, sext(v141), s81 dst_sel:DWORD dst_unused:UNUSED_PAD src0_sel:WORD_0 src1_sel:DWORD
	v_add_u32_e32 v138, v123, v116
	v_bfe_i32 v116, v141, 8, 16
	v_and_b32_e32 v116, 0xffffff00, v116
	v_lshl_add_u32 v139, v117, 16, v116
	v_and_b32_e32 v116, 0xffff0000, v117
	v_and_b32_sdwa v117, sext(v141), s81 dst_sel:DWORD dst_unused:UNUSED_PAD src0_sel:WORD_1 src1_sel:DWORD
	v_add_u32_e32 v137, v117, v116
	v_pk_mul_f32 v[116:117], v[138:139], s[26:27] op_sel_hi:[1,0]
	v_mov_b32_e32 v139, v114
	v_lshrrev_b32_e32 v114, 2, v142
	v_add_u32_e32 v145, v122, v133
	v_add_u32_e32 v164, v122, v163
	v_add_u32_e32 v165, v122, v150
	v_mul_lo_u32 v114, v114, s50
	v_add_u32_e32 v170, v122, v140
	v_or_b32_e32 v122, 32, v225
	v_add3_u32 v168, v148, v114, v147
	v_lshrrev_b32_e32 v114, 1, v122
	v_mov_b32_e32 v138, v113
	v_mov_b32_e32 v113, v115
	v_mad_u64_u32 v[114:115], s[6:7], v114, s50, v[134:135]
	v_lshrrev_b32_e32 v115, 2, v122
	v_add_u32_e32 v134, v114, v133
	v_add_u32_e32 v190, v114, v163
	v_add_u32_e32 v150, v114, v150
	v_add_u32_e32 v224, v114, v140
	v_lshrrev_b32_e32 v114, 2, v149
	v_mul_lo_u32 v115, v115, s50
	v_mul_lo_u32 v114, v114, s50
	s_add_i32 s1, s0, 0x40000
	v_pk_mul_f32 v[136:137], v[136:137], s[26:27] op_sel_hi:[1,0]
	v_add3_u32 v187, v148, v115, v147
	v_add_u32_e32 v226, v132, v133
	v_add3_u32 v133, v148, v114, v147
	s_lshl_b32 s3, s1, 1
	s_mov_b32 m0, s47
	ds_read_b64 v[214:215], v145
	ds_read_b64 v[210:211], v164
	ds_read_b64 v[206:207], v165
	v_pk_fma_f32 v[116:117], v[138:139], 0.5, v[116:117] op_sel_hi:[1,0,1]
	v_pk_fma_f32 v[112:113], v[112:113], 0.5, v[136:137] op_sel_hi:[1,0,1]
	ds_read2_b32 v[212:213], v168 offset1:4
	ds_read2_b32 v[138:139], v168 offset0:32 offset1:36
	ds_read2_b32 v[202:203], v187 offset1:4
	ds_read_b64 v[208:209], v170
	ds_read_b64 v[136:137], v134
	ds_read_b64 v[204:205], v190
	ds_read_b64 v[200:201], v150
	ds_read2_b32 v[142:143], v187 offset0:32 offset1:36
	ds_read2_b32 v[114:115], v133 offset1:4
	v_add_u32_e32 v227, v132, v163
	ds_read2_b32 v[194:195], v133 offset0:32 offset1:36
	v_add_u32_e32 v228, v132, v140
	ds_read_b64 v[198:199], v224
	ds_read_b64 v[140:141], v226
	ds_read_b64 v[122:123], v227
	ds_read_b64 v[196:197], v228
	s_waitcnt lgkmcnt(0)
	s_barrier
	buffer_load_dwordx4 v135, s[16:19], s3 offen lds
	s_mov_b32 m0, s51
	v_add_f32_e32 v132, 0, v130
	buffer_load_dwordx4 v152, s[16:19], s3 offen lds
	s_mov_b32 m0, s52
	v_mov_b32_e32 v135, v129
	buffer_load_dwordx4 v153, s[16:19], s3 offen lds
	s_mov_b32 m0, s53
	v_mul_f32_e32 v152, v112, v112
	buffer_load_dwordx4 v154, s[16:19], s3 offen lds
	s_mov_b32 m0, s31
	v_lshlrev_b32_e32 v229, 2, v222
	buffer_load_dwordx4 v155, s[16:19], s3 offen lds
	s_mov_b32 m0, s79
	v_xor_b32_e32 v221, 64, v229
	buffer_load_dwordx4 v156, s[16:19], s3 offen lds
	s_mov_b32 m0, s80
	v_lshlrev_b32_e32 v223, 9, v223
	buffer_load_dwordx4 v157, s[16:19], s3 offen lds
	s_mov_b32 m0, s27
	v_cmp_gt_u32_e32 vcc, 16, v222
	buffer_load_dwordx4 v158, s[16:19], s3 offen lds
	s_mov_b32 m0, s46
	v_lshlrev_b32_e32 v222, 3, v225
	buffer_load_dwordx4 v146, s[20:23], s1 offen lds
	s_mov_b32 m0, s76
	v_lshlrev_b32_e32 v223, 2, v223
	buffer_load_dwordx4 v159, s[20:23], s1 offen lds
	s_mov_b32 m0, s77
	s_nop 0
	buffer_load_dwordx4 v160, s[20:23], s1 offen lds
	s_mov_b32 m0, s78
	s_nop 0
	buffer_load_dwordx4 v161, s[20:23], s1 offen lds
	s_waitcnt vmcnt(0)
	s_barrier
	ds_read2_b32 v[184:185], v162 offset1:4
	ds_read2_b32 v[180:181], v162 offset0:32 offset1:36
	ds_read2_b32 v[174:175], v168 offset1:4
	ds_read_b64 v[182:183], v144
	ds_read_b64 v[178:179], v145
	ds_read_b64 v[176:177], v164
	ds_read_b64 v[172:173], v165
	ds_read2_b32 v[168:169], v168 offset0:32 offset1:36
	ds_read2_b32 v[160:161], v187 offset1:4
	ds_read_b64 v[170:171], v170
	ds_read_b64 v[164:165], v134
	ds_read_b64 v[162:163], v190
	ds_read_b64 v[158:159], v150
	ds_read2_b32 v[156:157], v187 offset0:32 offset1:36
	ds_read2_b32 v[148:149], v133 offset1:4
	ds_read_b64 v[192:193], v166
	ds_read_b64 v[190:191], v167
	ds_read_b64 v[186:187], v186
	ds_read_b64 v[146:147], v151
	ds_read2_b32 v[144:145], v133 offset0:32 offset1:36
	v_add_f32_e32 v134, v132, v128
	v_pk_mul_f32 v[132:133], v[128:129], v[128:129]
	v_add_f32_e32 v134, v129, v134
	v_pk_fma_f32 v[132:133], v[130:131], v[130:131], v[132:133]
	v_add_f32_e32 v151, v131, v134
	v_mul_f32_e32 v150, v129, v129
	v_mov_b32_e32 v134, v131
	v_pk_add_f32 v[132:133], v[150:151], v[132:133] op_sel_hi:[0,1]
	v_pk_fma_f32 v[132:133], v[134:135], v[134:135], v[132:133]
	v_add_f32_e32 v134, v126, v151
	v_add_f32_e32 v151, v124, v134
	v_mul_f32_e32 v150, v126, v126
	v_mov_b32_e32 v134, v124
	v_mov_b32_e32 v135, v126
	v_pk_add_f32 v[132:133], v[150:151], v[132:133] op_sel_hi:[0,1]
	v_pk_fma_f32 v[132:133], v[134:135], v[134:135], v[132:133]
	v_add_f32_e32 v134, v125, v151
	v_add_f32_e32 v151, v127, v134
	v_mul_f32_e32 v150, v125, v125
	v_mov_b32_e32 v134, v127
	v_mov_b32_e32 v135, v125
	v_pk_add_f32 v[132:133], v[150:151], v[132:133] op_sel_hi:[0,1]
	v_pk_fma_f32 v[132:133], v[134:135], v[134:135], v[132:133]
	v_add_f32_e32 v134, v120, v151
	v_add_f32_e32 v151, v118, v134
	v_mul_f32_e32 v150, v120, v120
	v_mov_b32_e32 v134, v118
	v_mov_b32_e32 v135, v120
	v_pk_add_f32 v[132:133], v[150:151], v[132:133] op_sel_hi:[0,1]
	v_pk_fma_f32 v[132:133], v[134:135], v[134:135], v[132:133]
	v_add_f32_e32 v134, v119, v151
	v_add_f32_e32 v151, v121, v134
	v_mul_f32_e32 v150, v119, v119
	v_mov_b32_e32 v134, v121
	v_mov_b32_e32 v135, v119
	v_pk_add_f32 v[132:133], v[150:151], v[132:133] op_sel_hi:[0,1]
	v_pk_fma_f32 v[132:133], v[134:135], v[134:135], v[132:133]
	v_add_f32_e32 v134, v112, v151
	v_mov_b32_e32 v150, v116
	v_mov_b32_e32 v151, v112
	v_pk_add_f32 v[132:133], v[152:153], v[132:133] op_sel_hi:[0,1]
	v_pk_fma_f32 v[132:133], v[150:151], v[150:151], v[132:133]
	v_pk_mul_f32 v[150:151], v[116:117], v[116:117]
	v_add_f32_e32 v134, v116, v134
	v_pk_mul_f32 v[152:153], v[112:113], v[112:113]
	v_pk_mov_b32 v[132:133], v[116:117], v[132:133] op_sel:[1,0]
	v_mov_b32_e32 v135, v151
	v_pk_add_f32 v[132:133], v[132:133], v[134:135]
	v_mov_b32_e32 v152, v113
	v_pk_add_f32 v[132:133], v[152:153], v[132:133]
	ds_bpermute_b32 v134, v221, v132
	ds_bpermute_b32 v135, v221, v133
	ds_read_b64 v[166:167], v224
	ds_read_b64 v[154:155], v226
	ds_read_b64 v[152:153], v227
	ds_read_b64 v[150:151], v228
	v_xor_b32_e32 v224, 0x80, v229
	s_waitcnt lgkmcnt(0)
	s_barrier
	v_pk_add_f32 v[132:133], v[132:133], v[134:135]
	ds_bpermute_b32 v134, v224, v132
	ds_bpermute_b32 v135, v224, v133
	s_and_saveexec_b64 s[6:7], vcc
	s_cbranch_execz .LBB0_399
	v_add3_u32 v225, v222, v223, s19
	s_waitcnt lgkmcnt(0)
	v_pk_add_f32 v[132:133], v[132:133], v[134:135]
	s_waitcnt vmcnt(0)
	ds_write_b64 v225, v[132:133]

; #define STAGE(P, RS, SOFF, OFF, kt) do { const int _so = (SOFF) + (kt) * (BK * 2); \
;     _Pragma("unroll") for (int _i = 0; _i < 2; ++_i) { \
;       __builtin_amdgcn_raw_ptr_buffer_load_lds(RS, (__attribute__((address_space(3))) void*)((P) + wave * 1024 + _i * 8192), 16, OFF[_i], _so, 0, 0); } } while (0)
; #define LDA(dst, b, h) _Pragma("unroll") for (int m = 0; m < 4; ++m) _Pragma("unroll") for (int k = 0; k < 2; ++k) \
;     dst[m][k] = *reinterpret_cast<const bf16x8*>(SA(b, h) + lds_byte(wr * 64 + m * 16 + fr, k * 32 + fq * 8))
; #define LDB(dst, b, h) _Pragma("unroll") for (int n = 0; n < 2; ++n) _Pragma("unroll") for (int k = 0; k < 2; ++k) \
;     dst[n][k] = *reinterpret_cast<const bf16x8*>(SB(b, h) + lds_byte(wc * 32 + n * 16 + fr, k * 32 + fq * 8))
; #define WAIT_V(n) asm volatile("s_waitcnt vmcnt(" #n ")" ::: "memory")
; #define WAIT_L(n) asm volatile("s_waitcnt lgkmcnt(" #n ")" ::: "memory")
; #define BAR __builtin_amdgcn_s_barrier()
; #define SCHED __builtin_amdgcn_sched_barrier(0)
;     ...
;     for (int t = 0; t < nt - 2; t += 2) {
;       LDB(B0, 0, 0); SCHED; LDA(At, 0, 0); STAGE(SA(1, 1), rsA, sA1, offA, t + 1);
;       WAIT_L(8); BAR; WAIT_L(0); MMA(0, 0, At, B0); BAR; SCHED;
;       LDB(B1, 0, 1); STAGE(SB(0, 0), rsB, sB0, offB, t + 2);
;       BAR; WAIT_L(0); MMA(0, 1, At, B1); BAR;
;       LDA(At, 0, 1); STAGE(SA(0, 0), rsA, sA0, offA, t + 2);
;       BAR; WAIT_L(0); MMA(1, 0, At, B0); BAR; SCHED;
;       STAGE(SB(0, 1), rsB, sB1, offB, t + 2);
;       WAIT_V(6); BAR; MMA(1, 1, At, B1); BAR;
.LBB0_494:
	ds_read_b128 v[152:155], v147
	ds_read_b128 v[156:159], v148
	ds_read_b128 v[160:163], v149
	ds_read_b128 v[164:167], v150
	s_add_i32 s5, s82, s3
	s_add_i32 s6, s5, 0x80
	s_mov_b32 m0, s36
	ds_read_b128 v[168:171], v129
	ds_read_b128 v[172:175], v129 offset:1024
	ds_read_b128 v[176:179], v132
	ds_read_b128 v[180:183], v132 offset:1024
	ds_read_b128 v[184:187], v131
	ds_read_b128 v[188:191], v131 offset:1024
	ds_read_b128 v[192:195], v130
	ds_read_b128 v[196:199], v130 offset:1024
	buffer_load_dwordx4 v141, s[8:11], s6 offen lds
	s_mov_b32 m0, s59
	s_nop 0
	buffer_load_dwordx4 v142, s[8:11], s6 offen lds
	s_waitcnt lgkmcnt(8)
	s_barrier
	s_waitcnt lgkmcnt(0)
	v_mfma_f32_16x16x32_bf16 v[124:127], v[152:155], v[168:171], v[124:127]
	v_mfma_f32_16x16x32_bf16 v[120:123], v[160:163], v[168:171], v[120:123]
	v_mfma_f32_16x16x32_bf16 v[116:119], v[152:155], v[176:179], v[116:119]
	v_mfma_f32_16x16x32_bf16 v[112:115], v[160:163], v[176:179], v[112:115]
	v_mfma_f32_16x16x32_bf16 v[108:111], v[152:155], v[184:187], v[108:111]
	v_mfma_f32_16x16x32_bf16 v[104:107], v[160:163], v[184:187], v[104:107]
	v_mfma_f32_16x16x32_bf16 v[100:103], v[152:155], v[192:195], v[100:103]
	v_mfma_f32_16x16x32_bf16 v[96:99], v[160:163], v[192:195], v[96:99]
	v_mfma_f32_16x16x32_bf16 v[124:127], v[156:159], v[172:175], v[124:127]
	v_mfma_f32_16x16x32_bf16 v[120:123], v[164:167], v[172:175], v[120:123]
	v_mfma_f32_16x16x32_bf16 v[116:119], v[156:159], v[180:183], v[116:119]
	v_mfma_f32_16x16x32_bf16 v[112:115], v[164:167], v[180:183], v[112:115]
	v_mfma_f32_16x16x32_bf16 v[108:111], v[156:159], v[188:191], v[108:111]
	v_mfma_f32_16x16x32_bf16 v[104:107], v[164:167], v[188:191], v[104:107]
	v_mfma_f32_16x16x32_bf16 v[100:103], v[156:159], v[196:199], v[100:103]
	v_mfma_f32_16x16x32_bf16 v[96:99], v[164:167], v[196:199], v[96:99]
	s_barrier
	s_add_i32 s6, s84, s3
	s_add_i32 s7, s6, 0x100
	s_mov_b32 s14, s10
	s_mov_b32 s15, s11
	s_mov_b32 m0, s37
	ds_read_b128 v[200:203], v143
	ds_read_b128 v[204:207], v144
	ds_read_b128 v[208:211], v145
	ds_read_b128 v[212:215], v146
	buffer_load_dwordx4 v141, s[12:15], s7 offen lds
	s_mov_b32 m0, s70
	s_nop 0
	buffer_load_dwordx4 v142, s[12:15], s7 offen lds
	s_barrier
	s_waitcnt lgkmcnt(0)
	v_mfma_f32_16x16x32_bf16 v[92:95], v[200:203], v[168:171], v[92:95]
	v_mfma_f32_16x16x32_bf16 v[88:91], v[208:211], v[168:171], v[88:91]
	v_mfma_f32_16x16x32_bf16 v[80:83], v[200:203], v[176:179], v[80:83]
	v_mfma_f32_16x16x32_bf16 v[68:71], v[208:211], v[176:179], v[68:71]
	v_mfma_f32_16x16x32_bf16 v[60:63], v[200:203], v[184:187], v[60:63]
	v_mfma_f32_16x16x32_bf16 v[56:59], v[208:211], v[184:187], v[56:59]
	v_mfma_f32_16x16x32_bf16 v[52:55], v[200:203], v[192:195], v[52:55]
	v_mfma_f32_16x16x32_bf16 v[48:51], v[208:211], v[192:195], v[48:51]
	v_mfma_f32_16x16x32_bf16 v[92:95], v[204:207], v[172:175], v[92:95]
	v_mfma_f32_16x16x32_bf16 v[88:91], v[212:215], v[172:175], v[88:91]
	v_mfma_f32_16x16x32_bf16 v[80:83], v[204:207], v[180:183], v[80:83]
	v_mfma_f32_16x16x32_bf16 v[68:71], v[212:215], v[180:183], v[68:71]
	v_mfma_f32_16x16x32_bf16 v[60:63], v[204:207], v[188:191], v[60:63]
	v_mfma_f32_16x16x32_bf16 v[56:59], v[212:215], v[188:191], v[56:59]
	v_mfma_f32_16x16x32_bf16 v[52:55], v[204:207], v[196:199], v[52:55]
	v_mfma_f32_16x16x32_bf16 v[48:51], v[212:215], v[196:199], v[48:51]
	s_add_i32 s7, s83, s3
	s_add_i32 s22, s7, 0x100
	s_mov_b32 m0, s35
	s_barrier
	ds_read_b128 v[168:171], v129 offset:16384
	ds_read_b128 v[172:175], v129 offset:17408
	ds_read_b128 v[176:179], v132 offset:16384
	ds_read_b128 v[180:183], v132 offset:17408
	ds_read_b128 v[184:187], v131 offset:16384
	ds_read_b128 v[188:191], v131 offset:17408
	ds_read_b128 v[192:195], v130 offset:16384
	ds_read_b128 v[196:199], v130 offset:17408
	buffer_load_dwordx4 v141, s[8:11], s22 offen lds
	s_mov_b32 m0, s95
	s_nop 0
	buffer_load_dwordx4 v142, s[8:11], s22 offen lds
	s_barrier
	s_waitcnt lgkmcnt(0)
	v_mfma_f32_16x16x32_bf16 v[44:47], v[152:155], v[168:171], v[44:47]
	v_mfma_f32_16x16x32_bf16 v[40:43], v[160:163], v[168:171], v[40:43]
	v_mfma_f32_16x16x32_bf16 v[36:39], v[152:155], v[176:179], v[36:39]
	v_mfma_f32_16x16x32_bf16 v[32:35], v[160:163], v[176:179], v[32:35]
	v_mfma_f32_16x16x32_bf16 v[28:31], v[152:155], v[184:187], v[28:31]
	v_mfma_f32_16x16x32_bf16 v[24:27], v[160:163], v[184:187], v[24:27]
	v_mfma_f32_16x16x32_bf16 v[20:23], v[152:155], v[192:195], v[20:23]
	v_mfma_f32_16x16x32_bf16 v[16:19], v[160:163], v[192:195], v[16:19]
	v_mfma_f32_16x16x32_bf16 v[44:47], v[156:159], v[172:175], v[44:47]
	v_mfma_f32_16x16x32_bf16 v[40:43], v[164:167], v[172:175], v[40:43]
	v_mfma_f32_16x16x32_bf16 v[36:39], v[156:159], v[180:183], v[36:39]
	v_mfma_f32_16x16x32_bf16 v[32:35], v[164:167], v[180:183], v[32:35]
	v_mfma_f32_16x16x32_bf16 v[28:31], v[156:159], v[188:191], v[28:31]
	v_mfma_f32_16x16x32_bf16 v[24:27], v[164:167], v[188:191], v[24:27]
	v_mfma_f32_16x16x32_bf16 v[20:23], v[156:159], v[196:199], v[20:23]
	v_mfma_f32_16x16x32_bf16 v[16:19], v[164:167], v[196:199], v[16:19]
	s_barrier
	s_add_i32 s22, s85, s3
	s_add_i32 s23, s22, 0x100
	s_mov_b32 m0, s38
	s_nop 0
	buffer_load_dwordx4 v141, s[12:15], s23 offen lds
	s_mov_b32 m0, s71
	s_nop 0
	buffer_load_dwordx4 v142, s[12:15], s23 offen lds
	s_waitcnt vmcnt(6)
	s_barrier
; #define STAGE(P, RS, SOFF, OFF, kt) do { const int _so = (SOFF) + (kt) * (BK * 2); \
;     _Pragma("unroll") for (int _i = 0; _i < 2; ++_i) { \
;       __builtin_amdgcn_raw_ptr_buffer_load_lds(RS, (__attribute__((address_space(3))) void*)((P) + wave * 1024 + _i * 8192), 16, OFF[_i], _so, 0, 0); } } while (0)
; #define LDA(dst, b, h) _Pragma("unroll") for (int m = 0; m < 4; ++m) _Pragma("unroll") for (int k = 0; k < 2; ++k) \
;     dst[m][k] = *reinterpret_cast<const bf16x8*>(SA(b, h) + lds_byte(wr * 64 + m * 16 + fr, k * 32 + fq * 8))
; #define LDB(dst, b, h) _Pragma("unroll") for (int n = 0; n < 2; ++n) _Pragma("unroll") for (int k = 0; k < 2; ++k) \
;     dst[n][k] = *reinterpret_cast<const bf16x8*>(SB(b, h) + lds_byte(wc * 32 + n * 16 + fr, k * 32 + fq * 8))
; #define WAIT_V(n) asm volatile("s_waitcnt vmcnt(" #n ")" ::: "memory")
; #define WAIT_L(n) asm volatile("s_waitcnt lgkmcnt(" #n ")" ::: "memory")
; #define BAR __builtin_amdgcn_s_barrier()
; #define SCHED __builtin_amdgcn_sched_barrier(0)
;     ...
;       WAIT_V(6); BAR; MMA(1, 1, At, B1); BAR;
;       LDB(B0, 1, 0); SCHED; LDA(At, 1, 0); STAGE(SA(0, 1), rsA, sA1, offA, t + 2);
;       WAIT_L(8); BAR; WAIT_L(0); MMA(0, 0, At, B0); BAR; SCHED;
;       LDB(B1, 1, 1); STAGE(SB(1, 0), rsB, sB0, offB, t + 3);
;       BAR; WAIT_L(0); MMA(0, 1, At, B1); BAR;
;       LDA(At, 1, 1); STAGE(SA(1, 0), rsA, sA0, offA, t + 3);
;       BAR; WAIT_L(0); MMA(1, 0, At, B0); BAR; SCHED;
;       STAGE(SB(1, 1), rsB, sB1, offB, t + 3);
;       WAIT_V(6); BAR; MMA(1, 1, At, B1); BAR;
	v_mfma_f32_16x16x32_bf16 v[12:15], v[200:203], v[168:171], v[12:15]
	v_mfma_f32_16x16x32_bf16 v[8:11], v[208:211], v[168:171], v[8:11]
	v_mfma_f32_16x16x32_bf16 v[4:7], v[200:203], v[176:179], v[4:7]
	v_mfma_f32_16x16x32_bf16 v[0:3], v[208:211], v[176:179], v[0:3]
	v_mfma_f32_16x16x32_bf16 v[64:67], v[200:203], v[184:187], v[64:67]
	v_mfma_f32_16x16x32_bf16 v[72:75], v[208:211], v[184:187], v[72:75]
	v_mfma_f32_16x16x32_bf16 v[76:79], v[200:203], v[192:195], v[76:79]
	v_mfma_f32_16x16x32_bf16 v[84:87], v[208:211], v[192:195], v[84:87]
	v_mfma_f32_16x16x32_bf16 v[12:15], v[204:207], v[172:175], v[12:15]
	v_mfma_f32_16x16x32_bf16 v[8:11], v[212:215], v[172:175], v[8:11]
	v_mfma_f32_16x16x32_bf16 v[4:7], v[204:207], v[180:183], v[4:7]
	v_mfma_f32_16x16x32_bf16 v[0:3], v[212:215], v[180:183], v[0:3]
	v_mfma_f32_16x16x32_bf16 v[64:67], v[204:207], v[188:191], v[64:67]
	v_mfma_f32_16x16x32_bf16 v[72:75], v[212:215], v[188:191], v[72:75]
	v_mfma_f32_16x16x32_bf16 v[76:79], v[204:207], v[196:199], v[76:79]
	v_mfma_f32_16x16x32_bf16 v[84:87], v[212:215], v[196:199], v[84:87]
	s_barrier
	ds_read_b128 v[152:155], v137
	ds_read_b128 v[156:159], v138
	ds_read_b128 v[160:163], v139
	ds_read_b128 v[164:167], v140
	s_addk_i32 s5, 0x100
	s_mov_b32 m0, s39
	ds_read_b128 v[168:171], v129 offset:32768
	ds_read_b128 v[172:175], v129 offset:33792
	ds_read_b128 v[176:179], v132 offset:32768
	ds_read_b128 v[180:183], v132 offset:33792
	ds_read_b128 v[184:187], v131 offset:32768
	ds_read_b128 v[188:191], v131 offset:33792
	ds_read_b128 v[192:195], v130 offset:32768
	ds_read_b128 v[196:199], v130 offset:33792
	buffer_load_dwordx4 v141, s[8:11], s5 offen lds
	s_mov_b32 m0, s97
	s_nop 0
	buffer_load_dwordx4 v142, s[8:11], s5 offen lds
	s_waitcnt lgkmcnt(8)
	s_barrier
	s_waitcnt lgkmcnt(0)
	v_mfma_f32_16x16x32_bf16 v[124:127], v[152:155], v[168:171], v[124:127]
	v_mfma_f32_16x16x32_bf16 v[120:123], v[160:163], v[168:171], v[120:123]
	v_mfma_f32_16x16x32_bf16 v[116:119], v[152:155], v[176:179], v[116:119]
	v_mfma_f32_16x16x32_bf16 v[112:115], v[160:163], v[176:179], v[112:115]
	v_mfma_f32_16x16x32_bf16 v[108:111], v[152:155], v[184:187], v[108:111]
	v_mfma_f32_16x16x32_bf16 v[104:107], v[160:163], v[184:187], v[104:107]
	v_mfma_f32_16x16x32_bf16 v[100:103], v[152:155], v[192:195], v[100:103]
	v_mfma_f32_16x16x32_bf16 v[96:99], v[160:163], v[192:195], v[96:99]
	v_mfma_f32_16x16x32_bf16 v[124:127], v[156:159], v[172:175], v[124:127]
	v_mfma_f32_16x16x32_bf16 v[120:123], v[164:167], v[172:175], v[120:123]
	v_mfma_f32_16x16x32_bf16 v[116:119], v[156:159], v[180:183], v[116:119]
	v_mfma_f32_16x16x32_bf16 v[112:115], v[164:167], v[180:183], v[112:115]
	v_mfma_f32_16x16x32_bf16 v[108:111], v[156:159], v[188:191], v[108:111]
	v_mfma_f32_16x16x32_bf16 v[104:107], v[164:167], v[188:191], v[104:107]
	v_mfma_f32_16x16x32_bf16 v[100:103], v[156:159], v[196:199], v[100:103]
	v_mfma_f32_16x16x32_bf16 v[96:99], v[164:167], v[196:199], v[96:99]
	s_barrier
	s_addk_i32 s6, 0x180
	s_mov_b32 m0, s92
	ds_read_b128 v[200:203], v133
	ds_read_b128 v[204:207], v134
	ds_read_b128 v[208:211], v135
	ds_read_b128 v[212:215], v136
	buffer_load_dwordx4 v141, s[12:15], s6 offen lds
	s_mov_b32 m0, s56
	s_nop 0
	buffer_load_dwordx4 v142, s[12:15], s6 offen lds
	s_barrier
	s_waitcnt lgkmcnt(0)
	v_mfma_f32_16x16x32_bf16 v[92:95], v[200:203], v[168:171], v[92:95]
	v_mfma_f32_16x16x32_bf16 v[88:91], v[208:211], v[168:171], v[88:91]
	v_mfma_f32_16x16x32_bf16 v[80:83], v[200:203], v[176:179], v[80:83]
	v_mfma_f32_16x16x32_bf16 v[68:71], v[208:211], v[176:179], v[68:71]
	v_mfma_f32_16x16x32_bf16 v[60:63], v[200:203], v[184:187], v[60:63]
	v_mfma_f32_16x16x32_bf16 v[56:59], v[208:211], v[184:187], v[56:59]
	v_mfma_f32_16x16x32_bf16 v[52:55], v[200:203], v[192:195], v[52:55]
	v_mfma_f32_16x16x32_bf16 v[48:51], v[208:211], v[192:195], v[48:51]
	v_mfma_f32_16x16x32_bf16 v[92:95], v[204:207], v[172:175], v[92:95]
	v_mfma_f32_16x16x32_bf16 v[88:91], v[212:215], v[172:175], v[88:91]
	v_mfma_f32_16x16x32_bf16 v[80:83], v[204:207], v[180:183], v[80:83]
	v_mfma_f32_16x16x32_bf16 v[68:71], v[212:215], v[180:183], v[68:71]
	v_mfma_f32_16x16x32_bf16 v[60:63], v[204:207], v[188:191], v[60:63]
	v_mfma_f32_16x16x32_bf16 v[56:59], v[212:215], v[188:191], v[56:59]
	v_mfma_f32_16x16x32_bf16 v[52:55], v[204:207], v[196:199], v[52:55]
	v_mfma_f32_16x16x32_bf16 v[48:51], v[212:215], v[196:199], v[48:51]
	s_addk_i32 s7, 0x180
	s_mov_b32 m0, s93
	s_barrier
	ds_read_b128 v[168:171], v129 offset:49152
	ds_read_b128 v[172:175], v129 offset:50176
	ds_read_b128 v[176:179], v132 offset:49152
	ds_read_b128 v[180:183], v132 offset:50176
	ds_read_b128 v[184:187], v131 offset:49152
	ds_read_b128 v[188:191], v131 offset:50176
	ds_read_b128 v[192:195], v130 offset:49152
	ds_read_b128 v[196:199], v130 offset:50176
	buffer_load_dwordx4 v141, s[8:11], s7 offen lds
	s_mov_b32 m0, s57
	s_nop 0
	buffer_load_dwordx4 v142, s[8:11], s7 offen lds
	s_barrier
	s_waitcnt lgkmcnt(0)
	v_mfma_f32_16x16x32_bf16 v[44:47], v[152:155], v[168:171], v[44:47]
	v_mfma_f32_16x16x32_bf16 v[40:43], v[160:163], v[168:171], v[40:43]
	v_mfma_f32_16x16x32_bf16 v[36:39], v[152:155], v[176:179], v[36:39]
	v_mfma_f32_16x16x32_bf16 v[32:35], v[160:163], v[176:179], v[32:35]
	v_mfma_f32_16x16x32_bf16 v[28:31], v[152:155], v[184:187], v[28:31]
	v_mfma_f32_16x16x32_bf16 v[24:27], v[160:163], v[184:187], v[24:27]
	v_mfma_f32_16x16x32_bf16 v[20:23], v[152:155], v[192:195], v[20:23]
	v_mfma_f32_16x16x32_bf16 v[16:19], v[160:163], v[192:195], v[16:19]
	v_mfma_f32_16x16x32_bf16 v[44:47], v[156:159], v[172:175], v[44:47]
	v_mfma_f32_16x16x32_bf16 v[40:43], v[164:167], v[172:175], v[40:43]
	v_mfma_f32_16x16x32_bf16 v[36:39], v[156:159], v[180:183], v[36:39]
	v_mfma_f32_16x16x32_bf16 v[32:35], v[164:167], v[180:183], v[32:35]
	v_mfma_f32_16x16x32_bf16 v[28:31], v[156:159], v[188:191], v[28:31]
	v_mfma_f32_16x16x32_bf16 v[24:27], v[164:167], v[188:191], v[24:27]
	v_mfma_f32_16x16x32_bf16 v[20:23], v[156:159], v[196:199], v[20:23]
	v_mfma_f32_16x16x32_bf16 v[16:19], v[164:167], v[196:199], v[16:19]
	s_barrier
; #define STAGE(P, RS, SOFF, OFF, kt) do { const int _so = (SOFF) + (kt) * (BK * 2); \
;     _Pragma("unroll") for (int _i = 0; _i < 2; ++_i) { \
;       __builtin_amdgcn_raw_ptr_buffer_load_lds(RS, (__attribute__((address_space(3))) void*)((P) + wave * 1024 + _i * 8192), 16, OFF[_i], _so, 0, 0); } } while (0)
; #define LDA(dst, b, h) _Pragma("unroll") for (int m = 0; m < 4; ++m) _Pragma("unroll") for (int k = 0; k < 2; ++k) \
;     dst[m][k] = *reinterpret_cast<const bf16x8*>(SA(b, h) + lds_byte(wr * 64 + m * 16 + fr, k * 32 + fq * 8))
; #define LDB(dst, b, h) _Pragma("unroll") for (int n = 0; n < 2; ++n) _Pragma("unroll") for (int k = 0; k < 2; ++k) \
;     dst[n][k] = *reinterpret_cast<const bf16x8*>(SB(b, h) + lds_byte(wc * 32 + n * 16 + fr, k * 32 + fq * 8))
; #define WAIT_V(n) asm volatile("s_waitcnt vmcnt(" #n ")" ::: "memory")
; #define WAIT_L(n) asm volatile("s_waitcnt lgkmcnt(" #n ")" ::: "memory")
; #define BAR __builtin_amdgcn_s_barrier()
; #define SCHED __builtin_amdgcn_sched_barrier(0)
;     ...
;       WAIT_V(6); BAR; MMA(1, 1, At, B1); BAR;
;       LDB(B0, 1, 0); SCHED; LDA(At, 1, 0); STAGE(SA(0, 1), rsA, sA1, offA, t + 2);
;       WAIT_L(8); BAR; WAIT_L(0); MMA(0, 0, At, B0); BAR; SCHED;
;       LDB(B1, 1, 1); STAGE(SB(1, 0), rsB, sB0, offB, t + 3);
;       BAR; WAIT_L(0); MMA(0, 1, At, B1); BAR;
;       LDA(At, 1, 1); STAGE(SA(1, 0), rsA, sA0, offA, t + 3);
;       BAR; WAIT_L(0); MMA(1, 0, At, B0); BAR; SCHED;
;       STAGE(SB(1, 1), rsB, sB1, offB, t + 3);
;       WAIT_V(6); BAR; MMA(1, 1, At, B1); BAR;
;     }
;     { LDB(B0, 0, 0); LDA(At, 0, 0); STAGE(SA(1, 1), rsA, sA1, offA, nt - 1);
;       BAR; WAIT_L(0); MMA(0, 0, At, B0); BAR;
;       LDB(B1, 0, 1); BAR; WAIT_L(0); MMA(0, 1, At, B1); BAR;
;       LDA(At, 0, 1); WAIT_V(4); BAR; WAIT_L(0); MMA(1, 0, At, B0); MMA(1, 1, At, B1); BAR; }
;     { LDB(B0, 1, 0); LDA(At, 1, 0); WAIT_V(2); BAR; WAIT_L(0); MMA(0, 0, At, B0); BAR;
;       LDB(B1, 1, 1); WAIT_V(0); BAR; WAIT_L(0); MMA(0, 1, At, B1); BAR;
;       LDA(At, 1, 1); BAR; WAIT_L(0); MMA(1, 0, At, B0); MMA(1, 1, At, B1); BAR; }
	s_addk_i32 s22, 0x180
	s_mov_b32 m0, s94
	s_nop 0
	buffer_load_dwordx4 v141, s[12:15], s22 offen lds
	s_mov_b32 m0, s58
	s_nop 0
	buffer_load_dwordx4 v142, s[12:15], s22 offen lds
	s_waitcnt vmcnt(6)
	s_barrier
	v_mfma_f32_16x16x32_bf16 v[12:15], v[200:203], v[168:171], v[12:15]
	v_mfma_f32_16x16x32_bf16 v[8:11], v[208:211], v[168:171], v[8:11]
	v_mfma_f32_16x16x32_bf16 v[4:7], v[200:203], v[176:179], v[4:7]
	v_mfma_f32_16x16x32_bf16 v[0:3], v[208:211], v[176:179], v[0:3]
	v_mfma_f32_16x16x32_bf16 v[64:67], v[200:203], v[184:187], v[64:67]
	v_mfma_f32_16x16x32_bf16 v[72:75], v[208:211], v[184:187], v[72:75]
	v_mfma_f32_16x16x32_bf16 v[76:79], v[200:203], v[192:195], v[76:79]
	v_mfma_f32_16x16x32_bf16 v[84:87], v[208:211], v[192:195], v[84:87]
	v_mfma_f32_16x16x32_bf16 v[12:15], v[204:207], v[172:175], v[12:15]
	v_mfma_f32_16x16x32_bf16 v[8:11], v[212:215], v[172:175], v[8:11]
	v_mfma_f32_16x16x32_bf16 v[4:7], v[204:207], v[180:183], v[4:7]
	v_mfma_f32_16x16x32_bf16 v[0:3], v[212:215], v[180:183], v[0:3]
	v_mfma_f32_16x16x32_bf16 v[64:67], v[204:207], v[188:191], v[64:67]
	v_mfma_f32_16x16x32_bf16 v[72:75], v[212:215], v[188:191], v[72:75]
	v_mfma_f32_16x16x32_bf16 v[76:79], v[204:207], v[196:199], v[76:79]
	v_mfma_f32_16x16x32_bf16 v[84:87], v[212:215], v[196:199], v[84:87]
	s_add_i32 s1, s1, 2
	s_addk_i32 s3, 0x100
	s_cmp_gt_u32 s1, 59
	s_barrier
	s_cbranch_scc0 .LBB0_494
	s_add_i32 s1, s82, 0x1f80
	s_mov_b32 m0, s36
	ds_read_b128 v[152:155], v147
	ds_read_b128 v[156:159], v148
	ds_read_b128 v[160:163], v149
	ds_read_b128 v[148:151], v150
	ds_read_b128 v[164:167], v129
	ds_read_b128 v[168:171], v129 offset:1024
	ds_read_b128 v[172:175], v132
	ds_read_b128 v[176:179], v132 offset:1024
	ds_read_b128 v[180:183], v131
	ds_read_b128 v[184:187], v131 offset:1024
	ds_read_b128 v[188:191], v130
	ds_read_b128 v[192:195], v130 offset:1024
	buffer_load_dwordx4 v141, s[8:11], s1 offen lds
	s_mov_b32 m0, s59
	s_nop 0
	buffer_load_dwordx4 v142, s[8:11], s1 offen lds
	s_barrier
	s_waitcnt lgkmcnt(0)
	v_mfma_f32_16x16x32_bf16 v[124:127], v[152:155], v[164:167], v[124:127]
	v_mfma_f32_16x16x32_bf16 v[120:123], v[160:163], v[164:167], v[120:123]
	v_mfma_f32_16x16x32_bf16 v[116:119], v[152:155], v[172:175], v[116:119]
	v_mfma_f32_16x16x32_bf16 v[112:115], v[160:163], v[172:175], v[112:115]
	v_mfma_f32_16x16x32_bf16 v[108:111], v[152:155], v[180:183], v[108:111]
	v_mfma_f32_16x16x32_bf16 v[104:107], v[160:163], v[180:183], v[104:107]
	v_mfma_f32_16x16x32_bf16 v[100:103], v[152:155], v[188:191], v[100:103]
	v_mfma_f32_16x16x32_bf16 v[96:99], v[160:163], v[188:191], v[96:99]
	v_mfma_f32_16x16x32_bf16 v[124:127], v[156:159], v[168:171], v[124:127]
	v_mfma_f32_16x16x32_bf16 v[120:123], v[148:151], v[168:171], v[120:123]
	v_mfma_f32_16x16x32_bf16 v[116:119], v[156:159], v[176:179], v[116:119]
	v_mfma_f32_16x16x32_bf16 v[112:115], v[148:151], v[176:179], v[112:115]
	v_mfma_f32_16x16x32_bf16 v[108:111], v[156:159], v[184:187], v[108:111]
	v_mfma_f32_16x16x32_bf16 v[104:107], v[148:151], v[184:187], v[104:107]
	v_mfma_f32_16x16x32_bf16 v[100:103], v[156:159], v[192:195], v[100:103]
	v_mfma_f32_16x16x32_bf16 v[96:99], v[148:151], v[192:195], v[96:99]
	s_barrier
	ds_read_b128 v[196:199], v143
	ds_read_b128 v[200:203], v144
	ds_read_b128 v[142:145], v145
	ds_read_b128 v[204:207], v146
	s_barrier
	s_waitcnt lgkmcnt(0)
	v_mfma_f32_16x16x32_bf16 v[80:83], v[196:199], v[172:175], v[80:83]
	v_mfma_f32_16x16x32_bf16 v[68:71], v[142:145], v[172:175], v[68:71]
	v_mfma_f32_16x16x32_bf16 v[60:63], v[196:199], v[180:183], v[60:63]
	v_mfma_f32_16x16x32_bf16 v[56:59], v[142:145], v[180:183], v[56:59]
	v_mfma_f32_16x16x32_bf16 v[52:55], v[196:199], v[188:191], v[52:55]
	v_mfma_f32_16x16x32_bf16 v[48:51], v[142:145], v[188:191], v[48:51]
	v_mfma_f32_16x16x32_bf16 v[92:95], v[196:199], v[164:167], v[92:95]
	v_mfma_f32_16x16x32_bf16 v[88:91], v[142:145], v[164:167], v[88:91]
	v_mfma_f32_16x16x32_bf16 v[80:83], v[200:203], v[176:179], v[80:83]
	v_mfma_f32_16x16x32_bf16 v[68:71], v[204:207], v[176:179], v[68:71]
	v_mfma_f32_16x16x32_bf16 v[60:63], v[200:203], v[184:187], v[60:63]
	v_mfma_f32_16x16x32_bf16 v[56:59], v[204:207], v[184:187], v[56:59]
	v_mfma_f32_16x16x32_bf16 v[52:55], v[200:203], v[192:195], v[52:55]
	v_mfma_f32_16x16x32_bf16 v[48:51], v[204:207], v[192:195], v[48:51]
	v_mfma_f32_16x16x32_bf16 v[164:167], v[200:203], v[168:171], v[92:95]
	v_mfma_f32_16x16x32_bf16 v[168:171], v[204:207], v[168:171], v[88:91]
	s_barrier
	s_nop 0
	ds_read_b128 v[88:91], v129 offset:16384
	ds_read_b128 v[92:95], v129 offset:17408
	ds_read_b128 v[172:175], v132 offset:16384
	ds_read_b128 v[176:179], v132 offset:17408
	ds_read_b128 v[180:183], v131 offset:16384
	ds_read_b128 v[184:187], v131 offset:17408
	ds_read_b128 v[188:191], v130 offset:16384
	ds_read_b128 v[192:195], v130 offset:17408
	s_waitcnt vmcnt(4)
	s_barrier
; #define LDA(dst, b, h) _Pragma("unroll") for (int m = 0; m < 4; ++m) _Pragma("unroll") for (int k = 0; k < 2; ++k) \
;     dst[m][k] = *reinterpret_cast<const bf16x8*>(SA(b, h) + lds_byte(wr * 64 + m * 16 + fr, k * 32 + fq * 8))
; #define LDB(dst, b, h) _Pragma("unroll") for (int n = 0; n < 2; ++n) _Pragma("unroll") for (int k = 0; k < 2; ++k) \
;     dst[n][k] = *reinterpret_cast<const bf16x8*>(SB(b, h) + lds_byte(wc * 32 + n * 16 + fr, k * 32 + fq * 8))
; #define WAIT_V(n) asm volatile("s_waitcnt vmcnt(" #n ")" ::: "memory")
; #define WAIT_L(n) asm volatile("s_waitcnt lgkmcnt(" #n ")" ::: "memory")
; #define BAR __builtin_amdgcn_s_barrier()
;     ...
;       LDA(At, 0, 1); WAIT_V(4); BAR; WAIT_L(0); MMA(1, 0, At, B0); MMA(1, 1, At, B1); BAR; }
;     { LDB(B0, 1, 0); LDA(At, 1, 0); WAIT_V(2); BAR; WAIT_L(0); MMA(0, 0, At, B0); BAR;
;       LDB(B1, 1, 1); WAIT_V(0); BAR; WAIT_L(0); MMA(0, 1, At, B1); BAR;
;       LDA(At, 1, 1); BAR; WAIT_L(0); MMA(1, 0, At, B0); MMA(1, 1, At, B1); BAR; }
	s_waitcnt lgkmcnt(0)
	v_mfma_f32_16x16x32_bf16 v[44:47], v[152:155], v[88:91], v[44:47]
	v_mfma_f32_16x16x32_bf16 v[40:43], v[160:163], v[88:91], v[40:43]
	v_mfma_f32_16x16x32_bf16 v[36:39], v[152:155], v[172:175], v[36:39]
	v_mfma_f32_16x16x32_bf16 v[32:35], v[160:163], v[172:175], v[32:35]
	v_mfma_f32_16x16x32_bf16 v[28:31], v[152:155], v[180:183], v[28:31]
	v_mfma_f32_16x16x32_bf16 v[24:27], v[160:163], v[180:183], v[24:27]
	v_mfma_f32_16x16x32_bf16 v[20:23], v[152:155], v[188:191], v[20:23]
	v_mfma_f32_16x16x32_bf16 v[16:19], v[160:163], v[188:191], v[16:19]
	v_mfma_f32_16x16x32_bf16 v[44:47], v[156:159], v[92:95], v[44:47]
	v_mfma_f32_16x16x32_bf16 v[40:43], v[148:151], v[92:95], v[40:43]
	v_mfma_f32_16x16x32_bf16 v[36:39], v[156:159], v[176:179], v[36:39]
	v_mfma_f32_16x16x32_bf16 v[32:35], v[148:151], v[176:179], v[32:35]
	v_mfma_f32_16x16x32_bf16 v[28:31], v[156:159], v[184:187], v[28:31]
	v_mfma_f32_16x16x32_bf16 v[24:27], v[148:151], v[184:187], v[24:27]
	v_mfma_f32_16x16x32_bf16 v[20:23], v[156:159], v[192:195], v[20:23]
	v_mfma_f32_16x16x32_bf16 v[16:19], v[148:151], v[192:195], v[16:19]
	v_mfma_f32_16x16x32_bf16 v[4:7], v[196:199], v[172:175], v[4:7]
	v_mfma_f32_16x16x32_bf16 v[0:3], v[142:145], v[172:175], v[0:3]
	v_mfma_f32_16x16x32_bf16 v[12:15], v[196:199], v[88:91], v[12:15]
	v_mfma_f32_16x16x32_bf16 v[8:11], v[142:145], v[88:91], v[8:11]
	v_mfma_f32_16x16x32_bf16 v[64:67], v[196:199], v[180:183], v[64:67]
	v_mfma_f32_16x16x32_bf16 v[72:75], v[142:145], v[180:183], v[72:75]
	v_mfma_f32_16x16x32_bf16 v[76:79], v[196:199], v[188:191], v[76:79]
	v_mfma_f32_16x16x32_bf16 v[84:87], v[142:145], v[188:191], v[84:87]
	v_mfma_f32_16x16x32_bf16 v[4:7], v[200:203], v[176:179], v[4:7]
	v_mfma_f32_16x16x32_bf16 v[0:3], v[204:207], v[176:179], v[0:3]
	v_mfma_f32_16x16x32_bf16 v[142:145], v[200:203], v[92:95], v[12:15]
	v_mfma_f32_16x16x32_bf16 v[146:149], v[204:207], v[92:95], v[8:11]
	v_mfma_f32_16x16x32_bf16 v[150:153], v[200:203], v[184:187], v[64:67]
	v_mfma_f32_16x16x32_bf16 v[154:157], v[204:207], v[184:187], v[72:75]
	v_mfma_f32_16x16x32_bf16 v[158:161], v[200:203], v[192:195], v[76:79]
	v_mfma_f32_16x16x32_bf16 v[172:175], v[204:207], v[192:195], v[84:87]
	s_barrier
	ds_read_b128 v[8:11], v137
	ds_read_b128 v[12:15], v138
	ds_read_b128 v[176:179], v139
	ds_read_b128 v[138:141], v140
	ds_read_b128 v[64:67], v129 offset:32768
	ds_read_b128 v[84:87], v129 offset:33792
	ds_read_b128 v[180:183], v132 offset:32768
	ds_read_b128 v[184:187], v132 offset:33792
	ds_read_b128 v[188:191], v131 offset:32768
	ds_read_b128 v[192:195], v131 offset:33792
	ds_read_b128 v[196:199], v130 offset:32768
	ds_read_b128 v[200:203], v130 offset:33792
	s_waitcnt vmcnt(2)
	s_barrier
	s_waitcnt lgkmcnt(0)
	v_mfma_f32_16x16x32_bf16 v[72:75], v[8:11], v[64:67], v[124:127]
	v_mfma_f32_16x16x32_bf16 v[76:79], v[176:179], v[64:67], v[120:123]
	v_mfma_f32_16x16x32_bf16 v[88:91], v[8:11], v[180:183], v[116:119]
	v_mfma_f32_16x16x32_bf16 v[92:95], v[176:179], v[180:183], v[112:115]
	v_mfma_f32_16x16x32_bf16 v[112:115], v[8:11], v[188:191], v[108:111]
	v_mfma_f32_16x16x32_bf16 v[120:123], v[176:179], v[188:191], v[104:107]
	v_mfma_f32_16x16x32_bf16 v[100:103], v[8:11], v[196:199], v[100:103]
	v_mfma_f32_16x16x32_bf16 v[96:99], v[176:179], v[196:199], v[96:99]
	v_mfma_f32_16x16x32_bf16 v[124:127], v[12:15], v[84:87], v[72:75]
	v_mfma_f32_16x16x32_bf16 v[116:119], v[138:141], v[84:87], v[76:79]
	v_mfma_f32_16x16x32_bf16 v[108:111], v[12:15], v[184:187], v[88:91]
	v_mfma_f32_16x16x32_bf16 v[104:107], v[138:141], v[184:187], v[92:95]
	v_mfma_f32_16x16x32_bf16 v[92:95], v[12:15], v[192:195], v[112:115]
	v_mfma_f32_16x16x32_bf16 v[88:91], v[138:141], v[192:195], v[120:123]
	v_mfma_f32_16x16x32_bf16 v[76:79], v[12:15], v[200:203], v[100:103]
	v_mfma_f32_16x16x32_bf16 v[72:75], v[138:141], v[200:203], v[96:99]
	s_barrier
; #define LDA(dst, b, h) _Pragma("unroll") for (int m = 0; m < 4; ++m) _Pragma("unroll") for (int k = 0; k < 2; ++k) \
;     dst[m][k] = *reinterpret_cast<const bf16x8*>(SA(b, h) + lds_byte(wr * 64 + m * 16 + fr, k * 32 + fq * 8))
; #define LDB(dst, b, h) _Pragma("unroll") for (int n = 0; n < 2; ++n) _Pragma("unroll") for (int k = 0; k < 2; ++k) \
;     dst[n][k] = *reinterpret_cast<const bf16x8*>(SB(b, h) + lds_byte(wc * 32 + n * 16 + fr, k * 32 + fq * 8))
; #define WAIT_V(n) asm volatile("s_waitcnt vmcnt(" #n ")" ::: "memory")
; #define WAIT_L(n) asm volatile("s_waitcnt lgkmcnt(" #n ")" ::: "memory")
; #define BAR __builtin_amdgcn_s_barrier()
;     ...
;     { LDB(B0, 1, 0); LDA(At, 1, 0); WAIT_V(2); BAR; WAIT_L(0); MMA(0, 0, At, B0); BAR;
;       LDB(B1, 1, 1); WAIT_V(0); BAR; WAIT_L(0); MMA(0, 1, At, B1); BAR;
;       LDA(At, 1, 1); BAR; WAIT_L(0); MMA(1, 0, At, B0); MMA(1, 1, At, B1); BAR; }
;     if (wr == 0) BAR;
	ds_read_b128 v[204:207], v133
	ds_read_b128 v[208:211], v134
	ds_read_b128 v[212:215], v135
	ds_read_b128 v[134:137], v136
	s_waitcnt vmcnt(0)
	s_barrier
	s_waitcnt lgkmcnt(0)
	v_mfma_f32_16x16x32_bf16 v[96:99], v[204:207], v[64:67], v[164:167]
	v_mfma_f32_16x16x32_bf16 v[64:67], v[212:215], v[64:67], v[168:171]
	v_mfma_f32_16x16x32_bf16 v[80:83], v[204:207], v[180:183], v[80:83]
	v_mfma_f32_16x16x32_bf16 v[68:71], v[212:215], v[180:183], v[68:71]
	v_mfma_f32_16x16x32_bf16 v[60:63], v[204:207], v[188:191], v[60:63]
	v_mfma_f32_16x16x32_bf16 v[56:59], v[212:215], v[188:191], v[56:59]
	v_mfma_f32_16x16x32_bf16 v[52:55], v[204:207], v[196:199], v[52:55]
	v_mfma_f32_16x16x32_bf16 v[48:51], v[212:215], v[196:199], v[48:51]
	v_mfma_f32_16x16x32_bf16 v[120:123], v[208:211], v[84:87], v[96:99]
	v_mfma_f32_16x16x32_bf16 v[112:115], v[134:137], v[84:87], v[64:67]
	v_mfma_f32_16x16x32_bf16 v[100:103], v[208:211], v[184:187], v[80:83]
	v_mfma_f32_16x16x32_bf16 v[96:99], v[134:137], v[184:187], v[68:71]
	v_mfma_f32_16x16x32_bf16 v[84:87], v[208:211], v[192:195], v[60:63]
	v_mfma_f32_16x16x32_bf16 v[80:83], v[134:137], v[192:195], v[56:59]
	v_mfma_f32_16x16x32_bf16 v[68:71], v[208:211], v[200:203], v[52:55]
	v_mfma_f32_16x16x32_bf16 v[64:67], v[134:137], v[200:203], v[48:51]
	s_barrier
	s_nop 0
	ds_read_b128 v[48:51], v129 offset:49152
	ds_read_b128 v[162:165], v129 offset:50176
	ds_read_b128 v[52:55], v132 offset:49152
	ds_read_b128 v[166:169], v132 offset:50176
	ds_read_b128 v[180:183], v131 offset:49152
	ds_read_b128 v[184:187], v131 offset:50176
	ds_read_b128 v[188:191], v130 offset:49152
	ds_read_b128 v[130:133], v130 offset:50176
	s_barrier
	s_waitcnt lgkmcnt(0)
	v_mfma_f32_16x16x32_bf16 v[44:47], v[8:11], v[48:51], v[44:47]
	v_mfma_f32_16x16x32_bf16 v[40:43], v[176:179], v[48:51], v[40:43]
	v_mfma_f32_16x16x32_bf16 v[36:39], v[8:11], v[52:55], v[36:39]
	v_mfma_f32_16x16x32_bf16 v[32:35], v[176:179], v[52:55], v[32:35]
	v_mfma_f32_16x16x32_bf16 v[28:31], v[8:11], v[180:183], v[28:31]
	v_mfma_f32_16x16x32_bf16 v[24:27], v[176:179], v[180:183], v[24:27]
	v_mfma_f32_16x16x32_bf16 v[8:11], v[8:11], v[188:191], v[20:23]
	v_mfma_f32_16x16x32_bf16 v[16:19], v[176:179], v[188:191], v[16:19]
	v_mfma_f32_16x16x32_bf16 v[60:63], v[12:15], v[162:165], v[44:47]
	v_mfma_f32_16x16x32_bf16 v[56:59], v[138:141], v[162:165], v[40:43]
	v_mfma_f32_16x16x32_bf16 v[44:47], v[12:15], v[166:169], v[36:39]
	v_mfma_f32_16x16x32_bf16 v[40:43], v[138:141], v[166:169], v[32:35]
	v_mfma_f32_16x16x32_bf16 v[28:31], v[12:15], v[184:187], v[28:31]
	v_mfma_f32_16x16x32_bf16 v[24:27], v[138:141], v[184:187], v[24:27]
	v_mfma_f32_16x16x32_bf16 v[12:15], v[12:15], v[130:133], v[8:11]
	v_mfma_f32_16x16x32_bf16 v[8:11], v[138:141], v[130:133], v[16:19]
	v_mfma_f32_16x16x32_bf16 v[16:19], v[204:207], v[48:51], v[142:145]
	v_mfma_f32_16x16x32_bf16 v[20:23], v[212:215], v[48:51], v[146:149]
	v_mfma_f32_16x16x32_bf16 v[4:7], v[204:207], v[52:55], v[4:7]
	v_mfma_f32_16x16x32_bf16 v[0:3], v[212:215], v[52:55], v[0:3]
	v_mfma_f32_16x16x32_bf16 v[138:141], v[204:207], v[180:183], v[150:153]
	v_mfma_f32_16x16x32_bf16 v[142:145], v[212:215], v[180:183], v[154:157]
	v_mfma_f32_16x16x32_bf16 v[146:149], v[204:207], v[188:191], v[158:161]
	v_mfma_f32_16x16x32_bf16 v[150:153], v[212:215], v[188:191], v[172:175]
	v_mfma_f32_16x16x32_bf16 v[52:55], v[208:211], v[162:165], v[16:19]
	v_mfma_f32_16x16x32_bf16 v[48:51], v[134:137], v[162:165], v[20:23]
	v_mfma_f32_16x16x32_bf16 v[36:39], v[208:211], v[166:169], v[4:7]
	v_mfma_f32_16x16x32_bf16 v[32:35], v[134:137], v[166:169], v[0:3]
	v_mfma_f32_16x16x32_bf16 v[20:23], v[208:211], v[184:187], v[138:141]
	v_mfma_f32_16x16x32_bf16 v[16:19], v[134:137], v[184:187], v[142:145]
	v_mfma_f32_16x16x32_bf16 v[4:7], v[208:211], v[130:133], v[146:149]
	v_mfma_f32_16x16x32_bf16 v[0:3], v[134:137], v[130:133], v[150:153]
	v_cmp_gt_u32_e32 vcc, s76, v128
	s_barrier
	s_and_saveexec_b64 s[6:7], vcc
	s_cbranch_execz .LBB0_497
	s_barrier

; #define WAIT_V(n) asm volatile("s_waitcnt vmcnt(" #n ")" ::: "memory")
; #define BAR __builtin_amdgcn_s_barrier()
;     ...
;         constexpr int PIECE = 1024 + 16, LOBASE = 64 * PIECE;
;         const int hvo = (lane >> 5) * (DM * 2) + (lane & 31) * 16;
;         const int lvo = (lane >> 4) * DM + (lane & 15) * 16;
;         _Pragma("unroll") for (int ai = 0; ai < 2; ++ai) {
;           const int rbase = brow + ai * HALF;
;           const int hso = ((rbase + 16 * wave) * DM + pn * BM) * 2;
;           const int lso = (rbase + 16 * wave) * DM + pn * BM;
;           _Pragma("unroll") for (int i = 0; i < 8; ++i)
;             __builtin_amdgcn_raw_ptr_buffer_load_lds(rsXB, (__attribute__((address_space(3))) void*)(smem + (wave * 8 + i) * PIECE), 16,
;                                                      hvo + i * (2 * DM * 2), hso, 0, 0);
;           _Pragma("unroll") for (int i = 0; i < 4; ++i)
;             __builtin_amdgcn_raw_ptr_buffer_load_lds(rsLO, (__attribute__((address_space(3))) void*)(smem + LOBASE + (wave * 4 + i) * PIECE), 16,
;                                                      lvo + i * (4 * DM), lso, 0, 0);
;           WAIT_V(0); BAR;
;           _Pragma("unroll") for (int m = 0; m < 4; ++m) _Pragma("unroll") for (int bj = 0; bj < 2; ++bj) _Pragma("unroll") for (int n = 0; n < 2; ++n) {
;             const int rr = wr * 64 + m * 16 + fr;
;             const int cc = bj * HALF + wc * 32 + n * 16 + fq * 4;
;             const u32x2 hv = *reinterpret_cast<const u32x2*>(smem + (rr >> 1) * PIECE + (rr & 1) * 512 + cc * 2);
;             const unsigned lv = *reinterpret_cast<const unsigned*>(smem + LOBASE + (rr >> 2) * PIECE + (rr & 3) * 256 + cc);
;             float x0 = __int_as_float((int)(hv[0] << 16) + (((int)(lv << 24)) >> 24) * 256);
;             float x1 = __int_as_float((int)(hv[0] & 0xffff0000u) + (((int)(lv << 16)) >> 24) * 256);
;             float x2 = __int_as_float((int)(hv[1] << 16) + (((int)(lv << 8)) >> 24) * 256);
;             float x3 = __int_as_float((int)(hv[1] & 0xffff0000u) + (((int)lv) >> 24) * 256);
;             acc[ai][bj][m][n][0] = ALPHA * x0 + sc * acc[ai][bj][m][n][0];
;             acc[ai][bj][m][n][1] = ALPHA * x1 + sc * acc[ai][bj][m][n][1];
;             acc[ai][bj][m][n][2] = ALPHA * x2 + sc * acc[ai][bj][m][n][2];
;             acc[ai][bj][m][n][3] = ALPHA * x3 + sc * acc[ai][bj][m][n][3];
.LBB0_499:
	s_lshl_b32 s1, s4, 19
	v_mbcnt_lo_u32_b32 v128, -1, 0
	v_mbcnt_hi_u32_b32 v128, -1, v128
	s_lshl_b32 s28, s0, 8
	v_lshlrev_b32_e32 v134, 4, v128
	s_add_i32 s0, s1, s96
	v_lshlrev_b32_e32 v133, 7, v128
	v_and_b32_e32 v134, 0x1f0, v134
	s_add_i32 s0, s0, s28
	s_mov_b32 m0, s60
	v_and_or_b32 v135, v133, s75, v134
	s_lshl_b32 s33, s0, 1
	buffer_load_dwordx4 v135, s[16:19], s33 offen lds
	v_or_b32_e32 v152, 0x2000, v135
	s_mov_b32 m0, s62
	v_or_b32_e32 v153, 0x4000, v135
	buffer_load_dwordx4 v152, s[16:19], s33 offen lds
	s_mov_b32 m0, s63
	v_or_b32_e32 v154, 0x6000, v135
	buffer_load_dwordx4 v153, s[16:19], s33 offen lds
	s_mov_b32 m0, s64
	v_or_b32_e32 v155, 0x8000, v135
	buffer_load_dwordx4 v154, s[16:19], s33 offen lds
	s_mov_b32 m0, s65
	v_or_b32_e32 v156, 0xa000, v135
	buffer_load_dwordx4 v155, s[16:19], s33 offen lds
	s_mov_b32 m0, s66
	v_and_b32_e32 v129, 15, v128
	buffer_load_dwordx4 v156, s[16:19], s33 offen lds
	v_or_b32_e32 v157, 0xc000, v135
	s_mov_b32 m0, s67
	v_add_u32_e32 v220, s34, v128
	v_bfe_u32 v130, v128, 4, 2
	v_lshlrev_b32_e32 v133, 4, v129
	buffer_load_dwordx4 v157, s[16:19], s33 offen lds
	v_or_b32_e32 v158, 0xe000, v135
	s_mov_b32 m0, s68
	v_ashrrev_i32_e32 v131, 2, v220
	v_lshl_or_b32 v146, v130, 11, v133
	buffer_load_dwordx4 v158, s[16:19], s33 offen lds
	s_mov_b32 s22, s18
	s_mov_b32 s23, s19
	s_mov_b32 m0, s69
	v_and_b32_e32 v222, 63, v128
	v_and_or_b32 v225, v131, s31, v129
	v_lshlrev_b32_e32 v129, 9, v128
	v_lshlrev_b32_e32 v128, 8, v128
	buffer_load_dwordx4 v146, s[20:23], s0 offen lds
	v_or_b32_e32 v159, 0x2000, v146
	s_mov_b32 m0, s72
	v_bfe_u32 v223, v220, 6, 2
	v_lshlrev_b32_e32 v132, 2, v130
	v_and_b32_e32 v134, 0x200, v129
	v_and_b32_e32 v128, 0x300, v128
	v_or_b32_e32 v149, 48, v225
	buffer_load_dwordx4 v159, s[20:23], s0 offen lds
	v_or_b32_e32 v160, 0x4000, v146
	s_mov_b32 m0, s73
	v_lshrrev_b32_e32 v129, 2, v225
	v_lshl_or_b32 v147, v223, 5, v132
	v_or_b32_e32 v148, 0x10400, v128
	v_lshrrev_b32_e32 v128, 1, v149
	buffer_load_dwordx4 v160, s[20:23], s0 offen lds
	v_or_b32_e32 v161, 0x6000, v146
	s_mov_b32 m0, s74
	v_mul_lo_u32 v129, v129, s61
	v_mad_u64_u32 v[132:133], s[6:7], v128, s61, v[134:135]
	buffer_load_dwordx4 v161, s[20:23], s0 offen lds
	v_lshrrev_b32_e32 v128, 1, v225
	v_add3_u32 v162, v148, v129, v147
	v_lshlrev_b32_e32 v133, 1, v147
	s_waitcnt vmcnt(0)
	s_barrier
	ds_read2_b32 v[136:137], v162 offset1:4
	v_mad_u64_u32 v[138:139], s[6:7], v128, s61, v[134:135]
	v_add_u32_e32 v166, v138, v133
	ds_read_b64 v[128:129], v166
	s_waitcnt lgkmcnt(1)
	v_lshlrev_b32_e32 v130, 24, v136
	v_ashrrev_i32_e32 v130, 16, v130
	v_and_b32_sdwa v131, sext(v136), s77 dst_sel:DWORD dst_unused:UNUSED_PAD src0_sel:WORD_0 src1_sel:DWORD
	v_or_b32_e32 v163, 32, v133
	s_waitcnt lgkmcnt(0)
	v_lshl_add_u32 v130, v128, 16, v130
	v_and_b32_e32 v128, 0xffff0000, v128
	v_add_u32_e32 v144, v131, v128
	v_bfe_i32 v128, v136, 8, 16
	v_and_b32_e32 v128, 0xffffff00, v128
	v_lshl_add_u32 v145, v129, 16, v128
	v_and_b32_e32 v128, 0xffff0000, v129
	v_and_b32_sdwa v129, sext(v136), s77 dst_sel:DWORD dst_unused:UNUSED_PAD src0_sel:WORD_1 src1_sel:DWORD
	v_or_b32_e32 v150, 0x100, v133
	v_add_u32_e32 v167, v138, v163
	v_add_u32_e32 v131, v129, v128
	v_add_u32_e32 v151, v132, v150
	v_add_u32_e32 v186, v138, v150
	ds_read_b64 v[140:141], v167
	ds_read_b64 v[142:143], v186
	ds_read_b64 v[188:189], v151
	v_pk_mul_f32 v[128:129], v[144:145], s[26:27] op_sel_hi:[1,0]
	v_mov_b32_e32 v144, v125
	v_pk_mul_f32 v[130:131], v[130:131], s[26:27] op_sel_hi:[1,0]
	v_mov_b32_e32 v125, v127
	v_pk_fma_f32 v[130:131], v[124:125], 0.5, v[130:131] op_sel_hi:[1,0,1]
	v_lshlrev_b32_e32 v124, 24, v137
	v_ashrrev_i32_e32 v124, 16, v124
	v_mov_b32_e32 v145, v126
	s_waitcnt lgkmcnt(2)
	v_lshl_add_u32 v126, v140, 16, v124
	v_and_b32_e32 v124, 0xffff0000, v140
	v_and_b32_sdwa v125, sext(v137), s77 dst_sel:DWORD dst_unused:UNUSED_PAD src0_sel:WORD_0 src1_sel:DWORD
	v_add_u32_e32 v124, v125, v124
	v_bfe_i32 v125, v137, 8, 16
	v_and_b32_e32 v125, 0xffffff00, v125
	v_lshl_add_u32 v125, v141, 16, v125
	v_and_b32_e32 v127, 0xffff0000, v141
	ds_read2_b32 v[140:141], v162 offset0:32 offset1:36
	v_and_b32_sdwa v136, sext(v137), s77 dst_sel:DWORD dst_unused:UNUSED_PAD src0_sel:WORD_1 src1_sel:DWORD
	v_add_u32_e32 v127, v136, v127
	v_mov_b32_e32 v136, v117
	v_pk_mul_f32 v[126:127], v[126:127], s[26:27] op_sel_hi:[1,0]
	v_mov_b32_e32 v117, v119
	v_mov_b32_e32 v137, v118
	v_pk_fma_f32 v[126:127], v[116:117], 0.5, v[126:127] op_sel_hi:[1,0,1]
	s_waitcnt lgkmcnt(2)
	v_and_b32_e32 v117, 0xffff0000, v142
	s_waitcnt lgkmcnt(0)
	v_and_b32_sdwa v118, sext(v140), s77 dst_sel:DWORD dst_unused:UNUSED_PAD src0_sel:WORD_0 src1_sel:DWORD
	v_add_u32_e32 v118, v118, v117
	v_bfe_i32 v117, v140, 8, 16
	v_pk_mul_f32 v[124:125], v[124:125], s[26:27] op_sel_hi:[1,0]
	v_lshlrev_b32_e32 v116, 24, v140
	v_and_b32_e32 v117, 0xffffff00, v117
	v_pk_fma_f32 v[124:125], v[136:137], 0.5, v[124:125] op_sel_hi:[1,0,1]
	v_ashrrev_i32_e32 v116, 16, v116
	v_lshl_add_u32 v119, v143, 16, v117
	v_and_b32_e32 v117, 0xffff0000, v143
	v_and_b32_sdwa v136, sext(v140), s77 dst_sel:DWORD dst_unused:UNUSED_PAD src0_sel:WORD_1 src1_sel:DWORD
	v_lshl_add_u32 v116, v142, 16, v116
	v_add_u32_e32 v117, v136, v117
	v_or_b32_e32 v140, 0x120, v133
	v_pk_fma_f32 v[128:129], v[144:145], 0.5, v[128:129] op_sel_hi:[1,0,1]
	v_mov_b32_e32 v136, v121
	v_pk_mul_f32 v[116:117], v[116:117], s[26:27] op_sel_hi:[1,0]
	v_mov_b32_e32 v121, v123
	v_add_u32_e32 v144, v138, v140
	v_pk_fma_f32 v[120:121], v[120:121], 0.5, v[116:117] op_sel_hi:[1,0,1]
	ds_read_b64 v[116:117], v144
	v_pk_mul_f32 v[118:119], v[118:119], s[26:27] op_sel_hi:[1,0]
	v_mov_b32_e32 v137, v122
	v_lshlrev_b32_e32 v122, 24, v141
	v_or_b32_e32 v142, 16, v225
	v_pk_fma_f32 v[118:119], v[136:137], 0.5, v[118:119] op_sel_hi:[1,0,1]
	v_ashrrev_i32_e32 v136, 16, v122
	v_lshrrev_b32_e32 v122, 1, v142
	v_mad_u64_u32 v[122:123], s[6:7], v122, s61, v[134:135]
	s_waitcnt lgkmcnt(0)
; #define BAR __builtin_amdgcn_s_barrier()
;     ...
;         _Pragma("unroll") for (int ai = 0; ai < 2; ++ai) {
;           const int rbase = brow + ai * HALF;
;           const int hso = ((rbase + 16 * wave) * DM + pn * BM) * 2;
;           const int lso = (rbase + 16 * wave) * DM + pn * BM;
;           _Pragma("unroll") for (int i = 0; i < 8; ++i)
;             __builtin_amdgcn_raw_ptr_buffer_load_lds(rsXB, (__attribute__((address_space(3))) void*)(smem + (wave * 8 + i) * PIECE), 16,
;                                                      hvo + i * (2 * DM * 2), hso, 0, 0);
;           _Pragma("unroll") for (int i = 0; i < 4; ++i)
;             __builtin_amdgcn_raw_ptr_buffer_load_lds(rsLO, (__attribute__((address_space(3))) void*)(smem + LOBASE + (wave * 4 + i) * PIECE), 16,
;                                                      lvo + i * (4 * DM), lso, 0, 0);
;           WAIT_V(0); BAR;
;           _Pragma("unroll") for (int m = 0; m < 4; ++m) _Pragma("unroll") for (int bj = 0; bj < 2; ++bj) _Pragma("unroll") for (int n = 0; n < 2; ++n) {
;             const int rr = wr * 64 + m * 16 + fr;
;             const int cc = bj * HALF + wc * 32 + n * 16 + fq * 4;
;             const u32x2 hv = *reinterpret_cast<const u32x2*>(smem + (rr >> 1) * PIECE + (rr & 1) * 512 + cc * 2);
;             const unsigned lv = *reinterpret_cast<const unsigned*>(smem + LOBASE + (rr >> 2) * PIECE + (rr & 3) * 256 + cc);
;             float x0 = __int_as_float((int)(hv[0] << 16) + (((int)(lv << 24)) >> 24) * 256);
;             float x1 = __int_as_float((int)(hv[0] & 0xffff0000u) + (((int)(lv << 16)) >> 24) * 256);
;             float x2 = __int_as_float((int)(hv[1] << 16) + (((int)(lv << 8)) >> 24) * 256);
;             float x3 = __int_as_float((int)(hv[1] & 0xffff0000u) + (((int)lv) >> 24) * 256);
;             acc[ai][bj][m][n][0] = ALPHA * x0 + sc * acc[ai][bj][m][n][0];
;             acc[ai][bj][m][n][1] = ALPHA * x1 + sc * acc[ai][bj][m][n][1];
;             acc[ai][bj][m][n][2] = ALPHA * x2 + sc * acc[ai][bj][m][n][2];
;             acc[ai][bj][m][n][3] = ALPHA * x3 + sc * acc[ai][bj][m][n][3];
;           }
;           WAIT_L(0); BAR;
;         }
;       }
;       float* red = reinterpret_cast<float*>(smem + 8 * HTB);
;       const int bp16 = (lane ^ 16) << 2, bp32 = (lane ^ 32) << 2;
;       float* red2 = red + 4 * 256 * 2;
;       float* mr = red2 + 2 * 256 * 2;
	v_lshl_add_u32 v136, v116, 16, v136
	v_and_b32_e32 v116, 0xffff0000, v116
	v_and_b32_sdwa v123, sext(v141), s77 dst_sel:DWORD dst_unused:UNUSED_PAD src0_sel:WORD_0 src1_sel:DWORD
	v_add_u32_e32 v138, v123, v116
	v_bfe_i32 v116, v141, 8, 16
	v_and_b32_e32 v116, 0xffffff00, v116
	v_lshl_add_u32 v139, v117, 16, v116
	v_and_b32_e32 v116, 0xffff0000, v117
	v_and_b32_sdwa v117, sext(v141), s77 dst_sel:DWORD dst_unused:UNUSED_PAD src0_sel:WORD_1 src1_sel:DWORD
	v_add_u32_e32 v137, v117, v116
	v_pk_mul_f32 v[116:117], v[138:139], s[26:27] op_sel_hi:[1,0]
	v_mov_b32_e32 v139, v114
	v_lshrrev_b32_e32 v114, 2, v142
	v_add_u32_e32 v145, v122, v133
	v_add_u32_e32 v164, v122, v163
	v_add_u32_e32 v165, v122, v150
	v_mul_lo_u32 v114, v114, s61
	v_add_u32_e32 v170, v122, v140
	v_or_b32_e32 v122, 32, v225
	v_add3_u32 v168, v148, v114, v147
	v_lshrrev_b32_e32 v114, 1, v122
	v_mov_b32_e32 v138, v113
	v_mov_b32_e32 v113, v115
	v_mad_u64_u32 v[114:115], s[6:7], v114, s61, v[134:135]
	v_lshrrev_b32_e32 v115, 2, v122
	v_add_u32_e32 v134, v114, v133
	v_add_u32_e32 v190, v114, v163
	v_add_u32_e32 v150, v114, v150
	v_add_u32_e32 v224, v114, v140
	v_lshrrev_b32_e32 v114, 2, v149
	v_mul_lo_u32 v115, v115, s61
	v_mul_lo_u32 v114, v114, s61
	s_add_i32 s1, s0, 0x40000
	v_pk_mul_f32 v[136:137], v[136:137], s[26:27] op_sel_hi:[1,0]
	v_add3_u32 v187, v148, v115, v147
	v_add_u32_e32 v226, v132, v133
	v_add3_u32 v133, v148, v114, v147
	s_lshl_b32 s3, s1, 1
	s_mov_b32 m0, s60
	ds_read_b64 v[214:215], v145
	ds_read_b64 v[210:211], v164
	ds_read_b64 v[206:207], v165
	v_pk_fma_f32 v[116:117], v[138:139], 0.5, v[116:117] op_sel_hi:[1,0,1]
	v_pk_fma_f32 v[112:113], v[112:113], 0.5, v[136:137] op_sel_hi:[1,0,1]
	ds_read2_b32 v[212:213], v168 offset1:4
	ds_read2_b32 v[138:139], v168 offset0:32 offset1:36
	ds_read2_b32 v[202:203], v187 offset1:4
	ds_read_b64 v[208:209], v170
	ds_read_b64 v[136:137], v134
	ds_read_b64 v[204:205], v190
	ds_read_b64 v[200:201], v150
	ds_read2_b32 v[142:143], v187 offset0:32 offset1:36
	ds_read2_b32 v[114:115], v133 offset1:4
	v_add_u32_e32 v227, v132, v163
	ds_read2_b32 v[194:195], v133 offset0:32 offset1:36
	v_add_u32_e32 v228, v132, v140
	ds_read_b64 v[198:199], v224
	ds_read_b64 v[140:141], v226
	ds_read_b64 v[122:123], v227
	ds_read_b64 v[196:197], v228
	s_waitcnt lgkmcnt(0)
	s_barrier
	buffer_load_dwordx4 v135, s[16:19], s3 offen lds
	s_mov_b32 m0, s62
	v_add_f32_e32 v132, 0, v130
	buffer_load_dwordx4 v152, s[16:19], s3 offen lds
	s_mov_b32 m0, s63
	v_mov_b32_e32 v135, v129
	buffer_load_dwordx4 v153, s[16:19], s3 offen lds
	s_mov_b32 m0, s64
	v_mul_f32_e32 v152, v112, v112
	buffer_load_dwordx4 v154, s[16:19], s3 offen lds
	s_mov_b32 m0, s65
	v_lshlrev_b32_e32 v229, 2, v222
	buffer_load_dwordx4 v155, s[16:19], s3 offen lds
	s_mov_b32 m0, s66
	v_xor_b32_e32 v221, 64, v229
	buffer_load_dwordx4 v156, s[16:19], s3 offen lds
	s_mov_b32 m0, s67
	v_lshlrev_b32_e32 v223, 9, v223
	buffer_load_dwordx4 v157, s[16:19], s3 offen lds
	s_mov_b32 m0, s68
	v_cmp_gt_u32_e32 vcc, 16, v222
	buffer_load_dwordx4 v158, s[16:19], s3 offen lds
	s_mov_b32 m0, s69
	v_lshlrev_b32_e32 v222, 3, v225
	buffer_load_dwordx4 v146, s[20:23], s1 offen lds
	s_mov_b32 m0, s72
	v_lshlrev_b32_e32 v223, 2, v223
	buffer_load_dwordx4 v159, s[20:23], s1 offen lds
	s_mov_b32 m0, s73
	s_nop 0
	buffer_load_dwordx4 v160, s[20:23], s1 offen lds
	s_mov_b32 m0, s74
	s_nop 0
	buffer_load_dwordx4 v161, s[20:23], s1 offen lds
	s_waitcnt vmcnt(0)
	s_barrier
	ds_read2_b32 v[184:185], v162 offset1:4
	ds_read2_b32 v[180:181], v162 offset0:32 offset1:36
	ds_read2_b32 v[174:175], v168 offset1:4
	ds_read_b64 v[182:183], v144
	ds_read_b64 v[178:179], v145
	ds_read_b64 v[176:177], v164
	ds_read_b64 v[172:173], v165
	ds_read2_b32 v[168:169], v168 offset0:32 offset1:36
	ds_read2_b32 v[160:161], v187 offset1:4
	ds_read_b64 v[170:171], v170
	ds_read_b64 v[164:165], v134
	ds_read_b64 v[162:163], v190
	ds_read_b64 v[158:159], v150
	ds_read2_b32 v[156:157], v187 offset0:32 offset1:36
	ds_read2_b32 v[148:149], v133 offset1:4
	ds_read_b64 v[192:193], v166
	ds_read_b64 v[190:191], v167
	ds_read_b64 v[186:187], v186
	ds_read_b64 v[146:147], v151
	ds_read2_b32 v[144:145], v133 offset0:32 offset1:36
	v_add_f32_e32 v134, v132, v128
	v_pk_mul_f32 v[132:133], v[128:129], v[128:129]
	v_add_f32_e32 v134, v129, v134
	v_pk_fma_f32 v[132:133], v[130:131], v[130:131], v[132:133]
	v_add_f32_e32 v151, v131, v134
	v_mul_f32_e32 v150, v129, v129
	v_mov_b32_e32 v134, v131
	v_pk_add_f32 v[132:133], v[150:151], v[132:133] op_sel_hi:[0,1]
	v_pk_fma_f32 v[132:133], v[134:135], v[134:135], v[132:133]
	v_add_f32_e32 v134, v126, v151
	v_add_f32_e32 v151, v124, v134
	v_mul_f32_e32 v150, v126, v126
	v_mov_b32_e32 v134, v124
	v_mov_b32_e32 v135, v126
	v_pk_add_f32 v[132:133], v[150:151], v[132:133] op_sel_hi:[0,1]
	v_pk_fma_f32 v[132:133], v[134:135], v[134:135], v[132:133]
	v_add_f32_e32 v134, v125, v151
	v_add_f32_e32 v151, v127, v134
	v_mul_f32_e32 v150, v125, v125
	v_mov_b32_e32 v134, v127
	v_mov_b32_e32 v135, v125
	v_pk_add_f32 v[132:133], v[150:151], v[132:133] op_sel_hi:[0,1]
	v_pk_fma_f32 v[132:133], v[134:135], v[134:135], v[132:133]
	v_add_f32_e32 v134, v120, v151
	v_add_f32_e32 v151, v118, v134
	v_mul_f32_e32 v150, v120, v120
	v_mov_b32_e32 v134, v118
	v_mov_b32_e32 v135, v120
	v_pk_add_f32 v[132:133], v[150:151], v[132:133] op_sel_hi:[0,1]
	v_pk_fma_f32 v[132:133], v[134:135], v[134:135], v[132:133]
	v_add_f32_e32 v134, v119, v151
	v_add_f32_e32 v151, v121, v134
	v_mul_f32_e32 v150, v119, v119
	v_mov_b32_e32 v134, v121
	v_mov_b32_e32 v135, v119
	v_pk_add_f32 v[132:133], v[150:151], v[132:133] op_sel_hi:[0,1]
	v_pk_fma_f32 v[132:133], v[134:135], v[134:135], v[132:133]
	v_add_f32_e32 v134, v112, v151
	v_mov_b32_e32 v150, v116
	v_mov_b32_e32 v151, v112
	v_pk_add_f32 v[132:133], v[152:153], v[132:133] op_sel_hi:[0,1]
	v_pk_fma_f32 v[132:133], v[150:151], v[150:151], v[132:133]
	v_pk_mul_f32 v[150:151], v[116:117], v[116:117]
	v_add_f32_e32 v134, v116, v134
	v_pk_mul_f32 v[152:153], v[112:113], v[112:113]
	v_pk_mov_b32 v[132:133], v[116:117], v[132:133] op_sel:[1,0]
	v_mov_b32_e32 v135, v151
	v_pk_add_f32 v[132:133], v[132:133], v[134:135]
	v_mov_b32_e32 v152, v113
	v_pk_add_f32 v[132:133], v[152:153], v[132:133]
	ds_bpermute_b32 v134, v221, v132
	ds_bpermute_b32 v135, v221, v133
	ds_read_b64 v[166:167], v224
	ds_read_b64 v[154:155], v226
	ds_read_b64 v[152:153], v227
	ds_read_b64 v[150:151], v228
	v_xor_b32_e32 v224, 0x80, v229
	s_waitcnt lgkmcnt(0)
	s_barrier
	v_pk_add_f32 v[132:133], v[132:133], v[134:135]
	ds_bpermute_b32 v134, v224, v132
	ds_bpermute_b32 v135, v224, v133
	s_and_saveexec_b64 s[6:7], vcc
	s_cbranch_execz .LBB0_501
	v_add3_u32 v225, v222, v223, s19
	s_waitcnt lgkmcnt(0)
	v_pk_add_f32 v[132:133], v[132:133], v[134:135]
	s_waitcnt vmcnt(0)
	ds_write_b64 v225, v[132:133]

; #define STAGE(P, RS, SOFF, OFF, kt) do { const int _so = (SOFF) + (kt) * (BK * 2); \
;     _Pragma("unroll") for (int _i = 0; _i < 2; ++_i) { \
;       __builtin_amdgcn_raw_ptr_buffer_load_lds(RS, (__attribute__((address_space(3))) void*)((P) + wave * 1024 + _i * 8192), 16, OFF[_i], _so, 0, 0); } } while (0)
; #define LDA(dst, b, h) _Pragma("unroll") for (int m = 0; m < 4; ++m) _Pragma("unroll") for (int k = 0; k < 2; ++k) \
;     dst[m][k] = *reinterpret_cast<const bf16x8*>(SA(b, h) + lds_byte(wr * 64 + m * 16 + fr, k * 32 + fq * 8))
; #define LDB(dst, b, h) _Pragma("unroll") for (int n = 0; n < 2; ++n) _Pragma("unroll") for (int k = 0; k < 2; ++k) \
;     dst[n][k] = *reinterpret_cast<const bf16x8*>(SB(b, h) + lds_byte(wc * 32 + n * 16 + fr, k * 32 + fq * 8))
; #define WAIT_V(n) asm volatile("s_waitcnt vmcnt(" #n ")" ::: "memory")
; #define WAIT_L(n) asm volatile("s_waitcnt lgkmcnt(" #n ")" ::: "memory")
; #define BAR __builtin_amdgcn_s_barrier()
; #define SCHED __builtin_amdgcn_sched_barrier(0)
;     ...
;     for (int t = 0; t < nt - 2; t += 2) {
;       LDB(B0, 0, 0); SCHED; LDA(At, 0, 0); STAGE(SA(1, 1), rsA, sA1, offA, t + 1);
;       WAIT_L(8); BAR; WAIT_L(0); MMA(0, 0, At, B0); BAR; SCHED;
;       LDB(B1, 0, 1); STAGE(SB(0, 0), rsB, sB0, offB, t + 2);
;       BAR; WAIT_L(0); MMA(0, 1, At, B1); BAR;
;       LDA(At, 0, 1); STAGE(SA(0, 0), rsA, sA0, offA, t + 2);
;       BAR; WAIT_L(0); MMA(1, 0, At, B0); BAR; SCHED;
;       STAGE(SB(0, 1), rsB, sB1, offB, t + 2);
;       WAIT_V(6); BAR; MMA(1, 1, At, B1); BAR;
;       LDB(B0, 1, 0); SCHED; LDA(At, 1, 0); STAGE(SA(0, 1), rsA, sA1, offA, t + 2);
;       WAIT_L(8); BAR; WAIT_L(0); MMA(0, 0, At, B0); BAR; SCHED;
;       LDB(B1, 1, 1); STAGE(SB(1, 0), rsB, sB0, offB, t + 3);
.LBB0_556:
	ds_read_b128 v[154:157], v149
	ds_read_b128 v[158:161], v150
	ds_read_b128 v[162:165], v151
	ds_read_b128 v[166:169], v152
	s_add_i32 s43, s37, s17
	s_add_i32 s10, s43, 0x80
	s_mov_b32 m0, s30
	ds_read_b128 v[170:173], v131
	ds_read_b128 v[174:177], v131 offset:1024
	ds_read_b128 v[178:181], v134
	ds_read_b128 v[182:185], v134 offset:1024
	ds_read_b128 v[186:189], v133
	ds_read_b128 v[190:193], v133 offset:1024
	ds_read_b128 v[194:197], v132
	ds_read_b128 v[198:201], v132 offset:1024
	buffer_load_dwordx4 v143, s[4:7], s10 offen lds
	s_mov_b32 m0, s31
	s_nop 0
	buffer_load_dwordx4 v144, s[4:7], s10 offen lds
	s_waitcnt lgkmcnt(8)
	s_barrier
	s_waitcnt lgkmcnt(0)
	v_mfma_f32_16x16x32_bf16 v[124:127], v[154:157], v[170:173], v[124:127]
	v_mfma_f32_16x16x32_bf16 v[120:123], v[162:165], v[170:173], v[120:123]
	v_mfma_f32_16x16x32_bf16 v[116:119], v[154:157], v[178:181], v[116:119]
	v_mfma_f32_16x16x32_bf16 v[112:115], v[162:165], v[178:181], v[112:115]
	v_mfma_f32_16x16x32_bf16 v[108:111], v[154:157], v[186:189], v[108:111]
	v_mfma_f32_16x16x32_bf16 v[104:107], v[162:165], v[186:189], v[104:107]
	v_mfma_f32_16x16x32_bf16 v[100:103], v[154:157], v[194:197], v[100:103]
	v_mfma_f32_16x16x32_bf16 v[96:99], v[162:165], v[194:197], v[96:99]
	v_mfma_f32_16x16x32_bf16 v[124:127], v[158:161], v[174:177], v[124:127]
	v_mfma_f32_16x16x32_bf16 v[120:123], v[166:169], v[174:177], v[120:123]
	v_mfma_f32_16x16x32_bf16 v[116:119], v[158:161], v[182:185], v[116:119]
	v_mfma_f32_16x16x32_bf16 v[112:115], v[166:169], v[182:185], v[112:115]
	v_mfma_f32_16x16x32_bf16 v[108:111], v[158:161], v[190:193], v[108:111]
	v_mfma_f32_16x16x32_bf16 v[104:107], v[166:169], v[190:193], v[104:107]
	v_mfma_f32_16x16x32_bf16 v[100:103], v[158:161], v[198:201], v[100:103]
	v_mfma_f32_16x16x32_bf16 v[96:99], v[166:169], v[198:201], v[96:99]
	s_barrier
	s_add_i32 s44, s39, s17
	s_add_i32 s45, s44, 0x100
	s_mov_b32 s10, s6
	s_mov_b32 s11, s7
	s_mov_b32 m0, s1
	ds_read_b128 v[202:205], v145
	ds_read_b128 v[206:209], v146
	ds_read_b128 v[210:213], v147
	ds_read_b128 v[214:217], v148
	buffer_load_dwordx4 v143, s[8:11], s45 offen lds
	s_mov_b32 m0, s3
	s_nop 0
	buffer_load_dwordx4 v144, s[8:11], s45 offen lds
	s_barrier
	s_waitcnt lgkmcnt(0)
	v_mfma_f32_16x16x32_bf16 v[92:95], v[202:205], v[170:173], v[92:95]
	v_mfma_f32_16x16x32_bf16 v[88:91], v[210:213], v[170:173], v[88:91]
	v_mfma_f32_16x16x32_bf16 v[84:87], v[202:205], v[178:181], v[84:87]
	v_mfma_f32_16x16x32_bf16 v[80:83], v[210:213], v[178:181], v[80:83]
	v_mfma_f32_16x16x32_bf16 v[76:79], v[202:205], v[186:189], v[76:79]
	v_mfma_f32_16x16x32_bf16 v[72:75], v[210:213], v[186:189], v[72:75]
	v_mfma_f32_16x16x32_bf16 v[68:71], v[202:205], v[194:197], v[68:71]
	v_mfma_f32_16x16x32_bf16 v[64:67], v[210:213], v[194:197], v[64:67]
	v_mfma_f32_16x16x32_bf16 v[92:95], v[206:209], v[174:177], v[92:95]
	v_mfma_f32_16x16x32_bf16 v[88:91], v[214:217], v[174:177], v[88:91]
	v_mfma_f32_16x16x32_bf16 v[84:87], v[206:209], v[182:185], v[84:87]
	v_mfma_f32_16x16x32_bf16 v[80:83], v[214:217], v[182:185], v[80:83]
	v_mfma_f32_16x16x32_bf16 v[76:79], v[206:209], v[190:193], v[76:79]
	v_mfma_f32_16x16x32_bf16 v[72:75], v[214:217], v[190:193], v[72:75]
	v_mfma_f32_16x16x32_bf16 v[68:71], v[206:209], v[198:201], v[68:71]
	v_mfma_f32_16x16x32_bf16 v[64:67], v[214:217], v[198:201], v[64:67]
	s_add_i32 s45, s38, s17
	s_add_i32 s46, s45, 0x100
	s_mov_b32 m0, s0
	s_barrier
	ds_read_b128 v[170:173], v131 offset:16384
	ds_read_b128 v[174:177], v131 offset:17408
	ds_read_b128 v[178:181], v134 offset:16384
	ds_read_b128 v[182:185], v134 offset:17408
	ds_read_b128 v[186:189], v133 offset:16384
	ds_read_b128 v[190:193], v133 offset:17408
	ds_read_b128 v[194:197], v132 offset:16384
	ds_read_b128 v[198:201], v132 offset:17408
	buffer_load_dwordx4 v143, s[4:7], s46 offen lds
	s_mov_b32 m0, s18
	s_nop 0
	buffer_load_dwordx4 v144, s[4:7], s46 offen lds
	s_barrier
	s_waitcnt lgkmcnt(0)
	v_mfma_f32_16x16x32_bf16 v[60:63], v[154:157], v[170:173], v[60:63]
	v_mfma_f32_16x16x32_bf16 v[56:59], v[162:165], v[170:173], v[56:59]
	v_mfma_f32_16x16x32_bf16 v[52:55], v[154:157], v[178:181], v[52:55]
	v_mfma_f32_16x16x32_bf16 v[48:51], v[162:165], v[178:181], v[48:51]
	v_mfma_f32_16x16x32_bf16 v[44:47], v[154:157], v[186:189], v[44:47]
	v_mfma_f32_16x16x32_bf16 v[40:43], v[162:165], v[186:189], v[40:43]
	v_mfma_f32_16x16x32_bf16 v[36:39], v[154:157], v[194:197], v[36:39]
	v_mfma_f32_16x16x32_bf16 v[32:35], v[162:165], v[194:197], v[32:35]
	v_mfma_f32_16x16x32_bf16 v[60:63], v[158:161], v[174:177], v[60:63]
	v_mfma_f32_16x16x32_bf16 v[56:59], v[166:169], v[174:177], v[56:59]
	v_mfma_f32_16x16x32_bf16 v[52:55], v[158:161], v[182:185], v[52:55]
	v_mfma_f32_16x16x32_bf16 v[48:51], v[166:169], v[182:185], v[48:51]
	v_mfma_f32_16x16x32_bf16 v[44:47], v[158:161], v[190:193], v[44:47]
	v_mfma_f32_16x16x32_bf16 v[40:43], v[166:169], v[190:193], v[40:43]
	v_mfma_f32_16x16x32_bf16 v[36:39], v[158:161], v[198:201], v[36:39]
	v_mfma_f32_16x16x32_bf16 v[32:35], v[166:169], v[198:201], v[32:35]
	s_barrier
	s_add_i32 s46, s40, s17
	s_add_i32 s47, s46, 0x100
	s_mov_b32 m0, s19
	s_nop 0
	buffer_load_dwordx4 v143, s[8:11], s47 offen lds
	s_mov_b32 m0, s20
	s_nop 0
	buffer_load_dwordx4 v144, s[8:11], s47 offen lds
	s_waitcnt vmcnt(6)
	s_barrier
; #define STAGE(P, RS, SOFF, OFF, kt) do { const int _so = (SOFF) + (kt) * (BK * 2); \
;     _Pragma("unroll") for (int _i = 0; _i < 2; ++_i) { \
;       __builtin_amdgcn_raw_ptr_buffer_load_lds(RS, (__attribute__((address_space(3))) void*)((P) + wave * 1024 + _i * 8192), 16, OFF[_i], _so, 0, 0); } } while (0)
; #define LDA(dst, b, h) _Pragma("unroll") for (int m = 0; m < 4; ++m) _Pragma("unroll") for (int k = 0; k < 2; ++k) \
;     dst[m][k] = *reinterpret_cast<const bf16x8*>(SA(b, h) + lds_byte(wr * 64 + m * 16 + fr, k * 32 + fq * 8))
; #define LDB(dst, b, h) _Pragma("unroll") for (int n = 0; n < 2; ++n) _Pragma("unroll") for (int k = 0; k < 2; ++k) \
;     dst[n][k] = *reinterpret_cast<const bf16x8*>(SB(b, h) + lds_byte(wc * 32 + n * 16 + fr, k * 32 + fq * 8))
; #define WAIT_V(n) asm volatile("s_waitcnt vmcnt(" #n ")" ::: "memory")
; #define WAIT_L(n) asm volatile("s_waitcnt lgkmcnt(" #n ")" ::: "memory")
; #define BAR __builtin_amdgcn_s_barrier()
; #define SCHED __builtin_amdgcn_sched_barrier(0)
;     ...
;       WAIT_V(6); BAR; MMA(1, 1, At, B1); BAR;
;       LDB(B0, 1, 0); SCHED; LDA(At, 1, 0); STAGE(SA(0, 1), rsA, sA1, offA, t + 2);
;       WAIT_L(8); BAR; WAIT_L(0); MMA(0, 0, At, B0); BAR; SCHED;
;       LDB(B1, 1, 1); STAGE(SB(1, 0), rsB, sB0, offB, t + 3);
;       BAR; WAIT_L(0); MMA(0, 1, At, B1); BAR;
;       LDA(At, 1, 1); STAGE(SA(1, 0), rsA, sA0, offA, t + 3);
;       BAR; WAIT_L(0); MMA(1, 0, At, B0); BAR; SCHED;
	v_mfma_f32_16x16x32_bf16 v[28:31], v[202:205], v[170:173], v[28:31]
	v_mfma_f32_16x16x32_bf16 v[24:27], v[210:213], v[170:173], v[24:27]
	v_mfma_f32_16x16x32_bf16 v[20:23], v[202:205], v[178:181], v[20:23]
	v_mfma_f32_16x16x32_bf16 v[16:19], v[210:213], v[178:181], v[16:19]
	v_mfma_f32_16x16x32_bf16 v[12:15], v[202:205], v[186:189], v[12:15]
	v_mfma_f32_16x16x32_bf16 v[8:11], v[210:213], v[186:189], v[8:11]
	v_mfma_f32_16x16x32_bf16 v[4:7], v[202:205], v[194:197], v[4:7]
	v_mfma_f32_16x16x32_bf16 v[0:3], v[210:213], v[194:197], v[0:3]
	v_mfma_f32_16x16x32_bf16 v[28:31], v[206:209], v[174:177], v[28:31]
	v_mfma_f32_16x16x32_bf16 v[24:27], v[214:217], v[174:177], v[24:27]
	v_mfma_f32_16x16x32_bf16 v[20:23], v[206:209], v[182:185], v[20:23]
	v_mfma_f32_16x16x32_bf16 v[16:19], v[214:217], v[182:185], v[16:19]
	v_mfma_f32_16x16x32_bf16 v[12:15], v[206:209], v[190:193], v[12:15]
	v_mfma_f32_16x16x32_bf16 v[8:11], v[214:217], v[190:193], v[8:11]
	v_mfma_f32_16x16x32_bf16 v[4:7], v[206:209], v[198:201], v[4:7]
	v_mfma_f32_16x16x32_bf16 v[0:3], v[214:217], v[198:201], v[0:3]
	s_barrier
	ds_read_b128 v[154:157], v139
	ds_read_b128 v[158:161], v140
	ds_read_b128 v[162:165], v141
	ds_read_b128 v[166:169], v142
	s_addk_i32 s43, 0x100
	s_mov_b32 m0, s21
	ds_read_b128 v[170:173], v131 offset:32768
	ds_read_b128 v[174:177], v131 offset:33792
	ds_read_b128 v[178:181], v134 offset:32768
	ds_read_b128 v[182:185], v134 offset:33792
	ds_read_b128 v[186:189], v133 offset:32768
	ds_read_b128 v[190:193], v133 offset:33792
	ds_read_b128 v[194:197], v132 offset:32768
	ds_read_b128 v[198:201], v132 offset:33792
	buffer_load_dwordx4 v143, s[4:7], s43 offen lds
	s_mov_b32 m0, s22
	s_nop 0
	buffer_load_dwordx4 v144, s[4:7], s43 offen lds
	s_waitcnt lgkmcnt(8)
	s_barrier
	s_waitcnt lgkmcnt(0)
	v_mfma_f32_16x16x32_bf16 v[124:127], v[154:157], v[170:173], v[124:127]
	v_mfma_f32_16x16x32_bf16 v[120:123], v[162:165], v[170:173], v[120:123]
	v_mfma_f32_16x16x32_bf16 v[116:119], v[154:157], v[178:181], v[116:119]
	v_mfma_f32_16x16x32_bf16 v[112:115], v[162:165], v[178:181], v[112:115]
	v_mfma_f32_16x16x32_bf16 v[108:111], v[154:157], v[186:189], v[108:111]
	v_mfma_f32_16x16x32_bf16 v[104:107], v[162:165], v[186:189], v[104:107]
	v_mfma_f32_16x16x32_bf16 v[100:103], v[154:157], v[194:197], v[100:103]
	v_mfma_f32_16x16x32_bf16 v[96:99], v[162:165], v[194:197], v[96:99]
	v_mfma_f32_16x16x32_bf16 v[124:127], v[158:161], v[174:177], v[124:127]
	v_mfma_f32_16x16x32_bf16 v[120:123], v[166:169], v[174:177], v[120:123]
	v_mfma_f32_16x16x32_bf16 v[116:119], v[158:161], v[182:185], v[116:119]
	v_mfma_f32_16x16x32_bf16 v[112:115], v[166:169], v[182:185], v[112:115]
	v_mfma_f32_16x16x32_bf16 v[108:111], v[158:161], v[190:193], v[108:111]
	v_mfma_f32_16x16x32_bf16 v[104:107], v[166:169], v[190:193], v[104:107]
	v_mfma_f32_16x16x32_bf16 v[100:103], v[158:161], v[198:201], v[100:103]
	v_mfma_f32_16x16x32_bf16 v[96:99], v[166:169], v[198:201], v[96:99]
	s_barrier
	s_addk_i32 s44, 0x180
	s_mov_b32 m0, s23
	ds_read_b128 v[202:205], v135
	ds_read_b128 v[206:209], v136
	ds_read_b128 v[210:213], v137
	ds_read_b128 v[214:217], v138
	buffer_load_dwordx4 v143, s[8:11], s44 offen lds
	s_mov_b32 m0, s24
	s_nop 0
	buffer_load_dwordx4 v144, s[8:11], s44 offen lds
	s_barrier
	s_waitcnt lgkmcnt(0)
	v_mfma_f32_16x16x32_bf16 v[92:95], v[202:205], v[170:173], v[92:95]
	v_mfma_f32_16x16x32_bf16 v[88:91], v[210:213], v[170:173], v[88:91]
	v_mfma_f32_16x16x32_bf16 v[84:87], v[202:205], v[178:181], v[84:87]
	v_mfma_f32_16x16x32_bf16 v[80:83], v[210:213], v[178:181], v[80:83]
	v_mfma_f32_16x16x32_bf16 v[76:79], v[202:205], v[186:189], v[76:79]
	v_mfma_f32_16x16x32_bf16 v[72:75], v[210:213], v[186:189], v[72:75]
	v_mfma_f32_16x16x32_bf16 v[68:71], v[202:205], v[194:197], v[68:71]
	v_mfma_f32_16x16x32_bf16 v[64:67], v[210:213], v[194:197], v[64:67]
	v_mfma_f32_16x16x32_bf16 v[92:95], v[206:209], v[174:177], v[92:95]
	v_mfma_f32_16x16x32_bf16 v[88:91], v[214:217], v[174:177], v[88:91]
	v_mfma_f32_16x16x32_bf16 v[84:87], v[206:209], v[182:185], v[84:87]
	v_mfma_f32_16x16x32_bf16 v[80:83], v[214:217], v[182:185], v[80:83]
	v_mfma_f32_16x16x32_bf16 v[76:79], v[206:209], v[190:193], v[76:79]
	v_mfma_f32_16x16x32_bf16 v[72:75], v[214:217], v[190:193], v[72:75]
	v_mfma_f32_16x16x32_bf16 v[68:71], v[206:209], v[198:201], v[68:71]
	v_mfma_f32_16x16x32_bf16 v[64:67], v[214:217], v[198:201], v[64:67]
	s_addk_i32 s45, 0x180
	s_mov_b32 m0, s25
	s_barrier
	ds_read_b128 v[170:173], v131 offset:49152
	ds_read_b128 v[174:177], v131 offset:50176
	ds_read_b128 v[178:181], v134 offset:49152
	ds_read_b128 v[182:185], v134 offset:50176
	ds_read_b128 v[186:189], v133 offset:49152
	ds_read_b128 v[190:193], v133 offset:50176
	ds_read_b128 v[194:197], v132 offset:49152
	ds_read_b128 v[198:201], v132 offset:50176
	buffer_load_dwordx4 v143, s[4:7], s45 offen lds
	s_mov_b32 m0, s26
	s_nop 0
	buffer_load_dwordx4 v144, s[4:7], s45 offen lds
	s_barrier
	s_waitcnt lgkmcnt(0)
	v_mfma_f32_16x16x32_bf16 v[60:63], v[154:157], v[170:173], v[60:63]
	v_mfma_f32_16x16x32_bf16 v[56:59], v[162:165], v[170:173], v[56:59]
	v_mfma_f32_16x16x32_bf16 v[52:55], v[154:157], v[178:181], v[52:55]
	v_mfma_f32_16x16x32_bf16 v[48:51], v[162:165], v[178:181], v[48:51]
	v_mfma_f32_16x16x32_bf16 v[44:47], v[154:157], v[186:189], v[44:47]
	v_mfma_f32_16x16x32_bf16 v[40:43], v[162:165], v[186:189], v[40:43]
	v_mfma_f32_16x16x32_bf16 v[36:39], v[154:157], v[194:197], v[36:39]
	v_mfma_f32_16x16x32_bf16 v[32:35], v[162:165], v[194:197], v[32:35]
	v_mfma_f32_16x16x32_bf16 v[60:63], v[158:161], v[174:177], v[60:63]
	v_mfma_f32_16x16x32_bf16 v[56:59], v[166:169], v[174:177], v[56:59]
	v_mfma_f32_16x16x32_bf16 v[52:55], v[158:161], v[182:185], v[52:55]
	v_mfma_f32_16x16x32_bf16 v[48:51], v[166:169], v[182:185], v[48:51]
	v_mfma_f32_16x16x32_bf16 v[44:47], v[158:161], v[190:193], v[44:47]
	v_mfma_f32_16x16x32_bf16 v[40:43], v[166:169], v[190:193], v[40:43]
	v_mfma_f32_16x16x32_bf16 v[36:39], v[158:161], v[198:201], v[36:39]
	v_mfma_f32_16x16x32_bf16 v[32:35], v[166:169], v[198:201], v[32:35]
	s_barrier
; #define STAGE(P, RS, SOFF, OFF, kt) do { const int _so = (SOFF) + (kt) * (BK * 2); \
;     _Pragma("unroll") for (int _i = 0; _i < 2; ++_i) { \
;       __builtin_amdgcn_raw_ptr_buffer_load_lds(RS, (__attribute__((address_space(3))) void*)((P) + wave * 1024 + _i * 8192), 16, OFF[_i], _so, 0, 0); } } while (0)
; #define LDA(dst, b, h) _Pragma("unroll") for (int m = 0; m < 4; ++m) _Pragma("unroll") for (int k = 0; k < 2; ++k) \
;     dst[m][k] = *reinterpret_cast<const bf16x8*>(SA(b, h) + lds_byte(wr * 64 + m * 16 + fr, k * 32 + fq * 8))
; #define LDB(dst, b, h) _Pragma("unroll") for (int n = 0; n < 2; ++n) _Pragma("unroll") for (int k = 0; k < 2; ++k) \
;     dst[n][k] = *reinterpret_cast<const bf16x8*>(SB(b, h) + lds_byte(wc * 32 + n * 16 + fr, k * 32 + fq * 8))
; #define WAIT_V(n) asm volatile("s_waitcnt vmcnt(" #n ")" ::: "memory")
; #define WAIT_L(n) asm volatile("s_waitcnt lgkmcnt(" #n ")" ::: "memory")
; #define BAR __builtin_amdgcn_s_barrier()
;     ...
;       STAGE(SB(1, 1), rsB, sB1, offB, t + 3);
;       WAIT_V(6); BAR; MMA(1, 1, At, B1); BAR;
;     }
;     { LDB(B0, 0, 0); LDA(At, 0, 0); STAGE(SA(1, 1), rsA, sA1, offA, nt - 1);
;       BAR; WAIT_L(0); MMA(0, 0, At, B0); BAR;
;       LDB(B1, 0, 1); BAR; WAIT_L(0); MMA(0, 1, At, B1); BAR;
;       LDA(At, 0, 1); WAIT_V(4); BAR; WAIT_L(0); MMA(1, 0, At, B0); MMA(1, 1, At, B1); BAR; }
;     { LDB(B0, 1, 0); LDA(At, 1, 0); WAIT_V(2); BAR; WAIT_L(0); MMA(0, 0, At, B0); BAR;
	s_addk_i32 s46, 0x180
	s_mov_b32 m0, s27
	s_nop 0
	buffer_load_dwordx4 v143, s[8:11], s46 offen lds
	s_mov_b32 m0, s28
	s_nop 0
	buffer_load_dwordx4 v144, s[8:11], s46 offen lds
	s_waitcnt vmcnt(6)
	s_barrier
	v_mfma_f32_16x16x32_bf16 v[28:31], v[202:205], v[170:173], v[28:31]
	v_mfma_f32_16x16x32_bf16 v[24:27], v[210:213], v[170:173], v[24:27]
	v_mfma_f32_16x16x32_bf16 v[20:23], v[202:205], v[178:181], v[20:23]
	v_mfma_f32_16x16x32_bf16 v[16:19], v[210:213], v[178:181], v[16:19]
	v_mfma_f32_16x16x32_bf16 v[12:15], v[202:205], v[186:189], v[12:15]
	v_mfma_f32_16x16x32_bf16 v[8:11], v[210:213], v[186:189], v[8:11]
	v_mfma_f32_16x16x32_bf16 v[4:7], v[202:205], v[194:197], v[4:7]
	v_mfma_f32_16x16x32_bf16 v[0:3], v[210:213], v[194:197], v[0:3]
	v_mfma_f32_16x16x32_bf16 v[28:31], v[206:209], v[174:177], v[28:31]
	v_mfma_f32_16x16x32_bf16 v[24:27], v[214:217], v[174:177], v[24:27]
	v_mfma_f32_16x16x32_bf16 v[20:23], v[206:209], v[182:185], v[20:23]
	v_mfma_f32_16x16x32_bf16 v[16:19], v[214:217], v[182:185], v[16:19]
	v_mfma_f32_16x16x32_bf16 v[12:15], v[206:209], v[190:193], v[12:15]
	v_mfma_f32_16x16x32_bf16 v[8:11], v[214:217], v[190:193], v[8:11]
	v_mfma_f32_16x16x32_bf16 v[4:7], v[206:209], v[198:201], v[4:7]
	v_mfma_f32_16x16x32_bf16 v[0:3], v[214:217], v[198:201], v[0:3]
	s_add_i32 s16, s16, 2
	s_addk_i32 s17, 0x100
	s_cmp_gt_u32 s16, 27
	s_barrier
	s_cbranch_scc0 .LBB0_556
	s_add_i32 s10, s37, 0xf80
	s_mov_b32 m0, s30
	ds_read_b128 v[154:157], v149
	ds_read_b128 v[158:161], v150
	ds_read_b128 v[162:165], v151
	ds_read_b128 v[150:153], v152
	ds_read_b128 v[166:169], v131
	ds_read_b128 v[170:173], v131 offset:1024
	ds_read_b128 v[174:177], v134
	ds_read_b128 v[178:181], v134 offset:1024
	ds_read_b128 v[182:185], v133
	ds_read_b128 v[186:189], v133 offset:1024
	ds_read_b128 v[190:193], v132
	ds_read_b128 v[194:197], v132 offset:1024
	buffer_load_dwordx4 v143, s[4:7], s10 offen lds
	s_mov_b32 m0, s31
	s_nop 0
	buffer_load_dwordx4 v144, s[4:7], s10 offen lds
	s_barrier
	s_waitcnt lgkmcnt(0)
	v_mfma_f32_16x16x32_bf16 v[124:127], v[154:157], v[166:169], v[124:127]
	v_mfma_f32_16x16x32_bf16 v[120:123], v[162:165], v[166:169], v[120:123]
	v_mfma_f32_16x16x32_bf16 v[116:119], v[154:157], v[174:177], v[116:119]
	v_mfma_f32_16x16x32_bf16 v[112:115], v[162:165], v[174:177], v[112:115]
	v_mfma_f32_16x16x32_bf16 v[108:111], v[154:157], v[182:185], v[108:111]
	v_mfma_f32_16x16x32_bf16 v[104:107], v[162:165], v[182:185], v[104:107]
	v_mfma_f32_16x16x32_bf16 v[100:103], v[154:157], v[190:193], v[100:103]
	v_mfma_f32_16x16x32_bf16 v[96:99], v[162:165], v[190:193], v[96:99]
	v_mfma_f32_16x16x32_bf16 v[124:127], v[158:161], v[170:173], v[124:127]
	v_mfma_f32_16x16x32_bf16 v[120:123], v[150:153], v[170:173], v[120:123]
	v_mfma_f32_16x16x32_bf16 v[116:119], v[158:161], v[178:181], v[116:119]
	v_mfma_f32_16x16x32_bf16 v[112:115], v[150:153], v[178:181], v[112:115]
	v_mfma_f32_16x16x32_bf16 v[108:111], v[158:161], v[186:189], v[108:111]
	v_mfma_f32_16x16x32_bf16 v[104:107], v[150:153], v[186:189], v[104:107]
	v_mfma_f32_16x16x32_bf16 v[100:103], v[158:161], v[194:197], v[100:103]
	v_mfma_f32_16x16x32_bf16 v[96:99], v[150:153], v[194:197], v[96:99]
	s_barrier
	ds_read_b128 v[198:201], v145
	ds_read_b128 v[202:205], v146
	ds_read_b128 v[144:147], v147
	ds_read_b128 v[206:209], v148
	s_barrier
	s_waitcnt lgkmcnt(0)
	v_mfma_f32_16x16x32_bf16 v[92:95], v[198:201], v[166:169], v[92:95]
	v_mfma_f32_16x16x32_bf16 v[88:91], v[144:147], v[166:169], v[88:91]
	v_mfma_f32_16x16x32_bf16 v[84:87], v[198:201], v[174:177], v[84:87]
	v_mfma_f32_16x16x32_bf16 v[80:83], v[144:147], v[174:177], v[80:83]
	v_mfma_f32_16x16x32_bf16 v[76:79], v[198:201], v[182:185], v[76:79]
	v_mfma_f32_16x16x32_bf16 v[72:75], v[144:147], v[182:185], v[72:75]
	v_mfma_f32_16x16x32_bf16 v[68:71], v[198:201], v[190:193], v[68:71]
	v_mfma_f32_16x16x32_bf16 v[64:67], v[144:147], v[190:193], v[64:67]
	v_mfma_f32_16x16x32_bf16 v[92:95], v[202:205], v[170:173], v[92:95]
	v_mfma_f32_16x16x32_bf16 v[88:91], v[206:209], v[170:173], v[88:91]
	v_mfma_f32_16x16x32_bf16 v[84:87], v[202:205], v[178:181], v[84:87]
	v_mfma_f32_16x16x32_bf16 v[80:83], v[206:209], v[178:181], v[80:83]
	v_mfma_f32_16x16x32_bf16 v[76:79], v[202:205], v[186:189], v[76:79]
	v_mfma_f32_16x16x32_bf16 v[72:75], v[206:209], v[186:189], v[72:75]
	v_mfma_f32_16x16x32_bf16 v[68:71], v[202:205], v[194:197], v[68:71]
	v_mfma_f32_16x16x32_bf16 v[64:67], v[206:209], v[194:197], v[64:67]
	s_barrier
	ds_read_b128 v[166:169], v131 offset:16384
	ds_read_b128 v[170:173], v131 offset:17408
	ds_read_b128 v[174:177], v134 offset:16384
	ds_read_b128 v[178:181], v134 offset:17408
	ds_read_b128 v[182:185], v133 offset:16384
	ds_read_b128 v[186:189], v133 offset:17408
	ds_read_b128 v[190:193], v132 offset:16384
	ds_read_b128 v[194:197], v132 offset:17408
	s_waitcnt vmcnt(4)
	s_barrier
; #define LDA(dst, b, h) _Pragma("unroll") for (int m = 0; m < 4; ++m) _Pragma("unroll") for (int k = 0; k < 2; ++k) \
;     dst[m][k] = *reinterpret_cast<const bf16x8*>(SA(b, h) + lds_byte(wr * 64 + m * 16 + fr, k * 32 + fq * 8))
; #define LDB(dst, b, h) _Pragma("unroll") for (int n = 0; n < 2; ++n) _Pragma("unroll") for (int k = 0; k < 2; ++k) \
;     dst[n][k] = *reinterpret_cast<const bf16x8*>(SB(b, h) + lds_byte(wc * 32 + n * 16 + fr, k * 32 + fq * 8))
; #define WAIT_V(n) asm volatile("s_waitcnt vmcnt(" #n ")" ::: "memory")
; #define WAIT_L(n) asm volatile("s_waitcnt lgkmcnt(" #n ")" ::: "memory")
; #define BAR __builtin_amdgcn_s_barrier()
;     ...
;       LDA(At, 0, 1); WAIT_V(4); BAR; WAIT_L(0); MMA(1, 0, At, B0); MMA(1, 1, At, B1); BAR; }
;     { LDB(B0, 1, 0); LDA(At, 1, 0); WAIT_V(2); BAR; WAIT_L(0); MMA(0, 0, At, B0); BAR;
;       LDB(B1, 1, 1); WAIT_V(0); BAR; WAIT_L(0); MMA(0, 1, At, B1); BAR;
	s_waitcnt lgkmcnt(0)
	v_mfma_f32_16x16x32_bf16 v[60:63], v[154:157], v[166:169], v[60:63]
	v_mfma_f32_16x16x32_bf16 v[56:59], v[162:165], v[166:169], v[56:59]
	v_mfma_f32_16x16x32_bf16 v[52:55], v[154:157], v[174:177], v[52:55]
	v_mfma_f32_16x16x32_bf16 v[48:51], v[162:165], v[174:177], v[48:51]
	v_mfma_f32_16x16x32_bf16 v[44:47], v[154:157], v[182:185], v[44:47]
	v_mfma_f32_16x16x32_bf16 v[40:43], v[162:165], v[182:185], v[40:43]
	v_mfma_f32_16x16x32_bf16 v[36:39], v[154:157], v[190:193], v[36:39]
	v_mfma_f32_16x16x32_bf16 v[32:35], v[162:165], v[190:193], v[32:35]
	v_mfma_f32_16x16x32_bf16 v[60:63], v[158:161], v[170:173], v[60:63]
	v_mfma_f32_16x16x32_bf16 v[56:59], v[150:153], v[170:173], v[56:59]
	v_mfma_f32_16x16x32_bf16 v[52:55], v[158:161], v[178:181], v[52:55]
	v_mfma_f32_16x16x32_bf16 v[48:51], v[150:153], v[178:181], v[48:51]
	v_mfma_f32_16x16x32_bf16 v[44:47], v[158:161], v[186:189], v[44:47]
	v_mfma_f32_16x16x32_bf16 v[40:43], v[150:153], v[186:189], v[40:43]
	v_mfma_f32_16x16x32_bf16 v[36:39], v[158:161], v[194:197], v[36:39]
	v_mfma_f32_16x16x32_bf16 v[32:35], v[150:153], v[194:197], v[32:35]
	v_mfma_f32_16x16x32_bf16 v[28:31], v[198:201], v[166:169], v[28:31]
	v_mfma_f32_16x16x32_bf16 v[24:27], v[144:147], v[166:169], v[24:27]
	v_mfma_f32_16x16x32_bf16 v[20:23], v[198:201], v[174:177], v[20:23]
	v_mfma_f32_16x16x32_bf16 v[16:19], v[144:147], v[174:177], v[16:19]
	v_mfma_f32_16x16x32_bf16 v[12:15], v[198:201], v[182:185], v[12:15]
	v_mfma_f32_16x16x32_bf16 v[8:11], v[144:147], v[182:185], v[8:11]
	v_mfma_f32_16x16x32_bf16 v[4:7], v[198:201], v[190:193], v[4:7]
	v_mfma_f32_16x16x32_bf16 v[0:3], v[144:147], v[190:193], v[0:3]
	v_mfma_f32_16x16x32_bf16 v[28:31], v[202:205], v[170:173], v[28:31]
	v_mfma_f32_16x16x32_bf16 v[24:27], v[206:209], v[170:173], v[24:27]
	v_mfma_f32_16x16x32_bf16 v[20:23], v[202:205], v[178:181], v[20:23]
	v_mfma_f32_16x16x32_bf16 v[16:19], v[206:209], v[178:181], v[16:19]
	v_mfma_f32_16x16x32_bf16 v[12:15], v[202:205], v[186:189], v[12:15]
	v_mfma_f32_16x16x32_bf16 v[8:11], v[206:209], v[186:189], v[8:11]
	v_mfma_f32_16x16x32_bf16 v[4:7], v[202:205], v[194:197], v[4:7]
	v_mfma_f32_16x16x32_bf16 v[0:3], v[206:209], v[194:197], v[0:3]
	s_barrier
	ds_read_b128 v[144:147], v139
	ds_read_b128 v[148:151], v140
	ds_read_b128 v[152:155], v141
	ds_read_b128 v[140:143], v142
	ds_read_b128 v[156:159], v131 offset:32768
	ds_read_b128 v[160:163], v131 offset:33792
	ds_read_b128 v[164:167], v134 offset:32768
	ds_read_b128 v[168:171], v134 offset:33792
	ds_read_b128 v[172:175], v133 offset:32768
	ds_read_b128 v[176:179], v133 offset:33792
	ds_read_b128 v[180:183], v132 offset:32768
	ds_read_b128 v[184:187], v132 offset:33792
	s_waitcnt vmcnt(2)
	s_barrier
	s_waitcnt lgkmcnt(0)
	v_mfma_f32_16x16x32_bf16 v[124:127], v[144:147], v[156:159], v[124:127]
	v_mfma_f32_16x16x32_bf16 v[120:123], v[152:155], v[156:159], v[120:123]
	v_mfma_f32_16x16x32_bf16 v[116:119], v[144:147], v[164:167], v[116:119]
	v_mfma_f32_16x16x32_bf16 v[112:115], v[152:155], v[164:167], v[112:115]
	v_mfma_f32_16x16x32_bf16 v[108:111], v[144:147], v[172:175], v[108:111]
	v_mfma_f32_16x16x32_bf16 v[104:107], v[152:155], v[172:175], v[104:107]
	v_mfma_f32_16x16x32_bf16 v[100:103], v[144:147], v[180:183], v[100:103]
	v_mfma_f32_16x16x32_bf16 v[96:99], v[152:155], v[180:183], v[96:99]
	v_mfma_f32_16x16x32_bf16 v[124:127], v[148:151], v[160:163], v[124:127]
	v_mfma_f32_16x16x32_bf16 v[120:123], v[140:143], v[160:163], v[120:123]
	v_mfma_f32_16x16x32_bf16 v[116:119], v[148:151], v[168:171], v[116:119]
	v_mfma_f32_16x16x32_bf16 v[112:115], v[140:143], v[168:171], v[112:115]
	v_mfma_f32_16x16x32_bf16 v[108:111], v[148:151], v[176:179], v[108:111]
	v_mfma_f32_16x16x32_bf16 v[104:107], v[140:143], v[176:179], v[104:107]
	v_mfma_f32_16x16x32_bf16 v[100:103], v[148:151], v[184:187], v[100:103]
	v_mfma_f32_16x16x32_bf16 v[96:99], v[140:143], v[184:187], v[96:99]
	s_barrier
; #define LDA(dst, b, h) _Pragma("unroll") for (int m = 0; m < 4; ++m) _Pragma("unroll") for (int k = 0; k < 2; ++k) \
;     dst[m][k] = *reinterpret_cast<const bf16x8*>(SA(b, h) + lds_byte(wr * 64 + m * 16 + fr, k * 32 + fq * 8))
; #define LDB(dst, b, h) _Pragma("unroll") for (int n = 0; n < 2; ++n) _Pragma("unroll") for (int k = 0; k < 2; ++k) \
;     dst[n][k] = *reinterpret_cast<const bf16x8*>(SB(b, h) + lds_byte(wc * 32 + n * 16 + fr, k * 32 + fq * 8))
; #define WAIT_V(n) asm volatile("s_waitcnt vmcnt(" #n ")" ::: "memory")
; #define WAIT_L(n) asm volatile("s_waitcnt lgkmcnt(" #n ")" ::: "memory")
; #define BAR __builtin_amdgcn_s_barrier()
;     ...
;     { LDB(B0, 1, 0); LDA(At, 1, 0); WAIT_V(2); BAR; WAIT_L(0); MMA(0, 0, At, B0); BAR;
;       LDB(B1, 1, 1); WAIT_V(0); BAR; WAIT_L(0); MMA(0, 1, At, B1); BAR;
;       LDA(At, 1, 1); BAR; WAIT_L(0); MMA(1, 0, At, B0); MMA(1, 1, At, B1); BAR; }
;     if (wr == 0) BAR;
	ds_read_b128 v[188:191], v135
	ds_read_b128 v[192:195], v136
	ds_read_b128 v[196:199], v137
	ds_read_b128 v[136:139], v138
	s_waitcnt vmcnt(0)
	s_barrier
	s_waitcnt lgkmcnt(0)
	v_mfma_f32_16x16x32_bf16 v[92:95], v[188:191], v[156:159], v[92:95]
	v_mfma_f32_16x16x32_bf16 v[88:91], v[196:199], v[156:159], v[88:91]
	v_mfma_f32_16x16x32_bf16 v[84:87], v[188:191], v[164:167], v[84:87]
	v_mfma_f32_16x16x32_bf16 v[80:83], v[196:199], v[164:167], v[80:83]
	v_mfma_f32_16x16x32_bf16 v[76:79], v[188:191], v[172:175], v[76:79]
	v_mfma_f32_16x16x32_bf16 v[72:75], v[196:199], v[172:175], v[72:75]
	v_mfma_f32_16x16x32_bf16 v[68:71], v[188:191], v[180:183], v[68:71]
	v_mfma_f32_16x16x32_bf16 v[64:67], v[196:199], v[180:183], v[64:67]
	v_mfma_f32_16x16x32_bf16 v[92:95], v[192:195], v[160:163], v[92:95]
	v_mfma_f32_16x16x32_bf16 v[88:91], v[136:139], v[160:163], v[88:91]
	v_mfma_f32_16x16x32_bf16 v[84:87], v[192:195], v[168:171], v[84:87]
	v_mfma_f32_16x16x32_bf16 v[80:83], v[136:139], v[168:171], v[80:83]
	v_mfma_f32_16x16x32_bf16 v[76:79], v[192:195], v[176:179], v[76:79]
	v_mfma_f32_16x16x32_bf16 v[72:75], v[136:139], v[176:179], v[72:75]
	v_mfma_f32_16x16x32_bf16 v[68:71], v[192:195], v[184:187], v[68:71]
	v_mfma_f32_16x16x32_bf16 v[64:67], v[136:139], v[184:187], v[64:67]
	s_barrier
	ds_read_b128 v[156:159], v131 offset:49152
	ds_read_b128 v[160:163], v131 offset:50176
	ds_read_b128 v[164:167], v134 offset:49152
	ds_read_b128 v[168:171], v134 offset:50176
	ds_read_b128 v[172:175], v133 offset:49152
	ds_read_b128 v[176:179], v133 offset:50176
	ds_read_b128 v[180:183], v132 offset:49152
	ds_read_b128 v[132:135], v132 offset:50176
	s_barrier
	s_waitcnt lgkmcnt(0)
	v_mfma_f32_16x16x32_bf16 v[60:63], v[144:147], v[156:159], v[60:63]
	v_mfma_f32_16x16x32_bf16 v[56:59], v[152:155], v[156:159], v[56:59]
	v_mfma_f32_16x16x32_bf16 v[52:55], v[144:147], v[164:167], v[52:55]
	v_mfma_f32_16x16x32_bf16 v[48:51], v[152:155], v[164:167], v[48:51]
	v_mfma_f32_16x16x32_bf16 v[44:47], v[144:147], v[172:175], v[44:47]
	v_mfma_f32_16x16x32_bf16 v[40:43], v[152:155], v[172:175], v[40:43]
	v_mfma_f32_16x16x32_bf16 v[36:39], v[144:147], v[180:183], v[36:39]
	v_mfma_f32_16x16x32_bf16 v[32:35], v[152:155], v[180:183], v[32:35]
	v_mfma_f32_16x16x32_bf16 v[60:63], v[148:151], v[160:163], v[60:63]
	v_mfma_f32_16x16x32_bf16 v[56:59], v[140:143], v[160:163], v[56:59]
	v_mfma_f32_16x16x32_bf16 v[52:55], v[148:151], v[168:171], v[52:55]
	v_mfma_f32_16x16x32_bf16 v[48:51], v[140:143], v[168:171], v[48:51]
	v_mfma_f32_16x16x32_bf16 v[44:47], v[148:151], v[176:179], v[44:47]
	v_mfma_f32_16x16x32_bf16 v[40:43], v[140:143], v[176:179], v[40:43]
	v_mfma_f32_16x16x32_bf16 v[36:39], v[148:151], v[132:135], v[36:39]
	v_mfma_f32_16x16x32_bf16 v[32:35], v[140:143], v[132:135], v[32:35]
	v_mfma_f32_16x16x32_bf16 v[28:31], v[188:191], v[156:159], v[28:31]
	v_mfma_f32_16x16x32_bf16 v[24:27], v[196:199], v[156:159], v[24:27]
	v_mfma_f32_16x16x32_bf16 v[20:23], v[188:191], v[164:167], v[20:23]
	v_mfma_f32_16x16x32_bf16 v[16:19], v[196:199], v[164:167], v[16:19]
	v_mfma_f32_16x16x32_bf16 v[12:15], v[188:191], v[172:175], v[12:15]
	v_mfma_f32_16x16x32_bf16 v[8:11], v[196:199], v[172:175], v[8:11]
	v_mfma_f32_16x16x32_bf16 v[4:7], v[188:191], v[180:183], v[4:7]
	v_mfma_f32_16x16x32_bf16 v[0:3], v[196:199], v[180:183], v[0:3]
	v_mfma_f32_16x16x32_bf16 v[28:31], v[192:195], v[160:163], v[28:31]
	v_mfma_f32_16x16x32_bf16 v[24:27], v[136:139], v[160:163], v[24:27]
	v_mfma_f32_16x16x32_bf16 v[20:23], v[192:195], v[168:171], v[20:23]
	v_mfma_f32_16x16x32_bf16 v[16:19], v[136:139], v[168:171], v[16:19]
	v_mfma_f32_16x16x32_bf16 v[12:15], v[192:195], v[176:179], v[12:15]
	v_mfma_f32_16x16x32_bf16 v[8:11], v[136:139], v[176:179], v[8:11]
	v_mfma_f32_16x16x32_bf16 v[4:7], v[192:195], v[132:135], v[4:7]
	v_mfma_f32_16x16x32_bf16 v[0:3], v[136:139], v[132:135], v[0:3]
	v_cmp_gt_u32_e32 vcc, s35, v130
	s_barrier
	s_and_saveexec_b64 s[10:11], vcc
	s_cbranch_execz .LBB0_559
	s_barrier

; #define STAGE(P, RS, SOFF, OFF, kt) do { const int _so = (SOFF) + (kt) * (BK * 2); \
;     _Pragma("unroll") for (int _i = 0; _i < 2; ++_i) { \
;       __builtin_amdgcn_raw_ptr_buffer_load_lds(RS, (__attribute__((address_space(3))) void*)((P) + wave * 1024 + _i * 8192), 16, OFF[_i], _so, 0, 0); } } while (0)
; #define LDA(dst, b, h) _Pragma("unroll") for (int m = 0; m < 4; ++m) _Pragma("unroll") for (int k = 0; k < 2; ++k) \
;     dst[m][k] = *reinterpret_cast<const bf16x8*>(SA(b, h) + lds_byte(wr * 64 + m * 16 + fr, k * 32 + fq * 8))
; #define LDB(dst, b, h) _Pragma("unroll") for (int n = 0; n < 2; ++n) _Pragma("unroll") for (int k = 0; k < 2; ++k) \
;     dst[n][k] = *reinterpret_cast<const bf16x8*>(SB(b, h) + lds_byte(wc * 32 + n * 16 + fr, k * 32 + fq * 8))
; #define WAIT_V(n) asm volatile("s_waitcnt vmcnt(" #n ")" ::: "memory")
; #define WAIT_L(n) asm volatile("s_waitcnt lgkmcnt(" #n ")" ::: "memory")
; #define BAR __builtin_amdgcn_s_barrier()
; #define SCHED __builtin_amdgcn_sched_barrier(0)
;     ...
;     for (int t = 0; t < nt - 2; t += 2) {
;       LDB(B0, 0, 0); SCHED; LDA(At, 0, 0); STAGE(SA(1, 1), rsA, sA1, offA, t + 1);
;       WAIT_L(8); BAR; WAIT_L(0); MMA(0, 0, At, B0); BAR; SCHED;
;       LDB(B1, 0, 1); STAGE(SB(0, 0), rsB, sB0, offB, t + 2);
;       BAR; WAIT_L(0); MMA(0, 1, At, B1); BAR;
;       LDA(At, 0, 1); STAGE(SA(0, 0), rsA, sA0, offA, t + 2);
;       BAR; WAIT_L(0); MMA(1, 0, At, B0); BAR; SCHED;
;       STAGE(SB(0, 1), rsB, sB1, offB, t + 2);
;       WAIT_V(6); BAR; MMA(1, 1, At, B1); BAR;
.LBB0_657:
	ds_read_b128 v[152:155], v147
	ds_read_b128 v[156:159], v148
	ds_read_b128 v[160:163], v149
	ds_read_b128 v[164:167], v150
	s_add_i32 s5, s81, s3
	s_add_i32 s6, s5, 0x80
	s_mov_b32 m0, s39
	ds_read_b128 v[168:171], v129
	ds_read_b128 v[172:175], v129 offset:1024
	ds_read_b128 v[176:179], v132
	ds_read_b128 v[180:183], v132 offset:1024
	ds_read_b128 v[184:187], v131
	ds_read_b128 v[188:191], v131 offset:1024
	ds_read_b128 v[192:195], v130
	ds_read_b128 v[196:199], v130 offset:1024
	buffer_load_dwordx4 v141, s[8:11], s6 offen lds
	s_mov_b32 m0, s58
	s_nop 0
	buffer_load_dwordx4 v142, s[8:11], s6 offen lds
	s_waitcnt lgkmcnt(8)
	s_barrier
	s_waitcnt lgkmcnt(0)
	v_mfma_f32_16x16x32_bf16 v[124:127], v[152:155], v[168:171], v[124:127]
	v_mfma_f32_16x16x32_bf16 v[120:123], v[160:163], v[168:171], v[120:123]
	v_mfma_f32_16x16x32_bf16 v[116:119], v[152:155], v[176:179], v[116:119]
	v_mfma_f32_16x16x32_bf16 v[112:115], v[160:163], v[176:179], v[112:115]
	v_mfma_f32_16x16x32_bf16 v[108:111], v[152:155], v[184:187], v[108:111]
	v_mfma_f32_16x16x32_bf16 v[104:107], v[160:163], v[184:187], v[104:107]
	v_mfma_f32_16x16x32_bf16 v[100:103], v[152:155], v[192:195], v[100:103]
	v_mfma_f32_16x16x32_bf16 v[96:99], v[160:163], v[192:195], v[96:99]
	v_mfma_f32_16x16x32_bf16 v[124:127], v[156:159], v[172:175], v[124:127]
	v_mfma_f32_16x16x32_bf16 v[120:123], v[164:167], v[172:175], v[120:123]
	v_mfma_f32_16x16x32_bf16 v[116:119], v[156:159], v[180:183], v[116:119]
	v_mfma_f32_16x16x32_bf16 v[112:115], v[164:167], v[180:183], v[112:115]
	v_mfma_f32_16x16x32_bf16 v[108:111], v[156:159], v[188:191], v[108:111]
	v_mfma_f32_16x16x32_bf16 v[104:107], v[164:167], v[188:191], v[104:107]
	v_mfma_f32_16x16x32_bf16 v[100:103], v[156:159], v[196:199], v[100:103]
	v_mfma_f32_16x16x32_bf16 v[96:99], v[164:167], v[196:199], v[96:99]
	s_barrier
	s_add_i32 s6, s83, s3
	s_add_i32 s7, s6, 0x100
	s_mov_b32 s14, s10
	s_mov_b32 s15, s11
	s_mov_b32 m0, s85
	ds_read_b128 v[200:203], v143
	ds_read_b128 v[204:207], v144
	ds_read_b128 v[208:211], v145
	ds_read_b128 v[212:215], v146
	buffer_load_dwordx4 v141, s[12:15], s7 offen lds
	s_mov_b32 m0, s75
	s_nop 0
	buffer_load_dwordx4 v142, s[12:15], s7 offen lds
	s_barrier
	s_waitcnt lgkmcnt(0)
	v_mfma_f32_16x16x32_bf16 v[92:95], v[200:203], v[168:171], v[92:95]
	v_mfma_f32_16x16x32_bf16 v[88:91], v[208:211], v[168:171], v[88:91]
	v_mfma_f32_16x16x32_bf16 v[80:83], v[200:203], v[176:179], v[80:83]
	v_mfma_f32_16x16x32_bf16 v[68:71], v[208:211], v[176:179], v[68:71]
	v_mfma_f32_16x16x32_bf16 v[60:63], v[200:203], v[184:187], v[60:63]
	v_mfma_f32_16x16x32_bf16 v[56:59], v[208:211], v[184:187], v[56:59]
	v_mfma_f32_16x16x32_bf16 v[52:55], v[200:203], v[192:195], v[52:55]
	v_mfma_f32_16x16x32_bf16 v[48:51], v[208:211], v[192:195], v[48:51]
	v_mfma_f32_16x16x32_bf16 v[92:95], v[204:207], v[172:175], v[92:95]
	v_mfma_f32_16x16x32_bf16 v[88:91], v[212:215], v[172:175], v[88:91]
	v_mfma_f32_16x16x32_bf16 v[80:83], v[204:207], v[180:183], v[80:83]
	v_mfma_f32_16x16x32_bf16 v[68:71], v[212:215], v[180:183], v[68:71]
	v_mfma_f32_16x16x32_bf16 v[60:63], v[204:207], v[188:191], v[60:63]
	v_mfma_f32_16x16x32_bf16 v[56:59], v[212:215], v[188:191], v[56:59]
	v_mfma_f32_16x16x32_bf16 v[52:55], v[204:207], v[196:199], v[52:55]
	v_mfma_f32_16x16x32_bf16 v[48:51], v[212:215], v[196:199], v[48:51]
	s_add_i32 s7, s82, s3
	s_add_i32 s22, s7, 0x100
	s_mov_b32 m0, s38
	s_barrier
	ds_read_b128 v[168:171], v129 offset:16384
	ds_read_b128 v[172:175], v129 offset:17408
	ds_read_b128 v[176:179], v132 offset:16384
	ds_read_b128 v[180:183], v132 offset:17408
	ds_read_b128 v[184:187], v131 offset:16384
	ds_read_b128 v[188:191], v131 offset:17408
	ds_read_b128 v[192:195], v130 offset:16384
	ds_read_b128 v[196:199], v130 offset:17408
	buffer_load_dwordx4 v141, s[8:11], s22 offen lds
	s_mov_b32 m0, s95
	s_nop 0
	buffer_load_dwordx4 v142, s[8:11], s22 offen lds
	s_barrier
	s_waitcnt lgkmcnt(0)
	v_mfma_f32_16x16x32_bf16 v[44:47], v[152:155], v[168:171], v[44:47]
	v_mfma_f32_16x16x32_bf16 v[40:43], v[160:163], v[168:171], v[40:43]
	v_mfma_f32_16x16x32_bf16 v[36:39], v[152:155], v[176:179], v[36:39]
	v_mfma_f32_16x16x32_bf16 v[32:35], v[160:163], v[176:179], v[32:35]
	v_mfma_f32_16x16x32_bf16 v[28:31], v[152:155], v[184:187], v[28:31]
	v_mfma_f32_16x16x32_bf16 v[24:27], v[160:163], v[184:187], v[24:27]
	v_mfma_f32_16x16x32_bf16 v[20:23], v[152:155], v[192:195], v[20:23]
	v_mfma_f32_16x16x32_bf16 v[16:19], v[160:163], v[192:195], v[16:19]
	v_mfma_f32_16x16x32_bf16 v[44:47], v[156:159], v[172:175], v[44:47]
	v_mfma_f32_16x16x32_bf16 v[40:43], v[164:167], v[172:175], v[40:43]
	v_mfma_f32_16x16x32_bf16 v[36:39], v[156:159], v[180:183], v[36:39]
	v_mfma_f32_16x16x32_bf16 v[32:35], v[164:167], v[180:183], v[32:35]
	v_mfma_f32_16x16x32_bf16 v[28:31], v[156:159], v[188:191], v[28:31]
	v_mfma_f32_16x16x32_bf16 v[24:27], v[164:167], v[188:191], v[24:27]
	v_mfma_f32_16x16x32_bf16 v[20:23], v[156:159], v[196:199], v[20:23]
	v_mfma_f32_16x16x32_bf16 v[16:19], v[164:167], v[196:199], v[16:19]
	s_barrier
	s_add_i32 s22, s84, s3
	s_add_i32 s23, s22, 0x100
	s_mov_b32 m0, s86
	s_nop 0
	buffer_load_dwordx4 v141, s[12:15], s23 offen lds
	s_mov_b32 m0, s28
	s_nop 0
	buffer_load_dwordx4 v142, s[12:15], s23 offen lds
	s_waitcnt vmcnt(6)
	s_barrier
; #define STAGE(P, RS, SOFF, OFF, kt) do { const int _so = (SOFF) + (kt) * (BK * 2); \
;     _Pragma("unroll") for (int _i = 0; _i < 2; ++_i) { \
;       __builtin_amdgcn_raw_ptr_buffer_load_lds(RS, (__attribute__((address_space(3))) void*)((P) + wave * 1024 + _i * 8192), 16, OFF[_i], _so, 0, 0); } } while (0)
; #define LDA(dst, b, h) _Pragma("unroll") for (int m = 0; m < 4; ++m) _Pragma("unroll") for (int k = 0; k < 2; ++k) \
;     dst[m][k] = *reinterpret_cast<const bf16x8*>(SA(b, h) + lds_byte(wr * 64 + m * 16 + fr, k * 32 + fq * 8))
; #define LDB(dst, b, h) _Pragma("unroll") for (int n = 0; n < 2; ++n) _Pragma("unroll") for (int k = 0; k < 2; ++k) \
;     dst[n][k] = *reinterpret_cast<const bf16x8*>(SB(b, h) + lds_byte(wc * 32 + n * 16 + fr, k * 32 + fq * 8))
; #define WAIT_V(n) asm volatile("s_waitcnt vmcnt(" #n ")" ::: "memory")
; #define WAIT_L(n) asm volatile("s_waitcnt lgkmcnt(" #n ")" ::: "memory")
; #define BAR __builtin_amdgcn_s_barrier()
; #define SCHED __builtin_amdgcn_sched_barrier(0)
;     ...
;       WAIT_V(6); BAR; MMA(1, 1, At, B1); BAR;
;       LDB(B0, 1, 0); SCHED; LDA(At, 1, 0); STAGE(SA(0, 1), rsA, sA1, offA, t + 2);
;       WAIT_L(8); BAR; WAIT_L(0); MMA(0, 0, At, B0); BAR; SCHED;
;       LDB(B1, 1, 1); STAGE(SB(1, 0), rsB, sB0, offB, t + 3);
;       BAR; WAIT_L(0); MMA(0, 1, At, B1); BAR;
;       LDA(At, 1, 1); STAGE(SA(1, 0), rsA, sA0, offA, t + 3);
;       BAR; WAIT_L(0); MMA(1, 0, At, B0); BAR; SCHED;
	v_mfma_f32_16x16x32_bf16 v[12:15], v[200:203], v[168:171], v[12:15]
	v_mfma_f32_16x16x32_bf16 v[8:11], v[208:211], v[168:171], v[8:11]
	v_mfma_f32_16x16x32_bf16 v[4:7], v[200:203], v[176:179], v[4:7]
	v_mfma_f32_16x16x32_bf16 v[0:3], v[208:211], v[176:179], v[0:3]
	v_mfma_f32_16x16x32_bf16 v[64:67], v[200:203], v[184:187], v[64:67]
	v_mfma_f32_16x16x32_bf16 v[72:75], v[208:211], v[184:187], v[72:75]
	v_mfma_f32_16x16x32_bf16 v[76:79], v[200:203], v[192:195], v[76:79]
	v_mfma_f32_16x16x32_bf16 v[84:87], v[208:211], v[192:195], v[84:87]
	v_mfma_f32_16x16x32_bf16 v[12:15], v[204:207], v[172:175], v[12:15]
	v_mfma_f32_16x16x32_bf16 v[8:11], v[212:215], v[172:175], v[8:11]
	v_mfma_f32_16x16x32_bf16 v[4:7], v[204:207], v[180:183], v[4:7]
	v_mfma_f32_16x16x32_bf16 v[0:3], v[212:215], v[180:183], v[0:3]
	v_mfma_f32_16x16x32_bf16 v[64:67], v[204:207], v[188:191], v[64:67]
	v_mfma_f32_16x16x32_bf16 v[72:75], v[212:215], v[188:191], v[72:75]
	v_mfma_f32_16x16x32_bf16 v[76:79], v[204:207], v[196:199], v[76:79]
	v_mfma_f32_16x16x32_bf16 v[84:87], v[212:215], v[196:199], v[84:87]
	s_barrier
	ds_read_b128 v[152:155], v137
	ds_read_b128 v[156:159], v138
	ds_read_b128 v[160:163], v139
	ds_read_b128 v[164:167], v140
	s_addk_i32 s5, 0x100
	s_mov_b32 m0, s87
	ds_read_b128 v[168:171], v129 offset:32768
	ds_read_b128 v[172:175], v129 offset:33792
	ds_read_b128 v[176:179], v132 offset:32768
	ds_read_b128 v[180:183], v132 offset:33792
	ds_read_b128 v[184:187], v131 offset:32768
	ds_read_b128 v[188:191], v131 offset:33792
	ds_read_b128 v[192:195], v130 offset:32768
	ds_read_b128 v[196:199], v130 offset:33792
	buffer_load_dwordx4 v141, s[8:11], s5 offen lds
	s_mov_b32 m0, s97
	s_nop 0
	buffer_load_dwordx4 v142, s[8:11], s5 offen lds
	s_waitcnt lgkmcnt(8)
	s_barrier
	s_waitcnt lgkmcnt(0)
	v_mfma_f32_16x16x32_bf16 v[124:127], v[152:155], v[168:171], v[124:127]
	v_mfma_f32_16x16x32_bf16 v[120:123], v[160:163], v[168:171], v[120:123]
	v_mfma_f32_16x16x32_bf16 v[116:119], v[152:155], v[176:179], v[116:119]
	v_mfma_f32_16x16x32_bf16 v[112:115], v[160:163], v[176:179], v[112:115]
	v_mfma_f32_16x16x32_bf16 v[108:111], v[152:155], v[184:187], v[108:111]
	v_mfma_f32_16x16x32_bf16 v[104:107], v[160:163], v[184:187], v[104:107]
	v_mfma_f32_16x16x32_bf16 v[100:103], v[152:155], v[192:195], v[100:103]
	v_mfma_f32_16x16x32_bf16 v[96:99], v[160:163], v[192:195], v[96:99]
	v_mfma_f32_16x16x32_bf16 v[124:127], v[156:159], v[172:175], v[124:127]
	v_mfma_f32_16x16x32_bf16 v[120:123], v[164:167], v[172:175], v[120:123]
	v_mfma_f32_16x16x32_bf16 v[116:119], v[156:159], v[180:183], v[116:119]
	v_mfma_f32_16x16x32_bf16 v[112:115], v[164:167], v[180:183], v[112:115]
	v_mfma_f32_16x16x32_bf16 v[108:111], v[156:159], v[188:191], v[108:111]
	v_mfma_f32_16x16x32_bf16 v[104:107], v[164:167], v[188:191], v[104:107]
	v_mfma_f32_16x16x32_bf16 v[100:103], v[156:159], v[196:199], v[100:103]
	v_mfma_f32_16x16x32_bf16 v[96:99], v[164:167], v[196:199], v[96:99]
	s_barrier
	s_addk_i32 s6, 0x180
	s_mov_b32 m0, s92
	ds_read_b128 v[200:203], v133
	ds_read_b128 v[204:207], v134
	ds_read_b128 v[208:211], v135
	ds_read_b128 v[212:215], v136
	buffer_load_dwordx4 v141, s[12:15], s6 offen lds
	s_mov_b32 m0, s29
	s_nop 0
	buffer_load_dwordx4 v142, s[12:15], s6 offen lds
	s_barrier
	s_waitcnt lgkmcnt(0)
	v_mfma_f32_16x16x32_bf16 v[92:95], v[200:203], v[168:171], v[92:95]
	v_mfma_f32_16x16x32_bf16 v[88:91], v[208:211], v[168:171], v[88:91]
	v_mfma_f32_16x16x32_bf16 v[80:83], v[200:203], v[176:179], v[80:83]
	v_mfma_f32_16x16x32_bf16 v[68:71], v[208:211], v[176:179], v[68:71]
	v_mfma_f32_16x16x32_bf16 v[60:63], v[200:203], v[184:187], v[60:63]
	v_mfma_f32_16x16x32_bf16 v[56:59], v[208:211], v[184:187], v[56:59]
	v_mfma_f32_16x16x32_bf16 v[52:55], v[200:203], v[192:195], v[52:55]
	v_mfma_f32_16x16x32_bf16 v[48:51], v[208:211], v[192:195], v[48:51]
	v_mfma_f32_16x16x32_bf16 v[92:95], v[204:207], v[172:175], v[92:95]
	v_mfma_f32_16x16x32_bf16 v[88:91], v[212:215], v[172:175], v[88:91]
	v_mfma_f32_16x16x32_bf16 v[80:83], v[204:207], v[180:183], v[80:83]
	v_mfma_f32_16x16x32_bf16 v[68:71], v[212:215], v[180:183], v[68:71]
	v_mfma_f32_16x16x32_bf16 v[60:63], v[204:207], v[188:191], v[60:63]
	v_mfma_f32_16x16x32_bf16 v[56:59], v[212:215], v[188:191], v[56:59]
	v_mfma_f32_16x16x32_bf16 v[52:55], v[204:207], v[196:199], v[52:55]
	v_mfma_f32_16x16x32_bf16 v[48:51], v[212:215], v[196:199], v[48:51]
	s_addk_i32 s7, 0x180
	s_mov_b32 m0, s93
	s_barrier
	ds_read_b128 v[168:171], v129 offset:49152
	ds_read_b128 v[172:175], v129 offset:50176
	ds_read_b128 v[176:179], v132 offset:49152
	ds_read_b128 v[180:183], v132 offset:50176
	ds_read_b128 v[184:187], v131 offset:49152
	ds_read_b128 v[188:191], v131 offset:50176
	ds_read_b128 v[192:195], v130 offset:49152
	ds_read_b128 v[196:199], v130 offset:50176
	buffer_load_dwordx4 v141, s[8:11], s7 offen lds
	s_mov_b32 m0, s56
	s_nop 0
	buffer_load_dwordx4 v142, s[8:11], s7 offen lds
	s_barrier
	s_waitcnt lgkmcnt(0)
	v_mfma_f32_16x16x32_bf16 v[44:47], v[152:155], v[168:171], v[44:47]
	v_mfma_f32_16x16x32_bf16 v[40:43], v[160:163], v[168:171], v[40:43]
	v_mfma_f32_16x16x32_bf16 v[36:39], v[152:155], v[176:179], v[36:39]
	v_mfma_f32_16x16x32_bf16 v[32:35], v[160:163], v[176:179], v[32:35]
	v_mfma_f32_16x16x32_bf16 v[28:31], v[152:155], v[184:187], v[28:31]
	v_mfma_f32_16x16x32_bf16 v[24:27], v[160:163], v[184:187], v[24:27]
	v_mfma_f32_16x16x32_bf16 v[20:23], v[152:155], v[192:195], v[20:23]
	v_mfma_f32_16x16x32_bf16 v[16:19], v[160:163], v[192:195], v[16:19]
	v_mfma_f32_16x16x32_bf16 v[44:47], v[156:159], v[172:175], v[44:47]
	v_mfma_f32_16x16x32_bf16 v[40:43], v[164:167], v[172:175], v[40:43]
	v_mfma_f32_16x16x32_bf16 v[36:39], v[156:159], v[180:183], v[36:39]
	v_mfma_f32_16x16x32_bf16 v[32:35], v[164:167], v[180:183], v[32:35]
	v_mfma_f32_16x16x32_bf16 v[28:31], v[156:159], v[188:191], v[28:31]
	v_mfma_f32_16x16x32_bf16 v[24:27], v[164:167], v[188:191], v[24:27]
	v_mfma_f32_16x16x32_bf16 v[20:23], v[156:159], v[196:199], v[20:23]
	v_mfma_f32_16x16x32_bf16 v[16:19], v[164:167], v[196:199], v[16:19]
	s_barrier
; #define STAGE(P, RS, SOFF, OFF, kt) do { const int _so = (SOFF) + (kt) * (BK * 2); \
;     _Pragma("unroll") for (int _i = 0; _i < 2; ++_i) { \
;       __builtin_amdgcn_raw_ptr_buffer_load_lds(RS, (__attribute__((address_space(3))) void*)((P) + wave * 1024 + _i * 8192), 16, OFF[_i], _so, 0, 0); } } while (0)
; #define LDA(dst, b, h) _Pragma("unroll") for (int m = 0; m < 4; ++m) _Pragma("unroll") for (int k = 0; k < 2; ++k) \
;     dst[m][k] = *reinterpret_cast<const bf16x8*>(SA(b, h) + lds_byte(wr * 64 + m * 16 + fr, k * 32 + fq * 8))
; #define LDB(dst, b, h) _Pragma("unroll") for (int n = 0; n < 2; ++n) _Pragma("unroll") for (int k = 0; k < 2; ++k) \
;     dst[n][k] = *reinterpret_cast<const bf16x8*>(SB(b, h) + lds_byte(wc * 32 + n * 16 + fr, k * 32 + fq * 8))
; #define WAIT_V(n) asm volatile("s_waitcnt vmcnt(" #n ")" ::: "memory")
; #define WAIT_L(n) asm volatile("s_waitcnt lgkmcnt(" #n ")" ::: "memory")
; #define BAR __builtin_amdgcn_s_barrier()
;     ...
;       STAGE(SB(1, 1), rsB, sB1, offB, t + 3);
;       WAIT_V(6); BAR; MMA(1, 1, At, B1); BAR;
;     }
;     { LDB(B0, 0, 0); LDA(At, 0, 0); STAGE(SA(1, 1), rsA, sA1, offA, nt - 1);
;       BAR; WAIT_L(0); MMA(0, 0, At, B0); BAR;
;       LDB(B1, 0, 1); BAR; WAIT_L(0); MMA(0, 1, At, B1); BAR;
;       LDA(At, 0, 1); WAIT_V(4); BAR; WAIT_L(0); MMA(1, 0, At, B0); MMA(1, 1, At, B1); BAR; }
;     { LDB(B0, 1, 0); LDA(At, 1, 0); WAIT_V(2); BAR; WAIT_L(0); MMA(0, 0, At, B0); BAR;
	s_addk_i32 s22, 0x180
	s_mov_b32 m0, s94
	s_nop 0
	buffer_load_dwordx4 v141, s[12:15], s22 offen lds
	s_mov_b32 m0, s57
	s_nop 0
	buffer_load_dwordx4 v142, s[12:15], s22 offen lds
	s_waitcnt vmcnt(6)
	s_barrier
	v_mfma_f32_16x16x32_bf16 v[12:15], v[200:203], v[168:171], v[12:15]
	v_mfma_f32_16x16x32_bf16 v[8:11], v[208:211], v[168:171], v[8:11]
	v_mfma_f32_16x16x32_bf16 v[4:7], v[200:203], v[176:179], v[4:7]
	v_mfma_f32_16x16x32_bf16 v[0:3], v[208:211], v[176:179], v[0:3]
	v_mfma_f32_16x16x32_bf16 v[64:67], v[200:203], v[184:187], v[64:67]
	v_mfma_f32_16x16x32_bf16 v[72:75], v[208:211], v[184:187], v[72:75]
	v_mfma_f32_16x16x32_bf16 v[76:79], v[200:203], v[192:195], v[76:79]
	v_mfma_f32_16x16x32_bf16 v[84:87], v[208:211], v[192:195], v[84:87]
	v_mfma_f32_16x16x32_bf16 v[12:15], v[204:207], v[172:175], v[12:15]
	v_mfma_f32_16x16x32_bf16 v[8:11], v[212:215], v[172:175], v[8:11]
	v_mfma_f32_16x16x32_bf16 v[4:7], v[204:207], v[180:183], v[4:7]
	v_mfma_f32_16x16x32_bf16 v[0:3], v[212:215], v[180:183], v[0:3]
	v_mfma_f32_16x16x32_bf16 v[64:67], v[204:207], v[188:191], v[64:67]
	v_mfma_f32_16x16x32_bf16 v[72:75], v[212:215], v[188:191], v[72:75]
	v_mfma_f32_16x16x32_bf16 v[76:79], v[204:207], v[196:199], v[76:79]
	v_mfma_f32_16x16x32_bf16 v[84:87], v[212:215], v[196:199], v[84:87]
	s_add_i32 s1, s1, 2
	s_addk_i32 s3, 0x100
	s_cmp_gt_u32 s1, 27
	s_barrier
	s_cbranch_scc0 .LBB0_657
	s_add_i32 s1, s81, 0xf80
	s_mov_b32 m0, s39
	ds_read_b128 v[152:155], v147
	ds_read_b128 v[156:159], v148
	ds_read_b128 v[160:163], v149
	ds_read_b128 v[148:151], v150
	ds_read_b128 v[164:167], v129
	ds_read_b128 v[168:171], v129 offset:1024
	ds_read_b128 v[172:175], v132
	ds_read_b128 v[176:179], v132 offset:1024
	ds_read_b128 v[180:183], v131
	ds_read_b128 v[184:187], v131 offset:1024
	ds_read_b128 v[188:191], v130
	ds_read_b128 v[192:195], v130 offset:1024
	buffer_load_dwordx4 v141, s[8:11], s1 offen lds
	s_mov_b32 m0, s58
	s_nop 0
	buffer_load_dwordx4 v142, s[8:11], s1 offen lds
	s_barrier
	s_waitcnt lgkmcnt(0)
	v_mfma_f32_16x16x32_bf16 v[124:127], v[152:155], v[164:167], v[124:127]
	v_mfma_f32_16x16x32_bf16 v[120:123], v[160:163], v[164:167], v[120:123]
	v_mfma_f32_16x16x32_bf16 v[116:119], v[152:155], v[172:175], v[116:119]
	v_mfma_f32_16x16x32_bf16 v[112:115], v[160:163], v[172:175], v[112:115]
	v_mfma_f32_16x16x32_bf16 v[108:111], v[152:155], v[180:183], v[108:111]
	v_mfma_f32_16x16x32_bf16 v[104:107], v[160:163], v[180:183], v[104:107]
	v_mfma_f32_16x16x32_bf16 v[100:103], v[152:155], v[188:191], v[100:103]
	v_mfma_f32_16x16x32_bf16 v[96:99], v[160:163], v[188:191], v[96:99]
	v_mfma_f32_16x16x32_bf16 v[124:127], v[156:159], v[168:171], v[124:127]
	v_mfma_f32_16x16x32_bf16 v[120:123], v[148:151], v[168:171], v[120:123]
	v_mfma_f32_16x16x32_bf16 v[116:119], v[156:159], v[176:179], v[116:119]
	v_mfma_f32_16x16x32_bf16 v[112:115], v[148:151], v[176:179], v[112:115]
	v_mfma_f32_16x16x32_bf16 v[108:111], v[156:159], v[184:187], v[108:111]
	v_mfma_f32_16x16x32_bf16 v[104:107], v[148:151], v[184:187], v[104:107]
	v_mfma_f32_16x16x32_bf16 v[100:103], v[156:159], v[192:195], v[100:103]
	v_mfma_f32_16x16x32_bf16 v[96:99], v[148:151], v[192:195], v[96:99]
	s_barrier
	ds_read_b128 v[196:199], v143
	ds_read_b128 v[200:203], v144
	ds_read_b128 v[142:145], v145
	ds_read_b128 v[204:207], v146
	s_barrier
	s_waitcnt lgkmcnt(0)
	v_mfma_f32_16x16x32_bf16 v[88:91], v[142:145], v[164:167], v[88:91]
	v_mfma_f32_16x16x32_bf16 v[80:83], v[196:199], v[172:175], v[80:83]
	v_mfma_f32_16x16x32_bf16 v[60:63], v[196:199], v[180:183], v[60:63]
	v_mfma_f32_16x16x32_bf16 v[56:59], v[142:145], v[180:183], v[56:59]
	v_mfma_f32_16x16x32_bf16 v[52:55], v[196:199], v[188:191], v[52:55]
	v_mfma_f32_16x16x32_bf16 v[48:51], v[142:145], v[188:191], v[48:51]
	v_mfma_f32_16x16x32_bf16 v[92:95], v[196:199], v[164:167], v[92:95]
	v_mfma_f32_16x16x32_bf16 v[68:71], v[142:145], v[172:175], v[68:71]
	v_mfma_f32_16x16x32_bf16 v[88:91], v[204:207], v[168:171], v[88:91]
	v_mfma_f32_16x16x32_bf16 v[80:83], v[200:203], v[176:179], v[80:83]
	v_mfma_f32_16x16x32_bf16 v[60:63], v[200:203], v[184:187], v[60:63]
	v_mfma_f32_16x16x32_bf16 v[56:59], v[204:207], v[184:187], v[56:59]
	v_mfma_f32_16x16x32_bf16 v[52:55], v[200:203], v[192:195], v[52:55]
	v_mfma_f32_16x16x32_bf16 v[48:51], v[204:207], v[192:195], v[48:51]
	v_mfma_f32_16x16x32_bf16 v[164:167], v[200:203], v[168:171], v[92:95]
	v_mfma_f32_16x16x32_bf16 v[168:171], v[204:207], v[176:179], v[68:71]
	s_barrier
	s_nop 0
	ds_read_b128 v[68:71], v129 offset:16384
	ds_read_b128 v[92:95], v129 offset:17408
	ds_read_b128 v[172:175], v132 offset:16384
	ds_read_b128 v[176:179], v132 offset:17408
	ds_read_b128 v[180:183], v131 offset:16384
	ds_read_b128 v[184:187], v131 offset:17408
	ds_read_b128 v[188:191], v130 offset:16384
	ds_read_b128 v[192:195], v130 offset:17408
	s_waitcnt vmcnt(4)
	s_barrier
; #define LDA(dst, b, h) _Pragma("unroll") for (int m = 0; m < 4; ++m) _Pragma("unroll") for (int k = 0; k < 2; ++k) \
;     dst[m][k] = *reinterpret_cast<const bf16x8*>(SA(b, h) + lds_byte(wr * 64 + m * 16 + fr, k * 32 + fq * 8))
; #define LDB(dst, b, h) _Pragma("unroll") for (int n = 0; n < 2; ++n) _Pragma("unroll") for (int k = 0; k < 2; ++k) \
;     dst[n][k] = *reinterpret_cast<const bf16x8*>(SB(b, h) + lds_byte(wc * 32 + n * 16 + fr, k * 32 + fq * 8))
; #define WAIT_V(n) asm volatile("s_waitcnt vmcnt(" #n ")" ::: "memory")
; #define WAIT_L(n) asm volatile("s_waitcnt lgkmcnt(" #n ")" ::: "memory")
; #define BAR __builtin_amdgcn_s_barrier()
;     ...
;       LDA(At, 0, 1); WAIT_V(4); BAR; WAIT_L(0); MMA(1, 0, At, B0); MMA(1, 1, At, B1); BAR; }
;     { LDB(B0, 1, 0); LDA(At, 1, 0); WAIT_V(2); BAR; WAIT_L(0); MMA(0, 0, At, B0); BAR;
;       LDB(B1, 1, 1); WAIT_V(0); BAR; WAIT_L(0); MMA(0, 1, At, B1); BAR;
	s_waitcnt lgkmcnt(0)
	v_mfma_f32_16x16x32_bf16 v[44:47], v[152:155], v[68:71], v[44:47]
	v_mfma_f32_16x16x32_bf16 v[40:43], v[160:163], v[68:71], v[40:43]
	v_mfma_f32_16x16x32_bf16 v[36:39], v[152:155], v[172:175], v[36:39]
	v_mfma_f32_16x16x32_bf16 v[32:35], v[160:163], v[172:175], v[32:35]
	v_mfma_f32_16x16x32_bf16 v[28:31], v[152:155], v[180:183], v[28:31]
	v_mfma_f32_16x16x32_bf16 v[24:27], v[160:163], v[180:183], v[24:27]
	v_mfma_f32_16x16x32_bf16 v[20:23], v[152:155], v[188:191], v[20:23]
	v_mfma_f32_16x16x32_bf16 v[16:19], v[160:163], v[188:191], v[16:19]
	v_mfma_f32_16x16x32_bf16 v[44:47], v[156:159], v[92:95], v[44:47]
	v_mfma_f32_16x16x32_bf16 v[40:43], v[148:151], v[92:95], v[40:43]
	v_mfma_f32_16x16x32_bf16 v[36:39], v[156:159], v[176:179], v[36:39]
	v_mfma_f32_16x16x32_bf16 v[32:35], v[148:151], v[176:179], v[32:35]
	v_mfma_f32_16x16x32_bf16 v[28:31], v[156:159], v[184:187], v[28:31]
	v_mfma_f32_16x16x32_bf16 v[24:27], v[148:151], v[184:187], v[24:27]
	v_mfma_f32_16x16x32_bf16 v[20:23], v[156:159], v[192:195], v[20:23]
	v_mfma_f32_16x16x32_bf16 v[16:19], v[148:151], v[192:195], v[16:19]
	v_mfma_f32_16x16x32_bf16 v[4:7], v[196:199], v[172:175], v[4:7]
	v_mfma_f32_16x16x32_bf16 v[0:3], v[142:145], v[172:175], v[0:3]
	v_mfma_f32_16x16x32_bf16 v[12:15], v[196:199], v[68:71], v[12:15]
	v_mfma_f32_16x16x32_bf16 v[8:11], v[142:145], v[68:71], v[8:11]
	v_mfma_f32_16x16x32_bf16 v[64:67], v[196:199], v[180:183], v[64:67]
	v_mfma_f32_16x16x32_bf16 v[68:71], v[142:145], v[180:183], v[72:75]
	v_mfma_f32_16x16x32_bf16 v[72:75], v[196:199], v[188:191], v[76:79]
	v_mfma_f32_16x16x32_bf16 v[76:79], v[142:145], v[188:191], v[84:87]
	v_mfma_f32_16x16x32_bf16 v[4:7], v[200:203], v[176:179], v[4:7]
	v_mfma_f32_16x16x32_bf16 v[0:3], v[204:207], v[176:179], v[0:3]
	v_mfma_f32_16x16x32_bf16 v[142:145], v[200:203], v[92:95], v[12:15]
	v_mfma_f32_16x16x32_bf16 v[146:149], v[204:207], v[92:95], v[8:11]
	v_mfma_f32_16x16x32_bf16 v[150:153], v[200:203], v[184:187], v[64:67]
	v_mfma_f32_16x16x32_bf16 v[154:157], v[204:207], v[184:187], v[68:71]
	v_mfma_f32_16x16x32_bf16 v[158:161], v[200:203], v[192:195], v[72:75]
	v_mfma_f32_16x16x32_bf16 v[172:175], v[204:207], v[192:195], v[76:79]
	s_barrier
	ds_read_b128 v[8:11], v137
	ds_read_b128 v[12:15], v138
	ds_read_b128 v[176:179], v139
	ds_read_b128 v[138:141], v140
	ds_read_b128 v[64:67], v129 offset:32768
	ds_read_b128 v[72:75], v129 offset:33792
	ds_read_b128 v[180:183], v132 offset:32768
	ds_read_b128 v[184:187], v132 offset:33792
	ds_read_b128 v[188:191], v131 offset:32768
	ds_read_b128 v[192:195], v131 offset:33792
	ds_read_b128 v[196:199], v130 offset:32768
	ds_read_b128 v[200:203], v130 offset:33792
	s_waitcnt vmcnt(2)
	s_barrier
	s_waitcnt lgkmcnt(0)
	v_mfma_f32_16x16x32_bf16 v[68:71], v[8:11], v[64:67], v[124:127]
	v_mfma_f32_16x16x32_bf16 v[76:79], v[176:179], v[64:67], v[120:123]
	v_mfma_f32_16x16x32_bf16 v[84:87], v[8:11], v[180:183], v[116:119]
	v_mfma_f32_16x16x32_bf16 v[92:95], v[176:179], v[180:183], v[112:115]
	v_mfma_f32_16x16x32_bf16 v[112:115], v[8:11], v[188:191], v[108:111]
	v_mfma_f32_16x16x32_bf16 v[104:107], v[176:179], v[188:191], v[104:107]
	v_mfma_f32_16x16x32_bf16 v[120:123], v[8:11], v[196:199], v[100:103]
	v_mfma_f32_16x16x32_bf16 v[96:99], v[176:179], v[196:199], v[96:99]
	v_mfma_f32_16x16x32_bf16 v[124:127], v[12:15], v[72:75], v[68:71]
	v_mfma_f32_16x16x32_bf16 v[116:119], v[138:141], v[72:75], v[76:79]
	v_mfma_f32_16x16x32_bf16 v[108:111], v[12:15], v[184:187], v[84:87]
	v_mfma_f32_16x16x32_bf16 v[100:103], v[138:141], v[184:187], v[92:95]
	v_mfma_f32_16x16x32_bf16 v[92:95], v[12:15], v[192:195], v[112:115]
	v_mfma_f32_16x16x32_bf16 v[84:87], v[138:141], v[192:195], v[104:107]
	v_mfma_f32_16x16x32_bf16 v[76:79], v[12:15], v[200:203], v[120:123]
	v_mfma_f32_16x16x32_bf16 v[68:71], v[138:141], v[200:203], v[96:99]
	s_barrier
; #define LDA(dst, b, h) _Pragma("unroll") for (int m = 0; m < 4; ++m) _Pragma("unroll") for (int k = 0; k < 2; ++k) \
;     dst[m][k] = *reinterpret_cast<const bf16x8*>(SA(b, h) + lds_byte(wr * 64 + m * 16 + fr, k * 32 + fq * 8))
; #define LDB(dst, b, h) _Pragma("unroll") for (int n = 0; n < 2; ++n) _Pragma("unroll") for (int k = 0; k < 2; ++k) \
;     dst[n][k] = *reinterpret_cast<const bf16x8*>(SB(b, h) + lds_byte(wc * 32 + n * 16 + fr, k * 32 + fq * 8))
; #define WAIT_V(n) asm volatile("s_waitcnt vmcnt(" #n ")" ::: "memory")
; #define WAIT_L(n) asm volatile("s_waitcnt lgkmcnt(" #n ")" ::: "memory")
; #define BAR __builtin_amdgcn_s_barrier()
;     ...
;     { LDB(B0, 1, 0); LDA(At, 1, 0); WAIT_V(2); BAR; WAIT_L(0); MMA(0, 0, At, B0); BAR;
;       LDB(B1, 1, 1); WAIT_V(0); BAR; WAIT_L(0); MMA(0, 1, At, B1); BAR;
;       LDA(At, 1, 1); BAR; WAIT_L(0); MMA(1, 0, At, B0); MMA(1, 1, At, B1); BAR; }
;     if (wr == 0) BAR;
	ds_read_b128 v[204:207], v133
	ds_read_b128 v[208:211], v134
	ds_read_b128 v[212:215], v135
	ds_read_b128 v[134:137], v136
	s_waitcnt vmcnt(0)
	s_barrier
	s_waitcnt lgkmcnt(0)
	v_mfma_f32_16x16x32_bf16 v[96:99], v[204:207], v[64:67], v[164:167]
	v_mfma_f32_16x16x32_bf16 v[64:67], v[212:215], v[64:67], v[88:91]
	v_mfma_f32_16x16x32_bf16 v[80:83], v[204:207], v[180:183], v[80:83]
	v_mfma_f32_16x16x32_bf16 v[88:91], v[212:215], v[180:183], v[168:171]
	v_mfma_f32_16x16x32_bf16 v[60:63], v[204:207], v[188:191], v[60:63]
	v_mfma_f32_16x16x32_bf16 v[56:59], v[212:215], v[188:191], v[56:59]
	v_mfma_f32_16x16x32_bf16 v[52:55], v[204:207], v[196:199], v[52:55]
	v_mfma_f32_16x16x32_bf16 v[48:51], v[212:215], v[196:199], v[48:51]
	v_mfma_f32_16x16x32_bf16 v[120:123], v[208:211], v[72:75], v[96:99]
	v_mfma_f32_16x16x32_bf16 v[112:115], v[134:137], v[72:75], v[64:67]
	v_mfma_f32_16x16x32_bf16 v[104:107], v[208:211], v[184:187], v[80:83]
	v_mfma_f32_16x16x32_bf16 v[96:99], v[134:137], v[184:187], v[88:91]
	v_mfma_f32_16x16x32_bf16 v[88:91], v[208:211], v[192:195], v[60:63]
	v_mfma_f32_16x16x32_bf16 v[80:83], v[134:137], v[192:195], v[56:59]
	v_mfma_f32_16x16x32_bf16 v[72:75], v[208:211], v[200:203], v[52:55]
	v_mfma_f32_16x16x32_bf16 v[64:67], v[134:137], v[200:203], v[48:51]
	s_barrier
	s_nop 0
	ds_read_b128 v[48:51], v129 offset:49152
	ds_read_b128 v[162:165], v129 offset:50176
	ds_read_b128 v[52:55], v132 offset:49152
	ds_read_b128 v[166:169], v132 offset:50176
	ds_read_b128 v[180:183], v131 offset:49152
	ds_read_b128 v[184:187], v131 offset:50176
	ds_read_b128 v[188:191], v130 offset:49152
	ds_read_b128 v[130:133], v130 offset:50176
	s_barrier
	s_waitcnt lgkmcnt(0)
	v_mfma_f32_16x16x32_bf16 v[44:47], v[8:11], v[48:51], v[44:47]
	v_mfma_f32_16x16x32_bf16 v[40:43], v[176:179], v[48:51], v[40:43]
	v_mfma_f32_16x16x32_bf16 v[36:39], v[8:11], v[52:55], v[36:39]
	v_mfma_f32_16x16x32_bf16 v[32:35], v[176:179], v[52:55], v[32:35]
	v_mfma_f32_16x16x32_bf16 v[28:31], v[8:11], v[180:183], v[28:31]
	v_mfma_f32_16x16x32_bf16 v[24:27], v[176:179], v[180:183], v[24:27]
	v_mfma_f32_16x16x32_bf16 v[8:11], v[8:11], v[188:191], v[20:23]
	v_mfma_f32_16x16x32_bf16 v[16:19], v[176:179], v[188:191], v[16:19]
	v_mfma_f32_16x16x32_bf16 v[60:63], v[12:15], v[162:165], v[44:47]
	v_mfma_f32_16x16x32_bf16 v[56:59], v[138:141], v[162:165], v[40:43]
	v_mfma_f32_16x16x32_bf16 v[44:47], v[12:15], v[166:169], v[36:39]
	v_mfma_f32_16x16x32_bf16 v[40:43], v[138:141], v[166:169], v[32:35]
	v_mfma_f32_16x16x32_bf16 v[28:31], v[12:15], v[184:187], v[28:31]
	v_mfma_f32_16x16x32_bf16 v[24:27], v[138:141], v[184:187], v[24:27]
	v_mfma_f32_16x16x32_bf16 v[12:15], v[12:15], v[130:133], v[8:11]
	v_mfma_f32_16x16x32_bf16 v[8:11], v[138:141], v[130:133], v[16:19]
	v_mfma_f32_16x16x32_bf16 v[16:19], v[204:207], v[48:51], v[142:145]
	v_mfma_f32_16x16x32_bf16 v[20:23], v[212:215], v[48:51], v[146:149]
	v_mfma_f32_16x16x32_bf16 v[4:7], v[204:207], v[52:55], v[4:7]
	v_mfma_f32_16x16x32_bf16 v[0:3], v[212:215], v[52:55], v[0:3]
	v_mfma_f32_16x16x32_bf16 v[138:141], v[204:207], v[180:183], v[150:153]
	v_mfma_f32_16x16x32_bf16 v[142:145], v[212:215], v[180:183], v[154:157]
	v_mfma_f32_16x16x32_bf16 v[146:149], v[204:207], v[188:191], v[158:161]
	v_mfma_f32_16x16x32_bf16 v[150:153], v[212:215], v[188:191], v[172:175]
	v_mfma_f32_16x16x32_bf16 v[52:55], v[208:211], v[162:165], v[16:19]
	v_mfma_f32_16x16x32_bf16 v[48:51], v[134:137], v[162:165], v[20:23]
	v_mfma_f32_16x16x32_bf16 v[36:39], v[208:211], v[166:169], v[4:7]
	v_mfma_f32_16x16x32_bf16 v[32:35], v[134:137], v[166:169], v[0:3]
	v_mfma_f32_16x16x32_bf16 v[20:23], v[208:211], v[184:187], v[138:141]
	v_mfma_f32_16x16x32_bf16 v[16:19], v[134:137], v[184:187], v[142:145]
	v_mfma_f32_16x16x32_bf16 v[4:7], v[208:211], v[130:133], v[146:149]
	v_mfma_f32_16x16x32_bf16 v[0:3], v[134:137], v[130:133], v[150:153]
	v_cmp_gt_u32_e32 vcc, s73, v128
	s_barrier
	s_and_saveexec_b64 s[6:7], vcc
	s_cbranch_execz .LBB0_660
	s_barrier

; #define WAIT_V(n) asm volatile("s_waitcnt vmcnt(" #n ")" ::: "memory")
; #define BAR __builtin_amdgcn_s_barrier()
;     ...
;         constexpr int PIECE = 1024 + 16, LOBASE = 64 * PIECE;
;         const int hvo = (lane >> 5) * (DM * 2) + (lane & 31) * 16;
;         const int lvo = (lane >> 4) * DM + (lane & 15) * 16;
;         _Pragma("unroll") for (int ai = 0; ai < 2; ++ai) {
;           const int rbase = brow + ai * HALF;
;           const int hso = ((rbase + 16 * wave) * DM + pn * BM) * 2;
;           const int lso = (rbase + 16 * wave) * DM + pn * BM;
;           _Pragma("unroll") for (int i = 0; i < 8; ++i)
;             __builtin_amdgcn_raw_ptr_buffer_load_lds(rsXB, (__attribute__((address_space(3))) void*)(smem + (wave * 8 + i) * PIECE), 16,
;                                                      hvo + i * (2 * DM * 2), hso, 0, 0);
;           _Pragma("unroll") for (int i = 0; i < 4; ++i)
;             __builtin_amdgcn_raw_ptr_buffer_load_lds(rsLO, (__attribute__((address_space(3))) void*)(smem + LOBASE + (wave * 4 + i) * PIECE), 16,
;                                                      lvo + i * (4 * DM), lso, 0, 0);
;           WAIT_V(0); BAR;
;           _Pragma("unroll") for (int m = 0; m < 4; ++m) _Pragma("unroll") for (int bj = 0; bj < 2; ++bj) _Pragma("unroll") for (int n = 0; n < 2; ++n) {
;             const int rr = wr * 64 + m * 16 + fr;
;             const int cc = bj * HALF + wc * 32 + n * 16 + fq * 4;
;             const u32x2 hv = *reinterpret_cast<const u32x2*>(smem + (rr >> 1) * PIECE + (rr & 1) * 512 + cc * 2);
;             const unsigned lv = *reinterpret_cast<const unsigned*>(smem + LOBASE + (rr >> 2) * PIECE + (rr & 3) * 256 + cc);
;             float x0 = __int_as_float((int)(hv[0] << 16) + (((int)(lv << 24)) >> 24) * 256);
;             float x1 = __int_as_float((int)(hv[0] & 0xffff0000u) + (((int)(lv << 16)) >> 24) * 256);
;             float x2 = __int_as_float((int)(hv[1] << 16) + (((int)(lv << 8)) >> 24) * 256);
;             float x3 = __int_as_float((int)(hv[1] & 0xffff0000u) + (((int)lv) >> 24) * 256);
;             acc[ai][bj][m][n][0] = ALPHA * x0 + sc * acc[ai][bj][m][n][0];
;             acc[ai][bj][m][n][1] = ALPHA * x1 + sc * acc[ai][bj][m][n][1];
;             acc[ai][bj][m][n][2] = ALPHA * x2 + sc * acc[ai][bj][m][n][2];
;             acc[ai][bj][m][n][3] = ALPHA * x3 + sc * acc[ai][bj][m][n][3];
.LBB0_662:
	s_lshl_b32 s5, s4, 19
	v_mbcnt_lo_u32_b32 v128, -1, 0
	v_mbcnt_hi_u32_b32 v128, -1, v128
	s_lshl_b32 s34, s0, 8
	v_lshlrev_b32_e32 v134, 4, v128
	s_add_i32 s50, s5, s96
	v_lshlrev_b32_e32 v133, 7, v128
	v_and_b32_e32 v134, 0x1f0, v134
	s_add_i32 s33, s50, s34
	s_mov_b32 m0, s59
	v_and_or_b32 v146, v133, s72, v134
	s_lshl_b32 s76, s33, 1
	buffer_load_dwordx4 v146, s[16:19], s76 offen lds
	v_or_b32_e32 v152, 0x2000, v146
	s_mov_b32 m0, s61
	v_or_b32_e32 v153, 0x4000, v146
	buffer_load_dwordx4 v152, s[16:19], s76 offen lds
	s_mov_b32 m0, s62
	v_or_b32_e32 v154, 0x6000, v146
	buffer_load_dwordx4 v153, s[16:19], s76 offen lds
	s_mov_b32 m0, s63
	v_or_b32_e32 v155, 0x8000, v146
	buffer_load_dwordx4 v154, s[16:19], s76 offen lds
	s_mov_b32 m0, s64
	v_add_u32_e32 v220, s37, v128
	buffer_load_dwordx4 v155, s[16:19], s76 offen lds
	v_or_b32_e32 v156, 0xa000, v146
	s_mov_b32 m0, s65
	v_and_b32_e32 v129, 15, v128
	v_ashrrev_i32_e32 v131, 2, v220
	buffer_load_dwordx4 v156, s[16:19], s76 offen lds
	v_or_b32_e32 v157, 0xc000, v146
	s_mov_b32 m0, s66
	v_and_b32_e32 v223, 63, v128
	v_bfe_u32 v130, v128, 4, 2
	v_lshlrev_b32_e32 v133, 4, v129
	v_and_or_b32 v225, v131, s36, v129
	v_lshlrev_b32_e32 v129, 9, v128
	v_lshlrev_b32_e32 v128, 8, v128
	buffer_load_dwordx4 v157, s[16:19], s76 offen lds
	v_or_b32_e32 v158, 0xe000, v146
	s_mov_b32 m0, s67
	v_lshl_or_b32 v147, v130, 11, v133
	v_and_b32_e32 v128, 0x300, v128
	v_or_b32_e32 v150, 48, v225
	buffer_load_dwordx4 v158, s[16:19], s76 offen lds
	s_mov_b32 s22, s18
	s_mov_b32 s23, s19
	s_mov_b32 m0, s68
	v_bfe_u32 v224, v220, 6, 2
	v_lshlrev_b32_e32 v132, 2, v130
	v_and_b32_e32 v136, 0x200, v129
	v_or_b32_e32 v149, 0x10400, v128
	v_lshrrev_b32_e32 v128, 1, v150
	buffer_load_dwordx4 v147, s[20:23], s33 offen lds
	v_or_b32_e32 v159, 0x2000, v147
	s_mov_b32 m0, s69
	v_lshl_or_b32 v148, v224, 5, v132
	v_mad_u64_u32 v[134:135], s[6:7], v128, s60, v[136:137]
	buffer_load_dwordx4 v159, s[20:23], s33 offen lds
	v_or_b32_e32 v160, 0x4000, v147
	s_mov_b32 m0, s70
	v_lshrrev_b32_e32 v128, 2, v225
	v_lshlrev_b32_e32 v135, 1, v148
	buffer_load_dwordx4 v160, s[20:23], s33 offen lds
	v_or_b32_e32 v161, 0x6000, v147
	s_mov_b32 m0, s71
	v_mul_lo_u32 v128, v128, s60
	v_or_b32_e32 v137, 0x100, v135
	buffer_load_dwordx4 v161, s[20:23], s33 offen lds
	v_lshrrev_b32_e32 v130, 1, v225
	v_add3_u32 v162, v149, v128, v148
	s_waitcnt vmcnt(0)
	s_barrier
	ds_read2_b32 v[128:129], v162 offset1:4
	v_mad_u64_u32 v[138:139], s[6:7], v130, s60, v[136:137]
	v_add_u32_e32 v166, v138, v135
	ds_read_b64 v[130:131], v166
	s_waitcnt lgkmcnt(1)
	v_lshlrev_b32_e32 v132, 24, v128
	v_ashrrev_i32_e32 v132, 16, v132
	v_or_b32_e32 v163, 32, v135
	v_add_u32_e32 v167, v138, v163
	s_waitcnt lgkmcnt(0)
	v_lshl_add_u32 v144, v130, 16, v132
	v_and_b32_e32 v130, 0xffff0000, v130
	v_and_b32_sdwa v132, sext(v128), s74 dst_sel:DWORD dst_unused:UNUSED_PAD src0_sel:WORD_0 src1_sel:DWORD
	v_add_u32_e32 v132, v132, v130
	v_bfe_i32 v130, v128, 8, 16
	v_add_u32_e32 v151, v134, v137
	v_add_u32_e32 v186, v138, v137
	ds_read_b64 v[140:141], v167
	ds_read_b64 v[142:143], v186
	ds_read_b64 v[188:189], v151
	v_and_b32_e32 v130, 0xffffff00, v130
	v_lshl_add_u32 v133, v131, 16, v130
	v_and_b32_e32 v130, 0xffff0000, v131
	v_and_b32_sdwa v128, sext(v128), s74 dst_sel:DWORD dst_unused:UNUSED_PAD src0_sel:WORD_1 src1_sel:DWORD
	v_add_u32_e32 v145, v128, v130
	v_mov_b32_e32 v130, v125
	v_mov_b32_e32 v131, v126
	v_mov_b32_e32 v125, v127
	v_pk_fma_f32 v[132:133], v[132:133], s[26:27], v[130:131] op_sel_hi:[1,0,1]
	v_pk_fma_f32 v[130:131], v[144:145], s[26:27], v[124:125] op_sel_hi:[1,0,1]
	s_waitcnt lgkmcnt(2)
	v_and_b32_e32 v125, 0xffff0000, v140
	v_and_b32_sdwa v126, sext(v129), s74 dst_sel:DWORD dst_unused:UNUSED_PAD src0_sel:WORD_0 src1_sel:DWORD
	v_lshlrev_b32_e32 v124, 24, v129
	v_add_u32_e32 v126, v126, v125
	v_bfe_i32 v125, v129, 8, 16
	v_ashrrev_i32_e32 v124, 16, v124
	v_and_b32_e32 v125, 0xffffff00, v125
	v_lshl_add_u32 v124, v140, 16, v124
	v_lshl_add_u32 v127, v141, 16, v125
	v_and_b32_e32 v125, 0xffff0000, v141
	ds_read2_b32 v[140:141], v162 offset0:32 offset1:36
	v_and_b32_sdwa v128, sext(v129), s74 dst_sel:DWORD dst_unused:UNUSED_PAD src0_sel:WORD_1 src1_sel:DWORD
	v_add_u32_e32 v125, v128, v125
	v_mov_b32_e32 v128, v117
	v_mov_b32_e32 v129, v118
	v_mov_b32_e32 v117, v119
	v_pk_fma_f32 v[128:129], v[126:127], s[26:27], v[128:129] op_sel_hi:[1,0,1]
	v_pk_fma_f32 v[126:127], v[124:125], s[26:27], v[116:117] op_sel_hi:[1,0,1]
	s_waitcnt lgkmcnt(2)
	v_and_b32_e32 v117, 0xffff0000, v142
	s_waitcnt lgkmcnt(0)
	v_and_b32_sdwa v118, sext(v140), s74 dst_sel:DWORD dst_unused:UNUSED_PAD src0_sel:WORD_0 src1_sel:DWORD
	v_add_u32_e32 v118, v118, v117
	v_bfe_i32 v117, v140, 8, 16
	v_lshlrev_b32_e32 v116, 24, v140
	v_and_b32_e32 v117, 0xffffff00, v117
	v_ashrrev_i32_e32 v116, 16, v116
	v_lshl_add_u32 v119, v143, 16, v117
	v_and_b32_e32 v117, 0xffff0000, v143
	v_and_b32_sdwa v124, sext(v140), s74 dst_sel:DWORD dst_unused:UNUSED_PAD src0_sel:WORD_1 src1_sel:DWORD
	v_or_b32_e32 v140, 0x120, v135
	v_lshl_add_u32 v116, v142, 16, v116
	v_add_u32_e32 v117, v124, v117
	v_mov_b32_e32 v124, v121
	v_mov_b32_e32 v125, v122
	v_mov_b32_e32 v121, v123
	v_add_u32_e32 v144, v138, v140
	v_pk_fma_f32 v[124:125], v[118:119], s[26:27], v[124:125] op_sel_hi:[1,0,1]
	v_pk_fma_f32 v[118:119], v[116:117], s[26:27], v[120:121] op_sel_hi:[1,0,1]
	ds_read_b64 v[116:117], v144
	v_lshlrev_b32_e32 v120, 24, v141
	v_or_b32_e32 v145, 16, v225
	v_ashrrev_i32_e32 v138, 16, v120
	v_lshrrev_b32_e32 v120, 1, v145
	v_mad_u64_u32 v[120:121], s[6:7], v120, s60, v[136:137]
	s_waitcnt lgkmcnt(0)
; #define BAR __builtin_amdgcn_s_barrier()
;     ...
;         _Pragma("unroll") for (int ai = 0; ai < 2; ++ai) {
;           const int rbase = brow + ai * HALF;
;           const int hso = ((rbase + 16 * wave) * DM + pn * BM) * 2;
;           const int lso = (rbase + 16 * wave) * DM + pn * BM;
;           _Pragma("unroll") for (int i = 0; i < 8; ++i)
;             __builtin_amdgcn_raw_ptr_buffer_load_lds(rsXB, (__attribute__((address_space(3))) void*)(smem + (wave * 8 + i) * PIECE), 16,
;                                                      hvo + i * (2 * DM * 2), hso, 0, 0);
;           _Pragma("unroll") for (int i = 0; i < 4; ++i)
;             __builtin_amdgcn_raw_ptr_buffer_load_lds(rsLO, (__attribute__((address_space(3))) void*)(smem + LOBASE + (wave * 4 + i) * PIECE), 16,
;                                                      lvo + i * (4 * DM), lso, 0, 0);
;           WAIT_V(0); BAR;
;           _Pragma("unroll") for (int m = 0; m < 4; ++m) _Pragma("unroll") for (int bj = 0; bj < 2; ++bj) _Pragma("unroll") for (int n = 0; n < 2; ++n) {
;             const int rr = wr * 64 + m * 16 + fr;
;             const int cc = bj * HALF + wc * 32 + n * 16 + fq * 4;
;             const u32x2 hv = *reinterpret_cast<const u32x2*>(smem + (rr >> 1) * PIECE + (rr & 1) * 512 + cc * 2);
;             const unsigned lv = *reinterpret_cast<const unsigned*>(smem + LOBASE + (rr >> 2) * PIECE + (rr & 3) * 256 + cc);
;             float x0 = __int_as_float((int)(hv[0] << 16) + (((int)(lv << 24)) >> 24) * 256);
;             float x1 = __int_as_float((int)(hv[0] & 0xffff0000u) + (((int)(lv << 16)) >> 24) * 256);
;             float x2 = __int_as_float((int)(hv[1] << 16) + (((int)(lv << 8)) >> 24) * 256);
;             float x3 = __int_as_float((int)(hv[1] & 0xffff0000u) + (((int)lv) >> 24) * 256);
;             acc[ai][bj][m][n][0] = ALPHA * x0 + sc * acc[ai][bj][m][n][0];
;             acc[ai][bj][m][n][1] = ALPHA * x1 + sc * acc[ai][bj][m][n][1];
;             acc[ai][bj][m][n][2] = ALPHA * x2 + sc * acc[ai][bj][m][n][2];
;             acc[ai][bj][m][n][3] = ALPHA * x3 + sc * acc[ai][bj][m][n][3];
;           }
;           WAIT_L(0); BAR;
;         }
;       }
;       float* red = reinterpret_cast<float*>(smem + 8 * HTB);
;       const int bp16 = (lane ^ 16) << 2, bp32 = (lane ^ 32) << 2;
;       float* red2 = red + 4 * 256 * 2;
;       float* mr = red2 + 2 * 256 * 2;
	v_lshl_add_u32 v138, v116, 16, v138
	v_and_b32_e32 v116, 0xffff0000, v116
	v_and_b32_sdwa v121, sext(v141), s74 dst_sel:DWORD dst_unused:UNUSED_PAD src0_sel:WORD_0 src1_sel:DWORD
	v_add_u32_e32 v142, v121, v116
	v_bfe_i32 v116, v141, 8, 16
	v_and_b32_e32 v116, 0xffffff00, v116
	v_lshl_add_u32 v143, v117, 16, v116
	v_and_b32_e32 v116, 0xffff0000, v117
	v_and_b32_sdwa v117, sext(v141), s74 dst_sel:DWORD dst_unused:UNUSED_PAD src0_sel:WORD_1 src1_sel:DWORD
	v_add_u32_e32 v139, v117, v116
	v_mov_b32_e32 v117, v114
	v_lshrrev_b32_e32 v114, 2, v145
	v_add_u32_e32 v164, v120, v135
	v_add_u32_e32 v165, v120, v163
	v_add_u32_e32 v168, v120, v137
	v_mul_lo_u32 v114, v114, s60
	v_add_u32_e32 v170, v120, v140
	v_or_b32_e32 v120, 32, v225
	v_add3_u32 v145, v149, v114, v148
	v_lshrrev_b32_e32 v114, 1, v120
	v_mov_b32_e32 v116, v113
	v_mov_b32_e32 v113, v115
	v_mad_u64_u32 v[114:115], s[6:7], v114, s60, v[136:137]
	v_lshrrev_b32_e32 v115, 2, v120
	v_add_u32_e32 v187, v114, v135
	v_add_u32_e32 v191, v114, v163
	v_add_u32_e32 v192, v114, v137
	v_add_u32_e32 v222, v114, v140
	v_lshrrev_b32_e32 v114, 2, v150
	v_mul_lo_u32 v115, v115, s60
	v_mul_lo_u32 v114, v114, s60
	s_add_i32 s30, s33, 0x40000
	v_add3_u32 v190, v149, v115, v148
	v_add_u32_e32 v226, v134, v135
	v_add3_u32 v135, v149, v114, v148
	s_lshl_b32 s0, s30, 1
	s_mov_b32 m0, s59
	ds_read_b64 v[122:123], v164
	ds_read_b64 v[210:211], v165
	ds_read_b64 v[206:207], v168
	v_pk_fma_f32 v[116:117], v[142:143], s[26:27], v[116:117] op_sel_hi:[1,0,1]
	v_pk_fma_f32 v[112:113], v[138:139], s[26:27], v[112:113] op_sel_hi:[1,0,1]
	ds_read2_b32 v[212:213], v145 offset1:4
	ds_read2_b32 v[138:139], v145 offset0:32 offset1:36
	ds_read2_b32 v[202:203], v190 offset1:4
	ds_read_b64 v[208:209], v170
	ds_read_b64 v[136:137], v187
	ds_read_b64 v[204:205], v191
	ds_read_b64 v[200:201], v192
	ds_read2_b32 v[142:143], v190 offset0:32 offset1:36
	ds_read2_b32 v[114:115], v135 offset1:4
	v_add_u32_e32 v227, v134, v163
	ds_read2_b32 v[194:195], v135 offset0:32 offset1:36
	v_add_u32_e32 v228, v134, v140
	ds_read_b64 v[198:199], v222
	ds_read_b64 v[140:141], v226
	ds_read_b64 v[120:121], v227
	ds_read_b64 v[196:197], v228
	s_waitcnt lgkmcnt(0)
	s_barrier
	buffer_load_dwordx4 v146, s[16:19], s0 offen lds
	s_mov_b32 m0, s61
	v_add_f32_e32 v134, 0, v130
	buffer_load_dwordx4 v152, s[16:19], s0 offen lds
	s_mov_b32 m0, s62
	v_add_f32_e32 v150, v134, v132
	buffer_load_dwordx4 v153, s[16:19], s0 offen lds
	s_mov_b32 m0, s63
	v_add_f32_e32 v150, v133, v150
	buffer_load_dwordx4 v154, s[16:19], s0 offen lds
	s_mov_b32 m0, s64
	v_add_f32_e32 v153, v131, v150
	buffer_load_dwordx4 v155, s[16:19], s0 offen lds
	s_mov_b32 m0, s65
	v_mul_f32_e32 v152, v133, v133
	buffer_load_dwordx4 v156, s[16:19], s0 offen lds
	s_mov_b32 m0, s66
	v_mov_b32_e32 v150, v131
	buffer_load_dwordx4 v157, s[16:19], s0 offen lds
	s_mov_b32 m0, s67
	v_mul_f32_e32 v154, v112, v112
	buffer_load_dwordx4 v158, s[16:19], s0 offen lds
	s_mov_b32 m0, s68
	v_lshlrev_b32_e32 v229, 2, v223
	buffer_load_dwordx4 v147, s[20:23], s30 offen lds
	s_mov_b32 m0, s69
	v_xor_b32_e32 v221, 64, v229
	buffer_load_dwordx4 v159, s[20:23], s30 offen lds
	s_mov_b32 m0, s70
	v_lshlrev_b32_e32 v224, 9, v224
	buffer_load_dwordx4 v160, s[20:23], s30 offen lds
	s_mov_b32 m0, s71
	v_cmp_gt_u32_e32 vcc, 16, v223
	buffer_load_dwordx4 v161, s[20:23], s30 offen lds
	s_waitcnt vmcnt(0)
	s_barrier
	ds_read2_b32 v[184:185], v162 offset1:4
	ds_read2_b32 v[180:181], v162 offset0:32 offset1:36
	ds_read2_b32 v[174:175], v145 offset1:4
	ds_read_b64 v[182:183], v144
	ds_read_b64 v[178:179], v164
	ds_read_b64 v[176:177], v165
	ds_read_b64 v[172:173], v168
	ds_read2_b32 v[168:169], v145 offset0:32 offset1:36
	ds_read2_b32 v[160:161], v190 offset1:4
	ds_read_b64 v[170:171], v170
	ds_read_b64 v[164:165], v187
	ds_read_b64 v[162:163], v191
	ds_read_b64 v[158:159], v192
	ds_read2_b32 v[156:157], v190 offset0:32 offset1:36
	ds_read2_b32 v[148:149], v135 offset1:4
	ds_read_b64 v[192:193], v166
	ds_read_b64 v[190:191], v167
	ds_read_b64 v[186:187], v186
	ds_read_b64 v[146:147], v151
	ds_read2_b32 v[144:145], v135 offset0:32 offset1:36
	v_pk_mul_f32 v[134:135], v[132:133], v[132:133]
	v_mov_b32_e32 v151, v133
	v_pk_fma_f32 v[134:135], v[130:131], v[130:131], v[134:135]
	v_lshlrev_b32_e32 v223, 3, v225
	v_pk_add_f32 v[134:135], v[152:153], v[134:135] op_sel_hi:[0,1]
	v_pk_fma_f32 v[134:135], v[150:151], v[150:151], v[134:135]
	v_add_f32_e32 v150, v126, v153
	v_add_f32_e32 v153, v128, v150
	v_mul_f32_e32 v152, v126, v126
	v_mov_b32_e32 v150, v128
	v_mov_b32_e32 v151, v126
	v_pk_add_f32 v[134:135], v[152:153], v[134:135] op_sel_hi:[0,1]
	v_pk_fma_f32 v[134:135], v[150:151], v[150:151], v[134:135]
	v_add_f32_e32 v150, v129, v153
	v_add_f32_e32 v153, v127, v150
	v_mul_f32_e32 v152, v129, v129
	v_mov_b32_e32 v150, v127
	v_mov_b32_e32 v151, v129
	v_pk_add_f32 v[134:135], v[152:153], v[134:135] op_sel_hi:[0,1]
	v_pk_fma_f32 v[134:135], v[150:151], v[150:151], v[134:135]
	v_add_f32_e32 v150, v118, v153
	v_add_f32_e32 v153, v124, v150
	v_mul_f32_e32 v152, v118, v118
	v_mov_b32_e32 v150, v124
	v_mov_b32_e32 v151, v118
	v_pk_add_f32 v[134:135], v[152:153], v[134:135] op_sel_hi:[0,1]
	v_pk_fma_f32 v[134:135], v[150:151], v[150:151], v[134:135]
	v_add_f32_e32 v150, v125, v153
	v_add_f32_e32 v153, v119, v150
	v_mul_f32_e32 v152, v125, v125
	v_mov_b32_e32 v150, v119
	v_mov_b32_e32 v151, v125
	v_pk_add_f32 v[134:135], v[152:153], v[134:135] op_sel_hi:[0,1]
	v_pk_fma_f32 v[134:135], v[150:151], v[150:151], v[134:135]
	v_add_f32_e32 v150, v112, v153
	v_mov_b32_e32 v152, v116
	v_mov_b32_e32 v153, v112
	v_pk_add_f32 v[134:135], v[154:155], v[134:135] op_sel_hi:[0,1]
	v_pk_fma_f32 v[134:135], v[152:153], v[152:153], v[134:135]
	v_pk_mul_f32 v[152:153], v[116:117], v[116:117]
	v_add_f32_e32 v150, v116, v150
	v_pk_mul_f32 v[154:155], v[112:113], v[112:113]
	v_pk_mov_b32 v[134:135], v[116:117], v[134:135] op_sel:[1,0]
	v_mov_b32_e32 v151, v153
	v_pk_add_f32 v[134:135], v[134:135], v[150:151]
	v_mov_b32_e32 v154, v113
	v_pk_add_f32 v[134:135], v[154:155], v[134:135]
	ds_bpermute_b32 v214, v221, v134
	ds_bpermute_b32 v215, v221, v135
	ds_read_b64 v[166:167], v222
	ds_read_b64 v[154:155], v226
	ds_read_b64 v[152:153], v227
	ds_read_b64 v[150:151], v228
	v_xor_b32_e32 v222, 0x80, v229
	s_waitcnt lgkmcnt(0)
	v_lshlrev_b32_e32 v224, 2, v224
	v_pk_add_f32 v[134:135], v[134:135], v[214:215]
	ds_bpermute_b32 v214, v222, v134
	ds_bpermute_b32 v215, v222, v135
	s_barrier
	s_and_saveexec_b64 s[6:7], vcc
	s_cbranch_execz .LBB0_664
	v_add3_u32 v225, v223, v224, s19
	s_waitcnt lgkmcnt(0)
	v_pk_add_f32 v[134:135], v[134:135], v[214:215]
	s_waitcnt vmcnt(0)
	ds_write_b64 v225, v[134:135]

; #define STAGE(P, RS, SOFF, OFF, kt) do { const int _so = (SOFF) + (kt) * (BK * 2); \
;     _Pragma("unroll") for (int _i = 0; _i < 2; ++_i) { \
;       __builtin_amdgcn_raw_ptr_buffer_load_lds(RS, (__attribute__((address_space(3))) void*)((P) + wave * 1024 + _i * 8192), 16, OFF[_i], _so, 0, 0); } } while (0)
; #define LDA(dst, b, h) _Pragma("unroll") for (int m = 0; m < 4; ++m) _Pragma("unroll") for (int k = 0; k < 2; ++k) \
;     dst[m][k] = *reinterpret_cast<const bf16x8*>(SA(b, h) + lds_byte(wr * 64 + m * 16 + fr, k * 32 + fq * 8))
; #define LDB(dst, b, h) _Pragma("unroll") for (int n = 0; n < 2; ++n) _Pragma("unroll") for (int k = 0; k < 2; ++k) \
;     dst[n][k] = *reinterpret_cast<const bf16x8*>(SB(b, h) + lds_byte(wc * 32 + n * 16 + fr, k * 32 + fq * 8))
; #define WAIT_V(n) asm volatile("s_waitcnt vmcnt(" #n ")" ::: "memory")
; #define WAIT_L(n) asm volatile("s_waitcnt lgkmcnt(" #n ")" ::: "memory")
; #define BAR __builtin_amdgcn_s_barrier()
; #define SCHED __builtin_amdgcn_sched_barrier(0)
;     ...
;     for (int t = 0; t < nt - 2; t += 2) {
;       LDB(B0, 0, 0); SCHED; LDA(At, 0, 0); STAGE(SA(1, 1), rsA, sA1, offA, t + 1);
;       WAIT_L(8); BAR; WAIT_L(0); MMA(0, 0, At, B0); BAR; SCHED;
;       LDB(B1, 0, 1); STAGE(SB(0, 0), rsB, sB0, offB, t + 2);
;       BAR; WAIT_L(0); MMA(0, 1, At, B1); BAR;
;       LDA(At, 0, 1); STAGE(SA(0, 0), rsA, sA0, offA, t + 2);
;       BAR; WAIT_L(0); MMA(1, 0, At, B0); BAR; SCHED;
;       STAGE(SB(0, 1), rsB, sB1, offB, t + 2);
;       WAIT_V(6); BAR; MMA(1, 1, At, B1); BAR;
.LBB0_757:
	ds_read_b128 v[152:155], v147
	ds_read_b128 v[156:159], v148
	ds_read_b128 v[160:163], v149
	ds_read_b128 v[164:167], v150
	s_add_i32 s6, s85, s5
	s_add_i32 s7, s6, 0x80
	s_mov_b32 m0, s39
	ds_read_b128 v[168:171], v129
	ds_read_b128 v[172:175], v129 offset:1024
	ds_read_b128 v[176:179], v132
	ds_read_b128 v[180:183], v132 offset:1024
	ds_read_b128 v[184:187], v131
	ds_read_b128 v[188:191], v131 offset:1024
	ds_read_b128 v[192:195], v130
	ds_read_b128 v[196:199], v130 offset:1024
	buffer_load_dwordx4 v141, s[8:11], s7 offen lds
	s_mov_b32 m0, s56
	s_nop 0
	buffer_load_dwordx4 v142, s[8:11], s7 offen lds
	s_waitcnt lgkmcnt(8)
	s_barrier
	s_waitcnt lgkmcnt(0)
	v_mfma_f32_16x16x32_bf16 v[124:127], v[152:155], v[168:171], v[124:127]
	v_mfma_f32_16x16x32_bf16 v[120:123], v[160:163], v[168:171], v[120:123]
	v_mfma_f32_16x16x32_bf16 v[116:119], v[152:155], v[176:179], v[116:119]
	v_mfma_f32_16x16x32_bf16 v[112:115], v[160:163], v[176:179], v[112:115]
	v_mfma_f32_16x16x32_bf16 v[108:111], v[152:155], v[184:187], v[108:111]
	v_mfma_f32_16x16x32_bf16 v[104:107], v[160:163], v[184:187], v[104:107]
	v_mfma_f32_16x16x32_bf16 v[100:103], v[152:155], v[192:195], v[100:103]
	v_mfma_f32_16x16x32_bf16 v[96:99], v[160:163], v[192:195], v[96:99]
	v_mfma_f32_16x16x32_bf16 v[124:127], v[156:159], v[172:175], v[124:127]
	v_mfma_f32_16x16x32_bf16 v[120:123], v[164:167], v[172:175], v[120:123]
	v_mfma_f32_16x16x32_bf16 v[116:119], v[156:159], v[180:183], v[116:119]
	v_mfma_f32_16x16x32_bf16 v[112:115], v[164:167], v[180:183], v[112:115]
	v_mfma_f32_16x16x32_bf16 v[108:111], v[156:159], v[188:191], v[108:111]
	v_mfma_f32_16x16x32_bf16 v[104:107], v[164:167], v[188:191], v[104:107]
	v_mfma_f32_16x16x32_bf16 v[100:103], v[156:159], v[196:199], v[100:103]
	v_mfma_f32_16x16x32_bf16 v[96:99], v[164:167], v[196:199], v[96:99]
	s_barrier
	s_add_i32 s7, s87, s5
	s_add_i32 s23, s7, 0x100
	s_mov_b32 s14, s10
	s_mov_b32 s15, s11
	s_mov_b32 m0, s42
	ds_read_b128 v[200:203], v143
	ds_read_b128 v[204:207], v144
	ds_read_b128 v[208:211], v145
	ds_read_b128 v[212:215], v146
	buffer_load_dwordx4 v141, s[12:15], s23 offen lds
	s_mov_b32 m0, s49
	s_nop 0
	buffer_load_dwordx4 v142, s[12:15], s23 offen lds
	s_barrier
	s_waitcnt lgkmcnt(0)
	v_mfma_f32_16x16x32_bf16 v[92:95], v[200:203], v[168:171], v[92:95]
	v_mfma_f32_16x16x32_bf16 v[88:91], v[208:211], v[168:171], v[88:91]
	v_mfma_f32_16x16x32_bf16 v[80:83], v[200:203], v[176:179], v[80:83]
	v_mfma_f32_16x16x32_bf16 v[68:71], v[208:211], v[176:179], v[68:71]
	v_mfma_f32_16x16x32_bf16 v[60:63], v[200:203], v[184:187], v[60:63]
	v_mfma_f32_16x16x32_bf16 v[56:59], v[208:211], v[184:187], v[56:59]
	v_mfma_f32_16x16x32_bf16 v[52:55], v[200:203], v[192:195], v[52:55]
	v_mfma_f32_16x16x32_bf16 v[48:51], v[208:211], v[192:195], v[48:51]
	v_mfma_f32_16x16x32_bf16 v[92:95], v[204:207], v[172:175], v[92:95]
	v_mfma_f32_16x16x32_bf16 v[88:91], v[212:215], v[172:175], v[88:91]
	v_mfma_f32_16x16x32_bf16 v[80:83], v[204:207], v[180:183], v[80:83]
	v_mfma_f32_16x16x32_bf16 v[68:71], v[212:215], v[180:183], v[68:71]
	v_mfma_f32_16x16x32_bf16 v[60:63], v[204:207], v[188:191], v[60:63]
	v_mfma_f32_16x16x32_bf16 v[56:59], v[212:215], v[188:191], v[56:59]
	v_mfma_f32_16x16x32_bf16 v[52:55], v[204:207], v[196:199], v[52:55]
	v_mfma_f32_16x16x32_bf16 v[48:51], v[212:215], v[196:199], v[48:51]
	s_add_i32 s23, s86, s5
	s_add_i32 s26, s23, 0x100
	s_mov_b32 m0, s33
	s_barrier
	ds_read_b128 v[168:171], v129 offset:16384
	ds_read_b128 v[172:175], v129 offset:17408
	ds_read_b128 v[176:179], v132 offset:16384
	ds_read_b128 v[180:183], v132 offset:17408
	ds_read_b128 v[184:187], v131 offset:16384
	ds_read_b128 v[188:191], v131 offset:17408
	ds_read_b128 v[192:195], v130 offset:16384
	ds_read_b128 v[196:199], v130 offset:17408
	buffer_load_dwordx4 v141, s[8:11], s26 offen lds
	s_mov_b32 m0, s50
	s_nop 0
	buffer_load_dwordx4 v142, s[8:11], s26 offen lds
	s_barrier
	s_waitcnt lgkmcnt(0)
	v_mfma_f32_16x16x32_bf16 v[44:47], v[152:155], v[168:171], v[44:47]
	v_mfma_f32_16x16x32_bf16 v[40:43], v[160:163], v[168:171], v[40:43]
	v_mfma_f32_16x16x32_bf16 v[36:39], v[152:155], v[176:179], v[36:39]
	v_mfma_f32_16x16x32_bf16 v[32:35], v[160:163], v[176:179], v[32:35]
	v_mfma_f32_16x16x32_bf16 v[28:31], v[152:155], v[184:187], v[28:31]
	v_mfma_f32_16x16x32_bf16 v[24:27], v[160:163], v[184:187], v[24:27]
	v_mfma_f32_16x16x32_bf16 v[20:23], v[152:155], v[192:195], v[20:23]
	v_mfma_f32_16x16x32_bf16 v[16:19], v[160:163], v[192:195], v[16:19]
	v_mfma_f32_16x16x32_bf16 v[44:47], v[156:159], v[172:175], v[44:47]
	v_mfma_f32_16x16x32_bf16 v[40:43], v[164:167], v[172:175], v[40:43]
	v_mfma_f32_16x16x32_bf16 v[36:39], v[156:159], v[180:183], v[36:39]
	v_mfma_f32_16x16x32_bf16 v[32:35], v[164:167], v[180:183], v[32:35]
	v_mfma_f32_16x16x32_bf16 v[28:31], v[156:159], v[188:191], v[28:31]
	v_mfma_f32_16x16x32_bf16 v[24:27], v[164:167], v[188:191], v[24:27]
	v_mfma_f32_16x16x32_bf16 v[20:23], v[156:159], v[196:199], v[20:23]
	v_mfma_f32_16x16x32_bf16 v[16:19], v[164:167], v[196:199], v[16:19]
	s_barrier
	s_add_i32 s26, s90, s5
	s_add_i32 s27, s26, 0x100
	s_mov_b32 m0, s43
	s_nop 0
	buffer_load_dwordx4 v141, s[12:15], s27 offen lds
	s_mov_b32 m0, s51
	s_nop 0
	buffer_load_dwordx4 v142, s[12:15], s27 offen lds
	s_waitcnt vmcnt(6)
	s_barrier
; #define STAGE(P, RS, SOFF, OFF, kt) do { const int _so = (SOFF) + (kt) * (BK * 2); \
;     _Pragma("unroll") for (int _i = 0; _i < 2; ++_i) { \
;       __builtin_amdgcn_raw_ptr_buffer_load_lds(RS, (__attribute__((address_space(3))) void*)((P) + wave * 1024 + _i * 8192), 16, OFF[_i], _so, 0, 0); } } while (0)
; #define LDA(dst, b, h) _Pragma("unroll") for (int m = 0; m < 4; ++m) _Pragma("unroll") for (int k = 0; k < 2; ++k) \
;     dst[m][k] = *reinterpret_cast<const bf16x8*>(SA(b, h) + lds_byte(wr * 64 + m * 16 + fr, k * 32 + fq * 8))
; #define LDB(dst, b, h) _Pragma("unroll") for (int n = 0; n < 2; ++n) _Pragma("unroll") for (int k = 0; k < 2; ++k) \
;     dst[n][k] = *reinterpret_cast<const bf16x8*>(SB(b, h) + lds_byte(wc * 32 + n * 16 + fr, k * 32 + fq * 8))
; #define WAIT_V(n) asm volatile("s_waitcnt vmcnt(" #n ")" ::: "memory")
; #define WAIT_L(n) asm volatile("s_waitcnt lgkmcnt(" #n ")" ::: "memory")
; #define BAR __builtin_amdgcn_s_barrier()
; #define SCHED __builtin_amdgcn_sched_barrier(0)
;     ...
;       WAIT_V(6); BAR; MMA(1, 1, At, B1); BAR;
;       LDB(B0, 1, 0); SCHED; LDA(At, 1, 0); STAGE(SA(0, 1), rsA, sA1, offA, t + 2);
;       WAIT_L(8); BAR; WAIT_L(0); MMA(0, 0, At, B0); BAR; SCHED;
;       LDB(B1, 1, 1); STAGE(SB(1, 0), rsB, sB0, offB, t + 3);
;       BAR; WAIT_L(0); MMA(0, 1, At, B1); BAR;
;       LDA(At, 1, 1); STAGE(SA(1, 0), rsA, sA0, offA, t + 3);
;       BAR; WAIT_L(0); MMA(1, 0, At, B0); BAR; SCHED;
	v_mfma_f32_16x16x32_bf16 v[12:15], v[200:203], v[168:171], v[12:15]
	v_mfma_f32_16x16x32_bf16 v[8:11], v[208:211], v[168:171], v[8:11]
	v_mfma_f32_16x16x32_bf16 v[4:7], v[200:203], v[176:179], v[4:7]
	v_mfma_f32_16x16x32_bf16 v[0:3], v[208:211], v[176:179], v[0:3]
	v_mfma_f32_16x16x32_bf16 v[64:67], v[200:203], v[184:187], v[64:67]
	v_mfma_f32_16x16x32_bf16 v[72:75], v[208:211], v[184:187], v[72:75]
	v_mfma_f32_16x16x32_bf16 v[76:79], v[200:203], v[192:195], v[76:79]
	v_mfma_f32_16x16x32_bf16 v[84:87], v[208:211], v[192:195], v[84:87]
	v_mfma_f32_16x16x32_bf16 v[12:15], v[204:207], v[172:175], v[12:15]
	v_mfma_f32_16x16x32_bf16 v[8:11], v[212:215], v[172:175], v[8:11]
	v_mfma_f32_16x16x32_bf16 v[4:7], v[204:207], v[180:183], v[4:7]
	v_mfma_f32_16x16x32_bf16 v[0:3], v[212:215], v[180:183], v[0:3]
	v_mfma_f32_16x16x32_bf16 v[64:67], v[204:207], v[188:191], v[64:67]
	v_mfma_f32_16x16x32_bf16 v[72:75], v[212:215], v[188:191], v[72:75]
	v_mfma_f32_16x16x32_bf16 v[76:79], v[204:207], v[196:199], v[76:79]
	v_mfma_f32_16x16x32_bf16 v[84:87], v[212:215], v[196:199], v[84:87]
	s_barrier
	ds_read_b128 v[152:155], v137
	ds_read_b128 v[156:159], v138
	ds_read_b128 v[160:163], v139
	ds_read_b128 v[164:167], v140
	s_addk_i32 s6, 0x100
	s_mov_b32 m0, s44
	ds_read_b128 v[168:171], v129 offset:32768
	ds_read_b128 v[172:175], v129 offset:33792
	ds_read_b128 v[176:179], v132 offset:32768
	ds_read_b128 v[180:183], v132 offset:33792
	ds_read_b128 v[184:187], v131 offset:32768
	ds_read_b128 v[188:191], v131 offset:33792
	ds_read_b128 v[192:195], v130 offset:32768
	ds_read_b128 v[196:199], v130 offset:33792
	buffer_load_dwordx4 v141, s[8:11], s6 offen lds
	s_mov_b32 m0, s52
	s_nop 0
	buffer_load_dwordx4 v142, s[8:11], s6 offen lds
	s_waitcnt lgkmcnt(8)
	s_barrier
	s_waitcnt lgkmcnt(0)
	v_mfma_f32_16x16x32_bf16 v[124:127], v[152:155], v[168:171], v[124:127]
	v_mfma_f32_16x16x32_bf16 v[120:123], v[160:163], v[168:171], v[120:123]
	v_mfma_f32_16x16x32_bf16 v[116:119], v[152:155], v[176:179], v[116:119]
	v_mfma_f32_16x16x32_bf16 v[112:115], v[160:163], v[176:179], v[112:115]
	v_mfma_f32_16x16x32_bf16 v[108:111], v[152:155], v[184:187], v[108:111]
	v_mfma_f32_16x16x32_bf16 v[104:107], v[160:163], v[184:187], v[104:107]
	v_mfma_f32_16x16x32_bf16 v[100:103], v[152:155], v[192:195], v[100:103]
	v_mfma_f32_16x16x32_bf16 v[96:99], v[160:163], v[192:195], v[96:99]
	v_mfma_f32_16x16x32_bf16 v[124:127], v[156:159], v[172:175], v[124:127]
	v_mfma_f32_16x16x32_bf16 v[120:123], v[164:167], v[172:175], v[120:123]
	v_mfma_f32_16x16x32_bf16 v[116:119], v[156:159], v[180:183], v[116:119]
	v_mfma_f32_16x16x32_bf16 v[112:115], v[164:167], v[180:183], v[112:115]
	v_mfma_f32_16x16x32_bf16 v[108:111], v[156:159], v[188:191], v[108:111]
	v_mfma_f32_16x16x32_bf16 v[104:107], v[164:167], v[188:191], v[104:107]
	v_mfma_f32_16x16x32_bf16 v[100:103], v[156:159], v[196:199], v[100:103]
	v_mfma_f32_16x16x32_bf16 v[96:99], v[164:167], v[196:199], v[96:99]
	s_barrier
	s_addk_i32 s7, 0x180
	s_mov_b32 m0, s45
	ds_read_b128 v[200:203], v133
	ds_read_b128 v[204:207], v134
	ds_read_b128 v[208:211], v135
	ds_read_b128 v[212:215], v136
	buffer_load_dwordx4 v141, s[12:15], s7 offen lds
	s_mov_b32 m0, s53
	s_nop 0
	buffer_load_dwordx4 v142, s[12:15], s7 offen lds
	s_barrier
	s_waitcnt lgkmcnt(0)
	v_mfma_f32_16x16x32_bf16 v[92:95], v[200:203], v[168:171], v[92:95]
	v_mfma_f32_16x16x32_bf16 v[88:91], v[208:211], v[168:171], v[88:91]
	v_mfma_f32_16x16x32_bf16 v[80:83], v[200:203], v[176:179], v[80:83]
	v_mfma_f32_16x16x32_bf16 v[68:71], v[208:211], v[176:179], v[68:71]
	v_mfma_f32_16x16x32_bf16 v[60:63], v[200:203], v[184:187], v[60:63]
	v_mfma_f32_16x16x32_bf16 v[56:59], v[208:211], v[184:187], v[56:59]
	v_mfma_f32_16x16x32_bf16 v[52:55], v[200:203], v[192:195], v[52:55]
	v_mfma_f32_16x16x32_bf16 v[48:51], v[208:211], v[192:195], v[48:51]
	v_mfma_f32_16x16x32_bf16 v[92:95], v[204:207], v[172:175], v[92:95]
	v_mfma_f32_16x16x32_bf16 v[88:91], v[212:215], v[172:175], v[88:91]
	v_mfma_f32_16x16x32_bf16 v[80:83], v[204:207], v[180:183], v[80:83]
	v_mfma_f32_16x16x32_bf16 v[68:71], v[212:215], v[180:183], v[68:71]
	v_mfma_f32_16x16x32_bf16 v[60:63], v[204:207], v[188:191], v[60:63]
	v_mfma_f32_16x16x32_bf16 v[56:59], v[212:215], v[188:191], v[56:59]
	v_mfma_f32_16x16x32_bf16 v[52:55], v[204:207], v[196:199], v[52:55]
	v_mfma_f32_16x16x32_bf16 v[48:51], v[212:215], v[196:199], v[48:51]
	s_addk_i32 s23, 0x180
	s_mov_b32 m0, s46
	s_barrier
	ds_read_b128 v[168:171], v129 offset:49152
	ds_read_b128 v[172:175], v129 offset:50176
	ds_read_b128 v[176:179], v132 offset:49152
	ds_read_b128 v[180:183], v132 offset:50176
	ds_read_b128 v[184:187], v131 offset:49152
	ds_read_b128 v[188:191], v131 offset:50176
	ds_read_b128 v[192:195], v130 offset:49152
	ds_read_b128 v[196:199], v130 offset:50176
	buffer_load_dwordx4 v141, s[8:11], s23 offen lds
	s_mov_b32 m0, s54
	s_nop 0
	buffer_load_dwordx4 v142, s[8:11], s23 offen lds
	s_barrier
	s_waitcnt lgkmcnt(0)
	v_mfma_f32_16x16x32_bf16 v[44:47], v[152:155], v[168:171], v[44:47]
	v_mfma_f32_16x16x32_bf16 v[40:43], v[160:163], v[168:171], v[40:43]
	v_mfma_f32_16x16x32_bf16 v[36:39], v[152:155], v[176:179], v[36:39]
	v_mfma_f32_16x16x32_bf16 v[32:35], v[160:163], v[176:179], v[32:35]
	v_mfma_f32_16x16x32_bf16 v[28:31], v[152:155], v[184:187], v[28:31]
	v_mfma_f32_16x16x32_bf16 v[24:27], v[160:163], v[184:187], v[24:27]
	v_mfma_f32_16x16x32_bf16 v[20:23], v[152:155], v[192:195], v[20:23]
	v_mfma_f32_16x16x32_bf16 v[16:19], v[160:163], v[192:195], v[16:19]
	v_mfma_f32_16x16x32_bf16 v[44:47], v[156:159], v[172:175], v[44:47]
	v_mfma_f32_16x16x32_bf16 v[40:43], v[164:167], v[172:175], v[40:43]
	v_mfma_f32_16x16x32_bf16 v[36:39], v[156:159], v[180:183], v[36:39]
	v_mfma_f32_16x16x32_bf16 v[32:35], v[164:167], v[180:183], v[32:35]
	v_mfma_f32_16x16x32_bf16 v[28:31], v[156:159], v[188:191], v[28:31]
	v_mfma_f32_16x16x32_bf16 v[24:27], v[164:167], v[188:191], v[24:27]
	v_mfma_f32_16x16x32_bf16 v[20:23], v[156:159], v[196:199], v[20:23]
	v_mfma_f32_16x16x32_bf16 v[16:19], v[164:167], v[196:199], v[16:19]
	s_barrier
; #define STAGE(P, RS, SOFF, OFF, kt) do { const int _so = (SOFF) + (kt) * (BK * 2); \
;     _Pragma("unroll") for (int _i = 0; _i < 2; ++_i) { \
;       __builtin_amdgcn_raw_ptr_buffer_load_lds(RS, (__attribute__((address_space(3))) void*)((P) + wave * 1024 + _i * 8192), 16, OFF[_i], _so, 0, 0); } } while (0)
; #define LDA(dst, b, h) _Pragma("unroll") for (int m = 0; m < 4; ++m) _Pragma("unroll") for (int k = 0; k < 2; ++k) \
;     dst[m][k] = *reinterpret_cast<const bf16x8*>(SA(b, h) + lds_byte(wr * 64 + m * 16 + fr, k * 32 + fq * 8))
; #define LDB(dst, b, h) _Pragma("unroll") for (int n = 0; n < 2; ++n) _Pragma("unroll") for (int k = 0; k < 2; ++k) \
;     dst[n][k] = *reinterpret_cast<const bf16x8*>(SB(b, h) + lds_byte(wc * 32 + n * 16 + fr, k * 32 + fq * 8))
; #define WAIT_V(n) asm volatile("s_waitcnt vmcnt(" #n ")" ::: "memory")
; #define WAIT_L(n) asm volatile("s_waitcnt lgkmcnt(" #n ")" ::: "memory")
; #define BAR __builtin_amdgcn_s_barrier()
;     ...
;       STAGE(SB(1, 1), rsB, sB1, offB, t + 3);
;       WAIT_V(6); BAR; MMA(1, 1, At, B1); BAR;
;     }
;     { LDB(B0, 0, 0); LDA(At, 0, 0); STAGE(SA(1, 1), rsA, sA1, offA, nt - 1);
;       BAR; WAIT_L(0); MMA(0, 0, At, B0); BAR;
;       LDB(B1, 0, 1); BAR; WAIT_L(0); MMA(0, 1, At, B1); BAR;
;       LDA(At, 0, 1); WAIT_V(4); BAR; WAIT_L(0); MMA(1, 0, At, B0); MMA(1, 1, At, B1); BAR; }
;     { LDB(B0, 1, 0); LDA(At, 1, 0); WAIT_V(2); BAR; WAIT_L(0); MMA(0, 0, At, B0); BAR;
	s_addk_i32 s26, 0x180
	s_mov_b32 m0, s47
	s_nop 0
	buffer_load_dwordx4 v141, s[12:15], s26 offen lds
	s_mov_b32 m0, s55
	s_nop 0
	buffer_load_dwordx4 v142, s[12:15], s26 offen lds
	s_waitcnt vmcnt(6)
	s_barrier
	v_mfma_f32_16x16x32_bf16 v[12:15], v[200:203], v[168:171], v[12:15]
	v_mfma_f32_16x16x32_bf16 v[8:11], v[208:211], v[168:171], v[8:11]
	v_mfma_f32_16x16x32_bf16 v[4:7], v[200:203], v[176:179], v[4:7]
	v_mfma_f32_16x16x32_bf16 v[0:3], v[208:211], v[176:179], v[0:3]
	v_mfma_f32_16x16x32_bf16 v[64:67], v[200:203], v[184:187], v[64:67]
	v_mfma_f32_16x16x32_bf16 v[72:75], v[208:211], v[184:187], v[72:75]
	v_mfma_f32_16x16x32_bf16 v[76:79], v[200:203], v[192:195], v[76:79]
	v_mfma_f32_16x16x32_bf16 v[84:87], v[208:211], v[192:195], v[84:87]
	v_mfma_f32_16x16x32_bf16 v[12:15], v[204:207], v[172:175], v[12:15]
	v_mfma_f32_16x16x32_bf16 v[8:11], v[212:215], v[172:175], v[8:11]
	v_mfma_f32_16x16x32_bf16 v[4:7], v[204:207], v[180:183], v[4:7]
	v_mfma_f32_16x16x32_bf16 v[0:3], v[212:215], v[180:183], v[0:3]
	v_mfma_f32_16x16x32_bf16 v[64:67], v[204:207], v[188:191], v[64:67]
	v_mfma_f32_16x16x32_bf16 v[72:75], v[212:215], v[188:191], v[72:75]
	v_mfma_f32_16x16x32_bf16 v[76:79], v[204:207], v[196:199], v[76:79]
	v_mfma_f32_16x16x32_bf16 v[84:87], v[212:215], v[196:199], v[84:87]
	s_add_i32 s4, s4, 2
	s_addk_i32 s5, 0x100
	s_cmp_gt_u32 s4, 59
	s_barrier
	s_cbranch_scc0 .LBB0_757
	s_add_i32 s4, s85, 0x1f80
	s_mov_b32 m0, s39
	ds_read_b128 v[152:155], v147
	ds_read_b128 v[156:159], v148
	ds_read_b128 v[160:163], v149
	ds_read_b128 v[148:151], v150
	ds_read_b128 v[164:167], v129
	ds_read_b128 v[168:171], v129 offset:1024
	ds_read_b128 v[172:175], v132
	ds_read_b128 v[176:179], v132 offset:1024
	ds_read_b128 v[180:183], v131
	ds_read_b128 v[184:187], v131 offset:1024
	ds_read_b128 v[188:191], v130
	ds_read_b128 v[192:195], v130 offset:1024
	buffer_load_dwordx4 v141, s[8:11], s4 offen lds
	s_mov_b32 m0, s56
	s_nop 0
	buffer_load_dwordx4 v142, s[8:11], s4 offen lds
	s_barrier
	s_waitcnt lgkmcnt(0)
	v_mfma_f32_16x16x32_bf16 v[124:127], v[152:155], v[164:167], v[124:127]
	v_mfma_f32_16x16x32_bf16 v[120:123], v[160:163], v[164:167], v[120:123]
	v_mfma_f32_16x16x32_bf16 v[116:119], v[152:155], v[172:175], v[116:119]
	v_mfma_f32_16x16x32_bf16 v[112:115], v[160:163], v[172:175], v[112:115]
	v_mfma_f32_16x16x32_bf16 v[108:111], v[152:155], v[180:183], v[108:111]
	v_mfma_f32_16x16x32_bf16 v[104:107], v[160:163], v[180:183], v[104:107]
	v_mfma_f32_16x16x32_bf16 v[100:103], v[152:155], v[188:191], v[100:103]
	v_mfma_f32_16x16x32_bf16 v[96:99], v[160:163], v[188:191], v[96:99]
	v_mfma_f32_16x16x32_bf16 v[124:127], v[156:159], v[168:171], v[124:127]
	v_mfma_f32_16x16x32_bf16 v[120:123], v[148:151], v[168:171], v[120:123]
	v_mfma_f32_16x16x32_bf16 v[116:119], v[156:159], v[176:179], v[116:119]
	v_mfma_f32_16x16x32_bf16 v[112:115], v[148:151], v[176:179], v[112:115]
	v_mfma_f32_16x16x32_bf16 v[108:111], v[156:159], v[184:187], v[108:111]
	v_mfma_f32_16x16x32_bf16 v[104:107], v[148:151], v[184:187], v[104:107]
	v_mfma_f32_16x16x32_bf16 v[100:103], v[156:159], v[192:195], v[100:103]
	v_mfma_f32_16x16x32_bf16 v[96:99], v[148:151], v[192:195], v[96:99]
	s_barrier
	ds_read_b128 v[196:199], v143
	ds_read_b128 v[200:203], v144
	ds_read_b128 v[142:145], v145
	ds_read_b128 v[204:207], v146
	s_barrier
	s_waitcnt lgkmcnt(0)
	v_mfma_f32_16x16x32_bf16 v[88:91], v[142:145], v[164:167], v[88:91]
	v_mfma_f32_16x16x32_bf16 v[80:83], v[196:199], v[172:175], v[80:83]
	v_mfma_f32_16x16x32_bf16 v[60:63], v[196:199], v[180:183], v[60:63]
	v_mfma_f32_16x16x32_bf16 v[56:59], v[142:145], v[180:183], v[56:59]
	v_mfma_f32_16x16x32_bf16 v[52:55], v[196:199], v[188:191], v[52:55]
	v_mfma_f32_16x16x32_bf16 v[48:51], v[142:145], v[188:191], v[48:51]
	v_mfma_f32_16x16x32_bf16 v[92:95], v[196:199], v[164:167], v[92:95]
	v_mfma_f32_16x16x32_bf16 v[68:71], v[142:145], v[172:175], v[68:71]
	v_mfma_f32_16x16x32_bf16 v[88:91], v[204:207], v[168:171], v[88:91]
	v_mfma_f32_16x16x32_bf16 v[80:83], v[200:203], v[176:179], v[80:83]
	v_mfma_f32_16x16x32_bf16 v[60:63], v[200:203], v[184:187], v[60:63]
	v_mfma_f32_16x16x32_bf16 v[56:59], v[204:207], v[184:187], v[56:59]
	v_mfma_f32_16x16x32_bf16 v[52:55], v[200:203], v[192:195], v[52:55]
	v_mfma_f32_16x16x32_bf16 v[48:51], v[204:207], v[192:195], v[48:51]
	v_mfma_f32_16x16x32_bf16 v[164:167], v[200:203], v[168:171], v[92:95]
	v_mfma_f32_16x16x32_bf16 v[168:171], v[204:207], v[176:179], v[68:71]
	s_barrier
	s_nop 0
	ds_read_b128 v[68:71], v129 offset:16384
	ds_read_b128 v[92:95], v129 offset:17408
	ds_read_b128 v[172:175], v132 offset:16384
	ds_read_b128 v[176:179], v132 offset:17408
	ds_read_b128 v[180:183], v131 offset:16384
	ds_read_b128 v[184:187], v131 offset:17408
	ds_read_b128 v[188:191], v130 offset:16384
	ds_read_b128 v[192:195], v130 offset:17408
	s_waitcnt vmcnt(4)
	s_barrier
; #define LDA(dst, b, h) _Pragma("unroll") for (int m = 0; m < 4; ++m) _Pragma("unroll") for (int k = 0; k < 2; ++k) \
;     dst[m][k] = *reinterpret_cast<const bf16x8*>(SA(b, h) + lds_byte(wr * 64 + m * 16 + fr, k * 32 + fq * 8))
; #define LDB(dst, b, h) _Pragma("unroll") for (int n = 0; n < 2; ++n) _Pragma("unroll") for (int k = 0; k < 2; ++k) \
;     dst[n][k] = *reinterpret_cast<const bf16x8*>(SB(b, h) + lds_byte(wc * 32 + n * 16 + fr, k * 32 + fq * 8))
; #define WAIT_V(n) asm volatile("s_waitcnt vmcnt(" #n ")" ::: "memory")
; #define WAIT_L(n) asm volatile("s_waitcnt lgkmcnt(" #n ")" ::: "memory")
; #define BAR __builtin_amdgcn_s_barrier()
;     ...
;       LDA(At, 0, 1); WAIT_V(4); BAR; WAIT_L(0); MMA(1, 0, At, B0); MMA(1, 1, At, B1); BAR; }
;     { LDB(B0, 1, 0); LDA(At, 1, 0); WAIT_V(2); BAR; WAIT_L(0); MMA(0, 0, At, B0); BAR;
;       LDB(B1, 1, 1); WAIT_V(0); BAR; WAIT_L(0); MMA(0, 1, At, B1); BAR;
	s_waitcnt lgkmcnt(0)
	v_mfma_f32_16x16x32_bf16 v[44:47], v[152:155], v[68:71], v[44:47]
	v_mfma_f32_16x16x32_bf16 v[40:43], v[160:163], v[68:71], v[40:43]
	v_mfma_f32_16x16x32_bf16 v[36:39], v[152:155], v[172:175], v[36:39]
	v_mfma_f32_16x16x32_bf16 v[32:35], v[160:163], v[172:175], v[32:35]
	v_mfma_f32_16x16x32_bf16 v[28:31], v[152:155], v[180:183], v[28:31]
	v_mfma_f32_16x16x32_bf16 v[24:27], v[160:163], v[180:183], v[24:27]
	v_mfma_f32_16x16x32_bf16 v[20:23], v[152:155], v[188:191], v[20:23]
	v_mfma_f32_16x16x32_bf16 v[16:19], v[160:163], v[188:191], v[16:19]
	v_mfma_f32_16x16x32_bf16 v[44:47], v[156:159], v[92:95], v[44:47]
	v_mfma_f32_16x16x32_bf16 v[40:43], v[148:151], v[92:95], v[40:43]
	v_mfma_f32_16x16x32_bf16 v[36:39], v[156:159], v[176:179], v[36:39]
	v_mfma_f32_16x16x32_bf16 v[32:35], v[148:151], v[176:179], v[32:35]
	v_mfma_f32_16x16x32_bf16 v[28:31], v[156:159], v[184:187], v[28:31]
	v_mfma_f32_16x16x32_bf16 v[24:27], v[148:151], v[184:187], v[24:27]
	v_mfma_f32_16x16x32_bf16 v[20:23], v[156:159], v[192:195], v[20:23]
	v_mfma_f32_16x16x32_bf16 v[16:19], v[148:151], v[192:195], v[16:19]
	v_mfma_f32_16x16x32_bf16 v[4:7], v[196:199], v[172:175], v[4:7]
	v_mfma_f32_16x16x32_bf16 v[0:3], v[142:145], v[172:175], v[0:3]
	v_mfma_f32_16x16x32_bf16 v[12:15], v[196:199], v[68:71], v[12:15]
	v_mfma_f32_16x16x32_bf16 v[8:11], v[142:145], v[68:71], v[8:11]
	v_mfma_f32_16x16x32_bf16 v[64:67], v[196:199], v[180:183], v[64:67]
	v_mfma_f32_16x16x32_bf16 v[68:71], v[142:145], v[180:183], v[72:75]
	v_mfma_f32_16x16x32_bf16 v[72:75], v[196:199], v[188:191], v[76:79]
	v_mfma_f32_16x16x32_bf16 v[76:79], v[142:145], v[188:191], v[84:87]
	v_mfma_f32_16x16x32_bf16 v[4:7], v[200:203], v[176:179], v[4:7]
	v_mfma_f32_16x16x32_bf16 v[0:3], v[204:207], v[176:179], v[0:3]
	v_mfma_f32_16x16x32_bf16 v[142:145], v[200:203], v[92:95], v[12:15]
	v_mfma_f32_16x16x32_bf16 v[146:149], v[204:207], v[92:95], v[8:11]
	v_mfma_f32_16x16x32_bf16 v[150:153], v[200:203], v[184:187], v[64:67]
	v_mfma_f32_16x16x32_bf16 v[154:157], v[204:207], v[184:187], v[68:71]
	v_mfma_f32_16x16x32_bf16 v[158:161], v[200:203], v[192:195], v[72:75]
	v_mfma_f32_16x16x32_bf16 v[172:175], v[204:207], v[192:195], v[76:79]
	s_barrier
	ds_read_b128 v[8:11], v137
	ds_read_b128 v[12:15], v138
	ds_read_b128 v[176:179], v139
	ds_read_b128 v[138:141], v140
	ds_read_b128 v[64:67], v129 offset:32768
	ds_read_b128 v[72:75], v129 offset:33792
	ds_read_b128 v[180:183], v132 offset:32768
	ds_read_b128 v[184:187], v132 offset:33792
	ds_read_b128 v[188:191], v131 offset:32768
	ds_read_b128 v[192:195], v131 offset:33792
	ds_read_b128 v[196:199], v130 offset:32768
	ds_read_b128 v[200:203], v130 offset:33792
	s_waitcnt vmcnt(2)
	s_barrier
	s_waitcnt lgkmcnt(0)
	v_mfma_f32_16x16x32_bf16 v[68:71], v[8:11], v[64:67], v[124:127]
	v_mfma_f32_16x16x32_bf16 v[76:79], v[176:179], v[64:67], v[120:123]
	v_mfma_f32_16x16x32_bf16 v[84:87], v[8:11], v[180:183], v[116:119]
	v_mfma_f32_16x16x32_bf16 v[92:95], v[176:179], v[180:183], v[112:115]
	v_mfma_f32_16x16x32_bf16 v[112:115], v[8:11], v[188:191], v[108:111]
	v_mfma_f32_16x16x32_bf16 v[104:107], v[176:179], v[188:191], v[104:107]
	v_mfma_f32_16x16x32_bf16 v[120:123], v[8:11], v[196:199], v[100:103]
	v_mfma_f32_16x16x32_bf16 v[96:99], v[176:179], v[196:199], v[96:99]
	v_mfma_f32_16x16x32_bf16 v[124:127], v[12:15], v[72:75], v[68:71]
	v_mfma_f32_16x16x32_bf16 v[116:119], v[138:141], v[72:75], v[76:79]
	v_mfma_f32_16x16x32_bf16 v[108:111], v[12:15], v[184:187], v[84:87]
	v_mfma_f32_16x16x32_bf16 v[100:103], v[138:141], v[184:187], v[92:95]
	v_mfma_f32_16x16x32_bf16 v[92:95], v[12:15], v[192:195], v[112:115]
	v_mfma_f32_16x16x32_bf16 v[84:87], v[138:141], v[192:195], v[104:107]
	v_mfma_f32_16x16x32_bf16 v[76:79], v[12:15], v[200:203], v[120:123]
	v_mfma_f32_16x16x32_bf16 v[68:71], v[138:141], v[200:203], v[96:99]
	s_barrier
; #define LDA(dst, b, h) _Pragma("unroll") for (int m = 0; m < 4; ++m) _Pragma("unroll") for (int k = 0; k < 2; ++k) \
;     dst[m][k] = *reinterpret_cast<const bf16x8*>(SA(b, h) + lds_byte(wr * 64 + m * 16 + fr, k * 32 + fq * 8))
; #define LDB(dst, b, h) _Pragma("unroll") for (int n = 0; n < 2; ++n) _Pragma("unroll") for (int k = 0; k < 2; ++k) \
;     dst[n][k] = *reinterpret_cast<const bf16x8*>(SB(b, h) + lds_byte(wc * 32 + n * 16 + fr, k * 32 + fq * 8))
; #define WAIT_V(n) asm volatile("s_waitcnt vmcnt(" #n ")" ::: "memory")
; #define WAIT_L(n) asm volatile("s_waitcnt lgkmcnt(" #n ")" ::: "memory")
; #define BAR __builtin_amdgcn_s_barrier()
;     ...
;     { LDB(B0, 1, 0); LDA(At, 1, 0); WAIT_V(2); BAR; WAIT_L(0); MMA(0, 0, At, B0); BAR;
;       LDB(B1, 1, 1); WAIT_V(0); BAR; WAIT_L(0); MMA(0, 1, At, B1); BAR;
;       LDA(At, 1, 1); BAR; WAIT_L(0); MMA(1, 0, At, B0); MMA(1, 1, At, B1); BAR; }
;     if (wr == 0) BAR;
	ds_read_b128 v[204:207], v133
	ds_read_b128 v[208:211], v134
	ds_read_b128 v[212:215], v135
	ds_read_b128 v[134:137], v136
	s_waitcnt vmcnt(0)
	s_barrier
	s_waitcnt lgkmcnt(0)
	v_mfma_f32_16x16x32_bf16 v[96:99], v[204:207], v[64:67], v[164:167]
	v_mfma_f32_16x16x32_bf16 v[64:67], v[212:215], v[64:67], v[88:91]
	v_mfma_f32_16x16x32_bf16 v[80:83], v[204:207], v[180:183], v[80:83]
	v_mfma_f32_16x16x32_bf16 v[88:91], v[212:215], v[180:183], v[168:171]
	v_mfma_f32_16x16x32_bf16 v[60:63], v[204:207], v[188:191], v[60:63]
	v_mfma_f32_16x16x32_bf16 v[56:59], v[212:215], v[188:191], v[56:59]
	v_mfma_f32_16x16x32_bf16 v[52:55], v[204:207], v[196:199], v[52:55]
	v_mfma_f32_16x16x32_bf16 v[48:51], v[212:215], v[196:199], v[48:51]
	v_mfma_f32_16x16x32_bf16 v[120:123], v[208:211], v[72:75], v[96:99]
	v_mfma_f32_16x16x32_bf16 v[112:115], v[134:137], v[72:75], v[64:67]
	v_mfma_f32_16x16x32_bf16 v[104:107], v[208:211], v[184:187], v[80:83]
	v_mfma_f32_16x16x32_bf16 v[96:99], v[134:137], v[184:187], v[88:91]
	v_mfma_f32_16x16x32_bf16 v[88:91], v[208:211], v[192:195], v[60:63]
	v_mfma_f32_16x16x32_bf16 v[80:83], v[134:137], v[192:195], v[56:59]
	v_mfma_f32_16x16x32_bf16 v[72:75], v[208:211], v[200:203], v[52:55]
	v_mfma_f32_16x16x32_bf16 v[64:67], v[134:137], v[200:203], v[48:51]
	s_barrier
	s_nop 0
	ds_read_b128 v[48:51], v129 offset:49152
	ds_read_b128 v[162:165], v129 offset:50176
	ds_read_b128 v[52:55], v132 offset:49152
	ds_read_b128 v[166:169], v132 offset:50176
	ds_read_b128 v[180:183], v131 offset:49152
	ds_read_b128 v[184:187], v131 offset:50176
	ds_read_b128 v[188:191], v130 offset:49152
	ds_read_b128 v[130:133], v130 offset:50176
	s_barrier
	s_waitcnt lgkmcnt(0)
	v_mfma_f32_16x16x32_bf16 v[44:47], v[8:11], v[48:51], v[44:47]
	v_mfma_f32_16x16x32_bf16 v[40:43], v[176:179], v[48:51], v[40:43]
	v_mfma_f32_16x16x32_bf16 v[36:39], v[8:11], v[52:55], v[36:39]
	v_mfma_f32_16x16x32_bf16 v[32:35], v[176:179], v[52:55], v[32:35]
	v_mfma_f32_16x16x32_bf16 v[28:31], v[8:11], v[180:183], v[28:31]
	v_mfma_f32_16x16x32_bf16 v[24:27], v[176:179], v[180:183], v[24:27]
	v_mfma_f32_16x16x32_bf16 v[8:11], v[8:11], v[188:191], v[20:23]
	v_mfma_f32_16x16x32_bf16 v[16:19], v[176:179], v[188:191], v[16:19]
	v_mfma_f32_16x16x32_bf16 v[60:63], v[12:15], v[162:165], v[44:47]
	v_mfma_f32_16x16x32_bf16 v[56:59], v[138:141], v[162:165], v[40:43]
	v_mfma_f32_16x16x32_bf16 v[44:47], v[12:15], v[166:169], v[36:39]
	v_mfma_f32_16x16x32_bf16 v[40:43], v[138:141], v[166:169], v[32:35]
	v_mfma_f32_16x16x32_bf16 v[28:31], v[12:15], v[184:187], v[28:31]
	v_mfma_f32_16x16x32_bf16 v[24:27], v[138:141], v[184:187], v[24:27]
	v_mfma_f32_16x16x32_bf16 v[12:15], v[12:15], v[130:133], v[8:11]
	v_mfma_f32_16x16x32_bf16 v[8:11], v[138:141], v[130:133], v[16:19]
	v_mfma_f32_16x16x32_bf16 v[16:19], v[204:207], v[48:51], v[142:145]
	v_mfma_f32_16x16x32_bf16 v[20:23], v[212:215], v[48:51], v[146:149]
	v_mfma_f32_16x16x32_bf16 v[4:7], v[204:207], v[52:55], v[4:7]
	v_mfma_f32_16x16x32_bf16 v[0:3], v[212:215], v[52:55], v[0:3]
	v_mfma_f32_16x16x32_bf16 v[138:141], v[204:207], v[180:183], v[150:153]
	v_mfma_f32_16x16x32_bf16 v[142:145], v[212:215], v[180:183], v[154:157]
	v_mfma_f32_16x16x32_bf16 v[146:149], v[204:207], v[188:191], v[158:161]
	v_mfma_f32_16x16x32_bf16 v[150:153], v[212:215], v[188:191], v[172:175]
	v_mfma_f32_16x16x32_bf16 v[52:55], v[208:211], v[162:165], v[16:19]
	v_mfma_f32_16x16x32_bf16 v[48:51], v[134:137], v[162:165], v[20:23]
	v_mfma_f32_16x16x32_bf16 v[36:39], v[208:211], v[166:169], v[4:7]
	v_mfma_f32_16x16x32_bf16 v[32:35], v[134:137], v[166:169], v[0:3]
	v_mfma_f32_16x16x32_bf16 v[20:23], v[208:211], v[184:187], v[138:141]
	v_mfma_f32_16x16x32_bf16 v[16:19], v[134:137], v[184:187], v[142:145]
	v_mfma_f32_16x16x32_bf16 v[4:7], v[208:211], v[130:133], v[146:149]
	v_mfma_f32_16x16x32_bf16 v[0:3], v[134:137], v[130:133], v[150:153]
	v_cmp_gt_u32_e32 vcc, s74, v128
	s_barrier
	s_and_saveexec_b64 s[4:5], vcc
	s_cbranch_execz .LBB0_760
	s_barrier

; #define WAIT_V(n) asm volatile("s_waitcnt vmcnt(" #n ")" ::: "memory")
; #define BAR __builtin_amdgcn_s_barrier()
;     ...
;         constexpr int PIECE = 1024 + 16, LOBASE = 64 * PIECE;
;         const int hvo = (lane >> 5) * (DM * 2) + (lane & 31) * 16;
;         const int lvo = (lane >> 4) * DM + (lane & 15) * 16;
;         _Pragma("unroll") for (int ai = 0; ai < 2; ++ai) {
;           const int rbase = brow + ai * HALF;
;           const int hso = ((rbase + 16 * wave) * DM + pn * BM) * 2;
;           const int lso = (rbase + 16 * wave) * DM + pn * BM;
;           _Pragma("unroll") for (int i = 0; i < 8; ++i)
;             __builtin_amdgcn_raw_ptr_buffer_load_lds(rsXB, (__attribute__((address_space(3))) void*)(smem + (wave * 8 + i) * PIECE), 16,
;                                                      hvo + i * (2 * DM * 2), hso, 0, 0);
;           _Pragma("unroll") for (int i = 0; i < 4; ++i)
;             __builtin_amdgcn_raw_ptr_buffer_load_lds(rsLO, (__attribute__((address_space(3))) void*)(smem + LOBASE + (wave * 4 + i) * PIECE), 16,
;                                                      lvo + i * (4 * DM), lso, 0, 0);
;           WAIT_V(0); BAR;
;           _Pragma("unroll") for (int m = 0; m < 4; ++m) _Pragma("unroll") for (int bj = 0; bj < 2; ++bj) _Pragma("unroll") for (int n = 0; n < 2; ++n) {
;             const int rr = wr * 64 + m * 16 + fr;
;             const int cc = bj * HALF + wc * 32 + n * 16 + fq * 4;
;             const u32x2 hv = *reinterpret_cast<const u32x2*>(smem + (rr >> 1) * PIECE + (rr & 1) * 512 + cc * 2);
;             const unsigned lv = *reinterpret_cast<const unsigned*>(smem + LOBASE + (rr >> 2) * PIECE + (rr & 3) * 256 + cc);
;             float x0 = __int_as_float((int)(hv[0] << 16) + (((int)(lv << 24)) >> 24) * 256);
;             float x1 = __int_as_float((int)(hv[0] & 0xffff0000u) + (((int)(lv << 16)) >> 24) * 256);
;             float x2 = __int_as_float((int)(hv[1] << 16) + (((int)(lv << 8)) >> 24) * 256);
;             float x3 = __int_as_float((int)(hv[1] & 0xffff0000u) + (((int)lv) >> 24) * 256);
;             acc[ai][bj][m][n][0] = ALPHA * x0 + sc * acc[ai][bj][m][n][0];
;             acc[ai][bj][m][n][1] = ALPHA * x1 + sc * acc[ai][bj][m][n][1];
;             acc[ai][bj][m][n][2] = ALPHA * x2 + sc * acc[ai][bj][m][n][2];
;             acc[ai][bj][m][n][3] = ALPHA * x3 + sc * acc[ai][bj][m][n][3];
.LBB0_762:
	s_lshl_b32 s4, s40, 19
	v_mbcnt_lo_u32_b32 v128, -1, 0
	v_mbcnt_hi_u32_b32 v128, -1, v128
	s_lshl_b32 s26, s22, 8
	v_lshlrev_b32_e32 v134, 4, v128
	s_add_i32 s4, s4, s48
	v_lshlrev_b32_e32 v133, 7, v128
	v_and_b32_e32 v134, 0x1f0, v134
	s_add_i32 s4, s4, s26
	s_mov_b32 m0, s57
	v_and_or_b32 v135, v133, s73, v134
	s_lshl_b32 s5, s4, 1
	buffer_load_dwordx4 v135, s[16:19], s5 offen lds
	v_or_b32_e32 v149, 0x2000, v135
	s_mov_b32 m0, s59
	v_or_b32_e32 v150, 0x4000, v135
	buffer_load_dwordx4 v149, s[16:19], s5 offen lds
	s_mov_b32 m0, s60
	v_or_b32_e32 v151, 0x6000, v135
	buffer_load_dwordx4 v150, s[16:19], s5 offen lds
	s_mov_b32 m0, s61
	v_or_b32_e32 v152, 0x8000, v135
	buffer_load_dwordx4 v151, s[16:19], s5 offen lds
	s_mov_b32 m0, s62
	v_or_b32_e32 v153, 0xa000, v135
	buffer_load_dwordx4 v152, s[16:19], s5 offen lds
	s_mov_b32 m0, s63
	v_add_u32_e32 v220, s31, v128
	v_and_b32_e32 v129, 15, v128
	buffer_load_dwordx4 v153, s[16:19], s5 offen lds
	v_or_b32_e32 v155, 0xc000, v135
	s_mov_b32 m0, s64
	v_bfe_u32 v130, v128, 4, 2
	v_ashrrev_i32_e32 v131, 2, v220
	v_lshlrev_b32_e32 v133, 4, v129
	buffer_load_dwordx4 v155, s[16:19], s5 offen lds
	v_or_b32_e32 v156, 0xe000, v135
	s_mov_b32 m0, s65
	v_and_b32_e32 v223, 63, v128
	v_lshl_or_b32 v144, v130, 11, v133
	v_and_or_b32 v225, v131, s3, v129
	v_lshlrev_b32_e32 v129, 9, v128
	v_lshlrev_b32_e32 v128, 8, v128
	buffer_load_dwordx4 v156, s[16:19], s5 offen lds
	s_mov_b32 s22, s18
	s_mov_b32 s23, s19
	s_mov_b32 m0, s66
	v_and_b32_e32 v128, 0x300, v128
	v_or_b32_e32 v147, 48, v225
	buffer_load_dwordx4 v144, s[20:23], s4 offen lds
	v_or_b32_e32 v157, 0x2000, v144
	s_mov_b32 m0, s67
	v_bfe_u32 v224, v220, 6, 2
	v_lshlrev_b32_e32 v132, 2, v130
	v_and_b32_e32 v134, 0x200, v129
	v_or_b32_e32 v146, 0x10400, v128
	v_lshrrev_b32_e32 v128, 1, v147
	buffer_load_dwordx4 v157, s[20:23], s4 offen lds
	v_or_b32_e32 v158, 0x4000, v144
	s_mov_b32 m0, s68
	v_lshrrev_b32_e32 v129, 2, v225
	v_lshl_or_b32 v145, v224, 5, v132
	v_mad_u64_u32 v[132:133], s[6:7], v128, s58, v[134:135]
	buffer_load_dwordx4 v158, s[20:23], s4 offen lds
	v_or_b32_e32 v159, 0x6000, v144
	s_mov_b32 m0, s69
	v_lshrrev_b32_e32 v128, 1, v225
	v_mul_lo_u32 v129, v129, s58
	v_lshlrev_b32_e32 v133, 1, v145
	buffer_load_dwordx4 v159, s[20:23], s4 offen lds
	v_add3_u32 v160, v146, v129, v145
	v_mad_u64_u32 v[138:139], s[6:7], v128, s58, v[134:135]
	s_waitcnt vmcnt(0)
	s_barrier
	ds_read2_b32 v[136:137], v160 offset1:4
	v_add_u32_e32 v176, v138, v133
	ds_read_b64 v[130:131], v176
	v_or_b32_e32 v161, 32, v133
	v_or_b32_e32 v148, 0x100, v133
	s_waitcnt lgkmcnt(1)
	v_lshlrev_b32_e32 v128, 24, v136
	v_ashrrev_i32_e32 v128, 16, v128
	s_waitcnt lgkmcnt(0)
	v_and_b32_e32 v129, 0xffff0000, v130
	v_and_b32_sdwa v139, sext(v136), s75 dst_sel:DWORD dst_unused:UNUSED_PAD src0_sel:WORD_0 src1_sel:DWORD
	v_lshl_add_u32 v128, v130, 16, v128
	v_add_u32_e32 v129, v139, v129
	v_pk_mul_f32 v[128:129], v[128:129], s[30:31] op_sel_hi:[1,0]
	v_add_u32_e32 v177, v138, v161
	v_pk_fma_f32 v[128:129], v[124:125], 0.5, v[128:129] op_sel_hi:[1,0,1]
	v_bfe_i32 v124, v136, 8, 16
	v_and_b32_e32 v125, 0xffff0000, v131
	v_and_b32_sdwa v130, sext(v136), s75 dst_sel:DWORD dst_unused:UNUSED_PAD src0_sel:WORD_1 src1_sel:DWORD
	v_and_b32_e32 v124, 0xffffff00, v124
	v_add_u32_e32 v154, v132, v148
	v_add_u32_e32 v214, v138, v148
	ds_read_b64 v[140:141], v177
	ds_read_b64 v[142:143], v214
	ds_read_b64 v[172:173], v154
	v_lshl_add_u32 v124, v131, 16, v124
	v_add_u32_e32 v125, v130, v125
	v_pk_mul_f32 v[124:125], v[124:125], s[30:31] op_sel_hi:[1,0]
	s_add_i32 s4, s4, 0x40000
	v_pk_fma_f32 v[130:131], v[126:127], 0.5, v[124:125] op_sel_hi:[1,0,1]
	v_lshlrev_b32_e32 v124, 24, v137
	s_waitcnt lgkmcnt(2)
	v_and_b32_e32 v125, 0xffff0000, v140
	v_ashrrev_i32_e32 v124, 16, v124
	v_and_b32_sdwa v126, sext(v137), s75 dst_sel:DWORD dst_unused:UNUSED_PAD src0_sel:WORD_0 src1_sel:DWORD
	v_lshl_add_u32 v124, v140, 16, v124
	v_add_u32_e32 v125, v126, v125
	v_pk_mul_f32 v[124:125], v[124:125], s[30:31] op_sel_hi:[1,0]
	v_and_b32_sdwa v126, sext(v137), s75 dst_sel:DWORD dst_unused:UNUSED_PAD src0_sel:WORD_1 src1_sel:DWORD
	v_pk_fma_f32 v[124:125], v[116:117], 0.5, v[124:125] op_sel_hi:[1,0,1]
	v_bfe_i32 v116, v137, 8, 16
	ds_read2_b32 v[136:137], v160 offset0:32 offset1:36
	v_and_b32_e32 v117, 0xffff0000, v141
	v_and_b32_e32 v116, 0xffffff00, v116
	v_lshl_add_u32 v116, v141, 16, v116
	v_add_u32_e32 v117, v126, v117
	v_pk_mul_f32 v[116:117], v[116:117], s[30:31] op_sel_hi:[1,0]
	s_waitcnt lgkmcnt(0)
	v_lshlrev_b32_e32 v140, 24, v137
	v_pk_fma_f32 v[126:127], v[118:119], 0.5, v[116:117] op_sel_hi:[1,0,1]
	v_lshlrev_b32_e32 v116, 24, v136
	v_and_b32_e32 v117, 0xffff0000, v142
	v_ashrrev_i32_e32 v116, 16, v116
	v_and_b32_sdwa v118, sext(v136), s75 dst_sel:DWORD dst_unused:UNUSED_PAD src0_sel:WORD_0 src1_sel:DWORD
	v_lshl_add_u32 v116, v142, 16, v116
	v_add_u32_e32 v117, v118, v117
	v_pk_mul_f32 v[116:117], v[116:117], s[30:31] op_sel_hi:[1,0]
	v_bfe_i32 v118, v136, 8, 16
	v_pk_fma_f32 v[116:117], v[120:121], 0.5, v[116:117] op_sel_hi:[1,0,1]
	v_and_b32_sdwa v120, sext(v136), s75 dst_sel:DWORD dst_unused:UNUSED_PAD src0_sel:WORD_1 src1_sel:DWORD
	v_or_b32_e32 v136, 0x120, v133
	v_and_b32_e32 v119, 0xffff0000, v143
	v_add_u32_e32 v142, v138, v136
	v_add_u32_e32 v119, v120, v119
	ds_read_b64 v[120:121], v142
	v_ashrrev_i32_e32 v140, 16, v140
	v_and_b32_sdwa v162, sext(v137), s75 dst_sel:DWORD dst_unused:UNUSED_PAD src0_sel:WORD_0 src1_sel:DWORD
	v_and_b32_e32 v118, 0xffffff00, v118
	v_lshl_add_u32 v118, v143, 16, v118
	s_waitcnt lgkmcnt(0)
; #define WAIT_V(n) asm volatile("s_waitcnt vmcnt(" #n ")" ::: "memory")
; #define WAIT_L(n) asm volatile("s_waitcnt lgkmcnt(" #n ")" ::: "memory")
;     ...
;           _Pragma("unroll") for (int i = 0; i < 8; ++i)
;             __builtin_amdgcn_raw_ptr_buffer_load_lds(rsXB, (__attribute__((address_space(3))) void*)(smem + (wave * 8 + i) * PIECE), 16,
;                                                      hvo + i * (2 * DM * 2), hso, 0, 0);
;           _Pragma("unroll") for (int i = 0; i < 4; ++i)
;             __builtin_amdgcn_raw_ptr_buffer_load_lds(rsLO, (__attribute__((address_space(3))) void*)(smem + LOBASE + (wave * 4 + i) * PIECE), 16,
;                                                      lvo + i * (4 * DM), lso, 0, 0);
;           WAIT_V(0); BAR;
;           _Pragma("unroll") for (int m = 0; m < 4; ++m) _Pragma("unroll") for (int bj = 0; bj < 2; ++bj) _Pragma("unroll") for (int n = 0; n < 2; ++n) {
;             const int rr = wr * 64 + m * 16 + fr;
;             const int cc = bj * HALF + wc * 32 + n * 16 + fq * 4;
;             const u32x2 hv = *reinterpret_cast<const u32x2*>(smem + (rr >> 1) * PIECE + (rr & 1) * 512 + cc * 2);
;             const unsigned lv = *reinterpret_cast<const unsigned*>(smem + LOBASE + (rr >> 2) * PIECE + (rr & 3) * 256 + cc);
;             float x0 = __int_as_float((int)(hv[0] << 16) + (((int)(lv << 24)) >> 24) * 256);
;             float x1 = __int_as_float((int)(hv[0] & 0xffff0000u) + (((int)(lv << 16)) >> 24) * 256);
;             float x2 = __int_as_float((int)(hv[1] << 16) + (((int)(lv << 8)) >> 24) * 256);
;             float x3 = __int_as_float((int)(hv[1] & 0xffff0000u) + (((int)lv) >> 24) * 256);
;             acc[ai][bj][m][n][0] = ALPHA * x0 + sc * acc[ai][bj][m][n][0];
;             acc[ai][bj][m][n][1] = ALPHA * x1 + sc * acc[ai][bj][m][n][1];
;             acc[ai][bj][m][n][2] = ALPHA * x2 + sc * acc[ai][bj][m][n][2];
;             acc[ai][bj][m][n][3] = ALPHA * x3 + sc * acc[ai][bj][m][n][3];
;           }
;           WAIT_L(0); BAR;
;         }
;       }
;       float* red = reinterpret_cast<float*>(smem + 8 * HTB);
;       const int bp16 = (lane ^ 16) << 2, bp32 = (lane ^ 32) << 2;
;       float* red2 = red + 4 * 256 * 2;
;       float* mr = red2 + 2 * 256 * 2;
;       _Pragma("unroll") for (int ai = 0; ai < 2; ++ai) _Pragma("unroll") for (int m = 0; m < 4; ++m) {
;         float s1 = 0.f, s2 = 0.f;
	v_and_b32_e32 v141, 0xffff0000, v120
	v_lshl_add_u32 v140, v120, 16, v140
	v_add_u32_e32 v141, v162, v141
	v_pk_mul_f32 v[140:141], v[140:141], s[30:31] op_sel_hi:[1,0]
	v_bfe_i32 v120, v137, 8, 16
	v_pk_fma_f32 v[112:113], v[112:113], 0.5, v[140:141] op_sel_hi:[1,0,1]
	v_and_b32_e32 v140, 0xffff0000, v121
	v_and_b32_sdwa v137, sext(v137), s75 dst_sel:DWORD dst_unused:UNUSED_PAD src0_sel:WORD_1 src1_sel:DWORD
	v_and_b32_e32 v120, 0xffffff00, v120
	v_lshl_add_u32 v120, v121, 16, v120
	v_add_u32_e32 v121, v137, v140
	v_or_b32_e32 v143, 16, v225
	v_pk_mul_f32 v[120:121], v[120:121], s[30:31] op_sel_hi:[1,0]
	v_or_b32_e32 v140, 32, v225
	v_pk_fma_f32 v[114:115], v[114:115], 0.5, v[120:121] op_sel_hi:[1,0,1]
	v_lshrrev_b32_e32 v120, 2, v143
	v_mul_lo_u32 v120, v120, s58
	v_pk_mul_f32 v[118:119], v[118:119], s[30:31] op_sel_hi:[1,0]
	v_add3_u32 v137, v146, v120, v145
	v_lshrrev_b32_e32 v120, 1, v140
	v_pk_fma_f32 v[118:119], v[122:123], 0.5, v[118:119] op_sel_hi:[1,0,1]
	v_lshrrev_b32_e32 v122, 1, v143
	v_mad_u64_u32 v[120:121], s[6:7], v120, s58, v[134:135]
	v_mad_u64_u32 v[138:139], s[6:7], v122, s58, v[134:135]
	v_lshrrev_b32_e32 v121, 2, v140
	v_add_u32_e32 v134, v120, v133
	v_add_u32_e32 v140, v120, v161
	v_add_u32_e32 v141, v120, v148
	v_add_u32_e32 v143, v120, v136
	v_lshrrev_b32_e32 v120, 2, v147
	v_mul_lo_u32 v121, v121, s58
	v_mul_lo_u32 v120, v120, s58
	v_add_u32_e32 v139, v138, v133
	v_add_u32_e32 v164, v138, v161
	v_add_u32_e32 v178, v138, v148
	v_add_u32_e32 v138, v138, v136
	v_add3_u32 v121, v146, v121, v145
	v_add3_u32 v120, v146, v120, v145
	s_lshl_b32 s5, s4, 1
	s_mov_b32 m0, s57
	ds_read_b64 v[122:123], v139
	ds_read_b64 v[210:211], v164
	ds_read_b64 v[204:205], v178
	ds_read2_b32 v[212:213], v137 offset1:4
	ds_read2_b32 v[206:207], v137 offset0:32 offset1:36
	ds_read2_b32 v[198:199], v121 offset1:4
	ds_read_b64 v[208:209], v138
	ds_read_b64 v[202:203], v134
	ds_read_b64 v[200:201], v140
	ds_read_b64 v[196:197], v141
	ds_read2_b32 v[192:193], v121 offset0:32 offset1:36
	v_add_u32_e32 v222, v132, v133
	ds_read2_b32 v[186:187], v120 offset1:4
	v_add_u32_e32 v226, v132, v161
	ds_read2_b32 v[182:183], v120 offset0:32 offset1:36
	v_add_u32_e32 v227, v132, v136
	ds_read_b64 v[194:195], v143
	ds_read_b64 v[190:191], v222
	ds_read_b64 v[188:189], v226
	ds_read_b64 v[184:185], v227
	s_waitcnt lgkmcnt(0)
	s_barrier
	buffer_load_dwordx4 v135, s[16:19], s5 offen lds
	s_mov_b32 m0, s59
	v_lshlrev_b32_e32 v228, 2, v223
	buffer_load_dwordx4 v149, s[16:19], s5 offen lds
	s_mov_b32 m0, s60
	v_xor_b32_e32 v221, 64, v228
	buffer_load_dwordx4 v150, s[16:19], s5 offen lds
	s_mov_b32 m0, s61
	v_lshlrev_b32_e32 v224, 9, v224
	buffer_load_dwordx4 v151, s[16:19], s5 offen lds
	s_mov_b32 m0, s62
	v_cmp_gt_u32_e32 vcc, 16, v223
	buffer_load_dwordx4 v152, s[16:19], s5 offen lds
	s_mov_b32 m0, s63
	v_lshlrev_b32_e32 v223, 3, v225
	buffer_load_dwordx4 v153, s[16:19], s5 offen lds
	s_mov_b32 m0, s64
	v_lshlrev_b32_e32 v224, 2, v224
	buffer_load_dwordx4 v155, s[16:19], s5 offen lds
	s_mov_b32 m0, s65
	s_nop 0
	buffer_load_dwordx4 v156, s[16:19], s5 offen lds
	s_mov_b32 m0, s66
	s_nop 0
	buffer_load_dwordx4 v144, s[20:23], s4 offen lds
	s_mov_b32 m0, s67
	s_nop 0
	buffer_load_dwordx4 v157, s[20:23], s4 offen lds
	s_mov_b32 m0, s68
	s_nop 0
	buffer_load_dwordx4 v158, s[20:23], s4 offen lds
	s_mov_b32 m0, s69
	s_nop 0
	buffer_load_dwordx4 v159, s[20:23], s4 offen lds
	s_waitcnt vmcnt(0)
	s_barrier
	ds_read2_b32 v[174:175], v160 offset1:4
	ds_read2_b32 v[168:169], v160 offset0:32 offset1:36
	ds_read2_b32 v[162:163], v137 offset1:4
	ds_read_b64 v[170:171], v142
	ds_read_b64 v[166:167], v139
	ds_read_b64 v[164:165], v164
	ds_read_b64 v[160:161], v178
	ds_read2_b32 v[156:157], v137 offset0:32 offset1:36
	ds_read2_b32 v[148:149], v121 offset1:4
	ds_read_b64 v[158:159], v138
	ds_read_b64 v[152:153], v134
	ds_read_b64 v[150:151], v140
	ds_read_b64 v[146:147], v141
	ds_read2_b32 v[144:145], v121 offset0:32 offset1:36
	ds_read2_b32 v[136:137], v120 offset1:4
	ds_read_b64 v[180:181], v176
	ds_read_b64 v[178:179], v177
	ds_read_b64 v[176:177], v214
	ds_read_b64 v[134:135], v154
	ds_read2_b32 v[132:133], v120 offset0:32 offset1:36
	v_add_f32_e32 v120, 0, v128
	v_add_f32_e32 v138, v120, v129
	v_mul_f32_e32 v120, v129, v129
	v_add_f32_e32 v138, v130, v138
	v_pk_fma_f32 v[120:121], v[128:129], v[128:129], v[120:121] op_sel_hi:[1,1,0]
	v_add_f32_e32 v138, v131, v138
	v_pk_fma_f32 v[120:121], v[130:131], v[130:131], v[120:121]
	v_add_f32_e32 v141, v124, v138
	v_mul_f32_e32 v140, v131, v131
	v_mov_b32_e32 v138, v124
	v_mov_b32_e32 v139, v131
	v_pk_add_f32 v[120:121], v[140:141], v[120:121] op_sel_hi:[0,1]
	v_pk_fma_f32 v[120:121], v[138:139], v[138:139], v[120:121]
	v_add_f32_e32 v138, v125, v141
	v_add_f32_e32 v141, v126, v138
	v_mul_f32_e32 v140, v125, v125
	v_mov_b32_e32 v138, v126
	v_mov_b32_e32 v139, v125
	v_pk_add_f32 v[120:121], v[140:141], v[120:121] op_sel_hi:[0,1]
	v_pk_fma_f32 v[120:121], v[138:139], v[138:139], v[120:121]
	v_add_f32_e32 v138, v127, v141
	v_add_f32_e32 v141, v116, v138
	v_mul_f32_e32 v140, v127, v127
	v_mov_b32_e32 v138, v116
	v_mov_b32_e32 v139, v127
	v_pk_add_f32 v[120:121], v[140:141], v[120:121] op_sel_hi:[0,1]
	v_pk_fma_f32 v[120:121], v[138:139], v[138:139], v[120:121]
	v_add_f32_e32 v138, v117, v141
	v_add_f32_e32 v141, v118, v138
	v_mul_f32_e32 v140, v117, v117
	v_mov_b32_e32 v138, v118
	v_mov_b32_e32 v139, v117
	v_pk_add_f32 v[120:121], v[140:141], v[120:121] op_sel_hi:[0,1]
	v_pk_fma_f32 v[120:121], v[138:139], v[138:139], v[120:121]
	v_add_f32_e32 v138, v119, v141
	v_add_f32_e32 v141, v112, v138
	v_mul_f32_e32 v140, v119, v119
	v_mov_b32_e32 v138, v112
	v_mov_b32_e32 v139, v119
	v_pk_add_f32 v[120:121], v[140:141], v[120:121] op_sel_hi:[0,1]
	v_pk_fma_f32 v[120:121], v[138:139], v[138:139], v[120:121]
	v_mul_f32_e32 v142, v113, v113
	v_add_f32_e32 v138, v113, v141
	v_mov_b32_e32 v140, v114
	v_mov_b32_e32 v141, v113
	v_pk_add_f32 v[120:121], v[142:143], v[120:121] op_sel_hi:[0,1]
	v_pk_fma_f32 v[120:121], v[140:141], v[140:141], v[120:121]
	v_pk_mul_f32 v[140:141], v[114:115], v[114:115]
	v_add_f32_e32 v138, v114, v138
	v_pk_mov_b32 v[120:121], v[114:115], v[120:121] op_sel:[1,0]
	v_mov_b32_e32 v139, v141
	v_pk_add_f32 v[120:121], v[120:121], v[138:139]
	ds_bpermute_b32 v214, v221, v120
	ds_bpermute_b32 v215, v221, v121
	ds_read_b64 v[154:155], v143
	ds_read_b64 v[142:143], v222
	ds_read_b64 v[140:141], v226
	ds_read_b64 v[138:139], v227
	v_xor_b32_e32 v222, 0x80, v228
	s_waitcnt lgkmcnt(0)
	s_barrier
	v_pk_add_f32 v[120:121], v[120:121], v[214:215]
	ds_bpermute_b32 v214, v222, v120
	ds_bpermute_b32 v215, v222, v121
	s_and_saveexec_b64 s[4:5], vcc
	s_cbranch_execz .LBB0_764
	v_add3_u32 v225, v223, v224, s19
	s_waitcnt lgkmcnt(0)
	v_pk_add_f32 v[120:121], v[120:121], v[214:215]
	s_waitcnt vmcnt(0)
	ds_write_b64 v225, v[120:121]
